# all plain global_store_dwordx4 made write-through (sc1) so the barrier's L2 writeback has less to flush
# speedup vs baseline: 1.0607x; 1.0607x over previous
.LBB0_56:
	s_waitcnt vmcnt(0)
	ds_write2_b32 v81, v2, v3 offset1:1
	ds_write2_b32 v81, v4, v5 offset0:2 offset1:3
	v_add_u32_e32 v2, 0x410, v81
	ds_write2_b32 v2, v6, v7 offset1:1
	v_add_u32_e32 v2, 0x418, v81
	ds_write2_b32 v2, v8, v9 offset1:1
	v_add_u32_e32 v2, 0x820, v81
	ds_write2_b32 v2, v14, v15 offset1:1
	v_add_u32_e32 v2, 0x828, v81
	ds_write2_b32 v2, v16, v17 offset1:1
	v_add_u32_e32 v2, 0xc30, v81
	ds_write2_b32 v2, v10, v11 offset1:1
	v_add_u32_e32 v2, 0xc38, v81
	ds_write2_b32 v2, v12, v13 offset1:1
	v_add_u32_e32 v2, 0x1040, v81
	ds_write2_b32 v2, v22, v23 offset1:1
	v_add_u32_e32 v2, 0x1048, v81
	ds_write2_b32 v2, v24, v25 offset1:1
	v_add_u32_e32 v2, 0x1450, v81
	ds_write2_b32 v2, v18, v19 offset1:1
	v_add_u32_e32 v2, 0x1458, v81
	ds_write2_b32 v2, v20, v21 offset1:1
	v_add_u32_e32 v2, 0x1860, v81
	ds_write2_b32 v2, v30, v31 offset1:1
	v_add_u32_e32 v2, 0x1868, v81
	ds_write2_b32 v2, v32, v33 offset1:1
	v_add_u32_e32 v2, 0x1c70, v81
	ds_write2_b32 v2, v26, v27 offset1:1
	v_add_u32_e32 v2, 0x1c78, v81
	ds_write2_b32 v2, v28, v29 offset1:1
	v_add_u32_e32 v2, 0x2080, v81
	ds_write2_b32 v2, v38, v39 offset1:1
	v_add_u32_e32 v2, 0x2088, v81
	ds_write2_b32 v2, v40, v41 offset1:1
	v_add_u32_e32 v2, 0x2490, v81
	ds_write2_b32 v2, v34, v35 offset1:1
	v_add_u32_e32 v2, 0x2498, v81
	ds_write2_b32 v2, v36, v37 offset1:1
	v_add_u32_e32 v2, 0x28a0, v81
	ds_write2_b32 v2, v46, v47 offset1:1
	v_add_u32_e32 v2, 0x28a8, v81
	ds_write2_b32 v2, v48, v49 offset1:1
	v_add_u32_e32 v2, 0x2cb0, v81
	ds_write2_b32 v2, v42, v43 offset1:1
	v_add_u32_e32 v2, 0x2cb8, v81
	ds_write2_b32 v2, v44, v45 offset1:1
	v_add_u32_e32 v2, 0x30c0, v81
	ds_write2_b32 v2, v54, v55 offset1:1
	v_add_u32_e32 v2, 0x30c8, v81
	ds_write2_b32 v2, v56, v57 offset1:1
	v_add_u32_e32 v2, 0x34d0, v81
	ds_write2_b32 v2, v50, v51 offset1:1
	v_add_u32_e32 v2, 0x34d8, v81
	ds_write2_b32 v2, v52, v53 offset1:1
	v_add_u32_e32 v2, 0x38e0, v81
	ds_write2_b32 v2, v62, v63 offset1:1
	v_add_u32_e32 v2, 0x38e8, v81
	ds_write2_b32 v2, v64, v65 offset1:1
	v_add_u32_e32 v2, 0x3cf0, v81
	ds_write2_b32 v2, v58, v59 offset1:1
	v_add_u32_e32 v2, 0x3cf8, v81
	ds_write2_b32 v2, v60, v61 offset1:1
	s_waitcnt lgkmcnt(0)
	ds_read2_b32 v[10:11], v83 offset1:8
	ds_read2_b32 v[12:13], v83 offset0:65 offset1:73
	ds_read2_b32 v[14:15], v83 offset0:130 offset1:138
	ds_read2_b32 v[16:17], v83 offset0:195 offset1:203
	v_add_u32_e32 v28, 0x400, v83
	s_waitcnt lgkmcnt(3)
	v_bfe_u32 v4, v10, 16, 1
	v_add3_u32 v4, v10, v4, s62
	s_waitcnt lgkmcnt(2)
	v_bfe_u32 v5, v12, 16, 1
	ds_read2_b32 v[18:19], v28 offset0:4 offset1:12
	v_lshrrev_b32_e32 v4, 16, v4
	v_add3_u32 v5, v12, v5, s62
	ds_read2_b32 v[20:21], v28 offset0:69 offset1:77
	v_and_or_b32 v6, v5, s63, v4
	s_waitcnt lgkmcnt(3)
	v_bfe_u32 v4, v14, 16, 1
	v_add3_u32 v4, v14, v4, s62
	s_waitcnt lgkmcnt(2)
	v_bfe_u32 v5, v16, 16, 1
	ds_read2_b32 v[22:23], v28 offset0:134 offset1:142
	v_lshrrev_b32_e32 v4, 16, v4
	v_add3_u32 v5, v16, v5, s62
	ds_read2_b32 v[24:25], v28 offset0:199 offset1:207
	s_lshl_b64 s[0:1], s[30:31], 25
	v_and_or_b32 v7, v5, s63, v4
	s_waitcnt lgkmcnt(3)
	v_bfe_u32 v4, v18, 16, 1
	s_add_u32 s30, s42, s0
	v_add3_u32 v4, v18, v4, s62
	s_waitcnt lgkmcnt(2)
	v_bfe_u32 v5, v20, 16, 1
	s_addc_u32 s31, s43, s1
	s_ashr_i32 s27, s26, 31
	v_lshrrev_b32_e32 v4, 16, v4
	v_add3_u32 v5, v20, v5, s62
	s_lshl_b64 s[0:1], s[26:27], 1
	v_and_or_b32 v8, v5, s63, v4
	s_waitcnt lgkmcnt(1)
	v_bfe_u32 v4, v22, 16, 1
	s_add_u32 s0, s30, s0
	v_add3_u32 v4, v22, v4, s62
	s_waitcnt lgkmcnt(0)
	v_bfe_u32 v5, v24, 16, 1
	s_addc_u32 s1, s31, s1
	v_lshrrev_b32_e32 v4, 16, v4
	v_add3_u32 v5, v24, v5, s62
	s_add_i32 s2, s2, s80
	v_and_or_b32 v9, v5, s63, v4
	v_add_u32_e32 v4, s2, v82
	v_lshlrev_b32_e32 v68, 1, v66
	v_ashrrev_i32_e32 v5, 31, v4
	v_lshl_add_u64 v[2:3], s[0:1], 0, v[68:69]
	v_lshlrev_b64 v[26:27], 14, v[4:5]
	v_lshl_add_u64 v[26:27], v[2:3], 0, v[26:27]
	v_bfe_u32 v5, v11, 16, 1
	global_store_dwordx4 v[26:27], v[6:9], off sc1
	v_add3_u32 v5, v11, v5, s62
	v_lshrrev_b32_e32 v5, 16, v5
	v_bfe_u32 v6, v13, 16, 1
	v_add3_u32 v6, v13, v6, s62
	v_and_or_b32 v6, v6, s63, v5
	v_bfe_u32 v5, v15, 16, 1
	v_add3_u32 v5, v15, v5, s62
	v_bfe_u32 v7, v17, 16, 1
	v_lshrrev_b32_e32 v5, 16, v5
	v_add3_u32 v7, v17, v7, s62
	v_and_or_b32 v7, v7, s63, v5
	v_bfe_u32 v5, v19, 16, 1
	v_add3_u32 v5, v19, v5, s62
	v_bfe_u32 v8, v21, 16, 1
	v_lshrrev_b32_e32 v5, 16, v5
	v_add3_u32 v8, v21, v8, s62
	v_and_or_b32 v8, v8, s63, v5
	v_bfe_u32 v5, v23, 16, 1
	v_add_u32_e32 v10, 8, v4
	v_add3_u32 v5, v23, v5, s62
	v_bfe_u32 v9, v25, 16, 1
	v_ashrrev_i32_e32 v11, 31, v10
	v_lshrrev_b32_e32 v5, 16, v5
	v_add3_u32 v9, v25, v9, s62
	v_lshlrev_b64 v[10:11], 14, v[10:11]
	v_and_or_b32 v9, v9, s63, v5
	ds_read2_b32 v[12:13], v83 offset0:16 offset1:24
	v_lshl_add_u64 v[10:11], v[2:3], 0, v[10:11]
	global_store_dwordx4 v[10:11], v[6:9], off sc1
	ds_read2_b32 v[10:11], v83 offset0:81 offset1:89
	ds_read2_b32 v[14:15], v83 offset0:146 offset1:154
	ds_read2_b32 v[16:17], v83 offset0:211 offset1:219
	s_waitcnt lgkmcnt(3)
	v_bfe_u32 v5, v12, 16, 1
	v_add3_u32 v5, v12, v5, s62
	s_waitcnt lgkmcnt(2)
	v_bfe_u32 v6, v10, 16, 1
	ds_read2_b32 v[18:19], v28 offset0:20 offset1:28
	v_lshrrev_b32_e32 v5, 16, v5
	v_add3_u32 v6, v10, v6, s62
	ds_read2_b32 v[20:21], v28 offset0:85 offset1:93
	v_and_or_b32 v6, v6, s63, v5
	s_waitcnt lgkmcnt(3)
	v_bfe_u32 v5, v14, 16, 1
	v_add3_u32 v5, v14, v5, s62
	s_waitcnt lgkmcnt(2)
	v_bfe_u32 v7, v16, 16, 1
	ds_read2_b32 v[22:23], v28 offset0:150 offset1:158
	v_lshrrev_b32_e32 v5, 16, v5
	v_add3_u32 v7, v16, v7, s62
	ds_read2_b32 v[24:25], v28 offset0:215 offset1:223
	v_and_or_b32 v7, v7, s63, v5
	s_waitcnt lgkmcnt(3)
	v_bfe_u32 v5, v18, 16, 1
	v_add3_u32 v5, v18, v5, s62
	s_waitcnt lgkmcnt(2)
	v_bfe_u32 v8, v20, 16, 1
	v_lshrrev_b32_e32 v5, 16, v5
	v_add3_u32 v8, v20, v8, s62
	v_and_or_b32 v8, v8, s63, v5
	s_waitcnt lgkmcnt(1)
	v_bfe_u32 v5, v22, 16, 1
	v_add_u32_e32 v26, 16, v4
	v_add3_u32 v5, v22, v5, s62
	s_waitcnt lgkmcnt(0)
	v_bfe_u32 v9, v24, 16, 1
	v_ashrrev_i32_e32 v27, 31, v26
	v_lshrrev_b32_e32 v5, 16, v5
	v_add3_u32 v9, v24, v9, s62
	v_lshlrev_b64 v[26:27], 14, v[26:27]
	v_and_or_b32 v9, v9, s63, v5
	v_lshl_add_u64 v[26:27], v[2:3], 0, v[26:27]
	v_bfe_u32 v5, v13, 16, 1
	global_store_dwordx4 v[26:27], v[6:9], off sc1
	v_add3_u32 v5, v13, v5, s62
	v_lshrrev_b32_e32 v5, 16, v5
	v_bfe_u32 v6, v11, 16, 1
	v_add3_u32 v6, v11, v6, s62
	v_and_or_b32 v6, v6, s63, v5
	v_bfe_u32 v5, v15, 16, 1
	v_add3_u32 v5, v15, v5, s62
	v_bfe_u32 v7, v17, 16, 1
	v_lshrrev_b32_e32 v5, 16, v5
	v_add3_u32 v7, v17, v7, s62
	v_and_or_b32 v7, v7, s63, v5
	v_bfe_u32 v5, v19, 16, 1
	v_add3_u32 v5, v19, v5, s62
	v_bfe_u32 v8, v21, 16, 1
	v_lshrrev_b32_e32 v5, 16, v5
	v_add3_u32 v8, v21, v8, s62
	v_and_or_b32 v8, v8, s63, v5
	v_bfe_u32 v5, v23, 16, 1
	v_add_u32_e32 v10, 24, v4
	v_add3_u32 v5, v23, v5, s62
	v_bfe_u32 v9, v25, 16, 1
	v_ashrrev_i32_e32 v11, 31, v10
	v_lshrrev_b32_e32 v5, 16, v5
	v_add3_u32 v9, v25, v9, s62
	v_lshlrev_b64 v[10:11], 14, v[10:11]
	v_and_or_b32 v9, v9, s63, v5
	ds_read2_b32 v[12:13], v83 offset0:32 offset1:40
	v_lshl_add_u64 v[10:11], v[2:3], 0, v[10:11]
	global_store_dwordx4 v[10:11], v[6:9], off sc1
	ds_read2_b32 v[10:11], v83 offset0:97 offset1:105
	ds_read2_b32 v[14:15], v83 offset0:162 offset1:170
	ds_read2_b32 v[16:17], v83 offset0:227 offset1:235
	s_waitcnt lgkmcnt(3)
	v_bfe_u32 v5, v12, 16, 1
	v_add3_u32 v5, v12, v5, s62
	s_waitcnt lgkmcnt(2)
	v_bfe_u32 v6, v10, 16, 1
	ds_read2_b32 v[18:19], v28 offset0:36 offset1:44
	v_lshrrev_b32_e32 v5, 16, v5
	v_add3_u32 v6, v10, v6, s62
	ds_read2_b32 v[20:21], v28 offset0:101 offset1:109
	v_and_or_b32 v6, v6, s63, v5
	s_waitcnt lgkmcnt(3)
	v_bfe_u32 v5, v14, 16, 1
	v_add3_u32 v5, v14, v5, s62
	s_waitcnt lgkmcnt(2)
	v_bfe_u32 v7, v16, 16, 1
	ds_read2_b32 v[22:23], v28 offset0:166 offset1:174
	v_lshrrev_b32_e32 v5, 16, v5
	v_add3_u32 v7, v16, v7, s62
	ds_read2_b32 v[24:25], v28 offset0:231 offset1:239
	v_and_or_b32 v7, v7, s63, v5
	s_waitcnt lgkmcnt(3)
	v_bfe_u32 v5, v18, 16, 1
	v_add3_u32 v5, v18, v5, s62
	s_waitcnt lgkmcnt(2)
	v_bfe_u32 v8, v20, 16, 1
	v_lshrrev_b32_e32 v5, 16, v5
	v_add3_u32 v8, v20, v8, s62
	v_and_or_b32 v8, v8, s63, v5
	s_waitcnt lgkmcnt(1)
	v_bfe_u32 v5, v22, 16, 1
	v_add_u32_e32 v26, 32, v4
	v_add3_u32 v5, v22, v5, s62
	s_waitcnt lgkmcnt(0)
	v_bfe_u32 v9, v24, 16, 1
	v_ashrrev_i32_e32 v27, 31, v26
	v_lshrrev_b32_e32 v5, 16, v5
	v_add3_u32 v9, v24, v9, s62
	v_lshlrev_b64 v[26:27], 14, v[26:27]
	v_and_or_b32 v9, v9, s63, v5
	v_lshl_add_u64 v[26:27], v[2:3], 0, v[26:27]
	v_bfe_u32 v5, v13, 16, 1
	global_store_dwordx4 v[26:27], v[6:9], off sc1
	v_add3_u32 v5, v13, v5, s62
	v_lshrrev_b32_e32 v5, 16, v5
	v_bfe_u32 v6, v11, 16, 1
	v_add3_u32 v6, v11, v6, s62
	v_and_or_b32 v6, v6, s63, v5
	v_bfe_u32 v5, v15, 16, 1
	v_add3_u32 v5, v15, v5, s62
	v_bfe_u32 v7, v17, 16, 1
	v_lshrrev_b32_e32 v5, 16, v5
	v_add3_u32 v7, v17, v7, s62
	v_and_or_b32 v7, v7, s63, v5
	v_bfe_u32 v5, v19, 16, 1
	v_add3_u32 v5, v19, v5, s62
	v_bfe_u32 v8, v21, 16, 1
	v_lshrrev_b32_e32 v5, 16, v5
	v_add3_u32 v8, v21, v8, s62
	v_and_or_b32 v8, v8, s63, v5
	v_bfe_u32 v5, v23, 16, 1
	v_add_u32_e32 v10, 40, v4
	v_add3_u32 v5, v23, v5, s62
	v_bfe_u32 v9, v25, 16, 1
	v_ashrrev_i32_e32 v11, 31, v10
	v_lshrrev_b32_e32 v5, 16, v5
	v_add3_u32 v9, v25, v9, s62
	v_lshlrev_b64 v[10:11], 14, v[10:11]
	v_and_or_b32 v9, v9, s63, v5
	ds_read2_b32 v[12:13], v83 offset0:48 offset1:56
	v_lshl_add_u64 v[10:11], v[2:3], 0, v[10:11]
	global_store_dwordx4 v[10:11], v[6:9], off sc1
	ds_read2_b32 v[10:11], v83 offset0:113 offset1:121
	ds_read2_b32 v[14:15], v83 offset0:178 offset1:186
	ds_read2_b32 v[16:17], v83 offset0:243 offset1:251
	s_waitcnt lgkmcnt(3)
	v_bfe_u32 v5, v12, 16, 1
	v_add3_u32 v5, v12, v5, s62
	s_waitcnt lgkmcnt(2)
	v_bfe_u32 v6, v10, 16, 1
	ds_read2_b32 v[18:19], v28 offset0:52 offset1:60
	v_lshrrev_b32_e32 v5, 16, v5
	v_add3_u32 v6, v10, v6, s62
	ds_read2_b32 v[20:21], v28 offset0:117 offset1:125
	v_and_or_b32 v6, v6, s63, v5
	s_waitcnt lgkmcnt(3)
	v_bfe_u32 v5, v14, 16, 1
	v_add3_u32 v5, v14, v5, s62
	s_waitcnt lgkmcnt(2)
	v_bfe_u32 v7, v16, 16, 1
	ds_read2_b32 v[22:23], v28 offset0:182 offset1:190
	v_lshrrev_b32_e32 v5, 16, v5
	v_add3_u32 v7, v16, v7, s62
	ds_read2_b32 v[24:25], v28 offset0:247 offset1:255
	v_and_or_b32 v7, v7, s63, v5
	s_waitcnt lgkmcnt(3)
	v_bfe_u32 v5, v18, 16, 1
	v_add3_u32 v5, v18, v5, s62
	s_waitcnt lgkmcnt(2)
	v_bfe_u32 v8, v20, 16, 1
	v_lshrrev_b32_e32 v5, 16, v5
	v_add3_u32 v8, v20, v8, s62
	v_and_or_b32 v8, v8, s63, v5
	s_waitcnt lgkmcnt(1)
	v_bfe_u32 v5, v22, 16, 1
	v_add_u32_e32 v26, 48, v4
	v_add3_u32 v5, v22, v5, s62
	s_waitcnt lgkmcnt(0)
	v_bfe_u32 v9, v24, 16, 1
	v_ashrrev_i32_e32 v27, 31, v26
	v_lshrrev_b32_e32 v5, 16, v5
	v_add3_u32 v9, v24, v9, s62
	v_lshlrev_b64 v[26:27], 14, v[26:27]
	v_and_or_b32 v9, v9, s63, v5
	v_lshl_add_u64 v[26:27], v[2:3], 0, v[26:27]
	v_bfe_u32 v5, v13, 16, 1
	global_store_dwordx4 v[26:27], v[6:9], off sc1
	v_add3_u32 v5, v13, v5, s62
	v_lshrrev_b32_e32 v5, 16, v5
	v_bfe_u32 v6, v11, 16, 1
	v_add3_u32 v6, v11, v6, s62
	v_and_or_b32 v6, v6, s63, v5
	v_bfe_u32 v5, v15, 16, 1
	v_add3_u32 v5, v15, v5, s62
	v_bfe_u32 v7, v17, 16, 1
	v_lshrrev_b32_e32 v5, 16, v5
	v_add3_u32 v7, v17, v7, s62
	v_and_or_b32 v7, v7, s63, v5
	v_bfe_u32 v5, v19, 16, 1
	v_add3_u32 v5, v19, v5, s62
	v_bfe_u32 v8, v21, 16, 1
	v_lshrrev_b32_e32 v5, 16, v5
	v_add3_u32 v8, v21, v8, s62
	v_and_or_b32 v8, v8, s63, v5
	v_bfe_u32 v5, v23, 16, 1
	v_add3_u32 v5, v23, v5, s62
	v_bfe_u32 v9, v25, 16, 1
	v_lshrrev_b32_e32 v5, 16, v5
	v_add3_u32 v9, v25, v9, s62
	v_add_u32_e32 v4, 56, v4
	v_and_or_b32 v9, v9, s63, v5
	v_ashrrev_i32_e32 v5, 31, v4
	v_lshlrev_b64 v[4:5], 14, v[4:5]
	v_lshl_add_u64 v[2:3], v[2:3], 0, v[4:5]
	global_store_dwordx4 v[2:3], v[6:9], off sc1
	s_waitcnt lgkmcnt(0)

.LBB0_95:
	s_waitcnt vmcnt(0)
	ds_write2_b32 v81, v2, v3 offset1:1
	ds_write2_b32 v81, v4, v5 offset0:2 offset1:3
	v_add_u32_e32 v2, 0x410, v81
	ds_write2_b32 v2, v6, v7 offset1:1
	v_add_u32_e32 v2, 0x418, v81
	ds_write2_b32 v2, v8, v9 offset1:1
	v_add_u32_e32 v2, 0x820, v81
	ds_write2_b32 v2, v14, v15 offset1:1
	v_add_u32_e32 v2, 0x828, v81
	ds_write2_b32 v2, v16, v17 offset1:1
	v_add_u32_e32 v2, 0xc30, v81
	ds_write2_b32 v2, v10, v11 offset1:1
	v_add_u32_e32 v2, 0xc38, v81
	ds_write2_b32 v2, v12, v13 offset1:1
	v_add_u32_e32 v2, 0x1040, v81
	ds_write2_b32 v2, v22, v23 offset1:1
	v_add_u32_e32 v2, 0x1048, v81
	ds_write2_b32 v2, v24, v25 offset1:1
	v_add_u32_e32 v2, 0x1450, v81
	ds_write2_b32 v2, v18, v19 offset1:1
	v_add_u32_e32 v2, 0x1458, v81
	ds_write2_b32 v2, v20, v21 offset1:1
	v_add_u32_e32 v2, 0x1860, v81
	ds_write2_b32 v2, v30, v31 offset1:1
	v_add_u32_e32 v2, 0x1868, v81
	ds_write2_b32 v2, v32, v33 offset1:1
	v_add_u32_e32 v2, 0x1c70, v81
	ds_write2_b32 v2, v26, v27 offset1:1
	v_add_u32_e32 v2, 0x1c78, v81
	ds_write2_b32 v2, v28, v29 offset1:1
	v_add_u32_e32 v2, 0x2080, v81
	ds_write2_b32 v2, v38, v39 offset1:1
	v_add_u32_e32 v2, 0x2088, v81
	ds_write2_b32 v2, v40, v41 offset1:1
	v_add_u32_e32 v2, 0x2490, v81
	ds_write2_b32 v2, v34, v35 offset1:1
	v_add_u32_e32 v2, 0x2498, v81
	ds_write2_b32 v2, v36, v37 offset1:1
	v_add_u32_e32 v2, 0x28a0, v81
	ds_write2_b32 v2, v46, v47 offset1:1
	v_add_u32_e32 v2, 0x28a8, v81
	ds_write2_b32 v2, v48, v49 offset1:1
	v_add_u32_e32 v2, 0x2cb0, v81
	ds_write2_b32 v2, v42, v43 offset1:1
	v_add_u32_e32 v2, 0x2cb8, v81
	ds_write2_b32 v2, v44, v45 offset1:1
	v_add_u32_e32 v2, 0x30c0, v81
	ds_write2_b32 v2, v54, v55 offset1:1
	v_add_u32_e32 v2, 0x30c8, v81
	ds_write2_b32 v2, v56, v57 offset1:1
	v_add_u32_e32 v2, 0x34d0, v81
	ds_write2_b32 v2, v50, v51 offset1:1
	v_add_u32_e32 v2, 0x34d8, v81
	ds_write2_b32 v2, v52, v53 offset1:1
	v_add_u32_e32 v2, 0x38e0, v81
	ds_write2_b32 v2, v62, v63 offset1:1
	v_add_u32_e32 v2, 0x38e8, v81
	ds_write2_b32 v2, v64, v65 offset1:1
	v_add_u32_e32 v2, 0x3cf0, v81
	ds_write2_b32 v2, v58, v59 offset1:1
	v_add_u32_e32 v2, 0x3cf8, v81
	ds_write2_b32 v2, v60, v61 offset1:1
	s_waitcnt lgkmcnt(0)
	ds_read2_b32 v[8:9], v83 offset1:8
	ds_read2_b32 v[10:11], v83 offset0:65 offset1:73
	ds_read2_b32 v[12:13], v83 offset0:130 offset1:138
	ds_read2_b32 v[14:15], v83 offset0:195 offset1:203
	v_add_u32_e32 v26, 0x400, v83
	s_waitcnt lgkmcnt(3)
	v_bfe_u32 v4, v8, 16, 1
	v_add3_u32 v4, v8, v4, s62
	s_waitcnt lgkmcnt(2)
	v_bfe_u32 v5, v10, 16, 1
	ds_read2_b32 v[16:17], v26 offset0:4 offset1:12
	v_lshrrev_b32_e32 v4, 16, v4
	v_add3_u32 v5, v10, v5, s62
	ds_read2_b32 v[18:19], v26 offset0:69 offset1:77
	v_and_or_b32 v4, v5, s63, v4
	s_waitcnt lgkmcnt(3)
	v_bfe_u32 v5, v12, 16, 1
	v_add3_u32 v5, v12, v5, s62
	s_waitcnt lgkmcnt(2)
	v_bfe_u32 v6, v14, 16, 1
	ds_read2_b32 v[20:21], v26 offset0:134 offset1:142
	v_lshrrev_b32_e32 v5, 16, v5
	v_add3_u32 v6, v14, v6, s62
	ds_read2_b32 v[22:23], v26 offset0:199 offset1:207
	v_and_or_b32 v5, v6, s63, v5
	s_waitcnt lgkmcnt(3)
	v_bfe_u32 v6, v16, 16, 1
	v_add3_u32 v6, v16, v6, s62
	s_waitcnt lgkmcnt(2)
	v_bfe_u32 v7, v18, 16, 1
	v_lshrrev_b32_e32 v6, 16, v6
	v_add3_u32 v7, v18, v7, s62
	v_and_or_b32 v6, v7, s63, v6
	s_waitcnt lgkmcnt(1)
	v_bfe_u32 v7, v20, 16, 1
	v_add_u32_e32 v24, s26, v100
	s_lshl_b32 s2, s2, 1
	v_add3_u32 v7, v20, v7, s62
	s_waitcnt lgkmcnt(0)
	v_bfe_u32 v8, v22, 16, 1
	v_ashrrev_i32_e32 v25, 31, v24
	v_lshl_add_u64 v[2:3], v[70:71], 0, s[2:3]
	v_lshrrev_b32_e32 v7, 16, v7
	v_add3_u32 v8, v22, v8, s62
	v_lshlrev_b64 v[24:25], 12, v[24:25]
	v_and_or_b32 v7, v8, s63, v7
	v_lshl_add_u64 v[24:25], v[2:3], 0, v[24:25]
	global_store_dwordx4 v[24:25], v[4:7], off sc1
	v_bfe_u32 v8, v23, 16, 1
	v_add3_u32 v8, v23, v8, s62
	v_bfe_u32 v4, v9, 16, 1
	v_add3_u32 v4, v9, v4, s62
	v_bfe_u32 v5, v11, 16, 1
	v_lshrrev_b32_e32 v4, 16, v4
	v_add3_u32 v5, v11, v5, s62
	v_and_or_b32 v4, v5, s63, v4
	v_bfe_u32 v5, v13, 16, 1
	v_add3_u32 v5, v13, v5, s62
	v_bfe_u32 v6, v15, 16, 1
	v_lshrrev_b32_e32 v5, 16, v5
	v_add3_u32 v6, v15, v6, s62
	v_and_or_b32 v5, v6, s63, v5
	v_bfe_u32 v6, v17, 16, 1
	v_add3_u32 v6, v17, v6, s62
	v_bfe_u32 v7, v19, 16, 1
	v_lshrrev_b32_e32 v6, 16, v6
	v_add3_u32 v7, v19, v7, s62
	v_and_or_b32 v6, v7, s63, v6
	v_bfe_u32 v7, v21, 16, 1
	v_add3_u32 v7, v21, v7, s62
	v_lshrrev_b32_e32 v7, 16, v7
	v_and_or_b32 v7, v8, s63, v7
	v_add_u32_e32 v8, s26, v99
	v_ashrrev_i32_e32 v9, 31, v8
	v_lshlrev_b64 v[8:9], 12, v[8:9]
	ds_read2_b32 v[10:11], v83 offset0:16 offset1:24
	v_lshl_add_u64 v[8:9], v[2:3], 0, v[8:9]
	global_store_dwordx4 v[8:9], v[4:7], off sc1
	ds_read2_b32 v[8:9], v83 offset0:81 offset1:89
	ds_read2_b32 v[12:13], v83 offset0:146 offset1:154
	ds_read2_b32 v[14:15], v83 offset0:211 offset1:219
	s_waitcnt lgkmcnt(3)
	v_bfe_u32 v4, v10, 16, 1
	v_add3_u32 v4, v10, v4, s62
	s_waitcnt lgkmcnt(2)
	v_bfe_u32 v5, v8, 16, 1
	ds_read2_b32 v[16:17], v26 offset0:20 offset1:28
	v_lshrrev_b32_e32 v4, 16, v4
	v_add3_u32 v5, v8, v5, s62
	ds_read2_b32 v[18:19], v26 offset0:85 offset1:93
	v_and_or_b32 v4, v5, s63, v4
	s_waitcnt lgkmcnt(3)
	v_bfe_u32 v5, v12, 16, 1
	v_add3_u32 v5, v12, v5, s62
	s_waitcnt lgkmcnt(2)
	v_bfe_u32 v6, v14, 16, 1
	ds_read2_b32 v[20:21], v26 offset0:150 offset1:158
	v_lshrrev_b32_e32 v5, 16, v5
	v_add3_u32 v6, v14, v6, s62
	ds_read2_b32 v[22:23], v26 offset0:215 offset1:223
	v_and_or_b32 v5, v6, s63, v5
	s_waitcnt lgkmcnt(3)
	v_bfe_u32 v6, v16, 16, 1
	v_add3_u32 v6, v16, v6, s62
	s_waitcnt lgkmcnt(2)
	v_bfe_u32 v7, v18, 16, 1
	v_lshrrev_b32_e32 v6, 16, v6
	v_add3_u32 v7, v18, v7, s62
	v_and_or_b32 v6, v7, s63, v6
	s_waitcnt lgkmcnt(1)
	v_bfe_u32 v7, v20, 16, 1
	v_add_u32_e32 v24, s26, v98
	v_add3_u32 v7, v20, v7, s62
	s_waitcnt lgkmcnt(0)
	v_bfe_u32 v8, v22, 16, 1
	v_ashrrev_i32_e32 v25, 31, v24
	v_lshrrev_b32_e32 v7, 16, v7
	v_add3_u32 v8, v22, v8, s62
	v_lshlrev_b64 v[24:25], 12, v[24:25]
	v_and_or_b32 v7, v8, s63, v7
	v_lshl_add_u64 v[24:25], v[2:3], 0, v[24:25]
	global_store_dwordx4 v[24:25], v[4:7], off sc1
	v_bfe_u32 v8, v23, 16, 1
	v_add3_u32 v8, v23, v8, s62
	v_bfe_u32 v4, v11, 16, 1
	v_add3_u32 v4, v11, v4, s62
	v_bfe_u32 v5, v9, 16, 1
	v_lshrrev_b32_e32 v4, 16, v4
	v_add3_u32 v5, v9, v5, s62
	v_and_or_b32 v4, v5, s63, v4
	v_bfe_u32 v5, v13, 16, 1
	v_add3_u32 v5, v13, v5, s62
	v_bfe_u32 v6, v15, 16, 1
	v_lshrrev_b32_e32 v5, 16, v5
	v_add3_u32 v6, v15, v6, s62
	v_and_or_b32 v5, v6, s63, v5
	v_bfe_u32 v6, v17, 16, 1
	v_add3_u32 v6, v17, v6, s62
	v_bfe_u32 v7, v19, 16, 1
	v_lshrrev_b32_e32 v6, 16, v6
	v_add3_u32 v7, v19, v7, s62
	v_and_or_b32 v6, v7, s63, v6
	v_bfe_u32 v7, v21, 16, 1
	v_add3_u32 v7, v21, v7, s62
	v_lshrrev_b32_e32 v7, 16, v7
	v_and_or_b32 v7, v8, s63, v7
	v_add_u32_e32 v8, s26, v97
	v_ashrrev_i32_e32 v9, 31, v8
	v_lshlrev_b64 v[8:9], 12, v[8:9]
	ds_read2_b32 v[10:11], v83 offset0:32 offset1:40
	v_lshl_add_u64 v[8:9], v[2:3], 0, v[8:9]
	global_store_dwordx4 v[8:9], v[4:7], off sc1
	ds_read2_b32 v[8:9], v83 offset0:97 offset1:105
	ds_read2_b32 v[12:13], v83 offset0:162 offset1:170
	ds_read2_b32 v[14:15], v83 offset0:227 offset1:235
	s_waitcnt lgkmcnt(3)
	v_bfe_u32 v4, v10, 16, 1
	v_add3_u32 v4, v10, v4, s62
	s_waitcnt lgkmcnt(2)
	v_bfe_u32 v5, v8, 16, 1
	ds_read2_b32 v[16:17], v26 offset0:36 offset1:44
	v_lshrrev_b32_e32 v4, 16, v4
	v_add3_u32 v5, v8, v5, s62
	ds_read2_b32 v[18:19], v26 offset0:101 offset1:109
	v_and_or_b32 v4, v5, s63, v4
	s_waitcnt lgkmcnt(3)
	v_bfe_u32 v5, v12, 16, 1
	v_add3_u32 v5, v12, v5, s62
	s_waitcnt lgkmcnt(2)
	v_bfe_u32 v6, v14, 16, 1
	ds_read2_b32 v[20:21], v26 offset0:166 offset1:174
	v_lshrrev_b32_e32 v5, 16, v5
	v_add3_u32 v6, v14, v6, s62
	ds_read2_b32 v[22:23], v26 offset0:231 offset1:239
	v_and_or_b32 v5, v6, s63, v5
	s_waitcnt lgkmcnt(3)
	v_bfe_u32 v6, v16, 16, 1
	v_add3_u32 v6, v16, v6, s62
	s_waitcnt lgkmcnt(2)
	v_bfe_u32 v7, v18, 16, 1
	v_lshrrev_b32_e32 v6, 16, v6
	v_add3_u32 v7, v18, v7, s62
	v_and_or_b32 v6, v7, s63, v6
	s_waitcnt lgkmcnt(1)
	v_bfe_u32 v7, v20, 16, 1
	v_add_u32_e32 v24, s26, v96
	v_add3_u32 v7, v20, v7, s62
	s_waitcnt lgkmcnt(0)
	v_bfe_u32 v8, v22, 16, 1
	v_ashrrev_i32_e32 v25, 31, v24
	v_lshrrev_b32_e32 v7, 16, v7
	v_add3_u32 v8, v22, v8, s62
	v_lshlrev_b64 v[24:25], 12, v[24:25]
	v_and_or_b32 v7, v8, s63, v7
	v_lshl_add_u64 v[24:25], v[2:3], 0, v[24:25]
	global_store_dwordx4 v[24:25], v[4:7], off sc1
	v_bfe_u32 v8, v23, 16, 1
	v_add3_u32 v8, v23, v8, s62
	v_bfe_u32 v4, v11, 16, 1
	v_add3_u32 v4, v11, v4, s62
	v_bfe_u32 v5, v9, 16, 1
	v_lshrrev_b32_e32 v4, 16, v4
	v_add3_u32 v5, v9, v5, s62
	v_and_or_b32 v4, v5, s63, v4
	v_bfe_u32 v5, v13, 16, 1
	v_add3_u32 v5, v13, v5, s62
	v_bfe_u32 v6, v15, 16, 1
	v_lshrrev_b32_e32 v5, 16, v5
	v_add3_u32 v6, v15, v6, s62
	v_and_or_b32 v5, v6, s63, v5
	v_bfe_u32 v6, v17, 16, 1
	v_add3_u32 v6, v17, v6, s62
	v_bfe_u32 v7, v19, 16, 1
	v_lshrrev_b32_e32 v6, 16, v6
	v_add3_u32 v7, v19, v7, s62
	v_and_or_b32 v6, v7, s63, v6
	v_bfe_u32 v7, v21, 16, 1
	v_add3_u32 v7, v21, v7, s62
	v_lshrrev_b32_e32 v7, 16, v7
	v_and_or_b32 v7, v8, s63, v7
	v_add_u32_e32 v8, s26, v95
	v_ashrrev_i32_e32 v9, 31, v8
	v_lshlrev_b64 v[8:9], 12, v[8:9]
	ds_read2_b32 v[10:11], v83 offset0:48 offset1:56
	v_lshl_add_u64 v[8:9], v[2:3], 0, v[8:9]
	global_store_dwordx4 v[8:9], v[4:7], off sc1
	ds_read2_b32 v[8:9], v83 offset0:113 offset1:121
	ds_read2_b32 v[12:13], v83 offset0:178 offset1:186
	ds_read2_b32 v[14:15], v83 offset0:243 offset1:251
	s_waitcnt lgkmcnt(3)
	v_bfe_u32 v4, v10, 16, 1
	v_add3_u32 v4, v10, v4, s62
	s_waitcnt lgkmcnt(2)
	v_bfe_u32 v5, v8, 16, 1
	ds_read2_b32 v[16:17], v26 offset0:52 offset1:60
	v_lshrrev_b32_e32 v4, 16, v4
	v_add3_u32 v5, v8, v5, s62
	ds_read2_b32 v[18:19], v26 offset0:117 offset1:125
	v_and_or_b32 v4, v5, s63, v4
	s_waitcnt lgkmcnt(3)
	v_bfe_u32 v5, v12, 16, 1
	v_add3_u32 v5, v12, v5, s62
	s_waitcnt lgkmcnt(2)
	v_bfe_u32 v6, v14, 16, 1
	ds_read2_b32 v[20:21], v26 offset0:182 offset1:190
	v_lshrrev_b32_e32 v5, 16, v5
	v_add3_u32 v6, v14, v6, s62
	ds_read2_b32 v[22:23], v26 offset0:247 offset1:255
	v_and_or_b32 v5, v6, s63, v5
	s_waitcnt lgkmcnt(3)
	v_bfe_u32 v6, v16, 16, 1
	v_add3_u32 v6, v16, v6, s62
	s_waitcnt lgkmcnt(2)
	v_bfe_u32 v7, v18, 16, 1
	v_lshrrev_b32_e32 v6, 16, v6
	v_add3_u32 v7, v18, v7, s62
	v_and_or_b32 v6, v7, s63, v6
	s_waitcnt lgkmcnt(1)
	v_bfe_u32 v7, v20, 16, 1
	v_add_u32_e32 v24, s26, v94
	v_add3_u32 v7, v20, v7, s62
	s_waitcnt lgkmcnt(0)
	v_bfe_u32 v8, v22, 16, 1
	v_ashrrev_i32_e32 v25, 31, v24
	v_lshrrev_b32_e32 v7, 16, v7
	v_add3_u32 v8, v22, v8, s62
	v_lshlrev_b64 v[24:25], 12, v[24:25]
	v_and_or_b32 v7, v8, s63, v7
	v_lshl_add_u64 v[24:25], v[2:3], 0, v[24:25]
	global_store_dwordx4 v[24:25], v[4:7], off sc1
	v_bfe_u32 v8, v23, 16, 1
	v_add3_u32 v8, v23, v8, s62
	v_bfe_u32 v4, v11, 16, 1
	v_add3_u32 v4, v11, v4, s62
	v_bfe_u32 v5, v9, 16, 1
	v_lshrrev_b32_e32 v4, 16, v4
	v_add3_u32 v5, v9, v5, s62
	v_and_or_b32 v4, v5, s63, v4
	v_bfe_u32 v5, v13, 16, 1
	v_add3_u32 v5, v13, v5, s62
	v_bfe_u32 v6, v15, 16, 1
	v_lshrrev_b32_e32 v5, 16, v5
	v_add3_u32 v6, v15, v6, s62
	v_and_or_b32 v5, v6, s63, v5
	v_bfe_u32 v6, v17, 16, 1
	v_add3_u32 v6, v17, v6, s62
	v_bfe_u32 v7, v19, 16, 1
	v_lshrrev_b32_e32 v6, 16, v6
	v_add3_u32 v7, v19, v7, s62
	v_and_or_b32 v6, v7, s63, v6
	v_bfe_u32 v7, v21, 16, 1
	v_add3_u32 v7, v21, v7, s62
	v_lshrrev_b32_e32 v7, 16, v7
	v_and_or_b32 v7, v8, s63, v7
	v_add_u32_e32 v8, s26, v93
	v_ashrrev_i32_e32 v9, 31, v8
	v_lshlrev_b64 v[8:9], 12, v[8:9]
	v_lshl_add_u64 v[2:3], v[2:3], 0, v[8:9]
	global_store_dwordx4 v[2:3], v[4:7], off sc1
	s_waitcnt lgkmcnt(0)
	s_mov_b64 s[0:1], 0
.LBB0_96:
	s_and_b64 vcc, exec, s[0:1]
	s_cbranch_vccz .LBB0_98
	s_add_i32 s0, s65, 0x100
	s_and_b32 s2, s0, 0xffffffc0
	s_add_i32 s0, s80, 0xffec2000
	s_and_b32 s0, s0, 0xfc0
	v_or_b32_e32 v68, s2, v80
	v_or_b32_e32 v4, s0, v67
	v_lshlrev_b64 v[2:3], 14, v[68:69]
	v_lshl_add_u64 v[2:3], s[20:21], 0, v[2:3]
	v_lshlrev_b32_e32 v68, 2, v4
	v_lshl_add_u64 v[62:63], v[2:3], 0, v[68:69]
	v_add_co_u32_e32 v6, vcc, 0x10000, v62
	s_mov_b32 s1, 0x30000
	s_nop 0
	v_addc_co_u32_e32 v7, vcc, 0, v63, vcc
	v_add_co_u32_e32 v10, vcc, 0x20000, v62
	global_load_dwordx4 v[2:5], v[62:63], off nt
	s_nop 0
	global_load_dwordx4 v[6:9], v[6:7], off nt
	v_addc_co_u32_e32 v11, vcc, 0, v63, vcc
	v_add_co_u32_e32 v14, vcc, s1, v62
	s_mov_b32 s1, 0x60000
	s_nop 0
	v_addc_co_u32_e32 v15, vcc, 0, v63, vcc
	global_load_dwordx4 v[10:13], v[10:11], off nt
	s_nop 0
	global_load_dwordx4 v[14:17], v[14:15], off nt
	v_add_co_u32_e32 v18, vcc, 0x40000, v62
	s_nop 1
	v_addc_co_u32_e32 v19, vcc, 0, v63, vcc
	v_add_co_u32_e32 v22, vcc, 0x50000, v62
	s_nop 1
	v_addc_co_u32_e32 v23, vcc, 0, v63, vcc
	global_load_dwordx4 v[18:21], v[18:19], off nt
	s_nop 0
	global_load_dwordx4 v[22:25], v[22:23], off nt
	v_add_co_u32_e32 v26, vcc, s1, v62
	s_mov_b32 s1, 0x90000
	s_nop 0
	v_addc_co_u32_e32 v27, vcc, 0, v63, vcc
	v_add_co_u32_e32 v30, vcc, 0x70000, v62
	s_nop 1
	v_addc_co_u32_e32 v31, vcc, 0, v63, vcc
	global_load_dwordx4 v[26:29], v[26:27], off nt
	s_nop 0
	global_load_dwordx4 v[30:33], v[30:31], off nt
	v_add_co_u32_e32 v34, vcc, 0x80000, v62
	s_nop 1
	v_addc_co_u32_e32 v35, vcc, 0, v63, vcc
	v_add_co_u32_e32 v38, vcc, s1, v62
	s_mov_b32 s1, 0xc0000
	s_nop 0
	v_addc_co_u32_e32 v39, vcc, 0, v63, vcc
	global_load_dwordx4 v[34:37], v[34:35], off nt
	s_nop 0
	global_load_dwordx4 v[38:41], v[38:39], off nt
	v_add_co_u32_e32 v42, vcc, 0xa0000, v62
	s_nop 1
	v_addc_co_u32_e32 v43, vcc, 0, v63, vcc
	v_add_co_u32_e32 v46, vcc, 0xb0000, v62
	s_nop 1
	v_addc_co_u32_e32 v47, vcc, 0, v63, vcc
	global_load_dwordx4 v[42:45], v[42:43], off nt
	s_nop 0
	global_load_dwordx4 v[46:49], v[46:47], off nt
	v_add_co_u32_e32 v50, vcc, s1, v62
	s_mov_b32 s1, 0xf0000
	s_nop 0
	v_addc_co_u32_e32 v51, vcc, 0, v63, vcc
	v_add_co_u32_e32 v54, vcc, 0xd0000, v62
	s_nop 1
	v_addc_co_u32_e32 v55, vcc, 0, v63, vcc
	global_load_dwordx4 v[50:53], v[50:51], off nt
	s_nop 0
	global_load_dwordx4 v[54:57], v[54:55], off nt
	v_add_co_u32_e32 v58, vcc, 0xe0000, v62
	s_nop 1
	v_addc_co_u32_e32 v59, vcc, 0, v63, vcc
	global_load_dwordx4 v[58:61], v[58:59], off nt
	v_add_co_u32_e32 v62, vcc, s1, v62
	s_nop 1
	v_addc_co_u32_e32 v63, vcc, 0, v63, vcc
	global_load_dwordx4 v[62:65], v[62:63], off nt
	s_waitcnt vmcnt(15)
	ds_write2_b32 v81, v2, v3 offset1:1
	ds_write2_b32 v81, v4, v5 offset0:2 offset1:3
	v_add_u32_e32 v2, 0x410, v81
	s_waitcnt vmcnt(14)
	ds_write2_b32 v2, v6, v7 offset1:1
	v_add_u32_e32 v2, 0x418, v81
	ds_write2_b32 v2, v8, v9 offset1:1
	v_add_u32_e32 v2, 0x820, v81
	s_waitcnt vmcnt(13)
	ds_write2_b32 v2, v10, v11 offset1:1
	v_add_u32_e32 v2, 0x828, v81
	ds_write2_b32 v2, v12, v13 offset1:1
	v_add_u32_e32 v2, 0xc30, v81
	s_waitcnt vmcnt(12)
	ds_write2_b32 v2, v14, v15 offset1:1
	v_add_u32_e32 v2, 0xc38, v81
	ds_write2_b32 v2, v16, v17 offset1:1
	v_add_u32_e32 v2, 0x1040, v81
	s_waitcnt vmcnt(11)
	ds_write2_b32 v2, v18, v19 offset1:1
	v_add_u32_e32 v2, 0x1048, v81
	ds_write2_b32 v2, v20, v21 offset1:1
	v_add_u32_e32 v2, 0x1450, v81
	s_waitcnt vmcnt(10)
	ds_write2_b32 v2, v22, v23 offset1:1
	v_add_u32_e32 v2, 0x1458, v81
	ds_write2_b32 v2, v24, v25 offset1:1
	v_add_u32_e32 v2, 0x1860, v81
	s_waitcnt vmcnt(9)
	ds_write2_b32 v2, v26, v27 offset1:1
	v_add_u32_e32 v2, 0x1868, v81
	ds_write2_b32 v2, v28, v29 offset1:1
	v_add_u32_e32 v2, 0x1c70, v81
	s_waitcnt vmcnt(8)
	ds_write2_b32 v2, v30, v31 offset1:1
	v_add_u32_e32 v2, 0x1c78, v81
	ds_write2_b32 v2, v32, v33 offset1:1
	v_add_u32_e32 v2, 0x2080, v81
	v_add_u32_e32 v26, 0x400, v83
	s_waitcnt vmcnt(7)
	ds_write2_b32 v2, v34, v35 offset1:1
	v_add_u32_e32 v2, 0x2088, v81
	ds_write2_b32 v2, v36, v37 offset1:1
	v_add_u32_e32 v2, 0x2490, v81
	s_waitcnt vmcnt(6)
	ds_write2_b32 v2, v38, v39 offset1:1
	v_add_u32_e32 v2, 0x2498, v81
	ds_write2_b32 v2, v40, v41 offset1:1
	v_add_u32_e32 v2, 0x28a0, v81
	s_waitcnt vmcnt(5)
	ds_write2_b32 v2, v42, v43 offset1:1
	v_add_u32_e32 v2, 0x28a8, v81
	ds_write2_b32 v2, v44, v45 offset1:1
	v_add_u32_e32 v2, 0x2cb0, v81
	s_waitcnt vmcnt(4)
	ds_write2_b32 v2, v46, v47 offset1:1
	v_add_u32_e32 v2, 0x2cb8, v81
	ds_write2_b32 v2, v48, v49 offset1:1
	v_add_u32_e32 v2, 0x30c0, v81
	s_waitcnt vmcnt(3)
	ds_write2_b32 v2, v50, v51 offset1:1
	v_add_u32_e32 v2, 0x30c8, v81
	ds_write2_b32 v2, v52, v53 offset1:1
	v_add_u32_e32 v2, 0x34d0, v81
	s_waitcnt vmcnt(2)
	ds_write2_b32 v2, v54, v55 offset1:1
	v_add_u32_e32 v2, 0x34d8, v81
	ds_write2_b32 v2, v56, v57 offset1:1
	v_add_u32_e32 v2, 0x38e0, v81
	s_waitcnt vmcnt(1)
	ds_write2_b32 v2, v58, v59 offset1:1
	v_add_u32_e32 v2, 0x38e8, v81
	ds_write2_b32 v2, v60, v61 offset1:1
	v_add_u32_e32 v2, 0x3cf0, v81
	s_waitcnt vmcnt(0)
	ds_write2_b32 v2, v62, v63 offset1:1
	v_add_u32_e32 v2, 0x3cf8, v81
	ds_write2_b32 v2, v64, v65 offset1:1
	s_waitcnt lgkmcnt(0)
	ds_read2_b32 v[8:9], v83 offset1:8
	ds_read2_b32 v[10:11], v83 offset0:65 offset1:73
	ds_read2_b32 v[12:13], v83 offset0:130 offset1:138
	ds_read2_b32 v[14:15], v83 offset0:195 offset1:203
	ds_read2_b32 v[16:17], v26 offset0:4 offset1:12
	s_waitcnt lgkmcnt(4)
	v_bfe_u32 v4, v8, 16, 1
	v_add3_u32 v4, v8, v4, s62
	s_waitcnt lgkmcnt(3)
	v_bfe_u32 v5, v10, 16, 1
	v_lshrrev_b32_e32 v4, 16, v4
	v_add3_u32 v5, v10, v5, s62
	ds_read2_b32 v[18:19], v26 offset0:69 offset1:77
	v_and_or_b32 v4, v5, s63, v4
	s_waitcnt lgkmcnt(3)
	v_bfe_u32 v5, v12, 16, 1
	v_add3_u32 v5, v12, v5, s62
	s_waitcnt lgkmcnt(2)
	v_bfe_u32 v6, v14, 16, 1
	ds_read2_b32 v[20:21], v26 offset0:134 offset1:142
	v_lshrrev_b32_e32 v5, 16, v5
	v_add3_u32 v6, v14, v6, s62
	ds_read2_b32 v[22:23], v26 offset0:199 offset1:207
	v_and_or_b32 v5, v6, s63, v5
	s_waitcnt lgkmcnt(3)
	v_bfe_u32 v6, v16, 16, 1
	v_add3_u32 v6, v16, v6, s62
	s_waitcnt lgkmcnt(2)
	v_bfe_u32 v7, v18, 16, 1
	v_lshrrev_b32_e32 v6, 16, v6
	v_add3_u32 v7, v18, v7, s62
	v_and_or_b32 v6, v7, s63, v6
	s_waitcnt lgkmcnt(1)
	v_bfe_u32 v7, v20, 16, 1
	v_add3_u32 v7, v20, v7, s62
	s_waitcnt lgkmcnt(0)
	v_bfe_u32 v8, v22, 16, 1
	v_lshrrev_b32_e32 v7, 16, v7
	v_add3_u32 v8, v22, v8, s62
	v_and_or_b32 v7, v8, s63, v7
	v_or_b32_e32 v8, s0, v82
	v_lshl_add_u64 v[2:3], s[2:3], 1, v[72:73]
	v_lshlrev_b32_e32 v68, 9, v8
	v_lshl_add_u64 v[24:25], v[2:3], 0, v[68:69]
	global_store_dwordx4 v[24:25], v[4:7], off sc1
	v_bfe_u32 v8, v23, 16, 1
	v_or_b32_e32 v10, s0, v84
	v_bfe_u32 v4, v9, 16, 1
	v_add3_u32 v4, v9, v4, s62
	v_bfe_u32 v5, v11, 16, 1
	v_lshrrev_b32_e32 v4, 16, v4
	v_add3_u32 v5, v11, v5, s62
	v_and_or_b32 v4, v5, s63, v4
	v_bfe_u32 v5, v13, 16, 1
	v_add3_u32 v5, v13, v5, s62
	v_bfe_u32 v6, v15, 16, 1
	v_lshrrev_b32_e32 v5, 16, v5
	v_add3_u32 v6, v15, v6, s62
	v_and_or_b32 v5, v6, s63, v5
	v_bfe_u32 v6, v17, 16, 1
	v_add3_u32 v6, v17, v6, s62
	v_bfe_u32 v7, v19, 16, 1
	v_lshrrev_b32_e32 v6, 16, v6
	v_add3_u32 v7, v19, v7, s62
	v_and_or_b32 v6, v7, s63, v6
	v_bfe_u32 v7, v21, 16, 1
	v_add3_u32 v7, v21, v7, s62
	v_lshrrev_b32_e32 v7, 16, v7
	v_add3_u32 v8, v23, v8, s62
	v_lshlrev_b32_e32 v68, 9, v10
	v_and_or_b32 v7, v8, s63, v7
	ds_read2_b32 v[8:9], v83 offset0:16 offset1:24
	v_lshl_add_u64 v[10:11], v[2:3], 0, v[68:69]
	global_store_dwordx4 v[10:11], v[4:7], off sc1
	ds_read2_b32 v[10:11], v83 offset0:81 offset1:89
	ds_read2_b32 v[12:13], v83 offset0:146 offset1:154
	ds_read2_b32 v[14:15], v83 offset0:211 offset1:219
	s_waitcnt lgkmcnt(3)
	v_bfe_u32 v4, v8, 16, 1
	v_add3_u32 v4, v8, v4, s62
	s_waitcnt lgkmcnt(2)
	v_bfe_u32 v5, v10, 16, 1
	ds_read2_b32 v[16:17], v26 offset0:20 offset1:28
	v_lshrrev_b32_e32 v4, 16, v4
	v_add3_u32 v5, v10, v5, s62
	ds_read2_b32 v[18:19], v26 offset0:85 offset1:93
	v_and_or_b32 v4, v5, s63, v4
	s_waitcnt lgkmcnt(3)
	v_bfe_u32 v5, v12, 16, 1
	v_add3_u32 v5, v12, v5, s62
	s_waitcnt lgkmcnt(2)
	v_bfe_u32 v6, v14, 16, 1
	ds_read2_b32 v[20:21], v26 offset0:150 offset1:158
	v_lshrrev_b32_e32 v5, 16, v5
	v_add3_u32 v6, v14, v6, s62
	ds_read2_b32 v[22:23], v26 offset0:215 offset1:223
	v_and_or_b32 v5, v6, s63, v5
	s_waitcnt lgkmcnt(3)
	v_bfe_u32 v6, v16, 16, 1
	v_add3_u32 v6, v16, v6, s62
	s_waitcnt lgkmcnt(2)
	v_bfe_u32 v7, v18, 16, 1
	v_lshrrev_b32_e32 v6, 16, v6
	v_add3_u32 v7, v18, v7, s62
	v_and_or_b32 v6, v7, s63, v6
	s_waitcnt lgkmcnt(1)
	v_bfe_u32 v7, v20, 16, 1
	v_add3_u32 v7, v20, v7, s62
	s_waitcnt lgkmcnt(0)
	v_bfe_u32 v8, v22, 16, 1
	v_lshrrev_b32_e32 v7, 16, v7
	v_add3_u32 v8, v22, v8, s62
	v_and_or_b32 v7, v8, s63, v7
	v_or_b32_e32 v8, s0, v85
	v_lshlrev_b32_e32 v68, 9, v8
	v_lshl_add_u64 v[24:25], v[2:3], 0, v[68:69]
	global_store_dwordx4 v[24:25], v[4:7], off sc1
	v_bfe_u32 v8, v23, 16, 1
	v_or_b32_e32 v10, s0, v86
	v_bfe_u32 v4, v9, 16, 1
	v_add3_u32 v4, v9, v4, s62
	v_bfe_u32 v5, v11, 16, 1
	v_lshrrev_b32_e32 v4, 16, v4
	v_add3_u32 v5, v11, v5, s62
	v_and_or_b32 v4, v5, s63, v4
	v_bfe_u32 v5, v13, 16, 1
	v_add3_u32 v5, v13, v5, s62
	v_bfe_u32 v6, v15, 16, 1
	v_lshrrev_b32_e32 v5, 16, v5
	v_add3_u32 v6, v15, v6, s62
	v_and_or_b32 v5, v6, s63, v5
	v_bfe_u32 v6, v17, 16, 1
	v_add3_u32 v6, v17, v6, s62
	v_bfe_u32 v7, v19, 16, 1
	v_lshrrev_b32_e32 v6, 16, v6
	v_add3_u32 v7, v19, v7, s62
	v_and_or_b32 v6, v7, s63, v6
	v_bfe_u32 v7, v21, 16, 1
	v_add3_u32 v7, v21, v7, s62
	v_lshrrev_b32_e32 v7, 16, v7
	v_add3_u32 v8, v23, v8, s62
	v_lshlrev_b32_e32 v68, 9, v10
	v_and_or_b32 v7, v8, s63, v7
	ds_read2_b32 v[8:9], v83 offset0:32 offset1:40
	v_lshl_add_u64 v[10:11], v[2:3], 0, v[68:69]
	global_store_dwordx4 v[10:11], v[4:7], off sc1
	ds_read2_b32 v[10:11], v83 offset0:97 offset1:105
	ds_read2_b32 v[12:13], v83 offset0:162 offset1:170
	ds_read2_b32 v[14:15], v83 offset0:227 offset1:235
	s_waitcnt lgkmcnt(3)
	v_bfe_u32 v4, v8, 16, 1
	v_add3_u32 v4, v8, v4, s62
	s_waitcnt lgkmcnt(2)
	v_bfe_u32 v5, v10, 16, 1
	ds_read2_b32 v[16:17], v26 offset0:36 offset1:44
	v_lshrrev_b32_e32 v4, 16, v4
	v_add3_u32 v5, v10, v5, s62
	ds_read2_b32 v[18:19], v26 offset0:101 offset1:109
	v_and_or_b32 v4, v5, s63, v4
	s_waitcnt lgkmcnt(3)
	v_bfe_u32 v5, v12, 16, 1
	v_add3_u32 v5, v12, v5, s62
	s_waitcnt lgkmcnt(2)
	v_bfe_u32 v6, v14, 16, 1
	ds_read2_b32 v[20:21], v26 offset0:166 offset1:174
	v_lshrrev_b32_e32 v5, 16, v5
	v_add3_u32 v6, v14, v6, s62
	ds_read2_b32 v[22:23], v26 offset0:231 offset1:239
	v_and_or_b32 v5, v6, s63, v5
	s_waitcnt lgkmcnt(3)
	v_bfe_u32 v6, v16, 16, 1
	v_add3_u32 v6, v16, v6, s62
	s_waitcnt lgkmcnt(2)
	v_bfe_u32 v7, v18, 16, 1
	v_lshrrev_b32_e32 v6, 16, v6
	v_add3_u32 v7, v18, v7, s62
	v_and_or_b32 v6, v7, s63, v6
	s_waitcnt lgkmcnt(1)
	v_bfe_u32 v7, v20, 16, 1
	v_add3_u32 v7, v20, v7, s62
	s_waitcnt lgkmcnt(0)
	v_bfe_u32 v8, v22, 16, 1
	v_lshrrev_b32_e32 v7, 16, v7
	v_add3_u32 v8, v22, v8, s62
	v_and_or_b32 v7, v8, s63, v7
	v_or_b32_e32 v8, s0, v87
	v_lshlrev_b32_e32 v68, 9, v8
	v_lshl_add_u64 v[24:25], v[2:3], 0, v[68:69]
	global_store_dwordx4 v[24:25], v[4:7], off sc1
	v_bfe_u32 v8, v23, 16, 1
	v_or_b32_e32 v10, s0, v88
	v_bfe_u32 v4, v9, 16, 1
	v_add3_u32 v4, v9, v4, s62
	v_bfe_u32 v5, v11, 16, 1
	v_lshrrev_b32_e32 v4, 16, v4
	v_add3_u32 v5, v11, v5, s62
	v_and_or_b32 v4, v5, s63, v4
	v_bfe_u32 v5, v13, 16, 1
	v_add3_u32 v5, v13, v5, s62
	v_bfe_u32 v6, v15, 16, 1
	v_lshrrev_b32_e32 v5, 16, v5
	v_add3_u32 v6, v15, v6, s62
	v_and_or_b32 v5, v6, s63, v5
	v_bfe_u32 v6, v17, 16, 1
	v_add3_u32 v6, v17, v6, s62
	v_bfe_u32 v7, v19, 16, 1
	v_lshrrev_b32_e32 v6, 16, v6
	v_add3_u32 v7, v19, v7, s62
	v_and_or_b32 v6, v7, s63, v6
	v_bfe_u32 v7, v21, 16, 1
	v_add3_u32 v7, v21, v7, s62
	v_lshrrev_b32_e32 v7, 16, v7
	v_add3_u32 v8, v23, v8, s62
	v_lshlrev_b32_e32 v68, 9, v10
	v_and_or_b32 v7, v8, s63, v7
	ds_read2_b32 v[8:9], v83 offset0:48 offset1:56
	v_lshl_add_u64 v[10:11], v[2:3], 0, v[68:69]
	global_store_dwordx4 v[10:11], v[4:7], off sc1
	ds_read2_b32 v[10:11], v83 offset0:113 offset1:121
	ds_read2_b32 v[12:13], v83 offset0:178 offset1:186
	ds_read2_b32 v[14:15], v83 offset0:243 offset1:251
	s_waitcnt lgkmcnt(3)
	v_bfe_u32 v4, v8, 16, 1
	v_add3_u32 v4, v8, v4, s62
	s_waitcnt lgkmcnt(2)
	v_bfe_u32 v5, v10, 16, 1
	ds_read2_b32 v[16:17], v26 offset0:52 offset1:60
	v_lshrrev_b32_e32 v4, 16, v4
	v_add3_u32 v5, v10, v5, s62
	ds_read2_b32 v[18:19], v26 offset0:117 offset1:125
	v_and_or_b32 v4, v5, s63, v4
	s_waitcnt lgkmcnt(3)
	v_bfe_u32 v5, v12, 16, 1
	v_add3_u32 v5, v12, v5, s62
	s_waitcnt lgkmcnt(2)
	v_bfe_u32 v6, v14, 16, 1
	ds_read2_b32 v[20:21], v26 offset0:182 offset1:190
	v_lshrrev_b32_e32 v5, 16, v5
	v_add3_u32 v6, v14, v6, s62
	ds_read2_b32 v[22:23], v26 offset0:247 offset1:255
	v_and_or_b32 v5, v6, s63, v5
	s_waitcnt lgkmcnt(3)
	v_bfe_u32 v6, v16, 16, 1
	v_add3_u32 v6, v16, v6, s62
	s_waitcnt lgkmcnt(2)
	v_bfe_u32 v7, v18, 16, 1
	v_lshrrev_b32_e32 v6, 16, v6
	v_add3_u32 v7, v18, v7, s62
	v_and_or_b32 v6, v7, s63, v6
	s_waitcnt lgkmcnt(1)
	v_bfe_u32 v7, v20, 16, 1
	v_add3_u32 v7, v20, v7, s62
	s_waitcnt lgkmcnt(0)
	v_bfe_u32 v8, v22, 16, 1
	v_lshrrev_b32_e32 v7, 16, v7
	v_add3_u32 v8, v22, v8, s62
	v_and_or_b32 v7, v8, s63, v7
	v_or_b32_e32 v8, s0, v89
	v_lshlrev_b32_e32 v68, 9, v8
	v_lshl_add_u64 v[24:25], v[2:3], 0, v[68:69]
	global_store_dwordx4 v[24:25], v[4:7], off sc1
	v_bfe_u32 v8, v23, 16, 1
	v_add3_u32 v8, v23, v8, s62
	v_bfe_u32 v4, v9, 16, 1
	v_add3_u32 v4, v9, v4, s62
	v_bfe_u32 v5, v11, 16, 1
	v_lshrrev_b32_e32 v4, 16, v4
	v_add3_u32 v5, v11, v5, s62
	v_and_or_b32 v4, v5, s63, v4
	v_bfe_u32 v5, v13, 16, 1
	v_add3_u32 v5, v13, v5, s62
	v_bfe_u32 v6, v15, 16, 1
	v_lshrrev_b32_e32 v5, 16, v5
	v_add3_u32 v6, v15, v6, s62
	v_and_or_b32 v5, v6, s63, v5
	v_bfe_u32 v6, v17, 16, 1
	v_add3_u32 v6, v17, v6, s62
	v_bfe_u32 v7, v19, 16, 1
	v_lshrrev_b32_e32 v6, 16, v6
	v_add3_u32 v7, v19, v7, s62
	v_and_or_b32 v6, v7, s63, v6
	v_bfe_u32 v7, v21, 16, 1
	v_add3_u32 v7, v21, v7, s62
	v_lshrrev_b32_e32 v7, 16, v7
	v_and_or_b32 v7, v8, s63, v7
	v_or_b32_e32 v8, s0, v90
	v_lshlrev_b32_e32 v68, 9, v8
	v_lshl_add_u64 v[2:3], v[2:3], 0, v[68:69]
	global_store_dwordx4 v[2:3], v[4:7], off sc1
	s_waitcnt lgkmcnt(0)

.LBB0_134:
	s_or_b64 exec, exec, s[26:27]
	s_waitcnt vmcnt(0)
	ds_write2_b32 v81, v2, v3 offset1:1
	ds_write2_b32 v81, v4, v5 offset0:2 offset1:3
	v_add_u32_e32 v2, 0x410, v81
	ds_write2_b32 v2, v6, v7 offset1:1
	v_add_u32_e32 v2, 0x418, v81
	ds_write2_b32 v2, v8, v9 offset1:1
	v_add_u32_e32 v2, 0x820, v81
	ds_write2_b32 v2, v14, v15 offset1:1
	v_add_u32_e32 v2, 0x828, v81
	ds_write2_b32 v2, v16, v17 offset1:1
	v_add_u32_e32 v2, 0xc30, v81
	ds_write2_b32 v2, v10, v11 offset1:1
	v_add_u32_e32 v2, 0xc38, v81
	ds_write2_b32 v2, v12, v13 offset1:1
	v_add_u32_e32 v2, 0x1040, v81
	ds_write2_b32 v2, v22, v23 offset1:1
	v_add_u32_e32 v2, 0x1048, v81
	ds_write2_b32 v2, v24, v25 offset1:1
	v_add_u32_e32 v2, 0x1450, v81
	ds_write2_b32 v2, v18, v19 offset1:1
	v_add_u32_e32 v2, 0x1458, v81
	ds_write2_b32 v2, v20, v21 offset1:1
	v_add_u32_e32 v2, 0x1860, v81
	ds_write2_b32 v2, v30, v31 offset1:1
	v_add_u32_e32 v2, 0x1868, v81
	ds_write2_b32 v2, v32, v33 offset1:1
	v_add_u32_e32 v2, 0x1c70, v81
	ds_write2_b32 v2, v26, v27 offset1:1
	v_add_u32_e32 v2, 0x1c78, v81
	ds_write2_b32 v2, v28, v29 offset1:1
	v_add_u32_e32 v2, 0x2080, v81
	ds_write2_b32 v2, v38, v39 offset1:1
	v_add_u32_e32 v2, 0x2088, v81
	ds_write2_b32 v2, v40, v41 offset1:1
	v_add_u32_e32 v2, 0x2490, v81
	ds_write2_b32 v2, v34, v35 offset1:1
	v_add_u32_e32 v2, 0x2498, v81
	ds_write2_b32 v2, v36, v37 offset1:1
	v_add_u32_e32 v2, 0x28a0, v81
	ds_write2_b32 v2, v46, v47 offset1:1
	v_add_u32_e32 v2, 0x28a8, v81
	ds_write2_b32 v2, v48, v49 offset1:1
	v_add_u32_e32 v2, 0x2cb0, v81
	ds_write2_b32 v2, v42, v43 offset1:1
	v_add_u32_e32 v2, 0x2cb8, v81
	ds_write2_b32 v2, v44, v45 offset1:1
	v_add_u32_e32 v2, 0x30c0, v81
	ds_write2_b32 v2, v54, v55 offset1:1
	v_add_u32_e32 v2, 0x30c8, v81
	ds_write2_b32 v2, v56, v57 offset1:1
	v_add_u32_e32 v2, 0x34d0, v81
	ds_write2_b32 v2, v50, v51 offset1:1
	v_add_u32_e32 v2, 0x34d8, v81
	ds_write2_b32 v2, v52, v53 offset1:1
	v_add_u32_e32 v2, 0x38e0, v81
	ds_write2_b32 v2, v62, v63 offset1:1
	v_add_u32_e32 v2, 0x38e8, v81
	ds_write2_b32 v2, v64, v65 offset1:1
	v_add_u32_e32 v2, 0x3cf0, v81
	ds_write2_b32 v2, v58, v59 offset1:1
	v_add_u32_e32 v2, 0x3cf8, v81
	ds_write2_b32 v2, v60, v61 offset1:1
	s_waitcnt lgkmcnt(0)
	ds_read2_b32 v[8:9], v83 offset1:8
	ds_read2_b32 v[10:11], v83 offset0:65 offset1:73
	ds_read2_b32 v[12:13], v83 offset0:130 offset1:138
	ds_read2_b32 v[14:15], v83 offset0:195 offset1:203
	v_add_u32_e32 v26, 0x400, v83
	s_waitcnt lgkmcnt(3)
	v_bfe_u32 v4, v8, 16, 1
	v_add3_u32 v4, v8, v4, s62
	s_waitcnt lgkmcnt(2)
	v_bfe_u32 v5, v10, 16, 1
	ds_read2_b32 v[16:17], v26 offset0:4 offset1:12
	v_lshrrev_b32_e32 v4, 16, v4
	v_add3_u32 v5, v10, v5, s62
	ds_read2_b32 v[18:19], v26 offset0:69 offset1:77
	v_and_or_b32 v4, v5, s63, v4
	s_waitcnt lgkmcnt(3)
	v_bfe_u32 v5, v12, 16, 1
	v_add3_u32 v5, v12, v5, s62
	s_waitcnt lgkmcnt(2)
	v_bfe_u32 v6, v14, 16, 1
	ds_read2_b32 v[20:21], v26 offset0:134 offset1:142
	v_lshrrev_b32_e32 v5, 16, v5
	v_add3_u32 v6, v14, v6, s62
	ds_read2_b32 v[22:23], v26 offset0:199 offset1:207
	v_and_or_b32 v5, v6, s63, v5
	s_waitcnt lgkmcnt(3)
	v_bfe_u32 v6, v16, 16, 1
	v_add3_u32 v6, v16, v6, s62
	s_waitcnt lgkmcnt(2)
	v_bfe_u32 v7, v18, 16, 1
	v_lshrrev_b32_e32 v6, 16, v6
	v_add3_u32 v7, v18, v7, s62
	v_and_or_b32 v6, v7, s63, v6
	s_waitcnt lgkmcnt(1)
	v_bfe_u32 v7, v20, 16, 1
	v_add_u32_e32 v24, s30, v109
	s_lshl_b32 s2, s2, 1
	v_add3_u32 v7, v20, v7, s62
	s_waitcnt lgkmcnt(0)
	v_bfe_u32 v8, v22, 16, 1
	v_ashrrev_i32_e32 v25, 31, v24
	v_lshl_add_u64 v[2:3], v[74:75], 0, s[2:3]
	v_lshrrev_b32_e32 v7, 16, v7
	v_add3_u32 v8, v22, v8, s62
	v_lshlrev_b64 v[24:25], 10, v[24:25]
	v_and_or_b32 v7, v8, s63, v7
	v_lshl_add_u64 v[24:25], v[2:3], 0, v[24:25]
	global_store_dwordx4 v[24:25], v[4:7], off sc1
	v_bfe_u32 v8, v23, 16, 1
	v_add3_u32 v8, v23, v8, s62
	v_bfe_u32 v4, v9, 16, 1
	v_add3_u32 v4, v9, v4, s62
	v_bfe_u32 v5, v11, 16, 1
	v_lshrrev_b32_e32 v4, 16, v4
	v_add3_u32 v5, v11, v5, s62
	v_and_or_b32 v4, v5, s63, v4
	v_bfe_u32 v5, v13, 16, 1
	v_add3_u32 v5, v13, v5, s62
	v_bfe_u32 v6, v15, 16, 1
	v_lshrrev_b32_e32 v5, 16, v5
	v_add3_u32 v6, v15, v6, s62
	v_and_or_b32 v5, v6, s63, v5
	v_bfe_u32 v6, v17, 16, 1
	v_add3_u32 v6, v17, v6, s62
	v_bfe_u32 v7, v19, 16, 1
	v_lshrrev_b32_e32 v6, 16, v6
	v_add3_u32 v7, v19, v7, s62
	v_and_or_b32 v6, v7, s63, v6
	v_bfe_u32 v7, v21, 16, 1
	v_add3_u32 v7, v21, v7, s62
	v_lshrrev_b32_e32 v7, 16, v7
	v_and_or_b32 v7, v8, s63, v7
	v_add_u32_e32 v8, s30, v108
	v_ashrrev_i32_e32 v9, 31, v8
	v_lshlrev_b64 v[8:9], 10, v[8:9]
	ds_read2_b32 v[10:11], v83 offset0:16 offset1:24
	v_lshl_add_u64 v[8:9], v[2:3], 0, v[8:9]
	global_store_dwordx4 v[8:9], v[4:7], off sc1
	ds_read2_b32 v[8:9], v83 offset0:81 offset1:89
	ds_read2_b32 v[12:13], v83 offset0:146 offset1:154
	ds_read2_b32 v[14:15], v83 offset0:211 offset1:219
	s_waitcnt lgkmcnt(3)
	v_bfe_u32 v4, v10, 16, 1
	v_add3_u32 v4, v10, v4, s62
	s_waitcnt lgkmcnt(2)
	v_bfe_u32 v5, v8, 16, 1
	ds_read2_b32 v[16:17], v26 offset0:20 offset1:28
	v_lshrrev_b32_e32 v4, 16, v4
	v_add3_u32 v5, v8, v5, s62
	ds_read2_b32 v[18:19], v26 offset0:85 offset1:93
	v_and_or_b32 v4, v5, s63, v4
	s_waitcnt lgkmcnt(3)
	v_bfe_u32 v5, v12, 16, 1
	v_add3_u32 v5, v12, v5, s62
	s_waitcnt lgkmcnt(2)
	v_bfe_u32 v6, v14, 16, 1
	ds_read2_b32 v[20:21], v26 offset0:150 offset1:158
	v_lshrrev_b32_e32 v5, 16, v5
	v_add3_u32 v6, v14, v6, s62
	ds_read2_b32 v[22:23], v26 offset0:215 offset1:223
	v_and_or_b32 v5, v6, s63, v5
	s_waitcnt lgkmcnt(3)
	v_bfe_u32 v6, v16, 16, 1
	v_add3_u32 v6, v16, v6, s62
	s_waitcnt lgkmcnt(2)
	v_bfe_u32 v7, v18, 16, 1
	v_lshrrev_b32_e32 v6, 16, v6
	v_add3_u32 v7, v18, v7, s62
	v_and_or_b32 v6, v7, s63, v6
	s_waitcnt lgkmcnt(1)
	v_bfe_u32 v7, v20, 16, 1
	v_add_u32_e32 v24, s30, v107
	v_add3_u32 v7, v20, v7, s62
	s_waitcnt lgkmcnt(0)
	v_bfe_u32 v8, v22, 16, 1
	v_ashrrev_i32_e32 v25, 31, v24
	v_lshrrev_b32_e32 v7, 16, v7
	v_add3_u32 v8, v22, v8, s62
	v_lshlrev_b64 v[24:25], 10, v[24:25]
	v_and_or_b32 v7, v8, s63, v7
	v_lshl_add_u64 v[24:25], v[2:3], 0, v[24:25]
	global_store_dwordx4 v[24:25], v[4:7], off sc1
	v_bfe_u32 v8, v23, 16, 1
	v_add3_u32 v8, v23, v8, s62
	v_bfe_u32 v4, v11, 16, 1
	v_add3_u32 v4, v11, v4, s62
	v_bfe_u32 v5, v9, 16, 1
	v_lshrrev_b32_e32 v4, 16, v4
	v_add3_u32 v5, v9, v5, s62
	v_and_or_b32 v4, v5, s63, v4
	v_bfe_u32 v5, v13, 16, 1
	v_add3_u32 v5, v13, v5, s62
	v_bfe_u32 v6, v15, 16, 1
	v_lshrrev_b32_e32 v5, 16, v5
	v_add3_u32 v6, v15, v6, s62
	v_and_or_b32 v5, v6, s63, v5
	v_bfe_u32 v6, v17, 16, 1
	v_add3_u32 v6, v17, v6, s62
	v_bfe_u32 v7, v19, 16, 1
	v_lshrrev_b32_e32 v6, 16, v6
	v_add3_u32 v7, v19, v7, s62
	v_and_or_b32 v6, v7, s63, v6
	v_bfe_u32 v7, v21, 16, 1
	v_add3_u32 v7, v21, v7, s62
	v_lshrrev_b32_e32 v7, 16, v7
	v_and_or_b32 v7, v8, s63, v7
	v_add_u32_e32 v8, s30, v106
	v_ashrrev_i32_e32 v9, 31, v8
	v_lshlrev_b64 v[8:9], 10, v[8:9]
	ds_read2_b32 v[10:11], v83 offset0:32 offset1:40
	v_lshl_add_u64 v[8:9], v[2:3], 0, v[8:9]
	global_store_dwordx4 v[8:9], v[4:7], off sc1
	ds_read2_b32 v[8:9], v83 offset0:97 offset1:105
	ds_read2_b32 v[12:13], v83 offset0:162 offset1:170
	ds_read2_b32 v[14:15], v83 offset0:227 offset1:235
	s_waitcnt lgkmcnt(3)
	v_bfe_u32 v4, v10, 16, 1
	v_add3_u32 v4, v10, v4, s62
	s_waitcnt lgkmcnt(2)
	v_bfe_u32 v5, v8, 16, 1
	ds_read2_b32 v[16:17], v26 offset0:36 offset1:44
	v_lshrrev_b32_e32 v4, 16, v4
	v_add3_u32 v5, v8, v5, s62
	ds_read2_b32 v[18:19], v26 offset0:101 offset1:109
	v_and_or_b32 v4, v5, s63, v4
	s_waitcnt lgkmcnt(3)
	v_bfe_u32 v5, v12, 16, 1
	v_add3_u32 v5, v12, v5, s62
	s_waitcnt lgkmcnt(2)
	v_bfe_u32 v6, v14, 16, 1
	ds_read2_b32 v[20:21], v26 offset0:166 offset1:174
	v_lshrrev_b32_e32 v5, 16, v5
	v_add3_u32 v6, v14, v6, s62
	ds_read2_b32 v[22:23], v26 offset0:231 offset1:239
	v_and_or_b32 v5, v6, s63, v5
	s_waitcnt lgkmcnt(3)
	v_bfe_u32 v6, v16, 16, 1
	v_add3_u32 v6, v16, v6, s62
	s_waitcnt lgkmcnt(2)
	v_bfe_u32 v7, v18, 16, 1
	v_lshrrev_b32_e32 v6, 16, v6
	v_add3_u32 v7, v18, v7, s62
	v_and_or_b32 v6, v7, s63, v6
	s_waitcnt lgkmcnt(1)
	v_bfe_u32 v7, v20, 16, 1
	v_add_u32_e32 v24, s30, v105
	v_add3_u32 v7, v20, v7, s62
	s_waitcnt lgkmcnt(0)
	v_bfe_u32 v8, v22, 16, 1
	v_ashrrev_i32_e32 v25, 31, v24
	v_lshrrev_b32_e32 v7, 16, v7
	v_add3_u32 v8, v22, v8, s62
	v_lshlrev_b64 v[24:25], 10, v[24:25]
	v_and_or_b32 v7, v8, s63, v7
	v_lshl_add_u64 v[24:25], v[2:3], 0, v[24:25]
	global_store_dwordx4 v[24:25], v[4:7], off sc1
	v_bfe_u32 v8, v23, 16, 1
	v_add3_u32 v8, v23, v8, s62
	v_bfe_u32 v4, v11, 16, 1
	v_add3_u32 v4, v11, v4, s62
	v_bfe_u32 v5, v9, 16, 1
	v_lshrrev_b32_e32 v4, 16, v4
	v_add3_u32 v5, v9, v5, s62
	v_and_or_b32 v4, v5, s63, v4
	v_bfe_u32 v5, v13, 16, 1
	v_add3_u32 v5, v13, v5, s62
	v_bfe_u32 v6, v15, 16, 1
	v_lshrrev_b32_e32 v5, 16, v5
	v_add3_u32 v6, v15, v6, s62
	v_and_or_b32 v5, v6, s63, v5
	v_bfe_u32 v6, v17, 16, 1
	v_add3_u32 v6, v17, v6, s62
	v_bfe_u32 v7, v19, 16, 1
	v_lshrrev_b32_e32 v6, 16, v6
	v_add3_u32 v7, v19, v7, s62
	v_and_or_b32 v6, v7, s63, v6
	v_bfe_u32 v7, v21, 16, 1
	v_add3_u32 v7, v21, v7, s62
	v_lshrrev_b32_e32 v7, 16, v7
	v_and_or_b32 v7, v8, s63, v7
	v_add_u32_e32 v8, s30, v104
	v_ashrrev_i32_e32 v9, 31, v8
	v_lshlrev_b64 v[8:9], 10, v[8:9]
	ds_read2_b32 v[10:11], v83 offset0:48 offset1:56
	v_lshl_add_u64 v[8:9], v[2:3], 0, v[8:9]
	global_store_dwordx4 v[8:9], v[4:7], off sc1
	ds_read2_b32 v[8:9], v83 offset0:113 offset1:121
	ds_read2_b32 v[12:13], v83 offset0:178 offset1:186
	ds_read2_b32 v[14:15], v83 offset0:243 offset1:251
	s_waitcnt lgkmcnt(3)
	v_bfe_u32 v4, v10, 16, 1
	v_add3_u32 v4, v10, v4, s62
	s_waitcnt lgkmcnt(2)
	v_bfe_u32 v5, v8, 16, 1
	ds_read2_b32 v[16:17], v26 offset0:52 offset1:60
	v_lshrrev_b32_e32 v4, 16, v4
	v_add3_u32 v5, v8, v5, s62
	ds_read2_b32 v[18:19], v26 offset0:117 offset1:125
	v_and_or_b32 v4, v5, s63, v4
	s_waitcnt lgkmcnt(3)
	v_bfe_u32 v5, v12, 16, 1
	v_add3_u32 v5, v12, v5, s62
	s_waitcnt lgkmcnt(2)
	v_bfe_u32 v6, v14, 16, 1
	ds_read2_b32 v[20:21], v26 offset0:182 offset1:190
	v_lshrrev_b32_e32 v5, 16, v5
	v_add3_u32 v6, v14, v6, s62
	ds_read2_b32 v[22:23], v26 offset0:247 offset1:255
	v_and_or_b32 v5, v6, s63, v5
	s_waitcnt lgkmcnt(3)
	v_bfe_u32 v6, v16, 16, 1
	v_add3_u32 v6, v16, v6, s62
	s_waitcnt lgkmcnt(2)
	v_bfe_u32 v7, v18, 16, 1
	v_lshrrev_b32_e32 v6, 16, v6
	v_add3_u32 v7, v18, v7, s62
	v_and_or_b32 v6, v7, s63, v6
	s_waitcnt lgkmcnt(1)
	v_bfe_u32 v7, v20, 16, 1
	v_add_u32_e32 v24, s30, v103
	v_add3_u32 v7, v20, v7, s62
	s_waitcnt lgkmcnt(0)
	v_bfe_u32 v8, v22, 16, 1
	v_ashrrev_i32_e32 v25, 31, v24
	v_lshrrev_b32_e32 v7, 16, v7
	v_add3_u32 v8, v22, v8, s62
	v_lshlrev_b64 v[24:25], 10, v[24:25]
	v_and_or_b32 v7, v8, s63, v7
	v_lshl_add_u64 v[24:25], v[2:3], 0, v[24:25]
	global_store_dwordx4 v[24:25], v[4:7], off sc1
	v_bfe_u32 v8, v23, 16, 1
	v_add3_u32 v8, v23, v8, s62
	v_bfe_u32 v4, v11, 16, 1
	v_add3_u32 v4, v11, v4, s62
	v_bfe_u32 v5, v9, 16, 1
	v_lshrrev_b32_e32 v4, 16, v4
	v_add3_u32 v5, v9, v5, s62
	v_and_or_b32 v4, v5, s63, v4
	v_bfe_u32 v5, v13, 16, 1
	v_add3_u32 v5, v13, v5, s62
	v_bfe_u32 v6, v15, 16, 1
	v_lshrrev_b32_e32 v5, 16, v5
	v_add3_u32 v6, v15, v6, s62
	v_and_or_b32 v5, v6, s63, v5
	v_bfe_u32 v6, v17, 16, 1
	v_add3_u32 v6, v17, v6, s62
	v_bfe_u32 v7, v19, 16, 1
	v_lshrrev_b32_e32 v6, 16, v6
	v_add3_u32 v7, v19, v7, s62
	v_and_or_b32 v6, v7, s63, v6
	v_bfe_u32 v7, v21, 16, 1
	v_add3_u32 v7, v21, v7, s62
	v_lshrrev_b32_e32 v7, 16, v7
	v_and_or_b32 v7, v8, s63, v7
	v_add_u32_e32 v8, s30, v102
	v_ashrrev_i32_e32 v9, 31, v8
	v_lshlrev_b64 v[8:9], 10, v[8:9]
	v_lshl_add_u64 v[2:3], v[2:3], 0, v[8:9]
	global_store_dwordx4 v[2:3], v[4:7], off sc1
	s_waitcnt lgkmcnt(0)

.LBB0_172:
	s_or_b64 exec, exec, s[26:27]
	s_waitcnt vmcnt(0)
	ds_write2_b32 v81, v2, v3 offset1:1
	ds_write2_b32 v81, v4, v5 offset0:2 offset1:3
	v_add_u32_e32 v2, 0x410, v81
	ds_write2_b32 v2, v6, v7 offset1:1
	v_add_u32_e32 v2, 0x418, v81
	ds_write2_b32 v2, v8, v9 offset1:1
	v_add_u32_e32 v2, 0x820, v81
	ds_write2_b32 v2, v14, v15 offset1:1
	v_add_u32_e32 v2, 0x828, v81
	ds_write2_b32 v2, v16, v17 offset1:1
	v_add_u32_e32 v2, 0xc30, v81
	ds_write2_b32 v2, v10, v11 offset1:1
	v_add_u32_e32 v2, 0xc38, v81
	ds_write2_b32 v2, v12, v13 offset1:1
	v_add_u32_e32 v2, 0x1040, v81
	ds_write2_b32 v2, v22, v23 offset1:1
	v_add_u32_e32 v2, 0x1048, v81
	ds_write2_b32 v2, v24, v25 offset1:1
	v_add_u32_e32 v2, 0x1450, v81
	ds_write2_b32 v2, v18, v19 offset1:1
	v_add_u32_e32 v2, 0x1458, v81
	ds_write2_b32 v2, v20, v21 offset1:1
	v_add_u32_e32 v2, 0x1860, v81
	ds_write2_b32 v2, v30, v31 offset1:1
	v_add_u32_e32 v2, 0x1868, v81
	ds_write2_b32 v2, v32, v33 offset1:1
	v_add_u32_e32 v2, 0x1c70, v81
	ds_write2_b32 v2, v26, v27 offset1:1
	v_add_u32_e32 v2, 0x1c78, v81
	ds_write2_b32 v2, v28, v29 offset1:1
	v_add_u32_e32 v2, 0x2080, v81
	ds_write2_b32 v2, v38, v39 offset1:1
	v_add_u32_e32 v2, 0x2088, v81
	ds_write2_b32 v2, v40, v41 offset1:1
	v_add_u32_e32 v2, 0x2490, v81
	ds_write2_b32 v2, v34, v35 offset1:1
	v_add_u32_e32 v2, 0x2498, v81
	ds_write2_b32 v2, v36, v37 offset1:1
	v_add_u32_e32 v2, 0x28a0, v81
	ds_write2_b32 v2, v46, v47 offset1:1
	v_add_u32_e32 v2, 0x28a8, v81
	ds_write2_b32 v2, v48, v49 offset1:1
	v_add_u32_e32 v2, 0x2cb0, v81
	ds_write2_b32 v2, v42, v43 offset1:1
	v_add_u32_e32 v2, 0x2cb8, v81
	ds_write2_b32 v2, v44, v45 offset1:1
	v_add_u32_e32 v2, 0x30c0, v81
	ds_write2_b32 v2, v54, v55 offset1:1
	v_add_u32_e32 v2, 0x30c8, v81
	ds_write2_b32 v2, v56, v57 offset1:1
	v_add_u32_e32 v2, 0x34d0, v81
	ds_write2_b32 v2, v50, v51 offset1:1
	v_add_u32_e32 v2, 0x34d8, v81
	ds_write2_b32 v2, v52, v53 offset1:1
	v_add_u32_e32 v2, 0x38e0, v81
	ds_write2_b32 v2, v62, v63 offset1:1
	v_add_u32_e32 v2, 0x38e8, v81
	ds_write2_b32 v2, v64, v65 offset1:1
	v_add_u32_e32 v2, 0x3cf0, v81
	ds_write2_b32 v2, v58, v59 offset1:1
	v_add_u32_e32 v2, 0x3cf8, v81
	ds_write2_b32 v2, v60, v61 offset1:1
	s_waitcnt lgkmcnt(0)
	ds_read2_b32 v[8:9], v83 offset1:8
	ds_read2_b32 v[10:11], v83 offset0:65 offset1:73
	ds_read2_b32 v[12:13], v83 offset0:130 offset1:138
	ds_read2_b32 v[14:15], v83 offset0:195 offset1:203
	v_add_u32_e32 v26, 0x400, v83
	s_waitcnt lgkmcnt(3)
	v_bfe_u32 v4, v8, 16, 1
	v_add3_u32 v4, v8, v4, s62
	s_waitcnt lgkmcnt(2)
	v_bfe_u32 v5, v10, 16, 1
	ds_read2_b32 v[16:17], v26 offset0:4 offset1:12
	v_lshrrev_b32_e32 v4, 16, v4
	v_add3_u32 v5, v10, v5, s62
	ds_read2_b32 v[18:19], v26 offset0:69 offset1:77
	v_and_or_b32 v4, v5, s63, v4
	s_waitcnt lgkmcnt(3)
	v_bfe_u32 v5, v12, 16, 1
	v_add3_u32 v5, v12, v5, s62
	s_waitcnt lgkmcnt(2)
	v_bfe_u32 v6, v14, 16, 1
	ds_read2_b32 v[20:21], v26 offset0:134 offset1:142
	v_lshrrev_b32_e32 v5, 16, v5
	v_add3_u32 v6, v14, v6, s62
	ds_read2_b32 v[22:23], v26 offset0:199 offset1:207
	v_and_or_b32 v5, v6, s63, v5
	s_waitcnt lgkmcnt(3)
	v_bfe_u32 v6, v16, 16, 1
	v_add3_u32 v6, v16, v6, s62
	s_waitcnt lgkmcnt(2)
	v_bfe_u32 v7, v18, 16, 1
	v_lshrrev_b32_e32 v6, 16, v6
	v_add3_u32 v7, v18, v7, s62
	s_add_i32 s30, s30, s80
	v_and_or_b32 v6, v7, s63, v6
	s_waitcnt lgkmcnt(1)
	v_bfe_u32 v7, v20, 16, 1
	v_add_u32_e32 v24, s30, v118
	v_add3_u32 v7, v20, v7, s62
	s_waitcnt lgkmcnt(0)
	v_bfe_u32 v8, v22, 16, 1
	v_ashrrev_i32_e32 v25, 31, v24
	v_lshl_add_u64 v[2:3], s[2:3], 1, v[76:77]
	v_lshrrev_b32_e32 v7, 16, v7
	v_add3_u32 v8, v22, v8, s62
	v_lshlrev_b64 v[24:25], 12, v[24:25]
	v_and_or_b32 v7, v8, s63, v7
	v_lshl_add_u64 v[24:25], v[2:3], 0, v[24:25]
	global_store_dwordx4 v[24:25], v[4:7], off sc1
	v_bfe_u32 v8, v23, 16, 1
	v_add3_u32 v8, v23, v8, s62
	v_bfe_u32 v4, v9, 16, 1
	v_add3_u32 v4, v9, v4, s62
	v_bfe_u32 v5, v11, 16, 1
	v_lshrrev_b32_e32 v4, 16, v4
	v_add3_u32 v5, v11, v5, s62
	v_and_or_b32 v4, v5, s63, v4
	v_bfe_u32 v5, v13, 16, 1
	v_add3_u32 v5, v13, v5, s62
	v_bfe_u32 v6, v15, 16, 1
	v_lshrrev_b32_e32 v5, 16, v5
	v_add3_u32 v6, v15, v6, s62
	v_and_or_b32 v5, v6, s63, v5
	v_bfe_u32 v6, v17, 16, 1
	v_add3_u32 v6, v17, v6, s62
	v_bfe_u32 v7, v19, 16, 1
	v_lshrrev_b32_e32 v6, 16, v6
	v_add3_u32 v7, v19, v7, s62
	v_and_or_b32 v6, v7, s63, v6
	v_bfe_u32 v7, v21, 16, 1
	v_add3_u32 v7, v21, v7, s62
	v_lshrrev_b32_e32 v7, 16, v7
	v_and_or_b32 v7, v8, s63, v7
	v_add_u32_e32 v8, s30, v117
	v_ashrrev_i32_e32 v9, 31, v8
	v_lshlrev_b64 v[8:9], 12, v[8:9]
	ds_read2_b32 v[10:11], v83 offset0:16 offset1:24
	v_lshl_add_u64 v[8:9], v[2:3], 0, v[8:9]
	global_store_dwordx4 v[8:9], v[4:7], off sc1
	ds_read2_b32 v[8:9], v83 offset0:81 offset1:89
	ds_read2_b32 v[12:13], v83 offset0:146 offset1:154
	ds_read2_b32 v[14:15], v83 offset0:211 offset1:219
	s_waitcnt lgkmcnt(3)
	v_bfe_u32 v4, v10, 16, 1
	v_add3_u32 v4, v10, v4, s62
	s_waitcnt lgkmcnt(2)
	v_bfe_u32 v5, v8, 16, 1
	ds_read2_b32 v[16:17], v26 offset0:20 offset1:28
	v_lshrrev_b32_e32 v4, 16, v4
	v_add3_u32 v5, v8, v5, s62
	ds_read2_b32 v[18:19], v26 offset0:85 offset1:93
	v_and_or_b32 v4, v5, s63, v4
	s_waitcnt lgkmcnt(3)
	v_bfe_u32 v5, v12, 16, 1
	v_add3_u32 v5, v12, v5, s62
	s_waitcnt lgkmcnt(2)
	v_bfe_u32 v6, v14, 16, 1
	ds_read2_b32 v[20:21], v26 offset0:150 offset1:158
	v_lshrrev_b32_e32 v5, 16, v5
	v_add3_u32 v6, v14, v6, s62
	ds_read2_b32 v[22:23], v26 offset0:215 offset1:223
	v_and_or_b32 v5, v6, s63, v5
	s_waitcnt lgkmcnt(3)
	v_bfe_u32 v6, v16, 16, 1
	v_add3_u32 v6, v16, v6, s62
	s_waitcnt lgkmcnt(2)
	v_bfe_u32 v7, v18, 16, 1
	v_lshrrev_b32_e32 v6, 16, v6
	v_add3_u32 v7, v18, v7, s62
	v_and_or_b32 v6, v7, s63, v6
	s_waitcnt lgkmcnt(1)
	v_bfe_u32 v7, v20, 16, 1
	v_add_u32_e32 v24, s30, v116
	v_add3_u32 v7, v20, v7, s62
	s_waitcnt lgkmcnt(0)
	v_bfe_u32 v8, v22, 16, 1
	v_ashrrev_i32_e32 v25, 31, v24
	v_lshrrev_b32_e32 v7, 16, v7
	v_add3_u32 v8, v22, v8, s62
	v_lshlrev_b64 v[24:25], 12, v[24:25]
	v_and_or_b32 v7, v8, s63, v7
	v_lshl_add_u64 v[24:25], v[2:3], 0, v[24:25]
	global_store_dwordx4 v[24:25], v[4:7], off sc1
	v_bfe_u32 v8, v23, 16, 1
	v_add3_u32 v8, v23, v8, s62
	v_bfe_u32 v4, v11, 16, 1
	v_add3_u32 v4, v11, v4, s62
	v_bfe_u32 v5, v9, 16, 1
	v_lshrrev_b32_e32 v4, 16, v4
	v_add3_u32 v5, v9, v5, s62
	v_and_or_b32 v4, v5, s63, v4
	v_bfe_u32 v5, v13, 16, 1
	v_add3_u32 v5, v13, v5, s62
	v_bfe_u32 v6, v15, 16, 1
	v_lshrrev_b32_e32 v5, 16, v5
	v_add3_u32 v6, v15, v6, s62
	v_and_or_b32 v5, v6, s63, v5
	v_bfe_u32 v6, v17, 16, 1
	v_add3_u32 v6, v17, v6, s62
	v_bfe_u32 v7, v19, 16, 1
	v_lshrrev_b32_e32 v6, 16, v6
	v_add3_u32 v7, v19, v7, s62
	v_and_or_b32 v6, v7, s63, v6
	v_bfe_u32 v7, v21, 16, 1
	v_add3_u32 v7, v21, v7, s62
	v_lshrrev_b32_e32 v7, 16, v7
	v_and_or_b32 v7, v8, s63, v7
	v_add_u32_e32 v8, s30, v115
	v_ashrrev_i32_e32 v9, 31, v8
	v_lshlrev_b64 v[8:9], 12, v[8:9]
	ds_read2_b32 v[10:11], v83 offset0:32 offset1:40
	v_lshl_add_u64 v[8:9], v[2:3], 0, v[8:9]
	global_store_dwordx4 v[8:9], v[4:7], off sc1
	ds_read2_b32 v[8:9], v83 offset0:97 offset1:105
	ds_read2_b32 v[12:13], v83 offset0:162 offset1:170
	ds_read2_b32 v[14:15], v83 offset0:227 offset1:235
	s_waitcnt lgkmcnt(3)
	v_bfe_u32 v4, v10, 16, 1
	v_add3_u32 v4, v10, v4, s62
	s_waitcnt lgkmcnt(2)
	v_bfe_u32 v5, v8, 16, 1
	ds_read2_b32 v[16:17], v26 offset0:36 offset1:44
	v_lshrrev_b32_e32 v4, 16, v4
	v_add3_u32 v5, v8, v5, s62
	ds_read2_b32 v[18:19], v26 offset0:101 offset1:109
	v_and_or_b32 v4, v5, s63, v4
	s_waitcnt lgkmcnt(3)
	v_bfe_u32 v5, v12, 16, 1
	v_add3_u32 v5, v12, v5, s62
	s_waitcnt lgkmcnt(2)
	v_bfe_u32 v6, v14, 16, 1
	ds_read2_b32 v[20:21], v26 offset0:166 offset1:174
	v_lshrrev_b32_e32 v5, 16, v5
	v_add3_u32 v6, v14, v6, s62
	ds_read2_b32 v[22:23], v26 offset0:231 offset1:239
	v_and_or_b32 v5, v6, s63, v5
	s_waitcnt lgkmcnt(3)
	v_bfe_u32 v6, v16, 16, 1
	v_add3_u32 v6, v16, v6, s62
	s_waitcnt lgkmcnt(2)
	v_bfe_u32 v7, v18, 16, 1
	v_lshrrev_b32_e32 v6, 16, v6
	v_add3_u32 v7, v18, v7, s62
	v_and_or_b32 v6, v7, s63, v6
	s_waitcnt lgkmcnt(1)
	v_bfe_u32 v7, v20, 16, 1
	v_add_u32_e32 v24, s30, v114
	v_add3_u32 v7, v20, v7, s62
	s_waitcnt lgkmcnt(0)
	v_bfe_u32 v8, v22, 16, 1
	v_ashrrev_i32_e32 v25, 31, v24
	v_lshrrev_b32_e32 v7, 16, v7
	v_add3_u32 v8, v22, v8, s62
	v_lshlrev_b64 v[24:25], 12, v[24:25]
	v_and_or_b32 v7, v8, s63, v7
	v_lshl_add_u64 v[24:25], v[2:3], 0, v[24:25]
	global_store_dwordx4 v[24:25], v[4:7], off sc1
	v_bfe_u32 v8, v23, 16, 1
	v_add3_u32 v8, v23, v8, s62
	v_bfe_u32 v4, v11, 16, 1
	v_add3_u32 v4, v11, v4, s62
	v_bfe_u32 v5, v9, 16, 1
	v_lshrrev_b32_e32 v4, 16, v4
	v_add3_u32 v5, v9, v5, s62
	v_and_or_b32 v4, v5, s63, v4
	v_bfe_u32 v5, v13, 16, 1
	v_add3_u32 v5, v13, v5, s62
	v_bfe_u32 v6, v15, 16, 1
	v_lshrrev_b32_e32 v5, 16, v5
	v_add3_u32 v6, v15, v6, s62
	v_and_or_b32 v5, v6, s63, v5
	v_bfe_u32 v6, v17, 16, 1
	v_add3_u32 v6, v17, v6, s62
	v_bfe_u32 v7, v19, 16, 1
	v_lshrrev_b32_e32 v6, 16, v6
	v_add3_u32 v7, v19, v7, s62
	v_and_or_b32 v6, v7, s63, v6
	v_bfe_u32 v7, v21, 16, 1
	v_add3_u32 v7, v21, v7, s62
	v_lshrrev_b32_e32 v7, 16, v7
	v_and_or_b32 v7, v8, s63, v7
	v_add_u32_e32 v8, s30, v113
	v_ashrrev_i32_e32 v9, 31, v8
	v_lshlrev_b64 v[8:9], 12, v[8:9]
	ds_read2_b32 v[10:11], v83 offset0:48 offset1:56
	v_lshl_add_u64 v[8:9], v[2:3], 0, v[8:9]
	global_store_dwordx4 v[8:9], v[4:7], off sc1
	ds_read2_b32 v[8:9], v83 offset0:113 offset1:121
	ds_read2_b32 v[12:13], v83 offset0:178 offset1:186
	ds_read2_b32 v[14:15], v83 offset0:243 offset1:251
	s_waitcnt lgkmcnt(3)
	v_bfe_u32 v4, v10, 16, 1
	v_add3_u32 v4, v10, v4, s62
	s_waitcnt lgkmcnt(2)
	v_bfe_u32 v5, v8, 16, 1
	ds_read2_b32 v[16:17], v26 offset0:52 offset1:60
	v_lshrrev_b32_e32 v4, 16, v4
	v_add3_u32 v5, v8, v5, s62
	ds_read2_b32 v[18:19], v26 offset0:117 offset1:125
	v_and_or_b32 v4, v5, s63, v4
	s_waitcnt lgkmcnt(3)
	v_bfe_u32 v5, v12, 16, 1
	v_add3_u32 v5, v12, v5, s62
	s_waitcnt lgkmcnt(2)
	v_bfe_u32 v6, v14, 16, 1
	ds_read2_b32 v[20:21], v26 offset0:182 offset1:190
	v_lshrrev_b32_e32 v5, 16, v5
	v_add3_u32 v6, v14, v6, s62
	ds_read2_b32 v[22:23], v26 offset0:247 offset1:255
	v_and_or_b32 v5, v6, s63, v5
	s_waitcnt lgkmcnt(3)
	v_bfe_u32 v6, v16, 16, 1
	v_add3_u32 v6, v16, v6, s62
	s_waitcnt lgkmcnt(2)
	v_bfe_u32 v7, v18, 16, 1
	v_lshrrev_b32_e32 v6, 16, v6
	v_add3_u32 v7, v18, v7, s62
	v_and_or_b32 v6, v7, s63, v6
	s_waitcnt lgkmcnt(1)
	v_bfe_u32 v7, v20, 16, 1
	v_add_u32_e32 v24, s30, v112
	v_add3_u32 v7, v20, v7, s62
	s_waitcnt lgkmcnt(0)
	v_bfe_u32 v8, v22, 16, 1
	v_ashrrev_i32_e32 v25, 31, v24
	v_lshrrev_b32_e32 v7, 16, v7
	v_add3_u32 v8, v22, v8, s62
	v_lshlrev_b64 v[24:25], 12, v[24:25]
	v_and_or_b32 v7, v8, s63, v7
	v_lshl_add_u64 v[24:25], v[2:3], 0, v[24:25]
	global_store_dwordx4 v[24:25], v[4:7], off sc1
	v_bfe_u32 v8, v23, 16, 1
	v_add3_u32 v8, v23, v8, s62
	v_bfe_u32 v4, v11, 16, 1
	v_add3_u32 v4, v11, v4, s62
	v_bfe_u32 v5, v9, 16, 1
	v_lshrrev_b32_e32 v4, 16, v4
	v_add3_u32 v5, v9, v5, s62
	v_and_or_b32 v4, v5, s63, v4
	v_bfe_u32 v5, v13, 16, 1
	v_add3_u32 v5, v13, v5, s62
	v_bfe_u32 v6, v15, 16, 1
	v_lshrrev_b32_e32 v5, 16, v5
	v_add3_u32 v6, v15, v6, s62
	v_and_or_b32 v5, v6, s63, v5
	v_bfe_u32 v6, v17, 16, 1
	v_add3_u32 v6, v17, v6, s62
	v_bfe_u32 v7, v19, 16, 1
	v_lshrrev_b32_e32 v6, 16, v6
	v_add3_u32 v7, v19, v7, s62
	v_and_or_b32 v6, v7, s63, v6
	v_bfe_u32 v7, v21, 16, 1
	v_add3_u32 v7, v21, v7, s62
	v_lshrrev_b32_e32 v7, 16, v7
	v_and_or_b32 v7, v8, s63, v7
	v_add_u32_e32 v8, s30, v111
	v_ashrrev_i32_e32 v9, 31, v8
	v_lshlrev_b64 v[8:9], 12, v[8:9]
	v_lshl_add_u64 v[2:3], v[2:3], 0, v[8:9]
	global_store_dwordx4 v[2:3], v[4:7], off sc1
	s_waitcnt lgkmcnt(0)

.LBB0_207:
	s_or_b64 exec, exec, s[34:35]
	s_waitcnt vmcnt(0)
	ds_write2_b32 v81, v2, v3 offset1:1
	ds_write2_b32 v81, v4, v5 offset0:2 offset1:3
	v_add_u32_e32 v2, 0x410, v81
	ds_write2_b32 v2, v6, v7 offset1:1
	v_add_u32_e32 v2, 0x418, v81
	ds_write2_b32 v2, v8, v9 offset1:1
	v_add_u32_e32 v2, 0x820, v81
	ds_write2_b32 v2, v14, v15 offset1:1
	v_add_u32_e32 v2, 0x828, v81
	ds_write2_b32 v2, v16, v17 offset1:1
	v_add_u32_e32 v2, 0xc30, v81
	ds_write2_b32 v2, v10, v11 offset1:1
	v_add_u32_e32 v2, 0xc38, v81
	ds_write2_b32 v2, v12, v13 offset1:1
	v_add_u32_e32 v2, 0x1040, v81
	ds_write2_b32 v2, v22, v23 offset1:1
	v_add_u32_e32 v2, 0x1048, v81
	ds_write2_b32 v2, v24, v25 offset1:1
	v_add_u32_e32 v2, 0x1450, v81
	ds_write2_b32 v2, v18, v19 offset1:1
	v_add_u32_e32 v2, 0x1458, v81
	ds_write2_b32 v2, v20, v21 offset1:1
	v_add_u32_e32 v2, 0x1860, v81
	ds_write2_b32 v2, v30, v31 offset1:1
	v_add_u32_e32 v2, 0x1868, v81
	ds_write2_b32 v2, v32, v33 offset1:1
	v_add_u32_e32 v2, 0x1c70, v81
	ds_write2_b32 v2, v26, v27 offset1:1
	v_add_u32_e32 v2, 0x1c78, v81
	ds_write2_b32 v2, v28, v29 offset1:1
	v_add_u32_e32 v2, 0x2080, v81
	ds_write2_b32 v2, v38, v39 offset1:1
	v_add_u32_e32 v2, 0x2088, v81
	ds_write2_b32 v2, v40, v41 offset1:1
	v_add_u32_e32 v2, 0x2490, v81
	ds_write2_b32 v2, v34, v35 offset1:1
	v_add_u32_e32 v2, 0x2498, v81
	ds_write2_b32 v2, v36, v37 offset1:1
	v_add_u32_e32 v2, 0x28a0, v81
	ds_write2_b32 v2, v46, v47 offset1:1
	v_add_u32_e32 v2, 0x28a8, v81
	ds_write2_b32 v2, v48, v49 offset1:1
	v_add_u32_e32 v2, 0x2cb0, v81
	ds_write2_b32 v2, v42, v43 offset1:1
	v_add_u32_e32 v2, 0x2cb8, v81
	ds_write2_b32 v2, v44, v45 offset1:1
	v_add_u32_e32 v2, 0x30c0, v81
	ds_write2_b32 v2, v54, v55 offset1:1
	v_add_u32_e32 v2, 0x30c8, v81
	ds_write2_b32 v2, v56, v57 offset1:1
	v_add_u32_e32 v2, 0x34d0, v81
	ds_write2_b32 v2, v50, v51 offset1:1
	v_add_u32_e32 v2, 0x34d8, v81
	ds_write2_b32 v2, v52, v53 offset1:1
	v_add_u32_e32 v2, 0x38e0, v81
	ds_write2_b32 v2, v62, v63 offset1:1
	v_add_u32_e32 v2, 0x38e8, v81
	ds_write2_b32 v2, v64, v65 offset1:1
	v_add_u32_e32 v2, 0x3cf0, v81
	ds_write2_b32 v2, v58, v59 offset1:1
	v_add_u32_e32 v2, 0x3cf8, v81
	ds_write2_b32 v2, v60, v61 offset1:1
	s_waitcnt lgkmcnt(0)
	ds_read2_b32 v[8:9], v83 offset1:8
	ds_read2_b32 v[10:11], v83 offset0:65 offset1:73
	ds_read2_b32 v[12:13], v83 offset0:130 offset1:138
	ds_read2_b32 v[14:15], v83 offset0:195 offset1:203
	v_add_u32_e32 v26, 0x400, v83
	s_waitcnt lgkmcnt(3)
	v_bfe_u32 v4, v8, 16, 1
	v_add3_u32 v4, v8, v4, s62
	s_waitcnt lgkmcnt(2)
	v_bfe_u32 v5, v10, 16, 1
	ds_read2_b32 v[16:17], v26 offset0:4 offset1:12
	v_lshrrev_b32_e32 v4, 16, v4
	v_add3_u32 v5, v10, v5, s62
	ds_read2_b32 v[18:19], v26 offset0:69 offset1:77
	v_and_or_b32 v4, v5, s63, v4
	s_waitcnt lgkmcnt(3)
	v_bfe_u32 v5, v12, 16, 1
	s_and_b64 s[0:1], s[30:31], exec
	v_add3_u32 v5, v12, v5, s62
	s_waitcnt lgkmcnt(2)
	v_bfe_u32 v6, v14, 16, 1
	ds_read2_b32 v[20:21], v26 offset0:134 offset1:142
	s_cselect_b32 s0, 0xc00000, 0
	v_lshrrev_b32_e32 v5, 16, v5
	v_add3_u32 v6, v14, v6, s62
	ds_read2_b32 v[22:23], v26 offset0:199 offset1:207
	s_add_u32 s30, s38, s0
	v_and_or_b32 v5, v6, s63, v5
	s_waitcnt lgkmcnt(3)
	v_bfe_u32 v6, v16, 16, 1
	s_addc_u32 s31, s39, 0
	s_ashr_i32 s27, s26, 31
	v_add3_u32 v6, v16, v6, s62
	s_waitcnt lgkmcnt(2)
	v_bfe_u32 v7, v18, 16, 1
	s_lshl_b64 s[0:1], s[26:27], 1
	v_lshrrev_b32_e32 v6, 16, v6
	v_add3_u32 v7, v18, v7, s62
	s_add_u32 s0, s30, s0
	v_and_or_b32 v6, v7, s63, v6
	s_waitcnt lgkmcnt(1)
	v_bfe_u32 v7, v20, 16, 1
	v_or_b32_e32 v24, s2, v82
	s_addc_u32 s1, s31, s1
	v_lshlrev_b32_e32 v68, 1, v66
	v_add3_u32 v7, v20, v7, s62
	s_waitcnt lgkmcnt(0)
	v_bfe_u32 v8, v22, 16, 1
	v_ashrrev_i32_e32 v25, 31, v24
	v_lshl_add_u64 v[2:3], s[0:1], 0, v[68:69]
	v_lshrrev_b32_e32 v7, 16, v7
	v_add3_u32 v8, v22, v8, s62
	v_lshlrev_b64 v[24:25], 12, v[24:25]
	v_and_or_b32 v7, v8, s63, v7
	v_lshl_add_u64 v[24:25], v[2:3], 0, v[24:25]
	global_store_dwordx4 v[24:25], v[4:7], off sc1
	v_bfe_u32 v8, v23, 16, 1
	v_add3_u32 v8, v23, v8, s62
	v_bfe_u32 v4, v9, 16, 1
	v_add3_u32 v4, v9, v4, s62
	v_bfe_u32 v5, v11, 16, 1
	v_lshrrev_b32_e32 v4, 16, v4
	v_add3_u32 v5, v11, v5, s62
	v_and_or_b32 v4, v5, s63, v4
	v_bfe_u32 v5, v13, 16, 1
	v_add3_u32 v5, v13, v5, s62
	v_bfe_u32 v6, v15, 16, 1
	v_lshrrev_b32_e32 v5, 16, v5
	v_add3_u32 v6, v15, v6, s62
	v_and_or_b32 v5, v6, s63, v5
	v_bfe_u32 v6, v17, 16, 1
	v_add3_u32 v6, v17, v6, s62
	v_bfe_u32 v7, v19, 16, 1
	v_lshrrev_b32_e32 v6, 16, v6
	v_add3_u32 v7, v19, v7, s62
	v_and_or_b32 v6, v7, s63, v6
	v_bfe_u32 v7, v21, 16, 1
	v_add3_u32 v7, v21, v7, s62
	v_lshrrev_b32_e32 v7, 16, v7
	v_and_or_b32 v7, v8, s63, v7
	v_or_b32_e32 v8, s2, v84
	v_ashrrev_i32_e32 v9, 31, v8
	v_lshlrev_b64 v[8:9], 12, v[8:9]
	ds_read2_b32 v[10:11], v83 offset0:16 offset1:24
	v_lshl_add_u64 v[8:9], v[2:3], 0, v[8:9]
	global_store_dwordx4 v[8:9], v[4:7], off sc1
	ds_read2_b32 v[8:9], v83 offset0:81 offset1:89
	ds_read2_b32 v[12:13], v83 offset0:146 offset1:154
	ds_read2_b32 v[14:15], v83 offset0:211 offset1:219
	s_waitcnt lgkmcnt(3)
	v_bfe_u32 v4, v10, 16, 1
	v_add3_u32 v4, v10, v4, s62
	s_waitcnt lgkmcnt(2)
	v_bfe_u32 v5, v8, 16, 1
	ds_read2_b32 v[16:17], v26 offset0:20 offset1:28
	v_lshrrev_b32_e32 v4, 16, v4
	v_add3_u32 v5, v8, v5, s62
	ds_read2_b32 v[18:19], v26 offset0:85 offset1:93
	v_and_or_b32 v4, v5, s63, v4
	s_waitcnt lgkmcnt(3)
	v_bfe_u32 v5, v12, 16, 1
	v_add3_u32 v5, v12, v5, s62
	s_waitcnt lgkmcnt(2)
	v_bfe_u32 v6, v14, 16, 1
	ds_read2_b32 v[20:21], v26 offset0:150 offset1:158
	v_lshrrev_b32_e32 v5, 16, v5
	v_add3_u32 v6, v14, v6, s62
	ds_read2_b32 v[22:23], v26 offset0:215 offset1:223
	v_and_or_b32 v5, v6, s63, v5
	s_waitcnt lgkmcnt(3)
	v_bfe_u32 v6, v16, 16, 1
	v_add3_u32 v6, v16, v6, s62
	s_waitcnt lgkmcnt(2)
	v_bfe_u32 v7, v18, 16, 1
	v_lshrrev_b32_e32 v6, 16, v6
	v_add3_u32 v7, v18, v7, s62
	v_and_or_b32 v6, v7, s63, v6
	s_waitcnt lgkmcnt(1)
	v_bfe_u32 v7, v20, 16, 1
	v_or_b32_e32 v24, s2, v85
	v_add3_u32 v7, v20, v7, s62
	s_waitcnt lgkmcnt(0)
	v_bfe_u32 v8, v22, 16, 1
	v_ashrrev_i32_e32 v25, 31, v24
	v_lshrrev_b32_e32 v7, 16, v7
	v_add3_u32 v8, v22, v8, s62
	v_lshlrev_b64 v[24:25], 12, v[24:25]
	v_and_or_b32 v7, v8, s63, v7
	v_lshl_add_u64 v[24:25], v[2:3], 0, v[24:25]
	global_store_dwordx4 v[24:25], v[4:7], off sc1
	v_bfe_u32 v8, v23, 16, 1
	v_add3_u32 v8, v23, v8, s62
	v_bfe_u32 v4, v11, 16, 1
	v_add3_u32 v4, v11, v4, s62
	v_bfe_u32 v5, v9, 16, 1
	v_lshrrev_b32_e32 v4, 16, v4
	v_add3_u32 v5, v9, v5, s62
	v_and_or_b32 v4, v5, s63, v4
	v_bfe_u32 v5, v13, 16, 1
	v_add3_u32 v5, v13, v5, s62
	v_bfe_u32 v6, v15, 16, 1
	v_lshrrev_b32_e32 v5, 16, v5
	v_add3_u32 v6, v15, v6, s62
	v_and_or_b32 v5, v6, s63, v5
	v_bfe_u32 v6, v17, 16, 1
	v_add3_u32 v6, v17, v6, s62
	v_bfe_u32 v7, v19, 16, 1
	v_lshrrev_b32_e32 v6, 16, v6
	v_add3_u32 v7, v19, v7, s62
	v_and_or_b32 v6, v7, s63, v6
	v_bfe_u32 v7, v21, 16, 1
	v_add3_u32 v7, v21, v7, s62
	v_lshrrev_b32_e32 v7, 16, v7
	v_and_or_b32 v7, v8, s63, v7
	v_or_b32_e32 v8, s2, v86
	v_ashrrev_i32_e32 v9, 31, v8
	v_lshlrev_b64 v[8:9], 12, v[8:9]
	ds_read2_b32 v[10:11], v83 offset0:32 offset1:40
	v_lshl_add_u64 v[8:9], v[2:3], 0, v[8:9]
	global_store_dwordx4 v[8:9], v[4:7], off sc1
	ds_read2_b32 v[8:9], v83 offset0:97 offset1:105
	ds_read2_b32 v[12:13], v83 offset0:162 offset1:170
	ds_read2_b32 v[14:15], v83 offset0:227 offset1:235
	s_waitcnt lgkmcnt(3)
	v_bfe_u32 v4, v10, 16, 1
	v_add3_u32 v4, v10, v4, s62
	s_waitcnt lgkmcnt(2)
	v_bfe_u32 v5, v8, 16, 1
	ds_read2_b32 v[16:17], v26 offset0:36 offset1:44
	v_lshrrev_b32_e32 v4, 16, v4
	v_add3_u32 v5, v8, v5, s62
	ds_read2_b32 v[18:19], v26 offset0:101 offset1:109
	v_and_or_b32 v4, v5, s63, v4
	s_waitcnt lgkmcnt(3)
	v_bfe_u32 v5, v12, 16, 1
	v_add3_u32 v5, v12, v5, s62
	s_waitcnt lgkmcnt(2)
	v_bfe_u32 v6, v14, 16, 1
	ds_read2_b32 v[20:21], v26 offset0:166 offset1:174
	v_lshrrev_b32_e32 v5, 16, v5
	v_add3_u32 v6, v14, v6, s62
	ds_read2_b32 v[22:23], v26 offset0:231 offset1:239
	v_and_or_b32 v5, v6, s63, v5
	s_waitcnt lgkmcnt(3)
	v_bfe_u32 v6, v16, 16, 1
	v_add3_u32 v6, v16, v6, s62
	s_waitcnt lgkmcnt(2)
	v_bfe_u32 v7, v18, 16, 1
	v_lshrrev_b32_e32 v6, 16, v6
	v_add3_u32 v7, v18, v7, s62
	v_and_or_b32 v6, v7, s63, v6
	s_waitcnt lgkmcnt(1)
	v_bfe_u32 v7, v20, 16, 1
	v_or_b32_e32 v24, s2, v87
	v_add3_u32 v7, v20, v7, s62
	s_waitcnt lgkmcnt(0)
	v_bfe_u32 v8, v22, 16, 1
	v_ashrrev_i32_e32 v25, 31, v24
	v_lshrrev_b32_e32 v7, 16, v7
	v_add3_u32 v8, v22, v8, s62
	v_lshlrev_b64 v[24:25], 12, v[24:25]
	v_and_or_b32 v7, v8, s63, v7
	v_lshl_add_u64 v[24:25], v[2:3], 0, v[24:25]
	global_store_dwordx4 v[24:25], v[4:7], off sc1
	v_bfe_u32 v8, v23, 16, 1
	v_add3_u32 v8, v23, v8, s62
	v_bfe_u32 v4, v11, 16, 1
	v_add3_u32 v4, v11, v4, s62
	v_bfe_u32 v5, v9, 16, 1
	v_lshrrev_b32_e32 v4, 16, v4
	v_add3_u32 v5, v9, v5, s62
	v_and_or_b32 v4, v5, s63, v4
	v_bfe_u32 v5, v13, 16, 1
	v_add3_u32 v5, v13, v5, s62
	v_bfe_u32 v6, v15, 16, 1
	v_lshrrev_b32_e32 v5, 16, v5
	v_add3_u32 v6, v15, v6, s62
	v_and_or_b32 v5, v6, s63, v5
	v_bfe_u32 v6, v17, 16, 1
	v_add3_u32 v6, v17, v6, s62
	v_bfe_u32 v7, v19, 16, 1
	v_lshrrev_b32_e32 v6, 16, v6
	v_add3_u32 v7, v19, v7, s62
	v_and_or_b32 v6, v7, s63, v6
	v_bfe_u32 v7, v21, 16, 1
	v_add3_u32 v7, v21, v7, s62
	v_lshrrev_b32_e32 v7, 16, v7
	v_and_or_b32 v7, v8, s63, v7
	v_or_b32_e32 v8, s2, v88
	v_ashrrev_i32_e32 v9, 31, v8
	v_lshlrev_b64 v[8:9], 12, v[8:9]
	ds_read2_b32 v[10:11], v83 offset0:48 offset1:56
	v_lshl_add_u64 v[8:9], v[2:3], 0, v[8:9]
	global_store_dwordx4 v[8:9], v[4:7], off sc1
	ds_read2_b32 v[8:9], v83 offset0:113 offset1:121
	ds_read2_b32 v[12:13], v83 offset0:178 offset1:186
	ds_read2_b32 v[14:15], v83 offset0:243 offset1:251
	s_waitcnt lgkmcnt(3)
	v_bfe_u32 v4, v10, 16, 1
	v_add3_u32 v4, v10, v4, s62
	s_waitcnt lgkmcnt(2)
	v_bfe_u32 v5, v8, 16, 1
	ds_read2_b32 v[16:17], v26 offset0:52 offset1:60
	v_lshrrev_b32_e32 v4, 16, v4
	v_add3_u32 v5, v8, v5, s62
	ds_read2_b32 v[18:19], v26 offset0:117 offset1:125
	v_and_or_b32 v4, v5, s63, v4
	s_waitcnt lgkmcnt(3)
	v_bfe_u32 v5, v12, 16, 1
	v_add3_u32 v5, v12, v5, s62
	s_waitcnt lgkmcnt(2)
	v_bfe_u32 v6, v14, 16, 1
	ds_read2_b32 v[20:21], v26 offset0:182 offset1:190
	v_lshrrev_b32_e32 v5, 16, v5
	v_add3_u32 v6, v14, v6, s62
	ds_read2_b32 v[22:23], v26 offset0:247 offset1:255
	v_and_or_b32 v5, v6, s63, v5
	s_waitcnt lgkmcnt(3)
	v_bfe_u32 v6, v16, 16, 1
	v_add3_u32 v6, v16, v6, s62
	s_waitcnt lgkmcnt(2)
	v_bfe_u32 v7, v18, 16, 1
	v_lshrrev_b32_e32 v6, 16, v6
	v_add3_u32 v7, v18, v7, s62
	v_and_or_b32 v6, v7, s63, v6
	s_waitcnt lgkmcnt(1)
	v_bfe_u32 v7, v20, 16, 1
	v_or_b32_e32 v24, s2, v89
	v_add3_u32 v7, v20, v7, s62
	s_waitcnt lgkmcnt(0)
	v_bfe_u32 v8, v22, 16, 1
	v_ashrrev_i32_e32 v25, 31, v24
	v_lshrrev_b32_e32 v7, 16, v7
	v_add3_u32 v8, v22, v8, s62
	v_lshlrev_b64 v[24:25], 12, v[24:25]
	v_and_or_b32 v7, v8, s63, v7
	v_lshl_add_u64 v[24:25], v[2:3], 0, v[24:25]
	global_store_dwordx4 v[24:25], v[4:7], off sc1
	v_bfe_u32 v8, v23, 16, 1
	v_add3_u32 v8, v23, v8, s62
	v_bfe_u32 v4, v11, 16, 1
	v_add3_u32 v4, v11, v4, s62
	v_bfe_u32 v5, v9, 16, 1
	v_lshrrev_b32_e32 v4, 16, v4
	v_add3_u32 v5, v9, v5, s62
	v_and_or_b32 v4, v5, s63, v4
	v_bfe_u32 v5, v13, 16, 1
	v_add3_u32 v5, v13, v5, s62
	v_bfe_u32 v6, v15, 16, 1
	v_lshrrev_b32_e32 v5, 16, v5
	v_add3_u32 v6, v15, v6, s62
	v_and_or_b32 v5, v6, s63, v5
	v_bfe_u32 v6, v17, 16, 1
	v_add3_u32 v6, v17, v6, s62
	v_bfe_u32 v7, v19, 16, 1
	v_lshrrev_b32_e32 v6, 16, v6
	v_add3_u32 v7, v19, v7, s62
	v_and_or_b32 v6, v7, s63, v6
	v_bfe_u32 v7, v21, 16, 1
	v_add3_u32 v7, v21, v7, s62
	v_lshrrev_b32_e32 v7, 16, v7
	v_and_or_b32 v7, v8, s63, v7
	v_or_b32_e32 v8, s2, v90
	v_ashrrev_i32_e32 v9, 31, v8
	v_lshlrev_b64 v[8:9], 12, v[8:9]
	v_lshl_add_u64 v[2:3], v[2:3], 0, v[8:9]
	global_store_dwordx4 v[2:3], v[4:7], off sc1
	s_waitcnt lgkmcnt(0)

.LBB0_304:
	s_or_b64 exec, exec, s[16:17]
	v_div_scale_f32 v154, s[16:17], v133, v133, 1.0
	v_rcp_f32_e32 v155, v154
	s_lshl_b64 s[12:13], s[12:13], 24
	s_add_u32 s12, s29, s12
	s_addc_u32 s13, s30, s13
	v_fma_f32 v156, -v154, v155, 1.0
	v_fmac_f32_e32 v155, v156, v155
	v_div_scale_f32 v156, vcc, 1.0, v133, 1.0
	v_mul_f32_e32 v157, v156, v155
	v_fma_f32 v158, -v154, v157, v156
	v_fmac_f32_e32 v157, v158, v155
	v_fma_f32 v154, -v154, v157, v156
	v_div_scale_f32 v156, s[16:17], v132, v132, 1.0
	v_rcp_f32_e32 v158, v156
	v_div_fmas_f32 v154, v154, v155, v157
	v_div_fixup_f32 v133, v154, v133, 1.0
	v_mul_f32_e32 v117, v117, v133
	v_fma_f32 v154, -v156, v158, 1.0
	v_fmac_f32_e32 v158, v154, v158
	v_div_scale_f32 v154, vcc, 1.0, v132, 1.0
	v_mul_f32_e32 v155, v154, v158
	v_fma_f32 v157, -v156, v155, v154
	v_fmac_f32_e32 v155, v157, v158
	v_fma_f32 v154, -v156, v155, v154
	v_div_scale_f32 v156, s[16:17], v131, v131, 1.0
	v_rcp_f32_e32 v157, v156
	v_div_fmas_f32 v154, v154, v158, v155
	v_div_fixup_f32 v132, v154, v132, 1.0
	v_mul_f32_e32 v116, v116, v132
	v_fma_f32 v154, -v156, v157, 1.0
	v_fmac_f32_e32 v157, v154, v157
	v_div_scale_f32 v154, vcc, 1.0, v131, 1.0
	v_mul_f32_e32 v155, v154, v157
	v_fma_f32 v158, -v156, v155, v154
	v_fmac_f32_e32 v155, v158, v157
	v_fma_f32 v154, -v156, v155, v154
	v_div_scale_f32 v156, s[16:17], v130, v130, 1.0
	v_rcp_f32_e32 v158, v156
	v_div_fmas_f32 v154, v154, v157, v155
	v_div_fixup_f32 v131, v154, v131, 1.0
	v_mul_f32_e32 v115, v115, v131
	v_fma_f32 v154, -v156, v158, 1.0
	v_fmac_f32_e32 v158, v154, v158
	v_div_scale_f32 v154, vcc, 1.0, v130, 1.0
	v_mul_f32_e32 v155, v154, v158
	v_fma_f32 v157, -v156, v155, v154
	v_fmac_f32_e32 v155, v157, v158
	v_fma_f32 v154, -v156, v155, v154
	v_div_fmas_f32 v154, v154, v158, v155
	v_div_fixup_f32 v130, v154, v130, 1.0
	v_mul_f32_e32 v114, v114, v130
	v_mul_f32_e32 v126, v126, v130
	v_mul_f32_e32 v98, v98, v130
	v_mul_f32_e32 v110, v110, v130
	v_mul_f32_e32 v82, v82, v130
	v_mul_f32_e32 v94, v94, v130
	v_mul_f32_e32 v66, v66, v130
	v_mul_f32_e32 v78, v78, v130
	v_mul_f32_e32 v50, v50, v130
	v_mul_f32_e32 v62, v62, v130
	v_mul_f32_e32 v34, v34, v130
	v_mul_f32_e32 v46, v46, v130
	v_mul_f32_e32 v18, v18, v130
	v_mul_f32_e32 v30, v30, v130
	v_mul_f32_e32 v2, v2, v130
	v_mul_f32_e32 v14, v14, v130
	v_mul_f32_e32 v118, v118, v130
	v_rndne_f32_e32 v114, v114
	v_rndne_f32_e32 v126, v126
	v_mul_f32_e32 v122, v122, v130
	v_mul_f32_e32 v102, v102, v130
	v_rndne_f32_e32 v98, v98
	v_rndne_f32_e32 v110, v110
	v_mul_f32_e32 v106, v106, v130
	v_mul_f32_e32 v86, v86, v130
	v_rndne_f32_e32 v82, v82
	v_rndne_f32_e32 v94, v94
	v_mul_f32_e32 v90, v90, v130
	v_mul_f32_e32 v70, v70, v130
	v_rndne_f32_e32 v66, v66
	v_rndne_f32_e32 v78, v78
	v_mul_f32_e32 v74, v74, v130
	v_mul_f32_e32 v54, v54, v130
	v_rndne_f32_e32 v50, v50
	v_rndne_f32_e32 v62, v62
	v_mul_f32_e32 v58, v58, v130
	v_mul_f32_e32 v38, v38, v130
	v_rndne_f32_e32 v34, v34
	v_rndne_f32_e32 v46, v46
	v_mul_f32_e32 v42, v42, v130
	v_mul_f32_e32 v22, v22, v130
	v_rndne_f32_e32 v18, v18
	v_rndne_f32_e32 v30, v30
	v_mul_f32_e32 v26, v26, v130
	v_mul_f32_e32 v6, v6, v130
	v_rndne_f32_e32 v2, v2
	v_rndne_f32_e32 v14, v14
	v_mul_f32_e32 v10, v10, v130
	v_rndne_f32_e32 v118, v118
	v_cvt_i32_f32_e32 v114, v114
	v_cvt_i32_f32_e32 v126, v126
	v_rndne_f32_e32 v122, v122
	v_rndne_f32_e32 v102, v102
	v_cvt_i32_f32_e32 v98, v98
	v_cvt_i32_f32_e32 v110, v110
	v_rndne_f32_e32 v106, v106
	v_rndne_f32_e32 v86, v86
	v_cvt_i32_f32_e32 v82, v82
	v_cvt_i32_f32_e32 v94, v94
	v_rndne_f32_e32 v90, v90
	v_rndne_f32_e32 v70, v70
	v_cvt_i32_f32_e32 v66, v66
	v_cvt_i32_f32_e32 v78, v78
	v_rndne_f32_e32 v74, v74
	v_rndne_f32_e32 v54, v54
	v_cvt_i32_f32_e32 v50, v50
	v_cvt_i32_f32_e32 v62, v62
	v_rndne_f32_e32 v58, v58
	v_rndne_f32_e32 v38, v38
	v_cvt_i32_f32_e32 v34, v34
	v_cvt_i32_f32_e32 v46, v46
	v_rndne_f32_e32 v42, v42
	v_rndne_f32_e32 v22, v22
	v_cvt_i32_f32_e32 v18, v18
	v_cvt_i32_f32_e32 v30, v30
	v_rndne_f32_e32 v26, v26
	v_rndne_f32_e32 v6, v6
	v_cvt_i32_f32_e32 v2, v2
	v_cvt_i32_f32_e32 v14, v14
	v_rndne_f32_e32 v10, v10
	v_cvt_i32_f32_e32 v118, v118
	v_cvt_i32_f32_e32 v122, v122
	v_cvt_i32_f32_e32 v102, v102
	v_cvt_i32_f32_e32 v106, v106
	v_cvt_i32_f32_e32 v86, v86
	v_cvt_i32_f32_e32 v90, v90
	v_cvt_i32_f32_e32 v70, v70
	v_cvt_i32_f32_e32 v74, v74
	v_cvt_i32_f32_e32 v54, v54
	v_cvt_i32_f32_e32 v58, v58
	v_cvt_i32_f32_e32 v38, v38
	v_cvt_i32_f32_e32 v42, v42
	v_cvt_i32_f32_e32 v22, v22
	v_cvt_i32_f32_e32 v26, v26
	v_cvt_i32_f32_e32 v6, v6
	v_cvt_i32_f32_e32 v10, v10
	v_med3_i32 v114, v114, s37, v153
	v_med3_i32 v126, v126, s37, v153
	v_med3_i32 v98, v98, s37, v153
	v_med3_i32 v110, v110, s37, v153
	v_med3_i32 v82, v82, s37, v153
	v_med3_i32 v94, v94, s37, v153
	v_med3_i32 v66, v66, s37, v153
	v_med3_i32 v78, v78, s37, v153
	v_med3_i32 v50, v50, s37, v153
	v_med3_i32 v62, v62, s37, v153
	v_med3_i32 v34, v34, s37, v153
	v_med3_i32 v46, v46, s37, v153
	v_med3_i32 v18, v18, s37, v153
	v_med3_i32 v30, v30, s37, v153
	v_med3_i32 v2, v2, s37, v153
	v_med3_i32 v14, v14, s37, v153
	v_med3_i32 v118, v118, s37, v153
	v_med3_i32 v122, v122, s37, v153
	v_lshlrev_b32_e32 v114, 8, v114
	v_lshlrev_b32_e32 v126, 16, v126
	v_med3_i32 v102, v102, s37, v153
	v_med3_i32 v106, v106, s37, v153
	v_lshlrev_b32_e32 v98, 8, v98
	v_lshlrev_b32_e32 v110, 16, v110
	v_med3_i32 v86, v86, s37, v153
	v_med3_i32 v90, v90, s37, v153
	v_lshlrev_b32_e32 v82, 8, v82
	v_lshlrev_b32_e32 v94, 16, v94
	v_med3_i32 v70, v70, s37, v153
	v_med3_i32 v74, v74, s37, v153
	v_lshlrev_b32_e32 v66, 8, v66
	v_lshlrev_b32_e32 v78, 16, v78
	v_med3_i32 v54, v54, s37, v153
	v_med3_i32 v58, v58, s37, v153
	v_lshlrev_b32_e32 v50, 8, v50
	v_lshlrev_b32_e32 v62, 16, v62
	v_med3_i32 v38, v38, s37, v153
	v_med3_i32 v42, v42, s37, v153
	v_lshlrev_b32_e32 v34, 8, v34
	v_lshlrev_b32_e32 v46, 16, v46
	v_med3_i32 v22, v22, s37, v153
	v_med3_i32 v26, v26, s37, v153
	v_lshlrev_b32_e32 v18, 8, v18
	v_lshlrev_b32_e32 v30, 16, v30
	v_med3_i32 v6, v6, s37, v153
	v_med3_i32 v10, v10, s37, v153
	v_lshlrev_b32_e32 v2, 8, v2
	v_lshlrev_b32_e32 v14, 16, v14
	v_and_b32_e32 v114, 0xff00, v114
	v_and_b32_e32 v126, 0xff0000, v126
	v_perm_b32 v118, v122, v118, s38
	v_and_b32_e32 v98, 0xff00, v98
	v_and_b32_e32 v110, 0xff0000, v110
	v_perm_b32 v102, v106, v102, s38
	v_and_b32_e32 v82, 0xff00, v82
	v_and_b32_e32 v94, 0xff0000, v94
	v_perm_b32 v86, v90, v86, s38
	v_and_b32_e32 v66, 0xff00, v66
	v_and_b32_e32 v78, 0xff0000, v78
	v_perm_b32 v70, v74, v70, s38
	v_and_b32_e32 v50, 0xff00, v50
	v_and_b32_e32 v62, 0xff0000, v62
	v_perm_b32 v54, v58, v54, s38
	v_and_b32_e32 v34, 0xff00, v34
	v_and_b32_e32 v46, 0xff0000, v46
	v_perm_b32 v38, v42, v38, s38
	v_and_b32_e32 v18, 0xff00, v18
	v_and_b32_e32 v30, 0xff0000, v30
	v_perm_b32 v22, v26, v22, s38
	v_and_b32_e32 v2, 0xff00, v2
	v_and_b32_e32 v14, 0xff0000, v14
	v_perm_b32 v6, v10, v6, s38
	v_or3_b32 v118, v118, v114, v126
	v_add_u32_e32 v114, v144, v145
	v_mul_f32_e32 v122, v127, v131
	v_or3_b32 v98, v102, v98, v110
	v_mul_f32_e32 v99, v99, v131
	v_mul_f32_e32 v102, v111, v131
	v_or3_b32 v82, v86, v82, v94
	v_mul_f32_e32 v86, v87, v131
	v_mul_f32_e32 v83, v83, v131
	v_mul_f32_e32 v87, v95, v131
	v_or3_b32 v66, v70, v66, v78
	v_mul_f32_e32 v67, v67, v131
	v_mul_f32_e32 v70, v79, v131
	v_or3_b32 v50, v54, v50, v62
	v_mul_f32_e32 v54, v55, v131
	v_mul_f32_e32 v51, v51, v131
	v_mul_f32_e32 v55, v63, v131
	v_or3_b32 v34, v38, v34, v46
	v_mul_f32_e32 v35, v35, v131
	v_mul_f32_e32 v38, v47, v131
	v_or3_b32 v18, v22, v18, v30
	v_mul_f32_e32 v22, v23, v131
	v_mul_f32_e32 v19, v19, v131
	v_mul_f32_e32 v23, v31, v131
	v_or3_b32 v2, v6, v2, v14
	v_mul_f32_e32 v3, v3, v131
	v_mul_f32_e32 v6, v15, v131
	v_mul_f32_e32 v119, v119, v131
	v_rndne_f32_e32 v115, v115
	v_rndne_f32_e32 v122, v122
	v_mul_f32_e32 v123, v123, v131
	ds_write2st64_b32 v114, v118, v98 offset1:1
	v_mul_f32_e32 v98, v103, v131
	v_rndne_f32_e32 v99, v99
	v_rndne_f32_e32 v102, v102
	v_mul_f32_e32 v103, v107, v131
	v_rndne_f32_e32 v83, v83
	v_rndne_f32_e32 v87, v87
	v_mul_f32_e32 v90, v91, v131
	ds_write2st64_b32 v114, v82, v66 offset0:2 offset1:3
	v_mul_f32_e32 v66, v71, v131
	v_rndne_f32_e32 v67, v67
	v_rndne_f32_e32 v70, v70
	v_mul_f32_e32 v71, v75, v131
	v_rndne_f32_e32 v51, v51
	v_rndne_f32_e32 v55, v55
	v_mul_f32_e32 v58, v59, v131
	ds_write2st64_b32 v114, v50, v34 offset0:4 offset1:5
	v_mul_f32_e32 v34, v39, v131
	v_rndne_f32_e32 v35, v35
	v_rndne_f32_e32 v38, v38
	v_mul_f32_e32 v39, v43, v131
	v_rndne_f32_e32 v19, v19
	v_rndne_f32_e32 v23, v23
	v_mul_f32_e32 v26, v27, v131
	ds_write2st64_b32 v114, v18, v2 offset0:6 offset1:7
	v_mul_f32_e32 v2, v7, v131
	v_rndne_f32_e32 v3, v3
	v_rndne_f32_e32 v6, v6
	v_mul_f32_e32 v7, v11, v131
	v_rndne_f32_e32 v119, v119
	v_cvt_i32_f32_e32 v115, v115
	v_cvt_i32_f32_e32 v122, v122
	v_rndne_f32_e32 v123, v123
	v_rndne_f32_e32 v98, v98
	v_cvt_i32_f32_e32 v99, v99
	v_cvt_i32_f32_e32 v102, v102
	v_rndne_f32_e32 v103, v103
	v_rndne_f32_e32 v86, v86
	v_cvt_i32_f32_e32 v83, v83
	v_cvt_i32_f32_e32 v87, v87
	v_rndne_f32_e32 v90, v90
	v_rndne_f32_e32 v66, v66
	v_cvt_i32_f32_e32 v67, v67
	v_cvt_i32_f32_e32 v70, v70
	v_rndne_f32_e32 v71, v71
	v_rndne_f32_e32 v54, v54
	v_cvt_i32_f32_e32 v51, v51
	v_cvt_i32_f32_e32 v55, v55
	v_rndne_f32_e32 v58, v58
	v_rndne_f32_e32 v34, v34
	v_cvt_i32_f32_e32 v35, v35
	v_cvt_i32_f32_e32 v38, v38
	v_rndne_f32_e32 v39, v39
	v_rndne_f32_e32 v22, v22
	v_cvt_i32_f32_e32 v19, v19
	v_cvt_i32_f32_e32 v23, v23
	v_rndne_f32_e32 v26, v26
	v_rndne_f32_e32 v2, v2
	v_cvt_i32_f32_e32 v3, v3
	v_cvt_i32_f32_e32 v6, v6
	v_rndne_f32_e32 v7, v7
	v_cvt_i32_f32_e32 v119, v119
	v_cvt_i32_f32_e32 v123, v123
	v_cvt_i32_f32_e32 v98, v98
	v_cvt_i32_f32_e32 v103, v103
	v_cvt_i32_f32_e32 v86, v86
	v_cvt_i32_f32_e32 v90, v90
	v_cvt_i32_f32_e32 v66, v66
	v_cvt_i32_f32_e32 v71, v71
	v_cvt_i32_f32_e32 v54, v54
	v_cvt_i32_f32_e32 v58, v58
	v_cvt_i32_f32_e32 v34, v34
	v_cvt_i32_f32_e32 v39, v39
	v_cvt_i32_f32_e32 v22, v22
	v_cvt_i32_f32_e32 v26, v26
	v_cvt_i32_f32_e32 v2, v2
	v_cvt_i32_f32_e32 v7, v7
	v_med3_i32 v115, v115, s37, v153
	v_med3_i32 v122, v122, s37, v153
	v_med3_i32 v99, v99, s37, v153
	v_med3_i32 v102, v102, s37, v153
	v_med3_i32 v83, v83, s37, v153
	v_med3_i32 v87, v87, s37, v153
	v_med3_i32 v67, v67, s37, v153
	v_med3_i32 v70, v70, s37, v153
	v_med3_i32 v51, v51, s37, v153
	v_med3_i32 v55, v55, s37, v153
	v_med3_i32 v35, v35, s37, v153
	v_med3_i32 v38, v38, s37, v153
	v_med3_i32 v19, v19, s37, v153
	v_med3_i32 v23, v23, s37, v153
	v_med3_i32 v3, v3, s37, v153
	v_med3_i32 v6, v6, s37, v153
	v_med3_i32 v119, v119, s37, v153
	v_med3_i32 v123, v123, s37, v153
	v_lshlrev_b32_e32 v115, 8, v115
	v_lshlrev_b32_e32 v122, 16, v122
	v_med3_i32 v98, v98, s37, v153
	v_med3_i32 v103, v103, s37, v153
	v_lshlrev_b32_e32 v99, 8, v99
	v_lshlrev_b32_e32 v102, 16, v102
	v_med3_i32 v86, v86, s37, v153
	v_med3_i32 v90, v90, s37, v153
	v_lshlrev_b32_e32 v83, 8, v83
	v_lshlrev_b32_e32 v87, 16, v87
	v_med3_i32 v66, v66, s37, v153
	v_med3_i32 v71, v71, s37, v153
	v_lshlrev_b32_e32 v67, 8, v67
	v_lshlrev_b32_e32 v70, 16, v70
	v_med3_i32 v54, v54, s37, v153
	v_med3_i32 v58, v58, s37, v153
	v_lshlrev_b32_e32 v51, 8, v51
	v_lshlrev_b32_e32 v55, 16, v55
	v_med3_i32 v34, v34, s37, v153
	v_med3_i32 v39, v39, s37, v153
	v_lshlrev_b32_e32 v35, 8, v35
	v_lshlrev_b32_e32 v38, 16, v38
	v_med3_i32 v22, v22, s37, v153
	v_med3_i32 v26, v26, s37, v153
	v_lshlrev_b32_e32 v19, 8, v19
	v_lshlrev_b32_e32 v23, 16, v23
	v_med3_i32 v2, v2, s37, v153
	v_med3_i32 v7, v7, s37, v153
	v_lshlrev_b32_e32 v3, 8, v3
	v_lshlrev_b32_e32 v6, 16, v6
	v_and_b32_e32 v115, 0xff00, v115
	v_and_b32_e32 v122, 0xff0000, v122
	v_perm_b32 v119, v123, v119, s38
	v_and_b32_e32 v99, 0xff00, v99
	v_and_b32_e32 v102, 0xff0000, v102
	v_perm_b32 v98, v103, v98, s38
	v_and_b32_e32 v83, 0xff00, v83
	v_and_b32_e32 v87, 0xff0000, v87
	v_perm_b32 v86, v90, v86, s38
	v_and_b32_e32 v67, 0xff00, v67
	v_and_b32_e32 v70, 0xff0000, v70
	v_perm_b32 v66, v71, v66, s38
	v_and_b32_e32 v51, 0xff00, v51
	v_and_b32_e32 v55, 0xff0000, v55
	v_perm_b32 v54, v58, v54, s38
	v_and_b32_e32 v35, 0xff00, v35
	v_and_b32_e32 v38, 0xff0000, v38
	v_perm_b32 v34, v39, v34, s38
	v_and_b32_e32 v19, 0xff00, v19
	v_and_b32_e32 v23, 0xff0000, v23
	v_perm_b32 v22, v26, v22, s38
	v_and_b32_e32 v3, 0xff00, v3
	v_and_b32_e32 v6, 0xff0000, v6
	v_perm_b32 v2, v7, v2, s38
	v_or3_b32 v115, v119, v115, v122
	v_mul_f32_e32 v119, v120, v132
	v_mul_f32_e32 v120, v128, v132
	v_or3_b32 v99, v98, v99, v102
	v_add_u32_e32 v98, 16, v114
	v_mul_f32_e32 v100, v100, v132
	v_mul_f32_e32 v102, v112, v132
	v_or3_b32 v83, v86, v83, v87
	v_mul_f32_e32 v84, v84, v132
	v_mul_f32_e32 v87, v96, v132
	v_or3_b32 v66, v66, v67, v70
	v_mul_f32_e32 v67, v68, v132
	v_mul_f32_e32 v68, v80, v132
	v_or3_b32 v51, v54, v51, v55
	v_mul_f32_e32 v52, v52, v132
	v_mul_f32_e32 v55, v64, v132
	v_or3_b32 v34, v34, v35, v38
	v_mul_f32_e32 v35, v36, v132
	v_mul_f32_e32 v36, v48, v132
	v_or3_b32 v19, v22, v19, v23
	v_mul_f32_e32 v20, v20, v132
	v_mul_f32_e32 v23, v32, v132
	v_or3_b32 v2, v2, v3, v6
	v_mul_f32_e32 v3, v4, v132
	v_mul_f32_e32 v4, v16, v132
	v_rndne_f32_e32 v116, v116
	v_rndne_f32_e32 v120, v120
	v_mul_f32_e32 v122, v124, v132
	ds_write2st64_b32 v98, v115, v99 offset0:8 offset1:9
	v_mul_f32_e32 v99, v104, v132
	v_rndne_f32_e32 v100, v100
	v_rndne_f32_e32 v102, v102
	v_mul_f32_e32 v103, v108, v132
	v_mul_f32_e32 v86, v88, v132
	v_rndne_f32_e32 v84, v84
	v_rndne_f32_e32 v87, v87
	v_mul_f32_e32 v88, v92, v132
	ds_write2st64_b32 v98, v83, v66 offset0:10 offset1:11
	v_mul_f32_e32 v66, v72, v132
	v_rndne_f32_e32 v67, v67
	v_rndne_f32_e32 v68, v68
	v_mul_f32_e32 v70, v76, v132
	v_mul_f32_e32 v54, v56, v132
	v_rndne_f32_e32 v52, v52
	v_rndne_f32_e32 v55, v55
	v_mul_f32_e32 v56, v60, v132
	ds_write2st64_b32 v98, v51, v34 offset0:12 offset1:13
	v_mul_f32_e32 v34, v40, v132
	v_rndne_f32_e32 v35, v35
	v_rndne_f32_e32 v36, v36
	v_mul_f32_e32 v38, v44, v132
	v_mul_f32_e32 v22, v24, v132
	v_rndne_f32_e32 v20, v20
	v_rndne_f32_e32 v23, v23
	v_mul_f32_e32 v24, v28, v132
	ds_write2st64_b32 v98, v19, v2 offset0:14 offset1:15
	v_mul_f32_e32 v2, v8, v132
	v_rndne_f32_e32 v3, v3
	v_rndne_f32_e32 v4, v4
	v_mul_f32_e32 v6, v12, v132
	v_rndne_f32_e32 v119, v119
	v_cvt_i32_f32_e32 v116, v116
	v_cvt_i32_f32_e32 v120, v120
	v_rndne_f32_e32 v122, v122
	v_rndne_f32_e32 v99, v99
	v_cvt_i32_f32_e32 v100, v100
	v_cvt_i32_f32_e32 v102, v102
	v_rndne_f32_e32 v103, v103
	v_rndne_f32_e32 v86, v86
	v_cvt_i32_f32_e32 v84, v84
	v_cvt_i32_f32_e32 v87, v87
	v_rndne_f32_e32 v88, v88
	v_rndne_f32_e32 v66, v66
	v_cvt_i32_f32_e32 v67, v67
	v_cvt_i32_f32_e32 v68, v68
	v_rndne_f32_e32 v70, v70
	v_rndne_f32_e32 v54, v54
	v_cvt_i32_f32_e32 v52, v52
	v_cvt_i32_f32_e32 v55, v55
	v_rndne_f32_e32 v56, v56
	v_rndne_f32_e32 v34, v34
	v_cvt_i32_f32_e32 v35, v35
	v_cvt_i32_f32_e32 v36, v36
	v_rndne_f32_e32 v38, v38
	v_rndne_f32_e32 v22, v22
	v_cvt_i32_f32_e32 v20, v20
	v_cvt_i32_f32_e32 v23, v23
	v_rndne_f32_e32 v24, v24
	v_rndne_f32_e32 v2, v2
	v_cvt_i32_f32_e32 v3, v3
	v_cvt_i32_f32_e32 v4, v4
	v_rndne_f32_e32 v6, v6
	v_cvt_i32_f32_e32 v119, v119
	v_cvt_i32_f32_e32 v122, v122
	v_cvt_i32_f32_e32 v99, v99
	v_cvt_i32_f32_e32 v103, v103
	v_cvt_i32_f32_e32 v86, v86
	v_cvt_i32_f32_e32 v88, v88
	v_cvt_i32_f32_e32 v66, v66
	v_cvt_i32_f32_e32 v70, v70
	v_cvt_i32_f32_e32 v54, v54
	v_cvt_i32_f32_e32 v56, v56
	v_cvt_i32_f32_e32 v34, v34
	v_cvt_i32_f32_e32 v38, v38
	v_cvt_i32_f32_e32 v22, v22
	v_cvt_i32_f32_e32 v24, v24
	v_cvt_i32_f32_e32 v2, v2
	v_cvt_i32_f32_e32 v6, v6
	v_med3_i32 v116, v116, s37, v153
	v_med3_i32 v120, v120, s37, v153
	v_med3_i32 v100, v100, s37, v153
	v_med3_i32 v102, v102, s37, v153
	v_med3_i32 v84, v84, s37, v153
	v_med3_i32 v87, v87, s37, v153
	v_med3_i32 v67, v67, s37, v153
	v_med3_i32 v68, v68, s37, v153
	v_med3_i32 v52, v52, s37, v153
	v_med3_i32 v55, v55, s37, v153
	v_med3_i32 v35, v35, s37, v153
	v_med3_i32 v36, v36, s37, v153
	v_med3_i32 v20, v20, s37, v153
	v_med3_i32 v23, v23, s37, v153
	v_med3_i32 v3, v3, s37, v153
	v_med3_i32 v4, v4, s37, v153
	v_med3_i32 v119, v119, s37, v153
	v_med3_i32 v122, v122, s37, v153
	v_lshlrev_b32_e32 v116, 8, v116
	v_lshlrev_b32_e32 v120, 16, v120
	v_med3_i32 v99, v99, s37, v153
	v_med3_i32 v103, v103, s37, v153
	v_lshlrev_b32_e32 v100, 8, v100
	v_lshlrev_b32_e32 v102, 16, v102
	v_med3_i32 v86, v86, s37, v153
	v_med3_i32 v88, v88, s37, v153
	v_lshlrev_b32_e32 v84, 8, v84
	v_lshlrev_b32_e32 v87, 16, v87
	v_med3_i32 v66, v66, s37, v153
	v_med3_i32 v70, v70, s37, v153
	v_lshlrev_b32_e32 v67, 8, v67
	v_lshlrev_b32_e32 v68, 16, v68
	v_med3_i32 v54, v54, s37, v153
	v_med3_i32 v56, v56, s37, v153
	v_lshlrev_b32_e32 v52, 8, v52
	v_lshlrev_b32_e32 v55, 16, v55
	v_med3_i32 v34, v34, s37, v153
	v_med3_i32 v38, v38, s37, v153
	v_lshlrev_b32_e32 v35, 8, v35
	v_lshlrev_b32_e32 v36, 16, v36
	v_med3_i32 v22, v22, s37, v153
	v_med3_i32 v24, v24, s37, v153
	v_lshlrev_b32_e32 v20, 8, v20
	v_lshlrev_b32_e32 v23, 16, v23
	v_med3_i32 v2, v2, s37, v153
	v_med3_i32 v6, v6, s37, v153
	v_lshlrev_b32_e32 v3, 8, v3
	v_lshlrev_b32_e32 v4, 16, v4
	v_and_b32_e32 v116, 0xff00, v116
	v_and_b32_e32 v120, 0xff0000, v120
	v_perm_b32 v119, v122, v119, s38
	v_and_b32_e32 v100, 0xff00, v100
	v_and_b32_e32 v102, 0xff0000, v102
	v_perm_b32 v99, v103, v99, s38
	v_and_b32_e32 v84, 0xff00, v84
	v_and_b32_e32 v87, 0xff0000, v87
	v_perm_b32 v86, v88, v86, s38
	v_and_b32_e32 v67, 0xff00, v67
	v_and_b32_e32 v68, 0xff0000, v68
	v_perm_b32 v66, v70, v66, s38
	v_and_b32_e32 v52, 0xff00, v52
	v_and_b32_e32 v55, 0xff0000, v55
	v_perm_b32 v54, v56, v54, s38
	v_and_b32_e32 v35, 0xff00, v35
	v_and_b32_e32 v36, 0xff0000, v36
	v_perm_b32 v34, v38, v34, s38
	v_and_b32_e32 v20, 0xff00, v20
	v_and_b32_e32 v23, 0xff0000, v23
	v_perm_b32 v22, v24, v22, s38
	v_and_b32_e32 v3, 0xff00, v3
	v_and_b32_e32 v4, 0xff0000, v4
	v_perm_b32 v2, v6, v2, s38
	v_or3_b32 v116, v119, v116, v120
	v_mul_f32_e32 v120, v129, v133
	v_or3_b32 v100, v99, v100, v102
	v_add_u32_e32 v99, 32, v114
	v_mul_f32_e32 v101, v101, v133
	v_mul_f32_e32 v102, v113, v133
	v_or3_b32 v84, v86, v84, v87
	v_mul_f32_e32 v85, v85, v133
	v_mul_f32_e32 v87, v97, v133
	v_or3_b32 v66, v66, v67, v68
	v_mul_f32_e32 v67, v69, v133
	v_mul_f32_e32 v68, v81, v133
	v_or3_b32 v52, v54, v52, v55
	v_mul_f32_e32 v53, v53, v133
	v_mul_f32_e32 v55, v65, v133
	v_or3_b32 v34, v34, v35, v36
	v_mul_f32_e32 v35, v37, v133
	v_mul_f32_e32 v36, v49, v133
	v_or3_b32 v20, v22, v20, v23
	v_mul_f32_e32 v21, v21, v133
	v_mul_f32_e32 v23, v33, v133
	v_or3_b32 v2, v2, v3, v4
	v_mul_f32_e32 v3, v5, v133
	v_mul_f32_e32 v4, v17, v133
	v_mul_f32_e32 v119, v121, v133
	v_rndne_f32_e32 v117, v117
	v_rndne_f32_e32 v120, v120
	v_mul_f32_e32 v121, v125, v133
	ds_write2st64_b32 v99, v116, v100 offset0:16 offset1:17
	v_mul_f32_e32 v100, v105, v133
	v_rndne_f32_e32 v101, v101
	v_rndne_f32_e32 v102, v102
	v_mul_f32_e32 v103, v109, v133
	v_mul_f32_e32 v86, v89, v133
	v_rndne_f32_e32 v85, v85
	v_rndne_f32_e32 v87, v87
	v_mul_f32_e32 v88, v93, v133
	ds_write2st64_b32 v99, v84, v66 offset0:18 offset1:19
	v_mul_f32_e32 v66, v73, v133
	v_rndne_f32_e32 v67, v67
	v_rndne_f32_e32 v68, v68
	v_mul_f32_e32 v69, v77, v133
	v_mul_f32_e32 v54, v57, v133
	v_rndne_f32_e32 v53, v53
	v_rndne_f32_e32 v55, v55
	v_mul_f32_e32 v56, v61, v133
	ds_write2st64_b32 v99, v52, v34 offset0:20 offset1:21
	v_mul_f32_e32 v34, v41, v133
	v_rndne_f32_e32 v35, v35
	v_rndne_f32_e32 v36, v36
	v_mul_f32_e32 v37, v45, v133
	v_mul_f32_e32 v22, v25, v133
	v_rndne_f32_e32 v21, v21
	v_rndne_f32_e32 v23, v23
	v_mul_f32_e32 v24, v29, v133
	ds_write2st64_b32 v99, v20, v2 offset0:22 offset1:23
	v_mul_f32_e32 v2, v9, v133
	v_rndne_f32_e32 v3, v3
	v_rndne_f32_e32 v4, v4
	v_mul_f32_e32 v5, v13, v133
	v_rndne_f32_e32 v119, v119
	v_cvt_i32_f32_e32 v117, v117
	v_cvt_i32_f32_e32 v120, v120
	v_rndne_f32_e32 v121, v121
	v_rndne_f32_e32 v100, v100
	v_cvt_i32_f32_e32 v101, v101
	v_cvt_i32_f32_e32 v102, v102
	v_rndne_f32_e32 v103, v103
	v_rndne_f32_e32 v86, v86
	v_cvt_i32_f32_e32 v85, v85
	v_cvt_i32_f32_e32 v87, v87
	v_rndne_f32_e32 v88, v88
	v_rndne_f32_e32 v66, v66
	v_cvt_i32_f32_e32 v67, v67
	v_cvt_i32_f32_e32 v68, v68
	v_rndne_f32_e32 v69, v69
	v_rndne_f32_e32 v54, v54
	v_cvt_i32_f32_e32 v53, v53
	v_cvt_i32_f32_e32 v55, v55
	v_rndne_f32_e32 v56, v56
	v_rndne_f32_e32 v34, v34
	v_cvt_i32_f32_e32 v35, v35
	v_cvt_i32_f32_e32 v36, v36
	v_rndne_f32_e32 v37, v37
	v_rndne_f32_e32 v22, v22
	v_cvt_i32_f32_e32 v21, v21
	v_cvt_i32_f32_e32 v23, v23
	v_rndne_f32_e32 v24, v24
	v_rndne_f32_e32 v2, v2
	v_cvt_i32_f32_e32 v3, v3
	v_cvt_i32_f32_e32 v4, v4
	v_rndne_f32_e32 v5, v5
	v_cvt_i32_f32_e32 v119, v119
	v_cvt_i32_f32_e32 v121, v121
	v_cvt_i32_f32_e32 v100, v100
	v_cvt_i32_f32_e32 v103, v103
	v_cvt_i32_f32_e32 v86, v86
	v_cvt_i32_f32_e32 v88, v88
	v_cvt_i32_f32_e32 v66, v66
	v_cvt_i32_f32_e32 v69, v69
	v_cvt_i32_f32_e32 v54, v54
	v_cvt_i32_f32_e32 v56, v56
	v_cvt_i32_f32_e32 v34, v34
	v_cvt_i32_f32_e32 v37, v37
	v_cvt_i32_f32_e32 v22, v22
	v_cvt_i32_f32_e32 v24, v24
	v_cvt_i32_f32_e32 v2, v2
	v_cvt_i32_f32_e32 v5, v5
	v_med3_i32 v117, v117, s37, v153
	v_med3_i32 v120, v120, s37, v153
	v_med3_i32 v101, v101, s37, v153
	v_med3_i32 v102, v102, s37, v153
	v_med3_i32 v85, v85, s37, v153
	v_med3_i32 v87, v87, s37, v153
	v_med3_i32 v67, v67, s37, v153
	v_med3_i32 v68, v68, s37, v153
	v_med3_i32 v53, v53, s37, v153
	v_med3_i32 v55, v55, s37, v153
	v_med3_i32 v35, v35, s37, v153
	v_med3_i32 v36, v36, s37, v153
	v_med3_i32 v21, v21, s37, v153
	v_med3_i32 v23, v23, s37, v153
	v_med3_i32 v3, v3, s37, v153
	v_med3_i32 v4, v4, s37, v153
	v_med3_i32 v119, v119, s37, v153
	v_med3_i32 v121, v121, s37, v153
	v_lshlrev_b32_e32 v117, 8, v117
	v_lshlrev_b32_e32 v120, 16, v120
	v_med3_i32 v100, v100, s37, v153
	v_med3_i32 v103, v103, s37, v153
	v_lshlrev_b32_e32 v101, 8, v101
	v_lshlrev_b32_e32 v102, 16, v102
	v_med3_i32 v86, v86, s37, v153
	v_med3_i32 v88, v88, s37, v153
	v_lshlrev_b32_e32 v85, 8, v85
	v_lshlrev_b32_e32 v87, 16, v87
	v_med3_i32 v66, v66, s37, v153
	v_med3_i32 v69, v69, s37, v153
	v_lshlrev_b32_e32 v67, 8, v67
	v_lshlrev_b32_e32 v68, 16, v68
	v_med3_i32 v54, v54, s37, v153
	v_med3_i32 v56, v56, s37, v153
	v_lshlrev_b32_e32 v53, 8, v53
	v_lshlrev_b32_e32 v55, 16, v55
	v_med3_i32 v34, v34, s37, v153
	v_med3_i32 v37, v37, s37, v153
	v_lshlrev_b32_e32 v35, 8, v35
	v_lshlrev_b32_e32 v36, 16, v36
	v_med3_i32 v22, v22, s37, v153
	v_med3_i32 v24, v24, s37, v153
	v_lshlrev_b32_e32 v21, 8, v21
	v_lshlrev_b32_e32 v23, 16, v23
	v_med3_i32 v2, v2, s37, v153
	v_med3_i32 v5, v5, s37, v153
	v_lshlrev_b32_e32 v3, 8, v3
	v_lshlrev_b32_e32 v4, 16, v4
	v_and_b32_e32 v117, 0xff00, v117
	v_and_b32_e32 v120, 0xff0000, v120
	v_perm_b32 v119, v121, v119, s38
	v_and_b32_e32 v101, 0xff00, v101
	v_and_b32_e32 v102, 0xff0000, v102
	v_perm_b32 v100, v103, v100, s38
	v_and_b32_e32 v85, 0xff00, v85
	v_and_b32_e32 v87, 0xff0000, v87
	v_perm_b32 v86, v88, v86, s38
	v_and_b32_e32 v67, 0xff00, v67
	v_and_b32_e32 v68, 0xff0000, v68
	v_perm_b32 v66, v69, v66, s38
	v_and_b32_e32 v53, 0xff00, v53
	v_and_b32_e32 v55, 0xff0000, v55
	v_perm_b32 v54, v56, v54, s38
	v_and_b32_e32 v35, 0xff00, v35
	v_and_b32_e32 v36, 0xff0000, v36
	v_perm_b32 v34, v37, v34, s38
	v_and_b32_e32 v21, 0xff00, v21
	v_and_b32_e32 v23, 0xff0000, v23
	v_perm_b32 v22, v24, v22, s38
	v_and_b32_e32 v3, 0xff00, v3
	v_and_b32_e32 v4, 0xff0000, v4
	v_perm_b32 v2, v5, v2, s38
	v_or3_b32 v117, v119, v117, v120
	v_or3_b32 v101, v100, v101, v102
	v_add_u32_e32 v100, 48, v114
	v_or3_b32 v85, v86, v85, v87
	v_or3_b32 v66, v66, v67, v68
	v_or3_b32 v53, v54, v53, v55
	v_or3_b32 v34, v34, v35, v36
	v_or3_b32 v21, v22, v21, v23
	v_or3_b32 v2, v2, v3, v4
	v_add_lshl_u32 v10, s20, v146, 11
	v_mov_b32_e32 v11, v137
	v_add_u32_e32 v18, v147, v138
	ds_write2st64_b32 v100, v117, v101 offset0:24 offset1:25
	ds_write2st64_b32 v100, v85, v66 offset0:26 offset1:27
	ds_write2st64_b32 v100, v53, v34 offset0:28 offset1:29
	ds_write2st64_b32 v100, v21, v2 offset0:30 offset1:31
	s_waitcnt lgkmcnt(0)
	s_barrier
	ds_read_b128 v[2:5], v18
	ds_read_b128 v[6:9], v18 offset:256
	v_lshl_add_u64 v[14:15], s[12:13], 0, v[10:11]
	ds_read_b128 v[10:13], v18 offset:512
	v_lshl_add_u64 v[22:23], v[14:15], 0, v[138:139]
	s_waitcnt lgkmcnt(2)
	global_store_dwordx4 v[22:23], v[2:5], off sc1
	s_waitcnt lgkmcnt(1)
	global_store_dwordx4 v[22:23], v[6:9], off offset:256 sc1
	ds_read_b128 v[2:5], v18 offset:768
	s_waitcnt lgkmcnt(1)
	global_store_dwordx4 v[22:23], v[10:13], off offset:512 sc1
	ds_read_b128 v[6:9], v18 offset:1024
	ds_read_b128 v[10:13], v18 offset:1280
	ds_read_b128 v[14:17], v18 offset:1536
	ds_read_b128 v[18:21], v18 offset:1792
	s_waitcnt lgkmcnt(4)
	global_store_dwordx4 v[22:23], v[2:5], off offset:768 sc1
	s_waitcnt lgkmcnt(3)
	global_store_dwordx4 v[22:23], v[6:9], off offset:1024 sc1
	s_waitcnt lgkmcnt(2)
	global_store_dwordx4 v[22:23], v[10:13], off offset:1280 sc1
	s_waitcnt lgkmcnt(1)
	global_store_dwordx4 v[22:23], v[14:17], off offset:1536 sc1
	s_waitcnt lgkmcnt(0)
	global_store_dwordx4 v[22:23], v[18:21], off offset:1792 sc1
	s_barrier

.LBB0_316:
	s_or_b64 exec, exec, s[16:17]
	s_waitcnt lgkmcnt(0)
	s_barrier
	ds_read_b128 v[130:133], v143
	ds_read_b128 v[154:157], v143 offset:128
	s_waitcnt lgkmcnt(1)
	v_max_f32_e32 v130, v130, v130
	s_waitcnt lgkmcnt(0)
	v_max_f32_e32 v154, v154, v154
	v_max_f32_e32 v158, v130, v154
	v_max_f32_e32 v130, v155, v155
	v_max_f32_e32 v131, v131, v131
	v_max_f32_e32 v159, v131, v130
	v_max_f32_e32 v130, v156, v156
	v_max_f32_e32 v131, v132, v132
	v_max_f32_e32 v160, v131, v130
	v_max_f32_e32 v130, v157, v157
	v_max_f32_e32 v131, v133, v133
	v_max_f32_e32 v161, v131, v130
	ds_read_b128 v[130:133], v143 offset:256
	ds_read_b128 v[154:157], v143 offset:384
	s_waitcnt lgkmcnt(0)
	v_max3_f32 v161, v161, v133, v157
	v_max3_f32 v160, v160, v132, v156
	v_max3_f32 v159, v159, v131, v155
	v_max3_f32 v158, v158, v130, v154
	ds_read_b128 v[130:133], v143 offset:512
	ds_read_b128 v[154:157], v143 offset:640
	s_waitcnt lgkmcnt(0)
	v_max3_f32 v158, v158, v130, v154
	v_max3_f32 v159, v159, v131, v155
	v_max3_f32 v160, v160, v132, v156
	v_max3_f32 v161, v161, v133, v157
	ds_read_b128 v[130:133], v143 offset:768
	ds_read_b128 v[154:157], v143 offset:896
	s_waitcnt lgkmcnt(0)
	v_max3_f32 v133, v161, v133, v157
	v_max3_f32 v132, v160, v132, v156
	v_max3_f32 v131, v159, v131, v155
	v_max3_f32 v130, v158, v130, v154
	v_max_f32_e32 v130, 0xda24260, v130
	v_max_f32_e32 v131, 0xda24260, v131
	v_max_f32_e32 v132, 0xda24260, v132
	v_max_f32_e32 v133, 0xda24260, v133
	v_pk_mul_f32 v[130:131], v[130:131], s[8:9] op_sel_hi:[1,0]
	v_pk_mul_f32 v[132:133], v[132:133], s[8:9] op_sel_hi:[1,0]
	s_and_saveexec_b64 s[16:17], s[2:3]
	s_cbranch_execz .LBB0_318
	s_lshl_b32 s42, s12, 11
	s_mov_b32 s43, s11
	s_lshl_b64 s[42:43], s[42:43], 2
	s_add_u32 s13, s26, s42
	s_addc_u32 s21, s27, s43
	s_add_u32 s42, s13, s10
	s_addc_u32 s43, s21, 0
	global_store_dwordx4 v136, v[130:133], s[42:43] sc1
.LBB0_318:
	s_or_b64 exec, exec, s[16:17]
	v_div_scale_f32 v154, s[16:17], v133, v133, 1.0
	v_rcp_f32_e32 v155, v154
	s_mov_b32 s13, s11
	s_lshl_b64 s[12:13], s[12:13], 22
	s_add_u32 s12, s24, s12
	v_fma_f32 v156, -v154, v155, 1.0
	v_fmac_f32_e32 v155, v156, v155
	v_div_scale_f32 v156, vcc, 1.0, v133, 1.0
	v_mul_f32_e32 v157, v156, v155
	v_fma_f32 v158, -v154, v157, v156
	v_fmac_f32_e32 v157, v158, v155
	v_fma_f32 v154, -v154, v157, v156
	v_div_scale_f32 v156, s[16:17], v132, v132, 1.0
	v_rcp_f32_e32 v158, v156
	v_div_fmas_f32 v154, v154, v155, v157
	v_div_fixup_f32 v133, v154, v133, 1.0
	v_mul_f32_e32 v117, v117, v133
	v_fma_f32 v154, -v156, v158, 1.0
	v_fmac_f32_e32 v158, v154, v158
	v_div_scale_f32 v154, vcc, 1.0, v132, 1.0
	v_mul_f32_e32 v155, v154, v158
	v_fma_f32 v157, -v156, v155, v154
	v_fmac_f32_e32 v155, v157, v158
	v_fma_f32 v154, -v156, v155, v154
	v_div_scale_f32 v156, s[16:17], v131, v131, 1.0
	v_rcp_f32_e32 v157, v156
	v_div_fmas_f32 v154, v154, v158, v155
	v_div_fixup_f32 v132, v154, v132, 1.0
	v_mul_f32_e32 v116, v116, v132
	v_fma_f32 v154, -v156, v157, 1.0
	v_fmac_f32_e32 v157, v154, v157
	v_div_scale_f32 v154, vcc, 1.0, v131, 1.0
	v_mul_f32_e32 v155, v154, v157
	v_fma_f32 v158, -v156, v155, v154
	v_fmac_f32_e32 v155, v158, v157
	v_fma_f32 v154, -v156, v155, v154
	v_div_scale_f32 v156, s[16:17], v130, v130, 1.0
	v_rcp_f32_e32 v158, v156
	v_div_fmas_f32 v154, v154, v157, v155
	v_div_fixup_f32 v131, v154, v131, 1.0
	v_mul_f32_e32 v115, v115, v131
	v_fma_f32 v154, -v156, v158, 1.0
	v_fmac_f32_e32 v158, v154, v158
	v_div_scale_f32 v154, vcc, 1.0, v130, 1.0
	v_mul_f32_e32 v155, v154, v158
	v_fma_f32 v157, -v156, v155, v154
	v_fmac_f32_e32 v155, v157, v158
	v_fma_f32 v154, -v156, v155, v154
	v_div_fmas_f32 v154, v154, v158, v155
	v_div_fixup_f32 v130, v154, v130, 1.0
	v_mul_f32_e32 v114, v114, v130
	v_mul_f32_e32 v126, v126, v130
	v_mul_f32_e32 v98, v98, v130
	v_mul_f32_e32 v110, v110, v130
	v_mul_f32_e32 v82, v82, v130
	v_mul_f32_e32 v94, v94, v130
	v_mul_f32_e32 v66, v66, v130
	v_mul_f32_e32 v78, v78, v130
	v_mul_f32_e32 v50, v50, v130
	v_mul_f32_e32 v62, v62, v130
	v_mul_f32_e32 v34, v34, v130
	v_mul_f32_e32 v46, v46, v130
	v_mul_f32_e32 v18, v18, v130
	v_mul_f32_e32 v30, v30, v130
	v_mul_f32_e32 v2, v2, v130
	v_mul_f32_e32 v14, v14, v130
	v_mul_f32_e32 v118, v118, v130
	v_rndne_f32_e32 v114, v114
	v_rndne_f32_e32 v126, v126
	v_mul_f32_e32 v122, v122, v130
	v_mul_f32_e32 v102, v102, v130
	v_rndne_f32_e32 v98, v98
	v_rndne_f32_e32 v110, v110
	v_mul_f32_e32 v106, v106, v130
	v_mul_f32_e32 v86, v86, v130
	v_rndne_f32_e32 v82, v82
	v_rndne_f32_e32 v94, v94
	v_mul_f32_e32 v90, v90, v130
	v_mul_f32_e32 v70, v70, v130
	v_rndne_f32_e32 v66, v66
	v_rndne_f32_e32 v78, v78
	v_mul_f32_e32 v74, v74, v130
	v_mul_f32_e32 v54, v54, v130
	v_rndne_f32_e32 v50, v50
	v_rndne_f32_e32 v62, v62
	v_mul_f32_e32 v58, v58, v130
	v_mul_f32_e32 v38, v38, v130
	v_rndne_f32_e32 v34, v34
	v_rndne_f32_e32 v46, v46
	v_mul_f32_e32 v42, v42, v130
	v_mul_f32_e32 v22, v22, v130
	v_rndne_f32_e32 v18, v18
	v_rndne_f32_e32 v30, v30
	v_mul_f32_e32 v26, v26, v130
	v_mul_f32_e32 v6, v6, v130
	v_rndne_f32_e32 v2, v2
	v_rndne_f32_e32 v14, v14
	v_mul_f32_e32 v10, v10, v130
	v_rndne_f32_e32 v118, v118
	v_cvt_i32_f32_e32 v114, v114
	v_cvt_i32_f32_e32 v126, v126
	v_rndne_f32_e32 v122, v122
	v_rndne_f32_e32 v102, v102
	v_cvt_i32_f32_e32 v98, v98
	v_cvt_i32_f32_e32 v110, v110
	v_rndne_f32_e32 v106, v106
	v_rndne_f32_e32 v86, v86
	v_cvt_i32_f32_e32 v82, v82
	v_cvt_i32_f32_e32 v94, v94
	v_rndne_f32_e32 v90, v90
	v_rndne_f32_e32 v70, v70
	v_cvt_i32_f32_e32 v66, v66
	v_cvt_i32_f32_e32 v78, v78
	v_rndne_f32_e32 v74, v74
	v_rndne_f32_e32 v54, v54
	v_cvt_i32_f32_e32 v50, v50
	v_cvt_i32_f32_e32 v62, v62
	v_rndne_f32_e32 v58, v58
	v_rndne_f32_e32 v38, v38
	v_cvt_i32_f32_e32 v34, v34
	v_cvt_i32_f32_e32 v46, v46
	v_rndne_f32_e32 v42, v42
	v_rndne_f32_e32 v22, v22
	v_cvt_i32_f32_e32 v18, v18
	v_cvt_i32_f32_e32 v30, v30
	v_rndne_f32_e32 v26, v26
	v_rndne_f32_e32 v6, v6
	v_cvt_i32_f32_e32 v2, v2
	v_cvt_i32_f32_e32 v14, v14
	v_rndne_f32_e32 v10, v10
	v_cvt_i32_f32_e32 v118, v118
	v_cvt_i32_f32_e32 v122, v122
	v_cvt_i32_f32_e32 v102, v102
	v_cvt_i32_f32_e32 v106, v106
	v_cvt_i32_f32_e32 v86, v86
	v_cvt_i32_f32_e32 v90, v90
	v_cvt_i32_f32_e32 v70, v70
	v_cvt_i32_f32_e32 v74, v74
	v_cvt_i32_f32_e32 v54, v54
	v_cvt_i32_f32_e32 v58, v58
	v_cvt_i32_f32_e32 v38, v38
	v_cvt_i32_f32_e32 v42, v42
	v_cvt_i32_f32_e32 v22, v22
	v_cvt_i32_f32_e32 v26, v26
	v_cvt_i32_f32_e32 v6, v6
	v_cvt_i32_f32_e32 v10, v10
	v_med3_i32 v114, v114, s37, v153
	v_med3_i32 v126, v126, s37, v153
	v_med3_i32 v98, v98, s37, v153
	v_med3_i32 v110, v110, s37, v153
	v_med3_i32 v82, v82, s37, v153
	v_med3_i32 v94, v94, s37, v153
	v_med3_i32 v66, v66, s37, v153
	v_med3_i32 v78, v78, s37, v153
	v_med3_i32 v50, v50, s37, v153
	v_med3_i32 v62, v62, s37, v153
	v_med3_i32 v34, v34, s37, v153
	v_med3_i32 v46, v46, s37, v153
	v_med3_i32 v18, v18, s37, v153
	v_med3_i32 v30, v30, s37, v153
	v_med3_i32 v2, v2, s37, v153
	v_med3_i32 v14, v14, s37, v153
	v_med3_i32 v118, v118, s37, v153
	v_med3_i32 v122, v122, s37, v153
	v_lshlrev_b32_e32 v114, 8, v114
	v_lshlrev_b32_e32 v126, 16, v126
	v_med3_i32 v102, v102, s37, v153
	v_med3_i32 v106, v106, s37, v153
	v_lshlrev_b32_e32 v98, 8, v98
	v_lshlrev_b32_e32 v110, 16, v110
	v_med3_i32 v86, v86, s37, v153
	v_med3_i32 v90, v90, s37, v153
	v_lshlrev_b32_e32 v82, 8, v82
	v_lshlrev_b32_e32 v94, 16, v94
	v_med3_i32 v70, v70, s37, v153
	v_med3_i32 v74, v74, s37, v153
	v_lshlrev_b32_e32 v66, 8, v66
	v_lshlrev_b32_e32 v78, 16, v78
	v_med3_i32 v54, v54, s37, v153
	v_med3_i32 v58, v58, s37, v153
	v_lshlrev_b32_e32 v50, 8, v50
	v_lshlrev_b32_e32 v62, 16, v62
	v_med3_i32 v38, v38, s37, v153
	v_med3_i32 v42, v42, s37, v153
	v_lshlrev_b32_e32 v34, 8, v34
	v_lshlrev_b32_e32 v46, 16, v46
	v_med3_i32 v22, v22, s37, v153
	v_med3_i32 v26, v26, s37, v153
	v_lshlrev_b32_e32 v18, 8, v18
	v_lshlrev_b32_e32 v30, 16, v30
	v_med3_i32 v6, v6, s37, v153
	v_med3_i32 v10, v10, s37, v153
	v_lshlrev_b32_e32 v2, 8, v2
	v_lshlrev_b32_e32 v14, 16, v14
	v_and_b32_e32 v114, 0xff00, v114
	v_and_b32_e32 v126, 0xff0000, v126
	v_perm_b32 v118, v122, v118, s38
	v_and_b32_e32 v98, 0xff00, v98
	v_and_b32_e32 v110, 0xff0000, v110
	v_perm_b32 v102, v106, v102, s38
	v_and_b32_e32 v82, 0xff00, v82
	v_and_b32_e32 v94, 0xff0000, v94
	v_perm_b32 v86, v90, v86, s38
	v_and_b32_e32 v66, 0xff00, v66
	v_and_b32_e32 v78, 0xff0000, v78
	v_perm_b32 v70, v74, v70, s38
	v_and_b32_e32 v50, 0xff00, v50
	v_and_b32_e32 v62, 0xff0000, v62
	v_perm_b32 v54, v58, v54, s38
	v_and_b32_e32 v34, 0xff00, v34
	v_and_b32_e32 v46, 0xff0000, v46
	v_perm_b32 v38, v42, v38, s38
	v_and_b32_e32 v18, 0xff00, v18
	v_and_b32_e32 v30, 0xff0000, v30
	v_perm_b32 v22, v26, v22, s38
	v_and_b32_e32 v2, 0xff00, v2
	v_and_b32_e32 v14, 0xff0000, v14
	v_perm_b32 v6, v10, v6, s38
	v_or3_b32 v118, v118, v114, v126
	v_add_u32_e32 v114, v144, v145
	v_mul_f32_e32 v122, v127, v131
	v_or3_b32 v98, v102, v98, v110
	v_mul_f32_e32 v99, v99, v131
	v_mul_f32_e32 v102, v111, v131
	v_or3_b32 v82, v86, v82, v94
	v_mul_f32_e32 v86, v87, v131
	v_mul_f32_e32 v83, v83, v131
	v_mul_f32_e32 v87, v95, v131
	v_or3_b32 v66, v70, v66, v78
	v_mul_f32_e32 v67, v67, v131
	v_mul_f32_e32 v70, v79, v131
	v_or3_b32 v50, v54, v50, v62
	v_mul_f32_e32 v54, v55, v131
	v_mul_f32_e32 v51, v51, v131
	v_mul_f32_e32 v55, v63, v131
	v_or3_b32 v34, v38, v34, v46
	v_mul_f32_e32 v35, v35, v131
	v_mul_f32_e32 v38, v47, v131
	v_or3_b32 v18, v22, v18, v30
	v_mul_f32_e32 v22, v23, v131
	v_mul_f32_e32 v19, v19, v131
	v_mul_f32_e32 v23, v31, v131
	v_or3_b32 v2, v6, v2, v14
	v_mul_f32_e32 v3, v3, v131
	v_mul_f32_e32 v6, v15, v131
	v_mul_f32_e32 v119, v119, v131
	v_rndne_f32_e32 v115, v115
	v_rndne_f32_e32 v122, v122
	v_mul_f32_e32 v123, v123, v131
	ds_write2st64_b32 v114, v118, v98 offset1:1
	v_mul_f32_e32 v98, v103, v131
	v_rndne_f32_e32 v99, v99
	v_rndne_f32_e32 v102, v102
	v_mul_f32_e32 v103, v107, v131
	v_rndne_f32_e32 v83, v83
	v_rndne_f32_e32 v87, v87
	v_mul_f32_e32 v90, v91, v131
	ds_write2st64_b32 v114, v82, v66 offset0:2 offset1:3
	v_mul_f32_e32 v66, v71, v131
	v_rndne_f32_e32 v67, v67
	v_rndne_f32_e32 v70, v70
	v_mul_f32_e32 v71, v75, v131
	v_rndne_f32_e32 v51, v51
	v_rndne_f32_e32 v55, v55
	v_mul_f32_e32 v58, v59, v131
	ds_write2st64_b32 v114, v50, v34 offset0:4 offset1:5
	v_mul_f32_e32 v34, v39, v131
	v_rndne_f32_e32 v35, v35
	v_rndne_f32_e32 v38, v38
	v_mul_f32_e32 v39, v43, v131
	v_rndne_f32_e32 v19, v19
	v_rndne_f32_e32 v23, v23
	v_mul_f32_e32 v26, v27, v131
	ds_write2st64_b32 v114, v18, v2 offset0:6 offset1:7
	v_mul_f32_e32 v2, v7, v131
	v_rndne_f32_e32 v3, v3
	v_rndne_f32_e32 v6, v6
	v_mul_f32_e32 v7, v11, v131
	v_rndne_f32_e32 v119, v119
	v_cvt_i32_f32_e32 v115, v115
	v_cvt_i32_f32_e32 v122, v122
	v_rndne_f32_e32 v123, v123
	v_rndne_f32_e32 v98, v98
	v_cvt_i32_f32_e32 v99, v99
	v_cvt_i32_f32_e32 v102, v102
	v_rndne_f32_e32 v103, v103
	v_rndne_f32_e32 v86, v86
	v_cvt_i32_f32_e32 v83, v83
	v_cvt_i32_f32_e32 v87, v87
	v_rndne_f32_e32 v90, v90
	v_rndne_f32_e32 v66, v66
	v_cvt_i32_f32_e32 v67, v67
	v_cvt_i32_f32_e32 v70, v70
	v_rndne_f32_e32 v71, v71
	v_rndne_f32_e32 v54, v54
	v_cvt_i32_f32_e32 v51, v51
	v_cvt_i32_f32_e32 v55, v55
	v_rndne_f32_e32 v58, v58
	v_rndne_f32_e32 v34, v34
	v_cvt_i32_f32_e32 v35, v35
	v_cvt_i32_f32_e32 v38, v38
	v_rndne_f32_e32 v39, v39
	v_rndne_f32_e32 v22, v22
	v_cvt_i32_f32_e32 v19, v19
	v_cvt_i32_f32_e32 v23, v23
	v_rndne_f32_e32 v26, v26
	v_rndne_f32_e32 v2, v2
	v_cvt_i32_f32_e32 v3, v3
	v_cvt_i32_f32_e32 v6, v6
	v_rndne_f32_e32 v7, v7
	v_cvt_i32_f32_e32 v119, v119
	v_cvt_i32_f32_e32 v123, v123
	v_cvt_i32_f32_e32 v98, v98
	v_cvt_i32_f32_e32 v103, v103
	v_cvt_i32_f32_e32 v86, v86
	v_cvt_i32_f32_e32 v90, v90
	v_cvt_i32_f32_e32 v66, v66
	v_cvt_i32_f32_e32 v71, v71
	v_cvt_i32_f32_e32 v54, v54
	v_cvt_i32_f32_e32 v58, v58
	v_cvt_i32_f32_e32 v34, v34
	v_cvt_i32_f32_e32 v39, v39
	v_cvt_i32_f32_e32 v22, v22
	v_cvt_i32_f32_e32 v26, v26
	v_cvt_i32_f32_e32 v2, v2
	v_cvt_i32_f32_e32 v7, v7
	v_med3_i32 v115, v115, s37, v153
	v_med3_i32 v122, v122, s37, v153
	v_med3_i32 v99, v99, s37, v153
	v_med3_i32 v102, v102, s37, v153
	v_med3_i32 v83, v83, s37, v153
	v_med3_i32 v87, v87, s37, v153
	v_med3_i32 v67, v67, s37, v153
	v_med3_i32 v70, v70, s37, v153
	v_med3_i32 v51, v51, s37, v153
	v_med3_i32 v55, v55, s37, v153
	v_med3_i32 v35, v35, s37, v153
	v_med3_i32 v38, v38, s37, v153
	v_med3_i32 v19, v19, s37, v153
	v_med3_i32 v23, v23, s37, v153
	v_med3_i32 v3, v3, s37, v153
	v_med3_i32 v6, v6, s37, v153
	v_med3_i32 v119, v119, s37, v153
	v_med3_i32 v123, v123, s37, v153
	v_lshlrev_b32_e32 v115, 8, v115
	v_lshlrev_b32_e32 v122, 16, v122
	v_med3_i32 v98, v98, s37, v153
	v_med3_i32 v103, v103, s37, v153
	v_lshlrev_b32_e32 v99, 8, v99
	v_lshlrev_b32_e32 v102, 16, v102
	v_med3_i32 v86, v86, s37, v153
	v_med3_i32 v90, v90, s37, v153
	v_lshlrev_b32_e32 v83, 8, v83
	v_lshlrev_b32_e32 v87, 16, v87
	v_med3_i32 v66, v66, s37, v153
	v_med3_i32 v71, v71, s37, v153
	v_lshlrev_b32_e32 v67, 8, v67
	v_lshlrev_b32_e32 v70, 16, v70
	v_med3_i32 v54, v54, s37, v153
	v_med3_i32 v58, v58, s37, v153
	v_lshlrev_b32_e32 v51, 8, v51
	v_lshlrev_b32_e32 v55, 16, v55
	v_med3_i32 v34, v34, s37, v153
	v_med3_i32 v39, v39, s37, v153
	v_lshlrev_b32_e32 v35, 8, v35
	v_lshlrev_b32_e32 v38, 16, v38
	v_med3_i32 v22, v22, s37, v153
	v_med3_i32 v26, v26, s37, v153
	v_lshlrev_b32_e32 v19, 8, v19
	v_lshlrev_b32_e32 v23, 16, v23
	v_med3_i32 v2, v2, s37, v153
	v_med3_i32 v7, v7, s37, v153
	v_lshlrev_b32_e32 v3, 8, v3
	v_lshlrev_b32_e32 v6, 16, v6
	v_and_b32_e32 v115, 0xff00, v115
	v_and_b32_e32 v122, 0xff0000, v122
	v_perm_b32 v119, v123, v119, s38
	v_and_b32_e32 v99, 0xff00, v99
	v_and_b32_e32 v102, 0xff0000, v102
	v_perm_b32 v98, v103, v98, s38
	v_and_b32_e32 v83, 0xff00, v83
	v_and_b32_e32 v87, 0xff0000, v87
	v_perm_b32 v86, v90, v86, s38
	v_and_b32_e32 v67, 0xff00, v67
	v_and_b32_e32 v70, 0xff0000, v70
	v_perm_b32 v66, v71, v66, s38
	v_and_b32_e32 v51, 0xff00, v51
	v_and_b32_e32 v55, 0xff0000, v55
	v_perm_b32 v54, v58, v54, s38
	v_and_b32_e32 v35, 0xff00, v35
	v_and_b32_e32 v38, 0xff0000, v38
	v_perm_b32 v34, v39, v34, s38
	v_and_b32_e32 v19, 0xff00, v19
	v_and_b32_e32 v23, 0xff0000, v23
	v_perm_b32 v22, v26, v22, s38
	v_and_b32_e32 v3, 0xff00, v3
	v_and_b32_e32 v6, 0xff0000, v6
	v_perm_b32 v2, v7, v2, s38
	v_or3_b32 v115, v119, v115, v122
	v_mul_f32_e32 v119, v120, v132
	v_mul_f32_e32 v120, v128, v132
	v_or3_b32 v99, v98, v99, v102
	v_add_u32_e32 v98, 16, v114
	v_mul_f32_e32 v100, v100, v132
	v_mul_f32_e32 v102, v112, v132
	v_or3_b32 v83, v86, v83, v87
	v_mul_f32_e32 v84, v84, v132
	v_mul_f32_e32 v87, v96, v132
	v_or3_b32 v66, v66, v67, v70
	v_mul_f32_e32 v67, v68, v132
	v_mul_f32_e32 v68, v80, v132
	v_or3_b32 v51, v54, v51, v55
	v_mul_f32_e32 v52, v52, v132
	v_mul_f32_e32 v55, v64, v132
	v_or3_b32 v34, v34, v35, v38
	v_mul_f32_e32 v35, v36, v132
	v_mul_f32_e32 v36, v48, v132
	v_or3_b32 v19, v22, v19, v23
	v_mul_f32_e32 v20, v20, v132
	v_mul_f32_e32 v23, v32, v132
	v_or3_b32 v2, v2, v3, v6
	v_mul_f32_e32 v3, v4, v132
	v_mul_f32_e32 v4, v16, v132
	v_rndne_f32_e32 v116, v116
	v_rndne_f32_e32 v120, v120
	v_mul_f32_e32 v122, v124, v132
	ds_write2st64_b32 v98, v115, v99 offset0:8 offset1:9
	v_mul_f32_e32 v99, v104, v132
	v_rndne_f32_e32 v100, v100
	v_rndne_f32_e32 v102, v102
	v_mul_f32_e32 v103, v108, v132
	v_mul_f32_e32 v86, v88, v132
	v_rndne_f32_e32 v84, v84
	v_rndne_f32_e32 v87, v87
	v_mul_f32_e32 v88, v92, v132
	ds_write2st64_b32 v98, v83, v66 offset0:10 offset1:11
	v_mul_f32_e32 v66, v72, v132
	v_rndne_f32_e32 v67, v67
	v_rndne_f32_e32 v68, v68
	v_mul_f32_e32 v70, v76, v132
	v_mul_f32_e32 v54, v56, v132
	v_rndne_f32_e32 v52, v52
	v_rndne_f32_e32 v55, v55
	v_mul_f32_e32 v56, v60, v132
	ds_write2st64_b32 v98, v51, v34 offset0:12 offset1:13
	v_mul_f32_e32 v34, v40, v132
	v_rndne_f32_e32 v35, v35
	v_rndne_f32_e32 v36, v36
	v_mul_f32_e32 v38, v44, v132
	v_mul_f32_e32 v22, v24, v132
	v_rndne_f32_e32 v20, v20
	v_rndne_f32_e32 v23, v23
	v_mul_f32_e32 v24, v28, v132
	ds_write2st64_b32 v98, v19, v2 offset0:14 offset1:15
	v_mul_f32_e32 v2, v8, v132
	v_rndne_f32_e32 v3, v3
	v_rndne_f32_e32 v4, v4
	v_mul_f32_e32 v6, v12, v132
	v_rndne_f32_e32 v119, v119
	v_cvt_i32_f32_e32 v116, v116
	v_cvt_i32_f32_e32 v120, v120
	v_rndne_f32_e32 v122, v122
	v_rndne_f32_e32 v99, v99
	v_cvt_i32_f32_e32 v100, v100
	v_cvt_i32_f32_e32 v102, v102
	v_rndne_f32_e32 v103, v103
	v_rndne_f32_e32 v86, v86
	v_cvt_i32_f32_e32 v84, v84
	v_cvt_i32_f32_e32 v87, v87
	v_rndne_f32_e32 v88, v88
	v_rndne_f32_e32 v66, v66
	v_cvt_i32_f32_e32 v67, v67
	v_cvt_i32_f32_e32 v68, v68
	v_rndne_f32_e32 v70, v70
	v_rndne_f32_e32 v54, v54
	v_cvt_i32_f32_e32 v52, v52
	v_cvt_i32_f32_e32 v55, v55
	v_rndne_f32_e32 v56, v56
	v_rndne_f32_e32 v34, v34
	v_cvt_i32_f32_e32 v35, v35
	v_cvt_i32_f32_e32 v36, v36
	v_rndne_f32_e32 v38, v38
	v_rndne_f32_e32 v22, v22
	v_cvt_i32_f32_e32 v20, v20
	v_cvt_i32_f32_e32 v23, v23
	v_rndne_f32_e32 v24, v24
	v_rndne_f32_e32 v2, v2
	v_cvt_i32_f32_e32 v3, v3
	v_cvt_i32_f32_e32 v4, v4
	v_rndne_f32_e32 v6, v6
	v_cvt_i32_f32_e32 v119, v119
	v_cvt_i32_f32_e32 v122, v122
	v_cvt_i32_f32_e32 v99, v99
	v_cvt_i32_f32_e32 v103, v103
	v_cvt_i32_f32_e32 v86, v86
	v_cvt_i32_f32_e32 v88, v88
	v_cvt_i32_f32_e32 v66, v66
	v_cvt_i32_f32_e32 v70, v70
	v_cvt_i32_f32_e32 v54, v54
	v_cvt_i32_f32_e32 v56, v56
	v_cvt_i32_f32_e32 v34, v34
	v_cvt_i32_f32_e32 v38, v38
	v_cvt_i32_f32_e32 v22, v22
	v_cvt_i32_f32_e32 v24, v24
	v_cvt_i32_f32_e32 v2, v2
	v_cvt_i32_f32_e32 v6, v6
	v_med3_i32 v116, v116, s37, v153
	v_med3_i32 v120, v120, s37, v153
	v_med3_i32 v100, v100, s37, v153
	v_med3_i32 v102, v102, s37, v153
	v_med3_i32 v84, v84, s37, v153
	v_med3_i32 v87, v87, s37, v153
	v_med3_i32 v67, v67, s37, v153
	v_med3_i32 v68, v68, s37, v153
	v_med3_i32 v52, v52, s37, v153
	v_med3_i32 v55, v55, s37, v153
	v_med3_i32 v35, v35, s37, v153
	v_med3_i32 v36, v36, s37, v153
	v_med3_i32 v20, v20, s37, v153
	v_med3_i32 v23, v23, s37, v153
	v_med3_i32 v3, v3, s37, v153
	v_med3_i32 v4, v4, s37, v153
	v_med3_i32 v119, v119, s37, v153
	v_med3_i32 v122, v122, s37, v153
	v_lshlrev_b32_e32 v116, 8, v116
	v_lshlrev_b32_e32 v120, 16, v120
	v_med3_i32 v99, v99, s37, v153
	v_med3_i32 v103, v103, s37, v153
	v_lshlrev_b32_e32 v100, 8, v100
	v_lshlrev_b32_e32 v102, 16, v102
	v_med3_i32 v86, v86, s37, v153
	v_med3_i32 v88, v88, s37, v153
	v_lshlrev_b32_e32 v84, 8, v84
	v_lshlrev_b32_e32 v87, 16, v87
	v_med3_i32 v66, v66, s37, v153
	v_med3_i32 v70, v70, s37, v153
	v_lshlrev_b32_e32 v67, 8, v67
	v_lshlrev_b32_e32 v68, 16, v68
	v_med3_i32 v54, v54, s37, v153
	v_med3_i32 v56, v56, s37, v153
	v_lshlrev_b32_e32 v52, 8, v52
	v_lshlrev_b32_e32 v55, 16, v55
	v_med3_i32 v34, v34, s37, v153
	v_med3_i32 v38, v38, s37, v153
	v_lshlrev_b32_e32 v35, 8, v35
	v_lshlrev_b32_e32 v36, 16, v36
	v_med3_i32 v22, v22, s37, v153
	v_med3_i32 v24, v24, s37, v153
	v_lshlrev_b32_e32 v20, 8, v20
	v_lshlrev_b32_e32 v23, 16, v23
	v_med3_i32 v2, v2, s37, v153
	v_med3_i32 v6, v6, s37, v153
	v_lshlrev_b32_e32 v3, 8, v3
	v_lshlrev_b32_e32 v4, 16, v4
	v_and_b32_e32 v116, 0xff00, v116
	v_and_b32_e32 v120, 0xff0000, v120
	v_perm_b32 v119, v122, v119, s38
	v_and_b32_e32 v100, 0xff00, v100
	v_and_b32_e32 v102, 0xff0000, v102
	v_perm_b32 v99, v103, v99, s38
	v_and_b32_e32 v84, 0xff00, v84
	v_and_b32_e32 v87, 0xff0000, v87
	v_perm_b32 v86, v88, v86, s38
	v_and_b32_e32 v67, 0xff00, v67
	v_and_b32_e32 v68, 0xff0000, v68
	v_perm_b32 v66, v70, v66, s38
	v_and_b32_e32 v52, 0xff00, v52
	v_and_b32_e32 v55, 0xff0000, v55
	v_perm_b32 v54, v56, v54, s38
	v_and_b32_e32 v35, 0xff00, v35
	v_and_b32_e32 v36, 0xff0000, v36
	v_perm_b32 v34, v38, v34, s38
	v_and_b32_e32 v20, 0xff00, v20
	v_and_b32_e32 v23, 0xff0000, v23
	v_perm_b32 v22, v24, v22, s38
	v_and_b32_e32 v3, 0xff00, v3
	v_and_b32_e32 v4, 0xff0000, v4
	v_perm_b32 v2, v6, v2, s38
	v_or3_b32 v116, v119, v116, v120
	v_mul_f32_e32 v120, v129, v133
	v_or3_b32 v100, v99, v100, v102
	v_add_u32_e32 v99, 32, v114
	v_mul_f32_e32 v101, v101, v133
	v_mul_f32_e32 v102, v113, v133
	v_or3_b32 v84, v86, v84, v87
	v_mul_f32_e32 v85, v85, v133
	v_mul_f32_e32 v87, v97, v133
	v_or3_b32 v66, v66, v67, v68
	v_mul_f32_e32 v67, v69, v133
	v_mul_f32_e32 v68, v81, v133
	v_or3_b32 v52, v54, v52, v55
	v_mul_f32_e32 v53, v53, v133
	v_mul_f32_e32 v55, v65, v133
	v_or3_b32 v34, v34, v35, v36
	v_mul_f32_e32 v35, v37, v133
	v_mul_f32_e32 v36, v49, v133
	v_or3_b32 v20, v22, v20, v23
	v_mul_f32_e32 v21, v21, v133
	v_mul_f32_e32 v23, v33, v133
	v_or3_b32 v2, v2, v3, v4
	v_mul_f32_e32 v3, v5, v133
	v_mul_f32_e32 v4, v17, v133
	v_mul_f32_e32 v119, v121, v133
	v_rndne_f32_e32 v117, v117
	v_rndne_f32_e32 v120, v120
	v_mul_f32_e32 v121, v125, v133
	ds_write2st64_b32 v99, v116, v100 offset0:16 offset1:17
	v_mul_f32_e32 v100, v105, v133
	v_rndne_f32_e32 v101, v101
	v_rndne_f32_e32 v102, v102
	v_mul_f32_e32 v103, v109, v133
	v_mul_f32_e32 v86, v89, v133
	v_rndne_f32_e32 v85, v85
	v_rndne_f32_e32 v87, v87
	v_mul_f32_e32 v88, v93, v133
	ds_write2st64_b32 v99, v84, v66 offset0:18 offset1:19
	v_mul_f32_e32 v66, v73, v133
	v_rndne_f32_e32 v67, v67
	v_rndne_f32_e32 v68, v68
	v_mul_f32_e32 v69, v77, v133
	v_mul_f32_e32 v54, v57, v133
	v_rndne_f32_e32 v53, v53
	v_rndne_f32_e32 v55, v55
	v_mul_f32_e32 v56, v61, v133
	ds_write2st64_b32 v99, v52, v34 offset0:20 offset1:21
	v_mul_f32_e32 v34, v41, v133
	v_rndne_f32_e32 v35, v35
	v_rndne_f32_e32 v36, v36
	v_mul_f32_e32 v37, v45, v133
	v_mul_f32_e32 v22, v25, v133
	v_rndne_f32_e32 v21, v21
	v_rndne_f32_e32 v23, v23
	v_mul_f32_e32 v24, v29, v133
	ds_write2st64_b32 v99, v20, v2 offset0:22 offset1:23
	v_mul_f32_e32 v2, v9, v133
	v_rndne_f32_e32 v3, v3
	v_rndne_f32_e32 v4, v4
	v_mul_f32_e32 v5, v13, v133
	v_rndne_f32_e32 v119, v119
	v_cvt_i32_f32_e32 v117, v117
	v_cvt_i32_f32_e32 v120, v120
	v_rndne_f32_e32 v121, v121
	v_rndne_f32_e32 v100, v100
	v_cvt_i32_f32_e32 v101, v101
	v_cvt_i32_f32_e32 v102, v102
	v_rndne_f32_e32 v103, v103
	v_rndne_f32_e32 v86, v86
	v_cvt_i32_f32_e32 v85, v85
	v_cvt_i32_f32_e32 v87, v87
	v_rndne_f32_e32 v88, v88
	v_rndne_f32_e32 v66, v66
	v_cvt_i32_f32_e32 v67, v67
	v_cvt_i32_f32_e32 v68, v68
	v_rndne_f32_e32 v69, v69
	v_rndne_f32_e32 v54, v54
	v_cvt_i32_f32_e32 v53, v53
	v_cvt_i32_f32_e32 v55, v55
	v_rndne_f32_e32 v56, v56
	v_rndne_f32_e32 v34, v34
	v_cvt_i32_f32_e32 v35, v35
	v_cvt_i32_f32_e32 v36, v36
	v_rndne_f32_e32 v37, v37
	v_rndne_f32_e32 v22, v22
	v_cvt_i32_f32_e32 v21, v21
	v_cvt_i32_f32_e32 v23, v23
	v_rndne_f32_e32 v24, v24
	v_rndne_f32_e32 v2, v2
	v_cvt_i32_f32_e32 v3, v3
	v_cvt_i32_f32_e32 v4, v4
	v_rndne_f32_e32 v5, v5
	v_cvt_i32_f32_e32 v119, v119
	v_cvt_i32_f32_e32 v121, v121
	v_cvt_i32_f32_e32 v100, v100
	v_cvt_i32_f32_e32 v103, v103
	v_cvt_i32_f32_e32 v86, v86
	v_cvt_i32_f32_e32 v88, v88
	v_cvt_i32_f32_e32 v66, v66
	v_cvt_i32_f32_e32 v69, v69
	v_cvt_i32_f32_e32 v54, v54
	v_cvt_i32_f32_e32 v56, v56
	v_cvt_i32_f32_e32 v34, v34
	v_cvt_i32_f32_e32 v37, v37
	v_cvt_i32_f32_e32 v22, v22
	v_cvt_i32_f32_e32 v24, v24
	v_cvt_i32_f32_e32 v2, v2
	v_cvt_i32_f32_e32 v5, v5
	v_med3_i32 v117, v117, s37, v153
	v_med3_i32 v120, v120, s37, v153
	v_med3_i32 v101, v101, s37, v153
	v_med3_i32 v102, v102, s37, v153
	v_med3_i32 v85, v85, s37, v153
	v_med3_i32 v87, v87, s37, v153
	v_med3_i32 v67, v67, s37, v153
	v_med3_i32 v68, v68, s37, v153
	v_med3_i32 v53, v53, s37, v153
	v_med3_i32 v55, v55, s37, v153
	v_med3_i32 v35, v35, s37, v153
	v_med3_i32 v36, v36, s37, v153
	v_med3_i32 v21, v21, s37, v153
	v_med3_i32 v23, v23, s37, v153
	v_med3_i32 v3, v3, s37, v153
	v_med3_i32 v4, v4, s37, v153
	v_med3_i32 v119, v119, s37, v153
	v_med3_i32 v121, v121, s37, v153
	v_lshlrev_b32_e32 v117, 8, v117
	v_lshlrev_b32_e32 v120, 16, v120
	v_med3_i32 v100, v100, s37, v153
	v_med3_i32 v103, v103, s37, v153
	v_lshlrev_b32_e32 v101, 8, v101
	v_lshlrev_b32_e32 v102, 16, v102
	v_med3_i32 v86, v86, s37, v153
	v_med3_i32 v88, v88, s37, v153
	v_lshlrev_b32_e32 v85, 8, v85
	v_lshlrev_b32_e32 v87, 16, v87
	v_med3_i32 v66, v66, s37, v153
	v_med3_i32 v69, v69, s37, v153
	v_lshlrev_b32_e32 v67, 8, v67
	v_lshlrev_b32_e32 v68, 16, v68
	v_med3_i32 v54, v54, s37, v153
	v_med3_i32 v56, v56, s37, v153
	v_lshlrev_b32_e32 v53, 8, v53
	v_lshlrev_b32_e32 v55, 16, v55
	v_med3_i32 v34, v34, s37, v153
	v_med3_i32 v37, v37, s37, v153
	v_lshlrev_b32_e32 v35, 8, v35
	v_lshlrev_b32_e32 v36, 16, v36
	v_med3_i32 v22, v22, s37, v153
	v_med3_i32 v24, v24, s37, v153
	v_lshlrev_b32_e32 v21, 8, v21
	v_lshlrev_b32_e32 v23, 16, v23
	v_med3_i32 v2, v2, s37, v153
	v_med3_i32 v5, v5, s37, v153
	v_lshlrev_b32_e32 v3, 8, v3
	v_lshlrev_b32_e32 v4, 16, v4
	v_and_b32_e32 v117, 0xff00, v117
	v_and_b32_e32 v120, 0xff0000, v120
	v_perm_b32 v119, v121, v119, s38
	v_and_b32_e32 v101, 0xff00, v101
	v_and_b32_e32 v102, 0xff0000, v102
	v_perm_b32 v100, v103, v100, s38
	v_and_b32_e32 v85, 0xff00, v85
	v_and_b32_e32 v87, 0xff0000, v87
	v_perm_b32 v86, v88, v86, s38
	v_and_b32_e32 v67, 0xff00, v67
	v_and_b32_e32 v68, 0xff0000, v68
	v_perm_b32 v66, v69, v66, s38
	v_and_b32_e32 v53, 0xff00, v53
	v_and_b32_e32 v55, 0xff0000, v55
	v_perm_b32 v54, v56, v54, s38
	v_and_b32_e32 v35, 0xff00, v35
	v_and_b32_e32 v36, 0xff0000, v36
	v_perm_b32 v34, v37, v34, s38
	v_and_b32_e32 v21, 0xff00, v21
	v_and_b32_e32 v23, 0xff0000, v23
	v_perm_b32 v22, v24, v22, s38
	v_and_b32_e32 v3, 0xff00, v3
	v_and_b32_e32 v4, 0xff0000, v4
	v_perm_b32 v2, v5, v2, s38
	s_addc_u32 s13, s25, s13
	v_or3_b32 v117, v119, v117, v120
	v_or3_b32 v101, v100, v101, v102
	v_add_u32_e32 v100, 48, v114
	v_or3_b32 v85, v86, v85, v87
	v_or3_b32 v66, v66, v67, v68
	v_or3_b32 v53, v54, v53, v55
	v_or3_b32 v34, v34, v35, v36
	v_or3_b32 v21, v22, v21, v23
	v_or3_b32 v2, v2, v3, v4
	v_add_lshl_u32 v10, s20, v146, 11
	v_mov_b32_e32 v11, v137
	v_add_u32_e32 v18, v147, v138
	ds_write2st64_b32 v100, v117, v101 offset0:24 offset1:25
	ds_write2st64_b32 v100, v85, v66 offset0:26 offset1:27
	ds_write2st64_b32 v100, v53, v34 offset0:28 offset1:29
	ds_write2st64_b32 v100, v21, v2 offset0:30 offset1:31
	s_waitcnt lgkmcnt(0)
	s_barrier
	ds_read_b128 v[2:5], v18
	ds_read_b128 v[6:9], v18 offset:256
	v_lshl_add_u64 v[14:15], s[12:13], 0, v[10:11]
	ds_read_b128 v[10:13], v18 offset:512
	v_lshl_add_u64 v[22:23], v[14:15], 0, v[138:139]
	s_waitcnt lgkmcnt(2)
	global_store_dwordx4 v[22:23], v[2:5], off sc1
	s_waitcnt lgkmcnt(1)
	global_store_dwordx4 v[22:23], v[6:9], off offset:256 sc1
	ds_read_b128 v[2:5], v18 offset:768
	s_waitcnt lgkmcnt(1)
	global_store_dwordx4 v[22:23], v[10:13], off offset:512 sc1
	ds_read_b128 v[6:9], v18 offset:1024
	ds_read_b128 v[10:13], v18 offset:1280
	ds_read_b128 v[14:17], v18 offset:1536
	ds_read_b128 v[18:21], v18 offset:1792
	s_waitcnt lgkmcnt(4)
	global_store_dwordx4 v[22:23], v[2:5], off offset:768 sc1
	s_waitcnt lgkmcnt(3)
	global_store_dwordx4 v[22:23], v[6:9], off offset:1024 sc1
	s_waitcnt lgkmcnt(2)
	global_store_dwordx4 v[22:23], v[10:13], off offset:1280 sc1
	s_waitcnt lgkmcnt(1)
	global_store_dwordx4 v[22:23], v[14:17], off offset:1536 sc1
	s_waitcnt lgkmcnt(0)
	global_store_dwordx4 v[22:23], v[18:21], off offset:1792 sc1
	s_barrier
	s_mov_b64 s[12:13], 0

.LBB0_322:
	s_or_b64 exec, exec, s[16:17]
	s_waitcnt lgkmcnt(0)
	s_barrier
	ds_read_b128 v[130:133], v143
	ds_read_b128 v[154:157], v143 offset:128
	s_waitcnt lgkmcnt(1)
	v_max_f32_e32 v130, v130, v130
	s_waitcnt lgkmcnt(0)
	v_max_f32_e32 v154, v154, v154
	v_max_f32_e32 v158, v130, v154
	v_max_f32_e32 v130, v155, v155
	v_max_f32_e32 v131, v131, v131
	v_max_f32_e32 v159, v131, v130
	v_max_f32_e32 v130, v156, v156
	v_max_f32_e32 v131, v132, v132
	v_max_f32_e32 v160, v131, v130
	v_max_f32_e32 v130, v157, v157
	v_max_f32_e32 v131, v133, v133
	v_max_f32_e32 v161, v131, v130
	ds_read_b128 v[130:133], v143 offset:256
	ds_read_b128 v[154:157], v143 offset:384
	s_waitcnt lgkmcnt(0)
	v_max3_f32 v161, v161, v133, v157
	v_max3_f32 v160, v160, v132, v156
	v_max3_f32 v159, v159, v131, v155
	v_max3_f32 v158, v158, v130, v154
	ds_read_b128 v[130:133], v143 offset:512
	ds_read_b128 v[154:157], v143 offset:640
	s_waitcnt lgkmcnt(0)
	v_max3_f32 v158, v158, v130, v154
	v_max3_f32 v159, v159, v131, v155
	v_max3_f32 v160, v160, v132, v156
	v_max3_f32 v161, v161, v133, v157
	ds_read_b128 v[130:133], v143 offset:768
	ds_read_b128 v[154:157], v143 offset:896
	s_waitcnt lgkmcnt(0)
	v_max3_f32 v133, v161, v133, v157
	v_max3_f32 v132, v160, v132, v156
	v_max3_f32 v131, v159, v131, v155
	v_max3_f32 v130, v158, v130, v154
	v_max_f32_e32 v130, 0xda24260, v130
	v_max_f32_e32 v131, 0xda24260, v131
	v_max_f32_e32 v132, 0xda24260, v132
	v_max_f32_e32 v133, 0xda24260, v133
	v_pk_mul_f32 v[130:131], v[130:131], s[8:9] op_sel_hi:[1,0]
	v_pk_mul_f32 v[132:133], v[132:133], s[8:9] op_sel_hi:[1,0]
	s_and_saveexec_b64 s[16:17], s[2:3]
	s_cbranch_execz .LBB0_304
	s_lshl_b32 s42, s12, 13
	s_ashr_i32 s43, s42, 31
	s_lshl_b64 s[42:43], s[42:43], 2
	s_add_u32 s21, s31, s42
	s_addc_u32 s43, s34, s43
	s_add_u32 s42, s21, s10
	s_addc_u32 s43, s43, 0
	global_store_dwordx4 v136, v[130:133], s[42:43] sc1
	s_branch .LBB0_304

.LBB0_418:
	s_lshl_b32 s50, s10, 1
	s_sub_i32 s51, s50, 20
	s_cmp_gt_i32 s10, 7
	v_lshlrev_b64 v[148:149], 10, v[184:185]
	s_cselect_b64 s[12:13], -1, 0
	s_waitcnt vmcnt(0) lgkmcnt(0)
	v_pk_fma_f32 v[144:145], v[144:145], v[190:191], v[48:49] op_sel_hi:[1,0,1]
	v_pk_fma_f32 v[142:143], v[142:143], v[190:191], v[46:47] op_sel_hi:[1,0,1]
	v_pk_fma_f32 v[140:141], v[140:141], v[190:191], v[44:45] op_sel_hi:[1,0,1]
	v_pk_fma_f32 v[138:139], v[138:139], v[190:191], v[42:43] op_sel_hi:[1,0,1]
	s_mov_b64 s[10:11], -1
	s_and_b64 vcc, exec, s[6:7]
	v_lshl_add_u64 v[192:193], s[34:35], 0, v[148:149]
	v_lshlrev_b32_e32 v162, 1, v164
	s_cbranch_vccz .LBB0_422
	s_lshl_b32 s24, s51, 7
	v_lshl_add_u64 v[152:153], s[24:25], 1, v[192:193]
	v_lshl_add_u64 v[152:153], v[152:153], 0, v[162:163]
	s_andn2_b64 vcc, exec, s[64:65]
	v_cvt_pk_bf16_f32 v202, v142, v143
	v_cvt_pk_bf16_f32 v203, v144, v145
	v_cvt_pk_bf16_f32 v204, v138, v139
	v_cvt_pk_bf16_f32 v205, v140, v141
	global_store_dwordx4 v[152:153], v[202:205], off sc1
	s_cbranch_vccnz .LBB0_421
	s_lshl_b32 s10, s89, 1
	s_ashr_i32 s11, s10, 31
	s_lshl_b64 s[10:11], s[10:11], 19
	v_lshl_add_u64 v[152:153], v[170:171], 0, s[10:11]
	v_lshl_add_u64 v[152:153], s[24:25], 2, v[152:153]
	v_mov_b32_e32 v183, v163
	v_lshl_add_u64 v[152:153], v[152:153], 0, v[182:183]
	global_store_dwordx4 v[152:153], v[142:145], off sc1
	global_store_dwordx4 v[152:153], v[138:141], off offset:16 sc1

.LBB0_422:
	s_add_i32 s50, s50, -16
	s_andn2_b64 vcc, exec, s[10:11]
	v_lshlrev_b64 v[152:153], 12, v[184:185]
	s_cbranch_vccnz .LBB0_429
	v_pk_mul_f32 v[202:203], v[140:141], v[186:187]
	v_pk_mul_f32 v[204:205], v[138:139], v[188:189]
	v_pk_mul_f32 v[206:207], v[140:141], v[146:147]
	v_pk_mul_f32 v[208:209], v[138:139], v[150:151]
	v_pk_fma_f32 v[202:203], v[144:145], v[146:147], v[202:203] neg_lo:[0,0,1] neg_hi:[0,0,1]
	v_pk_fma_f32 v[204:205], v[142:143], v[150:151], v[204:205] neg_lo:[0,0,1] neg_hi:[0,0,1]
	v_pk_fma_f32 v[206:207], v[144:145], v[186:187], v[206:207]
	v_pk_fma_f32 v[208:209], v[142:143], v[188:189], v[208:209]
	v_cndmask_b32_e64 v141, v141, v207, s[4:5]
	v_cndmask_b32_e64 v140, v140, v206, s[4:5]
	v_cndmask_b32_e64 v139, v139, v209, s[4:5]
	v_cndmask_b32_e64 v138, v138, v208, s[4:5]
	v_cndmask_b32_e64 v145, v145, v203, s[4:5]
	v_cndmask_b32_e64 v144, v144, v202, s[4:5]
	v_cndmask_b32_e64 v143, v143, v205, s[4:5]
	v_cndmask_b32_e64 v142, v142, v204, s[4:5]
	s_mov_b64 s[10:11], -1
	s_and_b64 vcc, exec, s[12:13]
	s_cbranch_vccz .LBB0_427
	v_lshl_add_u64 v[206:207], s[30:31], 0, v[148:149]
	s_lshl_b32 s24, s50, 8
	v_lshl_add_u64 v[206:207], v[206:207], 0, s[24:25]
	v_lshl_add_u64 v[206:207], v[206:207], 0, v[162:163]
	s_andn2_b64 vcc, exec, s[64:65]
	v_cvt_pk_bf16_f32 v202, v142, v143
	v_cvt_pk_bf16_f32 v203, v144, v145
	v_cvt_pk_bf16_f32 v204, v138, v139
	v_cvt_pk_bf16_f32 v205, v140, v141
	global_store_dwordx4 v[206:207], v[202:205], off sc1
	s_cbranch_vccnz .LBB0_426
	s_lshl_b32 s10, s89, 1
	s_ashr_i32 s11, s10, 31
	s_lshl_b64 s[10:11], s[10:11], 19
	s_lshl_b32 s24, s50, 7
	v_lshl_add_u64 v[202:203], v[172:173], 0, s[10:11]
	v_lshl_add_u64 v[202:203], s[24:25], 2, v[202:203]
	v_lshlrev_b32_e32 v204, 2, v166
	v_mov_b32_e32 v205, v163
	v_lshl_add_u64 v[202:203], v[202:203], 0, v[204:205]
	global_store_dwordx4 v[202:203], v[142:145], off sc1
	global_store_dwordx4 v[202:203], v[138:141], off offset:128 sc1

.LBB0_427:
	s_andn2_b64 vcc, exec, s[10:11]
	s_cbranch_vccnz .LBB0_429
	v_cvt_pk_bf16_f32 v142, v142, v143
	v_cvt_pk_bf16_f32 v143, v144, v145
	v_cvt_pk_bf16_f32 v144, v138, v139
	v_lshl_add_u64 v[138:139], s[28:29], 0, v[152:153]
	v_lshl_add_u64 v[138:139], s[62:63], 1, v[138:139]
	v_lshl_add_u64 v[138:139], v[138:139], 0, v[162:163]
	v_cvt_pk_bf16_f32 v145, v140, v141
	global_store_dwordx4 v[138:139], v[142:145], off sc1
.LBB0_429:
	v_mov_b32_e32 v138, v190
	v_mov_b32_e32 v139, v190
	v_mov_b32_e32 v191, v190
	v_pk_fma_f32 v[136:137], v[136:137], v[138:139], v[40:41]
	v_pk_fma_f32 v[132:133], v[132:133], v[138:139], v[36:37]
	v_cndmask_b32_e64 v138, 0, 1, s[6:7]
	v_pk_fma_f32 v[134:135], v[134:135], v[190:191], v[38:39]
	v_pk_fma_f32 v[130:131], v[130:131], v[190:191], v[34:35]
	v_cmp_ne_u32_e64 s[10:11], 1, v138
	s_andn2_b64 vcc, exec, s[6:7]
	s_mov_b64 s[6:7], -1
	s_cbranch_vccnz .LBB0_433
	s_add_i32 s24, s62, 0xfffff680
	v_lshl_add_u64 v[142:143], s[24:25], 1, v[192:193]
	v_lshl_add_u64 v[142:143], v[142:143], 0, v[162:163]
	s_andn2_b64 vcc, exec, s[64:65]
	v_cvt_pk_bf16_f32 v138, v134, v135
	v_cvt_pk_bf16_f32 v139, v136, v137
	v_cvt_pk_bf16_f32 v140, v130, v131
	v_cvt_pk_bf16_f32 v141, v132, v133
	global_store_dwordx4 v[142:143], v[138:141], off sc1
	s_cbranch_vccnz .LBB0_432
	s_lshl_b32 s6, s89, 1
	s_ashr_i32 s7, s6, 31
	s_lshl_b64 s[6:7], s[6:7], 19
	v_lshl_add_u64 v[138:139], v[170:171], 0, s[6:7]
	v_lshl_add_u64 v[138:139], s[24:25], 2, v[138:139]
	v_mov_b32_e32 v183, v163
	v_lshl_add_u64 v[138:139], v[138:139], 0, v[182:183]
	global_store_dwordx4 v[138:139], v[134:137], off sc1
	global_store_dwordx4 v[138:139], v[130:133], off offset:16 sc1

.LBB0_433:
	v_cndmask_b32_e64 v138, 0, 1, s[12:13]
	s_andn2_b64 vcc, exec, s[6:7]
	v_cmp_ne_u32_e64 s[6:7], 1, v138
	s_cbranch_vccnz .LBB0_440
	v_pk_mul_f32 v[138:139], v[132:133], v[186:187]
	v_pk_mul_f32 v[140:141], v[130:131], v[188:189]
	v_pk_mul_f32 v[142:143], v[132:133], v[146:147]
	v_pk_mul_f32 v[144:145], v[130:131], v[150:151]
	v_pk_fma_f32 v[138:139], v[136:137], v[146:147], v[138:139] neg_lo:[0,0,1] neg_hi:[0,0,1]
	v_pk_fma_f32 v[140:141], v[134:135], v[150:151], v[140:141] neg_lo:[0,0,1] neg_hi:[0,0,1]
	v_pk_fma_f32 v[142:143], v[136:137], v[186:187], v[142:143]
	v_pk_fma_f32 v[144:145], v[134:135], v[188:189], v[144:145]
	v_cndmask_b32_e64 v133, v133, v143, s[4:5]
	v_cndmask_b32_e64 v132, v132, v142, s[4:5]
	v_cndmask_b32_e64 v131, v131, v145, s[4:5]
	v_cndmask_b32_e64 v130, v130, v144, s[4:5]
	v_cndmask_b32_e64 v137, v137, v139, s[4:5]
	v_cndmask_b32_e64 v136, v136, v138, s[4:5]
	v_cndmask_b32_e64 v135, v135, v141, s[4:5]
	v_cndmask_b32_e64 v134, v134, v140, s[4:5]
	s_and_b64 vcc, exec, s[6:7]
	s_mov_b64 s[12:13], -1
	s_cbranch_vccnz .LBB0_438
	v_lshl_add_u64 v[142:143], s[30:31], 0, v[148:149]
	s_add_i32 s24, s62, 0xfffff880
	v_lshl_add_u64 v[142:143], s[24:25], 1, v[142:143]
	v_lshl_add_u64 v[142:143], v[142:143], 0, v[162:163]
	s_andn2_b64 vcc, exec, s[64:65]
	v_cvt_pk_bf16_f32 v138, v134, v135
	v_cvt_pk_bf16_f32 v139, v136, v137
	v_cvt_pk_bf16_f32 v140, v130, v131
	v_cvt_pk_bf16_f32 v141, v132, v133
	global_store_dwordx4 v[142:143], v[138:141], off sc1
	s_cbranch_vccnz .LBB0_437
	s_lshl_b32 s12, s89, 1
	s_ashr_i32 s13, s12, 31
	s_lshl_b64 s[12:13], s[12:13], 19
	v_lshl_add_u64 v[138:139], v[172:173], 0, s[12:13]
	v_lshl_add_u64 v[138:139], s[24:25], 2, v[138:139]
	v_lshlrev_b32_e32 v140, 2, v166
	v_mov_b32_e32 v141, v163
	v_lshl_add_u64 v[138:139], v[138:139], 0, v[140:141]
	global_store_dwordx4 v[138:139], v[134:137], off sc1
	global_store_dwordx4 v[138:139], v[130:133], off offset:128 sc1

.LBB0_438:
	s_andn2_b64 vcc, exec, s[12:13]
	s_cbranch_vccnz .LBB0_440
	v_cvt_pk_bf16_f32 v134, v134, v135
	v_cvt_pk_bf16_f32 v135, v136, v137
	v_cvt_pk_bf16_f32 v136, v130, v131
	v_lshl_add_u64 v[130:131], s[28:29], 0, v[152:153]
	v_lshl_add_u64 v[130:131], s[62:63], 1, v[130:131]
	v_lshl_add_u64 v[130:131], v[130:131], 0, v[162:163]
	v_cvt_pk_bf16_f32 v137, v132, v133
	global_store_dwordx4 v[130:131], v[134:137], off offset:256 sc1

.LBB0_447:
	v_lshlrev_b64 v[132:133], 10, v[144:145]
	v_lshlrev_b32_e32 v136, 9, v144
	v_and_b32_e32 v148, 0x1be00, v136
	s_waitcnt lgkmcnt(0)
	v_pk_fma_f32 v[128:129], v[128:129], v[142:143], v[48:49] op_sel_hi:[1,0,1]
	v_pk_fma_f32 v[126:127], v[126:127], v[142:143], v[46:47] op_sel_hi:[1,0,1]
	v_pk_fma_f32 v[124:125], v[124:125], v[142:143], v[44:45] op_sel_hi:[1,0,1]
	v_pk_fma_f32 v[122:123], v[122:123], v[142:143], v[42:43] op_sel_hi:[1,0,1]
	s_mov_b64 s[86:87], -1
	s_and_b64 vcc, exec, s[10:11]
	v_lshl_add_u64 v[146:147], s[34:35], 0, v[132:133]
	s_cbranch_vccnz .LBB0_451
	s_lshl_b32 s24, s51, 7
	v_lshl_add_u64 v[136:137], s[24:25], 1, v[146:147]
	v_lshl_add_u64 v[136:137], v[136:137], 0, v[162:163]
	s_andn2_b64 vcc, exec, s[64:65]
	v_cvt_pk_bf16_f32 v150, v126, v127
	v_cvt_pk_bf16_f32 v151, v128, v129
	v_cvt_pk_bf16_f32 v152, v122, v123
	v_cvt_pk_bf16_f32 v153, v124, v125
	global_store_dwordx4 v[136:137], v[150:153], off sc1
	s_cbranch_vccnz .LBB0_450
	s_lshl_b32 s86, s89, 1
	s_ashr_i32 s87, s86, 31
	s_lshl_b64 s[86:87], s[86:87], 19
	s_add_u32 s86, s38, s86
	s_addc_u32 s87, s39, s87
	v_lshlrev_b32_e32 v136, 2, v148
	v_mov_b32_e32 v137, v163
	v_lshl_add_u64 v[136:137], s[86:87], 0, v[136:137]
	v_lshl_add_u64 v[136:137], s[24:25], 2, v[136:137]
	v_mov_b32_e32 v183, v163
	v_lshl_add_u64 v[136:137], v[136:137], 0, v[182:183]
	global_store_dwordx4 v[136:137], v[126:129], off sc1
	global_store_dwordx4 v[136:137], v[122:125], off offset:16 sc1

.LBB0_451:
	s_andn2_b64 vcc, exec, s[86:87]
	v_lshlrev_b64 v[136:137], 12, v[144:145]
	s_cbranch_vccnz .LBB0_458
	v_pk_mul_f32 v[144:145], v[124:125], v[138:139]
	v_pk_mul_f32 v[150:151], v[122:123], v[140:141]
	v_pk_mul_f32 v[152:153], v[124:125], v[130:131]
	v_pk_mul_f32 v[186:187], v[122:123], v[134:135]
	v_pk_fma_f32 v[144:145], v[128:129], v[130:131], v[144:145] neg_lo:[0,0,1] neg_hi:[0,0,1]
	v_pk_fma_f32 v[150:151], v[126:127], v[134:135], v[150:151] neg_lo:[0,0,1] neg_hi:[0,0,1]
	v_pk_fma_f32 v[152:153], v[128:129], v[138:139], v[152:153]
	v_pk_fma_f32 v[186:187], v[126:127], v[140:141], v[186:187]
	v_cndmask_b32_e64 v125, v125, v153, s[4:5]
	v_cndmask_b32_e64 v124, v124, v152, s[4:5]
	v_cndmask_b32_e64 v123, v123, v187, s[4:5]
	v_cndmask_b32_e64 v122, v122, v186, s[4:5]
	v_cndmask_b32_e64 v129, v129, v145, s[4:5]
	v_cndmask_b32_e64 v128, v128, v144, s[4:5]
	v_cndmask_b32_e64 v127, v127, v151, s[4:5]
	v_cndmask_b32_e64 v126, v126, v150, s[4:5]
	s_and_b64 vcc, exec, s[6:7]
	s_mov_b64 s[86:87], -1
	s_cbranch_vccnz .LBB0_456
	v_lshl_add_u64 v[144:145], s[30:31], 0, v[132:133]
	s_lshl_b32 s24, s50, 8
	v_lshl_add_u64 v[144:145], v[144:145], 0, s[24:25]
	v_lshl_add_u64 v[144:145], v[144:145], 0, v[162:163]
	s_andn2_b64 vcc, exec, s[64:65]
	v_cvt_pk_bf16_f32 v150, v126, v127
	v_cvt_pk_bf16_f32 v151, v128, v129
	v_cvt_pk_bf16_f32 v152, v122, v123
	v_cvt_pk_bf16_f32 v153, v124, v125
	global_store_dwordx4 v[144:145], v[150:153], off sc1
	s_cbranch_vccnz .LBB0_455
	s_lshl_b32 s86, s89, 1
	s_ashr_i32 s87, s86, 31
	s_lshl_b32 s24, s50, 7
	s_lshl_b64 s[86:87], s[86:87], 19
	s_add_u32 s86, s36, s86
	s_addc_u32 s87, s37, s87
	v_lshlrev_b32_e32 v144, 2, v148
	v_mov_b32_e32 v145, v163
	v_lshl_add_u64 v[144:145], s[86:87], 0, v[144:145]
	v_lshl_add_u64 v[144:145], s[24:25], 2, v[144:145]
	v_lshlrev_b32_e32 v150, 2, v166
	v_mov_b32_e32 v151, v163
	v_lshl_add_u64 v[144:145], v[144:145], 0, v[150:151]
	global_store_dwordx4 v[144:145], v[126:129], off sc1
	global_store_dwordx4 v[144:145], v[122:125], off offset:128 sc1

.LBB0_456:
	s_andn2_b64 vcc, exec, s[86:87]
	s_cbranch_vccnz .LBB0_458
	v_cvt_pk_bf16_f32 v126, v126, v127
	v_cvt_pk_bf16_f32 v127, v128, v129
	v_cvt_pk_bf16_f32 v128, v122, v123
	v_lshl_add_u64 v[122:123], s[28:29], 0, v[136:137]
	v_lshl_add_u64 v[122:123], s[62:63], 1, v[122:123]
	v_lshl_add_u64 v[122:123], v[122:123], 0, v[162:163]
	v_cvt_pk_bf16_f32 v129, v124, v125
	global_store_dwordx4 v[122:123], v[126:129], off sc1
.LBB0_458:
	v_mov_b32_e32 v143, v142
	v_mov_b32_e32 v122, v142
	v_mov_b32_e32 v123, v142
	v_pk_fma_f32 v[120:121], v[120:121], v[122:123], v[40:41]
	v_pk_fma_f32 v[118:119], v[118:119], v[142:143], v[38:39]
	v_pk_fma_f32 v[116:117], v[116:117], v[122:123], v[36:37]
	v_pk_fma_f32 v[114:115], v[114:115], v[142:143], v[34:35]
	s_and_b64 vcc, exec, s[10:11]
	s_mov_b64 s[86:87], -1
	s_cbranch_vccnz .LBB0_462
	s_add_i32 s24, s62, 0xfffff680
	v_lshl_add_u64 v[126:127], s[24:25], 1, v[146:147]
	v_lshl_add_u64 v[126:127], v[126:127], 0, v[162:163]
	s_andn2_b64 vcc, exec, s[64:65]
	v_cvt_pk_bf16_f32 v122, v118, v119
	v_cvt_pk_bf16_f32 v123, v120, v121
	v_cvt_pk_bf16_f32 v124, v114, v115
	v_cvt_pk_bf16_f32 v125, v116, v117
	global_store_dwordx4 v[126:127], v[122:125], off sc1
	s_cbranch_vccnz .LBB0_461
	s_lshl_b32 s86, s89, 1
	s_ashr_i32 s87, s86, 31
	s_lshl_b64 s[86:87], s[86:87], 19
	s_add_u32 s86, s38, s86
	s_addc_u32 s87, s39, s87
	v_lshlrev_b32_e32 v122, 2, v148
	v_mov_b32_e32 v123, v163
	v_lshl_add_u64 v[122:123], s[86:87], 0, v[122:123]
	v_lshl_add_u64 v[122:123], s[24:25], 2, v[122:123]
	v_mov_b32_e32 v183, v163
	v_lshl_add_u64 v[122:123], v[122:123], 0, v[182:183]
	global_store_dwordx4 v[122:123], v[118:121], off sc1
	global_store_dwordx4 v[122:123], v[114:117], off offset:16 sc1

.LBB0_462:
	s_andn2_b64 vcc, exec, s[86:87]
	s_cbranch_vccnz .LBB0_469
	v_pk_mul_f32 v[122:123], v[116:117], v[138:139]
	v_pk_mul_f32 v[124:125], v[114:115], v[140:141]
	v_pk_mul_f32 v[126:127], v[116:117], v[130:131]
	v_pk_mul_f32 v[128:129], v[114:115], v[134:135]
	v_pk_fma_f32 v[122:123], v[120:121], v[130:131], v[122:123] neg_lo:[0,0,1] neg_hi:[0,0,1]
	v_pk_fma_f32 v[124:125], v[118:119], v[134:135], v[124:125] neg_lo:[0,0,1] neg_hi:[0,0,1]
	v_pk_fma_f32 v[126:127], v[120:121], v[138:139], v[126:127]
	v_pk_fma_f32 v[128:129], v[118:119], v[140:141], v[128:129]
	v_cndmask_b32_e64 v117, v117, v127, s[4:5]
	v_cndmask_b32_e64 v116, v116, v126, s[4:5]
	v_cndmask_b32_e64 v115, v115, v129, s[4:5]
	v_cndmask_b32_e64 v114, v114, v128, s[4:5]
	v_cndmask_b32_e64 v121, v121, v123, s[4:5]
	v_cndmask_b32_e64 v120, v120, v122, s[4:5]
	v_cndmask_b32_e64 v119, v119, v125, s[4:5]
	v_cndmask_b32_e64 v118, v118, v124, s[4:5]
	s_and_b64 vcc, exec, s[6:7]
	s_mov_b64 s[86:87], -1
	s_cbranch_vccnz .LBB0_467
	v_lshl_add_u64 v[126:127], s[30:31], 0, v[132:133]
	s_add_i32 s24, s62, 0xfffff880
	v_lshl_add_u64 v[126:127], s[24:25], 1, v[126:127]
	v_lshl_add_u64 v[126:127], v[126:127], 0, v[162:163]
	s_andn2_b64 vcc, exec, s[64:65]
	v_cvt_pk_bf16_f32 v122, v118, v119
	v_cvt_pk_bf16_f32 v123, v120, v121
	v_cvt_pk_bf16_f32 v124, v114, v115
	v_cvt_pk_bf16_f32 v125, v116, v117
	global_store_dwordx4 v[126:127], v[122:125], off sc1
	s_cbranch_vccnz .LBB0_466
	s_lshl_b32 s86, s89, 1
	s_ashr_i32 s87, s86, 31
	s_lshl_b64 s[86:87], s[86:87], 19
	s_add_u32 s86, s36, s86
	s_addc_u32 s87, s37, s87
	v_lshlrev_b32_e32 v122, 2, v148
	v_mov_b32_e32 v123, v163
	v_lshl_add_u64 v[122:123], s[86:87], 0, v[122:123]
	v_lshl_add_u64 v[122:123], s[24:25], 2, v[122:123]
	v_lshlrev_b32_e32 v124, 2, v166
	v_mov_b32_e32 v125, v163
	v_lshl_add_u64 v[122:123], v[122:123], 0, v[124:125]
	global_store_dwordx4 v[122:123], v[118:121], off sc1
	global_store_dwordx4 v[122:123], v[114:117], off offset:128 sc1

.LBB0_467:
	s_andn2_b64 vcc, exec, s[86:87]
	s_cbranch_vccnz .LBB0_469
	v_cvt_pk_bf16_f32 v118, v118, v119
	v_cvt_pk_bf16_f32 v119, v120, v121
	v_cvt_pk_bf16_f32 v120, v114, v115
	v_lshl_add_u64 v[114:115], s[28:29], 0, v[136:137]
	v_lshl_add_u64 v[114:115], s[62:63], 1, v[114:115]
	v_lshl_add_u64 v[114:115], v[114:115], 0, v[162:163]
	v_cvt_pk_bf16_f32 v121, v116, v117
	global_store_dwordx4 v[114:115], v[118:121], off offset:256 sc1

.LBB0_476:
	v_lshlrev_b64 v[116:117], 10, v[128:129]
	v_lshlrev_b32_e32 v120, 9, v128
	v_and_b32_e32 v132, 0x1de00, v120
	s_waitcnt lgkmcnt(0)
	v_pk_fma_f32 v[112:113], v[112:113], v[126:127], v[48:49] op_sel_hi:[1,0,1]
	v_pk_fma_f32 v[110:111], v[110:111], v[126:127], v[46:47] op_sel_hi:[1,0,1]
	v_pk_fma_f32 v[108:109], v[108:109], v[126:127], v[44:45] op_sel_hi:[1,0,1]
	v_pk_fma_f32 v[106:107], v[106:107], v[126:127], v[42:43] op_sel_hi:[1,0,1]
	s_mov_b64 s[86:87], -1
	s_and_b64 vcc, exec, s[10:11]
	v_lshl_add_u64 v[130:131], s[34:35], 0, v[116:117]
	s_cbranch_vccnz .LBB0_480
	s_lshl_b32 s24, s51, 7
	v_lshl_add_u64 v[120:121], s[24:25], 1, v[130:131]
	v_lshl_add_u64 v[120:121], v[120:121], 0, v[162:163]
	s_andn2_b64 vcc, exec, s[64:65]
	v_cvt_pk_bf16_f32 v134, v110, v111
	v_cvt_pk_bf16_f32 v135, v112, v113
	v_cvt_pk_bf16_f32 v136, v106, v107
	v_cvt_pk_bf16_f32 v137, v108, v109
	global_store_dwordx4 v[120:121], v[134:137], off sc1
	s_cbranch_vccnz .LBB0_479
	s_lshl_b32 s86, s89, 1
	s_ashr_i32 s87, s86, 31
	s_lshl_b64 s[86:87], s[86:87], 19
	s_add_u32 s86, s38, s86
	s_addc_u32 s87, s39, s87
	v_lshlrev_b32_e32 v120, 2, v132
	v_mov_b32_e32 v121, v163
	v_lshl_add_u64 v[120:121], s[86:87], 0, v[120:121]
	v_lshl_add_u64 v[120:121], s[24:25], 2, v[120:121]
	v_mov_b32_e32 v183, v163
	v_lshl_add_u64 v[120:121], v[120:121], 0, v[182:183]
	global_store_dwordx4 v[120:121], v[110:113], off sc1
	global_store_dwordx4 v[120:121], v[106:109], off offset:16 sc1

.LBB0_480:
	s_andn2_b64 vcc, exec, s[86:87]
	v_lshlrev_b64 v[120:121], 12, v[128:129]
	s_cbranch_vccnz .LBB0_487
	v_pk_mul_f32 v[128:129], v[108:109], v[122:123]
	v_pk_mul_f32 v[134:135], v[106:107], v[124:125]
	v_pk_mul_f32 v[136:137], v[108:109], v[114:115]
	v_pk_mul_f32 v[138:139], v[106:107], v[118:119]
	v_pk_fma_f32 v[128:129], v[112:113], v[114:115], v[128:129] neg_lo:[0,0,1] neg_hi:[0,0,1]
	v_pk_fma_f32 v[134:135], v[110:111], v[118:119], v[134:135] neg_lo:[0,0,1] neg_hi:[0,0,1]
	v_pk_fma_f32 v[136:137], v[112:113], v[122:123], v[136:137]
	v_pk_fma_f32 v[138:139], v[110:111], v[124:125], v[138:139]
	v_cndmask_b32_e64 v109, v109, v137, s[4:5]
	v_cndmask_b32_e64 v108, v108, v136, s[4:5]
	v_cndmask_b32_e64 v107, v107, v139, s[4:5]
	v_cndmask_b32_e64 v106, v106, v138, s[4:5]
	v_cndmask_b32_e64 v113, v113, v129, s[4:5]
	v_cndmask_b32_e64 v112, v112, v128, s[4:5]
	v_cndmask_b32_e64 v111, v111, v135, s[4:5]
	v_cndmask_b32_e64 v110, v110, v134, s[4:5]
	s_and_b64 vcc, exec, s[6:7]
	s_mov_b64 s[86:87], -1
	s_cbranch_vccnz .LBB0_485
	v_lshl_add_u64 v[128:129], s[30:31], 0, v[116:117]
	s_lshl_b32 s24, s50, 8
	v_lshl_add_u64 v[128:129], v[128:129], 0, s[24:25]
	v_lshl_add_u64 v[128:129], v[128:129], 0, v[162:163]
	s_andn2_b64 vcc, exec, s[64:65]
	v_cvt_pk_bf16_f32 v134, v110, v111
	v_cvt_pk_bf16_f32 v135, v112, v113
	v_cvt_pk_bf16_f32 v136, v106, v107
	v_cvt_pk_bf16_f32 v137, v108, v109
	global_store_dwordx4 v[128:129], v[134:137], off sc1
	s_cbranch_vccnz .LBB0_484
	s_lshl_b32 s86, s89, 1
	s_ashr_i32 s87, s86, 31
	s_lshl_b32 s24, s50, 7
	s_lshl_b64 s[86:87], s[86:87], 19
	s_add_u32 s86, s36, s86
	s_addc_u32 s87, s37, s87
	v_lshlrev_b32_e32 v128, 2, v132
	v_mov_b32_e32 v129, v163
	v_lshl_add_u64 v[128:129], s[86:87], 0, v[128:129]
	v_lshl_add_u64 v[128:129], s[24:25], 2, v[128:129]
	v_lshlrev_b32_e32 v134, 2, v166
	v_mov_b32_e32 v135, v163
	v_lshl_add_u64 v[128:129], v[128:129], 0, v[134:135]
	global_store_dwordx4 v[128:129], v[110:113], off sc1
	global_store_dwordx4 v[128:129], v[106:109], off offset:128 sc1

.LBB0_485:
	s_andn2_b64 vcc, exec, s[86:87]
	s_cbranch_vccnz .LBB0_487
	v_cvt_pk_bf16_f32 v110, v110, v111
	v_cvt_pk_bf16_f32 v111, v112, v113
	v_cvt_pk_bf16_f32 v112, v106, v107
	v_lshl_add_u64 v[106:107], s[28:29], 0, v[120:121]
	v_lshl_add_u64 v[106:107], s[62:63], 1, v[106:107]
	v_lshl_add_u64 v[106:107], v[106:107], 0, v[162:163]
	v_cvt_pk_bf16_f32 v113, v108, v109
	global_store_dwordx4 v[106:107], v[110:113], off sc1
.LBB0_487:
	v_mov_b32_e32 v127, v126
	v_mov_b32_e32 v106, v126
	v_mov_b32_e32 v107, v126
	v_pk_fma_f32 v[104:105], v[104:105], v[106:107], v[40:41]
	v_pk_fma_f32 v[102:103], v[102:103], v[126:127], v[38:39]
	v_pk_fma_f32 v[100:101], v[100:101], v[106:107], v[36:37]
	v_pk_fma_f32 v[98:99], v[98:99], v[126:127], v[34:35]
	s_and_b64 vcc, exec, s[10:11]
	s_mov_b64 s[86:87], -1
	s_cbranch_vccnz .LBB0_491
	s_add_i32 s24, s62, 0xfffff680
	v_lshl_add_u64 v[110:111], s[24:25], 1, v[130:131]
	v_lshl_add_u64 v[110:111], v[110:111], 0, v[162:163]
	s_andn2_b64 vcc, exec, s[64:65]
	v_cvt_pk_bf16_f32 v106, v102, v103
	v_cvt_pk_bf16_f32 v107, v104, v105
	v_cvt_pk_bf16_f32 v108, v98, v99
	v_cvt_pk_bf16_f32 v109, v100, v101
	global_store_dwordx4 v[110:111], v[106:109], off sc1
	s_cbranch_vccnz .LBB0_490
	s_lshl_b32 s86, s89, 1
	s_ashr_i32 s87, s86, 31
	s_lshl_b64 s[86:87], s[86:87], 19
	s_add_u32 s86, s38, s86
	s_addc_u32 s87, s39, s87
	v_lshlrev_b32_e32 v106, 2, v132
	v_mov_b32_e32 v107, v163
	v_lshl_add_u64 v[106:107], s[86:87], 0, v[106:107]
	v_lshl_add_u64 v[106:107], s[24:25], 2, v[106:107]
	v_mov_b32_e32 v183, v163
	v_lshl_add_u64 v[106:107], v[106:107], 0, v[182:183]
	global_store_dwordx4 v[106:107], v[102:105], off sc1
	global_store_dwordx4 v[106:107], v[98:101], off offset:16 sc1

.LBB0_491:
	s_andn2_b64 vcc, exec, s[86:87]
	s_cbranch_vccnz .LBB0_498
	v_pk_mul_f32 v[106:107], v[100:101], v[122:123]
	v_pk_mul_f32 v[108:109], v[98:99], v[124:125]
	v_pk_mul_f32 v[110:111], v[100:101], v[114:115]
	v_pk_mul_f32 v[112:113], v[98:99], v[118:119]
	v_pk_fma_f32 v[106:107], v[104:105], v[114:115], v[106:107] neg_lo:[0,0,1] neg_hi:[0,0,1]
	v_pk_fma_f32 v[108:109], v[102:103], v[118:119], v[108:109] neg_lo:[0,0,1] neg_hi:[0,0,1]
	v_pk_fma_f32 v[110:111], v[104:105], v[122:123], v[110:111]
	v_pk_fma_f32 v[112:113], v[102:103], v[124:125], v[112:113]
	v_cndmask_b32_e64 v101, v101, v111, s[4:5]
	v_cndmask_b32_e64 v100, v100, v110, s[4:5]
	v_cndmask_b32_e64 v99, v99, v113, s[4:5]
	v_cndmask_b32_e64 v98, v98, v112, s[4:5]
	v_cndmask_b32_e64 v105, v105, v107, s[4:5]
	v_cndmask_b32_e64 v104, v104, v106, s[4:5]
	v_cndmask_b32_e64 v103, v103, v109, s[4:5]
	v_cndmask_b32_e64 v102, v102, v108, s[4:5]
	s_and_b64 vcc, exec, s[6:7]
	s_mov_b64 s[86:87], -1
	s_cbranch_vccnz .LBB0_496
	v_lshl_add_u64 v[110:111], s[30:31], 0, v[116:117]
	s_add_i32 s24, s62, 0xfffff880
	v_lshl_add_u64 v[110:111], s[24:25], 1, v[110:111]
	v_lshl_add_u64 v[110:111], v[110:111], 0, v[162:163]
	s_andn2_b64 vcc, exec, s[64:65]
	v_cvt_pk_bf16_f32 v106, v102, v103
	v_cvt_pk_bf16_f32 v107, v104, v105
	v_cvt_pk_bf16_f32 v108, v98, v99
	v_cvt_pk_bf16_f32 v109, v100, v101
	global_store_dwordx4 v[110:111], v[106:109], off sc1
	s_cbranch_vccnz .LBB0_495
	s_lshl_b32 s86, s89, 1
	s_ashr_i32 s87, s86, 31
	s_lshl_b64 s[86:87], s[86:87], 19
	s_add_u32 s86, s36, s86
	s_addc_u32 s87, s37, s87
	v_lshlrev_b32_e32 v106, 2, v132
	v_mov_b32_e32 v107, v163
	v_lshl_add_u64 v[106:107], s[86:87], 0, v[106:107]
	v_lshl_add_u64 v[106:107], s[24:25], 2, v[106:107]
	v_lshlrev_b32_e32 v108, 2, v166
	v_mov_b32_e32 v109, v163
	v_lshl_add_u64 v[106:107], v[106:107], 0, v[108:109]
	global_store_dwordx4 v[106:107], v[102:105], off sc1
	global_store_dwordx4 v[106:107], v[98:101], off offset:128 sc1

.LBB0_496:
	s_andn2_b64 vcc, exec, s[86:87]
	s_cbranch_vccnz .LBB0_498
	v_cvt_pk_bf16_f32 v102, v102, v103
	v_cvt_pk_bf16_f32 v103, v104, v105
	v_cvt_pk_bf16_f32 v104, v98, v99
	v_lshl_add_u64 v[98:99], s[28:29], 0, v[120:121]
	v_lshl_add_u64 v[98:99], s[62:63], 1, v[98:99]
	v_lshl_add_u64 v[98:99], v[98:99], 0, v[162:163]
	v_cvt_pk_bf16_f32 v105, v100, v101
	global_store_dwordx4 v[98:99], v[102:105], off offset:256 sc1

.LBB0_505:
	v_lshlrev_b64 v[100:101], 10, v[112:113]
	v_lshlrev_b32_e32 v104, 9, v112
	v_and_b32_e32 v116, 0x1fe00, v104
	s_waitcnt lgkmcnt(0)
	v_pk_fma_f32 v[96:97], v[96:97], v[110:111], v[48:49] op_sel_hi:[1,0,1]
	v_pk_fma_f32 v[94:95], v[94:95], v[110:111], v[46:47] op_sel_hi:[1,0,1]
	v_pk_fma_f32 v[92:93], v[92:93], v[110:111], v[44:45] op_sel_hi:[1,0,1]
	v_pk_fma_f32 v[90:91], v[90:91], v[110:111], v[42:43] op_sel_hi:[1,0,1]
	s_mov_b64 s[86:87], -1
	s_and_b64 vcc, exec, s[10:11]
	v_lshl_add_u64 v[114:115], s[34:35], 0, v[100:101]
	s_cbranch_vccnz .LBB0_509
	s_lshl_b32 s24, s51, 7
	v_lshl_add_u64 v[104:105], s[24:25], 1, v[114:115]
	v_lshl_add_u64 v[104:105], v[104:105], 0, v[162:163]
	s_andn2_b64 vcc, exec, s[64:65]
	v_cvt_pk_bf16_f32 v118, v94, v95
	v_cvt_pk_bf16_f32 v119, v96, v97
	v_cvt_pk_bf16_f32 v120, v90, v91
	v_cvt_pk_bf16_f32 v121, v92, v93
	global_store_dwordx4 v[104:105], v[118:121], off sc1
	s_cbranch_vccnz .LBB0_508
	s_lshl_b32 s86, s89, 1
	s_ashr_i32 s87, s86, 31
	s_lshl_b64 s[86:87], s[86:87], 19
	s_add_u32 s86, s38, s86
	s_addc_u32 s87, s39, s87
	v_lshlrev_b32_e32 v104, 2, v116
	v_mov_b32_e32 v105, v163
	v_lshl_add_u64 v[104:105], s[86:87], 0, v[104:105]
	v_lshl_add_u64 v[104:105], s[24:25], 2, v[104:105]
	v_mov_b32_e32 v183, v163
	v_lshl_add_u64 v[104:105], v[104:105], 0, v[182:183]
	global_store_dwordx4 v[104:105], v[94:97], off sc1
	global_store_dwordx4 v[104:105], v[90:93], off offset:16 sc1

.LBB0_509:
	s_andn2_b64 vcc, exec, s[86:87]
	v_lshlrev_b64 v[104:105], 12, v[112:113]
	s_cbranch_vccnz .LBB0_516
	v_pk_mul_f32 v[112:113], v[92:93], v[106:107]
	v_pk_mul_f32 v[118:119], v[90:91], v[108:109]
	v_pk_mul_f32 v[120:121], v[92:93], v[98:99]
	v_pk_mul_f32 v[122:123], v[90:91], v[102:103]
	v_pk_fma_f32 v[112:113], v[96:97], v[98:99], v[112:113] neg_lo:[0,0,1] neg_hi:[0,0,1]
	v_pk_fma_f32 v[118:119], v[94:95], v[102:103], v[118:119] neg_lo:[0,0,1] neg_hi:[0,0,1]
	v_pk_fma_f32 v[120:121], v[96:97], v[106:107], v[120:121]
	v_pk_fma_f32 v[122:123], v[94:95], v[108:109], v[122:123]
	v_cndmask_b32_e64 v93, v93, v121, s[4:5]
	v_cndmask_b32_e64 v92, v92, v120, s[4:5]
	v_cndmask_b32_e64 v91, v91, v123, s[4:5]
	v_cndmask_b32_e64 v90, v90, v122, s[4:5]
	v_cndmask_b32_e64 v97, v97, v113, s[4:5]
	v_cndmask_b32_e64 v96, v96, v112, s[4:5]
	v_cndmask_b32_e64 v95, v95, v119, s[4:5]
	v_cndmask_b32_e64 v94, v94, v118, s[4:5]
	s_and_b64 vcc, exec, s[6:7]
	s_mov_b64 s[86:87], -1
	s_cbranch_vccnz .LBB0_514
	v_lshl_add_u64 v[112:113], s[30:31], 0, v[100:101]
	s_lshl_b32 s24, s50, 8
	v_lshl_add_u64 v[112:113], v[112:113], 0, s[24:25]
	v_lshl_add_u64 v[112:113], v[112:113], 0, v[162:163]
	s_andn2_b64 vcc, exec, s[64:65]
	v_cvt_pk_bf16_f32 v118, v94, v95
	v_cvt_pk_bf16_f32 v119, v96, v97
	v_cvt_pk_bf16_f32 v120, v90, v91
	v_cvt_pk_bf16_f32 v121, v92, v93
	global_store_dwordx4 v[112:113], v[118:121], off sc1
	s_cbranch_vccnz .LBB0_513
	s_lshl_b32 s86, s89, 1
	s_ashr_i32 s87, s86, 31
	s_lshl_b32 s24, s50, 7
	s_lshl_b64 s[86:87], s[86:87], 19
	s_add_u32 s86, s36, s86
	s_addc_u32 s87, s37, s87
	v_lshlrev_b32_e32 v112, 2, v116
	v_mov_b32_e32 v113, v163
	v_lshl_add_u64 v[112:113], s[86:87], 0, v[112:113]
	v_lshl_add_u64 v[112:113], s[24:25], 2, v[112:113]
	v_lshlrev_b32_e32 v118, 2, v166
	v_mov_b32_e32 v119, v163
	v_lshl_add_u64 v[112:113], v[112:113], 0, v[118:119]
	global_store_dwordx4 v[112:113], v[94:97], off sc1
	global_store_dwordx4 v[112:113], v[90:93], off offset:128 sc1

.LBB0_514:
	s_andn2_b64 vcc, exec, s[86:87]
	s_cbranch_vccnz .LBB0_516
	v_cvt_pk_bf16_f32 v94, v94, v95
	v_cvt_pk_bf16_f32 v95, v96, v97
	v_cvt_pk_bf16_f32 v96, v90, v91
	v_lshl_add_u64 v[90:91], s[28:29], 0, v[104:105]
	v_lshl_add_u64 v[90:91], s[62:63], 1, v[90:91]
	v_lshl_add_u64 v[90:91], v[90:91], 0, v[162:163]
	v_cvt_pk_bf16_f32 v97, v92, v93
	global_store_dwordx4 v[90:91], v[94:97], off sc1
.LBB0_516:
	v_mov_b32_e32 v111, v110
	v_mov_b32_e32 v90, v110
	v_mov_b32_e32 v91, v110
	v_pk_fma_f32 v[88:89], v[88:89], v[90:91], v[40:41]
	v_pk_fma_f32 v[86:87], v[86:87], v[110:111], v[38:39]
	v_pk_fma_f32 v[84:85], v[84:85], v[90:91], v[36:37]
	v_pk_fma_f32 v[82:83], v[82:83], v[110:111], v[34:35]
	s_and_b64 vcc, exec, s[10:11]
	s_mov_b64 s[86:87], -1
	s_cbranch_vccnz .LBB0_520
	s_add_i32 s24, s62, 0xfffff680
	v_lshl_add_u64 v[94:95], s[24:25], 1, v[114:115]
	v_lshl_add_u64 v[94:95], v[94:95], 0, v[162:163]
	s_andn2_b64 vcc, exec, s[64:65]
	v_cvt_pk_bf16_f32 v90, v86, v87
	v_cvt_pk_bf16_f32 v91, v88, v89
	v_cvt_pk_bf16_f32 v92, v82, v83
	v_cvt_pk_bf16_f32 v93, v84, v85
	global_store_dwordx4 v[94:95], v[90:93], off sc1
	s_cbranch_vccnz .LBB0_519
	s_lshl_b32 s86, s89, 1
	s_ashr_i32 s87, s86, 31
	s_lshl_b64 s[86:87], s[86:87], 19
	s_add_u32 s86, s38, s86
	s_addc_u32 s87, s39, s87
	v_lshlrev_b32_e32 v90, 2, v116
	v_mov_b32_e32 v91, v163
	v_lshl_add_u64 v[90:91], s[86:87], 0, v[90:91]
	v_lshl_add_u64 v[90:91], s[24:25], 2, v[90:91]
	v_mov_b32_e32 v183, v163
	v_lshl_add_u64 v[90:91], v[90:91], 0, v[182:183]
	global_store_dwordx4 v[90:91], v[86:89], off sc1
	global_store_dwordx4 v[90:91], v[82:85], off offset:16 sc1

.LBB0_520:
	s_andn2_b64 vcc, exec, s[86:87]
	s_cbranch_vccnz .LBB0_527
	v_pk_mul_f32 v[90:91], v[84:85], v[106:107]
	v_pk_mul_f32 v[92:93], v[82:83], v[108:109]
	v_pk_mul_f32 v[94:95], v[84:85], v[98:99]
	v_pk_mul_f32 v[96:97], v[82:83], v[102:103]
	v_pk_fma_f32 v[90:91], v[88:89], v[98:99], v[90:91] neg_lo:[0,0,1] neg_hi:[0,0,1]
	v_pk_fma_f32 v[92:93], v[86:87], v[102:103], v[92:93] neg_lo:[0,0,1] neg_hi:[0,0,1]
	v_pk_fma_f32 v[94:95], v[88:89], v[106:107], v[94:95]
	v_pk_fma_f32 v[96:97], v[86:87], v[108:109], v[96:97]
	v_cndmask_b32_e64 v85, v85, v95, s[4:5]
	v_cndmask_b32_e64 v84, v84, v94, s[4:5]
	v_cndmask_b32_e64 v83, v83, v97, s[4:5]
	v_cndmask_b32_e64 v82, v82, v96, s[4:5]
	v_cndmask_b32_e64 v89, v89, v91, s[4:5]
	v_cndmask_b32_e64 v88, v88, v90, s[4:5]
	v_cndmask_b32_e64 v87, v87, v93, s[4:5]
	v_cndmask_b32_e64 v86, v86, v92, s[4:5]
	s_and_b64 vcc, exec, s[6:7]
	s_mov_b64 s[86:87], -1
	s_cbranch_vccnz .LBB0_525
	v_lshl_add_u64 v[94:95], s[30:31], 0, v[100:101]
	s_add_i32 s24, s62, 0xfffff880
	v_lshl_add_u64 v[94:95], s[24:25], 1, v[94:95]
	v_lshl_add_u64 v[94:95], v[94:95], 0, v[162:163]
	s_andn2_b64 vcc, exec, s[64:65]
	v_cvt_pk_bf16_f32 v90, v86, v87
	v_cvt_pk_bf16_f32 v91, v88, v89
	v_cvt_pk_bf16_f32 v92, v82, v83
	v_cvt_pk_bf16_f32 v93, v84, v85
	global_store_dwordx4 v[94:95], v[90:93], off sc1
	s_cbranch_vccnz .LBB0_524
	s_lshl_b32 s86, s89, 1
	s_ashr_i32 s87, s86, 31
	s_lshl_b64 s[86:87], s[86:87], 19
	s_add_u32 s86, s36, s86
	s_addc_u32 s87, s37, s87
	v_lshlrev_b32_e32 v90, 2, v116
	v_mov_b32_e32 v91, v163
	v_lshl_add_u64 v[90:91], s[86:87], 0, v[90:91]
	v_lshl_add_u64 v[90:91], s[24:25], 2, v[90:91]
	v_lshlrev_b32_e32 v92, 2, v166
	v_mov_b32_e32 v93, v163
	v_lshl_add_u64 v[90:91], v[90:91], 0, v[92:93]
	global_store_dwordx4 v[90:91], v[86:89], off sc1
	global_store_dwordx4 v[90:91], v[82:85], off offset:128 sc1

.LBB0_525:
	s_andn2_b64 vcc, exec, s[86:87]
	s_cbranch_vccnz .LBB0_527
	v_cvt_pk_bf16_f32 v86, v86, v87
	v_cvt_pk_bf16_f32 v87, v88, v89
	v_cvt_pk_bf16_f32 v88, v82, v83
	v_lshl_add_u64 v[82:83], s[28:29], 0, v[104:105]
	v_lshl_add_u64 v[82:83], s[62:63], 1, v[82:83]
	v_lshl_add_u64 v[82:83], v[82:83], 0, v[162:163]
	v_cvt_pk_bf16_f32 v89, v84, v85
	global_store_dwordx4 v[82:83], v[86:89], off offset:256 sc1

.LBB0_534:
	v_lshlrev_b64 v[84:85], 10, v[96:97]
	v_lshlrev_b32_e32 v88, 9, v96
	v_and_b32_e32 v101, 0x19e00, v88
	s_waitcnt lgkmcnt(0)
	v_pk_fma_f32 v[80:81], v[80:81], v[94:95], v[48:49] op_sel_hi:[1,0,1]
	v_pk_fma_f32 v[78:79], v[78:79], v[94:95], v[46:47] op_sel_hi:[1,0,1]
	v_pk_fma_f32 v[76:77], v[76:77], v[94:95], v[44:45] op_sel_hi:[1,0,1]
	v_pk_fma_f32 v[74:75], v[74:75], v[94:95], v[42:43] op_sel_hi:[1,0,1]
	s_mov_b64 s[86:87], -1
	s_and_b64 vcc, exec, s[10:11]
	v_lshl_add_u64 v[98:99], s[34:35], 0, v[84:85]
	s_cbranch_vccnz .LBB0_538
	s_lshl_b32 s24, s51, 7
	v_lshl_add_u64 v[88:89], s[24:25], 1, v[98:99]
	v_lshl_add_u64 v[88:89], v[88:89], 0, v[162:163]
	s_andn2_b64 vcc, exec, s[64:65]
	v_cvt_pk_bf16_f32 v102, v78, v79
	v_cvt_pk_bf16_f32 v103, v80, v81
	v_cvt_pk_bf16_f32 v104, v74, v75
	v_cvt_pk_bf16_f32 v105, v76, v77
	global_store_dwordx4 v[88:89], v[102:105], off sc1
	s_cbranch_vccnz .LBB0_537
	s_lshl_b32 s86, s89, 1
	s_ashr_i32 s87, s86, 31
	s_lshl_b64 s[86:87], s[86:87], 19
	s_add_u32 s86, s38, s86
	s_addc_u32 s87, s39, s87
	v_lshlrev_b32_e32 v88, 2, v101
	v_mov_b32_e32 v89, v163
	v_lshl_add_u64 v[88:89], s[86:87], 0, v[88:89]
	v_lshl_add_u64 v[88:89], s[24:25], 2, v[88:89]
	v_mov_b32_e32 v183, v163
	v_lshl_add_u64 v[88:89], v[88:89], 0, v[182:183]
	global_store_dwordx4 v[88:89], v[78:81], off sc1
	global_store_dwordx4 v[88:89], v[74:77], off offset:16 sc1

.LBB0_538:
	s_andn2_b64 vcc, exec, s[86:87]
	v_lshlrev_b64 v[88:89], 12, v[96:97]
	s_cbranch_vccnz .LBB0_545
	v_pk_mul_f32 v[96:97], v[76:77], v[90:91]
	v_pk_mul_f32 v[102:103], v[74:75], v[92:93]
	v_pk_mul_f32 v[104:105], v[76:77], v[82:83]
	v_pk_mul_f32 v[106:107], v[74:75], v[86:87]
	v_pk_fma_f32 v[96:97], v[80:81], v[82:83], v[96:97] neg_lo:[0,0,1] neg_hi:[0,0,1]
	v_pk_fma_f32 v[102:103], v[78:79], v[86:87], v[102:103] neg_lo:[0,0,1] neg_hi:[0,0,1]
	v_pk_fma_f32 v[104:105], v[80:81], v[90:91], v[104:105]
	v_pk_fma_f32 v[106:107], v[78:79], v[92:93], v[106:107]
	v_cndmask_b32_e64 v77, v77, v105, s[4:5]
	v_cndmask_b32_e64 v76, v76, v104, s[4:5]
	v_cndmask_b32_e64 v75, v75, v107, s[4:5]
	v_cndmask_b32_e64 v74, v74, v106, s[4:5]
	v_cndmask_b32_e64 v81, v81, v97, s[4:5]
	v_cndmask_b32_e64 v80, v80, v96, s[4:5]
	v_cndmask_b32_e64 v79, v79, v103, s[4:5]
	v_cndmask_b32_e64 v78, v78, v102, s[4:5]
	s_and_b64 vcc, exec, s[6:7]
	s_mov_b64 s[86:87], -1
	s_cbranch_vccnz .LBB0_543
	v_lshl_add_u64 v[96:97], s[30:31], 0, v[84:85]
	s_lshl_b32 s24, s50, 8
	v_lshl_add_u64 v[96:97], v[96:97], 0, s[24:25]
	v_lshl_add_u64 v[96:97], v[96:97], 0, v[162:163]
	s_andn2_b64 vcc, exec, s[64:65]
	v_cvt_pk_bf16_f32 v102, v78, v79
	v_cvt_pk_bf16_f32 v103, v80, v81
	v_cvt_pk_bf16_f32 v104, v74, v75
	v_cvt_pk_bf16_f32 v105, v76, v77
	global_store_dwordx4 v[96:97], v[102:105], off sc1
	s_cbranch_vccnz .LBB0_542
	s_lshl_b32 s86, s89, 1
	s_ashr_i32 s87, s86, 31
	s_lshl_b32 s24, s50, 7
	s_lshl_b64 s[86:87], s[86:87], 19
	s_add_u32 s86, s36, s86
	s_addc_u32 s87, s37, s87
	v_lshlrev_b32_e32 v96, 2, v101
	v_mov_b32_e32 v97, v163
	v_lshl_add_u64 v[96:97], s[86:87], 0, v[96:97]
	v_lshl_add_u64 v[96:97], s[24:25], 2, v[96:97]
	v_lshlrev_b32_e32 v102, 2, v166
	v_mov_b32_e32 v103, v163
	v_lshl_add_u64 v[96:97], v[96:97], 0, v[102:103]
	global_store_dwordx4 v[96:97], v[78:81], off sc1
	global_store_dwordx4 v[96:97], v[74:77], off offset:128 sc1

.LBB0_543:
	s_andn2_b64 vcc, exec, s[86:87]
	s_cbranch_vccnz .LBB0_545
	v_cvt_pk_bf16_f32 v78, v78, v79
	v_cvt_pk_bf16_f32 v79, v80, v81
	v_cvt_pk_bf16_f32 v80, v74, v75
	v_lshl_add_u64 v[74:75], s[28:29], 0, v[88:89]
	v_lshl_add_u64 v[74:75], s[62:63], 1, v[74:75]
	v_lshl_add_u64 v[74:75], v[74:75], 0, v[162:163]
	v_cvt_pk_bf16_f32 v81, v76, v77
	global_store_dwordx4 v[74:75], v[78:81], off sc1
.LBB0_545:
	v_mov_b32_e32 v95, v94
	v_mov_b32_e32 v74, v94
	v_mov_b32_e32 v75, v94
	v_pk_fma_f32 v[72:73], v[72:73], v[74:75], v[40:41]
	v_pk_fma_f32 v[70:71], v[70:71], v[94:95], v[38:39]
	v_pk_fma_f32 v[68:69], v[68:69], v[74:75], v[36:37]
	v_pk_fma_f32 v[66:67], v[66:67], v[94:95], v[34:35]
	s_and_b64 vcc, exec, s[10:11]
	s_mov_b64 s[86:87], -1
	s_cbranch_vccnz .LBB0_549
	s_add_i32 s24, s62, 0xfffff680
	v_lshl_add_u64 v[78:79], s[24:25], 1, v[98:99]
	v_lshl_add_u64 v[78:79], v[78:79], 0, v[162:163]
	s_andn2_b64 vcc, exec, s[64:65]
	v_cvt_pk_bf16_f32 v74, v70, v71
	v_cvt_pk_bf16_f32 v75, v72, v73
	v_cvt_pk_bf16_f32 v76, v66, v67
	v_cvt_pk_bf16_f32 v77, v68, v69
	global_store_dwordx4 v[78:79], v[74:77], off sc1
	s_cbranch_vccnz .LBB0_548
	s_lshl_b32 s86, s89, 1
	s_ashr_i32 s87, s86, 31
	s_lshl_b64 s[86:87], s[86:87], 19
	s_add_u32 s86, s38, s86
	s_addc_u32 s87, s39, s87
	v_lshlrev_b32_e32 v74, 2, v101
	v_mov_b32_e32 v75, v163
	v_lshl_add_u64 v[74:75], s[86:87], 0, v[74:75]
	v_lshl_add_u64 v[74:75], s[24:25], 2, v[74:75]
	v_mov_b32_e32 v183, v163
	v_lshl_add_u64 v[74:75], v[74:75], 0, v[182:183]
	global_store_dwordx4 v[74:75], v[70:73], off sc1
	global_store_dwordx4 v[74:75], v[66:69], off offset:16 sc1

.LBB0_549:
	s_andn2_b64 vcc, exec, s[86:87]
	s_cbranch_vccnz .LBB0_556
	v_pk_mul_f32 v[74:75], v[68:69], v[90:91]
	v_pk_mul_f32 v[76:77], v[66:67], v[92:93]
	v_pk_mul_f32 v[78:79], v[68:69], v[82:83]
	v_pk_mul_f32 v[80:81], v[66:67], v[86:87]
	v_pk_fma_f32 v[74:75], v[72:73], v[82:83], v[74:75] neg_lo:[0,0,1] neg_hi:[0,0,1]
	v_pk_fma_f32 v[76:77], v[70:71], v[86:87], v[76:77] neg_lo:[0,0,1] neg_hi:[0,0,1]
	v_pk_fma_f32 v[78:79], v[72:73], v[90:91], v[78:79]
	v_pk_fma_f32 v[80:81], v[70:71], v[92:93], v[80:81]
	v_cndmask_b32_e64 v69, v69, v79, s[4:5]
	v_cndmask_b32_e64 v68, v68, v78, s[4:5]
	v_cndmask_b32_e64 v67, v67, v81, s[4:5]
	v_cndmask_b32_e64 v66, v66, v80, s[4:5]
	v_cndmask_b32_e64 v73, v73, v75, s[4:5]
	v_cndmask_b32_e64 v72, v72, v74, s[4:5]
	v_cndmask_b32_e64 v71, v71, v77, s[4:5]
	v_cndmask_b32_e64 v70, v70, v76, s[4:5]
	s_and_b64 vcc, exec, s[6:7]
	s_mov_b64 s[86:87], -1
	s_cbranch_vccnz .LBB0_554
	v_lshl_add_u64 v[78:79], s[30:31], 0, v[84:85]
	s_add_i32 s24, s62, 0xfffff880
	v_lshl_add_u64 v[78:79], s[24:25], 1, v[78:79]
	v_lshl_add_u64 v[78:79], v[78:79], 0, v[162:163]
	s_andn2_b64 vcc, exec, s[64:65]
	v_cvt_pk_bf16_f32 v74, v70, v71
	v_cvt_pk_bf16_f32 v75, v72, v73
	v_cvt_pk_bf16_f32 v76, v66, v67
	v_cvt_pk_bf16_f32 v77, v68, v69
	global_store_dwordx4 v[78:79], v[74:77], off sc1
	s_cbranch_vccnz .LBB0_553
	s_lshl_b32 s86, s89, 1
	s_ashr_i32 s87, s86, 31
	s_lshl_b64 s[86:87], s[86:87], 19
	s_add_u32 s86, s36, s86
	s_addc_u32 s87, s37, s87
	v_lshlrev_b32_e32 v74, 2, v101
	v_mov_b32_e32 v75, v163
	v_lshl_add_u64 v[74:75], s[86:87], 0, v[74:75]
	v_lshl_add_u64 v[74:75], s[24:25], 2, v[74:75]
	v_lshlrev_b32_e32 v76, 2, v166
	v_mov_b32_e32 v77, v163
	v_lshl_add_u64 v[74:75], v[74:75], 0, v[76:77]
	global_store_dwordx4 v[74:75], v[70:73], off sc1
	global_store_dwordx4 v[74:75], v[66:69], off offset:128 sc1

.LBB0_554:
	s_andn2_b64 vcc, exec, s[86:87]
	s_cbranch_vccnz .LBB0_556
	v_cvt_pk_bf16_f32 v70, v70, v71
	v_cvt_pk_bf16_f32 v71, v72, v73
	v_cvt_pk_bf16_f32 v72, v66, v67
	v_lshl_add_u64 v[66:67], s[28:29], 0, v[88:89]
	v_lshl_add_u64 v[66:67], s[62:63], 1, v[66:67]
	v_lshl_add_u64 v[66:67], v[66:67], 0, v[162:163]
	v_cvt_pk_bf16_f32 v73, v68, v69
	global_store_dwordx4 v[66:67], v[70:73], off offset:256 sc1

.LBB0_563:
	v_lshlrev_b64 v[68:69], 10, v[80:81]
	v_lshlrev_b32_e32 v72, 9, v80
	v_and_b32_e32 v84, 0x1be00, v72
	s_waitcnt lgkmcnt(0)
	v_pk_fma_f32 v[64:65], v[64:65], v[78:79], v[48:49] op_sel_hi:[1,0,1]
	v_pk_fma_f32 v[62:63], v[62:63], v[78:79], v[46:47] op_sel_hi:[1,0,1]
	v_pk_fma_f32 v[60:61], v[60:61], v[78:79], v[44:45] op_sel_hi:[1,0,1]
	v_pk_fma_f32 v[58:59], v[58:59], v[78:79], v[42:43] op_sel_hi:[1,0,1]
	s_mov_b64 s[86:87], -1
	s_and_b64 vcc, exec, s[10:11]
	v_lshl_add_u64 v[82:83], s[34:35], 0, v[68:69]
	s_cbranch_vccnz .LBB0_567
	s_lshl_b32 s24, s51, 7
	v_lshl_add_u64 v[72:73], s[24:25], 1, v[82:83]
	v_lshl_add_u64 v[72:73], v[72:73], 0, v[162:163]
	s_andn2_b64 vcc, exec, s[64:65]
	v_cvt_pk_bf16_f32 v86, v62, v63
	v_cvt_pk_bf16_f32 v87, v64, v65
	v_cvt_pk_bf16_f32 v88, v58, v59
	v_cvt_pk_bf16_f32 v89, v60, v61
	global_store_dwordx4 v[72:73], v[86:89], off sc1
	s_cbranch_vccnz .LBB0_566
	s_lshl_b32 s86, s89, 1
	s_ashr_i32 s87, s86, 31
	s_lshl_b64 s[86:87], s[86:87], 19
	s_add_u32 s86, s38, s86
	s_addc_u32 s87, s39, s87
	v_lshlrev_b32_e32 v72, 2, v84
	v_mov_b32_e32 v73, v163
	v_lshl_add_u64 v[72:73], s[86:87], 0, v[72:73]
	v_lshl_add_u64 v[72:73], s[24:25], 2, v[72:73]
	v_mov_b32_e32 v183, v163
	v_lshl_add_u64 v[72:73], v[72:73], 0, v[182:183]
	global_store_dwordx4 v[72:73], v[62:65], off sc1
	global_store_dwordx4 v[72:73], v[58:61], off offset:16 sc1

.LBB0_567:
	s_andn2_b64 vcc, exec, s[86:87]
	v_lshlrev_b64 v[72:73], 12, v[80:81]
	s_cbranch_vccnz .LBB0_574
	v_pk_mul_f32 v[80:81], v[60:61], v[74:75]
	v_pk_mul_f32 v[86:87], v[58:59], v[76:77]
	v_pk_mul_f32 v[88:89], v[60:61], v[66:67]
	v_pk_mul_f32 v[90:91], v[58:59], v[70:71]
	v_pk_fma_f32 v[80:81], v[64:65], v[66:67], v[80:81] neg_lo:[0,0,1] neg_hi:[0,0,1]
	v_pk_fma_f32 v[86:87], v[62:63], v[70:71], v[86:87] neg_lo:[0,0,1] neg_hi:[0,0,1]
	v_pk_fma_f32 v[88:89], v[64:65], v[74:75], v[88:89]
	v_pk_fma_f32 v[90:91], v[62:63], v[76:77], v[90:91]
	v_cndmask_b32_e64 v61, v61, v89, s[4:5]
	v_cndmask_b32_e64 v60, v60, v88, s[4:5]
	v_cndmask_b32_e64 v59, v59, v91, s[4:5]
	v_cndmask_b32_e64 v58, v58, v90, s[4:5]
	v_cndmask_b32_e64 v65, v65, v81, s[4:5]
	v_cndmask_b32_e64 v64, v64, v80, s[4:5]
	v_cndmask_b32_e64 v63, v63, v87, s[4:5]
	v_cndmask_b32_e64 v62, v62, v86, s[4:5]
	s_and_b64 vcc, exec, s[6:7]
	s_mov_b64 s[86:87], -1
	s_cbranch_vccnz .LBB0_572
	v_lshl_add_u64 v[80:81], s[30:31], 0, v[68:69]
	s_lshl_b32 s24, s50, 8
	v_lshl_add_u64 v[80:81], v[80:81], 0, s[24:25]
	v_lshl_add_u64 v[80:81], v[80:81], 0, v[162:163]
	s_andn2_b64 vcc, exec, s[64:65]
	v_cvt_pk_bf16_f32 v86, v62, v63
	v_cvt_pk_bf16_f32 v87, v64, v65
	v_cvt_pk_bf16_f32 v88, v58, v59
	v_cvt_pk_bf16_f32 v89, v60, v61
	global_store_dwordx4 v[80:81], v[86:89], off sc1
	s_cbranch_vccnz .LBB0_571
	s_lshl_b32 s86, s89, 1
	s_ashr_i32 s87, s86, 31
	s_lshl_b32 s24, s50, 7
	s_lshl_b64 s[86:87], s[86:87], 19
	s_add_u32 s86, s36, s86
	s_addc_u32 s87, s37, s87
	v_lshlrev_b32_e32 v80, 2, v84
	v_mov_b32_e32 v81, v163
	v_lshl_add_u64 v[80:81], s[86:87], 0, v[80:81]
	v_lshl_add_u64 v[80:81], s[24:25], 2, v[80:81]
	v_lshlrev_b32_e32 v86, 2, v166
	v_mov_b32_e32 v87, v163
	v_lshl_add_u64 v[80:81], v[80:81], 0, v[86:87]
	global_store_dwordx4 v[80:81], v[62:65], off sc1
	global_store_dwordx4 v[80:81], v[58:61], off offset:128 sc1

.LBB0_572:
	s_andn2_b64 vcc, exec, s[86:87]
	s_cbranch_vccnz .LBB0_574
	v_cvt_pk_bf16_f32 v62, v62, v63
	v_cvt_pk_bf16_f32 v63, v64, v65
	v_cvt_pk_bf16_f32 v64, v58, v59
	v_lshl_add_u64 v[58:59], s[28:29], 0, v[72:73]
	v_lshl_add_u64 v[58:59], s[62:63], 1, v[58:59]
	v_lshl_add_u64 v[58:59], v[58:59], 0, v[162:163]
	v_cvt_pk_bf16_f32 v65, v60, v61
	global_store_dwordx4 v[58:59], v[62:65], off sc1
.LBB0_574:
	v_mov_b32_e32 v79, v78
	v_mov_b32_e32 v58, v78
	v_mov_b32_e32 v59, v78
	v_pk_fma_f32 v[56:57], v[56:57], v[58:59], v[40:41]
	v_pk_fma_f32 v[54:55], v[54:55], v[78:79], v[38:39]
	v_pk_fma_f32 v[52:53], v[52:53], v[58:59], v[36:37]
	v_pk_fma_f32 v[50:51], v[50:51], v[78:79], v[34:35]
	s_and_b64 vcc, exec, s[10:11]
	s_mov_b64 s[86:87], -1
	s_cbranch_vccnz .LBB0_578
	s_add_i32 s24, s62, 0xfffff680
	v_lshl_add_u64 v[62:63], s[24:25], 1, v[82:83]
	v_lshl_add_u64 v[62:63], v[62:63], 0, v[162:163]
	s_andn2_b64 vcc, exec, s[64:65]
	v_cvt_pk_bf16_f32 v58, v54, v55
	v_cvt_pk_bf16_f32 v59, v56, v57
	v_cvt_pk_bf16_f32 v60, v50, v51
	v_cvt_pk_bf16_f32 v61, v52, v53
	global_store_dwordx4 v[62:63], v[58:61], off sc1
	s_cbranch_vccnz .LBB0_577
	s_lshl_b32 s86, s89, 1
	s_ashr_i32 s87, s86, 31
	s_lshl_b64 s[86:87], s[86:87], 19
	s_add_u32 s86, s38, s86
	s_addc_u32 s87, s39, s87
	v_lshlrev_b32_e32 v58, 2, v84
	v_mov_b32_e32 v59, v163
	v_lshl_add_u64 v[58:59], s[86:87], 0, v[58:59]
	v_lshl_add_u64 v[58:59], s[24:25], 2, v[58:59]
	v_mov_b32_e32 v183, v163
	v_lshl_add_u64 v[58:59], v[58:59], 0, v[182:183]
	global_store_dwordx4 v[58:59], v[54:57], off sc1
	global_store_dwordx4 v[58:59], v[50:53], off offset:16 sc1

.LBB0_578:
	s_andn2_b64 vcc, exec, s[86:87]
	s_cbranch_vccnz .LBB0_585
	v_pk_mul_f32 v[58:59], v[52:53], v[74:75]
	v_pk_mul_f32 v[60:61], v[50:51], v[76:77]
	v_pk_mul_f32 v[62:63], v[52:53], v[66:67]
	v_pk_mul_f32 v[64:65], v[50:51], v[70:71]
	v_pk_fma_f32 v[58:59], v[56:57], v[66:67], v[58:59] neg_lo:[0,0,1] neg_hi:[0,0,1]
	v_pk_fma_f32 v[60:61], v[54:55], v[70:71], v[60:61] neg_lo:[0,0,1] neg_hi:[0,0,1]
	v_pk_fma_f32 v[62:63], v[56:57], v[74:75], v[62:63]
	v_pk_fma_f32 v[64:65], v[54:55], v[76:77], v[64:65]
	v_cndmask_b32_e64 v53, v53, v63, s[4:5]
	v_cndmask_b32_e64 v52, v52, v62, s[4:5]
	v_cndmask_b32_e64 v51, v51, v65, s[4:5]
	v_cndmask_b32_e64 v50, v50, v64, s[4:5]
	v_cndmask_b32_e64 v57, v57, v59, s[4:5]
	v_cndmask_b32_e64 v56, v56, v58, s[4:5]
	v_cndmask_b32_e64 v55, v55, v61, s[4:5]
	v_cndmask_b32_e64 v54, v54, v60, s[4:5]
	s_and_b64 vcc, exec, s[6:7]
	s_mov_b64 s[86:87], -1
	s_cbranch_vccnz .LBB0_583
	v_lshl_add_u64 v[62:63], s[30:31], 0, v[68:69]
	s_add_i32 s24, s62, 0xfffff880
	v_lshl_add_u64 v[62:63], s[24:25], 1, v[62:63]
	v_lshl_add_u64 v[62:63], v[62:63], 0, v[162:163]
	s_andn2_b64 vcc, exec, s[64:65]
	v_cvt_pk_bf16_f32 v58, v54, v55
	v_cvt_pk_bf16_f32 v59, v56, v57
	v_cvt_pk_bf16_f32 v60, v50, v51
	v_cvt_pk_bf16_f32 v61, v52, v53
	global_store_dwordx4 v[62:63], v[58:61], off sc1
	s_cbranch_vccnz .LBB0_582
	s_lshl_b32 s86, s89, 1
	s_ashr_i32 s87, s86, 31
	s_lshl_b64 s[86:87], s[86:87], 19
	s_add_u32 s86, s36, s86
	s_addc_u32 s87, s37, s87
	v_lshlrev_b32_e32 v58, 2, v84
	v_mov_b32_e32 v59, v163
	v_lshl_add_u64 v[58:59], s[86:87], 0, v[58:59]
	v_lshl_add_u64 v[58:59], s[24:25], 2, v[58:59]
	v_lshlrev_b32_e32 v60, 2, v166
	v_mov_b32_e32 v61, v163
	v_lshl_add_u64 v[58:59], v[58:59], 0, v[60:61]
	global_store_dwordx4 v[58:59], v[54:57], off sc1
	global_store_dwordx4 v[58:59], v[50:53], off offset:128 sc1

.LBB0_583:
	s_andn2_b64 vcc, exec, s[86:87]
	s_cbranch_vccnz .LBB0_585
	v_cvt_pk_bf16_f32 v54, v54, v55
	v_cvt_pk_bf16_f32 v55, v56, v57
	v_cvt_pk_bf16_f32 v56, v50, v51
	v_lshl_add_u64 v[50:51], s[28:29], 0, v[72:73]
	v_lshl_add_u64 v[50:51], s[62:63], 1, v[50:51]
	v_lshl_add_u64 v[50:51], v[50:51], 0, v[162:163]
	v_cvt_pk_bf16_f32 v57, v52, v53
	global_store_dwordx4 v[50:51], v[54:57], off offset:256 sc1

.LBB0_592:
	v_lshlrev_b64 v[52:53], 10, v[64:65]
	v_lshlrev_b32_e32 v56, 9, v64
	v_and_b32_e32 v68, 0x1de00, v56
	s_waitcnt lgkmcnt(0)
	v_pk_fma_f32 v[32:33], v[32:33], v[62:63], v[48:49] op_sel_hi:[1,0,1]
	v_pk_fma_f32 v[30:31], v[30:31], v[62:63], v[46:47] op_sel_hi:[1,0,1]
	v_pk_fma_f32 v[28:29], v[28:29], v[62:63], v[44:45] op_sel_hi:[1,0,1]
	v_pk_fma_f32 v[26:27], v[26:27], v[62:63], v[42:43] op_sel_hi:[1,0,1]
	s_mov_b64 s[86:87], -1
	s_and_b64 vcc, exec, s[10:11]
	v_lshl_add_u64 v[66:67], s[34:35], 0, v[52:53]
	s_cbranch_vccnz .LBB0_596
	s_lshl_b32 s24, s51, 7
	v_lshl_add_u64 v[56:57], s[24:25], 1, v[66:67]
	v_lshl_add_u64 v[56:57], v[56:57], 0, v[162:163]
	s_andn2_b64 vcc, exec, s[64:65]
	v_cvt_pk_bf16_f32 v70, v30, v31
	v_cvt_pk_bf16_f32 v71, v32, v33
	v_cvt_pk_bf16_f32 v72, v26, v27
	v_cvt_pk_bf16_f32 v73, v28, v29
	global_store_dwordx4 v[56:57], v[70:73], off sc1
	s_cbranch_vccnz .LBB0_595
	s_lshl_b32 s86, s89, 1
	s_ashr_i32 s87, s86, 31
	s_lshl_b64 s[86:87], s[86:87], 19
	s_add_u32 s86, s38, s86
	s_addc_u32 s87, s39, s87
	v_lshlrev_b32_e32 v56, 2, v68
	v_mov_b32_e32 v57, v163
	v_lshl_add_u64 v[56:57], s[86:87], 0, v[56:57]
	v_lshl_add_u64 v[56:57], s[24:25], 2, v[56:57]
	v_mov_b32_e32 v183, v163
	v_lshl_add_u64 v[56:57], v[56:57], 0, v[182:183]
	global_store_dwordx4 v[56:57], v[30:33], off sc1
	global_store_dwordx4 v[56:57], v[26:29], off offset:16 sc1

.LBB0_596:
	s_andn2_b64 vcc, exec, s[86:87]
	v_lshlrev_b64 v[56:57], 12, v[64:65]
	s_cbranch_vccnz .LBB0_603
	v_pk_mul_f32 v[64:65], v[28:29], v[58:59]
	v_pk_mul_f32 v[70:71], v[26:27], v[60:61]
	v_pk_mul_f32 v[72:73], v[28:29], v[50:51]
	v_pk_mul_f32 v[74:75], v[26:27], v[54:55]
	v_pk_fma_f32 v[64:65], v[32:33], v[50:51], v[64:65] neg_lo:[0,0,1] neg_hi:[0,0,1]
	v_pk_fma_f32 v[70:71], v[30:31], v[54:55], v[70:71] neg_lo:[0,0,1] neg_hi:[0,0,1]
	v_pk_fma_f32 v[72:73], v[32:33], v[58:59], v[72:73]
	v_pk_fma_f32 v[74:75], v[30:31], v[60:61], v[74:75]
	v_cndmask_b32_e64 v29, v29, v73, s[4:5]
	v_cndmask_b32_e64 v28, v28, v72, s[4:5]
	v_cndmask_b32_e64 v27, v27, v75, s[4:5]
	v_cndmask_b32_e64 v26, v26, v74, s[4:5]
	v_cndmask_b32_e64 v33, v33, v65, s[4:5]
	v_cndmask_b32_e64 v32, v32, v64, s[4:5]
	v_cndmask_b32_e64 v31, v31, v71, s[4:5]
	v_cndmask_b32_e64 v30, v30, v70, s[4:5]
	s_and_b64 vcc, exec, s[6:7]
	s_mov_b64 s[86:87], -1
	s_cbranch_vccnz .LBB0_601
	v_lshl_add_u64 v[64:65], s[30:31], 0, v[52:53]
	s_lshl_b32 s24, s50, 8
	v_lshl_add_u64 v[64:65], v[64:65], 0, s[24:25]
	v_lshl_add_u64 v[64:65], v[64:65], 0, v[162:163]
	s_andn2_b64 vcc, exec, s[64:65]
	v_cvt_pk_bf16_f32 v70, v30, v31
	v_cvt_pk_bf16_f32 v71, v32, v33
	v_cvt_pk_bf16_f32 v72, v26, v27
	v_cvt_pk_bf16_f32 v73, v28, v29
	global_store_dwordx4 v[64:65], v[70:73], off sc1
	s_cbranch_vccnz .LBB0_600
	s_lshl_b32 s86, s89, 1
	s_ashr_i32 s87, s86, 31
	s_lshl_b32 s24, s50, 7
	s_lshl_b64 s[86:87], s[86:87], 19
	s_add_u32 s86, s36, s86
	s_addc_u32 s87, s37, s87
	v_lshlrev_b32_e32 v64, 2, v68
	v_mov_b32_e32 v65, v163
	v_lshl_add_u64 v[64:65], s[86:87], 0, v[64:65]
	v_lshl_add_u64 v[64:65], s[24:25], 2, v[64:65]
	v_lshlrev_b32_e32 v70, 2, v166
	v_mov_b32_e32 v71, v163
	v_lshl_add_u64 v[64:65], v[64:65], 0, v[70:71]
	global_store_dwordx4 v[64:65], v[30:33], off sc1
	global_store_dwordx4 v[64:65], v[26:29], off offset:128 sc1

.LBB0_601:
	s_andn2_b64 vcc, exec, s[86:87]
	s_cbranch_vccnz .LBB0_603
	v_cvt_pk_bf16_f32 v30, v30, v31
	v_cvt_pk_bf16_f32 v31, v32, v33
	v_cvt_pk_bf16_f32 v32, v26, v27
	v_lshl_add_u64 v[26:27], s[28:29], 0, v[56:57]
	v_lshl_add_u64 v[26:27], s[62:63], 1, v[26:27]
	v_lshl_add_u64 v[26:27], v[26:27], 0, v[162:163]
	v_cvt_pk_bf16_f32 v33, v28, v29
	global_store_dwordx4 v[26:27], v[30:33], off sc1
.LBB0_603:
	v_mov_b32_e32 v63, v62
	v_mov_b32_e32 v26, v62
	v_mov_b32_e32 v27, v62
	v_pk_fma_f32 v[24:25], v[24:25], v[26:27], v[40:41]
	v_pk_fma_f32 v[22:23], v[22:23], v[62:63], v[38:39]
	v_pk_fma_f32 v[20:21], v[20:21], v[26:27], v[36:37]
	v_pk_fma_f32 v[18:19], v[18:19], v[62:63], v[34:35]
	s_and_b64 vcc, exec, s[10:11]
	s_mov_b64 s[86:87], -1
	s_cbranch_vccnz .LBB0_607
	s_add_i32 s24, s62, 0xfffff680
	v_lshl_add_u64 v[30:31], s[24:25], 1, v[66:67]
	v_lshl_add_u64 v[30:31], v[30:31], 0, v[162:163]
	s_andn2_b64 vcc, exec, s[64:65]
	v_cvt_pk_bf16_f32 v26, v22, v23
	v_cvt_pk_bf16_f32 v27, v24, v25
	v_cvt_pk_bf16_f32 v28, v18, v19
	v_cvt_pk_bf16_f32 v29, v20, v21
	global_store_dwordx4 v[30:31], v[26:29], off sc1
	s_cbranch_vccnz .LBB0_606
	s_lshl_b32 s86, s89, 1
	s_ashr_i32 s87, s86, 31
	s_lshl_b64 s[86:87], s[86:87], 19
	s_add_u32 s86, s38, s86
	s_addc_u32 s87, s39, s87
	v_lshlrev_b32_e32 v26, 2, v68
	v_mov_b32_e32 v27, v163
	v_lshl_add_u64 v[26:27], s[86:87], 0, v[26:27]
	v_lshl_add_u64 v[26:27], s[24:25], 2, v[26:27]
	v_mov_b32_e32 v183, v163
	v_lshl_add_u64 v[26:27], v[26:27], 0, v[182:183]
	global_store_dwordx4 v[26:27], v[22:25], off sc1
	global_store_dwordx4 v[26:27], v[18:21], off offset:16 sc1

.LBB0_607:
	s_andn2_b64 vcc, exec, s[86:87]
	s_cbranch_vccnz .LBB0_614
	v_pk_mul_f32 v[26:27], v[20:21], v[58:59]
	v_pk_mul_f32 v[28:29], v[18:19], v[60:61]
	v_pk_mul_f32 v[30:31], v[20:21], v[50:51]
	v_pk_mul_f32 v[32:33], v[18:19], v[54:55]
	v_pk_fma_f32 v[26:27], v[24:25], v[50:51], v[26:27] neg_lo:[0,0,1] neg_hi:[0,0,1]
	v_pk_fma_f32 v[28:29], v[22:23], v[54:55], v[28:29] neg_lo:[0,0,1] neg_hi:[0,0,1]
	v_pk_fma_f32 v[30:31], v[24:25], v[58:59], v[30:31]
	v_pk_fma_f32 v[32:33], v[22:23], v[60:61], v[32:33]
	v_cndmask_b32_e64 v21, v21, v31, s[4:5]
	v_cndmask_b32_e64 v20, v20, v30, s[4:5]
	v_cndmask_b32_e64 v19, v19, v33, s[4:5]
	v_cndmask_b32_e64 v18, v18, v32, s[4:5]
	v_cndmask_b32_e64 v25, v25, v27, s[4:5]
	v_cndmask_b32_e64 v24, v24, v26, s[4:5]
	v_cndmask_b32_e64 v23, v23, v29, s[4:5]
	v_cndmask_b32_e64 v22, v22, v28, s[4:5]
	s_and_b64 vcc, exec, s[6:7]
	s_mov_b64 s[86:87], -1
	s_cbranch_vccnz .LBB0_612
	v_lshl_add_u64 v[30:31], s[30:31], 0, v[52:53]
	s_add_i32 s24, s62, 0xfffff880
	v_lshl_add_u64 v[30:31], s[24:25], 1, v[30:31]
	v_lshl_add_u64 v[30:31], v[30:31], 0, v[162:163]
	s_andn2_b64 vcc, exec, s[64:65]
	v_cvt_pk_bf16_f32 v26, v22, v23
	v_cvt_pk_bf16_f32 v27, v24, v25
	v_cvt_pk_bf16_f32 v28, v18, v19
	v_cvt_pk_bf16_f32 v29, v20, v21
	global_store_dwordx4 v[30:31], v[26:29], off sc1
	s_cbranch_vccnz .LBB0_611
	s_lshl_b32 s86, s89, 1
	s_ashr_i32 s87, s86, 31
	s_lshl_b64 s[86:87], s[86:87], 19
	s_add_u32 s86, s36, s86
	s_addc_u32 s87, s37, s87
	v_lshlrev_b32_e32 v26, 2, v68
	v_mov_b32_e32 v27, v163
	v_lshl_add_u64 v[26:27], s[86:87], 0, v[26:27]
	v_lshl_add_u64 v[26:27], s[24:25], 2, v[26:27]
	v_lshlrev_b32_e32 v28, 2, v166
	v_mov_b32_e32 v29, v163
	v_lshl_add_u64 v[26:27], v[26:27], 0, v[28:29]
	global_store_dwordx4 v[26:27], v[22:25], off sc1
	global_store_dwordx4 v[26:27], v[18:21], off offset:128 sc1

.LBB0_612:
	s_andn2_b64 vcc, exec, s[86:87]
	s_cbranch_vccnz .LBB0_614
	v_cvt_pk_bf16_f32 v22, v22, v23
	v_cvt_pk_bf16_f32 v23, v24, v25
	v_cvt_pk_bf16_f32 v24, v18, v19
	v_lshl_add_u64 v[18:19], s[28:29], 0, v[56:57]
	v_lshl_add_u64 v[18:19], s[62:63], 1, v[18:19]
	v_lshl_add_u64 v[18:19], v[18:19], 0, v[162:163]
	v_cvt_pk_bf16_f32 v25, v20, v21
	global_store_dwordx4 v[18:19], v[22:25], off offset:256 sc1

.LBB0_621:
	v_lshlrev_b64 v[20:21], 10, v[32:33]
	v_lshlrev_b32_e32 v24, 9, v32
	v_and_b32_e32 v50, 0x1fe00, v24
	s_waitcnt lgkmcnt(0)
	v_pk_fma_f32 v[16:17], v[16:17], v[30:31], v[48:49] op_sel_hi:[1,0,1]
	v_pk_fma_f32 v[14:15], v[14:15], v[30:31], v[46:47] op_sel_hi:[1,0,1]
	v_pk_fma_f32 v[12:13], v[12:13], v[30:31], v[44:45] op_sel_hi:[1,0,1]
	v_pk_fma_f32 v[10:11], v[10:11], v[30:31], v[42:43] op_sel_hi:[1,0,1]
	s_mov_b64 s[8:9], -1
	s_and_b64 vcc, exec, s[10:11]
	v_lshl_add_u64 v[42:43], s[34:35], 0, v[20:21]
	s_cbranch_vccnz .LBB0_625
	s_lshl_b32 s24, s51, 7
	v_lshl_add_u64 v[24:25], s[24:25], 1, v[42:43]
	v_lshl_add_u64 v[24:25], v[24:25], 0, v[162:163]
	s_andn2_b64 vcc, exec, s[64:65]
	v_cvt_pk_bf16_f32 v44, v14, v15
	v_cvt_pk_bf16_f32 v45, v16, v17
	v_cvt_pk_bf16_f32 v46, v10, v11
	v_cvt_pk_bf16_f32 v47, v12, v13
	global_store_dwordx4 v[24:25], v[44:47], off sc1
	s_cbranch_vccnz .LBB0_624
	s_lshl_b32 s8, s89, 1
	s_ashr_i32 s9, s8, 31
	s_lshl_b64 s[8:9], s[8:9], 19
	s_add_u32 s8, s38, s8
	s_addc_u32 s9, s39, s9
	v_lshlrev_b32_e32 v24, 2, v50
	v_mov_b32_e32 v25, v163
	v_lshl_add_u64 v[24:25], s[8:9], 0, v[24:25]
	v_lshl_add_u64 v[24:25], s[24:25], 2, v[24:25]
	v_mov_b32_e32 v183, v163
	v_lshl_add_u64 v[24:25], v[24:25], 0, v[182:183]
	global_store_dwordx4 v[24:25], v[14:17], off sc1
	global_store_dwordx4 v[24:25], v[10:13], off offset:16 sc1

.LBB0_625:
	s_andn2_b64 vcc, exec, s[8:9]
	v_lshlrev_b64 v[24:25], 12, v[32:33]
	s_cbranch_vccnz .LBB0_632
	v_pk_mul_f32 v[32:33], v[12:13], v[26:27]
	v_pk_mul_f32 v[44:45], v[10:11], v[28:29]
	v_pk_mul_f32 v[46:47], v[12:13], v[18:19]
	v_pk_mul_f32 v[48:49], v[10:11], v[22:23]
	v_pk_fma_f32 v[32:33], v[16:17], v[18:19], v[32:33] neg_lo:[0,0,1] neg_hi:[0,0,1]
	v_pk_fma_f32 v[44:45], v[14:15], v[22:23], v[44:45] neg_lo:[0,0,1] neg_hi:[0,0,1]
	v_pk_fma_f32 v[46:47], v[16:17], v[26:27], v[46:47]
	v_pk_fma_f32 v[48:49], v[14:15], v[28:29], v[48:49]
	v_cndmask_b32_e64 v13, v13, v47, s[4:5]
	v_cndmask_b32_e64 v12, v12, v46, s[4:5]
	v_cndmask_b32_e64 v11, v11, v49, s[4:5]
	v_cndmask_b32_e64 v10, v10, v48, s[4:5]
	v_cndmask_b32_e64 v17, v17, v33, s[4:5]
	v_cndmask_b32_e64 v16, v16, v32, s[4:5]
	v_cndmask_b32_e64 v15, v15, v45, s[4:5]
	v_cndmask_b32_e64 v14, v14, v44, s[4:5]
	s_and_b64 vcc, exec, s[6:7]
	s_mov_b64 s[8:9], -1
	s_cbranch_vccnz .LBB0_630
	v_lshl_add_u64 v[32:33], s[30:31], 0, v[20:21]
	s_lshl_b32 s24, s50, 8
	v_lshl_add_u64 v[32:33], v[32:33], 0, s[24:25]
	v_lshl_add_u64 v[32:33], v[32:33], 0, v[162:163]
	s_andn2_b64 vcc, exec, s[64:65]
	v_cvt_pk_bf16_f32 v44, v14, v15
	v_cvt_pk_bf16_f32 v45, v16, v17
	v_cvt_pk_bf16_f32 v46, v10, v11
	v_cvt_pk_bf16_f32 v47, v12, v13
	global_store_dwordx4 v[32:33], v[44:47], off sc1
	s_cbranch_vccnz .LBB0_629
	s_lshl_b32 s8, s89, 1
	s_ashr_i32 s9, s8, 31
	s_lshl_b32 s24, s50, 7
	s_lshl_b64 s[8:9], s[8:9], 19
	s_add_u32 s8, s36, s8
	s_addc_u32 s9, s37, s9
	v_lshlrev_b32_e32 v32, 2, v50
	v_mov_b32_e32 v33, v163
	v_lshl_add_u64 v[32:33], s[8:9], 0, v[32:33]
	v_lshl_add_u64 v[32:33], s[24:25], 2, v[32:33]
	v_lshlrev_b32_e32 v44, 2, v166
	v_mov_b32_e32 v45, v163
	v_lshl_add_u64 v[32:33], v[32:33], 0, v[44:45]
	global_store_dwordx4 v[32:33], v[14:17], off sc1
	global_store_dwordx4 v[32:33], v[10:13], off offset:128 sc1

.LBB0_630:
	s_andn2_b64 vcc, exec, s[8:9]
	s_cbranch_vccnz .LBB0_632
	v_cvt_pk_bf16_f32 v14, v14, v15
	v_cvt_pk_bf16_f32 v15, v16, v17
	v_cvt_pk_bf16_f32 v16, v10, v11
	v_lshl_add_u64 v[10:11], s[28:29], 0, v[24:25]
	v_lshl_add_u64 v[10:11], s[62:63], 1, v[10:11]
	v_lshl_add_u64 v[10:11], v[10:11], 0, v[162:163]
	v_cvt_pk_bf16_f32 v17, v12, v13
	global_store_dwordx4 v[10:11], v[14:17], off sc1
.LBB0_632:
	v_mov_b32_e32 v31, v30
	v_mov_b32_e32 v10, v30
	v_mov_b32_e32 v11, v30
	v_pk_fma_f32 v[8:9], v[8:9], v[10:11], v[40:41]
	v_pk_fma_f32 v[6:7], v[6:7], v[30:31], v[38:39]
	v_pk_fma_f32 v[4:5], v[4:5], v[10:11], v[36:37]
	v_pk_fma_f32 v[2:3], v[2:3], v[30:31], v[34:35]
	s_and_b64 vcc, exec, s[10:11]
	s_mov_b64 s[8:9], -1
	s_cbranch_vccnz .LBB0_636
	s_add_i32 s24, s62, 0xfffff680
	v_lshl_add_u64 v[14:15], s[24:25], 1, v[42:43]
	v_lshl_add_u64 v[14:15], v[14:15], 0, v[162:163]
	s_andn2_b64 vcc, exec, s[64:65]
	v_cvt_pk_bf16_f32 v10, v6, v7
	v_cvt_pk_bf16_f32 v11, v8, v9
	v_cvt_pk_bf16_f32 v12, v2, v3
	v_cvt_pk_bf16_f32 v13, v4, v5
	global_store_dwordx4 v[14:15], v[10:13], off sc1
	s_cbranch_vccnz .LBB0_635
	s_lshl_b32 s8, s89, 1
	s_ashr_i32 s9, s8, 31
	s_lshl_b64 s[8:9], s[8:9], 19
	s_add_u32 s8, s38, s8
	s_addc_u32 s9, s39, s9
	v_lshlrev_b32_e32 v10, 2, v50
	v_mov_b32_e32 v11, v163
	v_lshl_add_u64 v[10:11], s[8:9], 0, v[10:11]
	v_lshl_add_u64 v[10:11], s[24:25], 2, v[10:11]
	v_mov_b32_e32 v183, v163
	v_lshl_add_u64 v[10:11], v[10:11], 0, v[182:183]
	global_store_dwordx4 v[10:11], v[6:9], off sc1
	global_store_dwordx4 v[10:11], v[2:5], off offset:16 sc1

.LBB0_636:
	s_andn2_b64 vcc, exec, s[8:9]
	s_cbranch_vccnz .LBB0_643
	v_pk_mul_f32 v[10:11], v[4:5], v[26:27]
	v_pk_mul_f32 v[12:13], v[2:3], v[28:29]
	v_pk_mul_f32 v[14:15], v[4:5], v[18:19]
	v_pk_mul_f32 v[16:17], v[2:3], v[22:23]
	v_pk_fma_f32 v[10:11], v[8:9], v[18:19], v[10:11] neg_lo:[0,0,1] neg_hi:[0,0,1]
	v_pk_fma_f32 v[12:13], v[6:7], v[22:23], v[12:13] neg_lo:[0,0,1] neg_hi:[0,0,1]
	v_pk_fma_f32 v[14:15], v[8:9], v[26:27], v[14:15]
	v_pk_fma_f32 v[16:17], v[6:7], v[28:29], v[16:17]
	v_cndmask_b32_e64 v5, v5, v15, s[4:5]
	v_cndmask_b32_e64 v4, v4, v14, s[4:5]
	v_cndmask_b32_e64 v3, v3, v17, s[4:5]
	v_cndmask_b32_e64 v2, v2, v16, s[4:5]
	v_cndmask_b32_e64 v9, v9, v11, s[4:5]
	v_cndmask_b32_e64 v8, v8, v10, s[4:5]
	v_cndmask_b32_e64 v7, v7, v13, s[4:5]
	v_cndmask_b32_e64 v6, v6, v12, s[4:5]
	s_and_b64 vcc, exec, s[6:7]
	s_mov_b64 s[4:5], -1
	s_cbranch_vccnz .LBB0_641
	v_lshl_add_u64 v[14:15], s[30:31], 0, v[20:21]
	s_add_i32 s24, s62, 0xfffff880
	v_lshl_add_u64 v[14:15], s[24:25], 1, v[14:15]
	v_lshl_add_u64 v[14:15], v[14:15], 0, v[162:163]
	s_andn2_b64 vcc, exec, s[64:65]
	v_cvt_pk_bf16_f32 v10, v6, v7
	v_cvt_pk_bf16_f32 v11, v8, v9
	v_cvt_pk_bf16_f32 v12, v2, v3
	v_cvt_pk_bf16_f32 v13, v4, v5
	global_store_dwordx4 v[14:15], v[10:13], off sc1
	s_cbranch_vccnz .LBB0_640
	s_lshl_b32 s4, s89, 1
	s_ashr_i32 s5, s4, 31
	s_lshl_b64 s[4:5], s[4:5], 19
	s_add_u32 s4, s36, s4
	s_addc_u32 s5, s37, s5
	v_lshlrev_b32_e32 v10, 2, v50
	v_mov_b32_e32 v11, v163
	v_lshl_add_u64 v[10:11], s[4:5], 0, v[10:11]
	v_lshl_add_u64 v[10:11], s[24:25], 2, v[10:11]
	v_lshlrev_b32_e32 v12, 2, v166
	v_mov_b32_e32 v13, v163
	v_lshl_add_u64 v[10:11], v[10:11], 0, v[12:13]
	global_store_dwordx4 v[10:11], v[6:9], off sc1
	global_store_dwordx4 v[10:11], v[2:5], off offset:128 sc1

.LBB0_641:
	s_andn2_b64 vcc, exec, s[4:5]
	s_cbranch_vccnz .LBB0_643
	v_cvt_pk_bf16_f32 v6, v6, v7
	v_cvt_pk_bf16_f32 v7, v8, v9
	v_cvt_pk_bf16_f32 v8, v2, v3
	v_lshl_add_u64 v[2:3], s[28:29], 0, v[24:25]
	v_lshl_add_u64 v[2:3], s[62:63], 1, v[2:3]
	v_lshl_add_u64 v[2:3], v[2:3], 0, v[162:163]
	v_cvt_pk_bf16_f32 v9, v4, v5
	global_store_dwordx4 v[2:3], v[6:9], off offset:256 sc1

.LBB0_899:
	s_lshr_b32 s16, s94, 4
	s_add_i32 s16, s16, -1
	s_cmp_gt_i32 s94, 31
	s_cselect_b32 s16, s16, 0
	v_lshl_or_b32 v70, s12, 8, v228
	s_mul_i32 s47, s16, 0xc000
	s_mul_hi_i32 s46, s16, 0xc000
	s_add_u32 s16, s91, s47
	v_ashrrev_i32_e32 v71, 31, v70
	s_addc_u32 s17, s92, s46
	v_lshlrev_b64 v[108:109], 2, v[70:71]
	v_lshl_add_u64 v[26:27], s[16:17], 0, v[108:109]
	v_lshl_add_u64 v[28:29], s[24:25], 0, v[108:109]
	s_waitcnt lgkmcnt(0)
	global_load_dwordx4 v[2:5], v[26:27], off offset:16
	global_load_dwordx4 v[6:9], v[26:27], off
	global_load_dwordx4 v[10:13], v[28:29], off offset:16
	global_load_dwordx4 v[14:17], v[28:29], off
	s_add_u32 s16, s88, s47
	v_lshl_add_u64 v[30:31], s[28:29], 0, v[108:109]
	s_addc_u32 s17, s89, s46
	v_lshl_add_u64 v[32:33], s[16:17], 0, v[108:109]
	v_lshl_add_u32 v118, s94, 8, v226
	v_cmp_gt_i32_e32 vcc, s87, v118
	v_ashrrev_i32_e32 v119, 31, v118
	v_or_b32_e32 v34, 16, v118
	v_ashrrev_i32_e32 v35, 31, v34
	s_lshl_b32 s46, s12, 2
	s_ashr_i32 s47, s46, 31
	s_waitcnt vmcnt(0)
	v_pk_mul_f32 v[88:89], v[4:5], v[12:13]
	v_pk_mul_f32 v[76:77], v[8:9], v[16:17]
	v_pk_mul_f32 v[78:79], v[6:7], v[14:15]
	global_load_dwordx4 v[6:9], v[30:31], off offset:16
	global_load_dwordx4 v[14:17], v[30:31], off
	global_load_dwordx4 v[18:21], v[32:33], off offset:16
	global_load_dwordx4 v[22:25], v[32:33], off
	v_pk_mul_f32 v[90:91], v[2:3], v[10:11]
	s_waitcnt vmcnt(0)
	v_pk_add_f32 v[2:3], v[20:21], 1.0 op_sel_hi:[1,0]
	v_pk_add_f32 v[24:25], v[24:25], 1.0 op_sel_hi:[1,0]
	v_pk_add_f32 v[22:23], v[22:23], 1.0 op_sel_hi:[1,0]
	v_pk_add_f32 v[4:5], v[18:19], 1.0 op_sel_hi:[1,0]
	v_pk_mul_f32 v[80:81], v[16:17], v[24:25]
	v_pk_mul_f32 v[82:83], v[14:15], v[22:23]
	v_pk_mul_f32 v[84:85], v[8:9], v[2:3]
	v_pk_mul_f32 v[86:87], v[6:7], v[4:5]
	global_load_dwordx4 v[2:5], v[26:27], off offset:528
	global_load_dwordx4 v[6:9], v[26:27], off offset:512
	global_load_dwordx4 v[10:13], v[28:29], off offset:528
	global_load_dwordx4 v[14:17], v[28:29], off offset:512
	s_waitcnt vmcnt(0)
	v_pk_mul_f32 v[72:73], v[2:3], v[10:11]
	v_pk_mul_f32 v[66:67], v[8:9], v[16:17]
	v_pk_mul_f32 v[68:69], v[6:7], v[14:15]
	global_load_dwordx4 v[6:9], v[30:31], off offset:528
	global_load_dwordx4 v[14:17], v[30:31], off offset:512
	global_load_dwordx4 v[18:21], v[32:33], off offset:528
	global_load_dwordx4 v[22:25], v[32:33], off offset:512
	v_pk_mul_f32 v[74:75], v[4:5], v[12:13]
	s_waitcnt vmcnt(0)
	v_pk_add_f32 v[2:3], v[20:21], 1.0 op_sel_hi:[1,0]
	v_pk_add_f32 v[4:5], v[18:19], 1.0 op_sel_hi:[1,0]
	v_pk_mul_f32 v[62:63], v[8:9], v[2:3]
	v_add_u32_e32 v2, 0xffffe000, v118
	v_pk_mul_f32 v[64:65], v[6:7], v[4:5]
	v_cndmask_b32_e32 v3, 0, v119, vcc
	v_cndmask_b32_e32 v2, v2, v118, vcc
	v_mov_b32_e32 v6, s59
	v_mov_b32_e32 v7, s57
	v_mov_b32_e32 v8, s58
	v_mov_b32_e32 v9, s56
	v_cndmask_b32_e32 v5, v6, v7, vcc
	v_cndmask_b32_e32 v4, v8, v9, vcc
	v_lshlrev_b64 v[2:3], 13, v[2:3]
	v_lshl_add_u64 v[2:3], v[4:5], 0, v[2:3]
	v_pk_add_f32 v[24:25], v[24:25], 1.0 op_sel_hi:[1,0]
	v_pk_add_f32 v[22:23], v[22:23], 1.0 op_sel_hi:[1,0]
	v_lshl_add_u64 v[2:3], v[2:3], 0, v[108:109]
	v_pk_mul_f32 v[58:59], v[16:17], v[24:25]
	v_pk_mul_f32 v[60:61], v[14:15], v[22:23]
	global_load_dwordx4 v[26:29], v[2:3], off offset:16 nt
	global_load_dwordx4 v[30:33], v[2:3], off nt
	global_load_dwordx4 v[18:21], v[2:3], off offset:528 nt
	global_load_dwordx4 v[22:25], v[2:3], off offset:512 nt
	v_cmp_gt_i32_e32 vcc, s87, v34
	v_add_u32_e32 v2, 0xffffe010, v118
	s_nop 0
	v_cndmask_b32_e32 v3, 0, v35, vcc
	v_cndmask_b32_e32 v2, v2, v34, vcc
	v_cndmask_b32_e32 v5, v6, v7, vcc
	v_cndmask_b32_e32 v4, v8, v9, vcc
	v_lshlrev_b64 v[2:3], 13, v[2:3]
	v_lshl_add_u64 v[2:3], v[4:5], 0, v[2:3]
	v_lshl_add_u64 v[6:7], v[2:3], 0, v[108:109]
	global_load_dwordx4 v[10:13], v[6:7], off offset:16 nt
	global_load_dwordx4 v[14:17], v[6:7], off nt
	global_load_dwordx4 v[2:5], v[6:7], off offset:528 nt
	s_nop 0
	global_load_dwordx4 v[6:9], v[6:7], off offset:512 nt
	v_lshl_add_u64 v[176:177], v[118:119], 2, s[22:23]
	global_load_dword v38, v[176:177], off
	v_lshlrev_b64 v[36:37], 13, v[118:119]
	v_lshl_add_u64 v[36:37], s[20:21], 0, v[36:37]
	v_lshl_add_u64 v[36:37], v[36:37], 0, v[108:109]
	s_waitcnt vmcnt(0)
	v_pk_mul_f32 v[40:41], v[38:39], v[220:221] op_sel_hi:[0,1]
	v_pk_mul_f32 v[218:219], v[38:39], v[218:219] op_sel_hi:[0,1]
	v_pk_fma_f32 v[32:33], v[76:77], v[218:219], v[32:33]
	v_pk_fma_f32 v[30:31], v[78:79], v[40:41], v[30:31]
	v_pk_mul_f32 v[220:221], v[38:39], v[224:225] op_sel_hi:[0,1]
	v_pk_mul_f32 v[222:223], v[38:39], v[222:223] op_sel_hi:[0,1]
	v_mul_f32_e32 v39, v31, v31
	v_mul_f32_e32 v40, v33, v33
	v_pk_fma_f32 v[26:27], v[90:91], v[220:221], v[26:27]
	v_fmac_f32_e32 v39, v30, v30
	v_fmac_f32_e32 v40, v32, v32
	v_add_f32_e32 v39, v39, v40
	v_mul_f32_e32 v40, v27, v27
	v_pk_fma_f32 v[28:29], v[88:89], v[222:223], v[28:29]
	v_fmac_f32_e32 v40, v26, v26
	v_add_f32_e32 v39, v40, v39
	v_mul_f32_e32 v40, v29, v29
	global_store_dwordx4 v[36:37], v[30:33], off nt
	global_store_dwordx4 v[36:37], v[26:29], off offset:16 nt
	v_fmac_f32_e32 v40, v28, v28
	v_pk_mul_f32 v[30:31], v[82:83], v[30:31]
	v_add_f32_e32 v218, v40, v39
	v_pk_mul_f32 v[40:41], v[84:85], v[28:29]
	v_pk_mul_f32 v[28:29], v[86:87], v[26:27]
	v_cvt_pk_bf16_f32 v26, v30, v31
	v_lshlrev_b64 v[30:31], 12, v[118:119]
	v_lshl_add_u64 v[30:31], s[26:27], 0, v[30:31]
	v_pk_mul_f32 v[32:33], v[80:81], v[32:33]
	v_lshl_add_u64 v[30:31], v[70:71], 1, v[30:31]
	v_cvt_pk_bf16_f32 v27, v32, v33
	v_cvt_pk_bf16_f32 v28, v28, v29
	v_cvt_pk_bf16_f32 v29, v40, v41
	global_store_dwordx4 v[30:31], v[26:29], off sc1
	v_lshlrev_b32_e32 v32, 16, v26
	s_nop 0
	v_and_b32_e32 v26, 0xffff0000, v26
	v_max3_f32 v26, |v32|, 0, |v26|
	v_lshlrev_b32_e32 v32, 16, v27
	v_and_b32_e32 v27, 0xffff0000, v27
	v_max3_f32 v26, v26, |v32|, |v27|
	v_lshlrev_b32_e32 v27, 16, v28
	v_and_b32_e32 v28, 0xffff0000, v28
	v_max3_f32 v26, v26, |v27|, |v28|
	v_lshlrev_b32_e32 v27, 16, v29
	v_and_b32_e32 v28, 0xffff0000, v29
	v_max3_f32 v40, v26, |v27|, |v28|
	v_pk_mul_f32 v[26:27], v[38:39], v[212:213] op_sel_hi:[0,1]
	v_pk_mul_f32 v[28:29], v[38:39], v[210:211] op_sel_hi:[0,1]
	v_pk_mul_f32 v[32:33], v[38:39], v[216:217] op_sel_hi:[0,1]
	v_pk_fma_f32 v[24:25], v[66:67], v[28:29], v[24:25]
	v_pk_fma_f32 v[22:23], v[68:69], v[26:27], v[22:23]
	v_pk_fma_f32 v[26:27], v[72:73], v[32:33], v[18:19]
	v_mul_f32_e32 v18, v23, v23
	v_mul_f32_e32 v19, v25, v25
	v_fmac_f32_e32 v18, v22, v22
	v_fmac_f32_e32 v19, v24, v24
	v_pk_mul_f32 v[38:39], v[38:39], v[214:215] op_sel_hi:[0,1]
	v_add_f32_e32 v18, v18, v19
	v_mul_f32_e32 v19, v27, v27
	v_pk_fma_f32 v[28:29], v[74:75], v[38:39], v[20:21]
	v_fmac_f32_e32 v19, v26, v26
	v_add_f32_e32 v18, v19, v18
	v_mul_f32_e32 v19, v29, v29
	v_fmac_f32_e32 v19, v28, v28
	v_pk_mul_f32 v[20:21], v[60:61], v[22:23]
	global_store_dwordx4 v[36:37], v[22:25], off offset:512 nt
	global_store_dwordx4 v[36:37], v[26:29], off offset:528 nt
	v_add_f32_e32 v18, v19, v18
	v_pk_mul_f32 v[22:23], v[64:65], v[26:27]
	v_cvt_pk_bf16_f32 v20, v20, v21
	v_add_f32_e32 v19, v218, v18
	v_pk_mul_f32 v[24:25], v[58:59], v[24:25]
	v_pk_mul_f32 v[28:29], v[62:63], v[28:29]
	v_cvt_pk_bf16_f32 v21, v24, v25
	v_cvt_pk_bf16_f32 v22, v22, v23
	v_lshlrev_b32_e32 v18, 16, v20
	v_cvt_pk_bf16_f32 v23, v28, v29
	global_store_dwordx4 v[30:31], v[20:23], off offset:256 sc1
	s_nop 1
	v_and_b32_e32 v20, 0xffff0000, v20
	v_max3_f32 v18, v40, |v18|, |v20|
	v_lshlrev_b32_e32 v20, 16, v21
	v_and_b32_e32 v21, 0xffff0000, v21
	v_max3_f32 v18, v18, |v20|, |v21|
	v_lshlrev_b32_e32 v20, 16, v22
	v_and_b32_e32 v21, 0xffff0000, v22
	v_max3_f32 v18, v18, |v20|, |v21|
	v_lshlrev_b32_e32 v20, 16, v23
	v_and_b32_e32 v21, 0xffff0000, v23
	v_max3_f32 v18, v18, |v20|, |v21|
	v_and_b32_e32 v21, 64, v230
	v_xor_b32_e32 v20, 16, v230
	v_add_u32_e32 v21, 64, v21
	v_cmp_lt_i32_e32 vcc, v20, v21
	s_nop 1
	v_cndmask_b32_e32 v20, v230, v20, vcc
	v_lshlrev_b32_e32 v212, 2, v20
	ds_bpermute_b32 v20, v212, v19
	s_waitcnt lgkmcnt(0)
	v_add_f32_e32 v19, v19, v20
	v_xor_b32_e32 v20, 32, v230
	v_cmp_lt_i32_e32 vcc, v20, v21
	ds_bpermute_b32 v21, v212, v18
	s_waitcnt lgkmcnt(0)
	v_max_f32_e32 v21, v21, v21
	v_cndmask_b32_e32 v20, v230, v20, vcc
	v_lshlrev_b32_e32 v213, 2, v20
	v_max_f32_e32 v18, v18, v21
	ds_bpermute_b32 v20, v213, v19
	ds_bpermute_b32 v21, v213, v18
	s_and_saveexec_b64 s[50:51], s[0:1]
	s_cbranch_execz .LBB0_901
	s_waitcnt lgkmcnt(0)
	v_max_f32_e32 v21, v21, v21
	v_max_f32_e32 v18, v18, v18
	v_max_f32_e32 v22, v18, v21
	v_add_f32_e32 v23, v19, v20
	v_lshlrev_b64 v[18:19], 7, v[118:119]
	v_lshl_add_u64 v[20:21], s[30:31], 0, v[18:19]
	s_lshl_b64 s[16:17], s[46:47], 2
	v_lshl_add_u64 v[18:19], s[34:35], 0, v[18:19]
	v_lshl_add_u64 v[20:21], v[20:21], 0, s[16:17]
	s_lshl_b32 s12, s93, 2
	v_lshl_add_u64 v[18:19], v[18:19], 0, s[16:17]
	v_lshl_add_u64 v[20:21], v[20:21], 0, s[12:13]
	v_lshl_add_u64 v[18:19], v[18:19], 0, s[12:13]
	global_store_dword v[20:21], v23, off
	global_store_dword v[18:19], v22, off
.LBB0_901:
	s_or_b64 exec, exec, s[50:51]
	v_or_b32_e32 v210, 32, v118
	v_ashrrev_i32_e32 v211, 31, v210
	v_add_u32_e32 v18, 0xffffe020, v118
	v_cmp_gt_i32_e32 vcc, s87, v210
	s_waitcnt lgkmcnt(1)
	v_mov_b32_e32 v20, s59
	s_waitcnt lgkmcnt(0)
	v_mov_b32_e32 v21, s57
	v_cndmask_b32_e32 v19, 0, v211, vcc
	v_cndmask_b32_e32 v18, v18, v210, vcc
	v_cndmask_b32_e32 v21, v20, v21, vcc
	v_mov_b32_e32 v20, s58
	v_mov_b32_e32 v22, s56
	v_cndmask_b32_e32 v20, v20, v22, vcc
	v_lshlrev_b64 v[18:19], 13, v[18:19]
	v_lshl_add_u64 v[18:19], v[20:21], 0, v[18:19]
	v_lshl_add_u64 v[22:23], v[18:19], 0, v[108:109]
	global_load_dwordx4 v[26:29], v[22:23], off offset:16 nt
	global_load_dwordx4 v[30:33], v[22:23], off nt
	global_load_dwordx4 v[18:21], v[22:23], off offset:528 nt
	s_nop 0
	global_load_dwordx4 v[22:25], v[22:23], off offset:512 nt
	v_lshlrev_b64 v[36:37], 13, v[34:35]
	v_lshl_add_u64 v[214:215], s[20:21], 0, v[36:37]
	v_lshl_add_u64 v[36:37], v[34:35], 2, s[22:23]
	global_load_dword v36, v[36:37], off
	s_waitcnt vmcnt(0)
	v_pk_mul_f32 v[38:39], v[36:37], v[204:205] op_sel_hi:[0,1]
	v_pk_mul_f32 v[40:41], v[36:37], v[202:203] op_sel_hi:[0,1]
	v_pk_mul_f32 v[202:203], v[36:37], v[208:209] op_sel_hi:[0,1]
	v_pk_fma_f32 v[16:17], v[76:77], v[40:41], v[16:17]
	v_pk_fma_f32 v[14:15], v[78:79], v[38:39], v[14:15]
	v_pk_fma_f32 v[38:39], v[90:91], v[202:203], v[10:11]
	v_mul_f32_e32 v10, v15, v15
	v_mul_f32_e32 v11, v17, v17
	v_fmac_f32_e32 v10, v14, v14
	v_fmac_f32_e32 v11, v16, v16
	v_pk_mul_f32 v[204:205], v[36:37], v[206:207] op_sel_hi:[0,1]
	v_add_f32_e32 v10, v10, v11
	v_mul_f32_e32 v11, v39, v39
	v_pk_fma_f32 v[40:41], v[88:89], v[204:205], v[12:13]
	v_fmac_f32_e32 v11, v38, v38
	v_add_f32_e32 v10, v11, v10
	v_mul_f32_e32 v11, v41, v41
	v_lshl_add_u64 v[12:13], v[214:215], 0, v[108:109]
	v_fmac_f32_e32 v11, v40, v40
	global_store_dwordx4 v[12:13], v[14:17], off nt
	global_store_dwordx4 v[12:13], v[38:41], off offset:16 nt
	v_add_f32_e32 v119, v11, v10
	v_pk_mul_f32 v[10:11], v[80:81], v[16:17]
	v_pk_mul_f32 v[14:15], v[82:83], v[14:15]
	v_pk_mul_f32 v[16:17], v[86:87], v[38:39]
	v_cvt_pk_bf16_f32 v14, v14, v15
	v_cvt_pk_bf16_f32 v15, v10, v11
	v_lshlrev_b64 v[10:11], 12, v[34:35]
	v_lshl_add_u64 v[10:11], s[26:27], 0, v[10:11]
	v_lshl_add_u64 v[10:11], v[70:71], 1, v[10:11]
	v_pk_mul_f32 v[40:41], v[84:85], v[40:41]
	v_cvt_pk_bf16_f32 v16, v16, v17
	v_lshlrev_b32_e32 v37, 16, v14
	v_cvt_pk_bf16_f32 v17, v40, v41
	global_store_dwordx4 v[10:11], v[14:17], off sc1
	s_nop 1
	v_and_b32_e32 v14, 0xffff0000, v14
	v_max3_f32 v14, |v37|, 0, |v14|
	v_lshlrev_b32_e32 v37, 16, v15
	v_and_b32_e32 v15, 0xffff0000, v15
	v_max3_f32 v14, v14, |v37|, |v15|
	v_lshlrev_b32_e32 v15, 16, v16
	v_and_b32_e32 v16, 0xffff0000, v16
	v_max3_f32 v14, v14, |v15|, |v16|
	v_lshlrev_b32_e32 v15, 16, v17
	v_and_b32_e32 v16, 0xffff0000, v17
	v_max3_f32 v40, v14, |v15|, |v16|
	v_pk_mul_f32 v[14:15], v[36:37], v[198:199] op_sel_hi:[0,1]
	v_pk_mul_f32 v[16:17], v[36:37], v[194:195] op_sel_hi:[0,1]
	v_pk_mul_f32 v[38:39], v[36:37], v[200:201] op_sel_hi:[0,1]
	v_pk_mul_f32 v[36:37], v[36:37], v[196:197] op_sel_hi:[0,1]
	v_pk_fma_f32 v[8:9], v[66:67], v[16:17], v[8:9]
	v_pk_fma_f32 v[6:7], v[68:69], v[14:15], v[6:7]
	v_pk_fma_f32 v[4:5], v[74:75], v[36:37], v[4:5]
	v_pk_fma_f32 v[2:3], v[72:73], v[38:39], v[2:3]
	global_store_dwordx4 v[12:13], v[6:9], off offset:512 nt
	global_store_dwordx4 v[12:13], v[2:5], off offset:528 nt
	v_mul_f32_e32 v12, v7, v7
	v_mul_f32_e32 v13, v9, v9
	v_fmac_f32_e32 v12, v6, v6
	v_fmac_f32_e32 v13, v8, v8
	v_add_f32_e32 v12, v12, v13
	v_mul_f32_e32 v13, v3, v3
	v_fmac_f32_e32 v13, v2, v2
	v_add_f32_e32 v12, v13, v12
	v_mul_f32_e32 v13, v5, v5
	v_fmac_f32_e32 v13, v4, v4
	v_add_f32_e32 v12, v13, v12
	v_add_f32_e32 v14, v119, v12
	v_pk_mul_f32 v[6:7], v[60:61], v[6:7]
	v_pk_mul_f32 v[12:13], v[62:63], v[4:5]
	v_pk_mul_f32 v[4:5], v[64:65], v[2:3]
	v_cvt_pk_bf16_f32 v2, v6, v7
	v_pk_mul_f32 v[8:9], v[58:59], v[8:9]
	v_lshlrev_b32_e32 v6, 16, v2
	v_cvt_pk_bf16_f32 v3, v8, v9
	v_cvt_pk_bf16_f32 v4, v4, v5
	v_cvt_pk_bf16_f32 v5, v12, v13
	global_store_dwordx4 v[10:11], v[2:5], off offset:256 sc1
	s_nop 1
	v_and_b32_e32 v2, 0xffff0000, v2
	v_max3_f32 v2, v40, |v6|, |v2|
	v_lshlrev_b32_e32 v6, 16, v3
	v_and_b32_e32 v3, 0xffff0000, v3
	v_max3_f32 v2, v2, |v6|, |v3|
	v_lshlrev_b32_e32 v3, 16, v4
	v_and_b32_e32 v4, 0xffff0000, v4
	v_max3_f32 v2, v2, |v3|, |v4|
	v_lshlrev_b32_e32 v3, 16, v5
	v_and_b32_e32 v4, 0xffff0000, v5
	v_max3_f32 v4, v2, |v3|, |v4|
	ds_bpermute_b32 v5, v212, v4
	ds_bpermute_b32 v2, v212, v14
	s_waitcnt lgkmcnt(1)
	v_max_f32_e32 v5, v5, v5
	s_waitcnt lgkmcnt(0)
	v_add_f32_e32 v2, v14, v2
	v_max_f32_e32 v4, v4, v5
	ds_bpermute_b32 v3, v213, v2
	ds_bpermute_b32 v5, v213, v4
	s_and_saveexec_b64 s[50:51], s[0:1]
	s_cbranch_execz .LBB0_903
	s_waitcnt lgkmcnt(0)
	v_max_f32_e32 v5, v5, v5
	v_max_f32_e32 v4, v4, v4
	v_add_f32_e32 v7, v2, v3
	v_lshlrev_b64 v[2:3], 7, v[34:35]
	v_max_f32_e32 v6, v4, v5
	v_lshl_add_u64 v[4:5], s[30:31], 0, v[2:3]
	s_lshl_b64 s[16:17], s[46:47], 2
	v_lshl_add_u64 v[2:3], s[34:35], 0, v[2:3]
	v_lshl_add_u64 v[4:5], v[4:5], 0, s[16:17]
	s_lshl_b32 s12, s93, 2
	v_lshl_add_u64 v[2:3], v[2:3], 0, s[16:17]
	v_lshl_add_u64 v[4:5], v[4:5], 0, s[12:13]
	v_lshl_add_u64 v[2:3], v[2:3], 0, s[12:13]
	global_store_dword v[4:5], v7, off
	global_store_dword v[2:3], v6, off
.LBB0_903:
	s_or_b64 exec, exec, s[50:51]
	v_or_b32_e32 v194, 48, v118
	v_ashrrev_i32_e32 v195, 31, v194
	v_add_u32_e32 v2, 0xffffe030, v118
	v_cmp_gt_i32_e32 vcc, s87, v194
	v_mov_b32_e32 v4, s59
	s_waitcnt lgkmcnt(0)
	v_mov_b32_e32 v5, s57
	v_cndmask_b32_e32 v3, 0, v195, vcc
	v_cndmask_b32_e32 v2, v2, v194, vcc
	v_cndmask_b32_e32 v5, v4, v5, vcc
	v_mov_b32_e32 v4, s58
	v_mov_b32_e32 v6, s56
	v_cndmask_b32_e32 v4, v4, v6, vcc
	v_lshlrev_b64 v[2:3], 13, v[2:3]
	v_lshl_add_u64 v[2:3], v[4:5], 0, v[2:3]
	v_lshl_add_u64 v[2:3], v[2:3], 0, v[108:109]
	global_load_dwordx4 v[34:37], v[2:3], off offset:16 nt
	global_load_dwordx4 v[38:41], v[2:3], off nt
	global_load_dwordx4 v[6:9], v[2:3], off offset:528 nt
	global_load_dwordx4 v[14:17], v[2:3], off offset:512 nt
	v_lshl_add_u64 v[4:5], v[210:211], 2, s[22:23]
	global_load_dword v10, v[4:5], off
	v_lshlrev_b64 v[2:3], 13, v[210:211]
	v_lshl_add_u64 v[2:3], s[20:21], 0, v[2:3]
	s_waitcnt vmcnt(0)
	v_pk_mul_f32 v[4:5], v[10:11], v[188:189] op_sel_hi:[0,1]
	v_pk_mul_f32 v[12:13], v[10:11], v[186:187] op_sel_hi:[0,1]
	v_pk_fma_f32 v[32:33], v[76:77], v[12:13], v[32:33]
	v_pk_fma_f32 v[30:31], v[78:79], v[4:5], v[30:31]
	v_pk_mul_f32 v[186:187], v[10:11], v[192:193] op_sel_hi:[0,1]
	v_lshl_add_u64 v[4:5], v[2:3], 0, v[108:109]
	v_mul_f32_e32 v2, v31, v31
	v_mul_f32_e32 v3, v33, v33
	v_pk_fma_f32 v[26:27], v[90:91], v[186:187], v[26:27]
	v_fmac_f32_e32 v2, v30, v30
	v_fmac_f32_e32 v3, v32, v32
	v_pk_mul_f32 v[188:189], v[10:11], v[190:191] op_sel_hi:[0,1]
	v_add_f32_e32 v2, v2, v3
	v_mul_f32_e32 v3, v27, v27
	v_pk_fma_f32 v[28:29], v[88:89], v[188:189], v[28:29]
	v_fmac_f32_e32 v3, v26, v26
	v_add_f32_e32 v2, v3, v2
	v_mul_f32_e32 v3, v29, v29
	v_fmac_f32_e32 v3, v28, v28
	v_pk_mul_f32 v[12:13], v[82:83], v[30:31]
	global_store_dwordx4 v[4:5], v[30:33], off nt
	global_store_dwordx4 v[4:5], v[26:29], off offset:16 nt
	v_add_f32_e32 v119, v3, v2
	v_pk_mul_f32 v[2:3], v[80:81], v[32:33]
	v_pk_mul_f32 v[30:31], v[84:85], v[28:29]
	v_pk_mul_f32 v[28:29], v[86:87], v[26:27]
	v_cvt_pk_bf16_f32 v26, v12, v13
	v_cvt_pk_bf16_f32 v27, v2, v3
	v_lshlrev_b64 v[2:3], 12, v[210:211]
	v_lshlrev_b32_e32 v11, 16, v26
	v_and_b32_e32 v12, 0xffff0000, v26
	v_max3_f32 v11, |v11|, 0, |v12|
	v_lshlrev_b32_e32 v12, 16, v27
	v_and_b32_e32 v13, 0xffff0000, v27
	v_cvt_pk_bf16_f32 v28, v28, v29
	v_lshl_add_u64 v[2:3], s[26:27], 0, v[2:3]
	v_max3_f32 v11, v11, |v12|, |v13|
	v_lshlrev_b32_e32 v12, 16, v28
	v_and_b32_e32 v13, 0xffff0000, v28
	v_cvt_pk_bf16_f32 v29, v30, v31
	v_lshl_add_u64 v[2:3], v[70:71], 1, v[2:3]
	v_max3_f32 v11, v11, |v12|, |v13|
	v_lshlrev_b32_e32 v12, 16, v29
	v_and_b32_e32 v13, 0xffff0000, v29
	global_store_dwordx4 v[2:3], v[26:29], off sc1
	v_max3_f32 v32, v11, |v12|, |v13|
	v_pk_mul_f32 v[12:13], v[10:11], v[178:179] op_sel_hi:[0,1]
	v_pk_mul_f32 v[26:27], v[10:11], v[182:183] op_sel_hi:[0,1]
	v_pk_mul_f32 v[28:29], v[10:11], v[184:185] op_sel_hi:[0,1]
	v_pk_mul_f32 v[30:31], v[10:11], v[180:181] op_sel_hi:[0,1]
	v_pk_fma_f32 v[12:13], v[66:67], v[12:13], v[24:25]
	v_pk_fma_f32 v[10:11], v[68:69], v[26:27], v[22:23]
	v_pk_fma_f32 v[20:21], v[74:75], v[30:31], v[20:21]
	v_pk_fma_f32 v[18:19], v[72:73], v[28:29], v[18:19]
	global_store_dwordx4 v[4:5], v[10:13], off offset:512 nt
	global_store_dwordx4 v[4:5], v[18:21], off offset:528 nt
	v_mul_f32_e32 v4, v11, v11
	v_mul_f32_e32 v5, v13, v13
	v_fmac_f32_e32 v4, v10, v10
	v_fmac_f32_e32 v5, v12, v12
	v_add_f32_e32 v4, v4, v5
	v_mul_f32_e32 v5, v19, v19
	v_fmac_f32_e32 v5, v18, v18
	v_add_f32_e32 v4, v5, v4
	v_mul_f32_e32 v5, v21, v21
	v_fmac_f32_e32 v5, v20, v20
	v_add_f32_e32 v4, v5, v4
	v_add_f32_e32 v22, v119, v4
	v_pk_mul_f32 v[4:5], v[58:59], v[12:13]
	v_pk_mul_f32 v[10:11], v[60:61], v[10:11]
	v_pk_mul_f32 v[12:13], v[64:65], v[18:19]
	v_pk_mul_f32 v[20:21], v[62:63], v[20:21]
	v_cvt_pk_bf16_f32 v10, v10, v11
	v_cvt_pk_bf16_f32 v11, v4, v5
	v_cvt_pk_bf16_f32 v12, v12, v13
	s_nop 0
	v_cvt_pk_bf16_f32 v13, v20, v21
	global_store_dwordx4 v[2:3], v[10:13], off offset:256 sc1
	v_lshlrev_b32_e32 v2, 16, v10
	v_and_b32_e32 v3, 0xffff0000, v10
	v_max3_f32 v2, v32, |v2|, |v3|
	v_lshlrev_b32_e32 v3, 16, v11
	v_and_b32_e32 v4, 0xffff0000, v11
	v_max3_f32 v2, v2, |v3|, |v4|
	v_lshlrev_b32_e32 v3, 16, v12
	v_and_b32_e32 v4, 0xffff0000, v12
	v_max3_f32 v2, v2, |v3|, |v4|
	v_lshlrev_b32_e32 v3, 16, v13
	v_and_b32_e32 v4, 0xffff0000, v13
	v_max3_f32 v4, v2, |v3|, |v4|
	ds_bpermute_b32 v5, v212, v4
	ds_bpermute_b32 v2, v212, v22
	s_waitcnt lgkmcnt(1)
	v_max_f32_e32 v5, v5, v5
	s_waitcnt lgkmcnt(0)
	v_add_f32_e32 v2, v22, v2
	v_max_f32_e32 v4, v4, v5
	ds_bpermute_b32 v3, v213, v2
	ds_bpermute_b32 v5, v213, v4
	s_and_saveexec_b64 s[50:51], s[0:1]
	s_cbranch_execz .LBB0_905
	s_waitcnt lgkmcnt(0)
	v_max_f32_e32 v5, v5, v5
	v_max_f32_e32 v4, v4, v4
	v_add_f32_e32 v11, v2, v3
	v_lshlrev_b64 v[2:3], 7, v[210:211]
	v_max_f32_e32 v10, v4, v5
	v_lshl_add_u64 v[4:5], s[30:31], 0, v[2:3]
	s_lshl_b64 s[16:17], s[46:47], 2
	v_lshl_add_u64 v[2:3], s[34:35], 0, v[2:3]
	v_lshl_add_u64 v[4:5], v[4:5], 0, s[16:17]
	s_lshl_b32 s12, s93, 2
	v_lshl_add_u64 v[2:3], v[2:3], 0, s[16:17]
	v_lshl_add_u64 v[4:5], v[4:5], 0, s[12:13]
	v_lshl_add_u64 v[2:3], v[2:3], 0, s[12:13]
	global_store_dword v[4:5], v11, off
	global_store_dword v[2:3], v10, off
.LBB0_905:
	s_or_b64 exec, exec, s[50:51]
	v_add_u32_e32 v178, 0x80, v118
	s_movk_i32 s12, 0x1f80
	v_ashrrev_i32_e32 v179, 31, v178
	v_add_u32_e32 v2, 0xffffe080, v118
	v_cmp_gt_i32_e32 vcc, s12, v118
	v_mov_b32_e32 v4, s59
	s_waitcnt lgkmcnt(0)
	v_mov_b32_e32 v5, s57
	v_cndmask_b32_e32 v3, 0, v179, vcc
	v_cndmask_b32_e32 v2, v2, v178, vcc
	v_cndmask_b32_e32 v5, v4, v5, vcc
	v_mov_b32_e32 v4, s58
	v_mov_b32_e32 v10, s56
	v_cndmask_b32_e32 v4, v4, v10, vcc
	v_lshlrev_b64 v[2:3], 13, v[2:3]
	v_lshl_add_u64 v[2:3], v[4:5], 0, v[2:3]
	v_lshl_add_u64 v[10:11], v[2:3], 0, v[108:109]
	global_load_dwordx4 v[18:21], v[10:11], off offset:16 nt
	global_load_dwordx4 v[22:25], v[10:11], off nt
	global_load_dwordx4 v[2:5], v[10:11], off offset:528 nt
	s_nop 0
	global_load_dwordx4 v[10:13], v[10:11], off offset:512 nt
	v_lshl_add_u64 v[28:29], v[194:195], 2, s[22:23]
	global_load_dword v30, v[28:29], off
	v_lshlrev_b64 v[26:27], 13, v[194:195]
	v_lshl_add_u64 v[26:27], s[20:21], 0, v[26:27]
	s_waitcnt vmcnt(0)
	v_pk_mul_f32 v[28:29], v[30:31], v[170:171] op_sel_hi:[0,1]
	v_pk_mul_f32 v[32:33], v[30:31], v[168:169] op_sel_hi:[0,1]
	v_pk_fma_f32 v[40:41], v[76:77], v[32:33], v[40:41]
	v_pk_fma_f32 v[38:39], v[78:79], v[28:29], v[38:39]
	v_pk_mul_f32 v[168:169], v[30:31], v[174:175] op_sel_hi:[0,1]
	v_lshl_add_u64 v[28:29], v[26:27], 0, v[108:109]
	v_mul_f32_e32 v26, v39, v39
	v_mul_f32_e32 v27, v41, v41
	v_pk_fma_f32 v[34:35], v[90:91], v[168:169], v[34:35]
	v_fmac_f32_e32 v26, v38, v38
	v_fmac_f32_e32 v27, v40, v40
	v_pk_mul_f32 v[170:171], v[30:31], v[172:173] op_sel_hi:[0,1]
	v_add_f32_e32 v26, v26, v27
	v_mul_f32_e32 v27, v35, v35
	v_pk_fma_f32 v[36:37], v[88:89], v[170:171], v[36:37]
	v_fmac_f32_e32 v27, v34, v34
	v_add_f32_e32 v26, v27, v26
	v_mul_f32_e32 v27, v37, v37
	v_fmac_f32_e32 v27, v36, v36
	v_add_f32_e32 v119, v27, v26
	v_pk_mul_f32 v[26:27], v[80:81], v[40:41]
	v_pk_mul_f32 v[32:33], v[82:83], v[38:39]
	global_store_dwordx4 v[28:29], v[38:41], off nt
	global_store_dwordx4 v[28:29], v[34:37], off offset:16 nt
	v_cvt_pk_bf16_f32 v32, v32, v33
	v_cvt_pk_bf16_f32 v33, v26, v27
	v_lshlrev_b64 v[26:27], 12, v[194:195]
	v_lshl_add_u64 v[26:27], s[26:27], 0, v[26:27]
	v_pk_mul_f32 v[34:35], v[86:87], v[34:35]
	v_lshl_add_u64 v[26:27], v[70:71], 1, v[26:27]
	v_pk_mul_f32 v[36:37], v[84:85], v[36:37]
	v_cvt_pk_bf16_f32 v34, v34, v35
	v_lshlrev_b32_e32 v31, 16, v32
	v_cvt_pk_bf16_f32 v35, v36, v37
	global_store_dwordx4 v[26:27], v[32:35], off sc1
	s_nop 1
	v_and_b32_e32 v32, 0xffff0000, v32
	v_max3_f32 v31, |v31|, 0, |v32|
	v_lshlrev_b32_e32 v32, 16, v33
	v_and_b32_e32 v33, 0xffff0000, v33
	v_max3_f32 v31, v31, |v32|, |v33|
	v_lshlrev_b32_e32 v32, 16, v34
	v_and_b32_e32 v33, 0xffff0000, v34
	v_max3_f32 v31, v31, |v32|, |v33|
	v_lshlrev_b32_e32 v32, 16, v35
	v_and_b32_e32 v33, 0xffff0000, v35
	v_max3_f32 v38, v31, |v32|, |v33|
	v_pk_mul_f32 v[32:33], v[30:31], v[164:165] op_sel_hi:[0,1]
	v_pk_mul_f32 v[34:35], v[30:31], v[160:161] op_sel_hi:[0,1]
	v_pk_mul_f32 v[36:37], v[30:31], v[166:167] op_sel_hi:[0,1]
	v_pk_mul_f32 v[30:31], v[30:31], v[162:163] op_sel_hi:[0,1]
	v_pk_fma_f32 v[16:17], v[66:67], v[34:35], v[16:17]
	v_pk_fma_f32 v[14:15], v[68:69], v[32:33], v[14:15]
	v_pk_fma_f32 v[8:9], v[74:75], v[30:31], v[8:9]
	v_pk_fma_f32 v[6:7], v[72:73], v[36:37], v[6:7]
	global_store_dwordx4 v[28:29], v[14:17], off offset:512 nt
	global_store_dwordx4 v[28:29], v[6:9], off offset:528 nt
	v_mul_f32_e32 v28, v15, v15
	v_mul_f32_e32 v29, v17, v17
	v_fmac_f32_e32 v28, v14, v14
	v_fmac_f32_e32 v29, v16, v16
	v_add_f32_e32 v28, v28, v29
	v_mul_f32_e32 v29, v7, v7
	v_fmac_f32_e32 v29, v6, v6
	v_add_f32_e32 v28, v29, v28
	v_mul_f32_e32 v29, v9, v9
	v_fmac_f32_e32 v29, v8, v8
	v_add_f32_e32 v28, v29, v28
	v_add_f32_e32 v30, v119, v28
	v_pk_mul_f32 v[14:15], v[60:61], v[14:15]
	v_pk_mul_f32 v[28:29], v[62:63], v[8:9]
	v_pk_mul_f32 v[8:9], v[64:65], v[6:7]
	v_cvt_pk_bf16_f32 v6, v14, v15
	v_pk_mul_f32 v[16:17], v[58:59], v[16:17]
	v_lshlrev_b32_e32 v14, 16, v6
	v_cvt_pk_bf16_f32 v7, v16, v17
	v_cvt_pk_bf16_f32 v8, v8, v9
	v_cvt_pk_bf16_f32 v9, v28, v29
	global_store_dwordx4 v[26:27], v[6:9], off offset:256 sc1
	s_nop 1
	v_and_b32_e32 v6, 0xffff0000, v6
	v_max3_f32 v6, v38, |v14|, |v6|
	v_lshlrev_b32_e32 v14, 16, v7
	v_and_b32_e32 v7, 0xffff0000, v7
	v_max3_f32 v6, v6, |v14|, |v7|
	v_lshlrev_b32_e32 v7, 16, v8
	v_and_b32_e32 v8, 0xffff0000, v8
	v_max3_f32 v6, v6, |v7|, |v8|
	v_lshlrev_b32_e32 v7, 16, v9
	v_and_b32_e32 v8, 0xffff0000, v9
	v_max3_f32 v8, v6, |v7|, |v8|
	ds_bpermute_b32 v9, v212, v8
	ds_bpermute_b32 v6, v212, v30
	s_waitcnt lgkmcnt(1)
	v_max_f32_e32 v9, v9, v9
	s_waitcnt lgkmcnt(0)
	v_add_f32_e32 v6, v30, v6
	v_max_f32_e32 v8, v8, v9
	ds_bpermute_b32 v7, v213, v6
	ds_bpermute_b32 v9, v213, v8
	s_and_saveexec_b64 s[50:51], s[0:1]
	s_cbranch_execz .LBB0_907
	s_waitcnt lgkmcnt(0)
	v_max_f32_e32 v9, v9, v9
	v_max_f32_e32 v8, v8, v8
	v_add_f32_e32 v15, v6, v7
	v_lshlrev_b64 v[6:7], 7, v[194:195]
	v_max_f32_e32 v14, v8, v9
	v_lshl_add_u64 v[8:9], s[30:31], 0, v[6:7]
	s_lshl_b64 s[16:17], s[46:47], 2
	v_lshl_add_u64 v[6:7], s[34:35], 0, v[6:7]
	v_lshl_add_u64 v[8:9], v[8:9], 0, s[16:17]
	s_lshl_b32 s12, s93, 2
	v_lshl_add_u64 v[6:7], v[6:7], 0, s[16:17]
	v_lshl_add_u64 v[8:9], v[8:9], 0, s[12:13]
	v_lshl_add_u64 v[6:7], v[6:7], 0, s[12:13]
	global_store_dword v[8:9], v15, off
	global_store_dword v[6:7], v14, off
.LBB0_907:
	s_or_b64 exec, exec, s[50:51]
	v_or_b32_e32 v36, 16, v178
	v_ashrrev_i32_e32 v37, 31, v36
	v_add_u32_e32 v6, 0xffffe090, v118
	v_cmp_gt_i32_e32 vcc, s87, v36
	v_mov_b32_e32 v8, s59
	s_waitcnt lgkmcnt(0)
	v_mov_b32_e32 v9, s57
	v_cndmask_b32_e32 v7, 0, v37, vcc
	v_cndmask_b32_e32 v6, v6, v36, vcc
	v_cndmask_b32_e32 v9, v8, v9, vcc
	v_mov_b32_e32 v8, s58
	v_mov_b32_e32 v14, s56
	v_cndmask_b32_e32 v8, v8, v14, vcc
	v_lshlrev_b64 v[6:7], 13, v[6:7]
	v_lshl_add_u64 v[6:7], v[8:9], 0, v[6:7]
	v_lshl_add_u64 v[14:15], v[6:7], 0, v[108:109]
	global_load_dwordx4 v[26:29], v[14:15], off offset:16 nt
	global_load_dwordx4 v[30:33], v[14:15], off nt
	global_load_dwordx4 v[6:9], v[14:15], off offset:528 nt
	s_nop 0
	global_load_dwordx4 v[14:17], v[14:15], off offset:512 nt
	v_lshlrev_b64 v[34:35], 13, v[178:179]
	v_lshl_add_u64 v[160:161], s[20:21], 0, v[34:35]
	global_load_dword v34, v[176:177], off offset:512
	s_waitcnt vmcnt(0)
	v_pk_mul_f32 v[38:39], v[34:35], v[154:155] op_sel_hi:[0,1]
	v_pk_mul_f32 v[40:41], v[34:35], v[152:153] op_sel_hi:[0,1]
	v_pk_mul_f32 v[152:153], v[34:35], v[158:159] op_sel_hi:[0,1]
	v_pk_fma_f32 v[24:25], v[76:77], v[40:41], v[24:25]
	v_pk_fma_f32 v[22:23], v[78:79], v[38:39], v[22:23]
	v_pk_fma_f32 v[38:39], v[90:91], v[152:153], v[18:19]
	v_mul_f32_e32 v18, v23, v23
	v_mul_f32_e32 v19, v25, v25
	v_fmac_f32_e32 v18, v22, v22
	v_fmac_f32_e32 v19, v24, v24
	v_pk_mul_f32 v[154:155], v[34:35], v[156:157] op_sel_hi:[0,1]
	v_add_f32_e32 v18, v18, v19
	v_mul_f32_e32 v19, v39, v39
	v_pk_fma_f32 v[40:41], v[88:89], v[154:155], v[20:21]
	v_fmac_f32_e32 v19, v38, v38
	v_add_f32_e32 v18, v19, v18
	v_mul_f32_e32 v19, v41, v41
	v_lshl_add_u64 v[20:21], v[160:161], 0, v[108:109]
	v_fmac_f32_e32 v19, v40, v40
	global_store_dwordx4 v[20:21], v[22:25], off nt
	global_store_dwordx4 v[20:21], v[38:41], off offset:16 nt
	v_add_f32_e32 v119, v19, v18
	v_pk_mul_f32 v[18:19], v[80:81], v[24:25]
	v_pk_mul_f32 v[22:23], v[82:83], v[22:23]
	v_pk_mul_f32 v[24:25], v[86:87], v[38:39]
	v_cvt_pk_bf16_f32 v22, v22, v23
	v_cvt_pk_bf16_f32 v23, v18, v19
	v_lshlrev_b64 v[18:19], 12, v[178:179]
	v_lshl_add_u64 v[18:19], s[26:27], 0, v[18:19]
	v_lshl_add_u64 v[18:19], v[70:71], 1, v[18:19]
	v_pk_mul_f32 v[40:41], v[84:85], v[40:41]
	v_cvt_pk_bf16_f32 v24, v24, v25
	v_lshlrev_b32_e32 v35, 16, v22
	v_cvt_pk_bf16_f32 v25, v40, v41
	global_store_dwordx4 v[18:19], v[22:25], off sc1
	s_nop 1
	v_and_b32_e32 v22, 0xffff0000, v22
	v_max3_f32 v22, |v35|, 0, |v22|
	v_lshlrev_b32_e32 v35, 16, v23
	v_and_b32_e32 v23, 0xffff0000, v23
	v_max3_f32 v22, v22, |v35|, |v23|
	v_lshlrev_b32_e32 v23, 16, v24
	v_and_b32_e32 v24, 0xffff0000, v24
	v_max3_f32 v22, v22, |v23|, |v24|
	v_lshlrev_b32_e32 v23, 16, v25
	v_and_b32_e32 v24, 0xffff0000, v25
	v_max3_f32 v40, v22, |v23|, |v24|
	v_pk_mul_f32 v[22:23], v[34:35], v[148:149] op_sel_hi:[0,1]
	v_pk_mul_f32 v[24:25], v[34:35], v[128:129] op_sel_hi:[0,1]
	v_pk_mul_f32 v[38:39], v[34:35], v[150:151] op_sel_hi:[0,1]
	v_pk_mul_f32 v[34:35], v[34:35], v[146:147] op_sel_hi:[0,1]
	v_pk_fma_f32 v[12:13], v[66:67], v[24:25], v[12:13]
	v_pk_fma_f32 v[10:11], v[68:69], v[22:23], v[10:11]
	v_pk_fma_f32 v[4:5], v[74:75], v[34:35], v[4:5]
	v_pk_fma_f32 v[2:3], v[72:73], v[38:39], v[2:3]
	global_store_dwordx4 v[20:21], v[10:13], off offset:512 nt
	global_store_dwordx4 v[20:21], v[2:5], off offset:528 nt
	v_mul_f32_e32 v20, v11, v11
	v_mul_f32_e32 v21, v13, v13
	v_fmac_f32_e32 v20, v10, v10
	v_fmac_f32_e32 v21, v12, v12
	v_add_f32_e32 v20, v20, v21
	v_mul_f32_e32 v21, v3, v3
	v_fmac_f32_e32 v21, v2, v2
	v_add_f32_e32 v20, v21, v20
	v_mul_f32_e32 v21, v5, v5
	v_fmac_f32_e32 v21, v4, v4
	v_add_f32_e32 v20, v21, v20
	v_add_f32_e32 v22, v119, v20
	v_pk_mul_f32 v[10:11], v[60:61], v[10:11]
	v_pk_mul_f32 v[20:21], v[62:63], v[4:5]
	v_pk_mul_f32 v[4:5], v[64:65], v[2:3]
	v_cvt_pk_bf16_f32 v2, v10, v11
	v_pk_mul_f32 v[12:13], v[58:59], v[12:13]
	v_lshlrev_b32_e32 v10, 16, v2
	v_cvt_pk_bf16_f32 v3, v12, v13
	v_cvt_pk_bf16_f32 v4, v4, v5
	v_cvt_pk_bf16_f32 v5, v20, v21
	global_store_dwordx4 v[18:19], v[2:5], off offset:256 sc1
	s_nop 1
	v_and_b32_e32 v2, 0xffff0000, v2
	v_max3_f32 v2, v40, |v10|, |v2|
	v_lshlrev_b32_e32 v10, 16, v3
	v_and_b32_e32 v3, 0xffff0000, v3
	v_max3_f32 v2, v2, |v10|, |v3|
	v_lshlrev_b32_e32 v3, 16, v4
	v_and_b32_e32 v4, 0xffff0000, v4
	v_max3_f32 v2, v2, |v3|, |v4|
	v_lshlrev_b32_e32 v3, 16, v5
	v_and_b32_e32 v4, 0xffff0000, v5
	v_max3_f32 v4, v2, |v3|, |v4|
	ds_bpermute_b32 v5, v212, v4
	ds_bpermute_b32 v2, v212, v22
	s_waitcnt lgkmcnt(1)
	v_max_f32_e32 v5, v5, v5
	s_waitcnt lgkmcnt(0)
	v_add_f32_e32 v2, v22, v2
	v_max_f32_e32 v4, v4, v5
	ds_bpermute_b32 v3, v213, v2
	ds_bpermute_b32 v5, v213, v4
	s_and_saveexec_b64 s[50:51], s[0:1]
	s_cbranch_execz .LBB0_909
	s_waitcnt lgkmcnt(0)
	v_max_f32_e32 v5, v5, v5
	v_max_f32_e32 v4, v4, v4
	v_add_f32_e32 v11, v2, v3
	v_lshlrev_b64 v[2:3], 7, v[178:179]
	v_max_f32_e32 v10, v4, v5
	v_lshl_add_u64 v[4:5], s[30:31], 0, v[2:3]
	s_lshl_b64 s[16:17], s[46:47], 2
	v_lshl_add_u64 v[2:3], s[34:35], 0, v[2:3]
	v_lshl_add_u64 v[4:5], v[4:5], 0, s[16:17]
	s_lshl_b32 s12, s93, 2
	v_lshl_add_u64 v[2:3], v[2:3], 0, s[16:17]
	v_lshl_add_u64 v[4:5], v[4:5], 0, s[12:13]
	v_lshl_add_u64 v[2:3], v[2:3], 0, s[12:13]
	global_store_dword v[4:5], v11, off
	global_store_dword v[2:3], v10, off
.LBB0_909:
	s_or_b64 exec, exec, s[50:51]
	v_or_b32_e32 v34, 32, v178
	v_ashrrev_i32_e32 v35, 31, v34
	v_add_u32_e32 v2, 0xffffe0a0, v118
	v_cmp_gt_i32_e32 vcc, s87, v34
	v_mov_b32_e32 v4, s59
	s_waitcnt lgkmcnt(0)
	v_mov_b32_e32 v5, s57
	v_cndmask_b32_e32 v3, 0, v35, vcc
	v_cndmask_b32_e32 v2, v2, v34, vcc
	v_cndmask_b32_e32 v5, v4, v5, vcc
	v_mov_b32_e32 v4, s58
	v_mov_b32_e32 v10, s56
	v_cndmask_b32_e32 v4, v4, v10, vcc
	v_lshlrev_b64 v[2:3], 13, v[2:3]
	v_lshl_add_u64 v[2:3], v[4:5], 0, v[2:3]
	v_lshl_add_u64 v[10:11], v[2:3], 0, v[108:109]
	global_load_dwordx4 v[18:21], v[10:11], off offset:16 nt
	global_load_dwordx4 v[22:25], v[10:11], off nt
	global_load_dwordx4 v[2:5], v[10:11], off offset:528 nt
	s_nop 0
	global_load_dwordx4 v[10:13], v[10:11], off offset:512 nt
	v_lshlrev_b64 v[38:39], 13, v[36:37]
	v_lshl_add_u64 v[40:41], s[20:21], 0, v[38:39]
	v_lshl_add_u64 v[38:39], v[36:37], 2, s[22:23]
	global_load_dword v38, v[38:39], off
	s_waitcnt vmcnt(0)
	v_pk_mul_f32 v[122:123], v[38:39], v[122:123] op_sel_hi:[0,1]
	v_pk_mul_f32 v[120:121], v[38:39], v[120:121] op_sel_hi:[0,1]
	v_pk_mul_f32 v[126:127], v[38:39], v[126:127] op_sel_hi:[0,1]
	v_pk_fma_f32 v[32:33], v[76:77], v[120:121], v[32:33]
	v_pk_fma_f32 v[30:31], v[78:79], v[122:123], v[30:31]
	v_pk_fma_f32 v[120:121], v[90:91], v[126:127], v[26:27]
	v_mul_f32_e32 v26, v31, v31
	v_mul_f32_e32 v27, v33, v33
	v_fmac_f32_e32 v26, v30, v30
	v_fmac_f32_e32 v27, v32, v32
	v_pk_mul_f32 v[124:125], v[38:39], v[124:125] op_sel_hi:[0,1]
	v_add_f32_e32 v26, v26, v27
	v_mul_f32_e32 v27, v121, v121
	v_pk_fma_f32 v[122:123], v[88:89], v[124:125], v[28:29]
	v_fmac_f32_e32 v27, v120, v120
	v_add_f32_e32 v26, v27, v26
	v_mul_f32_e32 v27, v123, v123
	v_lshl_add_u64 v[28:29], v[40:41], 0, v[108:109]
	v_fmac_f32_e32 v27, v122, v122
	global_store_dwordx4 v[28:29], v[30:33], off nt
	global_store_dwordx4 v[28:29], v[120:123], off offset:16 nt
	v_add_f32_e32 v119, v27, v26
	v_pk_mul_f32 v[26:27], v[80:81], v[32:33]
	v_pk_mul_f32 v[30:31], v[82:83], v[30:31]
	v_pk_mul_f32 v[32:33], v[86:87], v[120:121]
	v_cvt_pk_bf16_f32 v30, v30, v31
	v_cvt_pk_bf16_f32 v31, v26, v27
	v_lshlrev_b64 v[26:27], 12, v[36:37]
	v_lshl_add_u64 v[26:27], s[26:27], 0, v[26:27]
	v_lshl_add_u64 v[26:27], v[70:71], 1, v[26:27]
	v_pk_mul_f32 v[40:41], v[84:85], v[122:123]
	v_cvt_pk_bf16_f32 v32, v32, v33
	v_lshlrev_b32_e32 v39, 16, v30
	v_cvt_pk_bf16_f32 v33, v40, v41
	global_store_dwordx4 v[26:27], v[30:33], off sc1
	s_nop 1
	v_and_b32_e32 v30, 0xffff0000, v30
	v_max3_f32 v30, |v39|, 0, |v30|
	v_lshlrev_b32_e32 v39, 16, v31
	v_and_b32_e32 v31, 0xffff0000, v31
	v_max3_f32 v30, v30, |v39|, |v31|
	v_lshlrev_b32_e32 v31, 16, v32
	v_and_b32_e32 v32, 0xffff0000, v32
	v_max3_f32 v30, v30, |v31|, |v32|
	v_lshlrev_b32_e32 v31, 16, v33
	v_and_b32_e32 v32, 0xffff0000, v33
	v_max3_f32 v120, v30, |v31|, |v32|
	v_pk_mul_f32 v[30:31], v[38:39], v[114:115] op_sel_hi:[0,1]
	v_pk_mul_f32 v[32:33], v[38:39], v[110:111] op_sel_hi:[0,1]
	v_pk_mul_f32 v[40:41], v[38:39], v[116:117] op_sel_hi:[0,1]
	v_pk_mul_f32 v[38:39], v[38:39], v[112:113] op_sel_hi:[0,1]
	v_pk_fma_f32 v[16:17], v[66:67], v[32:33], v[16:17]
	v_pk_fma_f32 v[14:15], v[68:69], v[30:31], v[14:15]
	v_pk_fma_f32 v[8:9], v[74:75], v[38:39], v[8:9]
	v_pk_fma_f32 v[6:7], v[72:73], v[40:41], v[6:7]
	global_store_dwordx4 v[28:29], v[14:17], off offset:512 nt
	global_store_dwordx4 v[28:29], v[6:9], off offset:528 nt
	v_mul_f32_e32 v28, v15, v15
	v_mul_f32_e32 v29, v17, v17
	v_fmac_f32_e32 v28, v14, v14
	v_fmac_f32_e32 v29, v16, v16
	v_add_f32_e32 v28, v28, v29
	v_mul_f32_e32 v29, v7, v7
	v_fmac_f32_e32 v29, v6, v6
	v_add_f32_e32 v28, v29, v28
	v_mul_f32_e32 v29, v9, v9
	v_fmac_f32_e32 v29, v8, v8
	v_add_f32_e32 v28, v29, v28
	v_add_f32_e32 v30, v119, v28
	v_pk_mul_f32 v[14:15], v[60:61], v[14:15]
	v_pk_mul_f32 v[28:29], v[62:63], v[8:9]
	v_pk_mul_f32 v[8:9], v[64:65], v[6:7]
	v_cvt_pk_bf16_f32 v6, v14, v15
	v_pk_mul_f32 v[16:17], v[58:59], v[16:17]
	v_lshlrev_b32_e32 v14, 16, v6
	v_cvt_pk_bf16_f32 v7, v16, v17
	v_cvt_pk_bf16_f32 v8, v8, v9
	v_cvt_pk_bf16_f32 v9, v28, v29
	global_store_dwordx4 v[26:27], v[6:9], off offset:256 sc1
	s_nop 1
	v_and_b32_e32 v6, 0xffff0000, v6
	v_max3_f32 v6, v120, |v14|, |v6|
	v_lshlrev_b32_e32 v14, 16, v7
	v_and_b32_e32 v7, 0xffff0000, v7
	v_max3_f32 v6, v6, |v14|, |v7|
	v_lshlrev_b32_e32 v7, 16, v8
	v_and_b32_e32 v8, 0xffff0000, v8
	v_max3_f32 v6, v6, |v7|, |v8|
	v_lshlrev_b32_e32 v7, 16, v9
	v_and_b32_e32 v8, 0xffff0000, v9
	v_max3_f32 v8, v6, |v7|, |v8|
	ds_bpermute_b32 v9, v212, v8
	ds_bpermute_b32 v6, v212, v30
	s_waitcnt lgkmcnt(1)
	v_max_f32_e32 v9, v9, v9
	s_waitcnt lgkmcnt(0)
	v_add_f32_e32 v6, v30, v6
	v_max_f32_e32 v8, v8, v9
	ds_bpermute_b32 v7, v213, v6
	ds_bpermute_b32 v9, v213, v8
	s_and_saveexec_b64 s[50:51], s[0:1]
	s_cbranch_execz .LBB0_911
	s_waitcnt lgkmcnt(0)
	v_max_f32_e32 v9, v9, v9
	v_max_f32_e32 v8, v8, v8
	v_add_f32_e32 v15, v6, v7
	v_lshlrev_b64 v[6:7], 7, v[36:37]
	v_max_f32_e32 v14, v8, v9
	v_lshl_add_u64 v[8:9], s[30:31], 0, v[6:7]
	s_lshl_b64 s[16:17], s[46:47], 2
	v_lshl_add_u64 v[6:7], s[34:35], 0, v[6:7]
	v_lshl_add_u64 v[8:9], v[8:9], 0, s[16:17]
	s_lshl_b32 s12, s93, 2
	v_lshl_add_u64 v[6:7], v[6:7], 0, s[16:17]
	v_lshl_add_u64 v[8:9], v[8:9], 0, s[12:13]
	v_lshl_add_u64 v[6:7], v[6:7], 0, s[12:13]
	global_store_dword v[8:9], v15, off
	global_store_dword v[6:7], v14, off
.LBB0_911:
	s_or_b64 exec, exec, s[50:51]
	v_or_b32_e32 v36, 48, v178
	v_ashrrev_i32_e32 v37, 31, v36
	v_add_u32_e32 v6, 0xffffe0b0, v118
	v_cmp_gt_i32_e32 vcc, s87, v36
	v_mov_b32_e32 v8, s59
	s_waitcnt lgkmcnt(0)
	v_mov_b32_e32 v9, s57
	v_cndmask_b32_e32 v7, 0, v37, vcc
	v_cndmask_b32_e32 v6, v6, v36, vcc
	v_cndmask_b32_e32 v9, v8, v9, vcc
	v_mov_b32_e32 v8, s58
	v_mov_b32_e32 v14, s56
	v_cndmask_b32_e32 v8, v8, v14, vcc
	v_lshlrev_b64 v[6:7], 13, v[6:7]
	v_lshl_add_u64 v[6:7], v[8:9], 0, v[6:7]
	v_lshl_add_u64 v[14:15], v[6:7], 0, v[108:109]
	global_load_dwordx4 v[26:29], v[14:15], off offset:16 nt
	global_load_dwordx4 v[30:33], v[14:15], off nt
	global_load_dwordx4 v[6:9], v[14:15], off offset:528 nt
	s_nop 0
	global_load_dwordx4 v[14:17], v[14:15], off offset:512 nt
	v_lshlrev_b64 v[38:39], 13, v[34:35]
	v_lshl_add_u64 v[40:41], s[20:21], 0, v[38:39]
	v_lshl_add_u64 v[38:39], v[34:35], 2, s[22:23]
	global_load_dword v38, v[38:39], off
	s_waitcnt vmcnt(0)
	v_pk_mul_f32 v[102:103], v[38:39], v[102:103] op_sel_hi:[0,1]
	v_pk_mul_f32 v[100:101], v[38:39], v[100:101] op_sel_hi:[0,1]
	v_pk_mul_f32 v[106:107], v[38:39], v[106:107] op_sel_hi:[0,1]
	v_pk_fma_f32 v[24:25], v[76:77], v[100:101], v[24:25]
	v_pk_fma_f32 v[22:23], v[78:79], v[102:103], v[22:23]
	v_pk_fma_f32 v[100:101], v[90:91], v[106:107], v[18:19]
	v_mul_f32_e32 v18, v23, v23
	v_mul_f32_e32 v19, v25, v25
	v_fmac_f32_e32 v18, v22, v22
	v_fmac_f32_e32 v19, v24, v24
	v_pk_mul_f32 v[104:105], v[38:39], v[104:105] op_sel_hi:[0,1]
	v_add_f32_e32 v18, v18, v19
	v_mul_f32_e32 v19, v101, v101
	v_pk_fma_f32 v[102:103], v[88:89], v[104:105], v[20:21]
	v_fmac_f32_e32 v19, v100, v100
	v_add_f32_e32 v18, v19, v18
	v_mul_f32_e32 v19, v103, v103
	v_lshl_add_u64 v[20:21], v[40:41], 0, v[108:109]
	v_fmac_f32_e32 v19, v102, v102
	global_store_dwordx4 v[20:21], v[22:25], off nt
	global_store_dwordx4 v[20:21], v[100:103], off offset:16 nt
	v_add_f32_e32 v104, v19, v18
	v_pk_mul_f32 v[18:19], v[80:81], v[24:25]
	v_pk_mul_f32 v[22:23], v[82:83], v[22:23]
	v_pk_mul_f32 v[24:25], v[86:87], v[100:101]
	v_cvt_pk_bf16_f32 v22, v22, v23
	v_cvt_pk_bf16_f32 v23, v18, v19
	v_lshlrev_b64 v[18:19], 12, v[34:35]
	v_lshl_add_u64 v[18:19], s[26:27], 0, v[18:19]
	v_lshl_add_u64 v[18:19], v[70:71], 1, v[18:19]
	v_pk_mul_f32 v[40:41], v[84:85], v[102:103]
	v_cvt_pk_bf16_f32 v24, v24, v25
	v_lshlrev_b32_e32 v39, 16, v22
	v_cvt_pk_bf16_f32 v25, v40, v41
	global_store_dwordx4 v[18:19], v[22:25], off sc1
	s_nop 1
	v_and_b32_e32 v22, 0xffff0000, v22
	v_max3_f32 v22, |v39|, 0, |v22|
	v_lshlrev_b32_e32 v39, 16, v23
	v_and_b32_e32 v23, 0xffff0000, v23
	v_max3_f32 v22, v22, |v39|, |v23|
	v_lshlrev_b32_e32 v23, 16, v24
	v_and_b32_e32 v24, 0xffff0000, v24
	v_max3_f32 v22, v22, |v23|, |v24|
	v_lshlrev_b32_e32 v23, 16, v25
	v_and_b32_e32 v24, 0xffff0000, v25
	v_max3_f32 v100, v22, |v23|, |v24|
	v_pk_mul_f32 v[22:23], v[38:39], v[96:97] op_sel_hi:[0,1]
	v_pk_mul_f32 v[24:25], v[38:39], v[92:93] op_sel_hi:[0,1]
	v_pk_mul_f32 v[40:41], v[38:39], v[98:99] op_sel_hi:[0,1]
	v_pk_mul_f32 v[38:39], v[38:39], v[94:95] op_sel_hi:[0,1]
	v_pk_fma_f32 v[12:13], v[66:67], v[24:25], v[12:13]
	v_pk_fma_f32 v[10:11], v[68:69], v[22:23], v[10:11]
	v_pk_fma_f32 v[4:5], v[74:75], v[38:39], v[4:5]
	v_pk_fma_f32 v[2:3], v[72:73], v[40:41], v[2:3]
	global_store_dwordx4 v[20:21], v[10:13], off offset:512 nt
	global_store_dwordx4 v[20:21], v[2:5], off offset:528 nt
	v_mul_f32_e32 v20, v11, v11
	v_mul_f32_e32 v21, v13, v13
	v_fmac_f32_e32 v20, v10, v10
	v_fmac_f32_e32 v21, v12, v12
	v_add_f32_e32 v20, v20, v21
	v_mul_f32_e32 v21, v3, v3
	v_fmac_f32_e32 v21, v2, v2
	v_add_f32_e32 v20, v21, v20
	v_mul_f32_e32 v21, v5, v5
	v_fmac_f32_e32 v21, v4, v4
	v_add_f32_e32 v20, v21, v20
	v_add_f32_e32 v22, v104, v20
	v_pk_mul_f32 v[10:11], v[60:61], v[10:11]
	v_pk_mul_f32 v[20:21], v[62:63], v[4:5]
	v_pk_mul_f32 v[4:5], v[64:65], v[2:3]
	v_cvt_pk_bf16_f32 v2, v10, v11
	v_pk_mul_f32 v[12:13], v[58:59], v[12:13]
	v_lshlrev_b32_e32 v10, 16, v2
	v_cvt_pk_bf16_f32 v3, v12, v13
	v_cvt_pk_bf16_f32 v4, v4, v5
	v_cvt_pk_bf16_f32 v5, v20, v21
	global_store_dwordx4 v[18:19], v[2:5], off offset:256 sc1
	s_nop 1
	v_and_b32_e32 v2, 0xffff0000, v2
	v_max3_f32 v2, v100, |v10|, |v2|
	v_lshlrev_b32_e32 v10, 16, v3
	v_and_b32_e32 v3, 0xffff0000, v3
	v_max3_f32 v2, v2, |v10|, |v3|
	v_lshlrev_b32_e32 v3, 16, v4
	v_and_b32_e32 v4, 0xffff0000, v4
	v_max3_f32 v2, v2, |v3|, |v4|
	v_lshlrev_b32_e32 v3, 16, v5
	v_and_b32_e32 v4, 0xffff0000, v5
	v_max3_f32 v4, v2, |v3|, |v4|
	ds_bpermute_b32 v5, v212, v4
	ds_bpermute_b32 v2, v212, v22
	s_waitcnt lgkmcnt(1)
	v_max_f32_e32 v5, v5, v5
	s_waitcnt lgkmcnt(0)
	v_add_f32_e32 v2, v22, v2
	v_max_f32_e32 v4, v4, v5
	ds_bpermute_b32 v3, v213, v2
	ds_bpermute_b32 v5, v213, v4
	s_and_saveexec_b64 s[50:51], s[0:1]
	s_cbranch_execz .LBB0_913
	s_waitcnt lgkmcnt(0)
	v_max_f32_e32 v5, v5, v5
	v_max_f32_e32 v4, v4, v4
	v_add_f32_e32 v11, v2, v3
	v_lshlrev_b64 v[2:3], 7, v[34:35]
	v_max_f32_e32 v10, v4, v5
	v_lshl_add_u64 v[4:5], s[30:31], 0, v[2:3]
	s_lshl_b64 s[16:17], s[46:47], 2
	v_lshl_add_u64 v[2:3], s[34:35], 0, v[2:3]
	v_lshl_add_u64 v[4:5], v[4:5], 0, s[16:17]
	s_lshl_b32 s12, s93, 2
	v_lshl_add_u64 v[2:3], v[2:3], 0, s[16:17]
	v_lshl_add_u64 v[4:5], v[4:5], 0, s[12:13]
	v_lshl_add_u64 v[2:3], v[2:3], 0, s[12:13]
	global_store_dword v[4:5], v11, off
	global_store_dword v[2:3], v10, off
.LBB0_913:
	s_or_b64 exec, exec, s[50:51]
	s_waitcnt lgkmcnt(0)
	v_lshl_add_u64 v[4:5], v[36:37], 2, s[22:23]
	global_load_dword v10, v[4:5], off
	v_lshlrev_b64 v[2:3], 13, v[36:37]
	v_lshl_add_u64 v[2:3], s[20:21], 0, v[2:3]
	s_waitcnt vmcnt(0)
	v_pk_mul_f32 v[4:5], v[10:11], v[52:53] op_sel_hi:[0,1]
	v_pk_mul_f32 v[12:13], v[10:11], v[50:51] op_sel_hi:[0,1]
	v_pk_fma_f32 v[20:21], v[76:77], v[12:13], v[32:33]
	v_pk_fma_f32 v[18:19], v[78:79], v[4:5], v[30:31]
	v_pk_mul_f32 v[22:23], v[10:11], v[56:57] op_sel_hi:[0,1]
	v_lshl_add_u64 v[4:5], v[70:71], 2, v[2:3]
	v_mul_f32_e32 v2, v19, v19
	v_mul_f32_e32 v3, v21, v21
	v_pk_fma_f32 v[22:23], v[90:91], v[22:23], v[26:27]
	v_fmac_f32_e32 v2, v18, v18
	v_fmac_f32_e32 v3, v20, v20
	v_pk_mul_f32 v[24:25], v[10:11], v[54:55] op_sel_hi:[0,1]
	v_add_f32_e32 v2, v2, v3
	v_mul_f32_e32 v3, v23, v23
	v_pk_fma_f32 v[24:25], v[88:89], v[24:25], v[28:29]
	v_fmac_f32_e32 v3, v22, v22
	v_add_f32_e32 v2, v3, v2
	v_mul_f32_e32 v3, v25, v25
	v_fmac_f32_e32 v3, v24, v24
	v_pk_mul_f32 v[12:13], v[82:83], v[18:19]
	global_store_dwordx4 v[4:5], v[18:21], off nt
	global_store_dwordx4 v[4:5], v[22:25], off offset:16 nt
	v_add_f32_e32 v26, v3, v2
	v_pk_mul_f32 v[2:3], v[80:81], v[20:21]
	v_cvt_pk_bf16_f32 v18, v12, v13
	v_pk_mul_f32 v[20:21], v[86:87], v[22:23]
	v_lshlrev_b32_e32 v11, 16, v18
	v_and_b32_e32 v12, 0xffff0000, v18
	v_cvt_pk_bf16_f32 v19, v2, v3
	v_lshlrev_b64 v[2:3], 12, v[36:37]
	v_max3_f32 v11, |v11|, 0, |v12|
	v_lshlrev_b32_e32 v12, 16, v19
	v_and_b32_e32 v13, 0xffff0000, v19
	v_cvt_pk_bf16_f32 v20, v20, v21
	v_lshl_add_u64 v[2:3], s[26:27], 0, v[2:3]
	v_max3_f32 v11, v11, |v12|, |v13|
	v_lshlrev_b32_e32 v12, 16, v20
	v_and_b32_e32 v13, 0xffff0000, v20
	v_pk_mul_f32 v[24:25], v[84:85], v[24:25]
	v_lshl_add_u64 v[2:3], v[70:71], 1, v[2:3]
	v_cvt_pk_bf16_f32 v21, v24, v25
	v_max3_f32 v11, v11, |v12|, |v13|
	v_lshlrev_b32_e32 v12, 16, v21
	v_and_b32_e32 v13, 0xffff0000, v21
	global_store_dwordx4 v[2:3], v[18:21], off sc1
	v_max3_f32 v24, v11, |v12|, |v13|
	v_pk_mul_f32 v[12:13], v[10:11], v[42:43] op_sel_hi:[0,1]
	v_pk_mul_f32 v[18:19], v[10:11], v[46:47] op_sel_hi:[0,1]
	v_pk_mul_f32 v[20:21], v[10:11], v[48:49] op_sel_hi:[0,1]
	v_pk_mul_f32 v[22:23], v[10:11], v[44:45] op_sel_hi:[0,1]
	v_pk_fma_f32 v[12:13], v[66:67], v[12:13], v[16:17]
	v_pk_fma_f32 v[10:11], v[68:69], v[18:19], v[14:15]
	v_pk_fma_f32 v[8:9], v[74:75], v[22:23], v[8:9]
	v_pk_fma_f32 v[6:7], v[72:73], v[20:21], v[6:7]
	global_store_dwordx4 v[4:5], v[10:13], off offset:512 nt
	global_store_dwordx4 v[4:5], v[6:9], off offset:528 nt
	v_mul_f32_e32 v4, v11, v11
	v_mul_f32_e32 v5, v13, v13
	v_fmac_f32_e32 v4, v10, v10
	v_fmac_f32_e32 v5, v12, v12
	v_add_f32_e32 v4, v4, v5
	v_mul_f32_e32 v5, v7, v7
	v_fmac_f32_e32 v5, v6, v6
	v_add_f32_e32 v4, v5, v4
	v_mul_f32_e32 v5, v9, v9
	v_fmac_f32_e32 v5, v8, v8
	v_add_f32_e32 v4, v5, v4
	v_add_f32_e32 v14, v26, v4
	v_pk_mul_f32 v[4:5], v[60:61], v[10:11]
	v_pk_mul_f32 v[6:7], v[64:65], v[6:7]
	v_pk_mul_f32 v[12:13], v[58:59], v[12:13]
	v_pk_mul_f32 v[8:9], v[62:63], v[8:9]
	v_cvt_pk_bf16_f32 v4, v4, v5
	v_cvt_pk_bf16_f32 v5, v12, v13
	v_cvt_pk_bf16_f32 v6, v6, v7
	s_nop 0
	v_cvt_pk_bf16_f32 v7, v8, v9
	global_store_dwordx4 v[2:3], v[4:7], off offset:256 sc1
	v_lshlrev_b32_e32 v2, 16, v4
	v_and_b32_e32 v3, 0xffff0000, v4
	v_max3_f32 v2, v24, |v2|, |v3|
	v_lshlrev_b32_e32 v3, 16, v5
	v_and_b32_e32 v4, 0xffff0000, v5
	v_max3_f32 v2, v2, |v3|, |v4|
	v_lshlrev_b32_e32 v3, 16, v6
	v_and_b32_e32 v4, 0xffff0000, v6
	v_max3_f32 v2, v2, |v3|, |v4|
	v_lshlrev_b32_e32 v3, 16, v7
	v_and_b32_e32 v4, 0xffff0000, v7
	v_max3_f32 v4, v2, |v3|, |v4|
	ds_bpermute_b32 v5, v212, v4
	ds_bpermute_b32 v2, v212, v14
	s_waitcnt lgkmcnt(1)
	v_max_f32_e32 v5, v5, v5
	s_waitcnt lgkmcnt(0)
	v_add_f32_e32 v2, v14, v2
	v_max_f32_e32 v4, v4, v5
	ds_bpermute_b32 v3, v213, v2
	ds_bpermute_b32 v5, v213, v4
	s_and_saveexec_b64 s[50:51], s[0:1]
	s_cbranch_execz .LBB0_915
	s_waitcnt lgkmcnt(0)
	v_max_f32_e32 v5, v5, v5
	v_max_f32_e32 v4, v4, v4
	v_add_f32_e32 v7, v2, v3
	v_lshlrev_b64 v[2:3], 7, v[36:37]
	v_max_f32_e32 v6, v4, v5
	v_lshl_add_u64 v[4:5], s[30:31], 0, v[2:3]
	s_lshl_b64 s[16:17], s[46:47], 2
	v_lshl_add_u64 v[2:3], s[34:35], 0, v[2:3]
	v_lshl_add_u64 v[4:5], v[4:5], 0, s[16:17]
	s_lshl_b32 s12, s93, 2
	v_lshl_add_u64 v[2:3], v[2:3], 0, s[16:17]
	v_lshl_add_u64 v[4:5], v[4:5], 0, s[12:13]
	v_lshl_add_u64 v[2:3], v[2:3], 0, s[12:13]
	global_store_dword v[4:5], v7, off
	global_store_dword v[2:3], v6, off

.LBB0_1091:
	s_lshl_b32 s30, s36, 8
	s_add_i32 s34, s30, s62
	s_lshl_b32 s30, s37, 8
	s_or_b32 s35, s30, s63
	s_lshr_b32 s30, s36, 4
	s_add_i32 s30, s30, -1
	v_or_b32_e32 v2, s35, v186
	s_cmp_gt_i32 s36, 31
	s_cselect_b32 s30, s30, 0
	v_ashrrev_i32_e32 v3, 31, v2
	v_or_b32_e32 v168, s34, v187
	v_lshlrev_b64 v[10:11], 2, v[2:3]
	v_ashrrev_i32_e32 v169, 31, v168
	s_ashr_i32 s31, s30, 31
	v_lshl_add_u64 v[12:13], s[20:21], 0, v[10:11]
	v_lshl_add_u64 v[100:101], v[168:169], 2, s[16:17]
	s_lshl_b64 s[30:31], s[30:31], 15
	global_load_dwordx4 v[2:5], v[12:13], off offset:16
	global_load_dwordx4 v[6:9], v[12:13], off
	global_load_dword v190, v[100:101], off
	s_add_u32 s30, s57, s30
	global_load_dwordx4 v[14:17], v[12:13], off offset:528
	global_load_dwordx4 v[30:33], v[12:13], off offset:512
	s_addc_u32 s31, s58, s31
	v_lshl_add_u64 v[10:11], s[30:31], 0, v[10:11]
	global_load_dwordx4 v[26:29], v[10:11], off
	global_load_dwordx4 v[22:25], v[10:11], off offset:16
	global_load_dwordx4 v[18:21], v[10:11], off offset:512
	s_nop 0
	global_load_dwordx4 v[10:13], v[10:11], off offset:528
	s_ashr_i32 s34, s34, 8
	v_bitop3_b32 v90, s35, 56, v186 bitop3:0xc8
	s_ashr_i32 s30, s35, 6
	s_ashr_i32 s35, s34, 31
	s_ashr_i32 s31, s30, 31
	s_lshl_b64 s[38:39], s[34:35], 7
	s_add_u32 s34, s38, s30
	s_addc_u32 s35, s39, s31
	s_lshl_b64 s[34:35], s[34:35], 15
	s_add_u32 s36, s12, s34
	s_addc_u32 s37, s13, s35
	s_or_b32 s34, s30, 2
	s_ashr_i32 s35, s34, 31
	s_add_u32 s38, s38, s34
	v_lshlrev_b32_e32 v169, 7, v168
	s_addc_u32 s39, s39, s35
	v_and_b32_e32 v138, 0x6780, v169
	s_lshl_b64 s[38:39], s[38:39], 15
	v_mov_b32_e32 v91, v139
	v_lshlrev_b32_e32 v90, 1, v90
	v_lshl_add_u64 v[192:193], s[36:37], 0, v[138:139]
	s_add_u32 s38, s12, s38
	v_lshl_add_u64 v[192:193], v[192:193], 0, v[90:91]
	s_addc_u32 s39, s13, s39
	s_and_b64 vcc, exec, s[0:1]
	s_mov_b64 s[0:1], -1
	s_waitcnt vmcnt(0)
	v_pk_mul_f32 v[194:195], v[6:7], v[190:191] op_sel_hi:[1,0]
	v_pk_mul_f32 v[196:197], v[8:9], v[190:191] op_sel_hi:[1,0]
	v_pk_mul_f32 v[198:199], v[2:3], v[190:191] op_sel_hi:[1,0]
	v_pk_mul_f32 v[204:205], v[32:33], v[190:191] op_sel_hi:[1,0]
	v_pk_fma_f32 v[170:171], v[196:197], v[170:171], v[28:29]
	v_pk_fma_f32 v[172:173], v[194:195], v[172:173], v[26:27]
	v_pk_mul_f32 v[200:201], v[4:5], v[190:191] op_sel_hi:[1,0]
	v_pk_mul_f32 v[202:203], v[30:31], v[190:191] op_sel_hi:[1,0]
	v_pk_mul_f32 v[206:207], v[14:15], v[190:191] op_sel_hi:[1,0]
	v_pk_mul_f32 v[190:191], v[16:17], v[190:191] op_sel_hi:[1,0]
	v_pk_fma_f32 v[174:175], v[198:199], v[174:175], v[22:23]
	v_pk_fma_f32 v[182:183], v[204:205], v[182:183], v[20:21]
	v_max_f32_e32 v173, 0, v173
	v_max_f32_e32 v172, 0, v172
	v_max_f32_e32 v171, 0, v171
	v_max_f32_e32 v170, 0, v170
	v_pk_fma_f32 v[176:177], v[200:201], v[176:177], v[24:25]
	v_pk_fma_f32 v[180:181], v[202:203], v[180:181], v[18:19]
	v_pk_fma_f32 v[184:185], v[190:191], v[184:185], v[12:13]
	v_max_f32_e32 v175, 0, v175
	v_max_f32_e32 v174, 0, v174
	v_max_f32_e32 v183, 0, v183
	v_max_f32_e32 v182, 0, v182
	v_pk_mul_f32 v[190:191], v[170:171], v[170:171]
	v_pk_mul_f32 v[170:171], v[172:173], v[172:173]
	v_max_f32_e32 v177, 0, v177
	v_max_f32_e32 v176, 0, v176
	v_max_f32_e32 v181, 0, v181
	v_max_f32_e32 v180, 0, v180
	v_pk_mul_f32 v[172:173], v[174:175], v[174:175]
	v_pk_mul_f32 v[174:175], v[182:183], v[182:183]
	v_cvt_pk_bf16_f32 v170, v170, v171
	v_cvt_pk_bf16_f32 v171, v190, v191
	v_pk_fma_f32 v[178:179], v[206:207], v[178:179], v[10:11]
	v_pk_mul_f32 v[176:177], v[176:177], v[176:177]
	v_pk_mul_f32 v[180:181], v[180:181], v[180:181]
	v_cvt_pk_bf16_f32 v172, v172, v173
	v_cvt_pk_bf16_f32 v173, v176, v177
	global_store_dwordx4 v[192:193], v[170:173], off sc1
	v_max_f32_e32 v179, 0, v179
	v_max_f32_e32 v178, 0, v178
	v_cvt_pk_bf16_f32 v170, v180, v181
	v_cvt_pk_bf16_f32 v171, v174, v175
	v_lshl_add_u64 v[174:175], s[38:39], 0, v[138:139]
	v_max_f32_e32 v185, 0, v185
	v_max_f32_e32 v184, 0, v184
	v_lshl_add_u64 v[174:175], v[174:175], 0, v[90:91]
	v_pk_mul_f32 v[182:183], v[184:185], v[184:185]
	v_pk_mul_f32 v[178:179], v[178:179], v[178:179]
	s_nop 0
	v_cvt_pk_bf16_f32 v172, v178, v179
	v_cvt_pk_bf16_f32 v173, v182, v183
	global_store_dwordx4 v[174:175], v[170:173], off sc1
	v_or_b32_e32 v174, 32, v168
	v_ashrrev_i32_e32 v175, 31, v174
	v_or_b32_e32 v170, 16, v168
	v_ashrrev_i32_e32 v171, 31, v170
	v_lshl_add_u64 v[172:173], v[170:171], 2, s[16:17]
	global_load_dword v172, v[172:173], off
	v_lshlrev_b32_e32 v138, 7, v170
	v_and_b32_e32 v138, 0x6f80, v138
	v_lshl_add_u64 v[176:177], s[36:37], 0, v[138:139]
	v_lshl_add_u64 v[178:179], s[38:39], 0, v[138:139]
	v_lshl_add_u64 v[176:177], v[176:177], 0, v[90:91]
	v_lshl_add_u64 v[178:179], v[178:179], 0, v[90:91]
	v_lshl_add_u64 v[170:171], v[174:175], 2, s[16:17]
	v_lshlrev_b32_e32 v138, 7, v174
	v_and_b32_e32 v138, 0x7780, v138
	s_waitcnt vmcnt(0)
	v_pk_mul_f32 v[180:181], v[6:7], v[172:173] op_sel_hi:[1,0]
	v_pk_mul_f32 v[182:183], v[8:9], v[172:173] op_sel_hi:[1,0]
	v_pk_mul_f32 v[184:185], v[2:3], v[172:173] op_sel_hi:[1,0]
	v_pk_mul_f32 v[190:191], v[4:5], v[172:173] op_sel_hi:[1,0]
	v_pk_fma_f32 v[154:155], v[182:183], v[154:155], v[28:29]
	v_pk_fma_f32 v[152:153], v[180:181], v[152:153], v[26:27]
	v_pk_mul_f32 v[192:193], v[30:31], v[172:173] op_sel_hi:[1,0]
	v_pk_mul_f32 v[194:195], v[32:33], v[172:173] op_sel_hi:[1,0]
	v_pk_mul_f32 v[196:197], v[14:15], v[172:173] op_sel_hi:[1,0]
	v_pk_mul_f32 v[172:173], v[16:17], v[172:173] op_sel_hi:[1,0]
	v_pk_fma_f32 v[158:159], v[190:191], v[158:159], v[24:25]
	v_pk_fma_f32 v[156:157], v[184:185], v[156:157], v[22:23]
	v_max_f32_e32 v153, 0, v153
	v_max_f32_e32 v152, 0, v152
	v_max_f32_e32 v155, 0, v155
	v_max_f32_e32 v154, 0, v154
	v_pk_fma_f32 v[162:163], v[194:195], v[162:163], v[20:21]
	v_pk_fma_f32 v[160:161], v[192:193], v[160:161], v[18:19]
	v_pk_fma_f32 v[166:167], v[172:173], v[166:167], v[12:13]
	v_pk_fma_f32 v[164:165], v[196:197], v[164:165], v[10:11]
	v_max_f32_e32 v157, 0, v157
	v_max_f32_e32 v156, 0, v156
	v_max_f32_e32 v159, 0, v159
	v_max_f32_e32 v158, 0, v158
	v_pk_mul_f32 v[154:155], v[154:155], v[154:155]
	v_pk_mul_f32 v[152:153], v[152:153], v[152:153]
	v_max_f32_e32 v161, 0, v161
	v_max_f32_e32 v160, 0, v160
	v_max_f32_e32 v163, 0, v163
	v_max_f32_e32 v162, 0, v162
	v_max_f32_e32 v165, 0, v165
	v_max_f32_e32 v164, 0, v164
	v_max_f32_e32 v167, 0, v167
	v_max_f32_e32 v166, 0, v166
	v_pk_mul_f32 v[158:159], v[158:159], v[158:159]
	v_pk_mul_f32 v[156:157], v[156:157], v[156:157]
	v_cvt_pk_bf16_f32 v152, v152, v153
	v_cvt_pk_bf16_f32 v153, v154, v155
	v_pk_mul_f32 v[162:163], v[162:163], v[162:163]
	v_cvt_pk_bf16_f32 v154, v156, v157
	v_cvt_pk_bf16_f32 v155, v158, v159
	v_pk_mul_f32 v[160:161], v[160:161], v[160:161]
	v_pk_mul_f32 v[166:167], v[166:167], v[166:167]
	v_pk_mul_f32 v[164:165], v[164:165], v[164:165]
	global_store_dwordx4 v[176:177], v[152:155], off sc1
	v_lshl_add_u64 v[158:159], s[36:37], 0, v[138:139]
	v_lshl_add_u64 v[158:159], v[158:159], 0, v[90:91]
	v_cvt_pk_bf16_f32 v152, v160, v161
	v_cvt_pk_bf16_f32 v153, v162, v163
	v_cvt_pk_bf16_f32 v154, v164, v165
	v_cvt_pk_bf16_f32 v155, v166, v167
	global_store_dwordx4 v[178:179], v[152:155], off sc1
	global_load_dword v152, v[170:171], off
	v_lshl_add_u64 v[160:161], s[38:39], 0, v[138:139]
	v_or_b32_e32 v154, 48, v168
	v_ashrrev_i32_e32 v155, 31, v154
	v_lshl_add_u64 v[160:161], v[160:161], 0, v[90:91]
	v_lshl_add_u64 v[156:157], v[154:155], 2, s[16:17]
	s_waitcnt vmcnt(0)
	v_pk_mul_f32 v[162:163], v[6:7], v[152:153] op_sel_hi:[1,0]
	v_pk_mul_f32 v[164:165], v[8:9], v[152:153] op_sel_hi:[1,0]
	v_pk_mul_f32 v[166:167], v[2:3], v[152:153] op_sel_hi:[1,0]
	v_pk_mul_f32 v[170:171], v[4:5], v[152:153] op_sel_hi:[1,0]
	v_pk_fma_f32 v[120:121], v[164:165], v[120:121], v[28:29]
	v_pk_fma_f32 v[118:119], v[162:163], v[118:119], v[26:27]
	v_pk_mul_f32 v[172:173], v[30:31], v[152:153] op_sel_hi:[1,0]
	v_pk_mul_f32 v[174:175], v[32:33], v[152:153] op_sel_hi:[1,0]
	v_pk_mul_f32 v[176:177], v[14:15], v[152:153] op_sel_hi:[1,0]
	v_pk_mul_f32 v[152:153], v[16:17], v[152:153] op_sel_hi:[1,0]
	v_pk_fma_f32 v[124:125], v[170:171], v[124:125], v[24:25]
	v_pk_fma_f32 v[122:123], v[166:167], v[122:123], v[22:23]
	v_max_f32_e32 v119, 0, v119
	v_max_f32_e32 v118, 0, v118
	v_max_f32_e32 v121, 0, v121
	v_max_f32_e32 v120, 0, v120
	v_pk_fma_f32 v[128:129], v[174:175], v[128:129], v[20:21]
	v_pk_fma_f32 v[126:127], v[172:173], v[126:127], v[18:19]
	v_pk_fma_f32 v[150:151], v[152:153], v[150:151], v[12:13]
	v_pk_fma_f32 v[148:149], v[176:177], v[148:149], v[10:11]
	v_max_f32_e32 v123, 0, v123
	v_max_f32_e32 v122, 0, v122
	v_max_f32_e32 v125, 0, v125
	v_max_f32_e32 v124, 0, v124
	v_pk_mul_f32 v[120:121], v[120:121], v[120:121]
	v_pk_mul_f32 v[118:119], v[118:119], v[118:119]
	v_max_f32_e32 v127, 0, v127
	v_max_f32_e32 v126, 0, v126
	v_max_f32_e32 v129, 0, v129
	v_max_f32_e32 v128, 0, v128
	v_max_f32_e32 v149, 0, v149
	v_max_f32_e32 v148, 0, v148
	v_max_f32_e32 v151, 0, v151
	v_max_f32_e32 v150, 0, v150
	v_pk_mul_f32 v[124:125], v[124:125], v[124:125]
	v_pk_mul_f32 v[122:123], v[122:123], v[122:123]
	v_cvt_pk_bf16_f32 v118, v118, v119
	v_cvt_pk_bf16_f32 v119, v120, v121
	v_pk_mul_f32 v[128:129], v[128:129], v[128:129]
	v_cvt_pk_bf16_f32 v120, v122, v123
	v_cvt_pk_bf16_f32 v121, v124, v125
	v_pk_mul_f32 v[126:127], v[126:127], v[126:127]
	v_pk_mul_f32 v[150:151], v[150:151], v[150:151]
	v_pk_mul_f32 v[148:149], v[148:149], v[148:149]
	global_store_dwordx4 v[158:159], v[118:121], off sc1
	s_nop 1
	v_cvt_pk_bf16_f32 v118, v126, v127
	v_cvt_pk_bf16_f32 v119, v128, v129
	v_cvt_pk_bf16_f32 v120, v148, v149
	v_cvt_pk_bf16_f32 v121, v150, v151
	global_store_dwordx4 v[160:161], v[118:121], off sc1
	global_load_dword v118, v[156:157], off
	s_nop 0
	v_lshlrev_b32_e32 v119, 7, v154
	v_and_b32_e32 v138, 0x7f80, v119
	v_lshl_add_u64 v[120:121], s[36:37], 0, v[138:139]
	v_lshl_add_u64 v[122:123], s[38:39], 0, v[138:139]
	v_lshl_add_u64 v[120:121], v[120:121], 0, v[90:91]
	v_lshl_add_u64 v[122:123], v[122:123], 0, v[90:91]
	s_waitcnt vmcnt(0)
	v_pk_mul_f32 v[124:125], v[6:7], v[118:119] op_sel_hi:[1,0]
	v_pk_mul_f32 v[126:127], v[8:9], v[118:119] op_sel_hi:[1,0]
	v_pk_mul_f32 v[128:129], v[2:3], v[118:119] op_sel_hi:[1,0]
	v_pk_mul_f32 v[148:149], v[4:5], v[118:119] op_sel_hi:[1,0]
	v_pk_fma_f32 v[104:105], v[126:127], v[104:105], v[28:29]
	v_pk_fma_f32 v[102:103], v[124:125], v[102:103], v[26:27]
	v_pk_mul_f32 v[150:151], v[30:31], v[118:119] op_sel_hi:[1,0]
	v_pk_mul_f32 v[152:153], v[32:33], v[118:119] op_sel_hi:[1,0]
	v_pk_mul_f32 v[154:155], v[14:15], v[118:119] op_sel_hi:[1,0]
	v_pk_mul_f32 v[118:119], v[16:17], v[118:119] op_sel_hi:[1,0]
	v_pk_fma_f32 v[108:109], v[148:149], v[108:109], v[24:25]
	v_pk_fma_f32 v[106:107], v[128:129], v[106:107], v[22:23]
	v_max_f32_e32 v103, 0, v103
	v_max_f32_e32 v102, 0, v102
	v_max_f32_e32 v105, 0, v105
	v_max_f32_e32 v104, 0, v104
	v_pk_fma_f32 v[112:113], v[152:153], v[112:113], v[20:21]
	v_pk_fma_f32 v[110:111], v[150:151], v[110:111], v[18:19]
	v_pk_fma_f32 v[116:117], v[118:119], v[116:117], v[12:13]
	v_pk_fma_f32 v[114:115], v[154:155], v[114:115], v[10:11]
	v_max_f32_e32 v107, 0, v107
	v_max_f32_e32 v106, 0, v106
	v_max_f32_e32 v109, 0, v109
	v_max_f32_e32 v108, 0, v108
	v_pk_mul_f32 v[104:105], v[104:105], v[104:105]
	v_pk_mul_f32 v[102:103], v[102:103], v[102:103]
	v_max_f32_e32 v111, 0, v111
	v_max_f32_e32 v110, 0, v110
	v_max_f32_e32 v113, 0, v113
	v_max_f32_e32 v112, 0, v112
	v_max_f32_e32 v115, 0, v115
	v_max_f32_e32 v114, 0, v114
	v_max_f32_e32 v117, 0, v117
	v_max_f32_e32 v116, 0, v116
	v_pk_mul_f32 v[108:109], v[108:109], v[108:109]
	v_pk_mul_f32 v[106:107], v[106:107], v[106:107]
	v_cvt_pk_bf16_f32 v102, v102, v103
	v_cvt_pk_bf16_f32 v103, v104, v105
	v_pk_mul_f32 v[112:113], v[112:113], v[112:113]
	v_cvt_pk_bf16_f32 v104, v106, v107
	v_cvt_pk_bf16_f32 v105, v108, v109
	v_pk_mul_f32 v[110:111], v[110:111], v[110:111]
	v_pk_mul_f32 v[116:117], v[116:117], v[116:117]
	v_pk_mul_f32 v[114:115], v[114:115], v[114:115]
	global_store_dwordx4 v[120:121], v[102:105], off sc1
	s_nop 1
	v_cvt_pk_bf16_f32 v102, v110, v111
	v_cvt_pk_bf16_f32 v103, v112, v113
	v_cvt_pk_bf16_f32 v104, v114, v115
	v_cvt_pk_bf16_f32 v105, v116, v117
	global_store_dwordx4 v[122:123], v[102:105], off sc1
	global_load_dword v106, v[100:101], off offset:512
	s_nop 0
	v_add_u32_e32 v103, 0x80, v168
	v_ashrrev_i32_e32 v102, 8, v103
	v_lshlrev_b32_e32 v107, 7, v103
	v_ashrrev_i32_e32 v103, 31, v102
	v_lshlrev_b64 v[104:105], 7, v[102:103]
	v_lshl_add_u64 v[102:103], v[104:105], 0, s[30:31]
	v_lshl_add_u64 v[104:105], v[104:105], 0, s[34:35]
	v_lshlrev_b64 v[102:103], 15, v[102:103]
	v_lshlrev_b64 v[104:105], 15, v[104:105]
	v_lshl_add_u64 v[102:103], s[12:13], 0, v[102:103]
	v_lshl_add_u64 v[104:105], s[12:13], 0, v[104:105]
	v_and_b32_e32 v138, 0x6780, v107
	v_lshl_add_u64 v[108:109], v[102:103], 0, v[138:139]
	v_lshl_add_u64 v[110:111], v[104:105], 0, v[138:139]
	v_lshl_add_u64 v[108:109], v[108:109], 0, v[90:91]
	v_lshl_add_u64 v[110:111], v[110:111], 0, v[90:91]
	s_waitcnt vmcnt(0)
	v_pk_mul_f32 v[112:113], v[6:7], v[106:107] op_sel_hi:[1,0]
	v_pk_mul_f32 v[114:115], v[8:9], v[106:107] op_sel_hi:[1,0]
	v_pk_mul_f32 v[116:117], v[2:3], v[106:107] op_sel_hi:[1,0]
	v_pk_mul_f32 v[118:119], v[4:5], v[106:107] op_sel_hi:[1,0]
	v_pk_fma_f32 v[84:85], v[114:115], v[84:85], v[28:29]
	v_pk_fma_f32 v[82:83], v[112:113], v[82:83], v[26:27]
	v_pk_mul_f32 v[120:121], v[30:31], v[106:107] op_sel_hi:[1,0]
	v_pk_mul_f32 v[122:123], v[32:33], v[106:107] op_sel_hi:[1,0]
	v_pk_mul_f32 v[124:125], v[14:15], v[106:107] op_sel_hi:[1,0]
	v_pk_mul_f32 v[106:107], v[16:17], v[106:107] op_sel_hi:[1,0]
	v_pk_fma_f32 v[88:89], v[118:119], v[88:89], v[24:25]
	v_pk_fma_f32 v[86:87], v[116:117], v[86:87], v[22:23]
	v_max_f32_e32 v83, 0, v83
	v_max_f32_e32 v82, 0, v82
	v_max_f32_e32 v85, 0, v85
	v_max_f32_e32 v84, 0, v84
	v_pk_fma_f32 v[94:95], v[122:123], v[94:95], v[20:21]
	v_pk_fma_f32 v[92:93], v[120:121], v[92:93], v[18:19]
	v_pk_fma_f32 v[98:99], v[106:107], v[98:99], v[12:13]
	v_pk_fma_f32 v[96:97], v[124:125], v[96:97], v[10:11]
	v_max_f32_e32 v87, 0, v87
	v_max_f32_e32 v86, 0, v86
	v_max_f32_e32 v89, 0, v89
	v_max_f32_e32 v88, 0, v88
	v_pk_mul_f32 v[84:85], v[84:85], v[84:85]
	v_pk_mul_f32 v[82:83], v[82:83], v[82:83]
	v_max_f32_e32 v93, 0, v93
	v_max_f32_e32 v92, 0, v92
	v_max_f32_e32 v95, 0, v95
	v_max_f32_e32 v94, 0, v94
	v_max_f32_e32 v97, 0, v97
	v_max_f32_e32 v96, 0, v96
	v_max_f32_e32 v99, 0, v99
	v_max_f32_e32 v98, 0, v98
	v_pk_mul_f32 v[88:89], v[88:89], v[88:89]
	v_pk_mul_f32 v[86:87], v[86:87], v[86:87]
	v_cvt_pk_bf16_f32 v82, v82, v83
	v_cvt_pk_bf16_f32 v83, v84, v85
	v_pk_mul_f32 v[94:95], v[94:95], v[94:95]
	v_cvt_pk_bf16_f32 v84, v86, v87
	v_cvt_pk_bf16_f32 v85, v88, v89
	v_pk_mul_f32 v[92:93], v[92:93], v[92:93]
	v_pk_mul_f32 v[98:99], v[98:99], v[98:99]
	v_pk_mul_f32 v[96:97], v[96:97], v[96:97]
	global_store_dwordx4 v[108:109], v[82:85], off sc1
	s_nop 1
	v_cvt_pk_bf16_f32 v82, v92, v93
	v_cvt_pk_bf16_f32 v83, v94, v95
	v_cvt_pk_bf16_f32 v84, v96, v97
	v_cvt_pk_bf16_f32 v85, v98, v99
	global_store_dwordx4 v[110:111], v[82:85], off sc1
	global_load_dword v82, v[100:101], off offset:576
	s_nop 0
	v_add_u32_e32 v83, 0x4800, v169
	v_and_b32_e32 v138, 0x6f80, v83
	v_lshl_add_u64 v[84:85], v[102:103], 0, v[138:139]
	v_lshl_add_u64 v[86:87], v[104:105], 0, v[138:139]
	v_lshl_add_u64 v[84:85], v[84:85], 0, v[90:91]
	v_lshl_add_u64 v[86:87], v[86:87], 0, v[90:91]
	s_waitcnt vmcnt(0)
	v_pk_mul_f32 v[88:89], v[6:7], v[82:83] op_sel_hi:[1,0]
	v_pk_mul_f32 v[92:93], v[8:9], v[82:83] op_sel_hi:[1,0]
	v_pk_mul_f32 v[94:95], v[2:3], v[82:83] op_sel_hi:[1,0]
	v_pk_mul_f32 v[96:97], v[4:5], v[82:83] op_sel_hi:[1,0]
	v_pk_fma_f32 v[68:69], v[92:93], v[68:69], v[28:29]
	v_pk_fma_f32 v[66:67], v[88:89], v[66:67], v[26:27]
	v_pk_mul_f32 v[98:99], v[30:31], v[82:83] op_sel_hi:[1,0]
	v_pk_mul_f32 v[106:107], v[32:33], v[82:83] op_sel_hi:[1,0]
	v_pk_mul_f32 v[108:109], v[14:15], v[82:83] op_sel_hi:[1,0]
	v_pk_mul_f32 v[82:83], v[16:17], v[82:83] op_sel_hi:[1,0]
	v_pk_fma_f32 v[72:73], v[96:97], v[72:73], v[24:25]
	v_pk_fma_f32 v[70:71], v[94:95], v[70:71], v[22:23]
	v_max_f32_e32 v67, 0, v67
	v_max_f32_e32 v66, 0, v66
	v_max_f32_e32 v69, 0, v69
	v_max_f32_e32 v68, 0, v68
	v_pk_fma_f32 v[76:77], v[106:107], v[76:77], v[20:21]
	v_pk_fma_f32 v[74:75], v[98:99], v[74:75], v[18:19]
	v_pk_fma_f32 v[80:81], v[82:83], v[80:81], v[12:13]
	v_pk_fma_f32 v[78:79], v[108:109], v[78:79], v[10:11]
	v_max_f32_e32 v71, 0, v71
	v_max_f32_e32 v70, 0, v70
	v_max_f32_e32 v73, 0, v73
	v_max_f32_e32 v72, 0, v72
	v_pk_mul_f32 v[68:69], v[68:69], v[68:69]
	v_pk_mul_f32 v[66:67], v[66:67], v[66:67]
	v_max_f32_e32 v75, 0, v75
	v_max_f32_e32 v74, 0, v74
	v_max_f32_e32 v77, 0, v77
	v_max_f32_e32 v76, 0, v76
	v_max_f32_e32 v79, 0, v79
	v_max_f32_e32 v78, 0, v78
	v_max_f32_e32 v81, 0, v81
	v_max_f32_e32 v80, 0, v80
	v_pk_mul_f32 v[72:73], v[72:73], v[72:73]
	v_pk_mul_f32 v[70:71], v[70:71], v[70:71]
	v_cvt_pk_bf16_f32 v66, v66, v67
	v_cvt_pk_bf16_f32 v67, v68, v69
	v_pk_mul_f32 v[76:77], v[76:77], v[76:77]
	v_cvt_pk_bf16_f32 v68, v70, v71
	v_cvt_pk_bf16_f32 v69, v72, v73
	v_pk_mul_f32 v[74:75], v[74:75], v[74:75]
	v_pk_mul_f32 v[80:81], v[80:81], v[80:81]
	v_pk_mul_f32 v[78:79], v[78:79], v[78:79]
	global_store_dwordx4 v[84:85], v[66:69], off sc1
	s_nop 1
	v_cvt_pk_bf16_f32 v66, v74, v75
	v_cvt_pk_bf16_f32 v67, v76, v77
	v_cvt_pk_bf16_f32 v68, v78, v79
	v_cvt_pk_bf16_f32 v69, v80, v81
	global_store_dwordx4 v[86:87], v[66:69], off sc1
	global_load_dword v66, v[100:101], off offset:640
	s_nop 0
	v_add_u32_e32 v67, 0x5000, v169
	v_and_b32_e32 v138, 0x7780, v67
	v_lshl_add_u64 v[68:69], v[102:103], 0, v[138:139]
	v_lshl_add_u64 v[70:71], v[104:105], 0, v[138:139]
	v_lshl_add_u64 v[68:69], v[68:69], 0, v[90:91]
	v_lshl_add_u64 v[70:71], v[70:71], 0, v[90:91]
	s_waitcnt vmcnt(0)
	v_pk_mul_f32 v[72:73], v[6:7], v[66:67] op_sel_hi:[1,0]
	v_pk_mul_f32 v[74:75], v[8:9], v[66:67] op_sel_hi:[1,0]
	v_pk_mul_f32 v[76:77], v[2:3], v[66:67] op_sel_hi:[1,0]
	v_pk_mul_f32 v[78:79], v[4:5], v[66:67] op_sel_hi:[1,0]
	v_pk_fma_f32 v[52:53], v[74:75], v[52:53], v[28:29]
	v_pk_fma_f32 v[50:51], v[72:73], v[50:51], v[26:27]
	v_pk_mul_f32 v[80:81], v[30:31], v[66:67] op_sel_hi:[1,0]
	v_pk_mul_f32 v[82:83], v[32:33], v[66:67] op_sel_hi:[1,0]
	v_pk_mul_f32 v[84:85], v[14:15], v[66:67] op_sel_hi:[1,0]
	v_pk_mul_f32 v[66:67], v[16:17], v[66:67] op_sel_hi:[1,0]
	v_pk_fma_f32 v[56:57], v[78:79], v[56:57], v[24:25]
	v_pk_fma_f32 v[54:55], v[76:77], v[54:55], v[22:23]
	v_max_f32_e32 v51, 0, v51
	v_max_f32_e32 v50, 0, v50
	v_max_f32_e32 v53, 0, v53
	v_max_f32_e32 v52, 0, v52
	v_pk_fma_f32 v[60:61], v[82:83], v[60:61], v[20:21]
	v_pk_fma_f32 v[58:59], v[80:81], v[58:59], v[18:19]
	v_pk_fma_f32 v[64:65], v[66:67], v[64:65], v[12:13]
	v_pk_fma_f32 v[62:63], v[84:85], v[62:63], v[10:11]
	v_max_f32_e32 v55, 0, v55
	v_max_f32_e32 v54, 0, v54
	v_max_f32_e32 v57, 0, v57
	v_max_f32_e32 v56, 0, v56
	v_pk_mul_f32 v[52:53], v[52:53], v[52:53]
	v_pk_mul_f32 v[50:51], v[50:51], v[50:51]
	v_max_f32_e32 v59, 0, v59
	v_max_f32_e32 v58, 0, v58
	v_max_f32_e32 v61, 0, v61
	v_max_f32_e32 v60, 0, v60
	v_max_f32_e32 v63, 0, v63
	v_max_f32_e32 v62, 0, v62
	v_max_f32_e32 v65, 0, v65
	v_max_f32_e32 v64, 0, v64
	v_pk_mul_f32 v[56:57], v[56:57], v[56:57]
	v_pk_mul_f32 v[54:55], v[54:55], v[54:55]
	v_cvt_pk_bf16_f32 v50, v50, v51
	v_cvt_pk_bf16_f32 v51, v52, v53
	v_pk_mul_f32 v[60:61], v[60:61], v[60:61]
	v_cvt_pk_bf16_f32 v52, v54, v55
	v_cvt_pk_bf16_f32 v53, v56, v57
	v_pk_mul_f32 v[58:59], v[58:59], v[58:59]
	v_pk_mul_f32 v[64:65], v[64:65], v[64:65]
	v_pk_mul_f32 v[62:63], v[62:63], v[62:63]
	global_store_dwordx4 v[68:69], v[50:53], off sc1
	s_nop 1
	v_cvt_pk_bf16_f32 v50, v58, v59
	v_cvt_pk_bf16_f32 v51, v60, v61
	v_cvt_pk_bf16_f32 v52, v62, v63
	v_cvt_pk_bf16_f32 v53, v64, v65
	global_store_dwordx4 v[70:71], v[50:53], off sc1
	global_load_dword v50, v[100:101], off offset:704
	s_nop 0
	v_add_u32_e32 v51, 0x5800, v169
	v_and_b32_e32 v138, 0x7f80, v51
	v_lshl_add_u64 v[52:53], v[102:103], 0, v[138:139]
	v_lshl_add_u64 v[54:55], v[104:105], 0, v[138:139]
	v_lshl_add_u64 v[52:53], v[52:53], 0, v[90:91]
	v_lshl_add_u64 v[54:55], v[54:55], 0, v[90:91]
	s_waitcnt vmcnt(0)
	v_pk_mul_f32 v[2:3], v[2:3], v[50:51] op_sel_hi:[1,0]
	v_pk_mul_f32 v[4:5], v[4:5], v[50:51] op_sel_hi:[1,0]
	v_pk_mul_f32 v[6:7], v[6:7], v[50:51] op_sel_hi:[1,0]
	v_pk_mul_f32 v[8:9], v[8:9], v[50:51] op_sel_hi:[1,0]
	v_pk_mul_f32 v[30:31], v[30:31], v[50:51] op_sel_hi:[1,0]
	v_pk_fma_f32 v[4:5], v[4:5], v[40:41], v[24:25]
	v_pk_fma_f32 v[2:3], v[2:3], v[38:39], v[22:23]
	v_pk_mul_f32 v[32:33], v[32:33], v[50:51] op_sel_hi:[1,0]
	v_pk_mul_f32 v[14:15], v[14:15], v[50:51] op_sel_hi:[1,0]
	v_pk_mul_f32 v[16:17], v[16:17], v[50:51] op_sel_hi:[1,0]
	v_pk_fma_f32 v[8:9], v[8:9], v[36:37], v[28:29]
	v_pk_fma_f32 v[6:7], v[6:7], v[34:35], v[26:27]
	v_pk_fma_f32 v[18:19], v[30:31], v[42:43], v[18:19]
	v_max_f32_e32 v3, 0, v3
	v_max_f32_e32 v2, 0, v2
	v_max_f32_e32 v5, 0, v5
	v_max_f32_e32 v4, 0, v4
	v_pk_fma_f32 v[20:21], v[32:33], v[44:45], v[20:21]
	v_pk_fma_f32 v[12:13], v[16:17], v[48:49], v[12:13]
	v_pk_fma_f32 v[10:11], v[14:15], v[46:47], v[10:11]
	v_max_f32_e32 v7, 0, v7
	v_max_f32_e32 v6, 0, v6
	v_max_f32_e32 v9, 0, v9
	v_max_f32_e32 v8, 0, v8
	v_max_f32_e32 v15, 0, v19
	v_max_f32_e32 v14, 0, v18
	v_pk_mul_f32 v[18:19], v[4:5], v[4:5]
	v_pk_mul_f32 v[4:5], v[2:3], v[2:3]
	v_max_f32_e32 v17, 0, v21
	v_max_f32_e32 v16, 0, v20
	v_max_f32_e32 v11, 0, v11
	v_max_f32_e32 v10, 0, v10
	v_max_f32_e32 v13, 0, v13
	v_max_f32_e32 v12, 0, v12
	v_pk_mul_f32 v[8:9], v[8:9], v[8:9]
	v_pk_mul_f32 v[6:7], v[6:7], v[6:7]
	v_pk_mul_f32 v[16:17], v[16:17], v[16:17]
	v_cvt_pk_bf16_f32 v2, v6, v7
	v_cvt_pk_bf16_f32 v3, v8, v9
	v_cvt_pk_bf16_f32 v4, v4, v5
	v_cvt_pk_bf16_f32 v5, v18, v19
	v_pk_mul_f32 v[14:15], v[14:15], v[14:15]
	v_pk_mul_f32 v[12:13], v[12:13], v[12:13]
	v_pk_mul_f32 v[10:11], v[10:11], v[10:11]
	global_store_dwordx4 v[52:53], v[2:5], off sc1
	s_nop 1
	v_cvt_pk_bf16_f32 v2, v14, v15
	v_cvt_pk_bf16_f32 v3, v16, v17
	v_cvt_pk_bf16_f32 v4, v10, v11
	v_cvt_pk_bf16_f32 v5, v12, v13
	global_store_dwordx4 v[54:55], v[2:5], off sc1
	s_cbranch_vccnz .LBB0_1074
	s_andn2_b64 vcc, exec, s[10:11]
	s_cbranch_vccnz .LBB0_1073
	s_barrier
	s_branch .LBB0_1073

.LBB0_1173:
	s_lshr_b32 s38, s89, 4
	s_add_i32 s38, s38, -1
	s_cmp_gt_i32 s89, 31
	s_cselect_b32 s38, s38, 0
	v_lshl_or_b32 v178, s12, 8, v208
	s_mul_i32 s43, s38, 0xc000
	s_mul_hi_i32 s42, s38, 0xc000
	s_add_u32 s38, s59, s43
	v_ashrrev_i32_e32 v179, 31, v178
	s_addc_u32 s39, s60, s42
	s_waitcnt lgkmcnt(0)
	v_lshlrev_b64 v[114:115], 2, v[178:179]
	v_lshl_add_u64 v[122:123], s[38:39], 0, v[114:115]
	s_add_u32 s38, s61, s43
	v_lshl_add_u32 v196, s89, 8, v206
	v_lshl_add_u64 v[116:117], s[24:25], 0, v[114:115]
	s_addc_u32 s39, s62, s42
	v_ashrrev_i32_e32 v197, 31, v196
	v_lshl_add_u64 v[124:125], s[38:39], 0, v[114:115]
	global_load_dwordx4 v[118:121], v[122:123], off offset:16
	global_load_dwordx4 v[126:129], v[122:123], off
	global_load_dwordx4 v[180:183], v[116:117], off offset:16
	global_load_dwordx4 v[184:187], v[116:117], off
	global_load_dwordx4 v[188:191], v[124:125], off offset:16
	global_load_dwordx4 v[192:195], v[124:125], off
	global_load_dwordx4 v[214:217], v[116:117], off offset:528
	global_load_dwordx4 v[218:221], v[116:117], off offset:512
	global_load_dwordx4 v[222:225], v[124:125], off offset:528
	global_load_dwordx4 v[226:229], v[124:125], off offset:512
	v_lshlrev_b64 v[116:117], 13, v[196:197]
	v_or_b32_e32 v198, 16, v196
	v_lshl_add_u64 v[116:117], s[20:21], 0, v[116:117]
	v_ashrrev_i32_e32 v199, 31, v198
	v_lshl_add_u64 v[200:201], v[116:117], 0, v[114:115]
	v_lshlrev_b64 v[116:117], 13, v[198:199]
	v_lshl_add_u64 v[116:117], s[20:21], 0, v[116:117]
	v_lshl_add_u64 v[202:203], v[116:117], 0, v[114:115]
	global_load_dwordx4 v[230:233], v[200:201], off offset:16 nt
	global_load_dwordx4 v[234:237], v[200:201], off nt
	global_load_dwordx4 v[238:241], v[200:201], off offset:528 nt
	global_load_dwordx4 v[242:245], v[200:201], off offset:512 nt
	global_load_dwordx4 v[154:157], v[202:203], off offset:16 nt
	global_load_dwordx4 v[158:161], v[202:203], off nt
	global_load_dwordx4 v[146:149], v[202:203], off offset:528 nt
	global_load_dwordx4 v[150:153], v[202:203], off offset:512 nt
	global_load_dwordx4 v[114:117], v[122:123], off offset:528
	s_nop 0
	global_load_dwordx4 v[122:125], v[122:123], off offset:512
	s_lshl_b32 s38, s12, 2
	s_ashr_i32 s39, s38, 31
	s_waitcnt vmcnt(0)
	v_pk_add_f32 v[190:191], v[190:191], 1.0 op_sel_hi:[1,0]
	v_pk_add_f32 v[194:195], v[194:195], 1.0 op_sel_hi:[1,0]
	v_pk_add_f32 v[204:205], v[192:193], 1.0 op_sel_hi:[1,0]
	v_pk_add_f32 v[246:247], v[188:189], 1.0 op_sel_hi:[1,0]
	v_pk_add_f32 v[224:225], v[224:225], 1.0 op_sel_hi:[1,0]
	v_pk_add_f32 v[228:229], v[228:229], 1.0 op_sel_hi:[1,0]
	v_pk_add_f32 v[226:227], v[226:227], 1.0 op_sel_hi:[1,0]
	v_pk_add_f32 v[222:223], v[222:223], 1.0 op_sel_hi:[1,0]
	v_pk_mul_f32 v[192:193], v[186:187], v[194:195]
	v_pk_mul_f32 v[194:195], v[184:185], v[204:205]
	v_pk_mul_f32 v[188:189], v[182:183], v[190:191]
	v_pk_mul_f32 v[190:191], v[180:181], v[246:247]
	v_pk_mul_f32 v[186:187], v[220:221], v[228:229]
	v_pk_mul_f32 v[184:185], v[218:219], v[226:227]
	v_pk_mul_f32 v[180:181], v[216:217], v[224:225]
	v_pk_mul_f32 v[182:183], v[214:215], v[222:223]
	v_pk_fma_f32 v[144:145], v[144:145], v[128:129], v[236:237]
	v_pk_fma_f32 v[142:143], v[142:143], v[126:127], v[234:235]
	v_mul_f32_e32 v205, v145, v145
	v_mul_f32_e32 v204, v143, v143
	v_pk_fma_f32 v[138:139], v[138:139], v[118:119], v[230:231]
	v_fmac_f32_e32 v204, v142, v142
	v_fmac_f32_e32 v205, v144, v144
	v_add_f32_e32 v204, v204, v205
	v_mul_f32_e32 v205, v139, v139
	v_pk_fma_f32 v[140:141], v[140:141], v[120:121], v[232:233]
	v_fmac_f32_e32 v205, v138, v138
	v_add_f32_e32 v204, v204, v205
	v_mul_f32_e32 v205, v141, v141
	global_store_dwordx4 v[200:201], v[142:145], off nt
	global_store_dwordx4 v[200:201], v[138:141], off offset:16 nt
	v_fmac_f32_e32 v205, v140, v140
	v_pk_mul_f32 v[142:143], v[194:195], v[142:143]
	v_add_f32_e32 v213, v205, v204
	v_pk_mul_f32 v[204:205], v[188:189], v[140:141]
	v_pk_mul_f32 v[140:141], v[190:191], v[138:139]
	v_cvt_pk_bf16_f32 v138, v142, v143
	v_lshlrev_b64 v[142:143], 12, v[196:197]
	v_lshl_add_u64 v[142:143], s[22:23], 0, v[142:143]
	v_pk_mul_f32 v[144:145], v[192:193], v[144:145]
	v_lshl_add_u64 v[142:143], v[178:179], 1, v[142:143]
	v_cvt_pk_bf16_f32 v139, v144, v145
	v_pk_fma_f32 v[136:137], v[136:137], v[124:125], v[244:245]
	v_pk_fma_f32 v[134:135], v[134:135], v[122:123], v[242:243]
	v_cvt_pk_bf16_f32 v140, v140, v141
	v_cvt_pk_bf16_f32 v141, v204, v205
	global_store_dwordx4 v[142:143], v[138:141], off sc1
	v_pk_fma_f32 v[130:131], v[130:131], v[114:115], v[238:239]
	v_pk_fma_f32 v[132:133], v[132:133], v[116:117], v[240:241]
	v_mul_f32_e32 v138, v135, v135
	v_mul_f32_e32 v139, v137, v137
	v_fmac_f32_e32 v138, v134, v134
	v_fmac_f32_e32 v139, v136, v136
	v_add_f32_e32 v138, v138, v139
	v_mul_f32_e32 v139, v131, v131
	v_fmac_f32_e32 v139, v130, v130
	v_add_f32_e32 v138, v138, v139
	v_mul_f32_e32 v139, v133, v133
	v_fmac_f32_e32 v139, v132, v132
	v_add_f32_e32 v138, v139, v138
	v_and_b32_e32 v139, 64, v212
	v_add_f32_e32 v144, v213, v138
	v_xor_b32_e32 v138, 16, v212
	v_add_u32_e32 v145, 64, v139
	v_cmp_lt_i32_e32 vcc, v138, v145
	global_store_dwordx4 v[200:201], v[134:137], off offset:512 nt
	global_store_dwordx4 v[200:201], v[130:133], off offset:528 nt
	v_cndmask_b32_e32 v138, v212, v138, vcc
	v_lshlrev_b32_e32 v213, 2, v138
	ds_bpermute_b32 v200, v213, v144
	v_pk_mul_f32 v[140:141], v[182:183], v[130:131]
	v_xor_b32_e32 v131, 32, v212
	v_cmp_lt_i32_e32 vcc, v131, v145
	v_pk_mul_f32 v[134:135], v[184:185], v[134:135]
	s_waitcnt lgkmcnt(0)
	v_add_f32_e32 v130, v144, v200
	v_cndmask_b32_e32 v131, v212, v131, vcc
	v_lshlrev_b32_e32 v214, 2, v131
	ds_bpermute_b32 v131, v214, v130
	v_pk_mul_f32 v[136:137], v[186:187], v[136:137]
	v_pk_mul_f32 v[138:139], v[180:181], v[132:133]
	v_cvt_pk_bf16_f32 v132, v134, v135
	v_cvt_pk_bf16_f32 v133, v136, v137
	v_cvt_pk_bf16_f32 v134, v140, v141
	s_nop 0
	v_cvt_pk_bf16_f32 v135, v138, v139
	global_store_dwordx4 v[142:143], v[132:135], off offset:256 sc1
	s_and_saveexec_b64 s[42:43], s[0:1]
	s_cbranch_execz .LBB0_1175
	s_waitcnt lgkmcnt(0)
	v_add_f32_e32 v132, v130, v131
	v_lshlrev_b64 v[130:131], 7, v[196:197]
	v_lshl_add_u64 v[130:131], s[26:27], 0, v[130:131]
	v_lshl_add_u64 v[130:131], s[38:39], 2, v[130:131]
	s_lshl_b32 s12, s63, 2
	v_lshl_add_u64 v[130:131], v[130:131], 0, s[12:13]
	global_store_dword v[130:131], v132, off
.LBB0_1175:
	s_or_b64 exec, exec, s[42:43]
	v_or_b32_e32 v200, 32, v196
	v_ashrrev_i32_e32 v201, 31, v200
	s_waitcnt lgkmcnt(0)
	v_lshlrev_b64 v[130:131], 13, v[200:201]
	v_lshl_add_u64 v[130:131], s[20:21], 0, v[130:131]
	v_lshl_add_u64 v[204:205], v[178:179], 2, v[130:131]
	global_load_dwordx4 v[138:141], v[204:205], off offset:16 nt
	global_load_dwordx4 v[142:145], v[204:205], off nt
	global_load_dwordx4 v[130:133], v[204:205], off offset:528 nt
	global_load_dwordx4 v[134:137], v[204:205], off offset:512 nt
	v_pk_fma_f32 v[112:113], v[112:113], v[128:129], v[160:161]
	v_pk_fma_f32 v[110:111], v[110:111], v[126:127], v[158:159]
	v_pk_fma_f32 v[106:107], v[106:107], v[118:119], v[154:155]
	v_mul_f32_e32 v154, v111, v111
	v_mul_f32_e32 v155, v113, v113
	v_fmac_f32_e32 v154, v110, v110
	v_fmac_f32_e32 v155, v112, v112
	v_add_f32_e32 v154, v154, v155
	v_mul_f32_e32 v155, v107, v107
	v_pk_fma_f32 v[108:109], v[108:109], v[120:121], v[156:157]
	v_fmac_f32_e32 v155, v106, v106
	v_add_f32_e32 v154, v154, v155
	v_mul_f32_e32 v155, v109, v109
	global_store_dwordx4 v[202:203], v[110:113], off nt
	global_store_dwordx4 v[202:203], v[106:109], off offset:16 nt
	v_fmac_f32_e32 v155, v108, v108
	v_pk_mul_f32 v[110:111], v[194:195], v[110:111]
	v_add_f32_e32 v156, v155, v154
	v_pk_mul_f32 v[154:155], v[188:189], v[108:109]
	v_pk_mul_f32 v[108:109], v[190:191], v[106:107]
	v_cvt_pk_bf16_f32 v106, v110, v111
	v_lshlrev_b64 v[110:111], 12, v[198:199]
	v_lshl_add_u64 v[110:111], s[22:23], 0, v[110:111]
	v_pk_mul_f32 v[112:113], v[192:193], v[112:113]
	v_lshl_add_u64 v[110:111], v[178:179], 1, v[110:111]
	v_cvt_pk_bf16_f32 v107, v112, v113
	v_pk_fma_f32 v[104:105], v[104:105], v[124:125], v[152:153]
	v_pk_fma_f32 v[102:103], v[102:103], v[122:123], v[150:151]
	v_cvt_pk_bf16_f32 v108, v108, v109
	v_cvt_pk_bf16_f32 v109, v154, v155
	global_store_dwordx4 v[110:111], v[106:109], off sc1
	v_pk_fma_f32 v[98:99], v[98:99], v[114:115], v[146:147]
	v_pk_fma_f32 v[100:101], v[100:101], v[116:117], v[148:149]
	v_mul_f32_e32 v106, v103, v103
	v_mul_f32_e32 v107, v105, v105
	v_fmac_f32_e32 v106, v102, v102
	v_fmac_f32_e32 v107, v104, v104
	v_add_f32_e32 v106, v106, v107
	v_mul_f32_e32 v107, v99, v99
	v_fmac_f32_e32 v107, v98, v98
	v_add_f32_e32 v106, v106, v107
	v_mul_f32_e32 v107, v101, v101
	v_fmac_f32_e32 v107, v100, v100
	v_add_f32_e32 v106, v107, v106
	v_add_f32_e32 v112, v156, v106
	ds_bpermute_b32 v113, v213, v112
	global_store_dwordx4 v[202:203], v[102:105], off offset:512 nt
	global_store_dwordx4 v[202:203], v[98:101], off offset:528 nt
	v_pk_mul_f32 v[108:109], v[182:183], v[98:99]
	v_pk_mul_f32 v[102:103], v[184:185], v[102:103]
	v_pk_mul_f32 v[104:105], v[186:187], v[104:105]
	s_waitcnt lgkmcnt(0)
	v_add_f32_e32 v98, v112, v113
	ds_bpermute_b32 v99, v214, v98
	v_pk_mul_f32 v[106:107], v[180:181], v[100:101]
	v_cvt_pk_bf16_f32 v100, v102, v103
	v_cvt_pk_bf16_f32 v101, v104, v105
	v_cvt_pk_bf16_f32 v102, v108, v109
	s_nop 0
	v_cvt_pk_bf16_f32 v103, v106, v107
	global_store_dwordx4 v[110:111], v[100:103], off offset:256 sc1
	s_and_saveexec_b64 s[42:43], s[0:1]
	s_cbranch_execz .LBB0_1177
	s_waitcnt lgkmcnt(0)
	v_add_f32_e32 v100, v98, v99
	v_lshlrev_b64 v[98:99], 7, v[198:199]
	v_lshl_add_u64 v[98:99], s[26:27], 0, v[98:99]
	v_lshl_add_u64 v[98:99], s[38:39], 2, v[98:99]
	s_lshl_b32 s12, s63, 2
	v_lshl_add_u64 v[98:99], v[98:99], 0, s[12:13]
	global_store_dword v[98:99], v100, off
.LBB0_1177:
	s_or_b64 exec, exec, s[42:43]
	v_or_b32_e32 v146, 48, v196
	v_ashrrev_i32_e32 v147, 31, v146
	s_waitcnt lgkmcnt(0)
	v_lshlrev_b64 v[98:99], 13, v[146:147]
	v_lshl_add_u64 v[98:99], s[20:21], 0, v[98:99]
	v_lshl_add_u64 v[148:149], v[178:179], 2, v[98:99]
	global_load_dwordx4 v[106:109], v[148:149], off offset:16 nt
	global_load_dwordx4 v[110:113], v[148:149], off nt
	global_load_dwordx4 v[98:101], v[148:149], off offset:528 nt
	global_load_dwordx4 v[102:105], v[148:149], off offset:512 nt
	s_waitcnt vmcnt(12)
	v_pk_fma_f32 v[96:97], v[96:97], v[128:129], v[144:145]
	v_pk_fma_f32 v[94:95], v[94:95], v[126:127], v[142:143]
	v_pk_fma_f32 v[90:91], v[90:91], v[118:119], v[138:139]
	v_mul_f32_e32 v138, v95, v95
	v_mul_f32_e32 v139, v97, v97
	v_fmac_f32_e32 v138, v94, v94
	v_fmac_f32_e32 v139, v96, v96
	v_add_f32_e32 v138, v138, v139
	v_mul_f32_e32 v139, v91, v91
	v_pk_fma_f32 v[92:93], v[92:93], v[120:121], v[140:141]
	v_fmac_f32_e32 v139, v90, v90
	v_add_f32_e32 v138, v138, v139
	v_mul_f32_e32 v139, v93, v93
	global_store_dwordx4 v[204:205], v[94:97], off nt
	global_store_dwordx4 v[204:205], v[90:93], off offset:16 nt
	v_fmac_f32_e32 v139, v92, v92
	v_pk_mul_f32 v[94:95], v[194:195], v[94:95]
	v_add_f32_e32 v140, v139, v138
	v_pk_mul_f32 v[138:139], v[188:189], v[92:93]
	v_pk_mul_f32 v[92:93], v[190:191], v[90:91]
	v_cvt_pk_bf16_f32 v90, v94, v95
	v_lshlrev_b64 v[94:95], 12, v[200:201]
	v_lshl_add_u64 v[94:95], s[22:23], 0, v[94:95]
	v_pk_mul_f32 v[96:97], v[192:193], v[96:97]
	v_lshl_add_u64 v[94:95], v[178:179], 1, v[94:95]
	v_cvt_pk_bf16_f32 v91, v96, v97
	s_waitcnt vmcnt(12)
	v_pk_fma_f32 v[88:89], v[88:89], v[124:125], v[136:137]
	v_pk_fma_f32 v[86:87], v[86:87], v[122:123], v[134:135]
	v_cvt_pk_bf16_f32 v92, v92, v93
	v_cvt_pk_bf16_f32 v93, v138, v139
	global_store_dwordx4 v[94:95], v[90:93], off sc1
	v_pk_fma_f32 v[82:83], v[82:83], v[114:115], v[130:131]
	v_pk_fma_f32 v[84:85], v[84:85], v[116:117], v[132:133]
	v_mul_f32_e32 v90, v87, v87
	v_mul_f32_e32 v91, v89, v89
	v_fmac_f32_e32 v90, v86, v86
	v_fmac_f32_e32 v91, v88, v88
	v_add_f32_e32 v90, v90, v91
	v_mul_f32_e32 v91, v83, v83
	v_fmac_f32_e32 v91, v82, v82
	v_add_f32_e32 v90, v90, v91
	v_mul_f32_e32 v91, v85, v85
	v_fmac_f32_e32 v91, v84, v84
	v_add_f32_e32 v90, v91, v90
	v_add_f32_e32 v96, v140, v90
	ds_bpermute_b32 v97, v213, v96
	global_store_dwordx4 v[204:205], v[86:89], off offset:512 nt
	global_store_dwordx4 v[204:205], v[82:85], off offset:528 nt
	v_pk_mul_f32 v[92:93], v[182:183], v[82:83]
	v_pk_mul_f32 v[86:87], v[184:185], v[86:87]
	v_pk_mul_f32 v[88:89], v[186:187], v[88:89]
	s_waitcnt lgkmcnt(0)
	v_add_f32_e32 v82, v96, v97
	ds_bpermute_b32 v83, v214, v82
	v_pk_mul_f32 v[90:91], v[180:181], v[84:85]
	v_cvt_pk_bf16_f32 v84, v86, v87
	v_cvt_pk_bf16_f32 v85, v88, v89
	v_cvt_pk_bf16_f32 v86, v92, v93
	s_nop 0
	v_cvt_pk_bf16_f32 v87, v90, v91
	global_store_dwordx4 v[94:95], v[84:87], off offset:256 sc1
	s_and_saveexec_b64 s[42:43], s[0:1]
	s_cbranch_execz .LBB0_1179
	s_waitcnt lgkmcnt(0)
	v_add_f32_e32 v84, v82, v83
	v_lshlrev_b64 v[82:83], 7, v[200:201]
	v_lshl_add_u64 v[82:83], s[26:27], 0, v[82:83]
	v_lshl_add_u64 v[82:83], s[38:39], 2, v[82:83]
	s_lshl_b32 s12, s63, 2
	v_lshl_add_u64 v[82:83], v[82:83], 0, s[12:13]
	global_store_dword v[82:83], v84, off
.LBB0_1179:
	s_or_b64 exec, exec, s[42:43]
	v_add_u32_e32 v130, 0x80, v196
	v_ashrrev_i32_e32 v131, 31, v130
	s_waitcnt lgkmcnt(0)
	v_lshlrev_b64 v[82:83], 13, v[130:131]
	v_lshl_add_u64 v[82:83], s[20:21], 0, v[82:83]
	v_lshl_add_u64 v[132:133], v[178:179], 2, v[82:83]
	global_load_dwordx4 v[90:93], v[132:133], off offset:16 nt
	global_load_dwordx4 v[94:97], v[132:133], off nt
	global_load_dwordx4 v[82:85], v[132:133], off offset:528 nt
	global_load_dwordx4 v[86:89], v[132:133], off offset:512 nt
	s_waitcnt vmcnt(12)
	v_pk_fma_f32 v[80:81], v[80:81], v[128:129], v[112:113]
	v_pk_fma_f32 v[78:79], v[78:79], v[126:127], v[110:111]
	v_pk_fma_f32 v[74:75], v[74:75], v[118:119], v[106:107]
	v_mul_f32_e32 v106, v79, v79
	v_mul_f32_e32 v107, v81, v81
	v_fmac_f32_e32 v106, v78, v78
	v_fmac_f32_e32 v107, v80, v80
	v_add_f32_e32 v106, v106, v107
	v_mul_f32_e32 v107, v75, v75
	v_pk_fma_f32 v[76:77], v[76:77], v[120:121], v[108:109]
	v_fmac_f32_e32 v107, v74, v74
	v_add_f32_e32 v106, v106, v107
	v_mul_f32_e32 v107, v77, v77
	global_store_dwordx4 v[148:149], v[78:81], off nt
	global_store_dwordx4 v[148:149], v[74:77], off offset:16 nt
	v_fmac_f32_e32 v107, v76, v76
	v_pk_mul_f32 v[78:79], v[194:195], v[78:79]
	v_add_f32_e32 v108, v107, v106
	v_pk_mul_f32 v[106:107], v[188:189], v[76:77]
	v_pk_mul_f32 v[76:77], v[190:191], v[74:75]
	v_cvt_pk_bf16_f32 v74, v78, v79
	v_lshlrev_b64 v[78:79], 12, v[146:147]
	v_lshl_add_u64 v[78:79], s[22:23], 0, v[78:79]
	v_pk_mul_f32 v[80:81], v[192:193], v[80:81]
	v_lshl_add_u64 v[78:79], v[178:179], 1, v[78:79]
	v_cvt_pk_bf16_f32 v75, v80, v81
	s_waitcnt vmcnt(12)
	v_pk_fma_f32 v[72:73], v[72:73], v[124:125], v[104:105]
	v_pk_fma_f32 v[70:71], v[70:71], v[122:123], v[102:103]
	v_cvt_pk_bf16_f32 v76, v76, v77
	v_cvt_pk_bf16_f32 v77, v106, v107
	global_store_dwordx4 v[78:79], v[74:77], off sc1
	v_pk_fma_f32 v[66:67], v[66:67], v[114:115], v[98:99]
	v_pk_fma_f32 v[68:69], v[68:69], v[116:117], v[100:101]
	v_mul_f32_e32 v74, v71, v71
	v_mul_f32_e32 v75, v73, v73
	v_fmac_f32_e32 v74, v70, v70
	v_fmac_f32_e32 v75, v72, v72
	v_add_f32_e32 v74, v74, v75
	v_mul_f32_e32 v75, v67, v67
	v_fmac_f32_e32 v75, v66, v66
	v_add_f32_e32 v74, v74, v75
	v_mul_f32_e32 v75, v69, v69
	v_fmac_f32_e32 v75, v68, v68
	v_add_f32_e32 v74, v75, v74
	v_add_f32_e32 v80, v108, v74
	ds_bpermute_b32 v81, v213, v80
	global_store_dwordx4 v[148:149], v[70:73], off offset:512 nt
	global_store_dwordx4 v[148:149], v[66:69], off offset:528 nt
	v_pk_mul_f32 v[76:77], v[182:183], v[66:67]
	v_pk_mul_f32 v[70:71], v[184:185], v[70:71]
	v_pk_mul_f32 v[72:73], v[186:187], v[72:73]
	s_waitcnt lgkmcnt(0)
	v_add_f32_e32 v66, v80, v81
	ds_bpermute_b32 v67, v214, v66
	v_pk_mul_f32 v[74:75], v[180:181], v[68:69]
	v_cvt_pk_bf16_f32 v68, v70, v71
	v_cvt_pk_bf16_f32 v69, v72, v73
	v_cvt_pk_bf16_f32 v70, v76, v77
	s_nop 0
	v_cvt_pk_bf16_f32 v71, v74, v75
	global_store_dwordx4 v[78:79], v[68:71], off offset:256 sc1
	s_and_saveexec_b64 s[42:43], s[0:1]
	s_cbranch_execz .LBB0_1181
	s_waitcnt lgkmcnt(0)
	v_add_f32_e32 v68, v66, v67
	v_lshlrev_b64 v[66:67], 7, v[146:147]
	v_lshl_add_u64 v[66:67], s[26:27], 0, v[66:67]
	v_lshl_add_u64 v[66:67], s[38:39], 2, v[66:67]
	s_lshl_b32 s12, s63, 2
	v_lshl_add_u64 v[66:67], v[66:67], 0, s[12:13]
	global_store_dword v[66:67], v68, off
.LBB0_1181:
	s_or_b64 exec, exec, s[42:43]
	v_or_b32_e32 v98, 16, v130
	v_ashrrev_i32_e32 v99, 31, v98
	s_waitcnt lgkmcnt(0)
	v_lshlrev_b64 v[66:67], 13, v[98:99]
	v_lshl_add_u64 v[66:67], s[20:21], 0, v[66:67]
	v_lshl_add_u64 v[100:101], v[178:179], 2, v[66:67]
	global_load_dwordx4 v[74:77], v[100:101], off offset:16 nt
	global_load_dwordx4 v[78:81], v[100:101], off nt
	global_load_dwordx4 v[66:69], v[100:101], off offset:528 nt
	global_load_dwordx4 v[70:73], v[100:101], off offset:512 nt
	s_waitcnt vmcnt(12)
	v_pk_fma_f32 v[64:65], v[64:65], v[128:129], v[96:97]
	v_pk_fma_f32 v[62:63], v[62:63], v[126:127], v[94:95]
	v_pk_fma_f32 v[58:59], v[58:59], v[118:119], v[90:91]
	v_mul_f32_e32 v90, v63, v63
	v_mul_f32_e32 v91, v65, v65
	v_fmac_f32_e32 v90, v62, v62
	v_fmac_f32_e32 v91, v64, v64
	v_add_f32_e32 v90, v90, v91
	v_mul_f32_e32 v91, v59, v59
	v_pk_fma_f32 v[60:61], v[60:61], v[120:121], v[92:93]
	v_fmac_f32_e32 v91, v58, v58
	v_add_f32_e32 v90, v90, v91
	v_mul_f32_e32 v91, v61, v61
	global_store_dwordx4 v[132:133], v[62:65], off nt
	global_store_dwordx4 v[132:133], v[58:61], off offset:16 nt
	v_fmac_f32_e32 v91, v60, v60
	v_pk_mul_f32 v[62:63], v[194:195], v[62:63]
	v_add_f32_e32 v92, v91, v90
	v_pk_mul_f32 v[90:91], v[188:189], v[60:61]
	v_pk_mul_f32 v[60:61], v[190:191], v[58:59]
	v_cvt_pk_bf16_f32 v58, v62, v63
	v_lshlrev_b64 v[62:63], 12, v[130:131]
	v_lshl_add_u64 v[62:63], s[22:23], 0, v[62:63]
	v_pk_mul_f32 v[64:65], v[192:193], v[64:65]
	v_lshl_add_u64 v[62:63], v[178:179], 1, v[62:63]
	v_cvt_pk_bf16_f32 v59, v64, v65
	s_waitcnt vmcnt(12)
	v_pk_fma_f32 v[56:57], v[56:57], v[124:125], v[88:89]
	v_pk_fma_f32 v[54:55], v[54:55], v[122:123], v[86:87]
	v_cvt_pk_bf16_f32 v60, v60, v61
	v_cvt_pk_bf16_f32 v61, v90, v91
	global_store_dwordx4 v[62:63], v[58:61], off sc1
	v_pk_fma_f32 v[50:51], v[50:51], v[114:115], v[82:83]
	v_pk_fma_f32 v[52:53], v[52:53], v[116:117], v[84:85]
	v_mul_f32_e32 v58, v55, v55
	v_mul_f32_e32 v59, v57, v57
	v_fmac_f32_e32 v58, v54, v54
	v_fmac_f32_e32 v59, v56, v56
	v_add_f32_e32 v58, v58, v59
	v_mul_f32_e32 v59, v51, v51
	v_fmac_f32_e32 v59, v50, v50
	v_add_f32_e32 v58, v58, v59
	v_mul_f32_e32 v59, v53, v53
	v_fmac_f32_e32 v59, v52, v52
	v_add_f32_e32 v58, v59, v58
	v_add_f32_e32 v64, v92, v58
	ds_bpermute_b32 v65, v213, v64
	global_store_dwordx4 v[132:133], v[54:57], off offset:512 nt
	global_store_dwordx4 v[132:133], v[50:53], off offset:528 nt
	v_pk_mul_f32 v[60:61], v[182:183], v[50:51]
	v_pk_mul_f32 v[54:55], v[184:185], v[54:55]
	v_pk_mul_f32 v[56:57], v[186:187], v[56:57]
	s_waitcnt lgkmcnt(0)
	v_add_f32_e32 v50, v64, v65
	ds_bpermute_b32 v51, v214, v50
	v_pk_mul_f32 v[58:59], v[180:181], v[52:53]
	v_cvt_pk_bf16_f32 v52, v54, v55
	v_cvt_pk_bf16_f32 v53, v56, v57
	v_cvt_pk_bf16_f32 v54, v60, v61
	s_nop 0
	v_cvt_pk_bf16_f32 v55, v58, v59
	global_store_dwordx4 v[62:63], v[52:55], off offset:256 sc1
	s_and_saveexec_b64 s[42:43], s[0:1]
	s_cbranch_execz .LBB0_1183
	s_waitcnt lgkmcnt(0)
	v_add_f32_e32 v52, v50, v51
	v_lshlrev_b64 v[50:51], 7, v[130:131]
	v_lshl_add_u64 v[50:51], s[26:27], 0, v[50:51]
	v_lshl_add_u64 v[50:51], s[38:39], 2, v[50:51]
	s_lshl_b32 s12, s63, 2
	v_lshl_add_u64 v[50:51], v[50:51], 0, s[12:13]
	global_store_dword v[50:51], v52, off
.LBB0_1183:
	s_or_b64 exec, exec, s[42:43]
	v_or_b32_e32 v82, 32, v130
	v_ashrrev_i32_e32 v83, 31, v82
	s_waitcnt lgkmcnt(0)
	v_lshlrev_b64 v[50:51], 13, v[82:83]
	v_lshl_add_u64 v[50:51], s[20:21], 0, v[50:51]
	v_lshl_add_u64 v[84:85], v[178:179], 2, v[50:51]
	global_load_dwordx4 v[58:61], v[84:85], off offset:16 nt
	global_load_dwordx4 v[62:65], v[84:85], off nt
	global_load_dwordx4 v[50:53], v[84:85], off offset:528 nt
	global_load_dwordx4 v[54:57], v[84:85], off offset:512 nt
	s_waitcnt vmcnt(12)
	v_pk_fma_f32 v[48:49], v[48:49], v[128:129], v[80:81]
	v_pk_fma_f32 v[46:47], v[46:47], v[126:127], v[78:79]
	v_pk_fma_f32 v[42:43], v[42:43], v[118:119], v[74:75]
	v_mul_f32_e32 v74, v47, v47
	v_mul_f32_e32 v75, v49, v49
	v_fmac_f32_e32 v74, v46, v46
	v_fmac_f32_e32 v75, v48, v48
	v_add_f32_e32 v74, v74, v75
	v_mul_f32_e32 v75, v43, v43
	v_pk_fma_f32 v[44:45], v[44:45], v[120:121], v[76:77]
	v_fmac_f32_e32 v75, v42, v42
	v_add_f32_e32 v74, v74, v75
	v_mul_f32_e32 v75, v45, v45
	global_store_dwordx4 v[100:101], v[46:49], off nt
	global_store_dwordx4 v[100:101], v[42:45], off offset:16 nt
	v_fmac_f32_e32 v75, v44, v44
	v_pk_mul_f32 v[46:47], v[194:195], v[46:47]
	v_add_f32_e32 v76, v75, v74
	v_pk_mul_f32 v[74:75], v[188:189], v[44:45]
	v_pk_mul_f32 v[44:45], v[190:191], v[42:43]
	v_cvt_pk_bf16_f32 v42, v46, v47
	v_lshlrev_b64 v[46:47], 12, v[98:99]
	v_lshl_add_u64 v[46:47], s[22:23], 0, v[46:47]
	v_pk_mul_f32 v[48:49], v[192:193], v[48:49]
	v_lshl_add_u64 v[46:47], v[178:179], 1, v[46:47]
	v_cvt_pk_bf16_f32 v43, v48, v49
	s_waitcnt vmcnt(12)
	v_pk_fma_f32 v[40:41], v[40:41], v[124:125], v[72:73]
	v_pk_fma_f32 v[38:39], v[38:39], v[122:123], v[70:71]
	v_cvt_pk_bf16_f32 v44, v44, v45
	v_cvt_pk_bf16_f32 v45, v74, v75
	global_store_dwordx4 v[46:47], v[42:45], off sc1
	v_pk_fma_f32 v[34:35], v[34:35], v[114:115], v[66:67]
	v_pk_fma_f32 v[36:37], v[36:37], v[116:117], v[68:69]
	v_mul_f32_e32 v42, v39, v39
	v_mul_f32_e32 v43, v41, v41
	v_fmac_f32_e32 v42, v38, v38
	v_fmac_f32_e32 v43, v40, v40
	v_add_f32_e32 v42, v42, v43
	v_mul_f32_e32 v43, v35, v35
	v_fmac_f32_e32 v43, v34, v34
	v_add_f32_e32 v42, v42, v43
	v_mul_f32_e32 v43, v37, v37
	v_fmac_f32_e32 v43, v36, v36
	v_add_f32_e32 v42, v43, v42
	v_add_f32_e32 v48, v76, v42
	ds_bpermute_b32 v49, v213, v48
	global_store_dwordx4 v[100:101], v[38:41], off offset:512 nt
	global_store_dwordx4 v[100:101], v[34:37], off offset:528 nt
	v_pk_mul_f32 v[44:45], v[182:183], v[34:35]
	v_pk_mul_f32 v[38:39], v[184:185], v[38:39]
	v_pk_mul_f32 v[40:41], v[186:187], v[40:41]
	s_waitcnt lgkmcnt(0)
	v_add_f32_e32 v34, v48, v49
	ds_bpermute_b32 v35, v214, v34
	v_pk_mul_f32 v[42:43], v[180:181], v[36:37]
	v_cvt_pk_bf16_f32 v36, v38, v39
	v_cvt_pk_bf16_f32 v37, v40, v41
	v_cvt_pk_bf16_f32 v38, v44, v45
	s_nop 0
	v_cvt_pk_bf16_f32 v39, v42, v43
	global_store_dwordx4 v[46:47], v[36:39], off offset:256 sc1
	s_and_saveexec_b64 s[42:43], s[0:1]
	s_cbranch_execz .LBB0_1185
	s_waitcnt lgkmcnt(0)
	v_add_f32_e32 v36, v34, v35
	v_lshlrev_b64 v[34:35], 7, v[98:99]
	v_lshl_add_u64 v[34:35], s[26:27], 0, v[34:35]
	v_lshl_add_u64 v[34:35], s[38:39], 2, v[34:35]
	s_lshl_b32 s12, s63, 2
	v_lshl_add_u64 v[34:35], v[34:35], 0, s[12:13]
	global_store_dword v[34:35], v36, off
.LBB0_1185:
	s_or_b64 exec, exec, s[42:43]
	v_or_b32_e32 v66, 48, v130
	v_ashrrev_i32_e32 v67, 31, v66
	s_waitcnt lgkmcnt(0)
	v_lshlrev_b64 v[34:35], 13, v[66:67]
	v_lshl_add_u64 v[34:35], s[20:21], 0, v[34:35]
	v_lshl_add_u64 v[68:69], v[178:179], 2, v[34:35]
	global_load_dwordx4 v[42:45], v[68:69], off offset:16 nt
	global_load_dwordx4 v[46:49], v[68:69], off nt
	global_load_dwordx4 v[34:37], v[68:69], off offset:528 nt
	global_load_dwordx4 v[38:41], v[68:69], off offset:512 nt
	s_waitcnt vmcnt(12)
	v_pk_fma_f32 v[32:33], v[32:33], v[128:129], v[64:65]
	v_pk_fma_f32 v[30:31], v[30:31], v[126:127], v[62:63]
	v_pk_fma_f32 v[26:27], v[26:27], v[118:119], v[58:59]
	v_mul_f32_e32 v58, v31, v31
	v_mul_f32_e32 v59, v33, v33
	v_fmac_f32_e32 v58, v30, v30
	v_fmac_f32_e32 v59, v32, v32
	v_add_f32_e32 v58, v58, v59
	v_mul_f32_e32 v59, v27, v27
	v_pk_fma_f32 v[28:29], v[28:29], v[120:121], v[60:61]
	v_fmac_f32_e32 v59, v26, v26
	v_add_f32_e32 v58, v58, v59
	v_mul_f32_e32 v59, v29, v29
	global_store_dwordx4 v[84:85], v[30:33], off nt
	global_store_dwordx4 v[84:85], v[26:29], off offset:16 nt
	v_fmac_f32_e32 v59, v28, v28
	v_pk_mul_f32 v[30:31], v[194:195], v[30:31]
	v_add_f32_e32 v60, v59, v58
	v_pk_mul_f32 v[58:59], v[188:189], v[28:29]
	v_pk_mul_f32 v[28:29], v[190:191], v[26:27]
	v_cvt_pk_bf16_f32 v26, v30, v31
	v_lshlrev_b64 v[30:31], 12, v[82:83]
	v_lshl_add_u64 v[30:31], s[22:23], 0, v[30:31]
	v_pk_mul_f32 v[32:33], v[192:193], v[32:33]
	v_lshl_add_u64 v[30:31], v[178:179], 1, v[30:31]
	v_cvt_pk_bf16_f32 v27, v32, v33
	s_waitcnt vmcnt(12)
	v_pk_fma_f32 v[24:25], v[24:25], v[124:125], v[56:57]
	v_pk_fma_f32 v[22:23], v[22:23], v[122:123], v[54:55]
	v_cvt_pk_bf16_f32 v28, v28, v29
	v_cvt_pk_bf16_f32 v29, v58, v59
	global_store_dwordx4 v[30:31], v[26:29], off sc1
	v_pk_fma_f32 v[18:19], v[18:19], v[114:115], v[50:51]
	v_pk_fma_f32 v[20:21], v[20:21], v[116:117], v[52:53]
	v_mul_f32_e32 v26, v23, v23
	v_mul_f32_e32 v27, v25, v25
	v_fmac_f32_e32 v26, v22, v22
	v_fmac_f32_e32 v27, v24, v24
	v_add_f32_e32 v26, v26, v27
	v_mul_f32_e32 v27, v19, v19
	v_fmac_f32_e32 v27, v18, v18
	v_add_f32_e32 v26, v26, v27
	v_mul_f32_e32 v27, v21, v21
	v_fmac_f32_e32 v27, v20, v20
	v_add_f32_e32 v26, v27, v26
	v_add_f32_e32 v32, v60, v26
	ds_bpermute_b32 v33, v213, v32
	global_store_dwordx4 v[84:85], v[22:25], off offset:512 nt
	global_store_dwordx4 v[84:85], v[18:21], off offset:528 nt
	v_pk_mul_f32 v[28:29], v[182:183], v[18:19]
	v_pk_mul_f32 v[22:23], v[184:185], v[22:23]
	v_pk_mul_f32 v[24:25], v[186:187], v[24:25]
	s_waitcnt lgkmcnt(0)
	v_add_f32_e32 v18, v32, v33
	ds_bpermute_b32 v19, v214, v18
	v_pk_mul_f32 v[26:27], v[180:181], v[20:21]
	v_cvt_pk_bf16_f32 v20, v22, v23
	v_cvt_pk_bf16_f32 v21, v24, v25
	v_cvt_pk_bf16_f32 v22, v28, v29
	s_nop 0
	v_cvt_pk_bf16_f32 v23, v26, v27
	global_store_dwordx4 v[30:31], v[20:23], off offset:256 sc1
	s_and_saveexec_b64 s[42:43], s[0:1]
	s_cbranch_execz .LBB0_1187
	s_waitcnt lgkmcnt(0)
	v_add_f32_e32 v20, v18, v19
	v_lshlrev_b64 v[18:19], 7, v[82:83]
	v_lshl_add_u64 v[18:19], s[26:27], 0, v[18:19]
	v_lshl_add_u64 v[18:19], s[38:39], 2, v[18:19]
	s_lshl_b32 s12, s63, 2
	v_lshl_add_u64 v[18:19], v[18:19], 0, s[12:13]
	global_store_dword v[18:19], v20, off
.LBB0_1187:
	s_or_b64 exec, exec, s[42:43]
	s_waitcnt vmcnt(8)
	v_pk_fma_f32 v[16:17], v[16:17], v[128:129], v[48:49]
	v_pk_fma_f32 v[14:15], v[14:15], v[126:127], v[46:47]
	s_waitcnt lgkmcnt(0)
	v_mul_f32_e32 v19, v17, v17
	v_mul_f32_e32 v18, v15, v15
	v_pk_fma_f32 v[10:11], v[10:11], v[118:119], v[42:43]
	v_fmac_f32_e32 v18, v14, v14
	v_fmac_f32_e32 v19, v16, v16
	v_add_f32_e32 v18, v18, v19
	v_mul_f32_e32 v19, v11, v11
	v_pk_fma_f32 v[12:13], v[12:13], v[120:121], v[44:45]
	v_fmac_f32_e32 v19, v10, v10
	v_add_f32_e32 v18, v18, v19
	v_mul_f32_e32 v19, v13, v13
	global_store_dwordx4 v[68:69], v[14:17], off nt
	global_store_dwordx4 v[68:69], v[10:13], off offset:16 nt
	v_fmac_f32_e32 v19, v12, v12
	v_pk_mul_f32 v[14:15], v[194:195], v[14:15]
	v_add_f32_e32 v20, v19, v18
	v_pk_mul_f32 v[18:19], v[188:189], v[12:13]
	v_pk_mul_f32 v[12:13], v[190:191], v[10:11]
	v_cvt_pk_bf16_f32 v10, v14, v15
	v_lshlrev_b64 v[14:15], 12, v[66:67]
	v_lshl_add_u64 v[14:15], s[22:23], 0, v[14:15]
	v_pk_mul_f32 v[16:17], v[192:193], v[16:17]
	v_lshl_add_u64 v[14:15], v[178:179], 1, v[14:15]
	v_cvt_pk_bf16_f32 v11, v16, v17
	s_waitcnt vmcnt(8)
	v_pk_fma_f32 v[8:9], v[8:9], v[124:125], v[40:41]
	v_pk_fma_f32 v[6:7], v[6:7], v[122:123], v[38:39]
	v_cvt_pk_bf16_f32 v12, v12, v13
	v_cvt_pk_bf16_f32 v13, v18, v19
	global_store_dwordx4 v[14:15], v[10:13], off sc1
	v_pk_fma_f32 v[2:3], v[2:3], v[114:115], v[34:35]
	v_pk_fma_f32 v[4:5], v[4:5], v[116:117], v[36:37]
	v_mul_f32_e32 v10, v7, v7
	v_mul_f32_e32 v11, v9, v9
	v_fmac_f32_e32 v10, v6, v6
	v_fmac_f32_e32 v11, v8, v8
	v_add_f32_e32 v10, v10, v11
	v_mul_f32_e32 v11, v3, v3
	v_fmac_f32_e32 v11, v2, v2
	v_add_f32_e32 v10, v10, v11
	v_mul_f32_e32 v11, v5, v5
	v_fmac_f32_e32 v11, v4, v4
	v_add_f32_e32 v10, v11, v10
	v_add_f32_e32 v16, v20, v10
	ds_bpermute_b32 v17, v213, v16
	global_store_dwordx4 v[68:69], v[6:9], off offset:512 nt
	global_store_dwordx4 v[68:69], v[2:5], off offset:528 nt
	v_pk_mul_f32 v[12:13], v[182:183], v[2:3]
	v_pk_mul_f32 v[6:7], v[184:185], v[6:7]
	v_pk_mul_f32 v[8:9], v[186:187], v[8:9]
	s_waitcnt lgkmcnt(0)
	v_add_f32_e32 v2, v16, v17
	ds_bpermute_b32 v3, v214, v2
	v_pk_mul_f32 v[10:11], v[180:181], v[4:5]
	v_cvt_pk_bf16_f32 v4, v6, v7
	v_cvt_pk_bf16_f32 v5, v8, v9
	v_cvt_pk_bf16_f32 v6, v12, v13
	s_nop 0
	v_cvt_pk_bf16_f32 v7, v10, v11
	global_store_dwordx4 v[14:15], v[4:7], off offset:256 sc1
	s_and_saveexec_b64 s[42:43], s[0:1]
	s_cbranch_execz .LBB0_1189
	s_waitcnt lgkmcnt(0)
	v_add_f32_e32 v4, v2, v3
	v_lshlrev_b64 v[2:3], 7, v[66:67]
	v_lshl_add_u64 v[2:3], s[26:27], 0, v[2:3]
	v_lshl_add_u64 v[2:3], s[38:39], 2, v[2:3]
	s_lshl_b32 s12, s63, 2
	v_lshl_add_u64 v[2:3], v[2:3], 0, s[12:13]
	global_store_dword v[2:3], v4, off

.LBB0_1283:
	v_lshlrev_b64 v[176:177], 12, v[164:165]
	v_lshl_add_u64 v[176:177], s[12:13], 0, v[176:177]
	v_lshl_add_u64 v[176:177], v[162:163], 2, v[176:177]
	s_waitcnt vmcnt(0) lgkmcnt(0)
	v_pk_fma_f32 v[128:129], v[128:129], v[166:167], v[116:117] op_sel_hi:[1,0,1]
	v_pk_fma_f32 v[126:127], v[126:127], v[166:167], v[114:115] op_sel_hi:[1,0,1]
	global_store_dwordx4 v[176:177], v[126:129], off offset:528 sc1
	v_pk_fma_f32 v[144:145], v[144:145], v[166:167], v[132:133] op_sel_hi:[1,0,1]
	v_pk_fma_f32 v[142:143], v[142:143], v[166:167], v[130:131] op_sel_hi:[1,0,1]
	v_or_b32_e32 v126, 16, v164
	v_cndmask_b32_e64 v127, 0, 1, s[30:31]
	v_pk_fma_f32 v[140:141], v[140:141], v[166:167], v[124:125] op_sel_hi:[1,0,1]
	v_pk_fma_f32 v[138:139], v[138:139], v[166:167], v[122:123] op_sel_hi:[1,0,1]
	v_pk_fma_f32 v[136:137], v[136:137], v[166:167], v[120:121] op_sel_hi:[1,0,1]
	v_pk_fma_f32 v[134:135], v[134:135], v[166:167], v[118:119] op_sel_hi:[1,0,1]
	s_mov_b64 s[34:35], -1
	v_cmp_ne_u32_e64 s[2:3], 1, v127
	s_andn2_b64 vcc, exec, s[30:31]
	v_ashrrev_i32_e32 v127, 31, v126
	global_store_dwordx4 v[176:177], v[142:145], off sc1
	global_store_dwordx4 v[176:177], v[138:141], off offset:16 sc1
	global_store_dwordx4 v[176:177], v[134:137], off offset:512 sc1
	s_cbranch_vccnz .LBB0_1285
	v_lshlrev_b64 v[128:129], 7, v[126:127]
	v_lshl_add_u64 v[128:129], s[16:17], 0, v[128:129]
	global_load_dwordx4 v[134:137], v[128:129], off
	global_load_dwordx4 v[138:141], v[128:129], off offset:16
	global_load_dwordx4 v[142:145], v[128:129], off offset:32
	global_load_dwordx4 v[176:179], v[128:129], off offset:48
	global_load_dwordx4 v[180:183], v[128:129], off offset:64
	global_load_dwordx4 v[184:187], v[128:129], off offset:80
	global_load_dwordx4 v[188:191], v[128:129], off offset:96
	global_load_dwordx4 v[192:195], v[128:129], off offset:112
	s_mov_b64 s[34:35], 0
	s_waitcnt vmcnt(6)
	v_pk_add_f32 v[128:129], v[136:137], v[140:141]
	v_pk_add_f32 v[134:135], v[134:135], v[138:139]
	s_waitcnt vmcnt(5)
	v_pk_add_f32 v[128:129], v[128:129], v[144:145]
	v_pk_add_f32 v[134:135], v[134:135], v[142:143]
	s_waitcnt vmcnt(4)
	v_pk_add_f32 v[128:129], v[128:129], v[178:179]
	v_pk_add_f32 v[134:135], v[134:135], v[176:177]
	s_waitcnt vmcnt(3)
	v_pk_add_f32 v[128:129], v[128:129], v[182:183]
	v_pk_add_f32 v[134:135], v[134:135], v[180:181]
	s_waitcnt vmcnt(2)
	v_pk_add_f32 v[128:129], v[128:129], v[186:187]
	v_pk_add_f32 v[134:135], v[134:135], v[184:185]
	s_waitcnt vmcnt(1)
	v_pk_add_f32 v[128:129], v[128:129], v[190:191]
	v_pk_add_f32 v[134:135], v[134:135], v[188:189]
	s_waitcnt vmcnt(0)
	v_pk_add_f32 v[128:129], v[128:129], v[194:195]
	v_pk_add_f32 v[134:135], v[134:135], v[192:193]
	s_nop 0
	v_pk_mov_b32 v[136:137], v[134:135], v[128:129] op_sel:[1,0]
	v_mov_b32_e32 v135, v129
	v_pk_add_f32 v[128:129], v[136:137], v[134:135]
	s_nop 0
	v_add_f32_e32 v128, v128, v129
	v_fmamk_f32 v128, v128, 0x3a000000, v174
	v_mul_f32_e32 v129, 0x4b800000, v128
	v_cmp_gt_f32_e32 vcc, s63, v128
	s_nop 1
	v_cndmask_b32_e32 v128, v128, v129, vcc
	v_rsq_f32_e32 v128, v128
	s_nop 0
	v_mul_f32_e32 v129, 0x45800000, v128
	v_cndmask_b32_e32 v128, v128, v129, vcc

.LBB0_1287:
	v_lshlrev_b64 v[126:127], 12, v[126:127]
	v_lshl_add_u64 v[126:127], s[12:13], 0, v[126:127]
	v_lshl_add_u64 v[126:127], v[162:163], 2, v[126:127]
	s_waitcnt lgkmcnt(0)
	v_pk_fma_f32 v[100:101], v[100:101], v[128:129], v[116:117] op_sel_hi:[1,0,1]
	v_pk_fma_f32 v[98:99], v[98:99], v[128:129], v[114:115] op_sel_hi:[1,0,1]
	global_store_dwordx4 v[126:127], v[98:101], off offset:528 sc1
	v_pk_fma_f32 v[112:113], v[112:113], v[128:129], v[132:133] op_sel_hi:[1,0,1]
	v_pk_fma_f32 v[110:111], v[110:111], v[128:129], v[130:131] op_sel_hi:[1,0,1]
	v_or_b32_e32 v98, 32, v164
	v_pk_fma_f32 v[108:109], v[108:109], v[128:129], v[124:125] op_sel_hi:[1,0,1]
	v_pk_fma_f32 v[106:107], v[106:107], v[128:129], v[122:123] op_sel_hi:[1,0,1]
	v_pk_fma_f32 v[104:105], v[104:105], v[128:129], v[120:121] op_sel_hi:[1,0,1]
	v_pk_fma_f32 v[102:103], v[102:103], v[128:129], v[118:119] op_sel_hi:[1,0,1]
	s_mov_b64 s[30:31], -1
	s_and_b64 vcc, exec, s[2:3]
	v_ashrrev_i32_e32 v99, 31, v98
	global_store_dwordx4 v[126:127], v[110:113], off sc1
	global_store_dwordx4 v[126:127], v[106:109], off offset:16 sc1
	global_store_dwordx4 v[126:127], v[102:105], off offset:512 sc1
	s_cbranch_vccnz .LBB0_1289
	v_lshlrev_b64 v[100:101], 7, v[98:99]
	v_lshl_add_u64 v[112:113], s[16:17], 0, v[100:101]
	global_load_dwordx4 v[100:103], v[112:113], off
	global_load_dwordx4 v[104:107], v[112:113], off offset:16
	global_load_dwordx4 v[108:111], v[112:113], off offset:32
	global_load_dwordx4 v[126:129], v[112:113], off offset:48
	global_load_dwordx4 v[134:137], v[112:113], off offset:64
	global_load_dwordx4 v[138:141], v[112:113], off offset:80
	global_load_dwordx4 v[142:145], v[112:113], off offset:96
	global_load_dwordx4 v[176:179], v[112:113], off offset:112
	s_mov_b64 s[30:31], 0
	s_waitcnt vmcnt(6)
	v_pk_add_f32 v[102:103], v[102:103], v[106:107]
	v_pk_add_f32 v[100:101], v[100:101], v[104:105]
	s_waitcnt vmcnt(5)
	v_pk_add_f32 v[102:103], v[102:103], v[110:111]
	v_pk_add_f32 v[100:101], v[100:101], v[108:109]
	s_waitcnt vmcnt(4)
	v_pk_add_f32 v[102:103], v[102:103], v[128:129]
	v_pk_add_f32 v[100:101], v[100:101], v[126:127]
	s_waitcnt vmcnt(3)
	v_pk_add_f32 v[102:103], v[102:103], v[136:137]
	v_pk_add_f32 v[100:101], v[100:101], v[134:135]
	s_waitcnt vmcnt(2)
	v_pk_add_f32 v[102:103], v[102:103], v[140:141]
	v_pk_add_f32 v[100:101], v[100:101], v[138:139]
	s_waitcnt vmcnt(1)
	v_pk_add_f32 v[102:103], v[102:103], v[144:145]
	v_pk_add_f32 v[100:101], v[100:101], v[142:143]
	s_waitcnt vmcnt(0)
	v_pk_add_f32 v[102:103], v[102:103], v[178:179]
	v_pk_add_f32 v[100:101], v[100:101], v[176:177]
	s_nop 0
	v_pk_mov_b32 v[104:105], v[100:101], v[102:103] op_sel:[1,0]
	v_mov_b32_e32 v101, v103
	v_pk_add_f32 v[100:101], v[104:105], v[100:101]
	s_nop 0
	v_add_f32_e32 v100, v100, v101
	v_fmamk_f32 v100, v100, 0x3a000000, v174
	v_mul_f32_e32 v101, 0x4b800000, v100
	v_cmp_gt_f32_e32 vcc, s63, v100
	s_nop 1
	v_cndmask_b32_e32 v100, v100, v101, vcc
	v_rsq_f32_e32 v100, v100
	s_nop 0
	v_mul_f32_e32 v101, 0x45800000, v100
	v_cndmask_b32_e32 v100, v100, v101, vcc

.LBB0_1291:
	v_lshlrev_b64 v[98:99], 12, v[98:99]
	v_lshl_add_u64 v[98:99], s[12:13], 0, v[98:99]
	v_lshl_add_u64 v[98:99], v[162:163], 2, v[98:99]
	s_waitcnt lgkmcnt(0)
	v_pk_fma_f32 v[84:85], v[84:85], v[100:101], v[116:117] op_sel_hi:[1,0,1]
	v_pk_fma_f32 v[82:83], v[82:83], v[100:101], v[114:115] op_sel_hi:[1,0,1]
	global_store_dwordx4 v[98:99], v[82:85], off offset:528 sc1
	v_pk_fma_f32 v[96:97], v[96:97], v[100:101], v[132:133] op_sel_hi:[1,0,1]
	v_pk_fma_f32 v[94:95], v[94:95], v[100:101], v[130:131] op_sel_hi:[1,0,1]
	v_or_b32_e32 v82, 48, v164
	v_pk_fma_f32 v[92:93], v[92:93], v[100:101], v[124:125] op_sel_hi:[1,0,1]
	v_pk_fma_f32 v[90:91], v[90:91], v[100:101], v[122:123] op_sel_hi:[1,0,1]
	v_pk_fma_f32 v[88:89], v[88:89], v[100:101], v[120:121] op_sel_hi:[1,0,1]
	v_pk_fma_f32 v[86:87], v[86:87], v[100:101], v[118:119] op_sel_hi:[1,0,1]
	s_mov_b64 s[30:31], -1
	s_and_b64 vcc, exec, s[2:3]
	v_ashrrev_i32_e32 v83, 31, v82
	global_store_dwordx4 v[98:99], v[94:97], off sc1
	global_store_dwordx4 v[98:99], v[90:93], off offset:16 sc1
	global_store_dwordx4 v[98:99], v[86:89], off offset:512 sc1
	s_cbranch_vccnz .LBB0_1293
	v_lshlrev_b64 v[84:85], 7, v[82:83]
	v_lshl_add_u64 v[112:113], s[16:17], 0, v[84:85]
	global_load_dwordx4 v[84:87], v[112:113], off
	global_load_dwordx4 v[88:91], v[112:113], off offset:16
	global_load_dwordx4 v[92:95], v[112:113], off offset:32
	global_load_dwordx4 v[96:99], v[112:113], off offset:48
	global_load_dwordx4 v[100:103], v[112:113], off offset:64
	global_load_dwordx4 v[104:107], v[112:113], off offset:80
	global_load_dwordx4 v[108:111], v[112:113], off offset:96
	global_load_dwordx4 v[126:129], v[112:113], off offset:112
	s_mov_b64 s[30:31], 0
	s_waitcnt vmcnt(6)
	v_pk_add_f32 v[86:87], v[86:87], v[90:91]
	v_pk_add_f32 v[84:85], v[84:85], v[88:89]
	s_waitcnt vmcnt(5)
	v_pk_add_f32 v[86:87], v[86:87], v[94:95]
	v_pk_add_f32 v[84:85], v[84:85], v[92:93]
	s_waitcnt vmcnt(4)
	v_pk_add_f32 v[86:87], v[86:87], v[98:99]
	v_pk_add_f32 v[84:85], v[84:85], v[96:97]
	s_waitcnt vmcnt(3)
	v_pk_add_f32 v[86:87], v[86:87], v[102:103]
	v_pk_add_f32 v[84:85], v[84:85], v[100:101]
	s_waitcnt vmcnt(2)
	v_pk_add_f32 v[86:87], v[86:87], v[106:107]
	v_pk_add_f32 v[84:85], v[84:85], v[104:105]
	s_waitcnt vmcnt(1)
	v_pk_add_f32 v[86:87], v[86:87], v[110:111]
	v_pk_add_f32 v[84:85], v[84:85], v[108:109]
	s_waitcnt vmcnt(0)
	v_pk_add_f32 v[86:87], v[86:87], v[128:129]
	v_pk_add_f32 v[84:85], v[84:85], v[126:127]
	s_nop 0
	v_pk_mov_b32 v[88:89], v[84:85], v[86:87] op_sel:[1,0]
	v_mov_b32_e32 v85, v87
	v_pk_add_f32 v[84:85], v[88:89], v[84:85]
	s_nop 0
	v_add_f32_e32 v84, v84, v85
	v_fmamk_f32 v84, v84, 0x3a000000, v174
	v_mul_f32_e32 v85, 0x4b800000, v84
	v_cmp_gt_f32_e32 vcc, s63, v84
	s_nop 1
	v_cndmask_b32_e32 v84, v84, v85, vcc
	v_rsq_f32_e32 v84, v84
	s_nop 0
	v_mul_f32_e32 v85, 0x45800000, v84
	v_cndmask_b32_e32 v84, v84, v85, vcc

.LBB0_1295:
	v_lshlrev_b64 v[82:83], 12, v[82:83]
	v_lshl_add_u64 v[82:83], s[12:13], 0, v[82:83]
	v_lshl_add_u64 v[82:83], v[162:163], 2, v[82:83]
	s_waitcnt lgkmcnt(0)
	v_pk_fma_f32 v[68:69], v[68:69], v[84:85], v[116:117] op_sel_hi:[1,0,1]
	v_pk_fma_f32 v[66:67], v[66:67], v[84:85], v[114:115] op_sel_hi:[1,0,1]
	global_store_dwordx4 v[82:83], v[66:69], off offset:528 sc1
	v_pk_fma_f32 v[80:81], v[80:81], v[84:85], v[132:133] op_sel_hi:[1,0,1]
	v_pk_fma_f32 v[78:79], v[78:79], v[84:85], v[130:131] op_sel_hi:[1,0,1]
	v_add_u32_e32 v66, 0x80, v164
	v_pk_fma_f32 v[76:77], v[76:77], v[84:85], v[124:125] op_sel_hi:[1,0,1]
	v_pk_fma_f32 v[74:75], v[74:75], v[84:85], v[122:123] op_sel_hi:[1,0,1]
	v_pk_fma_f32 v[72:73], v[72:73], v[84:85], v[120:121] op_sel_hi:[1,0,1]
	v_pk_fma_f32 v[70:71], v[70:71], v[84:85], v[118:119] op_sel_hi:[1,0,1]
	s_mov_b64 s[30:31], -1
	s_and_b64 vcc, exec, s[2:3]
	v_ashrrev_i32_e32 v67, 31, v66
	global_store_dwordx4 v[82:83], v[78:81], off sc1
	global_store_dwordx4 v[82:83], v[74:77], off offset:16 sc1
	global_store_dwordx4 v[82:83], v[70:73], off offset:512 sc1
	s_cbranch_vccnz .LBB0_1297
	v_lshlrev_b64 v[68:69], 7, v[66:67]
	v_lshl_add_u64 v[96:97], s[16:17], 0, v[68:69]
	global_load_dwordx4 v[68:71], v[96:97], off
	global_load_dwordx4 v[72:75], v[96:97], off offset:16
	global_load_dwordx4 v[76:79], v[96:97], off offset:32
	global_load_dwordx4 v[80:83], v[96:97], off offset:48
	global_load_dwordx4 v[84:87], v[96:97], off offset:64
	global_load_dwordx4 v[88:91], v[96:97], off offset:80
	global_load_dwordx4 v[92:95], v[96:97], off offset:96
	s_nop 0
	global_load_dwordx4 v[96:99], v[96:97], off offset:112
	s_mov_b64 s[30:31], 0
	s_waitcnt vmcnt(6)
	v_pk_add_f32 v[70:71], v[70:71], v[74:75]
	v_pk_add_f32 v[68:69], v[68:69], v[72:73]
	s_waitcnt vmcnt(5)
	v_pk_add_f32 v[70:71], v[70:71], v[78:79]
	v_pk_add_f32 v[68:69], v[68:69], v[76:77]
	s_waitcnt vmcnt(4)
	v_pk_add_f32 v[70:71], v[70:71], v[82:83]
	v_pk_add_f32 v[68:69], v[68:69], v[80:81]
	s_waitcnt vmcnt(3)
	v_pk_add_f32 v[70:71], v[70:71], v[86:87]
	v_pk_add_f32 v[68:69], v[68:69], v[84:85]
	s_waitcnt vmcnt(2)
	v_pk_add_f32 v[70:71], v[70:71], v[90:91]
	v_pk_add_f32 v[68:69], v[68:69], v[88:89]
	s_waitcnt vmcnt(1)
	v_pk_add_f32 v[70:71], v[70:71], v[94:95]
	v_pk_add_f32 v[68:69], v[68:69], v[92:93]
	s_waitcnt vmcnt(0)
	v_pk_add_f32 v[70:71], v[70:71], v[98:99]
	v_pk_add_f32 v[68:69], v[68:69], v[96:97]
	s_nop 0
	v_pk_mov_b32 v[72:73], v[68:69], v[70:71] op_sel:[1,0]
	v_mov_b32_e32 v69, v71
	v_pk_add_f32 v[68:69], v[72:73], v[68:69]
	s_nop 0
	v_add_f32_e32 v68, v68, v69
	v_fmamk_f32 v68, v68, 0x3a000000, v174
	v_mul_f32_e32 v69, 0x4b800000, v68
	v_cmp_gt_f32_e32 vcc, s63, v68
	s_nop 1
	v_cndmask_b32_e32 v68, v68, v69, vcc
	v_rsq_f32_e32 v68, v68
	s_nop 0
	v_mul_f32_e32 v69, 0x45800000, v68
	v_cndmask_b32_e32 v68, v68, v69, vcc

.LBB0_1299:
	v_lshlrev_b64 v[66:67], 12, v[66:67]
	v_lshl_add_u64 v[66:67], s[12:13], 0, v[66:67]
	v_lshl_add_u64 v[66:67], v[162:163], 2, v[66:67]
	s_waitcnt lgkmcnt(0)
	v_pk_fma_f32 v[52:53], v[52:53], v[68:69], v[116:117] op_sel_hi:[1,0,1]
	v_pk_fma_f32 v[50:51], v[50:51], v[68:69], v[114:115] op_sel_hi:[1,0,1]
	global_store_dwordx4 v[66:67], v[50:53], off offset:528 sc1
	v_pk_fma_f32 v[64:65], v[64:65], v[68:69], v[132:133] op_sel_hi:[1,0,1]
	v_pk_fma_f32 v[62:63], v[62:63], v[68:69], v[130:131] op_sel_hi:[1,0,1]
	v_add_u32_e32 v50, 0x90, v164
	v_pk_fma_f32 v[60:61], v[60:61], v[68:69], v[124:125] op_sel_hi:[1,0,1]
	v_pk_fma_f32 v[58:59], v[58:59], v[68:69], v[122:123] op_sel_hi:[1,0,1]
	v_pk_fma_f32 v[56:57], v[56:57], v[68:69], v[120:121] op_sel_hi:[1,0,1]
	v_pk_fma_f32 v[54:55], v[54:55], v[68:69], v[118:119] op_sel_hi:[1,0,1]
	s_mov_b64 s[30:31], -1
	s_and_b64 vcc, exec, s[2:3]
	v_ashrrev_i32_e32 v51, 31, v50
	global_store_dwordx4 v[66:67], v[62:65], off sc1
	global_store_dwordx4 v[66:67], v[58:61], off offset:16 sc1
	global_store_dwordx4 v[66:67], v[54:57], off offset:512 sc1
	s_cbranch_vccnz .LBB0_1301
	v_lshlrev_b64 v[52:53], 7, v[50:51]
	v_lshl_add_u64 v[80:81], s[16:17], 0, v[52:53]
	global_load_dwordx4 v[52:55], v[80:81], off
	global_load_dwordx4 v[56:59], v[80:81], off offset:16
	global_load_dwordx4 v[60:63], v[80:81], off offset:32
	global_load_dwordx4 v[64:67], v[80:81], off offset:48
	global_load_dwordx4 v[68:71], v[80:81], off offset:64
	global_load_dwordx4 v[72:75], v[80:81], off offset:80
	global_load_dwordx4 v[76:79], v[80:81], off offset:96
	s_nop 0
	global_load_dwordx4 v[80:83], v[80:81], off offset:112
	s_mov_b64 s[30:31], 0
	s_waitcnt vmcnt(6)
	v_pk_add_f32 v[54:55], v[54:55], v[58:59]
	v_pk_add_f32 v[52:53], v[52:53], v[56:57]
	s_waitcnt vmcnt(5)
	v_pk_add_f32 v[54:55], v[54:55], v[62:63]
	v_pk_add_f32 v[52:53], v[52:53], v[60:61]
	s_waitcnt vmcnt(4)
	v_pk_add_f32 v[54:55], v[54:55], v[66:67]
	v_pk_add_f32 v[52:53], v[52:53], v[64:65]
	s_waitcnt vmcnt(3)
	v_pk_add_f32 v[54:55], v[54:55], v[70:71]
	v_pk_add_f32 v[52:53], v[52:53], v[68:69]
	s_waitcnt vmcnt(2)
	v_pk_add_f32 v[54:55], v[54:55], v[74:75]
	v_pk_add_f32 v[52:53], v[52:53], v[72:73]
	s_waitcnt vmcnt(1)
	v_pk_add_f32 v[54:55], v[54:55], v[78:79]
	v_pk_add_f32 v[52:53], v[52:53], v[76:77]
	s_waitcnt vmcnt(0)
	v_pk_add_f32 v[54:55], v[54:55], v[82:83]
	v_pk_add_f32 v[52:53], v[52:53], v[80:81]
	s_nop 0
	v_pk_mov_b32 v[56:57], v[52:53], v[54:55] op_sel:[1,0]
	v_mov_b32_e32 v53, v55
	v_pk_add_f32 v[52:53], v[56:57], v[52:53]
	s_nop 0
	v_add_f32_e32 v52, v52, v53
	v_fmamk_f32 v52, v52, 0x3a000000, v174
	v_mul_f32_e32 v53, 0x4b800000, v52
	v_cmp_gt_f32_e32 vcc, s63, v52
	s_nop 1
	v_cndmask_b32_e32 v52, v52, v53, vcc
	v_rsq_f32_e32 v52, v52
	s_nop 0
	v_mul_f32_e32 v53, 0x45800000, v52
	v_cndmask_b32_e32 v52, v52, v53, vcc

.LBB0_1303:
	v_lshlrev_b64 v[50:51], 12, v[50:51]
	v_lshl_add_u64 v[50:51], s[12:13], 0, v[50:51]
	v_lshl_add_u64 v[50:51], v[162:163], 2, v[50:51]
	s_waitcnt lgkmcnt(0)
	v_pk_fma_f32 v[36:37], v[36:37], v[52:53], v[116:117] op_sel_hi:[1,0,1]
	v_pk_fma_f32 v[34:35], v[34:35], v[52:53], v[114:115] op_sel_hi:[1,0,1]
	global_store_dwordx4 v[50:51], v[34:37], off offset:528 sc1
	v_pk_fma_f32 v[48:49], v[48:49], v[52:53], v[132:133] op_sel_hi:[1,0,1]
	v_pk_fma_f32 v[46:47], v[46:47], v[52:53], v[130:131] op_sel_hi:[1,0,1]
	v_add_u32_e32 v34, 0xa0, v164
	v_pk_fma_f32 v[44:45], v[44:45], v[52:53], v[124:125] op_sel_hi:[1,0,1]
	v_pk_fma_f32 v[42:43], v[42:43], v[52:53], v[122:123] op_sel_hi:[1,0,1]
	v_pk_fma_f32 v[40:41], v[40:41], v[52:53], v[120:121] op_sel_hi:[1,0,1]
	v_pk_fma_f32 v[38:39], v[38:39], v[52:53], v[118:119] op_sel_hi:[1,0,1]
	s_mov_b64 s[30:31], -1
	s_and_b64 vcc, exec, s[2:3]
	v_ashrrev_i32_e32 v35, 31, v34
	global_store_dwordx4 v[50:51], v[46:49], off sc1
	global_store_dwordx4 v[50:51], v[42:45], off offset:16 sc1
	global_store_dwordx4 v[50:51], v[38:41], off offset:512 sc1
	s_cbranch_vccnz .LBB0_1305
	v_lshlrev_b64 v[36:37], 7, v[34:35]
	v_lshl_add_u64 v[64:65], s[16:17], 0, v[36:37]
	global_load_dwordx4 v[36:39], v[64:65], off
	global_load_dwordx4 v[40:43], v[64:65], off offset:16
	global_load_dwordx4 v[44:47], v[64:65], off offset:32
	global_load_dwordx4 v[48:51], v[64:65], off offset:48
	global_load_dwordx4 v[52:55], v[64:65], off offset:64
	global_load_dwordx4 v[56:59], v[64:65], off offset:80
	global_load_dwordx4 v[60:63], v[64:65], off offset:96
	s_nop 0
	global_load_dwordx4 v[64:67], v[64:65], off offset:112
	s_mov_b64 s[30:31], 0
	s_waitcnt vmcnt(6)
	v_pk_add_f32 v[38:39], v[38:39], v[42:43]
	v_pk_add_f32 v[36:37], v[36:37], v[40:41]
	s_waitcnt vmcnt(5)
	v_pk_add_f32 v[38:39], v[38:39], v[46:47]
	v_pk_add_f32 v[36:37], v[36:37], v[44:45]
	s_waitcnt vmcnt(4)
	v_pk_add_f32 v[38:39], v[38:39], v[50:51]
	v_pk_add_f32 v[36:37], v[36:37], v[48:49]
	s_waitcnt vmcnt(3)
	v_pk_add_f32 v[38:39], v[38:39], v[54:55]
	v_pk_add_f32 v[36:37], v[36:37], v[52:53]
	s_waitcnt vmcnt(2)
	v_pk_add_f32 v[38:39], v[38:39], v[58:59]
	v_pk_add_f32 v[36:37], v[36:37], v[56:57]
	s_waitcnt vmcnt(1)
	v_pk_add_f32 v[38:39], v[38:39], v[62:63]
	v_pk_add_f32 v[36:37], v[36:37], v[60:61]
	s_waitcnt vmcnt(0)
	v_pk_add_f32 v[38:39], v[38:39], v[66:67]
	v_pk_add_f32 v[36:37], v[36:37], v[64:65]
	s_nop 0
	v_pk_mov_b32 v[40:41], v[36:37], v[38:39] op_sel:[1,0]
	v_mov_b32_e32 v37, v39
	v_pk_add_f32 v[36:37], v[40:41], v[36:37]
	s_nop 0
	v_add_f32_e32 v36, v36, v37
	v_fmamk_f32 v36, v36, 0x3a000000, v174
	v_mul_f32_e32 v37, 0x4b800000, v36
	v_cmp_gt_f32_e32 vcc, s63, v36
	s_nop 1
	v_cndmask_b32_e32 v36, v36, v37, vcc
	v_rsq_f32_e32 v36, v36
	s_nop 0
	v_mul_f32_e32 v37, 0x45800000, v36
	v_cndmask_b32_e32 v36, v36, v37, vcc

.LBB0_1307:
	v_lshlrev_b64 v[34:35], 12, v[34:35]
	v_lshl_add_u64 v[34:35], s[12:13], 0, v[34:35]
	v_lshl_add_u64 v[34:35], v[162:163], 2, v[34:35]
	s_waitcnt lgkmcnt(0)
	v_pk_fma_f32 v[20:21], v[20:21], v[36:37], v[116:117] op_sel_hi:[1,0,1]
	v_pk_fma_f32 v[18:19], v[18:19], v[36:37], v[114:115] op_sel_hi:[1,0,1]
	global_store_dwordx4 v[34:35], v[18:21], off offset:528 sc1
	v_pk_fma_f32 v[32:33], v[32:33], v[36:37], v[132:133] op_sel_hi:[1,0,1]
	v_pk_fma_f32 v[30:31], v[30:31], v[36:37], v[130:131] op_sel_hi:[1,0,1]
	v_add_u32_e32 v18, 0xb0, v164
	v_pk_fma_f32 v[28:29], v[28:29], v[36:37], v[124:125] op_sel_hi:[1,0,1]
	v_pk_fma_f32 v[26:27], v[26:27], v[36:37], v[122:123] op_sel_hi:[1,0,1]
	v_pk_fma_f32 v[24:25], v[24:25], v[36:37], v[120:121] op_sel_hi:[1,0,1]
	v_pk_fma_f32 v[22:23], v[22:23], v[36:37], v[118:119] op_sel_hi:[1,0,1]
	s_mov_b64 s[30:31], -1
	s_and_b64 vcc, exec, s[2:3]
	v_ashrrev_i32_e32 v19, 31, v18
	global_store_dwordx4 v[34:35], v[30:33], off sc1
	global_store_dwordx4 v[34:35], v[26:29], off offset:16 sc1
	global_store_dwordx4 v[34:35], v[22:25], off offset:512 sc1
	s_cbranch_vccnz .LBB0_1309
	v_lshlrev_b64 v[20:21], 7, v[18:19]
	v_lshl_add_u64 v[48:49], s[16:17], 0, v[20:21]
	global_load_dwordx4 v[20:23], v[48:49], off
	global_load_dwordx4 v[24:27], v[48:49], off offset:16
	global_load_dwordx4 v[28:31], v[48:49], off offset:32
	global_load_dwordx4 v[32:35], v[48:49], off offset:48
	global_load_dwordx4 v[36:39], v[48:49], off offset:64
	global_load_dwordx4 v[40:43], v[48:49], off offset:80
	global_load_dwordx4 v[44:47], v[48:49], off offset:96
	s_nop 0
	global_load_dwordx4 v[48:51], v[48:49], off offset:112
	s_mov_b64 s[30:31], 0
	s_waitcnt vmcnt(6)
	v_pk_add_f32 v[22:23], v[22:23], v[26:27]
	v_pk_add_f32 v[20:21], v[20:21], v[24:25]
	s_waitcnt vmcnt(5)
	v_pk_add_f32 v[22:23], v[22:23], v[30:31]
	v_pk_add_f32 v[20:21], v[20:21], v[28:29]
	s_waitcnt vmcnt(4)
	v_pk_add_f32 v[22:23], v[22:23], v[34:35]
	v_pk_add_f32 v[20:21], v[20:21], v[32:33]
	s_waitcnt vmcnt(3)
	v_pk_add_f32 v[22:23], v[22:23], v[38:39]
	v_pk_add_f32 v[20:21], v[20:21], v[36:37]
	s_waitcnt vmcnt(2)
	v_pk_add_f32 v[22:23], v[22:23], v[42:43]
	v_pk_add_f32 v[20:21], v[20:21], v[40:41]
	s_waitcnt vmcnt(1)
	v_pk_add_f32 v[22:23], v[22:23], v[46:47]
	v_pk_add_f32 v[20:21], v[20:21], v[44:45]
	s_waitcnt vmcnt(0)
	v_pk_add_f32 v[22:23], v[22:23], v[50:51]
	v_pk_add_f32 v[20:21], v[20:21], v[48:49]
	s_nop 0
	v_pk_mov_b32 v[24:25], v[20:21], v[22:23] op_sel:[1,0]
	v_mov_b32_e32 v21, v23
	v_pk_add_f32 v[20:21], v[24:25], v[20:21]
	s_nop 0
	v_add_f32_e32 v20, v20, v21
	v_fmamk_f32 v20, v20, 0x3a000000, v174
	v_mul_f32_e32 v21, 0x4b800000, v20
	v_cmp_gt_f32_e32 vcc, s63, v20
	s_nop 1
	v_cndmask_b32_e32 v20, v20, v21, vcc
	v_rsq_f32_e32 v20, v20
	s_nop 0
	v_mul_f32_e32 v21, 0x45800000, v20
	v_cndmask_b32_e32 v20, v20, v21, vcc

.LBB0_1311:
	v_lshlrev_b64 v[18:19], 12, v[18:19]
	v_lshl_add_u64 v[18:19], s[12:13], 0, v[18:19]
	v_lshl_add_u64 v[18:19], v[162:163], 2, v[18:19]
	s_waitcnt lgkmcnt(0)
	v_pk_fma_f32 v[16:17], v[16:17], v[20:21], v[132:133] op_sel_hi:[1,0,1]
	v_pk_fma_f32 v[14:15], v[14:15], v[20:21], v[130:131] op_sel_hi:[1,0,1]
	v_pk_fma_f32 v[12:13], v[12:13], v[20:21], v[124:125] op_sel_hi:[1,0,1]
	v_pk_fma_f32 v[10:11], v[10:11], v[20:21], v[122:123] op_sel_hi:[1,0,1]
	v_pk_fma_f32 v[8:9], v[8:9], v[20:21], v[120:121] op_sel_hi:[1,0,1]
	v_pk_fma_f32 v[6:7], v[6:7], v[20:21], v[118:119] op_sel_hi:[1,0,1]
	v_pk_fma_f32 v[4:5], v[4:5], v[20:21], v[116:117] op_sel_hi:[1,0,1]
	v_pk_fma_f32 v[2:3], v[2:3], v[20:21], v[114:115] op_sel_hi:[1,0,1]
	s_and_b64 vcc, exec, s[0:1]
	s_mov_b64 s[0:1], -1
	global_store_dwordx4 v[18:19], v[14:17], off sc1
	global_store_dwordx4 v[18:19], v[10:13], off offset:16 sc1
	global_store_dwordx4 v[18:19], v[6:9], off offset:512 sc1
	global_store_dwordx4 v[18:19], v[2:5], off offset:528 sc1
	s_cbranch_vccnz .LBB0_1263
	s_andn2_b64 vcc, exec, s[10:11]
	s_cbranch_vccnz .LBB0_1262
	s_barrier
	s_branch .LBB0_1262

.LBB0_1368:
	s_lshl_b64 s[24:25], s[24:25], 7
	s_waitcnt vmcnt(0)
	v_lshl_add_u64 v[6:7], v[28:29], 0, s[24:25]
	v_cvt_pk_bf16_f32 v2, v14, v15
	v_cvt_pk_bf16_f32 v3, v16, v17
	v_cvt_pk_bf16_f32 v4, v10, v11
	v_cvt_pk_bf16_f32 v5, v12, v13
	global_store_dwordx4 v[6:7], v[2:5], off sc1

.LBB0_1370:
	v_lshl_add_u64 v[2:3], s[74:75], 0, v[38:39]
	v_add_co_u32_e32 v48, vcc, 0x26200000, v2
	s_add_i32 s24, s12, 0x400
	s_nop 0
	v_addc_co_u32_e32 v49, vcc, 0, v3, vcc
	global_load_dwordx4 v[2:5], v[48:49], off
	global_load_dwordx4 v[6:9], v[48:49], off offset:1024
	global_load_dwordx4 v[10:13], v[20:21], off
	global_load_dwordx4 v[14:17], v[20:21], off offset:1024
	s_ashr_i32 s25, s24, 31
	s_waitcnt vmcnt(3)
	v_pk_mul_f32 v[50:51], v[4:5], v[4:5]
	v_pk_mul_f32 v[52:53], v[2:3], v[2:3]
	s_waitcnt vmcnt(2)
	v_pk_mul_f32 v[54:55], v[8:9], v[8:9]
	v_pk_mul_f32 v[56:57], v[6:7], v[6:7]
	v_pk_mov_b32 v[58:59], v[52:53], v[50:51] op_sel:[1,0]
	v_mov_b32_e32 v53, v51
	v_mov_b32_e32 v50, v54
	v_mov_b32_e32 v51, v56
	v_mov_b32_e32 v56, v55
	v_pk_add_f32 v[52:53], v[58:59], v[52:53]
	v_pk_add_f32 v[50:51], v[50:51], v[56:57]
	v_add_f32_e32 v18, v52, v53
	v_add_f32_e32 v18, v18, v51
	v_add_f32_e32 v18, v50, v18
	ds_bpermute_b32 v47, v40, v18
	v_lshl_add_u64 v[50:51], s[74:75], 0, v[32:33]
	v_add_co_u32_e64 v50, s[4:5], s17, v50
	s_waitcnt lgkmcnt(0)
	v_add_f32_e32 v18, v18, v47
	ds_bpermute_b32 v47, v41, v18
	v_addc_co_u32_e64 v51, s[4:5], 0, v51, s[4:5]
	s_lshl_b64 s[4:5], s[24:25], 9
	s_cmpk_gt_i32 s12, 0x1fff
	s_waitcnt lgkmcnt(0)
	v_add_f32_e32 v18, v18, v47
	ds_bpermute_b32 v47, v42, v18
	s_cselect_b64 s[26:27], -1, 0
	s_waitcnt lgkmcnt(0)
	v_add_f32_e32 v18, v18, v47
	ds_bpermute_b32 v47, v43, v18
	s_waitcnt lgkmcnt(0)
	v_add_f32_e32 v18, v18, v47
	ds_bpermute_b32 v47, v44, v18
	s_waitcnt lgkmcnt(0)
	v_add_f32_e32 v18, v18, v47
	ds_bpermute_b32 v47, v45, v18
	s_waitcnt lgkmcnt(0)
	v_add_f32_e32 v18, v18, v47
	v_fmamk_f32 v18, v18, 0x3b000000, v46
	v_mul_f32_e32 v47, 0x4b800000, v18
	v_cmp_gt_f32_e32 vcc, s13, v18
	s_nop 1
	v_cndmask_b32_e32 v18, v18, v47, vcc
	v_rsq_f32_e32 v18, v18
	s_nop 0
	v_mul_f32_e32 v47, 0x45800000, v18
	v_cndmask_b32_e32 v18, v18, v47, vcc
	v_pk_mul_f32 v[2:3], v[2:3], v[18:19] op_sel_hi:[1,0]
	v_pk_mul_f32 v[4:5], v[4:5], v[18:19] op_sel_hi:[1,0]
	s_waitcnt vmcnt(1)
	v_pk_mul_f32 v[2:3], v[10:11], v[2:3]
	v_pk_mul_f32 v[6:7], v[6:7], v[18:19] op_sel_hi:[1,0]
	v_pk_mul_f32 v[8:9], v[8:9], v[18:19] op_sel_hi:[1,0]
	v_pk_mul_f32 v[4:5], v[12:13], v[4:5]
	v_cvt_pk_bf16_f32 v2, v2, v3
	s_waitcnt vmcnt(0)
	v_pk_mul_f32 v[8:9], v[16:17], v[8:9]
	v_cvt_pk_bf16_f32 v3, v4, v5
	v_pk_mul_f32 v[6:7], v[14:15], v[6:7]
	global_store_dwordx2 v[50:51], v[2:3], off
	v_cvt_pk_bf16_f32 v2, v6, v7
	v_cvt_pk_bf16_f32 v3, v8, v9
	global_store_dwordx2 v[50:51], v[2:3], off offset:512
	global_load_dwordx4 v[2:5], v[48:49], off offset:2048
	s_nop 0
	global_load_dwordx4 v[6:9], v[22:23], off
	s_waitcnt vmcnt(1)
	v_pk_mul_f32 v[10:11], v[4:5], v[4:5]
	v_pk_mul_f32 v[12:13], v[2:3], v[2:3]
	s_nop 0
	v_pk_mov_b32 v[14:15], v[12:13], v[10:11] op_sel:[1,0]
	v_mov_b32_e32 v13, v11
	v_pk_add_f32 v[10:11], v[14:15], v[12:13]
	s_nop 0
	v_add_f32_e32 v10, v10, v11
	ds_bpermute_b32 v11, v40, v10
	s_waitcnt lgkmcnt(0)
	v_add_f32_e32 v10, v10, v11
	ds_bpermute_b32 v11, v41, v10
	s_waitcnt lgkmcnt(0)
	v_add_f32_e32 v10, v10, v11
	ds_bpermute_b32 v11, v42, v10
	s_waitcnt lgkmcnt(0)
	v_add_f32_e32 v10, v10, v11
	ds_bpermute_b32 v11, v43, v10
	s_waitcnt lgkmcnt(0)
	v_add_f32_e32 v10, v10, v11
	ds_bpermute_b32 v11, v44, v10
	s_waitcnt lgkmcnt(0)
	v_add_f32_e32 v12, v10, v11
	ds_bpermute_b32 v13, v45, v12
	v_lshl_add_u64 v[10:11], v[24:25], 0, s[4:5]
	s_and_b64 s[4:5], exec, s[26:27]
	s_waitcnt lgkmcnt(0)
	v_add_f32_e32 v12, v12, v13
	v_fmamk_f32 v12, v12, 0x3b800000, v46
	v_mul_f32_e32 v13, 0x4b800000, v12
	v_cmp_gt_f32_e32 vcc, s13, v12
	s_nop 1
	v_cndmask_b32_e32 v12, v12, v13, vcc
	v_rsq_f32_e32 v12, v12
	s_nop 0
	v_mul_f32_e32 v13, 0x45800000, v12
	v_cndmask_b32_e32 v12, v12, v13, vcc
	v_pk_mul_f32 v[2:3], v[2:3], v[12:13] op_sel_hi:[1,0]
	v_pk_mul_f32 v[4:5], v[4:5], v[12:13] op_sel_hi:[1,0]
	s_waitcnt vmcnt(0)
	v_pk_mul_f32 v[2:3], v[6:7], v[2:3]
	v_pk_mul_f32 v[4:5], v[8:9], v[4:5]
	s_mov_b64 vcc, s[4:5]
	v_cvt_pk_bf16_f32 v6, v2, v3
	v_cvt_pk_bf16_f32 v7, v4, v5
	global_store_dwordx2 v[10:11], v[6:7], off
	s_cbranch_vccnz .LBB0_1372
	v_lshl_add_u64 v[6:7], s[72:73], 0, v[34:35]
	global_store_dwordx4 v[6:7], v[2:5], off sc1

.LBB0_1375:
	s_andn2_b64 vcc, exec, s[28:29]
	s_cbranch_vccnz .LBB0_1368
	v_lshl_add_u64 v[10:11], s[72:73], 0, v[30:31]
	v_add_co_u32_e32 v10, vcc, 0xc800000, v10
	s_waitcnt vmcnt(1)
	v_mov_b64_e32 v[16:17], v[4:5]
	v_addc_co_u32_e32 v11, vcc, 0, v11, vcc
	global_store_dwordx4 v[10:11], v[2:5], off sc1
	s_waitcnt vmcnt(1)
	global_store_dwordx4 v[10:11], v[6:9], off offset:64 sc1
	v_mov_b64_e32 v[12:13], v[8:9]
	v_mov_b64_e32 v[10:11], v[6:7]
	v_mov_b64_e32 v[14:15], v[2:3]
	s_branch .LBB0_1368

.LBB0_1466:
	s_or_b64 exec, exec, s[28:29]
	v_or_b32_e32 v171, s66, v158
	v_cvt_pk_bf16_f32 v128, v128, v129
	v_cvt_pk_bf16_f32 v129, v130, v131
	v_cvt_pk_bf16_f32 v130, v124, v125
	v_mov_b64_e32 v[124:125], s[12:13]
	v_ashrrev_i32_e32 v149, 31, v148
	v_mad_i64_i32 v[124:125], s[28:29], v171, s62, v[124:125]
	v_cvt_pk_bf16_f32 v131, v126, v127
	v_lshl_add_u64 v[124:125], v[148:149], 1, v[124:125]
	v_or_b32_e32 v126, 16, v171
	global_store_dwordx4 v[124:125], v[128:131], off sc1
	s_and_saveexec_b64 s[28:29], s[26:27]
	s_cbranch_execz .LBB0_1468
	v_mov_b32_e32 v3, s65
	v_cndmask_b32_e32 v3, v126, v3, vcc
	v_lshlrev_b32_e32 v3, 7, v3
	v_and_b32_e32 v128, 0x1f80, v3
	v_mov_b32_e32 v129, v2
	v_lshl_add_u64 v[128:129], s[14:15], 0, v[128:129]
	v_mov_b32_e32 v151, v2
	v_lshl_add_u64 v[172:173], v[128:129], 0, v[150:151]
	global_load_dwordx4 v[128:131], v[172:173], off
	s_nop 0
	global_load_dwordx4 v[172:175], v[172:173], off offset:16
	s_waitcnt vmcnt(0)
	v_mov_b32_e32 v176, v129
	v_mov_b32_e32 v177, v131
	v_mov_b32_e32 v178, v173
	v_mov_b32_e32 v179, v175
	v_mov_b32_e32 v173, v174
	v_mov_b32_e32 v129, v130
	v_pk_mul_f32 v[130:131], v[120:121], v[176:177]
	v_pk_mul_f32 v[174:175], v[122:123], v[178:179]
	v_pk_mul_f32 v[176:177], v[116:117], v[176:177]
	v_pk_mul_f32 v[178:179], v[118:119], v[178:179]
	v_pk_fma_f32 v[118:119], v[118:119], v[172:173], v[174:175]
	v_pk_fma_f32 v[116:117], v[116:117], v[128:129], v[130:131]
	v_pk_fma_f32 v[122:123], v[122:123], v[172:173], v[178:179] neg_lo:[0,0,1] neg_hi:[0,0,1]
	v_pk_fma_f32 v[120:121], v[120:121], v[128:129], v[176:177] neg_lo:[0,0,1] neg_hi:[0,0,1]
.LBB0_1468:
	s_or_b64 exec, exec, s[28:29]
	v_cvt_pk_bf16_f32 v120, v120, v121
	v_cvt_pk_bf16_f32 v121, v122, v123
	v_cvt_pk_bf16_f32 v122, v116, v117
	v_mov_b64_e32 v[116:117], s[12:13]
	v_mad_i64_i32 v[116:117], s[28:29], v126, s62, v[116:117]
	v_cvt_pk_bf16_f32 v123, v118, v119
	v_lshl_add_u64 v[116:117], v[148:149], 1, v[116:117]
	v_or_b32_e32 v118, 32, v171
	global_store_dwordx4 v[116:117], v[120:123], off sc1
	s_and_saveexec_b64 s[28:29], s[26:27]
	s_cbranch_execz .LBB0_1470
	v_mov_b32_e32 v3, s65
	v_cndmask_b32_e32 v3, v118, v3, vcc
	v_lshlrev_b32_e32 v3, 7, v3
	v_and_b32_e32 v120, 0x1f80, v3
	v_mov_b32_e32 v121, v2
	v_lshl_add_u64 v[120:121], s[14:15], 0, v[120:121]
	v_mov_b32_e32 v151, v2
	v_lshl_add_u64 v[128:129], v[120:121], 0, v[150:151]
	global_load_dwordx4 v[120:123], v[128:129], off
	s_nop 0
	global_load_dwordx4 v[128:131], v[128:129], off offset:16
	s_waitcnt vmcnt(0)
	v_mov_b32_e32 v172, v121
	v_mov_b32_e32 v173, v123
	v_mov_b32_e32 v174, v129
	v_mov_b32_e32 v175, v131
	v_mov_b32_e32 v129, v130
	v_mov_b32_e32 v121, v122
	v_pk_mul_f32 v[122:123], v[112:113], v[172:173]
	v_pk_mul_f32 v[130:131], v[114:115], v[174:175]
	v_pk_mul_f32 v[172:173], v[108:109], v[172:173]
	v_pk_mul_f32 v[174:175], v[110:111], v[174:175]
	v_pk_fma_f32 v[110:111], v[110:111], v[128:129], v[130:131]
	v_pk_fma_f32 v[108:109], v[108:109], v[120:121], v[122:123]
	v_pk_fma_f32 v[114:115], v[114:115], v[128:129], v[174:175] neg_lo:[0,0,1] neg_hi:[0,0,1]
	v_pk_fma_f32 v[112:113], v[112:113], v[120:121], v[172:173] neg_lo:[0,0,1] neg_hi:[0,0,1]
.LBB0_1470:
	s_or_b64 exec, exec, s[28:29]
	v_cvt_pk_bf16_f32 v112, v112, v113
	v_cvt_pk_bf16_f32 v113, v114, v115
	v_cvt_pk_bf16_f32 v114, v108, v109
	v_mov_b64_e32 v[108:109], s[12:13]
	v_mad_i64_i32 v[108:109], s[28:29], v118, s62, v[108:109]
	v_cvt_pk_bf16_f32 v115, v110, v111
	v_lshl_add_u64 v[108:109], v[148:149], 1, v[108:109]
	v_or_b32_e32 v110, 48, v171
	global_store_dwordx4 v[108:109], v[112:115], off sc1
	s_and_saveexec_b64 s[28:29], s[26:27]
	s_cbranch_execz .LBB0_1472
	v_mov_b32_e32 v3, s65
	v_cndmask_b32_e32 v3, v110, v3, vcc
	v_lshlrev_b32_e32 v3, 7, v3
	v_and_b32_e32 v112, 0x1f80, v3
	v_mov_b32_e32 v113, v2
	v_lshl_add_u64 v[112:113], s[14:15], 0, v[112:113]
	v_mov_b32_e32 v151, v2
	v_lshl_add_u64 v[120:121], v[112:113], 0, v[150:151]
	global_load_dwordx4 v[112:115], v[120:121], off
	s_nop 0
	global_load_dwordx4 v[120:123], v[120:121], off offset:16
	s_waitcnt vmcnt(0)
	v_mov_b32_e32 v128, v113
	v_mov_b32_e32 v129, v115
	v_mov_b32_e32 v130, v121
	v_mov_b32_e32 v131, v123
	v_mov_b32_e32 v121, v122
	v_mov_b32_e32 v113, v114
	v_pk_mul_f32 v[114:115], v[104:105], v[128:129]
	v_pk_mul_f32 v[122:123], v[106:107], v[130:131]
	v_pk_mul_f32 v[128:129], v[100:101], v[128:129]
	v_pk_mul_f32 v[130:131], v[102:103], v[130:131]
	v_pk_fma_f32 v[102:103], v[102:103], v[120:121], v[122:123]
	v_pk_fma_f32 v[100:101], v[100:101], v[112:113], v[114:115]
	v_pk_fma_f32 v[106:107], v[106:107], v[120:121], v[130:131] neg_lo:[0,0,1] neg_hi:[0,0,1]
	v_pk_fma_f32 v[104:105], v[104:105], v[112:113], v[128:129] neg_lo:[0,0,1] neg_hi:[0,0,1]
.LBB0_1472:
	s_or_b64 exec, exec, s[28:29]
	v_cvt_pk_bf16_f32 v104, v104, v105
	v_cvt_pk_bf16_f32 v105, v106, v107
	v_cvt_pk_bf16_f32 v106, v100, v101
	v_mov_b64_e32 v[100:101], s[12:13]
	v_cvt_pk_bf16_f32 v107, v102, v103
	v_mad_i64_i32 v[100:101], s[28:29], v110, s62, v[100:101]
	v_add_u32_e32 v102, 0x80, v171
	v_lshl_add_u64 v[100:101], v[148:149], 1, v[100:101]
	v_lshrrev_b32_e32 v3, 6, v102
	global_store_dwordx4 v[100:101], v[104:107], off sc1
	s_and_saveexec_b64 s[28:29], s[26:27]
	s_cbranch_execz .LBB0_1474
	v_cndmask_b32_e32 v103, v158, v3, vcc
	v_lshlrev_b32_e32 v103, 7, v103
	v_and_b32_e32 v104, 0x1f80, v103
	v_mov_b32_e32 v105, v2
	v_lshl_add_u64 v[104:105], s[14:15], 0, v[104:105]
	v_mov_b32_e32 v151, v2
	v_lshl_add_u64 v[112:113], v[104:105], 0, v[150:151]
	global_load_dwordx4 v[104:107], v[112:113], off
	s_nop 0
	global_load_dwordx4 v[112:115], v[112:113], off offset:16
	s_waitcnt vmcnt(0)
	v_mov_b32_e32 v120, v105
	v_mov_b32_e32 v121, v107
	v_mov_b32_e32 v122, v113
	v_mov_b32_e32 v123, v115
	v_mov_b32_e32 v113, v114
	v_mov_b32_e32 v105, v106
	v_pk_mul_f32 v[106:107], v[96:97], v[120:121]
	v_pk_mul_f32 v[114:115], v[98:99], v[122:123]
	v_pk_mul_f32 v[120:121], v[92:93], v[120:121]
	v_pk_mul_f32 v[122:123], v[94:95], v[122:123]
	v_pk_fma_f32 v[94:95], v[94:95], v[112:113], v[114:115]
	v_pk_fma_f32 v[92:93], v[92:93], v[104:105], v[106:107]
	v_pk_fma_f32 v[98:99], v[98:99], v[112:113], v[122:123] neg_lo:[0,0,1] neg_hi:[0,0,1]
	v_pk_fma_f32 v[96:97], v[96:97], v[104:105], v[120:121] neg_lo:[0,0,1] neg_hi:[0,0,1]
.LBB0_1474:
	s_or_b64 exec, exec, s[28:29]
	v_cvt_pk_bf16_f32 v96, v96, v97
	v_cvt_pk_bf16_f32 v97, v98, v99
	v_cvt_pk_bf16_f32 v98, v92, v93
	v_mov_b64_e32 v[92:93], s[12:13]
	v_mad_i64_i32 v[92:93], s[28:29], v102, s62, v[92:93]
	v_cvt_pk_bf16_f32 v99, v94, v95
	v_lshl_add_u64 v[92:93], v[148:149], 1, v[92:93]
	v_add_u32_e32 v94, 0x90, v171
	global_store_dwordx4 v[92:93], v[96:99], off sc1
	s_and_saveexec_b64 s[28:29], s[26:27]
	s_cbranch_execz .LBB0_1476
	v_cndmask_b32_e32 v95, v94, v3, vcc
	v_lshlrev_b32_e32 v95, 7, v95
	v_and_b32_e32 v96, 0x1f80, v95
	v_mov_b32_e32 v97, v2
	v_lshl_add_u64 v[96:97], s[14:15], 0, v[96:97]
	v_mov_b32_e32 v151, v2
	v_lshl_add_u64 v[102:103], v[96:97], 0, v[150:151]
	global_load_dwordx4 v[96:99], v[102:103], off
	s_nop 0
	global_load_dwordx4 v[102:105], v[102:103], off offset:16
	s_waitcnt vmcnt(0)
	v_mov_b32_e32 v106, v97
	v_mov_b32_e32 v107, v99
	v_mov_b32_e32 v112, v103
	v_mov_b32_e32 v113, v105
	v_mov_b32_e32 v103, v104
	v_mov_b32_e32 v97, v98
	v_pk_mul_f32 v[98:99], v[88:89], v[106:107]
	v_pk_mul_f32 v[104:105], v[90:91], v[112:113]
	v_pk_mul_f32 v[106:107], v[84:85], v[106:107]
	v_pk_mul_f32 v[112:113], v[86:87], v[112:113]
	v_pk_fma_f32 v[86:87], v[86:87], v[102:103], v[104:105]
	v_pk_fma_f32 v[84:85], v[84:85], v[96:97], v[98:99]
	v_pk_fma_f32 v[90:91], v[90:91], v[102:103], v[112:113] neg_lo:[0,0,1] neg_hi:[0,0,1]
	v_pk_fma_f32 v[88:89], v[88:89], v[96:97], v[106:107] neg_lo:[0,0,1] neg_hi:[0,0,1]
.LBB0_1476:
	s_or_b64 exec, exec, s[28:29]
	v_cvt_pk_bf16_f32 v88, v88, v89
	v_cvt_pk_bf16_f32 v89, v90, v91
	v_cvt_pk_bf16_f32 v90, v84, v85
	v_mov_b64_e32 v[84:85], s[12:13]
	v_mad_i64_i32 v[84:85], s[28:29], v94, s62, v[84:85]
	v_cvt_pk_bf16_f32 v91, v86, v87
	v_lshl_add_u64 v[84:85], v[148:149], 1, v[84:85]
	v_add_u32_e32 v86, 0xa0, v171
	global_store_dwordx4 v[84:85], v[88:91], off sc1
	s_and_saveexec_b64 s[28:29], s[26:27]
	s_cbranch_execz .LBB0_1478
	v_cndmask_b32_e32 v87, v86, v3, vcc
	v_lshlrev_b32_e32 v87, 7, v87
	v_and_b32_e32 v88, 0x1f80, v87
	v_mov_b32_e32 v89, v2
	v_lshl_add_u64 v[88:89], s[14:15], 0, v[88:89]
	v_mov_b32_e32 v151, v2
	v_lshl_add_u64 v[96:97], v[88:89], 0, v[150:151]
	global_load_dwordx4 v[88:91], v[96:97], off
	s_nop 0
	global_load_dwordx4 v[96:99], v[96:97], off offset:16
	s_waitcnt vmcnt(0)
	v_mov_b32_e32 v102, v89
	v_mov_b32_e32 v103, v91
	v_mov_b32_e32 v104, v97
	v_mov_b32_e32 v105, v99
	v_mov_b32_e32 v97, v98
	v_mov_b32_e32 v89, v90
	v_pk_mul_f32 v[90:91], v[80:81], v[102:103]
	v_pk_mul_f32 v[98:99], v[82:83], v[104:105]
	v_pk_mul_f32 v[102:103], v[76:77], v[102:103]
	v_pk_mul_f32 v[104:105], v[78:79], v[104:105]
	v_pk_fma_f32 v[78:79], v[78:79], v[96:97], v[98:99]
	v_pk_fma_f32 v[76:77], v[76:77], v[88:89], v[90:91]
	v_pk_fma_f32 v[82:83], v[82:83], v[96:97], v[104:105] neg_lo:[0,0,1] neg_hi:[0,0,1]
	v_pk_fma_f32 v[80:81], v[80:81], v[88:89], v[102:103] neg_lo:[0,0,1] neg_hi:[0,0,1]
.LBB0_1478:
	s_or_b64 exec, exec, s[28:29]
	v_cvt_pk_bf16_f32 v80, v80, v81
	v_cvt_pk_bf16_f32 v81, v82, v83
	v_cvt_pk_bf16_f32 v82, v76, v77
	v_mov_b64_e32 v[76:77], s[12:13]
	v_mad_i64_i32 v[76:77], s[28:29], v86, s62, v[76:77]
	v_cvt_pk_bf16_f32 v83, v78, v79
	v_lshl_add_u64 v[76:77], v[148:149], 1, v[76:77]
	v_add_u32_e32 v78, 0xb0, v171
	global_store_dwordx4 v[76:77], v[80:83], off sc1
	s_and_saveexec_b64 s[28:29], s[26:27]
	s_cbranch_execz .LBB0_1480
	v_cndmask_b32_e32 v79, v78, v3, vcc
	v_lshlrev_b32_e32 v79, 7, v79
	v_and_b32_e32 v80, 0x1f80, v79
	v_mov_b32_e32 v81, v2
	v_lshl_add_u64 v[80:81], s[14:15], 0, v[80:81]
	v_mov_b32_e32 v151, v2
	v_lshl_add_u64 v[88:89], v[80:81], 0, v[150:151]
	global_load_dwordx4 v[80:83], v[88:89], off
	s_nop 0
	global_load_dwordx4 v[88:91], v[88:89], off offset:16
	s_waitcnt vmcnt(0)
	v_mov_b32_e32 v96, v81
	v_mov_b32_e32 v97, v83
	v_mov_b32_e32 v98, v89
	v_mov_b32_e32 v99, v91
	v_mov_b32_e32 v89, v90
	v_mov_b32_e32 v81, v82
	v_pk_mul_f32 v[82:83], v[72:73], v[96:97]
	v_pk_mul_f32 v[90:91], v[74:75], v[98:99]
	v_pk_mul_f32 v[96:97], v[68:69], v[96:97]
	v_pk_mul_f32 v[98:99], v[70:71], v[98:99]
	v_pk_fma_f32 v[70:71], v[70:71], v[88:89], v[90:91]
	v_pk_fma_f32 v[68:69], v[68:69], v[80:81], v[82:83]
	v_pk_fma_f32 v[74:75], v[74:75], v[88:89], v[98:99] neg_lo:[0,0,1] neg_hi:[0,0,1]
	v_pk_fma_f32 v[72:73], v[72:73], v[80:81], v[96:97] neg_lo:[0,0,1] neg_hi:[0,0,1]
.LBB0_1480:
	s_or_b64 exec, exec, s[28:29]
	v_cvt_pk_bf16_f32 v72, v72, v73
	v_cvt_pk_bf16_f32 v73, v74, v75
	v_cvt_pk_bf16_f32 v74, v68, v69
	v_mov_b64_e32 v[68:69], s[12:13]
	v_cvt_pk_bf16_f32 v75, v70, v71
	v_mad_i64_i32 v[68:69], s[26:27], v78, s62, v[68:69]
	v_or_b32_e32 v70, 0x80, v148
	v_lshl_add_u64 v[68:69], v[148:149], 1, v[68:69]
	v_mul_hi_i32 v71, v70, s56
	global_store_dwordx4 v[68:69], v[72:75], off sc1
	s_nop 1
	v_lshrrev_b32_e32 v72, 31, v71
	v_lshrrev_b32_e32 v71, 5, v71
	v_add_u32_e32 v71, v71, v72
	v_mul_lo_u32 v71, v71, s59
	v_sub_u32_e32 v70, v70, v71
	v_lshrrev_b32_e32 v71, 1, v70
	v_and_b32_e32 v71, 12, v71
	v_cmp_gt_i32_e32 vcc, s60, v70
	s_nor_b64 s[24:25], s[24:25], vcc
	s_nop 0
	v_cndmask_b32_e64 v71, v71, 0, vcc
	v_cmp_gt_i32_e32 vcc, s61, v70
	v_lshlrev_b32_e32 v70, 3, v71
	s_and_saveexec_b64 s[26:27], s[24:25]
	s_cbranch_execz .LBB0_1482
	v_mov_b32_e32 v71, s65
	v_cndmask_b32_e32 v71, v158, v71, vcc
	v_lshlrev_b32_e32 v71, 7, v71
	v_and_b32_e32 v72, 0x1f80, v71
	v_mov_b32_e32 v73, v2
	v_lshl_add_u64 v[72:73], s[14:15], 0, v[72:73]
	v_mov_b32_e32 v71, v2
	v_lshl_add_u64 v[80:81], v[72:73], 0, v[70:71]
	global_load_dwordx4 v[72:75], v[80:81], off
	s_nop 0
	global_load_dwordx4 v[80:83], v[80:81], off offset:16
	s_waitcnt vmcnt(0)
	v_mov_b32_e32 v88, v73
	v_mov_b32_e32 v89, v75
	v_mov_b32_e32 v90, v81
	v_mov_b32_e32 v91, v83
	v_mov_b32_e32 v81, v82
	v_mov_b32_e32 v73, v74
	v_pk_mul_f32 v[74:75], v[64:65], v[88:89]
	v_pk_mul_f32 v[82:83], v[66:67], v[90:91]
	v_pk_mul_f32 v[88:89], v[60:61], v[88:89]
	v_pk_mul_f32 v[90:91], v[62:63], v[90:91]
	v_pk_fma_f32 v[62:63], v[62:63], v[80:81], v[82:83]
	v_pk_fma_f32 v[60:61], v[60:61], v[72:73], v[74:75]
	v_pk_fma_f32 v[66:67], v[66:67], v[80:81], v[90:91] neg_lo:[0,0,1] neg_hi:[0,0,1]
	v_pk_fma_f32 v[64:65], v[64:65], v[72:73], v[88:89] neg_lo:[0,0,1] neg_hi:[0,0,1]
.LBB0_1482:
	s_or_b64 exec, exec, s[26:27]
	v_cvt_pk_bf16_f32 v64, v64, v65
	v_cvt_pk_bf16_f32 v65, v66, v67
	v_cvt_pk_bf16_f32 v66, v60, v61
	v_cvt_pk_bf16_f32 v67, v62, v63
	global_store_dwordx4 v[124:125], v[64:67], off offset:256 sc1
	s_and_saveexec_b64 s[26:27], s[24:25]
	s_cbranch_execz .LBB0_1484
	v_mov_b32_e32 v60, s65
	v_cndmask_b32_e32 v60, v126, v60, vcc
	v_lshlrev_b32_e32 v60, 7, v60
	v_and_b32_e32 v60, 0x1f80, v60
	v_mov_b32_e32 v61, v2
	v_lshl_add_u64 v[60:61], s[14:15], 0, v[60:61]
	v_mov_b32_e32 v71, v2
	v_lshl_add_u64 v[64:65], v[60:61], 0, v[70:71]
	global_load_dwordx4 v[60:63], v[64:65], off
	s_nop 0
	global_load_dwordx4 v[64:67], v[64:65], off offset:16
	s_waitcnt vmcnt(0)
	v_mov_b32_e32 v72, v61
	v_mov_b32_e32 v73, v63
	v_mov_b32_e32 v74, v65
	v_mov_b32_e32 v75, v67
	v_mov_b32_e32 v65, v66
	v_mov_b32_e32 v61, v62
	v_pk_mul_f32 v[62:63], v[56:57], v[72:73]
	v_pk_mul_f32 v[66:67], v[58:59], v[74:75]
	v_pk_mul_f32 v[72:73], v[52:53], v[72:73]
	v_pk_mul_f32 v[74:75], v[54:55], v[74:75]
	v_pk_fma_f32 v[54:55], v[54:55], v[64:65], v[66:67]
	v_pk_fma_f32 v[52:53], v[52:53], v[60:61], v[62:63]
	v_pk_fma_f32 v[58:59], v[58:59], v[64:65], v[74:75] neg_lo:[0,0,1] neg_hi:[0,0,1]
	v_pk_fma_f32 v[56:57], v[56:57], v[60:61], v[72:73] neg_lo:[0,0,1] neg_hi:[0,0,1]
.LBB0_1484:
	s_or_b64 exec, exec, s[26:27]
	v_cvt_pk_bf16_f32 v56, v56, v57
	v_cvt_pk_bf16_f32 v57, v58, v59
	v_cvt_pk_bf16_f32 v58, v52, v53
	v_cvt_pk_bf16_f32 v59, v54, v55
	global_store_dwordx4 v[116:117], v[56:59], off offset:256 sc1
	s_and_saveexec_b64 s[26:27], s[24:25]
	s_cbranch_execz .LBB0_1486
	v_mov_b32_e32 v52, s65
	v_cndmask_b32_e32 v52, v118, v52, vcc
	v_lshlrev_b32_e32 v52, 7, v52
	v_and_b32_e32 v52, 0x1f80, v52
	v_mov_b32_e32 v53, v2
	v_lshl_add_u64 v[52:53], s[14:15], 0, v[52:53]
	v_mov_b32_e32 v71, v2
	v_lshl_add_u64 v[56:57], v[52:53], 0, v[70:71]
	global_load_dwordx4 v[52:55], v[56:57], off
	s_nop 0
	global_load_dwordx4 v[56:59], v[56:57], off offset:16
	s_waitcnt vmcnt(0)
	v_mov_b32_e32 v60, v53
	v_mov_b32_e32 v61, v55
	v_mov_b32_e32 v62, v57
	v_mov_b32_e32 v63, v59
	v_mov_b32_e32 v57, v58
	v_mov_b32_e32 v53, v54
	v_pk_mul_f32 v[54:55], v[48:49], v[60:61]
	v_pk_mul_f32 v[58:59], v[50:51], v[62:63]
	v_pk_mul_f32 v[60:61], v[44:45], v[60:61]
	v_pk_mul_f32 v[62:63], v[46:47], v[62:63]
	v_pk_fma_f32 v[46:47], v[46:47], v[56:57], v[58:59]
	v_pk_fma_f32 v[44:45], v[44:45], v[52:53], v[54:55]
	v_pk_fma_f32 v[50:51], v[50:51], v[56:57], v[62:63] neg_lo:[0,0,1] neg_hi:[0,0,1]
	v_pk_fma_f32 v[48:49], v[48:49], v[52:53], v[60:61] neg_lo:[0,0,1] neg_hi:[0,0,1]
.LBB0_1486:
	s_or_b64 exec, exec, s[26:27]
	v_cvt_pk_bf16_f32 v48, v48, v49
	v_cvt_pk_bf16_f32 v49, v50, v51
	v_cvt_pk_bf16_f32 v50, v44, v45
	v_cvt_pk_bf16_f32 v51, v46, v47
	global_store_dwordx4 v[108:109], v[48:51], off offset:256 sc1
	s_and_saveexec_b64 s[26:27], s[24:25]
	s_cbranch_execz .LBB0_1488
	v_mov_b32_e32 v44, s65
	v_cndmask_b32_e32 v44, v110, v44, vcc
	v_lshlrev_b32_e32 v44, 7, v44
	v_and_b32_e32 v44, 0x1f80, v44
	v_mov_b32_e32 v45, v2
	v_lshl_add_u64 v[44:45], s[14:15], 0, v[44:45]
	v_mov_b32_e32 v71, v2
	v_lshl_add_u64 v[48:49], v[44:45], 0, v[70:71]
	global_load_dwordx4 v[44:47], v[48:49], off
	s_nop 0
	global_load_dwordx4 v[48:51], v[48:49], off offset:16
	s_waitcnt vmcnt(0)
	v_mov_b32_e32 v52, v45
	v_mov_b32_e32 v53, v47
	v_mov_b32_e32 v54, v49
	v_mov_b32_e32 v55, v51
	v_mov_b32_e32 v49, v50
	v_mov_b32_e32 v45, v46
	v_pk_mul_f32 v[46:47], v[40:41], v[52:53]
	v_pk_mul_f32 v[50:51], v[42:43], v[54:55]
	v_pk_mul_f32 v[52:53], v[36:37], v[52:53]
	v_pk_mul_f32 v[54:55], v[38:39], v[54:55]
	v_pk_fma_f32 v[38:39], v[38:39], v[48:49], v[50:51]
	v_pk_fma_f32 v[36:37], v[36:37], v[44:45], v[46:47]
	v_pk_fma_f32 v[42:43], v[42:43], v[48:49], v[54:55] neg_lo:[0,0,1] neg_hi:[0,0,1]
	v_pk_fma_f32 v[40:41], v[40:41], v[44:45], v[52:53] neg_lo:[0,0,1] neg_hi:[0,0,1]
.LBB0_1488:
	s_or_b64 exec, exec, s[26:27]
	v_cvt_pk_bf16_f32 v40, v40, v41
	v_cvt_pk_bf16_f32 v41, v42, v43
	v_cvt_pk_bf16_f32 v42, v36, v37
	v_cvt_pk_bf16_f32 v43, v38, v39
	global_store_dwordx4 v[100:101], v[40:43], off offset:256 sc1
	s_and_saveexec_b64 s[26:27], s[24:25]
	s_cbranch_execz .LBB0_1490
	v_cndmask_b32_e32 v36, v158, v3, vcc
	v_lshlrev_b32_e32 v36, 7, v36
	v_and_b32_e32 v36, 0x1f80, v36
	v_mov_b32_e32 v37, v2
	v_lshl_add_u64 v[36:37], s[14:15], 0, v[36:37]
	v_mov_b32_e32 v71, v2
	v_lshl_add_u64 v[40:41], v[36:37], 0, v[70:71]
	global_load_dwordx4 v[36:39], v[40:41], off
	s_nop 0
	global_load_dwordx4 v[40:43], v[40:41], off offset:16
	s_waitcnt vmcnt(0)
	v_mov_b32_e32 v44, v37
	v_mov_b32_e32 v45, v39
	v_mov_b32_e32 v46, v41
	v_mov_b32_e32 v47, v43
	v_mov_b32_e32 v41, v42
	v_mov_b32_e32 v37, v38
	v_pk_mul_f32 v[38:39], v[32:33], v[44:45]
	v_pk_mul_f32 v[42:43], v[34:35], v[46:47]
	v_pk_mul_f32 v[44:45], v[28:29], v[44:45]
	v_pk_mul_f32 v[46:47], v[30:31], v[46:47]
	v_pk_fma_f32 v[30:31], v[30:31], v[40:41], v[42:43]
	v_pk_fma_f32 v[28:29], v[28:29], v[36:37], v[38:39]
	v_pk_fma_f32 v[34:35], v[34:35], v[40:41], v[46:47] neg_lo:[0,0,1] neg_hi:[0,0,1]
	v_pk_fma_f32 v[32:33], v[32:33], v[36:37], v[44:45] neg_lo:[0,0,1] neg_hi:[0,0,1]
.LBB0_1490:
	s_or_b64 exec, exec, s[26:27]
	v_cvt_pk_bf16_f32 v32, v32, v33
	v_cvt_pk_bf16_f32 v33, v34, v35
	v_cvt_pk_bf16_f32 v34, v28, v29
	v_cvt_pk_bf16_f32 v35, v30, v31
	global_store_dwordx4 v[92:93], v[32:35], off offset:256 sc1
	s_and_saveexec_b64 s[26:27], s[24:25]
	s_cbranch_execz .LBB0_1492
	v_cndmask_b32_e32 v28, v94, v3, vcc
	v_lshlrev_b32_e32 v28, 7, v28
	v_and_b32_e32 v28, 0x1f80, v28
	v_mov_b32_e32 v29, v2
	v_lshl_add_u64 v[28:29], s[14:15], 0, v[28:29]
	v_mov_b32_e32 v71, v2
	v_lshl_add_u64 v[32:33], v[28:29], 0, v[70:71]
	global_load_dwordx4 v[28:31], v[32:33], off
	s_nop 0
	global_load_dwordx4 v[32:35], v[32:33], off offset:16
	s_waitcnt vmcnt(0)
	v_mov_b32_e32 v36, v29
	v_mov_b32_e32 v37, v31
	v_mov_b32_e32 v38, v33
	v_mov_b32_e32 v39, v35
	v_mov_b32_e32 v33, v34
	v_mov_b32_e32 v29, v30
	v_pk_mul_f32 v[30:31], v[24:25], v[36:37]
	v_pk_mul_f32 v[34:35], v[26:27], v[38:39]
	v_pk_mul_f32 v[36:37], v[20:21], v[36:37]
	v_pk_mul_f32 v[38:39], v[22:23], v[38:39]
	v_pk_fma_f32 v[22:23], v[22:23], v[32:33], v[34:35]
	v_pk_fma_f32 v[20:21], v[20:21], v[28:29], v[30:31]
	v_pk_fma_f32 v[26:27], v[26:27], v[32:33], v[38:39] neg_lo:[0,0,1] neg_hi:[0,0,1]
	v_pk_fma_f32 v[24:25], v[24:25], v[28:29], v[36:37] neg_lo:[0,0,1] neg_hi:[0,0,1]
.LBB0_1492:
	s_or_b64 exec, exec, s[26:27]
	v_cvt_pk_bf16_f32 v24, v24, v25
	v_cvt_pk_bf16_f32 v25, v26, v27
	v_cvt_pk_bf16_f32 v26, v20, v21
	v_cvt_pk_bf16_f32 v27, v22, v23
	global_store_dwordx4 v[84:85], v[24:27], off offset:256 sc1
	s_and_saveexec_b64 s[26:27], s[24:25]
	s_cbranch_execz .LBB0_1494
	v_cndmask_b32_e32 v20, v86, v3, vcc
	v_lshlrev_b32_e32 v20, 7, v20
	v_and_b32_e32 v20, 0x1f80, v20
	v_mov_b32_e32 v21, v2
	v_lshl_add_u64 v[20:21], s[14:15], 0, v[20:21]
	v_mov_b32_e32 v71, v2
	v_lshl_add_u64 v[24:25], v[20:21], 0, v[70:71]
	global_load_dwordx4 v[20:23], v[24:25], off
	s_nop 0
	global_load_dwordx4 v[24:27], v[24:25], off offset:16
	s_waitcnt vmcnt(0)
	v_mov_b32_e32 v28, v21
	v_mov_b32_e32 v29, v23
	v_mov_b32_e32 v30, v25
	v_mov_b32_e32 v31, v27
	v_mov_b32_e32 v25, v26
	v_mov_b32_e32 v21, v22
	v_pk_mul_f32 v[22:23], v[16:17], v[28:29]
	v_pk_mul_f32 v[26:27], v[18:19], v[30:31]
	v_pk_mul_f32 v[28:29], v[12:13], v[28:29]
	v_pk_mul_f32 v[30:31], v[14:15], v[30:31]
	v_pk_fma_f32 v[14:15], v[14:15], v[24:25], v[26:27]
	v_pk_fma_f32 v[12:13], v[12:13], v[20:21], v[22:23]
	v_pk_fma_f32 v[18:19], v[18:19], v[24:25], v[30:31] neg_lo:[0,0,1] neg_hi:[0,0,1]
	v_pk_fma_f32 v[16:17], v[16:17], v[20:21], v[28:29] neg_lo:[0,0,1] neg_hi:[0,0,1]
.LBB0_1494:
	s_or_b64 exec, exec, s[26:27]
	v_cvt_pk_bf16_f32 v16, v16, v17
	v_cvt_pk_bf16_f32 v17, v18, v19
	v_cvt_pk_bf16_f32 v18, v12, v13
	v_cvt_pk_bf16_f32 v19, v14, v15
	global_store_dwordx4 v[76:77], v[16:19], off offset:256 sc1
	s_and_saveexec_b64 s[26:27], s[24:25]
	s_cbranch_execz .LBB0_1496
	v_cndmask_b32_e32 v3, v78, v3, vcc
	v_lshlrev_b32_e32 v3, 7, v3
	v_and_b32_e32 v12, 0x1f80, v3
	v_mov_b32_e32 v13, v2
	v_lshl_add_u64 v[12:13], s[14:15], 0, v[12:13]
	v_mov_b32_e32 v71, v2
	v_lshl_add_u64 v[16:17], v[12:13], 0, v[70:71]
	global_load_dwordx4 v[12:15], v[16:17], off
	s_nop 0
	global_load_dwordx4 v[16:19], v[16:17], off offset:16
	s_waitcnt vmcnt(0)
	v_mov_b32_e32 v20, v13
	v_mov_b32_e32 v21, v15
	v_mov_b32_e32 v22, v17
	v_mov_b32_e32 v23, v19
	v_mov_b32_e32 v17, v18
	v_mov_b32_e32 v13, v14
	v_pk_mul_f32 v[14:15], v[8:9], v[20:21]
	v_pk_mul_f32 v[18:19], v[10:11], v[22:23]
	v_pk_mul_f32 v[20:21], v[4:5], v[20:21]
	v_pk_mul_f32 v[22:23], v[6:7], v[22:23]
	v_pk_fma_f32 v[6:7], v[6:7], v[16:17], v[18:19]
	v_pk_fma_f32 v[4:5], v[4:5], v[12:13], v[14:15]
	v_pk_fma_f32 v[10:11], v[10:11], v[16:17], v[22:23] neg_lo:[0,0,1] neg_hi:[0,0,1]
	v_pk_fma_f32 v[8:9], v[8:9], v[12:13], v[20:21] neg_lo:[0,0,1] neg_hi:[0,0,1]
.LBB0_1496:
	s_or_b64 exec, exec, s[26:27]
	s_and_b64 vcc, exec, s[0:1]
	s_mov_b64 s[0:1], -1
	v_cvt_pk_bf16_f32 v8, v8, v9
	v_cvt_pk_bf16_f32 v9, v10, v11
	v_cvt_pk_bf16_f32 v10, v4, v5
	v_cvt_pk_bf16_f32 v11, v6, v7
	global_store_dwordx4 v[68:69], v[8:11], off offset:256 sc1
	s_cbranch_vccnz .LBB0_1452
	s_andn2_b64 vcc, exec, s[10:11]
	s_cbranch_vccnz .LBB0_1451
	s_barrier
	s_branch .LBB0_1451

.LBB0_1517:
	v_lshl_add_u32 v152, s63, 8, v146
	v_lshl_or_b32 v154, s66, 7, v148
	v_ashrrev_i32_e32 v153, 31, v152
	v_ashrrev_i32_e32 v155, 31, v154
	v_lshlrev_b64 v[156:157], 11, v[152:153]
	v_lshl_add_u64 v[156:157], v[156:157], 0, v[154:155]
	v_cvt_pk_bf16_f32 v122, v122, v123
	v_cvt_pk_bf16_f32 v123, v124, v125
	v_cvt_pk_bf16_f32 v124, v126, v127
	v_lshlrev_b64 v[126:127], 1, v[156:157]
	v_cvt_pk_bf16_f32 v125, v128, v129
	v_lshl_add_u64 v[128:129], s[12:13], 0, v[126:127]
	global_store_dwordx4 v[128:129], v[122:125], off sc1
	v_cvt_pk_bf16_f32 v118, v118, v119
	v_cvt_pk_bf16_f32 v119, v120, v121
	v_cvt_pk_bf16_f32 v120, v114, v115
	v_lshl_add_u64 v[114:115], s[14:15], 0, v[126:127]
	v_cvt_pk_bf16_f32 v121, v116, v117
	global_store_dwordx4 v[114:115], v[118:121], off sc1
	v_or_b32_e32 v114, 16, v152
	v_ashrrev_i32_e32 v115, 31, v114
	v_lshlrev_b64 v[114:115], 11, v[114:115]
	v_lshl_add_u64 v[114:115], v[114:115], 0, v[154:155]
	v_cvt_pk_bf16_f32 v110, v110, v111
	v_cvt_pk_bf16_f32 v111, v112, v113
	v_cvt_pk_bf16_f32 v112, v106, v107
	v_lshlrev_b64 v[106:107], 1, v[114:115]
	v_cvt_pk_bf16_f32 v113, v108, v109
	v_lshl_add_u64 v[108:109], s[12:13], 0, v[106:107]
	global_store_dwordx4 v[108:109], v[110:113], off sc1
	v_cvt_pk_bf16_f32 v102, v102, v103
	v_cvt_pk_bf16_f32 v103, v104, v105
	v_cvt_pk_bf16_f32 v104, v98, v99
	v_lshl_add_u64 v[98:99], s[14:15], 0, v[106:107]
	v_cvt_pk_bf16_f32 v105, v100, v101
	global_store_dwordx4 v[98:99], v[102:105], off sc1
	v_or_b32_e32 v98, 32, v152
	v_ashrrev_i32_e32 v99, 31, v98
	v_lshlrev_b64 v[98:99], 11, v[98:99]
	v_lshl_add_u64 v[98:99], v[98:99], 0, v[154:155]
	v_cvt_pk_bf16_f32 v94, v94, v95
	v_cvt_pk_bf16_f32 v95, v96, v97
	v_cvt_pk_bf16_f32 v96, v90, v91
	v_lshlrev_b64 v[90:91], 1, v[98:99]
	v_cvt_pk_bf16_f32 v97, v92, v93
	v_lshl_add_u64 v[92:93], s[12:13], 0, v[90:91]
	global_store_dwordx4 v[92:93], v[94:97], off sc1
	v_cvt_pk_bf16_f32 v86, v86, v87
	v_cvt_pk_bf16_f32 v87, v88, v89
	v_cvt_pk_bf16_f32 v88, v82, v83
	v_lshl_add_u64 v[82:83], s[14:15], 0, v[90:91]
	v_cvt_pk_bf16_f32 v89, v84, v85
	global_store_dwordx4 v[82:83], v[86:89], off sc1
	v_or_b32_e32 v82, 48, v152
	v_ashrrev_i32_e32 v83, 31, v82
	v_lshlrev_b64 v[82:83], 11, v[82:83]
	v_lshl_add_u64 v[82:83], v[82:83], 0, v[154:155]
	v_cvt_pk_bf16_f32 v78, v78, v79
	v_cvt_pk_bf16_f32 v79, v80, v81
	v_cvt_pk_bf16_f32 v80, v74, v75
	v_lshlrev_b64 v[74:75], 1, v[82:83]
	v_cvt_pk_bf16_f32 v81, v76, v77
	v_lshl_add_u64 v[76:77], s[12:13], 0, v[74:75]
	global_store_dwordx4 v[76:77], v[78:81], off sc1
	v_cvt_pk_bf16_f32 v70, v70, v71
	v_cvt_pk_bf16_f32 v71, v72, v73
	v_cvt_pk_bf16_f32 v72, v66, v67
	v_lshl_add_u64 v[66:67], s[14:15], 0, v[74:75]
	v_cvt_pk_bf16_f32 v73, v68, v69
	global_store_dwordx4 v[66:67], v[70:73], off sc1
	v_cvt_pk_bf16_f32 v62, v62, v63
	v_cvt_pk_bf16_f32 v63, v64, v65
	v_cvt_pk_bf16_f32 v64, v58, v59
	v_lshl_add_u64 v[58:59], v[126:127], 0, s[22:23]
	v_cvt_pk_bf16_f32 v65, v60, v61
	v_lshl_add_u64 v[60:61], s[12:13], 0, v[58:59]
	global_store_dwordx4 v[60:61], v[62:65], off sc1
	v_cvt_pk_bf16_f32 v54, v54, v55
	v_cvt_pk_bf16_f32 v55, v56, v57
	v_cvt_pk_bf16_f32 v56, v50, v51
	v_lshl_add_u64 v[50:51], s[14:15], 0, v[58:59]
	v_cvt_pk_bf16_f32 v57, v52, v53
	global_store_dwordx4 v[50:51], v[54:57], off sc1
	v_cvt_pk_bf16_f32 v46, v46, v47
	v_cvt_pk_bf16_f32 v47, v48, v49
	v_cvt_pk_bf16_f32 v48, v42, v43
	v_lshl_add_u64 v[42:43], v[126:127], 0, s[24:25]
	v_cvt_pk_bf16_f32 v49, v44, v45
	v_lshl_add_u64 v[44:45], s[12:13], 0, v[42:43]
	global_store_dwordx4 v[44:45], v[46:49], off sc1
	v_cvt_pk_bf16_f32 v38, v38, v39
	v_cvt_pk_bf16_f32 v39, v40, v41
	v_cvt_pk_bf16_f32 v40, v34, v35
	v_lshl_add_u64 v[34:35], s[14:15], 0, v[42:43]
	v_cvt_pk_bf16_f32 v41, v36, v37
	global_store_dwordx4 v[34:35], v[38:41], off sc1
	v_cvt_pk_bf16_f32 v30, v30, v31
	v_cvt_pk_bf16_f32 v31, v32, v33
	v_cvt_pk_bf16_f32 v32, v26, v27
	v_lshl_add_u64 v[26:27], v[126:127], 0, s[26:27]
	v_cvt_pk_bf16_f32 v33, v28, v29
	v_lshl_add_u64 v[28:29], s[12:13], 0, v[26:27]
	global_store_dwordx4 v[28:29], v[30:33], off sc1
	v_cvt_pk_bf16_f32 v22, v22, v23
	v_cvt_pk_bf16_f32 v23, v24, v25
	v_cvt_pk_bf16_f32 v24, v18, v19
	v_lshl_add_u64 v[18:19], s[14:15], 0, v[26:27]
	v_cvt_pk_bf16_f32 v25, v20, v21
	global_store_dwordx4 v[18:19], v[22:25], off sc1
	v_cvt_pk_bf16_f32 v14, v14, v15
	v_cvt_pk_bf16_f32 v15, v16, v17
	v_cvt_pk_bf16_f32 v16, v10, v11
	v_lshl_add_u64 v[10:11], v[126:127], 0, s[28:29]
	v_cvt_pk_bf16_f32 v17, v12, v13
	v_lshl_add_u64 v[12:13], s[12:13], 0, v[10:11]
	global_store_dwordx4 v[12:13], v[14:17], off sc1
	v_cvt_pk_bf16_f32 v6, v6, v7
	v_cvt_pk_bf16_f32 v7, v8, v9
	v_cvt_pk_bf16_f32 v8, v2, v3
	v_lshl_add_u64 v[2:3], s[14:15], 0, v[10:11]
	s_and_b64 vcc, exec, s[0:1]
	s_mov_b64 s[0:1], -1
	v_cvt_pk_bf16_f32 v9, v4, v5
	global_store_dwordx4 v[2:3], v[6:9], off sc1
	s_cbranch_vccnz .LBB0_1505
	s_andn2_b64 vcc, exec, s[10:11]
	s_cbranch_vccnz .LBB0_1504
	s_barrier
	s_branch .LBB0_1504

.LBB0_1758:
	s_lshr_b32 s42, s85, 4
	s_add_i32 s42, s42, -1
	s_cmp_gt_i32 s85, 31
	s_cselect_b32 s42, s42, 0
	v_lshl_or_b32 v90, s12, 8, v230
	s_mul_i32 s45, s42, 0xc000
	s_mul_hi_i32 s44, s42, 0xc000
	s_add_u32 s42, s59, s45
	v_ashrrev_i32_e32 v91, 31, v90
	s_addc_u32 s43, s60, s44
	v_lshlrev_b64 v[36:37], 2, v[90:91]
	v_lshl_add_u64 v[26:27], s[42:43], 0, v[36:37]
	v_lshl_add_u64 v[28:29], s[20:21], 0, v[36:37]
	s_waitcnt lgkmcnt(0)
	global_load_dwordx4 v[2:5], v[26:27], off offset:16
	global_load_dwordx4 v[6:9], v[26:27], off
	global_load_dwordx4 v[10:13], v[28:29], off offset:16
	global_load_dwordx4 v[14:17], v[28:29], off
	s_add_u32 s42, s61, s45
	v_lshl_add_u64 v[30:31], s[24:25], 0, v[36:37]
	s_addc_u32 s43, s62, s44
	v_lshl_add_u64 v[32:33], s[42:43], 0, v[36:37]
	v_lshl_add_u32 v210, s85, 8, v228
	v_ashrrev_i32_e32 v211, 31, v210
	v_or_b32_e32 v34, 16, v210
	v_ashrrev_i32_e32 v35, 31, v34
	s_lshl_b32 s42, s12, 2
	s_ashr_i32 s43, s42, 31
	s_waitcnt vmcnt(0)
	v_pk_mul_f32 v[92:93], v[4:5], v[12:13]
	v_pk_mul_f32 v[86:87], v[8:9], v[16:17]
	v_pk_mul_f32 v[88:89], v[6:7], v[14:15]
	global_load_dwordx4 v[6:9], v[30:31], off offset:16
	global_load_dwordx4 v[14:17], v[30:31], off
	global_load_dwordx4 v[18:21], v[32:33], off offset:16
	global_load_dwordx4 v[22:25], v[32:33], off
	v_pk_mul_f32 v[94:95], v[2:3], v[10:11]
	s_waitcnt vmcnt(0)
	v_pk_add_f32 v[2:3], v[20:21], 1.0 op_sel_hi:[1,0]
	v_pk_add_f32 v[24:25], v[24:25], 1.0 op_sel_hi:[1,0]
	v_pk_add_f32 v[22:23], v[22:23], 1.0 op_sel_hi:[1,0]
	v_pk_add_f32 v[4:5], v[18:19], 1.0 op_sel_hi:[1,0]
	v_pk_mul_f32 v[78:79], v[16:17], v[24:25]
	v_pk_mul_f32 v[80:81], v[14:15], v[22:23]
	v_pk_mul_f32 v[82:83], v[8:9], v[2:3]
	v_pk_mul_f32 v[84:85], v[6:7], v[4:5]
	global_load_dwordx4 v[2:5], v[26:27], off offset:528
	global_load_dwordx4 v[6:9], v[26:27], off offset:512
	global_load_dwordx4 v[10:13], v[28:29], off offset:528
	global_load_dwordx4 v[14:17], v[28:29], off offset:512
	s_waitcnt vmcnt(0)
	v_pk_mul_f32 v[108:109], v[2:3], v[10:11]
	v_pk_mul_f32 v[104:105], v[8:9], v[16:17]
	v_pk_mul_f32 v[106:107], v[6:7], v[14:15]
	global_load_dwordx4 v[6:9], v[30:31], off offset:528
	global_load_dwordx4 v[14:17], v[30:31], off offset:512
	global_load_dwordx4 v[18:21], v[32:33], off offset:528
	global_load_dwordx4 v[22:25], v[32:33], off offset:512
	v_pk_mul_f32 v[110:111], v[4:5], v[12:13]
	s_waitcnt vmcnt(0)
	v_pk_add_f32 v[2:3], v[20:21], 1.0 op_sel_hi:[1,0]
	s_nop 0
	v_pk_mul_f32 v[100:101], v[8:9], v[2:3]
	v_lshlrev_b64 v[2:3], 13, v[210:211]
	v_lshl_add_u64 v[2:3], s[16:17], 0, v[2:3]
	v_lshl_add_u64 v[38:39], v[2:3], 0, v[36:37]
	v_lshlrev_b64 v[2:3], 13, v[34:35]
	v_lshl_add_u64 v[2:3], s[16:17], 0, v[2:3]
	v_pk_add_f32 v[24:25], v[24:25], 1.0 op_sel_hi:[1,0]
	v_pk_add_f32 v[22:23], v[22:23], 1.0 op_sel_hi:[1,0]
	v_pk_add_f32 v[4:5], v[18:19], 1.0 op_sel_hi:[1,0]
	v_lshl_add_u64 v[36:37], v[2:3], 0, v[36:37]
	v_pk_mul_f32 v[96:97], v[16:17], v[24:25]
	v_pk_mul_f32 v[98:99], v[14:15], v[22:23]
	v_pk_mul_f32 v[102:103], v[6:7], v[4:5]
	global_load_dwordx4 v[22:25], v[38:39], off offset:16 nt
	global_load_dwordx4 v[30:33], v[38:39], off nt
	global_load_dwordx4 v[18:21], v[38:39], off offset:528 nt
	global_load_dwordx4 v[26:29], v[38:39], off offset:512 nt
	global_load_dwordx4 v[10:13], v[36:37], off offset:16 nt
	global_load_dwordx4 v[14:17], v[36:37], off nt
	global_load_dwordx4 v[2:5], v[36:37], off offset:528 nt
	global_load_dwordx4 v[6:9], v[36:37], off offset:512 nt
	v_lshl_add_u64 v[196:197], v[210:211], 2, s[18:19]
	global_load_dword v40, v[196:197], off
	v_and_b32_e32 v44, 64, v232
	v_xor_b32_e32 v41, 16, v232
	v_add_u32_e32 v234, 64, v44
	v_cmp_lt_i32_e32 vcc, v41, v234
	v_lshlrev_b64 v[42:43], 12, v[210:211]
	v_lshl_add_u64 v[42:43], s[22:23], 0, v[42:43]
	v_cndmask_b32_e32 v41, v232, v41, vcc
	v_lshlrev_b32_e32 v233, 2, v41
	v_lshl_add_u64 v[42:43], v[90:91], 1, v[42:43]
	s_waitcnt vmcnt(0)
	v_pk_mul_f32 v[44:45], v[40:41], v[214:215] op_sel_hi:[0,1]
	v_pk_mul_f32 v[212:213], v[40:41], v[212:213] op_sel_hi:[0,1]
	v_pk_mul_f32 v[214:215], v[40:41], v[218:219] op_sel_hi:[0,1]
	v_pk_mul_f32 v[218:219], v[40:41], v[222:223] op_sel_hi:[0,1]
	v_pk_mul_f32 v[220:221], v[40:41], v[220:221] op_sel_hi:[0,1]
	v_pk_mul_f32 v[216:217], v[40:41], v[216:217] op_sel_hi:[0,1]
	v_pk_mul_f32 v[222:223], v[40:41], v[226:227] op_sel_hi:[0,1]
	v_pk_mul_f32 v[40:41], v[40:41], v[224:225] op_sel_hi:[0,1]
	v_pk_fma_f32 v[32:33], v[86:87], v[212:213], v[32:33]
	v_pk_fma_f32 v[30:31], v[88:89], v[44:45], v[30:31]
	v_pk_fma_f32 v[28:29], v[104:105], v[220:221], v[28:29]
	v_pk_fma_f32 v[26:27], v[106:107], v[218:219], v[26:27]
	v_pk_fma_f32 v[24:25], v[92:93], v[216:217], v[24:25]
	v_pk_fma_f32 v[22:23], v[94:95], v[214:215], v[22:23]
	v_pk_fma_f32 v[20:21], v[110:111], v[40:41], v[20:21]
	v_pk_fma_f32 v[18:19], v[108:109], v[222:223], v[18:19]
	global_store_dwordx4 v[38:39], v[30:33], off nt
	global_store_dwordx4 v[38:39], v[22:25], off offset:16 nt
	v_mul_f32_e32 v224, v31, v31
	v_mul_f32_e32 v225, v33, v33
	v_pk_mul_f32 v[40:41], v[78:79], v[32:33]
	v_pk_mul_f32 v[44:45], v[80:81], v[30:31]
	v_mul_f32_e32 v31, v27, v27
	v_mul_f32_e32 v33, v29, v29
	v_mul_f32_e32 v226, v23, v23
	v_mul_f32_e32 v227, v25, v25
	v_mul_f32_e32 v235, v19, v19
	v_fmac_f32_e32 v224, v30, v30
	v_fmac_f32_e32 v225, v32, v32
	v_fmac_f32_e32 v31, v26, v26
	v_fmac_f32_e32 v33, v28, v28
	v_pk_mul_f32 v[212:213], v[82:83], v[24:25]
	v_pk_mul_f32 v[214:215], v[84:85], v[22:23]
	v_mul_f32_e32 v236, v21, v21
	v_pk_mul_f32 v[222:223], v[102:103], v[18:19]
	v_fmac_f32_e32 v226, v22, v22
	v_fmac_f32_e32 v227, v24, v24
	v_cvt_pk_bf16_f32 v22, v44, v45
	v_cvt_pk_bf16_f32 v23, v40, v41
	v_cvt_pk_bf16_f32 v24, v214, v215
	v_cvt_pk_bf16_f32 v25, v212, v213
	v_fmac_f32_e32 v235, v18, v18
	v_add_f32_e32 v30, v224, v225
	global_store_dwordx4 v[42:43], v[22:25], off sc1
	v_lshlrev_b32_e32 v32, 16, v22
	v_and_b32_e32 v40, 0xffff0000, v22
	global_store_dwordx4 v[38:39], v[26:29], off offset:512 nt
	global_store_dwordx4 v[38:39], v[18:21], off offset:528 nt
	v_pk_mul_f32 v[220:221], v[100:101], v[20:21]
	v_fmac_f32_e32 v236, v20, v20
	v_add_f32_e32 v18, v31, v33
	v_lshlrev_b32_e32 v41, 16, v23
	v_and_b32_e32 v44, 0xffff0000, v23
	v_add_f32_e32 v19, v226, v30
	v_max3_f32 v20, |v32|, 0, |v40|
	v_add_f32_e32 v18, v235, v18
	v_lshlrev_b32_e32 v45, 16, v24
	v_and_b32_e32 v212, 0xffff0000, v24
	v_add_f32_e32 v19, v227, v19
	v_max3_f32 v20, v20, |v41|, |v44|
	v_add_f32_e32 v18, v236, v18
	v_lshlrev_b32_e32 v213, 16, v25
	v_and_b32_e32 v214, 0xffff0000, v25
	v_max3_f32 v20, v20, |v45|, |v212|
	v_add_f32_e32 v18, v19, v18
	v_pk_mul_f32 v[218:219], v[98:99], v[26:27]
	v_max3_f32 v19, v20, |v213|, |v214|
	v_cvt_pk_bf16_f32 v22, v218, v219
	ds_bpermute_b32 v20, v233, v18
	v_lshlrev_b32_e32 v21, 16, v22
	v_and_b32_e32 v26, 0xffff0000, v22
	v_pk_mul_f32 v[216:217], v[96:97], v[28:29]
	v_max3_f32 v19, v19, |v21|, |v26|
	v_cvt_pk_bf16_f32 v23, v216, v217
	v_cvt_pk_bf16_f32 v24, v222, v223
	v_cvt_pk_bf16_f32 v25, v220, v221
	s_waitcnt lgkmcnt(0)
	v_add_f32_e32 v18, v18, v20
	v_lshlrev_b32_e32 v27, 16, v23
	v_and_b32_e32 v28, 0xffff0000, v23
	v_lshlrev_b32_e32 v29, 16, v24
	v_and_b32_e32 v30, 0xffff0000, v24
	v_max3_f32 v19, v19, |v27|, |v28|
	v_max3_f32 v19, v19, |v29|, |v30|
	v_lshlrev_b32_e32 v21, 16, v25
	v_and_b32_e32 v26, 0xffff0000, v25
	v_max3_f32 v21, v19, |v21|, |v26|
	ds_bpermute_b32 v20, v233, v21
	v_xor_b32_e32 v19, 32, v232
	v_cmp_lt_i32_e32 vcc, v19, v234
	global_store_dwordx4 v[42:43], v[22:25], off offset:256 sc1
	s_waitcnt lgkmcnt(0)
	v_max_f32_e32 v20, v20, v20
	v_cndmask_b32_e32 v19, v232, v19, vcc
	v_lshlrev_b32_e32 v216, 2, v19
	v_max_f32_e32 v20, v21, v20
	ds_bpermute_b32 v19, v216, v18
	ds_bpermute_b32 v21, v216, v20
	s_and_saveexec_b64 s[44:45], s[0:1]
	s_cbranch_execz .LBB0_1760
	s_waitcnt lgkmcnt(0)
	v_max_f32_e32 v21, v21, v21
	v_max_f32_e32 v20, v20, v20
	v_add_f32_e32 v23, v18, v19
	v_lshlrev_b64 v[18:19], 7, v[210:211]
	v_max_f32_e32 v22, v20, v21
	v_lshl_add_u64 v[20:21], s[26:27], 0, v[18:19]
	s_lshl_b64 s[86:87], s[42:43], 2
	v_lshl_add_u64 v[18:19], s[28:29], 0, v[18:19]
	v_lshl_add_u64 v[20:21], v[20:21], 0, s[86:87]
	s_lshl_b32 s12, s65, 2
	v_lshl_add_u64 v[18:19], v[18:19], 0, s[86:87]
	v_lshl_add_u64 v[20:21], v[20:21], 0, s[12:13]
	v_lshl_add_u64 v[18:19], v[18:19], 0, s[12:13]
	global_store_dword v[20:21], v23, off
	global_store_dword v[18:19], v22, off
.LBB0_1760:
	s_or_b64 exec, exec, s[44:45]
	v_or_b32_e32 v212, 32, v210
	v_ashrrev_i32_e32 v213, 31, v212
	s_waitcnt lgkmcnt(1)
	v_lshlrev_b64 v[18:19], 13, v[212:213]
	v_lshl_add_u64 v[18:19], s[16:17], 0, v[18:19]
	v_lshl_add_u64 v[214:215], v[90:91], 2, v[18:19]
	global_load_dwordx4 v[26:29], v[214:215], off offset:16 nt
	global_load_dwordx4 v[30:33], v[214:215], off nt
	s_waitcnt lgkmcnt(0)
	global_load_dwordx4 v[18:21], v[214:215], off offset:528 nt
	global_load_dwordx4 v[22:25], v[214:215], off offset:512 nt
	v_lshl_add_u64 v[38:39], v[34:35], 2, s[18:19]
	global_load_dword v38, v[38:39], off
	v_lshlrev_b64 v[40:41], 12, v[34:35]
	v_lshl_add_u64 v[40:41], s[22:23], 0, v[40:41]
	v_lshl_add_u64 v[40:41], v[90:91], 1, v[40:41]
	s_waitcnt vmcnt(0)
	v_pk_mul_f32 v[44:45], v[38:39], v[192:193] op_sel_hi:[0,1]
	v_pk_mul_f32 v[192:193], v[38:39], v[200:201] op_sel_hi:[0,1]
	v_pk_mul_f32 v[42:43], v[38:39], v[194:195] op_sel_hi:[0,1]
	v_pk_mul_f32 v[194:195], v[38:39], v[198:199] op_sel_hi:[0,1]
	v_pk_mul_f32 v[198:199], v[38:39], v[206:207] op_sel_hi:[0,1]
	v_pk_mul_f32 v[200:201], v[38:39], v[202:203] op_sel_hi:[0,1]
	v_pk_fma_f32 v[10:11], v[94:95], v[192:193], v[10:11]
	v_pk_mul_f32 v[202:203], v[38:39], v[208:209] op_sel_hi:[0,1]
	v_pk_mul_f32 v[38:39], v[38:39], v[204:205] op_sel_hi:[0,1]
	v_pk_fma_f32 v[16:17], v[86:87], v[44:45], v[16:17]
	v_pk_fma_f32 v[14:15], v[88:89], v[42:43], v[14:15]
	v_pk_fma_f32 v[12:13], v[92:93], v[194:195], v[12:13]
	v_pk_fma_f32 v[8:9], v[104:105], v[200:201], v[8:9]
	v_pk_fma_f32 v[6:7], v[106:107], v[198:199], v[6:7]
	v_mul_f32_e32 v206, v11, v11
	v_pk_fma_f32 v[4:5], v[110:111], v[38:39], v[4:5]
	v_pk_fma_f32 v[2:3], v[108:109], v[202:203], v[2:3]
	global_store_dwordx4 v[36:37], v[14:17], off nt
	global_store_dwordx4 v[36:37], v[10:13], off offset:16 nt
	v_mul_f32_e32 v204, v15, v15
	v_mul_f32_e32 v205, v17, v17
	v_mul_f32_e32 v207, v13, v13
	v_pk_mul_f32 v[38:39], v[78:79], v[16:17]
	v_pk_mul_f32 v[42:43], v[80:81], v[14:15]
	v_pk_mul_f32 v[192:193], v[84:85], v[10:11]
	v_mul_f32_e32 v15, v7, v7
	v_mul_f32_e32 v17, v9, v9
	v_fmac_f32_e32 v206, v10, v10
	v_cvt_pk_bf16_f32 v10, v42, v43
	v_pk_mul_f32 v[44:45], v[82:83], v[12:13]
	v_mul_f32_e32 v208, v3, v3
	v_mul_f32_e32 v209, v5, v5
	v_fmac_f32_e32 v204, v14, v14
	v_fmac_f32_e32 v205, v16, v16
	v_fmac_f32_e32 v207, v12, v12
	v_cvt_pk_bf16_f32 v11, v38, v39
	v_cvt_pk_bf16_f32 v12, v192, v193
	v_cvt_pk_bf16_f32 v13, v44, v45
	v_fmac_f32_e32 v15, v6, v6
	v_fmac_f32_e32 v17, v8, v8
	global_store_dwordx4 v[40:41], v[10:13], off sc1
	v_lshlrev_b32_e32 v16, 16, v10
	v_pk_mul_f32 v[200:201], v[100:101], v[4:5]
	v_and_b32_e32 v10, 0xffff0000, v10
	v_pk_mul_f32 v[202:203], v[102:103], v[2:3]
	v_fmac_f32_e32 v208, v2, v2
	v_fmac_f32_e32 v209, v4, v4
	v_add_f32_e32 v14, v204, v205
	v_lshlrev_b32_e32 v38, 16, v11
	v_and_b32_e32 v11, 0xffff0000, v11
	global_store_dwordx4 v[36:37], v[6:9], off offset:512 nt
	global_store_dwordx4 v[36:37], v[2:5], off offset:528 nt
	v_lshlrev_b32_e32 v39, 16, v12
	v_and_b32_e32 v12, 0xffff0000, v12
	v_add_f32_e32 v2, v15, v17
	v_max3_f32 v4, |v16|, 0, |v10|
	v_add_f32_e32 v3, v206, v14
	v_add_f32_e32 v2, v208, v2
	v_max3_f32 v4, v4, |v38|, |v11|
	v_lshlrev_b32_e32 v42, 16, v13
	v_and_b32_e32 v13, 0xffff0000, v13
	v_add_f32_e32 v3, v207, v3
	v_add_f32_e32 v2, v209, v2
	v_max3_f32 v4, v4, |v39|, |v12|
	v_pk_mul_f32 v[198:199], v[98:99], v[6:7]
	v_add_f32_e32 v2, v3, v2
	v_cvt_pk_bf16_f32 v6, v198, v199
	v_max3_f32 v3, v4, |v42|, |v13|
	v_lshlrev_b32_e32 v5, 16, v6
	v_and_b32_e32 v10, 0xffff0000, v6
	v_pk_mul_f32 v[194:195], v[96:97], v[8:9]
	v_max3_f32 v3, v3, |v5|, |v10|
	v_cvt_pk_bf16_f32 v7, v194, v195
	v_cvt_pk_bf16_f32 v8, v202, v203
	v_cvt_pk_bf16_f32 v9, v200, v201
	ds_bpermute_b32 v4, v233, v2
	v_lshlrev_b32_e32 v14, 16, v7
	v_and_b32_e32 v15, 0xffff0000, v7
	v_lshlrev_b32_e32 v16, 16, v8
	v_and_b32_e32 v17, 0xffff0000, v8
	v_max3_f32 v3, v3, |v14|, |v15|
	v_lshlrev_b32_e32 v36, 16, v9
	v_and_b32_e32 v37, 0xffff0000, v9
	v_max3_f32 v3, v3, |v16|, |v17|
	v_max3_f32 v5, v3, |v36|, |v37|
	ds_bpermute_b32 v10, v233, v5
	s_waitcnt lgkmcnt(1)
	v_add_f32_e32 v2, v2, v4
	ds_bpermute_b32 v3, v216, v2
	global_store_dwordx4 v[40:41], v[6:9], off offset:256 sc1
	s_waitcnt lgkmcnt(1)
	v_max_f32_e32 v4, v10, v10
	v_max_f32_e32 v4, v5, v4
	ds_bpermute_b32 v5, v216, v4
	s_and_saveexec_b64 s[44:45], s[0:1]
	s_cbranch_execz .LBB0_1762
	s_waitcnt lgkmcnt(0)
	v_max_f32_e32 v5, v5, v5
	v_max_f32_e32 v4, v4, v4
	v_add_f32_e32 v7, v2, v3
	v_lshlrev_b64 v[2:3], 7, v[34:35]
	v_max_f32_e32 v6, v4, v5
	v_lshl_add_u64 v[4:5], s[26:27], 0, v[2:3]
	s_lshl_b64 s[86:87], s[42:43], 2
	v_lshl_add_u64 v[2:3], s[28:29], 0, v[2:3]
	v_lshl_add_u64 v[4:5], v[4:5], 0, s[86:87]
	s_lshl_b32 s12, s65, 2
	v_lshl_add_u64 v[2:3], v[2:3], 0, s[86:87]
	v_lshl_add_u64 v[4:5], v[4:5], 0, s[12:13]
	v_lshl_add_u64 v[2:3], v[2:3], 0, s[12:13]
	global_store_dword v[4:5], v7, off
	global_store_dword v[2:3], v6, off
.LBB0_1762:
	s_or_b64 exec, exec, s[44:45]
	v_or_b32_e32 v192, 48, v210
	v_ashrrev_i32_e32 v193, 31, v192
	s_waitcnt lgkmcnt(1)
	v_lshlrev_b64 v[2:3], 13, v[192:193]
	v_lshl_add_u64 v[2:3], s[16:17], 0, v[2:3]
	v_lshl_add_u64 v[194:195], v[90:91], 2, v[2:3]
	global_load_dwordx4 v[38:41], v[194:195], off offset:16 nt
	global_load_dwordx4 v[42:45], v[194:195], off nt
	global_load_dwordx4 v[6:9], v[194:195], off offset:528 nt
	global_load_dwordx4 v[34:37], v[194:195], off offset:512 nt
	v_lshl_add_u64 v[2:3], v[212:213], 2, s[18:19]
	global_load_dword v2, v[2:3], off
	s_waitcnt lgkmcnt(0)
	v_lshlrev_b64 v[4:5], 12, v[212:213]
	v_lshl_add_u64 v[4:5], s[22:23], 0, v[4:5]
	v_lshl_add_u64 v[198:199], v[90:91], 1, v[4:5]
	s_waitcnt vmcnt(0)
	v_pk_mul_f32 v[10:11], v[2:3], v[178:179] op_sel_hi:[0,1]
	v_pk_mul_f32 v[4:5], v[2:3], v[176:177] op_sel_hi:[0,1]
	v_pk_mul_f32 v[14:15], v[2:3], v[182:183] op_sel_hi:[0,1]
	v_pk_mul_f32 v[12:13], v[2:3], v[180:181] op_sel_hi:[0,1]
	v_pk_mul_f32 v[176:177], v[2:3], v[188:189] op_sel_hi:[0,1]
	v_pk_mul_f32 v[16:17], v[2:3], v[184:185] op_sel_hi:[0,1]
	v_pk_mul_f32 v[178:179], v[2:3], v[190:191] op_sel_hi:[0,1]
	v_pk_mul_f32 v[180:181], v[2:3], v[186:187] op_sel_hi:[0,1]
	v_pk_fma_f32 v[2:3], v[88:89], v[10:11], v[30:31]
	v_pk_fma_f32 v[4:5], v[86:87], v[4:5], v[32:33]
	v_pk_fma_f32 v[20:21], v[110:111], v[180:181], v[20:21]
	v_mul_f32_e32 v180, v3, v3
	v_pk_fma_f32 v[12:13], v[92:93], v[12:13], v[28:29]
	v_pk_fma_f32 v[10:11], v[94:95], v[14:15], v[26:27]
	v_pk_fma_f32 v[16:17], v[104:105], v[16:17], v[24:25]
	v_pk_fma_f32 v[14:15], v[106:107], v[176:177], v[22:23]
	global_store_dwordx4 v[214:215], v[2:5], off nt
	global_store_dwordx4 v[214:215], v[10:13], off offset:16 nt
	v_mul_f32_e32 v181, v5, v5
	v_pk_mul_f32 v[22:23], v[78:79], v[4:5]
	v_pk_mul_f32 v[24:25], v[80:81], v[2:3]
	v_fmac_f32_e32 v180, v2, v2
	v_cvt_pk_bf16_f32 v2, v24, v25
	v_pk_mul_f32 v[26:27], v[82:83], v[12:13]
	v_pk_mul_f32 v[28:29], v[84:85], v[10:11]
	v_fmac_f32_e32 v181, v4, v4
	v_cvt_pk_bf16_f32 v3, v22, v23
	v_cvt_pk_bf16_f32 v4, v28, v29
	v_cvt_pk_bf16_f32 v5, v26, v27
	global_store_dwordx4 v[198:199], v[2:5], off sc1
	v_lshlrev_b32_e32 v23, 16, v2
	v_lshlrev_b32_e32 v24, 16, v3
	v_and_b32_e32 v2, 0xffff0000, v2
	v_and_b32_e32 v3, 0xffff0000, v3
	v_max3_f32 v2, |v23|, 0, |v2|
	v_lshlrev_b32_e32 v25, 16, v4
	v_and_b32_e32 v4, 0xffff0000, v4
	v_max3_f32 v2, v2, |v24|, |v3|
	v_pk_fma_f32 v[18:19], v[108:109], v[178:179], v[18:19]
	v_mul_f32_e32 v182, v11, v11
	v_mul_f32_e32 v183, v13, v13
	v_mul_f32_e32 v11, v15, v15
	v_mul_f32_e32 v13, v17, v17
	v_lshlrev_b32_e32 v26, 16, v5
	v_and_b32_e32 v5, 0xffff0000, v5
	v_max3_f32 v2, v2, |v25|, |v4|
	v_mul_f32_e32 v184, v19, v19
	v_pk_mul_f32 v[30:31], v[96:97], v[16:17]
	v_pk_mul_f32 v[32:33], v[98:99], v[14:15]
	v_fmac_f32_e32 v182, v10, v10
	v_fmac_f32_e32 v11, v14, v14
	v_fmac_f32_e32 v13, v16, v16
	global_store_dwordx4 v[214:215], v[14:17], off offset:512 nt
	global_store_dwordx4 v[214:215], v[18:21], off offset:528 nt
	v_cvt_pk_bf16_f32 v10, v32, v33
	v_max3_f32 v2, v2, |v26|, |v5|
	v_lshlrev_b32_e32 v16, 16, v10
	v_and_b32_e32 v17, 0xffff0000, v10
	v_mul_f32_e32 v185, v21, v21
	v_pk_mul_f32 v[178:179], v[102:103], v[18:19]
	v_fmac_f32_e32 v184, v18, v18
	v_add_f32_e32 v22, v180, v181
	v_add_f32_e32 v14, v11, v13
	v_cvt_pk_bf16_f32 v11, v30, v31
	v_max3_f32 v2, v2, |v16|, |v17|
	v_lshlrev_b32_e32 v18, 16, v11
	v_and_b32_e32 v19, 0xffff0000, v11
	v_pk_mul_f32 v[176:177], v[100:101], v[20:21]
	v_fmac_f32_e32 v183, v12, v12
	v_fmac_f32_e32 v185, v20, v20
	v_cvt_pk_bf16_f32 v12, v178, v179
	v_add_f32_e32 v15, v182, v22
	v_add_f32_e32 v14, v184, v14
	v_lshlrev_b32_e32 v20, 16, v12
	v_and_b32_e32 v21, 0xffff0000, v12
	v_max3_f32 v2, v2, |v18|, |v19|
	v_cvt_pk_bf16_f32 v13, v176, v177
	v_add_f32_e32 v15, v183, v15
	v_lshlrev_b32_e32 v22, 16, v13
	v_and_b32_e32 v23, 0xffff0000, v13
	v_add_f32_e32 v3, v185, v14
	v_max3_f32 v2, v2, |v20|, |v21|
	v_add_f32_e32 v3, v15, v3
	v_max3_f32 v5, v2, |v22|, |v23|
	ds_bpermute_b32 v4, v233, v3
	ds_bpermute_b32 v14, v233, v5
	global_store_dwordx4 v[198:199], v[10:13], off offset:256 sc1
	s_waitcnt lgkmcnt(1)
	v_add_f32_e32 v2, v3, v4
	s_waitcnt lgkmcnt(0)
	v_max_f32_e32 v4, v14, v14
	v_max_f32_e32 v4, v5, v4
	ds_bpermute_b32 v3, v216, v2
	ds_bpermute_b32 v5, v216, v4
	s_and_saveexec_b64 s[44:45], s[0:1]
	s_cbranch_execz .LBB0_1764
	s_waitcnt lgkmcnt(0)
	v_max_f32_e32 v5, v5, v5
	v_max_f32_e32 v4, v4, v4
	v_add_f32_e32 v11, v2, v3
	v_lshlrev_b64 v[2:3], 7, v[212:213]
	v_max_f32_e32 v10, v4, v5
	v_lshl_add_u64 v[4:5], s[26:27], 0, v[2:3]
	s_lshl_b64 s[86:87], s[42:43], 2
	v_lshl_add_u64 v[2:3], s[28:29], 0, v[2:3]
	v_lshl_add_u64 v[4:5], v[4:5], 0, s[86:87]
	s_lshl_b32 s12, s65, 2
	v_lshl_add_u64 v[2:3], v[2:3], 0, s[86:87]
	v_lshl_add_u64 v[4:5], v[4:5], 0, s[12:13]
	v_lshl_add_u64 v[2:3], v[2:3], 0, s[12:13]
	global_store_dword v[4:5], v11, off
	global_store_dword v[2:3], v10, off
.LBB0_1764:
	s_or_b64 exec, exec, s[44:45]
	v_add_u32_e32 v176, 0x80, v210
	v_ashrrev_i32_e32 v177, 31, v176
	s_waitcnt lgkmcnt(1)
	v_lshlrev_b64 v[2:3], 13, v[176:177]
	v_lshl_add_u64 v[2:3], s[16:17], 0, v[2:3]
	v_lshl_add_u64 v[178:179], v[90:91], 2, v[2:3]
	global_load_dwordx4 v[14:17], v[178:179], off offset:16 nt
	global_load_dwordx4 v[18:21], v[178:179], off nt
	s_waitcnt lgkmcnt(0)
	global_load_dwordx4 v[2:5], v[178:179], off offset:528 nt
	global_load_dwordx4 v[10:13], v[178:179], off offset:512 nt
	v_lshl_add_u64 v[22:23], v[192:193], 2, s[18:19]
	global_load_dword v22, v[22:23], off
	v_lshlrev_b64 v[24:25], 12, v[192:193]
	v_lshl_add_u64 v[24:25], s[22:23], 0, v[24:25]
	v_lshl_add_u64 v[180:181], v[90:91], 1, v[24:25]
	s_waitcnt vmcnt(0)
	v_pk_mul_f32 v[26:27], v[22:23], v[162:163] op_sel_hi:[0,1]
	v_pk_mul_f32 v[24:25], v[22:23], v[160:161] op_sel_hi:[0,1]
	v_pk_mul_f32 v[30:31], v[22:23], v[166:167] op_sel_hi:[0,1]
	v_pk_mul_f32 v[28:29], v[22:23], v[164:165] op_sel_hi:[0,1]
	v_pk_mul_f32 v[160:161], v[22:23], v[172:173] op_sel_hi:[0,1]
	v_pk_mul_f32 v[32:33], v[22:23], v[168:169] op_sel_hi:[0,1]
	v_pk_mul_f32 v[162:163], v[22:23], v[174:175] op_sel_hi:[0,1]
	v_pk_mul_f32 v[164:165], v[22:23], v[170:171] op_sel_hi:[0,1]
	v_pk_fma_f32 v[24:25], v[86:87], v[24:25], v[44:45]
	v_pk_fma_f32 v[22:23], v[88:89], v[26:27], v[42:43]
	v_pk_fma_f32 v[28:29], v[92:93], v[28:29], v[40:41]
	v_pk_fma_f32 v[26:27], v[94:95], v[30:31], v[38:39]
	v_pk_fma_f32 v[32:33], v[104:105], v[32:33], v[36:37]
	v_pk_fma_f32 v[30:31], v[106:107], v[160:161], v[34:35]
	v_pk_fma_f32 v[8:9], v[110:111], v[164:165], v[8:9]
	v_pk_fma_f32 v[6:7], v[108:109], v[162:163], v[6:7]
	global_store_dwordx4 v[194:195], v[22:25], off nt
	global_store_dwordx4 v[194:195], v[26:29], off offset:16 nt
	v_mul_f32_e32 v164, v23, v23
	v_mul_f32_e32 v165, v25, v25
	v_mul_f32_e32 v166, v27, v27
	v_mul_f32_e32 v167, v29, v29
	v_pk_mul_f32 v[34:35], v[78:79], v[24:25]
	v_pk_mul_f32 v[38:39], v[82:83], v[28:29]
	v_pk_mul_f32 v[40:41], v[84:85], v[26:27]
	v_mul_f32_e32 v27, v31, v31
	v_mul_f32_e32 v29, v33, v33
	v_pk_mul_f32 v[36:37], v[80:81], v[22:23]
	v_mul_f32_e32 v168, v7, v7
	v_mul_f32_e32 v169, v9, v9
	v_fmac_f32_e32 v164, v22, v22
	v_fmac_f32_e32 v165, v24, v24
	v_fmac_f32_e32 v167, v28, v28
	v_cvt_pk_bf16_f32 v22, v36, v37
	v_cvt_pk_bf16_f32 v23, v34, v35
	v_fmac_f32_e32 v27, v30, v30
	v_fmac_f32_e32 v29, v32, v32
	v_lshlrev_b32_e32 v28, 16, v22
	v_and_b32_e32 v34, 0xffff0000, v22
	v_pk_mul_f32 v[160:161], v[100:101], v[8:9]
	v_pk_mul_f32 v[162:163], v[102:103], v[6:7]
	v_fmac_f32_e32 v166, v26, v26
	v_cvt_pk_bf16_f32 v24, v40, v41
	v_cvt_pk_bf16_f32 v25, v38, v39
	v_fmac_f32_e32 v168, v6, v6
	v_fmac_f32_e32 v169, v8, v8
	v_add_f32_e32 v26, v164, v165
	global_store_dwordx4 v[180:181], v[22:25], off sc1
	v_lshlrev_b32_e32 v35, 16, v23
	v_and_b32_e32 v36, 0xffff0000, v23
	global_store_dwordx4 v[194:195], v[30:33], off offset:512 nt
	global_store_dwordx4 v[194:195], v[6:9], off offset:528 nt
	v_lshlrev_b32_e32 v37, 16, v24
	v_and_b32_e32 v38, 0xffff0000, v24
	v_add_f32_e32 v6, v27, v29
	v_max3_f32 v8, |v28|, 0, |v34|
	v_add_f32_e32 v7, v166, v26
	v_add_f32_e32 v6, v168, v6
	v_max3_f32 v8, v8, |v35|, |v36|
	v_lshlrev_b32_e32 v39, 16, v25
	v_and_b32_e32 v40, 0xffff0000, v25
	v_add_f32_e32 v7, v167, v7
	v_add_f32_e32 v6, v169, v6
	v_max3_f32 v8, v8, |v37|, |v38|
	v_pk_mul_f32 v[44:45], v[98:99], v[30:31]
	v_add_f32_e32 v6, v7, v6
	v_cvt_pk_bf16_f32 v22, v44, v45
	v_max3_f32 v7, v8, |v39|, |v40|
	v_lshlrev_b32_e32 v9, 16, v22
	v_and_b32_e32 v26, 0xffff0000, v22
	v_pk_mul_f32 v[42:43], v[96:97], v[32:33]
	v_max3_f32 v7, v7, |v9|, |v26|
	v_cvt_pk_bf16_f32 v23, v42, v43
	v_cvt_pk_bf16_f32 v24, v162, v163
	v_cvt_pk_bf16_f32 v25, v160, v161
	ds_bpermute_b32 v8, v233, v6
	v_lshlrev_b32_e32 v27, 16, v23
	v_and_b32_e32 v28, 0xffff0000, v23
	v_lshlrev_b32_e32 v29, 16, v24
	v_and_b32_e32 v30, 0xffff0000, v24
	v_max3_f32 v7, v7, |v27|, |v28|
	v_lshlrev_b32_e32 v31, 16, v25
	v_and_b32_e32 v32, 0xffff0000, v25
	v_max3_f32 v7, v7, |v29|, |v30|
	v_max3_f32 v9, v7, |v31|, |v32|
	ds_bpermute_b32 v26, v233, v9
	s_waitcnt lgkmcnt(1)
	v_add_f32_e32 v6, v6, v8
	ds_bpermute_b32 v7, v216, v6
	global_store_dwordx4 v[180:181], v[22:25], off offset:256 sc1
	s_waitcnt lgkmcnt(1)
	v_max_f32_e32 v8, v26, v26
	v_max_f32_e32 v8, v9, v8
	ds_bpermute_b32 v9, v216, v8
	s_and_saveexec_b64 s[44:45], s[0:1]
	s_cbranch_execz .LBB0_1766
	s_waitcnt lgkmcnt(0)
	v_max_f32_e32 v9, v9, v9
	v_max_f32_e32 v8, v8, v8
	v_add_f32_e32 v23, v6, v7
	v_lshlrev_b64 v[6:7], 7, v[192:193]
	v_max_f32_e32 v22, v8, v9
	v_lshl_add_u64 v[8:9], s[26:27], 0, v[6:7]
	s_lshl_b64 s[86:87], s[42:43], 2
	v_lshl_add_u64 v[6:7], s[28:29], 0, v[6:7]
	v_lshl_add_u64 v[8:9], v[8:9], 0, s[86:87]
	s_lshl_b32 s12, s65, 2
	v_lshl_add_u64 v[6:7], v[6:7], 0, s[86:87]
	v_lshl_add_u64 v[8:9], v[8:9], 0, s[12:13]
	v_lshl_add_u64 v[6:7], v[6:7], 0, s[12:13]
	global_store_dword v[8:9], v23, off
	global_store_dword v[6:7], v22, off
.LBB0_1766:
	s_or_b64 exec, exec, s[44:45]
	v_or_b32_e32 v36, 16, v176
	v_ashrrev_i32_e32 v37, 31, v36
	s_waitcnt lgkmcnt(1)
	v_lshlrev_b64 v[6:7], 13, v[36:37]
	v_lshl_add_u64 v[6:7], s[16:17], 0, v[6:7]
	v_lshl_add_u64 v[40:41], v[90:91], 2, v[6:7]
	global_load_dwordx4 v[26:29], v[40:41], off offset:16 nt
	global_load_dwordx4 v[30:33], v[40:41], off nt
	s_waitcnt lgkmcnt(0)
	global_load_dwordx4 v[6:9], v[40:41], off offset:528 nt
	global_load_dwordx4 v[22:25], v[40:41], off offset:512 nt
	global_load_dword v34, v[196:197], off offset:512
	v_lshlrev_b64 v[38:39], 12, v[176:177]
	v_lshl_add_u64 v[38:39], s[22:23], 0, v[38:39]
	v_lshl_add_u64 v[38:39], v[90:91], 1, v[38:39]
	s_waitcnt vmcnt(0)
	v_pk_mul_f32 v[44:45], v[34:35], v[128:129] op_sel_hi:[0,1]
	v_pk_mul_f32 v[128:129], v[34:35], v[150:151] op_sel_hi:[0,1]
	v_pk_mul_f32 v[42:43], v[34:35], v[146:147] op_sel_hi:[0,1]
	v_pk_mul_f32 v[146:147], v[34:35], v[148:149] op_sel_hi:[0,1]
	v_pk_mul_f32 v[148:149], v[34:35], v[156:157] op_sel_hi:[0,1]
	v_pk_mul_f32 v[150:151], v[34:35], v[152:153] op_sel_hi:[0,1]
	v_pk_fma_f32 v[14:15], v[94:95], v[128:129], v[14:15]
	v_pk_mul_f32 v[152:153], v[34:35], v[158:159] op_sel_hi:[0,1]
	v_pk_mul_f32 v[34:35], v[34:35], v[154:155] op_sel_hi:[0,1]
	v_pk_fma_f32 v[20:21], v[86:87], v[44:45], v[20:21]
	v_pk_fma_f32 v[18:19], v[88:89], v[42:43], v[18:19]
	v_pk_fma_f32 v[16:17], v[92:93], v[146:147], v[16:17]
	v_pk_fma_f32 v[12:13], v[104:105], v[150:151], v[12:13]
	v_pk_fma_f32 v[10:11], v[106:107], v[148:149], v[10:11]
	v_mul_f32_e32 v156, v15, v15
	v_pk_fma_f32 v[4:5], v[110:111], v[34:35], v[4:5]
	v_pk_fma_f32 v[2:3], v[108:109], v[152:153], v[2:3]
	global_store_dwordx4 v[178:179], v[18:21], off nt
	global_store_dwordx4 v[178:179], v[14:17], off offset:16 nt
	v_mul_f32_e32 v154, v19, v19
	v_mul_f32_e32 v155, v21, v21
	v_mul_f32_e32 v157, v17, v17
	v_pk_mul_f32 v[34:35], v[78:79], v[20:21]
	v_pk_mul_f32 v[42:43], v[80:81], v[18:19]
	v_pk_mul_f32 v[128:129], v[84:85], v[14:15]
	v_mul_f32_e32 v19, v11, v11
	v_mul_f32_e32 v21, v13, v13
	v_fmac_f32_e32 v156, v14, v14
	v_cvt_pk_bf16_f32 v14, v42, v43
	v_pk_mul_f32 v[44:45], v[82:83], v[16:17]
	v_mul_f32_e32 v158, v3, v3
	v_mul_f32_e32 v159, v5, v5
	v_fmac_f32_e32 v154, v18, v18
	v_fmac_f32_e32 v155, v20, v20
	v_fmac_f32_e32 v157, v16, v16
	v_cvt_pk_bf16_f32 v15, v34, v35
	v_cvt_pk_bf16_f32 v16, v128, v129
	v_cvt_pk_bf16_f32 v17, v44, v45
	v_fmac_f32_e32 v19, v10, v10
	v_fmac_f32_e32 v21, v12, v12
	global_store_dwordx4 v[38:39], v[14:17], off sc1
	v_lshlrev_b32_e32 v20, 16, v14
	v_pk_mul_f32 v[150:151], v[100:101], v[4:5]
	v_and_b32_e32 v14, 0xffff0000, v14
	v_pk_mul_f32 v[152:153], v[102:103], v[2:3]
	v_fmac_f32_e32 v158, v2, v2
	v_fmac_f32_e32 v159, v4, v4
	v_add_f32_e32 v18, v154, v155
	v_lshlrev_b32_e32 v34, 16, v15
	v_and_b32_e32 v15, 0xffff0000, v15
	global_store_dwordx4 v[178:179], v[10:13], off offset:512 nt
	global_store_dwordx4 v[178:179], v[2:5], off offset:528 nt
	v_lshlrev_b32_e32 v35, 16, v16
	v_and_b32_e32 v16, 0xffff0000, v16
	v_add_f32_e32 v2, v19, v21
	v_max3_f32 v4, |v20|, 0, |v14|
	v_add_f32_e32 v3, v156, v18
	v_add_f32_e32 v2, v158, v2
	v_max3_f32 v4, v4, |v34|, |v15|
	v_lshlrev_b32_e32 v42, 16, v17
	v_and_b32_e32 v17, 0xffff0000, v17
	v_add_f32_e32 v3, v157, v3
	v_add_f32_e32 v2, v159, v2
	v_max3_f32 v4, v4, |v35|, |v16|
	v_pk_mul_f32 v[148:149], v[98:99], v[10:11]
	v_add_f32_e32 v2, v3, v2
	v_cvt_pk_bf16_f32 v10, v148, v149
	v_max3_f32 v3, v4, |v42|, |v17|
	v_lshlrev_b32_e32 v5, 16, v10
	v_and_b32_e32 v14, 0xffff0000, v10
	v_pk_mul_f32 v[146:147], v[96:97], v[12:13]
	v_max3_f32 v3, v3, |v5|, |v14|
	v_cvt_pk_bf16_f32 v11, v146, v147
	v_cvt_pk_bf16_f32 v12, v152, v153
	v_cvt_pk_bf16_f32 v13, v150, v151
	ds_bpermute_b32 v4, v233, v2
	v_lshlrev_b32_e32 v18, 16, v11
	v_and_b32_e32 v19, 0xffff0000, v11
	v_lshlrev_b32_e32 v20, 16, v12
	v_and_b32_e32 v21, 0xffff0000, v12
	v_max3_f32 v3, v3, |v18|, |v19|
	v_lshlrev_b32_e32 v43, 16, v13
	v_and_b32_e32 v44, 0xffff0000, v13
	v_max3_f32 v3, v3, |v20|, |v21|
	v_max3_f32 v5, v3, |v43|, |v44|
	ds_bpermute_b32 v14, v233, v5
	s_waitcnt lgkmcnt(1)
	v_add_f32_e32 v2, v2, v4
	ds_bpermute_b32 v3, v216, v2
	global_store_dwordx4 v[38:39], v[10:13], off offset:256 sc1
	s_waitcnt lgkmcnt(1)
	v_max_f32_e32 v4, v14, v14
	v_max_f32_e32 v4, v5, v4
	ds_bpermute_b32 v5, v216, v4
	s_and_saveexec_b64 s[44:45], s[0:1]
	s_cbranch_execz .LBB0_1768
	s_waitcnt lgkmcnt(0)
	v_max_f32_e32 v5, v5, v5
	v_max_f32_e32 v4, v4, v4
	v_add_f32_e32 v11, v2, v3
	v_lshlrev_b64 v[2:3], 7, v[176:177]
	v_max_f32_e32 v10, v4, v5
	v_lshl_add_u64 v[4:5], s[26:27], 0, v[2:3]
	s_lshl_b64 s[86:87], s[42:43], 2
	v_lshl_add_u64 v[2:3], s[28:29], 0, v[2:3]
	v_lshl_add_u64 v[4:5], v[4:5], 0, s[86:87]
	s_lshl_b32 s12, s65, 2
	v_lshl_add_u64 v[2:3], v[2:3], 0, s[86:87]
	v_lshl_add_u64 v[4:5], v[4:5], 0, s[12:13]
	v_lshl_add_u64 v[2:3], v[2:3], 0, s[12:13]
	global_store_dword v[4:5], v11, off
	global_store_dword v[2:3], v10, off
.LBB0_1768:
	s_or_b64 exec, exec, s[44:45]
	v_or_b32_e32 v34, 32, v176
	v_ashrrev_i32_e32 v35, 31, v34
	s_waitcnt lgkmcnt(1)
	v_lshlrev_b64 v[2:3], 13, v[34:35]
	v_lshl_add_u64 v[2:3], s[16:17], 0, v[2:3]
	v_lshl_add_u64 v[38:39], v[90:91], 2, v[2:3]
	global_load_dwordx4 v[14:17], v[38:39], off offset:16 nt
	global_load_dwordx4 v[18:21], v[38:39], off nt
	s_waitcnt lgkmcnt(0)
	global_load_dwordx4 v[2:5], v[38:39], off offset:528 nt
	global_load_dwordx4 v[10:13], v[38:39], off offset:512 nt
	v_lshl_add_u64 v[42:43], v[36:37], 2, s[18:19]
	global_load_dword v42, v[42:43], off
	v_lshlrev_b64 v[44:45], 12, v[36:37]
	v_lshl_add_u64 v[44:45], s[22:23], 0, v[44:45]
	v_lshl_add_u64 v[44:45], v[90:91], 1, v[44:45]
	s_waitcnt vmcnt(0)
	v_pk_mul_f32 v[118:119], v[42:43], v[118:119] op_sel_hi:[0,1]
	v_pk_mul_f32 v[114:115], v[42:43], v[114:115] op_sel_hi:[0,1]
	v_pk_mul_f32 v[112:113], v[42:43], v[112:113] op_sel_hi:[0,1]
	v_pk_mul_f32 v[116:117], v[42:43], v[116:117] op_sel_hi:[0,1]
	v_pk_mul_f32 v[124:125], v[42:43], v[124:125] op_sel_hi:[0,1]
	v_pk_mul_f32 v[120:121], v[42:43], v[120:121] op_sel_hi:[0,1]
	v_pk_fma_f32 v[26:27], v[94:95], v[118:119], v[26:27]
	v_pk_mul_f32 v[126:127], v[42:43], v[126:127] op_sel_hi:[0,1]
	v_pk_mul_f32 v[42:43], v[42:43], v[122:123] op_sel_hi:[0,1]
	v_pk_fma_f32 v[32:33], v[86:87], v[112:113], v[32:33]
	v_pk_fma_f32 v[30:31], v[88:89], v[114:115], v[30:31]
	v_pk_fma_f32 v[28:29], v[92:93], v[116:117], v[28:29]
	v_pk_fma_f32 v[24:25], v[104:105], v[120:121], v[24:25]
	v_pk_fma_f32 v[22:23], v[106:107], v[124:125], v[22:23]
	v_mul_f32_e32 v128, v27, v27
	v_pk_fma_f32 v[8:9], v[110:111], v[42:43], v[8:9]
	v_pk_fma_f32 v[6:7], v[108:109], v[126:127], v[6:7]
	global_store_dwordx4 v[40:41], v[30:33], off nt
	global_store_dwordx4 v[40:41], v[26:29], off offset:16 nt
	v_mul_f32_e32 v126, v31, v31
	v_mul_f32_e32 v127, v33, v33
	v_mul_f32_e32 v129, v29, v29
	v_pk_mul_f32 v[42:43], v[78:79], v[32:33]
	v_pk_mul_f32 v[112:113], v[80:81], v[30:31]
	v_pk_mul_f32 v[116:117], v[84:85], v[26:27]
	v_mul_f32_e32 v31, v23, v23
	v_mul_f32_e32 v33, v25, v25
	v_fmac_f32_e32 v128, v26, v26
	v_cvt_pk_bf16_f32 v26, v112, v113
	v_pk_mul_f32 v[114:115], v[82:83], v[28:29]
	v_mul_f32_e32 v146, v7, v7
	v_mul_f32_e32 v147, v9, v9
	v_fmac_f32_e32 v126, v30, v30
	v_fmac_f32_e32 v127, v32, v32
	v_fmac_f32_e32 v129, v28, v28
	v_cvt_pk_bf16_f32 v27, v42, v43
	v_cvt_pk_bf16_f32 v28, v116, v117
	v_cvt_pk_bf16_f32 v29, v114, v115
	v_fmac_f32_e32 v31, v22, v22
	v_fmac_f32_e32 v33, v24, v24
	global_store_dwordx4 v[44:45], v[26:29], off sc1
	v_lshlrev_b32_e32 v32, 16, v26
	v_pk_mul_f32 v[122:123], v[100:101], v[8:9]
	v_and_b32_e32 v26, 0xffff0000, v26
	v_pk_mul_f32 v[124:125], v[102:103], v[6:7]
	v_fmac_f32_e32 v146, v6, v6
	v_fmac_f32_e32 v147, v8, v8
	v_add_f32_e32 v30, v126, v127
	v_lshlrev_b32_e32 v42, 16, v27
	v_and_b32_e32 v27, 0xffff0000, v27
	global_store_dwordx4 v[40:41], v[22:25], off offset:512 nt
	global_store_dwordx4 v[40:41], v[6:9], off offset:528 nt
	v_lshlrev_b32_e32 v43, 16, v28
	v_and_b32_e32 v28, 0xffff0000, v28
	v_add_f32_e32 v6, v31, v33
	v_max3_f32 v8, |v32|, 0, |v26|
	v_add_f32_e32 v7, v128, v30
	v_add_f32_e32 v6, v146, v6
	v_max3_f32 v8, v8, |v42|, |v27|
	v_lshlrev_b32_e32 v112, 16, v29
	v_and_b32_e32 v29, 0xffff0000, v29
	v_add_f32_e32 v7, v129, v7
	v_add_f32_e32 v6, v147, v6
	v_max3_f32 v8, v8, |v43|, |v28|
	v_pk_mul_f32 v[120:121], v[98:99], v[22:23]
	v_add_f32_e32 v6, v7, v6
	v_cvt_pk_bf16_f32 v22, v120, v121
	v_max3_f32 v7, v8, |v112|, |v29|
	v_lshlrev_b32_e32 v9, 16, v22
	v_and_b32_e32 v26, 0xffff0000, v22
	v_pk_mul_f32 v[118:119], v[96:97], v[24:25]
	v_max3_f32 v7, v7, |v9|, |v26|
	v_cvt_pk_bf16_f32 v23, v118, v119
	v_cvt_pk_bf16_f32 v24, v124, v125
	v_cvt_pk_bf16_f32 v25, v122, v123
	ds_bpermute_b32 v8, v233, v6
	v_lshlrev_b32_e32 v30, 16, v23
	v_and_b32_e32 v31, 0xffff0000, v23
	v_lshlrev_b32_e32 v32, 16, v24
	v_and_b32_e32 v33, 0xffff0000, v24
	v_max3_f32 v7, v7, |v30|, |v31|
	v_lshlrev_b32_e32 v40, 16, v25
	v_and_b32_e32 v41, 0xffff0000, v25
	v_max3_f32 v7, v7, |v32|, |v33|
	v_max3_f32 v9, v7, |v40|, |v41|
	ds_bpermute_b32 v26, v233, v9
	s_waitcnt lgkmcnt(1)
	v_add_f32_e32 v6, v6, v8
	ds_bpermute_b32 v7, v216, v6
	global_store_dwordx4 v[44:45], v[22:25], off offset:256 sc1
	s_waitcnt lgkmcnt(1)
	v_max_f32_e32 v8, v26, v26
	v_max_f32_e32 v8, v9, v8
	ds_bpermute_b32 v9, v216, v8
	s_and_saveexec_b64 s[44:45], s[0:1]
	s_cbranch_execz .LBB0_1770
	s_waitcnt lgkmcnt(0)
	v_max_f32_e32 v9, v9, v9
	v_max_f32_e32 v8, v8, v8
	v_add_f32_e32 v23, v6, v7
	v_lshlrev_b64 v[6:7], 7, v[36:37]
	v_max_f32_e32 v22, v8, v9
	v_lshl_add_u64 v[8:9], s[26:27], 0, v[6:7]
	s_lshl_b64 s[86:87], s[42:43], 2
	v_lshl_add_u64 v[6:7], s[28:29], 0, v[6:7]
	v_lshl_add_u64 v[8:9], v[8:9], 0, s[86:87]
	s_lshl_b32 s12, s65, 2
	v_lshl_add_u64 v[6:7], v[6:7], 0, s[86:87]
	v_lshl_add_u64 v[8:9], v[8:9], 0, s[12:13]
	v_lshl_add_u64 v[6:7], v[6:7], 0, s[12:13]
	global_store_dword v[8:9], v23, off
	global_store_dword v[6:7], v22, off
.LBB0_1770:
	s_or_b64 exec, exec, s[44:45]
	v_or_b32_e32 v36, 48, v176
	v_ashrrev_i32_e32 v37, 31, v36
	s_waitcnt lgkmcnt(1)
	v_lshlrev_b64 v[6:7], 13, v[36:37]
	v_lshl_add_u64 v[6:7], s[16:17], 0, v[6:7]
	v_lshl_add_u64 v[40:41], v[90:91], 2, v[6:7]
	global_load_dwordx4 v[26:29], v[40:41], off offset:16 nt
	global_load_dwordx4 v[30:33], v[40:41], off nt
	s_waitcnt lgkmcnt(0)
	global_load_dwordx4 v[6:9], v[40:41], off offset:528 nt
	global_load_dwordx4 v[22:25], v[40:41], off offset:512 nt
	v_lshl_add_u64 v[42:43], v[34:35], 2, s[18:19]
	global_load_dword v42, v[42:43], off
	v_lshlrev_b64 v[44:45], 12, v[34:35]
	v_lshl_add_u64 v[44:45], s[22:23], 0, v[44:45]
	v_lshl_add_u64 v[44:45], v[90:91], 1, v[44:45]
	s_waitcnt vmcnt(0)
	v_pk_mul_f32 v[68:69], v[42:43], v[68:69] op_sel_hi:[0,1]
	v_pk_mul_f32 v[64:65], v[42:43], v[64:65] op_sel_hi:[0,1]
	v_pk_mul_f32 v[62:63], v[42:43], v[62:63] op_sel_hi:[0,1]
	v_pk_mul_f32 v[66:67], v[42:43], v[66:67] op_sel_hi:[0,1]
	v_pk_mul_f32 v[74:75], v[42:43], v[74:75] op_sel_hi:[0,1]
	v_pk_mul_f32 v[70:71], v[42:43], v[70:71] op_sel_hi:[0,1]
	v_pk_fma_f32 v[14:15], v[94:95], v[68:69], v[14:15]
	v_pk_mul_f32 v[76:77], v[42:43], v[76:77] op_sel_hi:[0,1]
	v_pk_mul_f32 v[42:43], v[42:43], v[72:73] op_sel_hi:[0,1]
	v_pk_fma_f32 v[20:21], v[86:87], v[62:63], v[20:21]
	v_pk_fma_f32 v[18:19], v[88:89], v[64:65], v[18:19]
	v_pk_fma_f32 v[16:17], v[92:93], v[66:67], v[16:17]
	v_pk_fma_f32 v[12:13], v[104:105], v[70:71], v[12:13]
	v_pk_fma_f32 v[10:11], v[106:107], v[74:75], v[10:11]
	v_mul_f32_e32 v112, v15, v15
	v_pk_fma_f32 v[4:5], v[110:111], v[42:43], v[4:5]
	v_pk_fma_f32 v[2:3], v[108:109], v[76:77], v[2:3]
	global_store_dwordx4 v[38:39], v[18:21], off nt
	global_store_dwordx4 v[38:39], v[14:17], off offset:16 nt
	v_mul_f32_e32 v76, v19, v19
	v_mul_f32_e32 v77, v21, v21
	v_mul_f32_e32 v113, v17, v17
	v_pk_mul_f32 v[42:43], v[78:79], v[20:21]
	v_pk_mul_f32 v[62:63], v[80:81], v[18:19]
	v_pk_mul_f32 v[66:67], v[84:85], v[14:15]
	v_mul_f32_e32 v19, v11, v11
	v_mul_f32_e32 v21, v13, v13
	v_fmac_f32_e32 v112, v14, v14
	v_cvt_pk_bf16_f32 v14, v62, v63
	v_pk_mul_f32 v[64:65], v[82:83], v[16:17]
	v_mul_f32_e32 v114, v3, v3
	v_mul_f32_e32 v115, v5, v5
	v_fmac_f32_e32 v76, v18, v18
	v_fmac_f32_e32 v77, v20, v20
	v_fmac_f32_e32 v113, v16, v16
	v_cvt_pk_bf16_f32 v15, v42, v43
	v_cvt_pk_bf16_f32 v16, v66, v67
	v_cvt_pk_bf16_f32 v17, v64, v65
	v_fmac_f32_e32 v19, v10, v10
	v_fmac_f32_e32 v21, v12, v12
	global_store_dwordx4 v[44:45], v[14:17], off sc1
	v_lshlrev_b32_e32 v20, 16, v14
	v_pk_mul_f32 v[72:73], v[100:101], v[4:5]
	v_and_b32_e32 v14, 0xffff0000, v14
	v_pk_mul_f32 v[74:75], v[102:103], v[2:3]
	v_fmac_f32_e32 v114, v2, v2
	v_fmac_f32_e32 v115, v4, v4
	v_add_f32_e32 v18, v76, v77
	v_lshlrev_b32_e32 v42, 16, v15
	v_and_b32_e32 v15, 0xffff0000, v15
	global_store_dwordx4 v[38:39], v[10:13], off offset:512 nt
	global_store_dwordx4 v[38:39], v[2:5], off offset:528 nt
	v_lshlrev_b32_e32 v43, 16, v16
	v_and_b32_e32 v16, 0xffff0000, v16
	v_add_f32_e32 v2, v19, v21
	v_max3_f32 v4, |v20|, 0, |v14|
	v_add_f32_e32 v3, v112, v18
	v_add_f32_e32 v2, v114, v2
	v_max3_f32 v4, v4, |v42|, |v15|
	v_lshlrev_b32_e32 v62, 16, v17
	v_and_b32_e32 v17, 0xffff0000, v17
	v_add_f32_e32 v3, v113, v3
	v_add_f32_e32 v2, v115, v2
	v_max3_f32 v4, v4, |v43|, |v16|
	v_pk_mul_f32 v[70:71], v[98:99], v[10:11]
	v_add_f32_e32 v2, v3, v2
	v_cvt_pk_bf16_f32 v10, v70, v71
	v_max3_f32 v3, v4, |v62|, |v17|
	v_lshlrev_b32_e32 v5, 16, v10
	v_and_b32_e32 v14, 0xffff0000, v10
	v_pk_mul_f32 v[68:69], v[96:97], v[12:13]
	v_max3_f32 v3, v3, |v5|, |v14|
	v_cvt_pk_bf16_f32 v11, v68, v69
	v_cvt_pk_bf16_f32 v12, v74, v75
	v_cvt_pk_bf16_f32 v13, v72, v73
	ds_bpermute_b32 v4, v233, v2
	v_lshlrev_b32_e32 v18, 16, v11
	v_and_b32_e32 v19, 0xffff0000, v11
	v_lshlrev_b32_e32 v20, 16, v12
	v_and_b32_e32 v21, 0xffff0000, v12
	v_max3_f32 v3, v3, |v18|, |v19|
	v_lshlrev_b32_e32 v38, 16, v13
	v_and_b32_e32 v39, 0xffff0000, v13
	v_max3_f32 v3, v3, |v20|, |v21|
	v_max3_f32 v5, v3, |v38|, |v39|
	ds_bpermute_b32 v14, v233, v5
	s_waitcnt lgkmcnt(1)
	v_add_f32_e32 v2, v2, v4
	ds_bpermute_b32 v3, v216, v2
	global_store_dwordx4 v[44:45], v[10:13], off offset:256 sc1
	s_waitcnt lgkmcnt(1)
	v_max_f32_e32 v4, v14, v14
	v_max_f32_e32 v4, v5, v4
	ds_bpermute_b32 v5, v216, v4
	s_and_saveexec_b64 s[44:45], s[0:1]
	s_cbranch_execz .LBB0_1772
	s_waitcnt lgkmcnt(0)
	v_max_f32_e32 v5, v5, v5
	v_max_f32_e32 v4, v4, v4
	v_add_f32_e32 v11, v2, v3
	v_lshlrev_b64 v[2:3], 7, v[34:35]
	v_max_f32_e32 v10, v4, v5
	v_lshl_add_u64 v[4:5], s[26:27], 0, v[2:3]
	s_lshl_b64 s[86:87], s[42:43], 2
	v_lshl_add_u64 v[2:3], s[28:29], 0, v[2:3]
	v_lshl_add_u64 v[4:5], v[4:5], 0, s[86:87]
	s_lshl_b32 s12, s65, 2
	v_lshl_add_u64 v[2:3], v[2:3], 0, s[86:87]
	v_lshl_add_u64 v[4:5], v[4:5], 0, s[12:13]
	v_lshl_add_u64 v[2:3], v[2:3], 0, s[12:13]
	global_store_dword v[4:5], v11, off
	global_store_dword v[2:3], v10, off
.LBB0_1772:
	s_or_b64 exec, exec, s[44:45]
	s_waitcnt lgkmcnt(1)
	v_lshl_add_u64 v[2:3], v[36:37], 2, s[18:19]
	global_load_dword v2, v[2:3], off
	s_waitcnt lgkmcnt(0)
	v_lshlrev_b64 v[4:5], 12, v[36:37]
	v_lshl_add_u64 v[4:5], s[22:23], 0, v[4:5]
	v_lshl_add_u64 v[18:19], v[90:91], 1, v[4:5]
	s_waitcnt vmcnt(0)
	v_pk_mul_f32 v[10:11], v[2:3], v[48:49] op_sel_hi:[0,1]
	v_pk_mul_f32 v[4:5], v[2:3], v[46:47] op_sel_hi:[0,1]
	v_pk_mul_f32 v[14:15], v[2:3], v[52:53] op_sel_hi:[0,1]
	v_pk_mul_f32 v[12:13], v[2:3], v[50:51] op_sel_hi:[0,1]
	v_pk_mul_f32 v[20:21], v[2:3], v[58:59] op_sel_hi:[0,1]
	v_pk_mul_f32 v[16:17], v[2:3], v[54:55] op_sel_hi:[0,1]
	v_pk_mul_f32 v[34:35], v[2:3], v[60:61] op_sel_hi:[0,1]
	v_pk_mul_f32 v[38:39], v[2:3], v[56:57] op_sel_hi:[0,1]
	v_pk_fma_f32 v[2:3], v[88:89], v[10:11], v[30:31]
	v_pk_fma_f32 v[4:5], v[86:87], v[4:5], v[32:33]
	v_pk_fma_f32 v[12:13], v[92:93], v[12:13], v[28:29]
	v_pk_fma_f32 v[8:9], v[110:111], v[38:39], v[8:9]
	v_mul_f32_e32 v38, v3, v3
	v_pk_fma_f32 v[10:11], v[94:95], v[14:15], v[26:27]
	v_pk_fma_f32 v[14:15], v[106:107], v[20:21], v[22:23]
	global_store_dwordx4 v[40:41], v[2:5], off nt
	global_store_dwordx4 v[40:41], v[10:13], off offset:16 nt
	v_mul_f32_e32 v39, v5, v5
	v_mul_f32_e32 v43, v13, v13
	v_pk_mul_f32 v[22:23], v[80:81], v[2:3]
	v_fmac_f32_e32 v38, v2, v2
	v_cvt_pk_bf16_f32 v2, v22, v23
	v_pk_fma_f32 v[16:17], v[104:105], v[16:17], v[24:25]
	v_pk_mul_f32 v[20:21], v[78:79], v[4:5]
	v_pk_mul_f32 v[24:25], v[82:83], v[12:13]
	v_pk_mul_f32 v[26:27], v[84:85], v[10:11]
	v_fmac_f32_e32 v39, v4, v4
	v_fmac_f32_e32 v43, v12, v12
	v_cvt_pk_bf16_f32 v3, v20, v21
	v_cvt_pk_bf16_f32 v4, v26, v27
	v_cvt_pk_bf16_f32 v5, v24, v25
	global_store_dwordx4 v[18:19], v[2:5], off sc1
	v_lshlrev_b32_e32 v12, 16, v2
	v_lshlrev_b32_e32 v20, 16, v3
	v_and_b32_e32 v2, 0xffff0000, v2
	v_and_b32_e32 v3, 0xffff0000, v3
	v_max3_f32 v2, |v12|, 0, |v2|
	v_pk_fma_f32 v[6:7], v[108:109], v[34:35], v[6:7]
	v_mul_f32_e32 v42, v11, v11
	v_mul_f32_e32 v11, v15, v15
	v_mul_f32_e32 v13, v17, v17
	v_lshlrev_b32_e32 v21, 16, v4
	v_and_b32_e32 v4, 0xffff0000, v4
	v_max3_f32 v2, v2, |v20|, |v3|
	v_mul_f32_e32 v44, v7, v7
	v_fmac_f32_e32 v11, v14, v14
	v_fmac_f32_e32 v13, v16, v16
	v_lshlrev_b32_e32 v22, 16, v5
	v_and_b32_e32 v5, 0xffff0000, v5
	v_max3_f32 v2, v2, |v21|, |v4|
	v_pk_mul_f32 v[30:31], v[98:99], v[14:15]
	v_pk_mul_f32 v[34:35], v[102:103], v[6:7]
	v_fmac_f32_e32 v44, v6, v6
	global_store_dwordx4 v[40:41], v[14:17], off offset:512 nt
	global_store_dwordx4 v[40:41], v[6:9], off offset:528 nt
	v_add_f32_e32 v11, v11, v13
	v_max3_f32 v2, v2, |v22|, |v5|
	v_cvt_pk_bf16_f32 v6, v30, v31
	v_mul_f32_e32 v45, v9, v9
	v_lshlrev_b32_e32 v12, 16, v6
	v_and_b32_e32 v13, 0xffff0000, v6
	v_pk_mul_f32 v[28:29], v[96:97], v[16:17]
	v_fmac_f32_e32 v42, v10, v10
	v_add_f32_e32 v10, v38, v39
	v_cvt_pk_bf16_f32 v7, v28, v29
	v_max3_f32 v2, v2, |v12|, |v13|
	v_lshlrev_b32_e32 v14, 16, v7
	v_and_b32_e32 v15, 0xffff0000, v7
	v_pk_mul_f32 v[32:33], v[100:101], v[8:9]
	v_fmac_f32_e32 v45, v8, v8
	v_cvt_pk_bf16_f32 v8, v34, v35
	v_add_f32_e32 v10, v42, v10
	v_add_f32_e32 v11, v44, v11
	v_lshlrev_b32_e32 v16, 16, v8
	v_and_b32_e32 v17, 0xffff0000, v8
	v_max3_f32 v2, v2, |v14|, |v15|
	v_cvt_pk_bf16_f32 v9, v32, v33
	v_add_f32_e32 v10, v43, v10
	v_lshlrev_b32_e32 v23, 16, v9
	v_and_b32_e32 v24, 0xffff0000, v9
	v_add_f32_e32 v3, v45, v11
	v_max3_f32 v2, v2, |v16|, |v17|
	v_add_f32_e32 v3, v10, v3
	v_max3_f32 v5, v2, |v23|, |v24|
	ds_bpermute_b32 v4, v233, v3
	ds_bpermute_b32 v10, v233, v5
	global_store_dwordx4 v[18:19], v[6:9], off offset:256 sc1
	s_waitcnt lgkmcnt(1)
	v_add_f32_e32 v2, v3, v4
	s_waitcnt lgkmcnt(0)
	v_max_f32_e32 v4, v10, v10
	v_max_f32_e32 v4, v5, v4
	ds_bpermute_b32 v3, v216, v2
	ds_bpermute_b32 v5, v216, v4
	s_and_saveexec_b64 s[44:45], s[0:1]
	s_cbranch_execz .LBB0_1774
	s_waitcnt lgkmcnt(0)
	v_max_f32_e32 v5, v5, v5
	v_max_f32_e32 v4, v4, v4
	v_add_f32_e32 v7, v2, v3
	v_lshlrev_b64 v[2:3], 7, v[36:37]
	v_max_f32_e32 v6, v4, v5
	v_lshl_add_u64 v[4:5], s[26:27], 0, v[2:3]
	s_lshl_b64 s[42:43], s[42:43], 2
	v_lshl_add_u64 v[2:3], s[28:29], 0, v[2:3]
	v_lshl_add_u64 v[4:5], v[4:5], 0, s[42:43]
	s_lshl_b32 s12, s65, 2
	v_lshl_add_u64 v[2:3], v[2:3], 0, s[42:43]
	v_lshl_add_u64 v[4:5], v[4:5], 0, s[12:13]
	v_lshl_add_u64 v[2:3], v[2:3], 0, s[12:13]
	global_store_dword v[4:5], v7, off
	global_store_dword v[2:3], v6, off

.LBB0_1943:
	s_lshl_b32 s26, s30, 8
	s_add_i32 s28, s26, s58
	s_lshl_b32 s26, s31, 8
	s_or_b32 s29, s26, s59
	s_lshr_b32 s26, s30, 4
	s_add_i32 s26, s26, -1
	v_or_b32_e32 v2, s29, v186
	s_cmp_gt_i32 s30, 31
	s_cselect_b32 s26, s26, 0
	v_ashrrev_i32_e32 v3, 31, v2
	v_or_b32_e32 v168, s28, v187
	v_lshlrev_b64 v[10:11], 2, v[2:3]
	v_ashrrev_i32_e32 v169, 31, v168
	s_ashr_i32 s27, s26, 31
	v_lshl_add_u64 v[12:13], s[16:17], 0, v[10:11]
	v_lshl_add_u64 v[100:101], v[168:169], 2, s[14:15]
	s_lshl_b64 s[26:27], s[26:27], 15
	global_load_dwordx4 v[2:5], v[12:13], off offset:16
	global_load_dwordx4 v[6:9], v[12:13], off
	global_load_dword v190, v[100:101], off
	s_add_u32 s26, s51, s26
	global_load_dwordx4 v[14:17], v[12:13], off offset:528
	global_load_dwordx4 v[30:33], v[12:13], off offset:512
	s_addc_u32 s27, s54, s27
	v_lshl_add_u64 v[10:11], s[26:27], 0, v[10:11]
	global_load_dwordx4 v[26:29], v[10:11], off
	global_load_dwordx4 v[22:25], v[10:11], off offset:16
	global_load_dwordx4 v[18:21], v[10:11], off offset:512
	s_nop 0
	global_load_dwordx4 v[10:13], v[10:11], off offset:528
	s_ashr_i32 s28, s28, 8
	v_bitop3_b32 v90, s29, 56, v186 bitop3:0xc8
	s_ashr_i32 s26, s29, 6
	s_ashr_i32 s29, s28, 31
	s_ashr_i32 s27, s26, 31
	s_lshl_b64 s[34:35], s[28:29], 7
	s_add_u32 s28, s34, s26
	s_addc_u32 s29, s35, s27
	s_lshl_b64 s[28:29], s[28:29], 15
	s_add_u32 s30, s12, s28
	s_addc_u32 s31, s13, s29
	s_or_b32 s28, s26, 2
	s_ashr_i32 s29, s28, 31
	s_add_u32 s34, s34, s28
	v_lshlrev_b32_e32 v169, 7, v168
	s_addc_u32 s35, s35, s29
	v_and_b32_e32 v138, 0x6780, v169
	s_lshl_b64 s[34:35], s[34:35], 15
	v_mov_b32_e32 v91, v139
	v_lshlrev_b32_e32 v90, 1, v90
	v_lshl_add_u64 v[192:193], s[30:31], 0, v[138:139]
	s_add_u32 s34, s12, s34
	v_lshl_add_u64 v[192:193], v[192:193], 0, v[90:91]
	s_addc_u32 s35, s13, s35
	s_and_b64 vcc, exec, s[0:1]
	s_mov_b64 s[0:1], -1
	s_waitcnt vmcnt(0)
	v_pk_mul_f32 v[194:195], v[6:7], v[190:191] op_sel_hi:[1,0]
	v_pk_mul_f32 v[196:197], v[8:9], v[190:191] op_sel_hi:[1,0]
	v_pk_mul_f32 v[198:199], v[2:3], v[190:191] op_sel_hi:[1,0]
	v_pk_mul_f32 v[204:205], v[32:33], v[190:191] op_sel_hi:[1,0]
	v_pk_fma_f32 v[170:171], v[196:197], v[170:171], v[28:29]
	v_pk_fma_f32 v[172:173], v[194:195], v[172:173], v[26:27]
	v_pk_mul_f32 v[200:201], v[4:5], v[190:191] op_sel_hi:[1,0]
	v_pk_mul_f32 v[202:203], v[30:31], v[190:191] op_sel_hi:[1,0]
	v_pk_mul_f32 v[206:207], v[14:15], v[190:191] op_sel_hi:[1,0]
	v_pk_mul_f32 v[190:191], v[16:17], v[190:191] op_sel_hi:[1,0]
	v_pk_fma_f32 v[174:175], v[198:199], v[174:175], v[22:23]
	v_pk_fma_f32 v[182:183], v[204:205], v[182:183], v[20:21]
	v_max_f32_e32 v173, 0, v173
	v_max_f32_e32 v172, 0, v172
	v_max_f32_e32 v171, 0, v171
	v_max_f32_e32 v170, 0, v170
	v_pk_fma_f32 v[176:177], v[200:201], v[176:177], v[24:25]
	v_pk_fma_f32 v[180:181], v[202:203], v[180:181], v[18:19]
	v_pk_fma_f32 v[184:185], v[190:191], v[184:185], v[12:13]
	v_max_f32_e32 v175, 0, v175
	v_max_f32_e32 v174, 0, v174
	v_max_f32_e32 v183, 0, v183
	v_max_f32_e32 v182, 0, v182
	v_pk_mul_f32 v[190:191], v[170:171], v[170:171]
	v_pk_mul_f32 v[170:171], v[172:173], v[172:173]
	v_max_f32_e32 v177, 0, v177
	v_max_f32_e32 v176, 0, v176
	v_max_f32_e32 v181, 0, v181
	v_max_f32_e32 v180, 0, v180
	v_pk_mul_f32 v[172:173], v[174:175], v[174:175]
	v_pk_mul_f32 v[174:175], v[182:183], v[182:183]
	v_cvt_pk_bf16_f32 v170, v170, v171
	v_cvt_pk_bf16_f32 v171, v190, v191
	v_pk_fma_f32 v[178:179], v[206:207], v[178:179], v[10:11]
	v_pk_mul_f32 v[176:177], v[176:177], v[176:177]
	v_pk_mul_f32 v[180:181], v[180:181], v[180:181]
	v_cvt_pk_bf16_f32 v172, v172, v173
	v_cvt_pk_bf16_f32 v173, v176, v177
	global_store_dwordx4 v[192:193], v[170:173], off sc1
	v_max_f32_e32 v179, 0, v179
	v_max_f32_e32 v178, 0, v178
	v_cvt_pk_bf16_f32 v170, v180, v181
	v_cvt_pk_bf16_f32 v171, v174, v175
	v_lshl_add_u64 v[174:175], s[34:35], 0, v[138:139]
	v_max_f32_e32 v185, 0, v185
	v_max_f32_e32 v184, 0, v184
	v_lshl_add_u64 v[174:175], v[174:175], 0, v[90:91]
	v_pk_mul_f32 v[182:183], v[184:185], v[184:185]
	v_pk_mul_f32 v[178:179], v[178:179], v[178:179]
	s_nop 0
	v_cvt_pk_bf16_f32 v172, v178, v179
	v_cvt_pk_bf16_f32 v173, v182, v183
	global_store_dwordx4 v[174:175], v[170:173], off sc1
	v_or_b32_e32 v174, 32, v168
	v_ashrrev_i32_e32 v175, 31, v174
	v_or_b32_e32 v170, 16, v168
	v_ashrrev_i32_e32 v171, 31, v170
	v_lshl_add_u64 v[172:173], v[170:171], 2, s[14:15]
	global_load_dword v172, v[172:173], off
	v_lshlrev_b32_e32 v138, 7, v170
	v_and_b32_e32 v138, 0x6f80, v138
	v_lshl_add_u64 v[176:177], s[30:31], 0, v[138:139]
	v_lshl_add_u64 v[178:179], s[34:35], 0, v[138:139]
	v_lshl_add_u64 v[176:177], v[176:177], 0, v[90:91]
	v_lshl_add_u64 v[178:179], v[178:179], 0, v[90:91]
	v_lshl_add_u64 v[170:171], v[174:175], 2, s[14:15]
	v_lshlrev_b32_e32 v138, 7, v174
	v_and_b32_e32 v138, 0x7780, v138
	s_waitcnt vmcnt(0)
	v_pk_mul_f32 v[180:181], v[6:7], v[172:173] op_sel_hi:[1,0]
	v_pk_mul_f32 v[182:183], v[8:9], v[172:173] op_sel_hi:[1,0]
	v_pk_mul_f32 v[184:185], v[2:3], v[172:173] op_sel_hi:[1,0]
	v_pk_mul_f32 v[190:191], v[4:5], v[172:173] op_sel_hi:[1,0]
	v_pk_fma_f32 v[154:155], v[182:183], v[154:155], v[28:29]
	v_pk_fma_f32 v[152:153], v[180:181], v[152:153], v[26:27]
	v_pk_mul_f32 v[192:193], v[30:31], v[172:173] op_sel_hi:[1,0]
	v_pk_mul_f32 v[194:195], v[32:33], v[172:173] op_sel_hi:[1,0]
	v_pk_mul_f32 v[196:197], v[14:15], v[172:173] op_sel_hi:[1,0]
	v_pk_mul_f32 v[172:173], v[16:17], v[172:173] op_sel_hi:[1,0]
	v_pk_fma_f32 v[158:159], v[190:191], v[158:159], v[24:25]
	v_pk_fma_f32 v[156:157], v[184:185], v[156:157], v[22:23]
	v_max_f32_e32 v153, 0, v153
	v_max_f32_e32 v152, 0, v152
	v_max_f32_e32 v155, 0, v155
	v_max_f32_e32 v154, 0, v154
	v_pk_fma_f32 v[162:163], v[194:195], v[162:163], v[20:21]
	v_pk_fma_f32 v[160:161], v[192:193], v[160:161], v[18:19]
	v_pk_fma_f32 v[166:167], v[172:173], v[166:167], v[12:13]
	v_pk_fma_f32 v[164:165], v[196:197], v[164:165], v[10:11]
	v_max_f32_e32 v157, 0, v157
	v_max_f32_e32 v156, 0, v156
	v_max_f32_e32 v159, 0, v159
	v_max_f32_e32 v158, 0, v158
	v_pk_mul_f32 v[154:155], v[154:155], v[154:155]
	v_pk_mul_f32 v[152:153], v[152:153], v[152:153]
	v_max_f32_e32 v161, 0, v161
	v_max_f32_e32 v160, 0, v160
	v_max_f32_e32 v163, 0, v163
	v_max_f32_e32 v162, 0, v162
	v_max_f32_e32 v165, 0, v165
	v_max_f32_e32 v164, 0, v164
	v_max_f32_e32 v167, 0, v167
	v_max_f32_e32 v166, 0, v166
	v_pk_mul_f32 v[158:159], v[158:159], v[158:159]
	v_pk_mul_f32 v[156:157], v[156:157], v[156:157]
	v_cvt_pk_bf16_f32 v152, v152, v153
	v_cvt_pk_bf16_f32 v153, v154, v155
	v_pk_mul_f32 v[162:163], v[162:163], v[162:163]
	v_cvt_pk_bf16_f32 v154, v156, v157
	v_cvt_pk_bf16_f32 v155, v158, v159
	v_pk_mul_f32 v[160:161], v[160:161], v[160:161]
	v_pk_mul_f32 v[166:167], v[166:167], v[166:167]
	v_pk_mul_f32 v[164:165], v[164:165], v[164:165]
	global_store_dwordx4 v[176:177], v[152:155], off sc1
	v_lshl_add_u64 v[158:159], s[30:31], 0, v[138:139]
	v_lshl_add_u64 v[158:159], v[158:159], 0, v[90:91]
	v_cvt_pk_bf16_f32 v152, v160, v161
	v_cvt_pk_bf16_f32 v153, v162, v163
	v_cvt_pk_bf16_f32 v154, v164, v165
	v_cvt_pk_bf16_f32 v155, v166, v167
	global_store_dwordx4 v[178:179], v[152:155], off sc1
	global_load_dword v152, v[170:171], off
	v_lshl_add_u64 v[160:161], s[34:35], 0, v[138:139]
	v_or_b32_e32 v154, 48, v168
	v_ashrrev_i32_e32 v155, 31, v154
	v_lshl_add_u64 v[160:161], v[160:161], 0, v[90:91]
	v_lshl_add_u64 v[156:157], v[154:155], 2, s[14:15]
	s_waitcnt vmcnt(0)
	v_pk_mul_f32 v[162:163], v[6:7], v[152:153] op_sel_hi:[1,0]
	v_pk_mul_f32 v[164:165], v[8:9], v[152:153] op_sel_hi:[1,0]
	v_pk_mul_f32 v[166:167], v[2:3], v[152:153] op_sel_hi:[1,0]
	v_pk_mul_f32 v[170:171], v[4:5], v[152:153] op_sel_hi:[1,0]
	v_pk_fma_f32 v[120:121], v[164:165], v[120:121], v[28:29]
	v_pk_fma_f32 v[118:119], v[162:163], v[118:119], v[26:27]
	v_pk_mul_f32 v[172:173], v[30:31], v[152:153] op_sel_hi:[1,0]
	v_pk_mul_f32 v[174:175], v[32:33], v[152:153] op_sel_hi:[1,0]
	v_pk_mul_f32 v[176:177], v[14:15], v[152:153] op_sel_hi:[1,0]
	v_pk_mul_f32 v[152:153], v[16:17], v[152:153] op_sel_hi:[1,0]
	v_pk_fma_f32 v[124:125], v[170:171], v[124:125], v[24:25]
	v_pk_fma_f32 v[122:123], v[166:167], v[122:123], v[22:23]
	v_max_f32_e32 v119, 0, v119
	v_max_f32_e32 v118, 0, v118
	v_max_f32_e32 v121, 0, v121
	v_max_f32_e32 v120, 0, v120
	v_pk_fma_f32 v[128:129], v[174:175], v[128:129], v[20:21]
	v_pk_fma_f32 v[126:127], v[172:173], v[126:127], v[18:19]
	v_pk_fma_f32 v[150:151], v[152:153], v[150:151], v[12:13]
	v_pk_fma_f32 v[148:149], v[176:177], v[148:149], v[10:11]
	v_max_f32_e32 v123, 0, v123
	v_max_f32_e32 v122, 0, v122
	v_max_f32_e32 v125, 0, v125
	v_max_f32_e32 v124, 0, v124
	v_pk_mul_f32 v[120:121], v[120:121], v[120:121]
	v_pk_mul_f32 v[118:119], v[118:119], v[118:119]
	v_max_f32_e32 v127, 0, v127
	v_max_f32_e32 v126, 0, v126
	v_max_f32_e32 v129, 0, v129
	v_max_f32_e32 v128, 0, v128
	v_max_f32_e32 v149, 0, v149
	v_max_f32_e32 v148, 0, v148
	v_max_f32_e32 v151, 0, v151
	v_max_f32_e32 v150, 0, v150
	v_pk_mul_f32 v[124:125], v[124:125], v[124:125]
	v_pk_mul_f32 v[122:123], v[122:123], v[122:123]
	v_cvt_pk_bf16_f32 v118, v118, v119
	v_cvt_pk_bf16_f32 v119, v120, v121
	v_pk_mul_f32 v[128:129], v[128:129], v[128:129]
	v_cvt_pk_bf16_f32 v120, v122, v123
	v_cvt_pk_bf16_f32 v121, v124, v125
	v_pk_mul_f32 v[126:127], v[126:127], v[126:127]
	v_pk_mul_f32 v[150:151], v[150:151], v[150:151]
	v_pk_mul_f32 v[148:149], v[148:149], v[148:149]
	global_store_dwordx4 v[158:159], v[118:121], off sc1
	s_nop 1
	v_cvt_pk_bf16_f32 v118, v126, v127
	v_cvt_pk_bf16_f32 v119, v128, v129
	v_cvt_pk_bf16_f32 v120, v148, v149
	v_cvt_pk_bf16_f32 v121, v150, v151
	global_store_dwordx4 v[160:161], v[118:121], off sc1
	global_load_dword v118, v[156:157], off
	s_nop 0
	v_lshlrev_b32_e32 v119, 7, v154
	v_and_b32_e32 v138, 0x7f80, v119
	v_lshl_add_u64 v[120:121], s[30:31], 0, v[138:139]
	v_lshl_add_u64 v[122:123], s[34:35], 0, v[138:139]
	v_lshl_add_u64 v[120:121], v[120:121], 0, v[90:91]
	v_lshl_add_u64 v[122:123], v[122:123], 0, v[90:91]
	s_waitcnt vmcnt(0)
	v_pk_mul_f32 v[124:125], v[6:7], v[118:119] op_sel_hi:[1,0]
	v_pk_mul_f32 v[126:127], v[8:9], v[118:119] op_sel_hi:[1,0]
	v_pk_mul_f32 v[128:129], v[2:3], v[118:119] op_sel_hi:[1,0]
	v_pk_mul_f32 v[148:149], v[4:5], v[118:119] op_sel_hi:[1,0]
	v_pk_fma_f32 v[104:105], v[126:127], v[104:105], v[28:29]
	v_pk_fma_f32 v[102:103], v[124:125], v[102:103], v[26:27]
	v_pk_mul_f32 v[150:151], v[30:31], v[118:119] op_sel_hi:[1,0]
	v_pk_mul_f32 v[152:153], v[32:33], v[118:119] op_sel_hi:[1,0]
	v_pk_mul_f32 v[154:155], v[14:15], v[118:119] op_sel_hi:[1,0]
	v_pk_mul_f32 v[118:119], v[16:17], v[118:119] op_sel_hi:[1,0]
	v_pk_fma_f32 v[108:109], v[148:149], v[108:109], v[24:25]
	v_pk_fma_f32 v[106:107], v[128:129], v[106:107], v[22:23]
	v_max_f32_e32 v103, 0, v103
	v_max_f32_e32 v102, 0, v102
	v_max_f32_e32 v105, 0, v105
	v_max_f32_e32 v104, 0, v104
	v_pk_fma_f32 v[112:113], v[152:153], v[112:113], v[20:21]
	v_pk_fma_f32 v[110:111], v[150:151], v[110:111], v[18:19]
	v_pk_fma_f32 v[116:117], v[118:119], v[116:117], v[12:13]
	v_pk_fma_f32 v[114:115], v[154:155], v[114:115], v[10:11]
	v_max_f32_e32 v107, 0, v107
	v_max_f32_e32 v106, 0, v106
	v_max_f32_e32 v109, 0, v109
	v_max_f32_e32 v108, 0, v108
	v_pk_mul_f32 v[104:105], v[104:105], v[104:105]
	v_pk_mul_f32 v[102:103], v[102:103], v[102:103]
	v_max_f32_e32 v111, 0, v111
	v_max_f32_e32 v110, 0, v110
	v_max_f32_e32 v113, 0, v113
	v_max_f32_e32 v112, 0, v112
	v_max_f32_e32 v115, 0, v115
	v_max_f32_e32 v114, 0, v114
	v_max_f32_e32 v117, 0, v117
	v_max_f32_e32 v116, 0, v116
	v_pk_mul_f32 v[108:109], v[108:109], v[108:109]
	v_pk_mul_f32 v[106:107], v[106:107], v[106:107]
	v_cvt_pk_bf16_f32 v102, v102, v103
	v_cvt_pk_bf16_f32 v103, v104, v105
	v_pk_mul_f32 v[112:113], v[112:113], v[112:113]
	v_cvt_pk_bf16_f32 v104, v106, v107
	v_cvt_pk_bf16_f32 v105, v108, v109
	v_pk_mul_f32 v[110:111], v[110:111], v[110:111]
	v_pk_mul_f32 v[116:117], v[116:117], v[116:117]
	v_pk_mul_f32 v[114:115], v[114:115], v[114:115]
	global_store_dwordx4 v[120:121], v[102:105], off sc1
	s_nop 1
	v_cvt_pk_bf16_f32 v102, v110, v111
	v_cvt_pk_bf16_f32 v103, v112, v113
	v_cvt_pk_bf16_f32 v104, v114, v115
	v_cvt_pk_bf16_f32 v105, v116, v117
	global_store_dwordx4 v[122:123], v[102:105], off sc1
	global_load_dword v106, v[100:101], off offset:512
	s_nop 0
	v_add_u32_e32 v103, 0x80, v168
	v_ashrrev_i32_e32 v102, 8, v103
	v_lshlrev_b32_e32 v107, 7, v103
	v_ashrrev_i32_e32 v103, 31, v102
	v_lshlrev_b64 v[104:105], 7, v[102:103]
	v_lshl_add_u64 v[102:103], v[104:105], 0, s[26:27]
	v_lshl_add_u64 v[104:105], v[104:105], 0, s[28:29]
	v_lshlrev_b64 v[102:103], 15, v[102:103]
	v_lshlrev_b64 v[104:105], 15, v[104:105]
	v_lshl_add_u64 v[102:103], s[12:13], 0, v[102:103]
	v_lshl_add_u64 v[104:105], s[12:13], 0, v[104:105]
	v_and_b32_e32 v138, 0x6780, v107
	v_lshl_add_u64 v[108:109], v[102:103], 0, v[138:139]
	v_lshl_add_u64 v[110:111], v[104:105], 0, v[138:139]
	v_lshl_add_u64 v[108:109], v[108:109], 0, v[90:91]
	v_lshl_add_u64 v[110:111], v[110:111], 0, v[90:91]
	s_waitcnt vmcnt(0)
	v_pk_mul_f32 v[112:113], v[6:7], v[106:107] op_sel_hi:[1,0]
	v_pk_mul_f32 v[114:115], v[8:9], v[106:107] op_sel_hi:[1,0]
	v_pk_mul_f32 v[116:117], v[2:3], v[106:107] op_sel_hi:[1,0]
	v_pk_mul_f32 v[118:119], v[4:5], v[106:107] op_sel_hi:[1,0]
	v_pk_fma_f32 v[84:85], v[114:115], v[84:85], v[28:29]
	v_pk_fma_f32 v[82:83], v[112:113], v[82:83], v[26:27]
	v_pk_mul_f32 v[120:121], v[30:31], v[106:107] op_sel_hi:[1,0]
	v_pk_mul_f32 v[122:123], v[32:33], v[106:107] op_sel_hi:[1,0]
	v_pk_mul_f32 v[124:125], v[14:15], v[106:107] op_sel_hi:[1,0]
	v_pk_mul_f32 v[106:107], v[16:17], v[106:107] op_sel_hi:[1,0]
	v_pk_fma_f32 v[88:89], v[118:119], v[88:89], v[24:25]
	v_pk_fma_f32 v[86:87], v[116:117], v[86:87], v[22:23]
	v_max_f32_e32 v83, 0, v83
	v_max_f32_e32 v82, 0, v82
	v_max_f32_e32 v85, 0, v85
	v_max_f32_e32 v84, 0, v84
	v_pk_fma_f32 v[94:95], v[122:123], v[94:95], v[20:21]
	v_pk_fma_f32 v[92:93], v[120:121], v[92:93], v[18:19]
	v_pk_fma_f32 v[98:99], v[106:107], v[98:99], v[12:13]
	v_pk_fma_f32 v[96:97], v[124:125], v[96:97], v[10:11]
	v_max_f32_e32 v87, 0, v87
	v_max_f32_e32 v86, 0, v86
	v_max_f32_e32 v89, 0, v89
	v_max_f32_e32 v88, 0, v88
	v_pk_mul_f32 v[84:85], v[84:85], v[84:85]
	v_pk_mul_f32 v[82:83], v[82:83], v[82:83]
	v_max_f32_e32 v93, 0, v93
	v_max_f32_e32 v92, 0, v92
	v_max_f32_e32 v95, 0, v95
	v_max_f32_e32 v94, 0, v94
	v_max_f32_e32 v97, 0, v97
	v_max_f32_e32 v96, 0, v96
	v_max_f32_e32 v99, 0, v99
	v_max_f32_e32 v98, 0, v98
	v_pk_mul_f32 v[88:89], v[88:89], v[88:89]
	v_pk_mul_f32 v[86:87], v[86:87], v[86:87]
	v_cvt_pk_bf16_f32 v82, v82, v83
	v_cvt_pk_bf16_f32 v83, v84, v85
	v_pk_mul_f32 v[94:95], v[94:95], v[94:95]
	v_cvt_pk_bf16_f32 v84, v86, v87
	v_cvt_pk_bf16_f32 v85, v88, v89
	v_pk_mul_f32 v[92:93], v[92:93], v[92:93]
	v_pk_mul_f32 v[98:99], v[98:99], v[98:99]
	v_pk_mul_f32 v[96:97], v[96:97], v[96:97]
	global_store_dwordx4 v[108:109], v[82:85], off sc1
	s_nop 1
	v_cvt_pk_bf16_f32 v82, v92, v93
	v_cvt_pk_bf16_f32 v83, v94, v95
	v_cvt_pk_bf16_f32 v84, v96, v97
	v_cvt_pk_bf16_f32 v85, v98, v99
	global_store_dwordx4 v[110:111], v[82:85], off sc1
	global_load_dword v82, v[100:101], off offset:576
	s_nop 0
	v_add_u32_e32 v83, 0x4800, v169
	v_and_b32_e32 v138, 0x6f80, v83
	v_lshl_add_u64 v[84:85], v[102:103], 0, v[138:139]
	v_lshl_add_u64 v[86:87], v[104:105], 0, v[138:139]
	v_lshl_add_u64 v[84:85], v[84:85], 0, v[90:91]
	v_lshl_add_u64 v[86:87], v[86:87], 0, v[90:91]
	s_waitcnt vmcnt(0)
	v_pk_mul_f32 v[88:89], v[6:7], v[82:83] op_sel_hi:[1,0]
	v_pk_mul_f32 v[92:93], v[8:9], v[82:83] op_sel_hi:[1,0]
	v_pk_mul_f32 v[94:95], v[2:3], v[82:83] op_sel_hi:[1,0]
	v_pk_mul_f32 v[96:97], v[4:5], v[82:83] op_sel_hi:[1,0]
	v_pk_fma_f32 v[68:69], v[92:93], v[68:69], v[28:29]
	v_pk_fma_f32 v[66:67], v[88:89], v[66:67], v[26:27]
	v_pk_mul_f32 v[98:99], v[30:31], v[82:83] op_sel_hi:[1,0]
	v_pk_mul_f32 v[106:107], v[32:33], v[82:83] op_sel_hi:[1,0]
	v_pk_mul_f32 v[108:109], v[14:15], v[82:83] op_sel_hi:[1,0]
	v_pk_mul_f32 v[82:83], v[16:17], v[82:83] op_sel_hi:[1,0]
	v_pk_fma_f32 v[72:73], v[96:97], v[72:73], v[24:25]
	v_pk_fma_f32 v[70:71], v[94:95], v[70:71], v[22:23]
	v_max_f32_e32 v67, 0, v67
	v_max_f32_e32 v66, 0, v66
	v_max_f32_e32 v69, 0, v69
	v_max_f32_e32 v68, 0, v68
	v_pk_fma_f32 v[76:77], v[106:107], v[76:77], v[20:21]
	v_pk_fma_f32 v[74:75], v[98:99], v[74:75], v[18:19]
	v_pk_fma_f32 v[80:81], v[82:83], v[80:81], v[12:13]
	v_pk_fma_f32 v[78:79], v[108:109], v[78:79], v[10:11]
	v_max_f32_e32 v71, 0, v71
	v_max_f32_e32 v70, 0, v70
	v_max_f32_e32 v73, 0, v73
	v_max_f32_e32 v72, 0, v72
	v_pk_mul_f32 v[68:69], v[68:69], v[68:69]
	v_pk_mul_f32 v[66:67], v[66:67], v[66:67]
	v_max_f32_e32 v75, 0, v75
	v_max_f32_e32 v74, 0, v74
	v_max_f32_e32 v77, 0, v77
	v_max_f32_e32 v76, 0, v76
	v_max_f32_e32 v79, 0, v79
	v_max_f32_e32 v78, 0, v78
	v_max_f32_e32 v81, 0, v81
	v_max_f32_e32 v80, 0, v80
	v_pk_mul_f32 v[72:73], v[72:73], v[72:73]
	v_pk_mul_f32 v[70:71], v[70:71], v[70:71]
	v_cvt_pk_bf16_f32 v66, v66, v67
	v_cvt_pk_bf16_f32 v67, v68, v69
	v_pk_mul_f32 v[76:77], v[76:77], v[76:77]
	v_cvt_pk_bf16_f32 v68, v70, v71
	v_cvt_pk_bf16_f32 v69, v72, v73
	v_pk_mul_f32 v[74:75], v[74:75], v[74:75]
	v_pk_mul_f32 v[80:81], v[80:81], v[80:81]
	v_pk_mul_f32 v[78:79], v[78:79], v[78:79]
	global_store_dwordx4 v[84:85], v[66:69], off sc1
	s_nop 1
	v_cvt_pk_bf16_f32 v66, v74, v75
	v_cvt_pk_bf16_f32 v67, v76, v77
	v_cvt_pk_bf16_f32 v68, v78, v79
	v_cvt_pk_bf16_f32 v69, v80, v81
	global_store_dwordx4 v[86:87], v[66:69], off sc1
	global_load_dword v66, v[100:101], off offset:640
	s_nop 0
	v_add_u32_e32 v67, 0x5000, v169
	v_and_b32_e32 v138, 0x7780, v67
	v_lshl_add_u64 v[68:69], v[102:103], 0, v[138:139]
	v_lshl_add_u64 v[70:71], v[104:105], 0, v[138:139]
	v_lshl_add_u64 v[68:69], v[68:69], 0, v[90:91]
	v_lshl_add_u64 v[70:71], v[70:71], 0, v[90:91]
	s_waitcnt vmcnt(0)
	v_pk_mul_f32 v[72:73], v[6:7], v[66:67] op_sel_hi:[1,0]
	v_pk_mul_f32 v[74:75], v[8:9], v[66:67] op_sel_hi:[1,0]
	v_pk_mul_f32 v[76:77], v[2:3], v[66:67] op_sel_hi:[1,0]
	v_pk_mul_f32 v[78:79], v[4:5], v[66:67] op_sel_hi:[1,0]
	v_pk_fma_f32 v[52:53], v[74:75], v[52:53], v[28:29]
	v_pk_fma_f32 v[50:51], v[72:73], v[50:51], v[26:27]
	v_pk_mul_f32 v[80:81], v[30:31], v[66:67] op_sel_hi:[1,0]
	v_pk_mul_f32 v[82:83], v[32:33], v[66:67] op_sel_hi:[1,0]
	v_pk_mul_f32 v[84:85], v[14:15], v[66:67] op_sel_hi:[1,0]
	v_pk_mul_f32 v[66:67], v[16:17], v[66:67] op_sel_hi:[1,0]
	v_pk_fma_f32 v[56:57], v[78:79], v[56:57], v[24:25]
	v_pk_fma_f32 v[54:55], v[76:77], v[54:55], v[22:23]
	v_max_f32_e32 v51, 0, v51
	v_max_f32_e32 v50, 0, v50
	v_max_f32_e32 v53, 0, v53
	v_max_f32_e32 v52, 0, v52
	v_pk_fma_f32 v[60:61], v[82:83], v[60:61], v[20:21]
	v_pk_fma_f32 v[58:59], v[80:81], v[58:59], v[18:19]
	v_pk_fma_f32 v[64:65], v[66:67], v[64:65], v[12:13]
	v_pk_fma_f32 v[62:63], v[84:85], v[62:63], v[10:11]
	v_max_f32_e32 v55, 0, v55
	v_max_f32_e32 v54, 0, v54
	v_max_f32_e32 v57, 0, v57
	v_max_f32_e32 v56, 0, v56
	v_pk_mul_f32 v[52:53], v[52:53], v[52:53]
	v_pk_mul_f32 v[50:51], v[50:51], v[50:51]
	v_max_f32_e32 v59, 0, v59
	v_max_f32_e32 v58, 0, v58
	v_max_f32_e32 v61, 0, v61
	v_max_f32_e32 v60, 0, v60
	v_max_f32_e32 v63, 0, v63
	v_max_f32_e32 v62, 0, v62
	v_max_f32_e32 v65, 0, v65
	v_max_f32_e32 v64, 0, v64
	v_pk_mul_f32 v[56:57], v[56:57], v[56:57]
	v_pk_mul_f32 v[54:55], v[54:55], v[54:55]
	v_cvt_pk_bf16_f32 v50, v50, v51
	v_cvt_pk_bf16_f32 v51, v52, v53
	v_pk_mul_f32 v[60:61], v[60:61], v[60:61]
	v_cvt_pk_bf16_f32 v52, v54, v55
	v_cvt_pk_bf16_f32 v53, v56, v57
	v_pk_mul_f32 v[58:59], v[58:59], v[58:59]
	v_pk_mul_f32 v[64:65], v[64:65], v[64:65]
	v_pk_mul_f32 v[62:63], v[62:63], v[62:63]
	global_store_dwordx4 v[68:69], v[50:53], off sc1
	s_nop 1
	v_cvt_pk_bf16_f32 v50, v58, v59
	v_cvt_pk_bf16_f32 v51, v60, v61
	v_cvt_pk_bf16_f32 v52, v62, v63
	v_cvt_pk_bf16_f32 v53, v64, v65
	global_store_dwordx4 v[70:71], v[50:53], off sc1
	global_load_dword v50, v[100:101], off offset:704
	s_nop 0
	v_add_u32_e32 v51, 0x5800, v169
	v_and_b32_e32 v138, 0x7f80, v51
	v_lshl_add_u64 v[52:53], v[102:103], 0, v[138:139]
	v_lshl_add_u64 v[54:55], v[104:105], 0, v[138:139]
	v_lshl_add_u64 v[52:53], v[52:53], 0, v[90:91]
	v_lshl_add_u64 v[54:55], v[54:55], 0, v[90:91]
	s_waitcnt vmcnt(0)
	v_pk_mul_f32 v[2:3], v[2:3], v[50:51] op_sel_hi:[1,0]
	v_pk_mul_f32 v[4:5], v[4:5], v[50:51] op_sel_hi:[1,0]
	v_pk_mul_f32 v[6:7], v[6:7], v[50:51] op_sel_hi:[1,0]
	v_pk_mul_f32 v[8:9], v[8:9], v[50:51] op_sel_hi:[1,0]
	v_pk_mul_f32 v[30:31], v[30:31], v[50:51] op_sel_hi:[1,0]
	v_pk_fma_f32 v[4:5], v[4:5], v[40:41], v[24:25]
	v_pk_fma_f32 v[2:3], v[2:3], v[38:39], v[22:23]
	v_pk_mul_f32 v[32:33], v[32:33], v[50:51] op_sel_hi:[1,0]
	v_pk_mul_f32 v[14:15], v[14:15], v[50:51] op_sel_hi:[1,0]
	v_pk_mul_f32 v[16:17], v[16:17], v[50:51] op_sel_hi:[1,0]
	v_pk_fma_f32 v[8:9], v[8:9], v[36:37], v[28:29]
	v_pk_fma_f32 v[6:7], v[6:7], v[34:35], v[26:27]
	v_pk_fma_f32 v[18:19], v[30:31], v[42:43], v[18:19]
	v_max_f32_e32 v3, 0, v3
	v_max_f32_e32 v2, 0, v2
	v_max_f32_e32 v5, 0, v5
	v_max_f32_e32 v4, 0, v4
	v_pk_fma_f32 v[20:21], v[32:33], v[44:45], v[20:21]
	v_pk_fma_f32 v[12:13], v[16:17], v[48:49], v[12:13]
	v_pk_fma_f32 v[10:11], v[14:15], v[46:47], v[10:11]
	v_max_f32_e32 v7, 0, v7
	v_max_f32_e32 v6, 0, v6
	v_max_f32_e32 v9, 0, v9
	v_max_f32_e32 v8, 0, v8
	v_max_f32_e32 v15, 0, v19
	v_max_f32_e32 v14, 0, v18
	v_pk_mul_f32 v[18:19], v[4:5], v[4:5]
	v_pk_mul_f32 v[4:5], v[2:3], v[2:3]
	v_max_f32_e32 v17, 0, v21
	v_max_f32_e32 v16, 0, v20
	v_max_f32_e32 v11, 0, v11
	v_max_f32_e32 v10, 0, v10
	v_max_f32_e32 v13, 0, v13
	v_max_f32_e32 v12, 0, v12
	v_pk_mul_f32 v[8:9], v[8:9], v[8:9]
	v_pk_mul_f32 v[6:7], v[6:7], v[6:7]
	v_pk_mul_f32 v[16:17], v[16:17], v[16:17]
	v_cvt_pk_bf16_f32 v2, v6, v7
	v_cvt_pk_bf16_f32 v3, v8, v9
	v_cvt_pk_bf16_f32 v4, v4, v5
	v_cvt_pk_bf16_f32 v5, v18, v19
	v_pk_mul_f32 v[14:15], v[14:15], v[14:15]
	v_pk_mul_f32 v[12:13], v[12:13], v[12:13]
	v_pk_mul_f32 v[10:11], v[10:11], v[10:11]
	global_store_dwordx4 v[52:53], v[2:5], off sc1
	s_nop 1
	v_cvt_pk_bf16_f32 v2, v14, v15
	v_cvt_pk_bf16_f32 v3, v16, v17
	v_cvt_pk_bf16_f32 v4, v10, v11
	v_cvt_pk_bf16_f32 v5, v12, v13
	global_store_dwordx4 v[54:55], v[2:5], off sc1
	s_cbranch_vccnz .LBB0_1926
	s_andn2_b64 vcc, exec, s[10:11]
	s_cbranch_vccnz .LBB0_1925
	s_barrier
	s_branch .LBB0_1925

.LBB0_2025:
	s_lshr_b32 s34, s81, 4
	s_add_i32 s34, s34, -1
	s_cmp_gt_i32 s81, 31
	s_cselect_b32 s34, s34, 0
	v_lshl_or_b32 v178, s12, 8, v208
	s_mul_i32 s37, s34, 0xc000
	s_mul_hi_i32 s36, s34, 0xc000
	s_add_u32 s34, s55, s37
	v_ashrrev_i32_e32 v179, 31, v178
	s_addc_u32 s35, s56, s36
	v_lshlrev_b64 v[114:115], 2, v[178:179]
	v_lshl_add_u64 v[122:123], s[34:35], 0, v[114:115]
	s_add_u32 s34, s57, s37
	v_lshl_add_u32 v196, s81, 8, v206
	v_lshl_add_u64 v[116:117], s[20:21], 0, v[114:115]
	s_addc_u32 s35, s58, s36
	v_ashrrev_i32_e32 v197, 31, v196
	v_lshl_add_u64 v[124:125], s[34:35], 0, v[114:115]
	global_load_dwordx4 v[118:121], v[122:123], off offset:16
	global_load_dwordx4 v[126:129], v[122:123], off
	global_load_dwordx4 v[180:183], v[116:117], off offset:16
	global_load_dwordx4 v[184:187], v[116:117], off
	global_load_dwordx4 v[188:191], v[124:125], off offset:16
	global_load_dwordx4 v[192:195], v[124:125], off
	global_load_dwordx4 v[214:217], v[116:117], off offset:528
	global_load_dwordx4 v[218:221], v[116:117], off offset:512
	global_load_dwordx4 v[222:225], v[124:125], off offset:528
	global_load_dwordx4 v[226:229], v[124:125], off offset:512
	v_lshlrev_b64 v[116:117], 13, v[196:197]
	v_or_b32_e32 v198, 16, v196
	v_lshl_add_u64 v[116:117], s[16:17], 0, v[116:117]
	v_ashrrev_i32_e32 v199, 31, v198
	v_lshl_add_u64 v[200:201], v[116:117], 0, v[114:115]
	v_lshlrev_b64 v[116:117], 13, v[198:199]
	v_lshl_add_u64 v[116:117], s[16:17], 0, v[116:117]
	v_lshl_add_u64 v[202:203], v[116:117], 0, v[114:115]
	global_load_dwordx4 v[230:233], v[200:201], off offset:16 nt
	global_load_dwordx4 v[234:237], v[200:201], off nt
	global_load_dwordx4 v[238:241], v[200:201], off offset:528 nt
	global_load_dwordx4 v[242:245], v[200:201], off offset:512 nt
	global_load_dwordx4 v[154:157], v[202:203], off offset:16 nt
	global_load_dwordx4 v[158:161], v[202:203], off nt
	global_load_dwordx4 v[146:149], v[202:203], off offset:528 nt
	global_load_dwordx4 v[150:153], v[202:203], off offset:512 nt
	global_load_dwordx4 v[114:117], v[122:123], off offset:528
	s_nop 0
	global_load_dwordx4 v[122:125], v[122:123], off offset:512
	s_lshl_b32 s34, s12, 2
	s_ashr_i32 s35, s34, 31
	s_waitcnt vmcnt(0)
	v_pk_add_f32 v[190:191], v[190:191], 1.0 op_sel_hi:[1,0]
	v_pk_add_f32 v[194:195], v[194:195], 1.0 op_sel_hi:[1,0]
	v_pk_add_f32 v[204:205], v[192:193], 1.0 op_sel_hi:[1,0]
	v_pk_add_f32 v[246:247], v[188:189], 1.0 op_sel_hi:[1,0]
	v_pk_add_f32 v[224:225], v[224:225], 1.0 op_sel_hi:[1,0]
	v_pk_add_f32 v[228:229], v[228:229], 1.0 op_sel_hi:[1,0]
	v_pk_add_f32 v[226:227], v[226:227], 1.0 op_sel_hi:[1,0]
	v_pk_add_f32 v[222:223], v[222:223], 1.0 op_sel_hi:[1,0]
	v_pk_mul_f32 v[192:193], v[186:187], v[194:195]
	v_pk_mul_f32 v[194:195], v[184:185], v[204:205]
	v_pk_mul_f32 v[188:189], v[182:183], v[190:191]
	v_pk_mul_f32 v[190:191], v[180:181], v[246:247]
	v_pk_mul_f32 v[186:187], v[220:221], v[228:229]
	v_pk_mul_f32 v[184:185], v[218:219], v[226:227]
	v_pk_mul_f32 v[180:181], v[216:217], v[224:225]
	v_pk_mul_f32 v[182:183], v[214:215], v[222:223]
	v_pk_fma_f32 v[144:145], v[144:145], v[128:129], v[236:237]
	v_pk_fma_f32 v[142:143], v[142:143], v[126:127], v[234:235]
	v_mul_f32_e32 v205, v145, v145
	v_mul_f32_e32 v204, v143, v143
	v_pk_fma_f32 v[138:139], v[138:139], v[118:119], v[230:231]
	v_fmac_f32_e32 v204, v142, v142
	v_fmac_f32_e32 v205, v144, v144
	v_add_f32_e32 v204, v204, v205
	v_mul_f32_e32 v205, v139, v139
	v_pk_fma_f32 v[140:141], v[140:141], v[120:121], v[232:233]
	v_fmac_f32_e32 v205, v138, v138
	v_add_f32_e32 v204, v204, v205
	v_mul_f32_e32 v205, v141, v141
	global_store_dwordx4 v[200:201], v[142:145], off nt
	global_store_dwordx4 v[200:201], v[138:141], off offset:16 nt
	v_fmac_f32_e32 v205, v140, v140
	v_pk_mul_f32 v[142:143], v[194:195], v[142:143]
	v_add_f32_e32 v213, v205, v204
	v_pk_mul_f32 v[204:205], v[188:189], v[140:141]
	v_pk_mul_f32 v[140:141], v[190:191], v[138:139]
	v_cvt_pk_bf16_f32 v138, v142, v143
	v_lshlrev_b64 v[142:143], 12, v[196:197]
	v_lshl_add_u64 v[142:143], s[18:19], 0, v[142:143]
	v_pk_mul_f32 v[144:145], v[192:193], v[144:145]
	v_lshl_add_u64 v[142:143], v[178:179], 1, v[142:143]
	v_cvt_pk_bf16_f32 v139, v144, v145
	v_pk_fma_f32 v[136:137], v[136:137], v[124:125], v[244:245]
	v_pk_fma_f32 v[134:135], v[134:135], v[122:123], v[242:243]
	v_cvt_pk_bf16_f32 v140, v140, v141
	v_cvt_pk_bf16_f32 v141, v204, v205
	global_store_dwordx4 v[142:143], v[138:141], off sc1
	v_pk_fma_f32 v[130:131], v[130:131], v[114:115], v[238:239]
	v_pk_fma_f32 v[132:133], v[132:133], v[116:117], v[240:241]
	v_mul_f32_e32 v138, v135, v135
	v_mul_f32_e32 v139, v137, v137
	v_fmac_f32_e32 v138, v134, v134
	v_fmac_f32_e32 v139, v136, v136
	v_add_f32_e32 v138, v138, v139
	v_mul_f32_e32 v139, v131, v131
	v_fmac_f32_e32 v139, v130, v130
	v_add_f32_e32 v138, v138, v139
	v_mul_f32_e32 v139, v133, v133
	v_fmac_f32_e32 v139, v132, v132
	v_add_f32_e32 v138, v139, v138
	v_and_b32_e32 v139, 64, v212
	v_add_f32_e32 v144, v213, v138
	v_xor_b32_e32 v138, 16, v212
	v_add_u32_e32 v145, 64, v139
	v_cmp_lt_i32_e32 vcc, v138, v145
	global_store_dwordx4 v[200:201], v[134:137], off offset:512 nt
	global_store_dwordx4 v[200:201], v[130:133], off offset:528 nt
	v_cndmask_b32_e32 v138, v212, v138, vcc
	v_lshlrev_b32_e32 v213, 2, v138
	ds_bpermute_b32 v200, v213, v144
	v_pk_mul_f32 v[140:141], v[182:183], v[130:131]
	v_xor_b32_e32 v131, 32, v212
	v_cmp_lt_i32_e32 vcc, v131, v145
	v_pk_mul_f32 v[134:135], v[184:185], v[134:135]
	s_waitcnt lgkmcnt(0)
	v_add_f32_e32 v130, v144, v200
	v_cndmask_b32_e32 v131, v212, v131, vcc
	v_lshlrev_b32_e32 v214, 2, v131
	ds_bpermute_b32 v131, v214, v130
	v_pk_mul_f32 v[136:137], v[186:187], v[136:137]
	v_pk_mul_f32 v[138:139], v[180:181], v[132:133]
	v_cvt_pk_bf16_f32 v132, v134, v135
	v_cvt_pk_bf16_f32 v133, v136, v137
	v_cvt_pk_bf16_f32 v134, v140, v141
	s_nop 0
	v_cvt_pk_bf16_f32 v135, v138, v139
	global_store_dwordx4 v[142:143], v[132:135], off offset:256 sc1
	s_and_saveexec_b64 s[36:37], s[0:1]
	s_cbranch_execz .LBB0_2027
	s_waitcnt lgkmcnt(0)
	v_add_f32_e32 v132, v130, v131
	v_lshlrev_b64 v[130:131], 7, v[196:197]
	v_lshl_add_u64 v[130:131], s[22:23], 0, v[130:131]
	v_lshl_add_u64 v[130:131], s[34:35], 2, v[130:131]
	s_lshl_b32 s12, s59, 2
	v_lshl_add_u64 v[130:131], v[130:131], 0, s[12:13]
	global_store_dword v[130:131], v132, off
.LBB0_2027:
	s_or_b64 exec, exec, s[36:37]
	v_or_b32_e32 v200, 32, v196
	v_ashrrev_i32_e32 v201, 31, v200
	s_waitcnt lgkmcnt(0)
	v_lshlrev_b64 v[130:131], 13, v[200:201]
	v_lshl_add_u64 v[130:131], s[16:17], 0, v[130:131]
	v_lshl_add_u64 v[204:205], v[178:179], 2, v[130:131]
	global_load_dwordx4 v[138:141], v[204:205], off offset:16 nt
	global_load_dwordx4 v[142:145], v[204:205], off nt
	global_load_dwordx4 v[130:133], v[204:205], off offset:528 nt
	global_load_dwordx4 v[134:137], v[204:205], off offset:512 nt
	v_pk_fma_f32 v[112:113], v[112:113], v[128:129], v[160:161]
	v_pk_fma_f32 v[110:111], v[110:111], v[126:127], v[158:159]
	v_pk_fma_f32 v[106:107], v[106:107], v[118:119], v[154:155]
	v_mul_f32_e32 v154, v111, v111
	v_mul_f32_e32 v155, v113, v113
	v_fmac_f32_e32 v154, v110, v110
	v_fmac_f32_e32 v155, v112, v112
	v_add_f32_e32 v154, v154, v155
	v_mul_f32_e32 v155, v107, v107
	v_pk_fma_f32 v[108:109], v[108:109], v[120:121], v[156:157]
	v_fmac_f32_e32 v155, v106, v106
	v_add_f32_e32 v154, v154, v155
	v_mul_f32_e32 v155, v109, v109
	global_store_dwordx4 v[202:203], v[110:113], off nt
	global_store_dwordx4 v[202:203], v[106:109], off offset:16 nt
	v_fmac_f32_e32 v155, v108, v108
	v_pk_mul_f32 v[110:111], v[194:195], v[110:111]
	v_add_f32_e32 v156, v155, v154
	v_pk_mul_f32 v[154:155], v[188:189], v[108:109]
	v_pk_mul_f32 v[108:109], v[190:191], v[106:107]
	v_cvt_pk_bf16_f32 v106, v110, v111
	v_lshlrev_b64 v[110:111], 12, v[198:199]
	v_lshl_add_u64 v[110:111], s[18:19], 0, v[110:111]
	v_pk_mul_f32 v[112:113], v[192:193], v[112:113]
	v_lshl_add_u64 v[110:111], v[178:179], 1, v[110:111]
	v_cvt_pk_bf16_f32 v107, v112, v113
	v_pk_fma_f32 v[104:105], v[104:105], v[124:125], v[152:153]
	v_pk_fma_f32 v[102:103], v[102:103], v[122:123], v[150:151]
	v_cvt_pk_bf16_f32 v108, v108, v109
	v_cvt_pk_bf16_f32 v109, v154, v155
	global_store_dwordx4 v[110:111], v[106:109], off sc1
	v_pk_fma_f32 v[98:99], v[98:99], v[114:115], v[146:147]
	v_pk_fma_f32 v[100:101], v[100:101], v[116:117], v[148:149]
	v_mul_f32_e32 v106, v103, v103
	v_mul_f32_e32 v107, v105, v105
	v_fmac_f32_e32 v106, v102, v102
	v_fmac_f32_e32 v107, v104, v104
	v_add_f32_e32 v106, v106, v107
	v_mul_f32_e32 v107, v99, v99
	v_fmac_f32_e32 v107, v98, v98
	v_add_f32_e32 v106, v106, v107
	v_mul_f32_e32 v107, v101, v101
	v_fmac_f32_e32 v107, v100, v100
	v_add_f32_e32 v106, v107, v106
	v_add_f32_e32 v112, v156, v106
	ds_bpermute_b32 v113, v213, v112
	global_store_dwordx4 v[202:203], v[102:105], off offset:512 nt
	global_store_dwordx4 v[202:203], v[98:101], off offset:528 nt
	v_pk_mul_f32 v[108:109], v[182:183], v[98:99]
	v_pk_mul_f32 v[102:103], v[184:185], v[102:103]
	v_pk_mul_f32 v[104:105], v[186:187], v[104:105]
	s_waitcnt lgkmcnt(0)
	v_add_f32_e32 v98, v112, v113
	ds_bpermute_b32 v99, v214, v98
	v_pk_mul_f32 v[106:107], v[180:181], v[100:101]
	v_cvt_pk_bf16_f32 v100, v102, v103
	v_cvt_pk_bf16_f32 v101, v104, v105
	v_cvt_pk_bf16_f32 v102, v108, v109
	s_nop 0
	v_cvt_pk_bf16_f32 v103, v106, v107
	global_store_dwordx4 v[110:111], v[100:103], off offset:256 sc1
	s_and_saveexec_b64 s[36:37], s[0:1]
	s_cbranch_execz .LBB0_2029
	s_waitcnt lgkmcnt(0)
	v_add_f32_e32 v100, v98, v99
	v_lshlrev_b64 v[98:99], 7, v[198:199]
	v_lshl_add_u64 v[98:99], s[22:23], 0, v[98:99]
	v_lshl_add_u64 v[98:99], s[34:35], 2, v[98:99]
	s_lshl_b32 s12, s59, 2
	v_lshl_add_u64 v[98:99], v[98:99], 0, s[12:13]
	global_store_dword v[98:99], v100, off
.LBB0_2029:
	s_or_b64 exec, exec, s[36:37]
	v_or_b32_e32 v146, 48, v196
	v_ashrrev_i32_e32 v147, 31, v146
	s_waitcnt lgkmcnt(0)
	v_lshlrev_b64 v[98:99], 13, v[146:147]
	v_lshl_add_u64 v[98:99], s[16:17], 0, v[98:99]
	v_lshl_add_u64 v[148:149], v[178:179], 2, v[98:99]
	global_load_dwordx4 v[106:109], v[148:149], off offset:16 nt
	global_load_dwordx4 v[110:113], v[148:149], off nt
	global_load_dwordx4 v[98:101], v[148:149], off offset:528 nt
	global_load_dwordx4 v[102:105], v[148:149], off offset:512 nt
	s_waitcnt vmcnt(12)
	v_pk_fma_f32 v[96:97], v[96:97], v[128:129], v[144:145]
	v_pk_fma_f32 v[94:95], v[94:95], v[126:127], v[142:143]
	v_pk_fma_f32 v[90:91], v[90:91], v[118:119], v[138:139]
	v_mul_f32_e32 v138, v95, v95
	v_mul_f32_e32 v139, v97, v97
	v_fmac_f32_e32 v138, v94, v94
	v_fmac_f32_e32 v139, v96, v96
	v_add_f32_e32 v138, v138, v139
	v_mul_f32_e32 v139, v91, v91
	v_pk_fma_f32 v[92:93], v[92:93], v[120:121], v[140:141]
	v_fmac_f32_e32 v139, v90, v90
	v_add_f32_e32 v138, v138, v139
	v_mul_f32_e32 v139, v93, v93
	global_store_dwordx4 v[204:205], v[94:97], off nt
	global_store_dwordx4 v[204:205], v[90:93], off offset:16 nt
	v_fmac_f32_e32 v139, v92, v92
	v_pk_mul_f32 v[94:95], v[194:195], v[94:95]
	v_add_f32_e32 v140, v139, v138
	v_pk_mul_f32 v[138:139], v[188:189], v[92:93]
	v_pk_mul_f32 v[92:93], v[190:191], v[90:91]
	v_cvt_pk_bf16_f32 v90, v94, v95
	v_lshlrev_b64 v[94:95], 12, v[200:201]
	v_lshl_add_u64 v[94:95], s[18:19], 0, v[94:95]
	v_pk_mul_f32 v[96:97], v[192:193], v[96:97]
	v_lshl_add_u64 v[94:95], v[178:179], 1, v[94:95]
	v_cvt_pk_bf16_f32 v91, v96, v97
	s_waitcnt vmcnt(12)
	v_pk_fma_f32 v[88:89], v[88:89], v[124:125], v[136:137]
	v_pk_fma_f32 v[86:87], v[86:87], v[122:123], v[134:135]
	v_cvt_pk_bf16_f32 v92, v92, v93
	v_cvt_pk_bf16_f32 v93, v138, v139
	global_store_dwordx4 v[94:95], v[90:93], off sc1
	v_pk_fma_f32 v[82:83], v[82:83], v[114:115], v[130:131]
	v_pk_fma_f32 v[84:85], v[84:85], v[116:117], v[132:133]
	v_mul_f32_e32 v90, v87, v87
	v_mul_f32_e32 v91, v89, v89
	v_fmac_f32_e32 v90, v86, v86
	v_fmac_f32_e32 v91, v88, v88
	v_add_f32_e32 v90, v90, v91
	v_mul_f32_e32 v91, v83, v83
	v_fmac_f32_e32 v91, v82, v82
	v_add_f32_e32 v90, v90, v91
	v_mul_f32_e32 v91, v85, v85
	v_fmac_f32_e32 v91, v84, v84
	v_add_f32_e32 v90, v91, v90
	v_add_f32_e32 v96, v140, v90
	ds_bpermute_b32 v97, v213, v96
	global_store_dwordx4 v[204:205], v[86:89], off offset:512 nt
	global_store_dwordx4 v[204:205], v[82:85], off offset:528 nt
	v_pk_mul_f32 v[92:93], v[182:183], v[82:83]
	v_pk_mul_f32 v[86:87], v[184:185], v[86:87]
	v_pk_mul_f32 v[88:89], v[186:187], v[88:89]
	s_waitcnt lgkmcnt(0)
	v_add_f32_e32 v82, v96, v97
	ds_bpermute_b32 v83, v214, v82
	v_pk_mul_f32 v[90:91], v[180:181], v[84:85]
	v_cvt_pk_bf16_f32 v84, v86, v87
	v_cvt_pk_bf16_f32 v85, v88, v89
	v_cvt_pk_bf16_f32 v86, v92, v93
	s_nop 0
	v_cvt_pk_bf16_f32 v87, v90, v91
	global_store_dwordx4 v[94:95], v[84:87], off offset:256 sc1
	s_and_saveexec_b64 s[36:37], s[0:1]
	s_cbranch_execz .LBB0_2031
	s_waitcnt lgkmcnt(0)
	v_add_f32_e32 v84, v82, v83
	v_lshlrev_b64 v[82:83], 7, v[200:201]
	v_lshl_add_u64 v[82:83], s[22:23], 0, v[82:83]
	v_lshl_add_u64 v[82:83], s[34:35], 2, v[82:83]
	s_lshl_b32 s12, s59, 2
	v_lshl_add_u64 v[82:83], v[82:83], 0, s[12:13]
	global_store_dword v[82:83], v84, off
.LBB0_2031:
	s_or_b64 exec, exec, s[36:37]
	v_add_u32_e32 v130, 0x80, v196
	v_ashrrev_i32_e32 v131, 31, v130
	s_waitcnt lgkmcnt(0)
	v_lshlrev_b64 v[82:83], 13, v[130:131]
	v_lshl_add_u64 v[82:83], s[16:17], 0, v[82:83]
	v_lshl_add_u64 v[132:133], v[178:179], 2, v[82:83]
	global_load_dwordx4 v[90:93], v[132:133], off offset:16 nt
	global_load_dwordx4 v[94:97], v[132:133], off nt
	global_load_dwordx4 v[82:85], v[132:133], off offset:528 nt
	global_load_dwordx4 v[86:89], v[132:133], off offset:512 nt
	s_waitcnt vmcnt(12)
	v_pk_fma_f32 v[80:81], v[80:81], v[128:129], v[112:113]
	v_pk_fma_f32 v[78:79], v[78:79], v[126:127], v[110:111]
	v_pk_fma_f32 v[74:75], v[74:75], v[118:119], v[106:107]
	v_mul_f32_e32 v106, v79, v79
	v_mul_f32_e32 v107, v81, v81
	v_fmac_f32_e32 v106, v78, v78
	v_fmac_f32_e32 v107, v80, v80
	v_add_f32_e32 v106, v106, v107
	v_mul_f32_e32 v107, v75, v75
	v_pk_fma_f32 v[76:77], v[76:77], v[120:121], v[108:109]
	v_fmac_f32_e32 v107, v74, v74
	v_add_f32_e32 v106, v106, v107
	v_mul_f32_e32 v107, v77, v77
	global_store_dwordx4 v[148:149], v[78:81], off nt
	global_store_dwordx4 v[148:149], v[74:77], off offset:16 nt
	v_fmac_f32_e32 v107, v76, v76
	v_pk_mul_f32 v[78:79], v[194:195], v[78:79]
	v_add_f32_e32 v108, v107, v106
	v_pk_mul_f32 v[106:107], v[188:189], v[76:77]
	v_pk_mul_f32 v[76:77], v[190:191], v[74:75]
	v_cvt_pk_bf16_f32 v74, v78, v79
	v_lshlrev_b64 v[78:79], 12, v[146:147]
	v_lshl_add_u64 v[78:79], s[18:19], 0, v[78:79]
	v_pk_mul_f32 v[80:81], v[192:193], v[80:81]
	v_lshl_add_u64 v[78:79], v[178:179], 1, v[78:79]
	v_cvt_pk_bf16_f32 v75, v80, v81
	s_waitcnt vmcnt(12)
	v_pk_fma_f32 v[72:73], v[72:73], v[124:125], v[104:105]
	v_pk_fma_f32 v[70:71], v[70:71], v[122:123], v[102:103]
	v_cvt_pk_bf16_f32 v76, v76, v77
	v_cvt_pk_bf16_f32 v77, v106, v107
	global_store_dwordx4 v[78:79], v[74:77], off sc1
	v_pk_fma_f32 v[66:67], v[66:67], v[114:115], v[98:99]
	v_pk_fma_f32 v[68:69], v[68:69], v[116:117], v[100:101]
	v_mul_f32_e32 v74, v71, v71
	v_mul_f32_e32 v75, v73, v73
	v_fmac_f32_e32 v74, v70, v70
	v_fmac_f32_e32 v75, v72, v72
	v_add_f32_e32 v74, v74, v75
	v_mul_f32_e32 v75, v67, v67
	v_fmac_f32_e32 v75, v66, v66
	v_add_f32_e32 v74, v74, v75
	v_mul_f32_e32 v75, v69, v69
	v_fmac_f32_e32 v75, v68, v68
	v_add_f32_e32 v74, v75, v74
	v_add_f32_e32 v80, v108, v74
	ds_bpermute_b32 v81, v213, v80
	global_store_dwordx4 v[148:149], v[70:73], off offset:512 nt
	global_store_dwordx4 v[148:149], v[66:69], off offset:528 nt
	v_pk_mul_f32 v[76:77], v[182:183], v[66:67]
	v_pk_mul_f32 v[70:71], v[184:185], v[70:71]
	v_pk_mul_f32 v[72:73], v[186:187], v[72:73]
	s_waitcnt lgkmcnt(0)
	v_add_f32_e32 v66, v80, v81
	ds_bpermute_b32 v67, v214, v66
	v_pk_mul_f32 v[74:75], v[180:181], v[68:69]
	v_cvt_pk_bf16_f32 v68, v70, v71
	v_cvt_pk_bf16_f32 v69, v72, v73
	v_cvt_pk_bf16_f32 v70, v76, v77
	s_nop 0
	v_cvt_pk_bf16_f32 v71, v74, v75
	global_store_dwordx4 v[78:79], v[68:71], off offset:256 sc1
	s_and_saveexec_b64 s[36:37], s[0:1]
	s_cbranch_execz .LBB0_2033
	s_waitcnt lgkmcnt(0)
	v_add_f32_e32 v68, v66, v67
	v_lshlrev_b64 v[66:67], 7, v[146:147]
	v_lshl_add_u64 v[66:67], s[22:23], 0, v[66:67]
	v_lshl_add_u64 v[66:67], s[34:35], 2, v[66:67]
	s_lshl_b32 s12, s59, 2
	v_lshl_add_u64 v[66:67], v[66:67], 0, s[12:13]
	global_store_dword v[66:67], v68, off
.LBB0_2033:
	s_or_b64 exec, exec, s[36:37]
	v_or_b32_e32 v98, 16, v130
	v_ashrrev_i32_e32 v99, 31, v98
	s_waitcnt lgkmcnt(0)
	v_lshlrev_b64 v[66:67], 13, v[98:99]
	v_lshl_add_u64 v[66:67], s[16:17], 0, v[66:67]
	v_lshl_add_u64 v[100:101], v[178:179], 2, v[66:67]
	global_load_dwordx4 v[74:77], v[100:101], off offset:16 nt
	global_load_dwordx4 v[78:81], v[100:101], off nt
	global_load_dwordx4 v[66:69], v[100:101], off offset:528 nt
	global_load_dwordx4 v[70:73], v[100:101], off offset:512 nt
	s_waitcnt vmcnt(12)
	v_pk_fma_f32 v[64:65], v[64:65], v[128:129], v[96:97]
	v_pk_fma_f32 v[62:63], v[62:63], v[126:127], v[94:95]
	v_pk_fma_f32 v[58:59], v[58:59], v[118:119], v[90:91]
	v_mul_f32_e32 v90, v63, v63
	v_mul_f32_e32 v91, v65, v65
	v_fmac_f32_e32 v90, v62, v62
	v_fmac_f32_e32 v91, v64, v64
	v_add_f32_e32 v90, v90, v91
	v_mul_f32_e32 v91, v59, v59
	v_pk_fma_f32 v[60:61], v[60:61], v[120:121], v[92:93]
	v_fmac_f32_e32 v91, v58, v58
	v_add_f32_e32 v90, v90, v91
	v_mul_f32_e32 v91, v61, v61
	global_store_dwordx4 v[132:133], v[62:65], off nt
	global_store_dwordx4 v[132:133], v[58:61], off offset:16 nt
	v_fmac_f32_e32 v91, v60, v60
	v_pk_mul_f32 v[62:63], v[194:195], v[62:63]
	v_add_f32_e32 v92, v91, v90
	v_pk_mul_f32 v[90:91], v[188:189], v[60:61]
	v_pk_mul_f32 v[60:61], v[190:191], v[58:59]
	v_cvt_pk_bf16_f32 v58, v62, v63
	v_lshlrev_b64 v[62:63], 12, v[130:131]
	v_lshl_add_u64 v[62:63], s[18:19], 0, v[62:63]
	v_pk_mul_f32 v[64:65], v[192:193], v[64:65]
	v_lshl_add_u64 v[62:63], v[178:179], 1, v[62:63]
	v_cvt_pk_bf16_f32 v59, v64, v65
	s_waitcnt vmcnt(12)
	v_pk_fma_f32 v[56:57], v[56:57], v[124:125], v[88:89]
	v_pk_fma_f32 v[54:55], v[54:55], v[122:123], v[86:87]
	v_cvt_pk_bf16_f32 v60, v60, v61
	v_cvt_pk_bf16_f32 v61, v90, v91
	global_store_dwordx4 v[62:63], v[58:61], off sc1
	v_pk_fma_f32 v[50:51], v[50:51], v[114:115], v[82:83]
	v_pk_fma_f32 v[52:53], v[52:53], v[116:117], v[84:85]
	v_mul_f32_e32 v58, v55, v55
	v_mul_f32_e32 v59, v57, v57
	v_fmac_f32_e32 v58, v54, v54
	v_fmac_f32_e32 v59, v56, v56
	v_add_f32_e32 v58, v58, v59
	v_mul_f32_e32 v59, v51, v51
	v_fmac_f32_e32 v59, v50, v50
	v_add_f32_e32 v58, v58, v59
	v_mul_f32_e32 v59, v53, v53
	v_fmac_f32_e32 v59, v52, v52
	v_add_f32_e32 v58, v59, v58
	v_add_f32_e32 v64, v92, v58
	ds_bpermute_b32 v65, v213, v64
	global_store_dwordx4 v[132:133], v[54:57], off offset:512 nt
	global_store_dwordx4 v[132:133], v[50:53], off offset:528 nt
	v_pk_mul_f32 v[60:61], v[182:183], v[50:51]
	v_pk_mul_f32 v[54:55], v[184:185], v[54:55]
	v_pk_mul_f32 v[56:57], v[186:187], v[56:57]
	s_waitcnt lgkmcnt(0)
	v_add_f32_e32 v50, v64, v65
	ds_bpermute_b32 v51, v214, v50
	v_pk_mul_f32 v[58:59], v[180:181], v[52:53]
	v_cvt_pk_bf16_f32 v52, v54, v55
	v_cvt_pk_bf16_f32 v53, v56, v57
	v_cvt_pk_bf16_f32 v54, v60, v61
	s_nop 0
	v_cvt_pk_bf16_f32 v55, v58, v59
	global_store_dwordx4 v[62:63], v[52:55], off offset:256 sc1
	s_and_saveexec_b64 s[36:37], s[0:1]
	s_cbranch_execz .LBB0_2035
	s_waitcnt lgkmcnt(0)
	v_add_f32_e32 v52, v50, v51
	v_lshlrev_b64 v[50:51], 7, v[130:131]
	v_lshl_add_u64 v[50:51], s[22:23], 0, v[50:51]
	v_lshl_add_u64 v[50:51], s[34:35], 2, v[50:51]
	s_lshl_b32 s12, s59, 2
	v_lshl_add_u64 v[50:51], v[50:51], 0, s[12:13]
	global_store_dword v[50:51], v52, off
.LBB0_2035:
	s_or_b64 exec, exec, s[36:37]
	v_or_b32_e32 v82, 32, v130
	v_ashrrev_i32_e32 v83, 31, v82
	s_waitcnt lgkmcnt(0)
	v_lshlrev_b64 v[50:51], 13, v[82:83]
	v_lshl_add_u64 v[50:51], s[16:17], 0, v[50:51]
	v_lshl_add_u64 v[84:85], v[178:179], 2, v[50:51]
	global_load_dwordx4 v[58:61], v[84:85], off offset:16 nt
	global_load_dwordx4 v[62:65], v[84:85], off nt
	global_load_dwordx4 v[50:53], v[84:85], off offset:528 nt
	global_load_dwordx4 v[54:57], v[84:85], off offset:512 nt
	s_waitcnt vmcnt(12)
	v_pk_fma_f32 v[48:49], v[48:49], v[128:129], v[80:81]
	v_pk_fma_f32 v[46:47], v[46:47], v[126:127], v[78:79]
	v_pk_fma_f32 v[42:43], v[42:43], v[118:119], v[74:75]
	v_mul_f32_e32 v74, v47, v47
	v_mul_f32_e32 v75, v49, v49
	v_fmac_f32_e32 v74, v46, v46
	v_fmac_f32_e32 v75, v48, v48
	v_add_f32_e32 v74, v74, v75
	v_mul_f32_e32 v75, v43, v43
	v_pk_fma_f32 v[44:45], v[44:45], v[120:121], v[76:77]
	v_fmac_f32_e32 v75, v42, v42
	v_add_f32_e32 v74, v74, v75
	v_mul_f32_e32 v75, v45, v45
	global_store_dwordx4 v[100:101], v[46:49], off nt
	global_store_dwordx4 v[100:101], v[42:45], off offset:16 nt
	v_fmac_f32_e32 v75, v44, v44
	v_pk_mul_f32 v[46:47], v[194:195], v[46:47]
	v_add_f32_e32 v76, v75, v74
	v_pk_mul_f32 v[74:75], v[188:189], v[44:45]
	v_pk_mul_f32 v[44:45], v[190:191], v[42:43]
	v_cvt_pk_bf16_f32 v42, v46, v47
	v_lshlrev_b64 v[46:47], 12, v[98:99]
	v_lshl_add_u64 v[46:47], s[18:19], 0, v[46:47]
	v_pk_mul_f32 v[48:49], v[192:193], v[48:49]
	v_lshl_add_u64 v[46:47], v[178:179], 1, v[46:47]
	v_cvt_pk_bf16_f32 v43, v48, v49
	s_waitcnt vmcnt(12)
	v_pk_fma_f32 v[40:41], v[40:41], v[124:125], v[72:73]
	v_pk_fma_f32 v[38:39], v[38:39], v[122:123], v[70:71]
	v_cvt_pk_bf16_f32 v44, v44, v45
	v_cvt_pk_bf16_f32 v45, v74, v75
	global_store_dwordx4 v[46:47], v[42:45], off sc1
	v_pk_fma_f32 v[34:35], v[34:35], v[114:115], v[66:67]
	v_pk_fma_f32 v[36:37], v[36:37], v[116:117], v[68:69]
	v_mul_f32_e32 v42, v39, v39
	v_mul_f32_e32 v43, v41, v41
	v_fmac_f32_e32 v42, v38, v38
	v_fmac_f32_e32 v43, v40, v40
	v_add_f32_e32 v42, v42, v43
	v_mul_f32_e32 v43, v35, v35
	v_fmac_f32_e32 v43, v34, v34
	v_add_f32_e32 v42, v42, v43
	v_mul_f32_e32 v43, v37, v37
	v_fmac_f32_e32 v43, v36, v36
	v_add_f32_e32 v42, v43, v42
	v_add_f32_e32 v48, v76, v42
	ds_bpermute_b32 v49, v213, v48
	global_store_dwordx4 v[100:101], v[38:41], off offset:512 nt
	global_store_dwordx4 v[100:101], v[34:37], off offset:528 nt
	v_pk_mul_f32 v[44:45], v[182:183], v[34:35]
	v_pk_mul_f32 v[38:39], v[184:185], v[38:39]
	v_pk_mul_f32 v[40:41], v[186:187], v[40:41]
	s_waitcnt lgkmcnt(0)
	v_add_f32_e32 v34, v48, v49
	ds_bpermute_b32 v35, v214, v34
	v_pk_mul_f32 v[42:43], v[180:181], v[36:37]
	v_cvt_pk_bf16_f32 v36, v38, v39
	v_cvt_pk_bf16_f32 v37, v40, v41
	v_cvt_pk_bf16_f32 v38, v44, v45
	s_nop 0
	v_cvt_pk_bf16_f32 v39, v42, v43
	global_store_dwordx4 v[46:47], v[36:39], off offset:256 sc1
	s_and_saveexec_b64 s[36:37], s[0:1]
	s_cbranch_execz .LBB0_2037
	s_waitcnt lgkmcnt(0)
	v_add_f32_e32 v36, v34, v35
	v_lshlrev_b64 v[34:35], 7, v[98:99]
	v_lshl_add_u64 v[34:35], s[22:23], 0, v[34:35]
	v_lshl_add_u64 v[34:35], s[34:35], 2, v[34:35]
	s_lshl_b32 s12, s59, 2
	v_lshl_add_u64 v[34:35], v[34:35], 0, s[12:13]
	global_store_dword v[34:35], v36, off
.LBB0_2037:
	s_or_b64 exec, exec, s[36:37]
	v_or_b32_e32 v66, 48, v130
	v_ashrrev_i32_e32 v67, 31, v66
	s_waitcnt lgkmcnt(0)
	v_lshlrev_b64 v[34:35], 13, v[66:67]
	v_lshl_add_u64 v[34:35], s[16:17], 0, v[34:35]
	v_lshl_add_u64 v[68:69], v[178:179], 2, v[34:35]
	global_load_dwordx4 v[42:45], v[68:69], off offset:16 nt
	global_load_dwordx4 v[46:49], v[68:69], off nt
	global_load_dwordx4 v[34:37], v[68:69], off offset:528 nt
	global_load_dwordx4 v[38:41], v[68:69], off offset:512 nt
	s_waitcnt vmcnt(12)
	v_pk_fma_f32 v[32:33], v[32:33], v[128:129], v[64:65]
	v_pk_fma_f32 v[30:31], v[30:31], v[126:127], v[62:63]
	v_pk_fma_f32 v[26:27], v[26:27], v[118:119], v[58:59]
	v_mul_f32_e32 v58, v31, v31
	v_mul_f32_e32 v59, v33, v33
	v_fmac_f32_e32 v58, v30, v30
	v_fmac_f32_e32 v59, v32, v32
	v_add_f32_e32 v58, v58, v59
	v_mul_f32_e32 v59, v27, v27
	v_pk_fma_f32 v[28:29], v[28:29], v[120:121], v[60:61]
	v_fmac_f32_e32 v59, v26, v26
	v_add_f32_e32 v58, v58, v59
	v_mul_f32_e32 v59, v29, v29
	global_store_dwordx4 v[84:85], v[30:33], off nt
	global_store_dwordx4 v[84:85], v[26:29], off offset:16 nt
	v_fmac_f32_e32 v59, v28, v28
	v_pk_mul_f32 v[30:31], v[194:195], v[30:31]
	v_add_f32_e32 v60, v59, v58
	v_pk_mul_f32 v[58:59], v[188:189], v[28:29]
	v_pk_mul_f32 v[28:29], v[190:191], v[26:27]
	v_cvt_pk_bf16_f32 v26, v30, v31
	v_lshlrev_b64 v[30:31], 12, v[82:83]
	v_lshl_add_u64 v[30:31], s[18:19], 0, v[30:31]
	v_pk_mul_f32 v[32:33], v[192:193], v[32:33]
	v_lshl_add_u64 v[30:31], v[178:179], 1, v[30:31]
	v_cvt_pk_bf16_f32 v27, v32, v33
	s_waitcnt vmcnt(12)
	v_pk_fma_f32 v[24:25], v[24:25], v[124:125], v[56:57]
	v_pk_fma_f32 v[22:23], v[22:23], v[122:123], v[54:55]
	v_cvt_pk_bf16_f32 v28, v28, v29
	v_cvt_pk_bf16_f32 v29, v58, v59
	global_store_dwordx4 v[30:31], v[26:29], off sc1
	v_pk_fma_f32 v[18:19], v[18:19], v[114:115], v[50:51]
	v_pk_fma_f32 v[20:21], v[20:21], v[116:117], v[52:53]
	v_mul_f32_e32 v26, v23, v23
	v_mul_f32_e32 v27, v25, v25
	v_fmac_f32_e32 v26, v22, v22
	v_fmac_f32_e32 v27, v24, v24
	v_add_f32_e32 v26, v26, v27
	v_mul_f32_e32 v27, v19, v19
	v_fmac_f32_e32 v27, v18, v18
	v_add_f32_e32 v26, v26, v27
	v_mul_f32_e32 v27, v21, v21
	v_fmac_f32_e32 v27, v20, v20
	v_add_f32_e32 v26, v27, v26
	v_add_f32_e32 v32, v60, v26
	ds_bpermute_b32 v33, v213, v32
	global_store_dwordx4 v[84:85], v[22:25], off offset:512 nt
	global_store_dwordx4 v[84:85], v[18:21], off offset:528 nt
	v_pk_mul_f32 v[28:29], v[182:183], v[18:19]
	v_pk_mul_f32 v[22:23], v[184:185], v[22:23]
	v_pk_mul_f32 v[24:25], v[186:187], v[24:25]
	s_waitcnt lgkmcnt(0)
	v_add_f32_e32 v18, v32, v33
	ds_bpermute_b32 v19, v214, v18
	v_pk_mul_f32 v[26:27], v[180:181], v[20:21]
	v_cvt_pk_bf16_f32 v20, v22, v23
	v_cvt_pk_bf16_f32 v21, v24, v25
	v_cvt_pk_bf16_f32 v22, v28, v29
	s_nop 0
	v_cvt_pk_bf16_f32 v23, v26, v27
	global_store_dwordx4 v[30:31], v[20:23], off offset:256 sc1
	s_and_saveexec_b64 s[36:37], s[0:1]
	s_cbranch_execz .LBB0_2039
	s_waitcnt lgkmcnt(0)
	v_add_f32_e32 v20, v18, v19
	v_lshlrev_b64 v[18:19], 7, v[82:83]
	v_lshl_add_u64 v[18:19], s[22:23], 0, v[18:19]
	v_lshl_add_u64 v[18:19], s[34:35], 2, v[18:19]
	s_lshl_b32 s12, s59, 2
	v_lshl_add_u64 v[18:19], v[18:19], 0, s[12:13]
	global_store_dword v[18:19], v20, off
.LBB0_2039:
	s_or_b64 exec, exec, s[36:37]
	s_waitcnt vmcnt(8)
	v_pk_fma_f32 v[16:17], v[16:17], v[128:129], v[48:49]
	v_pk_fma_f32 v[14:15], v[14:15], v[126:127], v[46:47]
	s_waitcnt lgkmcnt(0)
	v_mul_f32_e32 v19, v17, v17
	v_mul_f32_e32 v18, v15, v15
	v_pk_fma_f32 v[10:11], v[10:11], v[118:119], v[42:43]
	v_fmac_f32_e32 v18, v14, v14
	v_fmac_f32_e32 v19, v16, v16
	v_add_f32_e32 v18, v18, v19
	v_mul_f32_e32 v19, v11, v11
	v_pk_fma_f32 v[12:13], v[12:13], v[120:121], v[44:45]
	v_fmac_f32_e32 v19, v10, v10
	v_add_f32_e32 v18, v18, v19
	v_mul_f32_e32 v19, v13, v13
	global_store_dwordx4 v[68:69], v[14:17], off nt
	global_store_dwordx4 v[68:69], v[10:13], off offset:16 nt
	v_fmac_f32_e32 v19, v12, v12
	v_pk_mul_f32 v[14:15], v[194:195], v[14:15]
	v_add_f32_e32 v20, v19, v18
	v_pk_mul_f32 v[18:19], v[188:189], v[12:13]
	v_pk_mul_f32 v[12:13], v[190:191], v[10:11]
	v_cvt_pk_bf16_f32 v10, v14, v15
	v_lshlrev_b64 v[14:15], 12, v[66:67]
	v_lshl_add_u64 v[14:15], s[18:19], 0, v[14:15]
	v_pk_mul_f32 v[16:17], v[192:193], v[16:17]
	v_lshl_add_u64 v[14:15], v[178:179], 1, v[14:15]
	v_cvt_pk_bf16_f32 v11, v16, v17
	s_waitcnt vmcnt(8)
	v_pk_fma_f32 v[8:9], v[8:9], v[124:125], v[40:41]
	v_pk_fma_f32 v[6:7], v[6:7], v[122:123], v[38:39]
	v_cvt_pk_bf16_f32 v12, v12, v13
	v_cvt_pk_bf16_f32 v13, v18, v19
	global_store_dwordx4 v[14:15], v[10:13], off sc1
	v_pk_fma_f32 v[2:3], v[2:3], v[114:115], v[34:35]
	v_pk_fma_f32 v[4:5], v[4:5], v[116:117], v[36:37]
	v_mul_f32_e32 v10, v7, v7
	v_mul_f32_e32 v11, v9, v9
	v_fmac_f32_e32 v10, v6, v6
	v_fmac_f32_e32 v11, v8, v8
	v_add_f32_e32 v10, v10, v11
	v_mul_f32_e32 v11, v3, v3
	v_fmac_f32_e32 v11, v2, v2
	v_add_f32_e32 v10, v10, v11
	v_mul_f32_e32 v11, v5, v5
	v_fmac_f32_e32 v11, v4, v4
	v_add_f32_e32 v10, v11, v10
	v_add_f32_e32 v16, v20, v10
	ds_bpermute_b32 v17, v213, v16
	global_store_dwordx4 v[68:69], v[6:9], off offset:512 nt
	global_store_dwordx4 v[68:69], v[2:5], off offset:528 nt
	v_pk_mul_f32 v[12:13], v[182:183], v[2:3]
	v_pk_mul_f32 v[6:7], v[184:185], v[6:7]
	v_pk_mul_f32 v[8:9], v[186:187], v[8:9]
	s_waitcnt lgkmcnt(0)
	v_add_f32_e32 v2, v16, v17
	ds_bpermute_b32 v3, v214, v2
	v_pk_mul_f32 v[10:11], v[180:181], v[4:5]
	v_cvt_pk_bf16_f32 v4, v6, v7
	v_cvt_pk_bf16_f32 v5, v8, v9
	v_cvt_pk_bf16_f32 v6, v12, v13
	s_nop 0
	v_cvt_pk_bf16_f32 v7, v10, v11
	global_store_dwordx4 v[14:15], v[4:7], off offset:256 sc1
	s_and_saveexec_b64 s[36:37], s[0:1]
	s_cbranch_execz .LBB0_2041
	s_waitcnt lgkmcnt(0)
	v_add_f32_e32 v4, v2, v3
	v_lshlrev_b64 v[2:3], 7, v[66:67]
	v_lshl_add_u64 v[2:3], s[22:23], 0, v[2:3]
	v_lshl_add_u64 v[2:3], s[34:35], 2, v[2:3]
	s_lshl_b32 s12, s59, 2
	v_lshl_add_u64 v[2:3], v[2:3], 0, s[12:13]
	global_store_dword v[2:3], v4, off

.LBB0_2123:
	s_cmp_gt_i32 s54, 3
	v_or_b32_e32 v168, s2, v156
	s_cselect_b64 s[2:3], -1, 0
	s_cmp_gt_u32 s54, 7
	s_cselect_b64 s[6:7], -1, 0
	s_cmp_gt_u32 s54, 15
	s_cselect_b64 s[50:51], -1, 0
	s_cmp_lt_u32 s54, 24
	s_cselect_b64 s[46:47], -1, 0
	s_cmp_gt_u32 s54, 23
	s_cselect_b64 s[54:55], -1, 0
	v_lshlrev_b64 v[174:175], 12, v[170:171]
	v_lshlrev_b64 v[172:173], 11, v[170:171]
	s_waitcnt vmcnt(0) lgkmcnt(0)
	v_pk_fma_f32 v[144:145], v[144:145], v[176:177], v[56:57] op_sel_hi:[1,0,1]
	v_pk_fma_f32 v[142:143], v[142:143], v[176:177], v[54:55] op_sel_hi:[1,0,1]
	v_pk_fma_f32 v[140:141], v[140:141], v[176:177], v[52:53] op_sel_hi:[1,0,1]
	v_pk_fma_f32 v[138:139], v[138:139], v[176:177], v[50:51] op_sel_hi:[1,0,1]
	s_mov_b64 s[4:5], -1
	s_and_b64 vcc, exec, s[2:3]
	s_cbranch_vccz .LBB0_2139
	s_and_b64 vcc, exec, s[6:7]
	s_cbranch_vccz .LBB0_2136
	s_and_b64 vcc, exec, s[50:51]
	s_cbranch_vccz .LBB0_2133
	s_and_b64 vcc, exec, s[54:55]
	s_cbranch_vccz .LBB0_2130
	s_andn2_b64 vcc, exec, s[36:37]
	s_cbranch_vccnz .LBB0_2129
	v_lshl_add_u64 v[178:179], v[158:159], 0, v[178:179]
	global_store_dwordx4 v[178:179], v[142:145], off sc1
	global_store_dwordx4 v[178:179], v[138:141], off offset:16 sc1

.LBB0_2130:
	s_andn2_b64 vcc, exec, s[4:5]
	s_cbranch_vccnz .LBB0_2132
	v_lshl_add_u64 v[178:179], s[26:27], 0, v[174:175]
	v_mov_b32_e32 v169, v155
	v_lshl_add_u64 v[178:179], v[168:169], 1, v[178:179]
	v_add_co_u32_e32 v178, vcc, 0xffffe000, v178
	v_cvt_pk_bf16_f32 v192, v142, v143
	v_cvt_pk_bf16_f32 v193, v144, v145
	v_cvt_pk_bf16_f32 v194, v138, v139
	v_cvt_pk_bf16_f32 v195, v140, v141
	s_nop 1
	v_addc_co_u32_e32 v179, vcc, -1, v179, vcc
	global_store_dwordx4 v[178:179], v[192:195], off sc1

.LBB0_2133:
	s_andn2_b64 vcc, exec, s[4:5]
	s_cbranch_vccnz .LBB0_2135
	v_lshl_add_u64 v[178:179], s[24:25], 0, v[174:175]
	v_mov_b32_e32 v169, v155
	v_lshl_add_u64 v[178:179], v[168:169], 1, v[178:179]
	v_cvt_pk_bf16_f32 v192, v142, v143
	v_cvt_pk_bf16_f32 v193, v144, v145
	v_cvt_pk_bf16_f32 v194, v138, v139
	v_cvt_pk_bf16_f32 v195, v140, v141
	global_store_dwordx4 v[178:179], v[192:195], off offset:-4096 sc1

.LBB0_2136:
	s_andn2_b64 vcc, exec, s[4:5]
	s_cbranch_vccnz .LBB0_2138
	v_lshl_add_u64 v[178:179], s[22:23], 0, v[172:173]
	v_mov_b32_e32 v169, v155
	v_lshl_add_u64 v[178:179], v[168:169], 1, v[178:179]
	v_cvt_pk_bf16_f32 v192, v142, v143
	v_cvt_pk_bf16_f32 v193, v144, v145
	v_cvt_pk_bf16_f32 v194, v138, v139
	v_cvt_pk_bf16_f32 v195, v140, v141
	global_store_dwordx4 v[178:179], v[192:195], off offset:-2048 sc1

.LBB0_2139:
	s_andn2_b64 vcc, exec, s[4:5]
	v_lshl_add_u64 v[178:179], s[20:21], 0, v[172:173]
	v_ashrrev_i32_e32 v169, 31, v168
	s_cbranch_vccnz .LBB0_2141
	v_pk_mul_f32 v[142:143], v[142:143], s[38:39] op_sel_hi:[1,0]
	v_pk_mul_f32 v[192:193], v[140:141], s[38:39] op_sel_hi:[1,0]
	v_pk_mul_f32 v[140:141], v[138:139], s[38:39] op_sel_hi:[1,0]
	v_cvt_pk_bf16_f32 v138, v142, v143
	v_lshl_add_u64 v[142:143], v[168:169], 1, v[178:179]
	v_pk_mul_f32 v[144:145], v[144:145], s[38:39] op_sel_hi:[1,0]
	s_nop 0
	v_cvt_pk_bf16_f32 v139, v144, v145
	v_cvt_pk_bf16_f32 v140, v140, v141
	v_cvt_pk_bf16_f32 v141, v192, v193
	global_store_dwordx4 v[142:143], v[138:141], off sc1
.LBB0_2141:
	s_nop 1
	v_mov_b32_e32 v138, v176
	v_mov_b32_e32 v139, v176
	v_pk_fma_f32 v[136:137], v[136:137], v[138:139], v[40:41]
	v_pk_fma_f32 v[132:133], v[132:133], v[138:139], v[36:37]
	v_cndmask_b32_e64 v138, 0, 1, s[2:3]
	v_mov_b32_e32 v177, v176
	v_cmp_ne_u32_e64 s[4:5], 1, v138
	v_cndmask_b32_e64 v138, 0, 1, s[6:7]
	v_pk_fma_f32 v[134:135], v[134:135], v[176:177], v[38:39]
	v_pk_fma_f32 v[130:131], v[130:131], v[176:177], v[34:35]
	s_mov_b64 s[58:59], -1
	s_andn2_b64 vcc, exec, s[2:3]
	v_cmp_ne_u32_e64 s[2:3], 1, v138
	s_cbranch_vccnz .LBB0_2153
	s_and_b64 vcc, exec, s[2:3]
	s_mov_b64 s[6:7], -1
	s_cbranch_vccnz .LBB0_2150
	s_andn2_b64 vcc, exec, s[50:51]
	s_cbranch_vccnz .LBB0_2147
	s_andn2_b64 vcc, exec, s[46:47]
	s_cbranch_vccnz .LBB0_2146
	v_lshl_add_u64 v[142:143], s[26:27], 0, v[174:175]
	v_mov_b32_e32 v154, v168
	v_lshl_add_u64 v[142:143], v[154:155], 1, v[142:143]
	v_add_co_u32_e32 v142, vcc, 0xfffff000, v142
	v_cvt_pk_bf16_f32 v138, v134, v135
	v_cvt_pk_bf16_f32 v139, v136, v137
	v_cvt_pk_bf16_f32 v140, v130, v131
	v_cvt_pk_bf16_f32 v141, v132, v133
	s_nop 1
	v_addc_co_u32_e32 v143, vcc, -1, v143, vcc
	global_store_dwordx4 v[142:143], v[138:141], off offset:-3840 sc1

.LBB0_2147:
	s_andn2_b64 vcc, exec, s[6:7]
	s_cbranch_vccnz .LBB0_2149
	v_lshl_add_u64 v[142:143], s[24:25], 0, v[174:175]
	v_mov_b32_e32 v154, v168
	v_lshl_add_u64 v[142:143], v[154:155], 1, v[142:143]
	v_cvt_pk_bf16_f32 v138, v134, v135
	v_cvt_pk_bf16_f32 v139, v136, v137
	v_cvt_pk_bf16_f32 v140, v130, v131
	v_cvt_pk_bf16_f32 v141, v132, v133
	global_store_dwordx4 v[142:143], v[138:141], off offset:-3840 sc1

.LBB0_2150:
	s_andn2_b64 vcc, exec, s[6:7]
	s_cbranch_vccnz .LBB0_2152
	v_lshl_add_u64 v[142:143], s[22:23], 0, v[172:173]
	v_mov_b32_e32 v154, v168
	v_lshl_add_u64 v[142:143], v[154:155], 1, v[142:143]
	v_cvt_pk_bf16_f32 v138, v134, v135
	v_cvt_pk_bf16_f32 v139, v136, v137
	v_cvt_pk_bf16_f32 v140, v130, v131
	v_cvt_pk_bf16_f32 v141, v132, v133
	global_store_dwordx4 v[142:143], v[138:141], off offset:-1792 sc1

.LBB0_2153:
	s_andn2_b64 vcc, exec, s[58:59]
	s_cbranch_vccnz .LBB0_2155
	v_pk_mul_f32 v[134:135], v[134:135], s[38:39] op_sel_hi:[1,0]
	v_pk_mul_f32 v[138:139], v[132:133], s[38:39] op_sel_hi:[1,0]
	v_pk_mul_f32 v[132:133], v[130:131], s[38:39] op_sel_hi:[1,0]
	v_cvt_pk_bf16_f32 v130, v134, v135
	v_lshl_add_u64 v[134:135], v[168:169], 1, v[178:179]
	v_pk_mul_f32 v[136:137], v[136:137], s[38:39] op_sel_hi:[1,0]
	s_nop 0
	v_cvt_pk_bf16_f32 v131, v136, v137
	v_cvt_pk_bf16_f32 v132, v132, v133
	v_cvt_pk_bf16_f32 v133, v138, v139
	global_store_dwordx4 v[134:135], v[130:133], off offset:256 sc1

.LBB0_2159:
	v_lshlrev_b64 v[132:133], 12, v[130:131]
	v_lshlrev_b64 v[130:131], 11, v[130:131]
	s_waitcnt lgkmcnt(0)
	v_pk_fma_f32 v[128:129], v[128:129], v[134:135], v[56:57] op_sel_hi:[1,0,1]
	v_pk_fma_f32 v[126:127], v[126:127], v[134:135], v[54:55] op_sel_hi:[1,0,1]
	v_pk_fma_f32 v[124:125], v[124:125], v[134:135], v[52:53] op_sel_hi:[1,0,1]
	v_pk_fma_f32 v[122:123], v[122:123], v[134:135], v[50:51] op_sel_hi:[1,0,1]
	s_and_b64 vcc, exec, s[4:5]
	s_mov_b64 s[56:57], -1
	s_cbranch_vccnz .LBB0_2175
	s_and_b64 vcc, exec, s[2:3]
	s_cbranch_vccnz .LBB0_2172
	s_andn2_b64 vcc, exec, s[50:51]
	s_cbranch_vccnz .LBB0_2169
	s_andn2_b64 vcc, exec, s[54:55]
	s_cbranch_vccnz .LBB0_2166
	s_andn2_b64 vcc, exec, s[36:37]
	s_cbranch_vccnz .LBB0_2165
	v_lshl_add_u64 v[136:137], v[158:159], 0, v[136:137]
	global_store_dwordx4 v[136:137], v[126:129], off sc1
	global_store_dwordx4 v[136:137], v[122:125], off offset:16 sc1

.LBB0_2166:
	s_andn2_b64 vcc, exec, s[56:57]
	s_cbranch_vccnz .LBB0_2168
	v_lshl_add_u64 v[140:141], s[26:27], 0, v[132:133]
	v_mov_b32_e32 v154, v168
	v_lshl_add_u64 v[140:141], v[154:155], 1, v[140:141]
	v_add_co_u32_e32 v140, vcc, 0xffffe000, v140
	v_cvt_pk_bf16_f32 v136, v126, v127
	v_cvt_pk_bf16_f32 v137, v128, v129
	v_cvt_pk_bf16_f32 v138, v122, v123
	v_cvt_pk_bf16_f32 v139, v124, v125
	s_nop 1
	v_addc_co_u32_e32 v141, vcc, -1, v141, vcc
	global_store_dwordx4 v[140:141], v[136:139], off sc1

.LBB0_2169:
	s_andn2_b64 vcc, exec, s[56:57]
	s_cbranch_vccnz .LBB0_2171
	v_lshl_add_u64 v[140:141], s[24:25], 0, v[132:133]
	v_mov_b32_e32 v154, v168
	v_lshl_add_u64 v[140:141], v[154:155], 1, v[140:141]
	v_cvt_pk_bf16_f32 v136, v126, v127
	v_cvt_pk_bf16_f32 v137, v128, v129
	v_cvt_pk_bf16_f32 v138, v122, v123
	v_cvt_pk_bf16_f32 v139, v124, v125
	global_store_dwordx4 v[140:141], v[136:139], off offset:-4096 sc1

.LBB0_2172:
	s_andn2_b64 vcc, exec, s[56:57]
	s_cbranch_vccnz .LBB0_2174
	v_lshl_add_u64 v[140:141], s[22:23], 0, v[130:131]
	v_mov_b32_e32 v154, v168
	v_lshl_add_u64 v[140:141], v[154:155], 1, v[140:141]
	v_cvt_pk_bf16_f32 v136, v126, v127
	v_cvt_pk_bf16_f32 v137, v128, v129
	v_cvt_pk_bf16_f32 v138, v122, v123
	v_cvt_pk_bf16_f32 v139, v124, v125
	global_store_dwordx4 v[140:141], v[136:139], off offset:-2048 sc1

.LBB0_2175:
	s_andn2_b64 vcc, exec, s[56:57]
	v_lshl_add_u64 v[136:137], s[20:21], 0, v[130:131]
	s_cbranch_vccnz .LBB0_2177
	v_pk_mul_f32 v[126:127], v[126:127], s[38:39] op_sel_hi:[1,0]
	v_pk_mul_f32 v[138:139], v[124:125], s[38:39] op_sel_hi:[1,0]
	v_pk_mul_f32 v[124:125], v[122:123], s[38:39] op_sel_hi:[1,0]
	v_cvt_pk_bf16_f32 v122, v126, v127
	v_lshl_add_u64 v[126:127], v[168:169], 1, v[136:137]
	v_pk_mul_f32 v[128:129], v[128:129], s[38:39] op_sel_hi:[1,0]
	s_nop 0
	v_cvt_pk_bf16_f32 v123, v128, v129
	v_cvt_pk_bf16_f32 v124, v124, v125
	v_cvt_pk_bf16_f32 v125, v138, v139
	global_store_dwordx4 v[126:127], v[122:125], off sc1
.LBB0_2177:
	v_mov_b32_e32 v135, v134
	s_nop 0
	v_mov_b32_e32 v122, v134
	v_mov_b32_e32 v123, v134
	v_pk_fma_f32 v[120:121], v[120:121], v[122:123], v[40:41]
	v_pk_fma_f32 v[118:119], v[118:119], v[134:135], v[38:39]
	v_pk_fma_f32 v[116:117], v[116:117], v[122:123], v[36:37]
	v_pk_fma_f32 v[114:115], v[114:115], v[134:135], v[34:35]
	s_and_b64 vcc, exec, s[4:5]
	s_mov_b64 s[56:57], -1
	s_cbranch_vccnz .LBB0_2189
	s_and_b64 vcc, exec, s[2:3]
	s_cbranch_vccnz .LBB0_2186
	s_andn2_b64 vcc, exec, s[50:51]
	s_cbranch_vccnz .LBB0_2183
	s_andn2_b64 vcc, exec, s[46:47]
	s_cbranch_vccnz .LBB0_2182
	v_lshl_add_u64 v[126:127], s[26:27], 0, v[132:133]
	v_mov_b32_e32 v154, v168
	v_lshl_add_u64 v[126:127], v[154:155], 1, v[126:127]
	v_add_co_u32_e32 v126, vcc, 0xfffff000, v126
	v_cvt_pk_bf16_f32 v122, v118, v119
	v_cvt_pk_bf16_f32 v123, v120, v121
	v_cvt_pk_bf16_f32 v124, v114, v115
	v_cvt_pk_bf16_f32 v125, v116, v117
	s_nop 1
	v_addc_co_u32_e32 v127, vcc, -1, v127, vcc
	global_store_dwordx4 v[126:127], v[122:125], off offset:-3840 sc1

.LBB0_2183:
	s_andn2_b64 vcc, exec, s[56:57]
	s_cbranch_vccnz .LBB0_2185
	v_lshl_add_u64 v[126:127], s[24:25], 0, v[132:133]
	v_mov_b32_e32 v154, v168
	v_lshl_add_u64 v[126:127], v[154:155], 1, v[126:127]
	v_cvt_pk_bf16_f32 v122, v118, v119
	v_cvt_pk_bf16_f32 v123, v120, v121
	v_cvt_pk_bf16_f32 v124, v114, v115
	v_cvt_pk_bf16_f32 v125, v116, v117
	global_store_dwordx4 v[126:127], v[122:125], off offset:-3840 sc1

.LBB0_2186:
	s_andn2_b64 vcc, exec, s[56:57]
	s_cbranch_vccnz .LBB0_2188
	v_lshl_add_u64 v[126:127], s[22:23], 0, v[130:131]
	v_mov_b32_e32 v154, v168
	v_lshl_add_u64 v[126:127], v[154:155], 1, v[126:127]
	v_cvt_pk_bf16_f32 v122, v118, v119
	v_cvt_pk_bf16_f32 v123, v120, v121
	v_cvt_pk_bf16_f32 v124, v114, v115
	v_cvt_pk_bf16_f32 v125, v116, v117
	global_store_dwordx4 v[126:127], v[122:125], off offset:-1792 sc1

.LBB0_2189:
	s_andn2_b64 vcc, exec, s[56:57]
	s_cbranch_vccnz .LBB0_2191
	v_pk_mul_f32 v[118:119], v[118:119], s[38:39] op_sel_hi:[1,0]
	v_pk_mul_f32 v[122:123], v[116:117], s[38:39] op_sel_hi:[1,0]
	v_pk_mul_f32 v[116:117], v[114:115], s[38:39] op_sel_hi:[1,0]
	v_cvt_pk_bf16_f32 v114, v118, v119
	v_lshl_add_u64 v[118:119], v[168:169], 1, v[136:137]
	v_pk_mul_f32 v[120:121], v[120:121], s[38:39] op_sel_hi:[1,0]
	s_nop 0
	v_cvt_pk_bf16_f32 v115, v120, v121
	v_cvt_pk_bf16_f32 v116, v116, v117
	v_cvt_pk_bf16_f32 v117, v122, v123
	global_store_dwordx4 v[118:119], v[114:117], off offset:256 sc1

.LBB0_2195:
	v_lshlrev_b64 v[116:117], 12, v[114:115]
	v_lshlrev_b64 v[114:115], 11, v[114:115]
	s_waitcnt lgkmcnt(0)
	v_pk_fma_f32 v[112:113], v[112:113], v[118:119], v[56:57] op_sel_hi:[1,0,1]
	v_pk_fma_f32 v[110:111], v[110:111], v[118:119], v[54:55] op_sel_hi:[1,0,1]
	v_pk_fma_f32 v[108:109], v[108:109], v[118:119], v[52:53] op_sel_hi:[1,0,1]
	v_pk_fma_f32 v[106:107], v[106:107], v[118:119], v[50:51] op_sel_hi:[1,0,1]
	s_and_b64 vcc, exec, s[4:5]
	s_mov_b64 s[56:57], -1
	s_cbranch_vccnz .LBB0_2211
	s_and_b64 vcc, exec, s[2:3]
	s_cbranch_vccnz .LBB0_2208
	s_andn2_b64 vcc, exec, s[50:51]
	s_cbranch_vccnz .LBB0_2205
	s_andn2_b64 vcc, exec, s[54:55]
	s_cbranch_vccnz .LBB0_2202
	s_andn2_b64 vcc, exec, s[36:37]
	s_cbranch_vccnz .LBB0_2201
	v_lshl_add_u64 v[120:121], v[158:159], 0, v[120:121]
	global_store_dwordx4 v[120:121], v[110:113], off sc1
	global_store_dwordx4 v[120:121], v[106:109], off offset:16 sc1

.LBB0_2202:
	s_andn2_b64 vcc, exec, s[56:57]
	s_cbranch_vccnz .LBB0_2204
	v_lshl_add_u64 v[124:125], s[26:27], 0, v[116:117]
	v_mov_b32_e32 v154, v168
	v_lshl_add_u64 v[124:125], v[154:155], 1, v[124:125]
	v_add_co_u32_e32 v124, vcc, 0xffffe000, v124
	v_cvt_pk_bf16_f32 v120, v110, v111
	v_cvt_pk_bf16_f32 v121, v112, v113
	v_cvt_pk_bf16_f32 v122, v106, v107
	v_cvt_pk_bf16_f32 v123, v108, v109
	s_nop 1
	v_addc_co_u32_e32 v125, vcc, -1, v125, vcc
	global_store_dwordx4 v[124:125], v[120:123], off sc1

.LBB0_2205:
	s_andn2_b64 vcc, exec, s[56:57]
	s_cbranch_vccnz .LBB0_2207
	v_lshl_add_u64 v[124:125], s[24:25], 0, v[116:117]
	v_mov_b32_e32 v154, v168
	v_lshl_add_u64 v[124:125], v[154:155], 1, v[124:125]
	v_cvt_pk_bf16_f32 v120, v110, v111
	v_cvt_pk_bf16_f32 v121, v112, v113
	v_cvt_pk_bf16_f32 v122, v106, v107
	v_cvt_pk_bf16_f32 v123, v108, v109
	global_store_dwordx4 v[124:125], v[120:123], off offset:-4096 sc1

.LBB0_2208:
	s_andn2_b64 vcc, exec, s[56:57]
	s_cbranch_vccnz .LBB0_2210
	v_lshl_add_u64 v[124:125], s[22:23], 0, v[114:115]
	v_mov_b32_e32 v154, v168
	v_lshl_add_u64 v[124:125], v[154:155], 1, v[124:125]
	v_cvt_pk_bf16_f32 v120, v110, v111
	v_cvt_pk_bf16_f32 v121, v112, v113
	v_cvt_pk_bf16_f32 v122, v106, v107
	v_cvt_pk_bf16_f32 v123, v108, v109
	global_store_dwordx4 v[124:125], v[120:123], off offset:-2048 sc1

.LBB0_2211:
	s_andn2_b64 vcc, exec, s[56:57]
	v_lshl_add_u64 v[120:121], s[20:21], 0, v[114:115]
	s_cbranch_vccnz .LBB0_2213
	v_pk_mul_f32 v[110:111], v[110:111], s[38:39] op_sel_hi:[1,0]
	v_pk_mul_f32 v[122:123], v[108:109], s[38:39] op_sel_hi:[1,0]
	v_pk_mul_f32 v[108:109], v[106:107], s[38:39] op_sel_hi:[1,0]
	v_cvt_pk_bf16_f32 v106, v110, v111
	v_lshl_add_u64 v[110:111], v[168:169], 1, v[120:121]
	v_pk_mul_f32 v[112:113], v[112:113], s[38:39] op_sel_hi:[1,0]
	s_nop 0
	v_cvt_pk_bf16_f32 v107, v112, v113
	v_cvt_pk_bf16_f32 v108, v108, v109
	v_cvt_pk_bf16_f32 v109, v122, v123
	global_store_dwordx4 v[110:111], v[106:109], off sc1
.LBB0_2213:
	v_mov_b32_e32 v119, v118
	s_nop 0
	v_mov_b32_e32 v106, v118
	v_mov_b32_e32 v107, v118
	v_pk_fma_f32 v[104:105], v[104:105], v[106:107], v[40:41]
	v_pk_fma_f32 v[102:103], v[102:103], v[118:119], v[38:39]
	v_pk_fma_f32 v[100:101], v[100:101], v[106:107], v[36:37]
	v_pk_fma_f32 v[98:99], v[98:99], v[118:119], v[34:35]
	s_and_b64 vcc, exec, s[4:5]
	s_mov_b64 s[56:57], -1
	s_cbranch_vccnz .LBB0_2225
	s_and_b64 vcc, exec, s[2:3]
	s_cbranch_vccnz .LBB0_2222
	s_andn2_b64 vcc, exec, s[50:51]
	s_cbranch_vccnz .LBB0_2219
	s_andn2_b64 vcc, exec, s[46:47]
	s_cbranch_vccnz .LBB0_2218
	v_lshl_add_u64 v[110:111], s[26:27], 0, v[116:117]
	v_mov_b32_e32 v154, v168
	v_lshl_add_u64 v[110:111], v[154:155], 1, v[110:111]
	v_add_co_u32_e32 v110, vcc, 0xfffff000, v110
	v_cvt_pk_bf16_f32 v106, v102, v103
	v_cvt_pk_bf16_f32 v107, v104, v105
	v_cvt_pk_bf16_f32 v108, v98, v99
	v_cvt_pk_bf16_f32 v109, v100, v101
	s_nop 1
	v_addc_co_u32_e32 v111, vcc, -1, v111, vcc
	global_store_dwordx4 v[110:111], v[106:109], off offset:-3840 sc1

.LBB0_2219:
	s_andn2_b64 vcc, exec, s[56:57]
	s_cbranch_vccnz .LBB0_2221
	v_lshl_add_u64 v[110:111], s[24:25], 0, v[116:117]
	v_mov_b32_e32 v154, v168
	v_lshl_add_u64 v[110:111], v[154:155], 1, v[110:111]
	v_cvt_pk_bf16_f32 v106, v102, v103
	v_cvt_pk_bf16_f32 v107, v104, v105
	v_cvt_pk_bf16_f32 v108, v98, v99
	v_cvt_pk_bf16_f32 v109, v100, v101
	global_store_dwordx4 v[110:111], v[106:109], off offset:-3840 sc1

.LBB0_2222:
	s_andn2_b64 vcc, exec, s[56:57]
	s_cbranch_vccnz .LBB0_2224
	v_lshl_add_u64 v[110:111], s[22:23], 0, v[114:115]
	v_mov_b32_e32 v154, v168
	v_lshl_add_u64 v[110:111], v[154:155], 1, v[110:111]
	v_cvt_pk_bf16_f32 v106, v102, v103
	v_cvt_pk_bf16_f32 v107, v104, v105
	v_cvt_pk_bf16_f32 v108, v98, v99
	v_cvt_pk_bf16_f32 v109, v100, v101
	global_store_dwordx4 v[110:111], v[106:109], off offset:-1792 sc1

.LBB0_2225:
	s_andn2_b64 vcc, exec, s[56:57]
	s_cbranch_vccnz .LBB0_2227
	v_pk_mul_f32 v[102:103], v[102:103], s[38:39] op_sel_hi:[1,0]
	v_pk_mul_f32 v[106:107], v[100:101], s[38:39] op_sel_hi:[1,0]
	v_pk_mul_f32 v[100:101], v[98:99], s[38:39] op_sel_hi:[1,0]
	v_cvt_pk_bf16_f32 v98, v102, v103
	v_lshl_add_u64 v[102:103], v[168:169], 1, v[120:121]
	v_pk_mul_f32 v[104:105], v[104:105], s[38:39] op_sel_hi:[1,0]
	s_nop 0
	v_cvt_pk_bf16_f32 v99, v104, v105
	v_cvt_pk_bf16_f32 v100, v100, v101
	v_cvt_pk_bf16_f32 v101, v106, v107
	global_store_dwordx4 v[102:103], v[98:101], off offset:256 sc1

.LBB0_2231:
	v_lshlrev_b64 v[100:101], 12, v[98:99]
	v_lshlrev_b64 v[98:99], 11, v[98:99]
	s_waitcnt lgkmcnt(0)
	v_pk_fma_f32 v[96:97], v[96:97], v[102:103], v[56:57] op_sel_hi:[1,0,1]
	v_pk_fma_f32 v[94:95], v[94:95], v[102:103], v[54:55] op_sel_hi:[1,0,1]
	v_pk_fma_f32 v[92:93], v[92:93], v[102:103], v[52:53] op_sel_hi:[1,0,1]
	v_pk_fma_f32 v[90:91], v[90:91], v[102:103], v[50:51] op_sel_hi:[1,0,1]
	s_and_b64 vcc, exec, s[4:5]
	s_mov_b64 s[56:57], -1
	s_cbranch_vccnz .LBB0_2247
	s_and_b64 vcc, exec, s[2:3]
	s_cbranch_vccnz .LBB0_2244
	s_andn2_b64 vcc, exec, s[50:51]
	s_cbranch_vccnz .LBB0_2241
	s_andn2_b64 vcc, exec, s[54:55]
	s_cbranch_vccnz .LBB0_2238
	s_andn2_b64 vcc, exec, s[36:37]
	s_cbranch_vccnz .LBB0_2237
	v_lshl_add_u64 v[104:105], v[158:159], 0, v[104:105]
	global_store_dwordx4 v[104:105], v[94:97], off sc1
	global_store_dwordx4 v[104:105], v[90:93], off offset:16 sc1

.LBB0_2238:
	s_andn2_b64 vcc, exec, s[56:57]
	s_cbranch_vccnz .LBB0_2240
	v_lshl_add_u64 v[108:109], s[26:27], 0, v[100:101]
	v_mov_b32_e32 v154, v168
	v_lshl_add_u64 v[108:109], v[154:155], 1, v[108:109]
	v_add_co_u32_e32 v108, vcc, 0xffffe000, v108
	v_cvt_pk_bf16_f32 v104, v94, v95
	v_cvt_pk_bf16_f32 v105, v96, v97
	v_cvt_pk_bf16_f32 v106, v90, v91
	v_cvt_pk_bf16_f32 v107, v92, v93
	s_nop 1
	v_addc_co_u32_e32 v109, vcc, -1, v109, vcc
	global_store_dwordx4 v[108:109], v[104:107], off sc1

.LBB0_2241:
	s_andn2_b64 vcc, exec, s[56:57]
	s_cbranch_vccnz .LBB0_2243
	v_lshl_add_u64 v[108:109], s[24:25], 0, v[100:101]
	v_mov_b32_e32 v154, v168
	v_lshl_add_u64 v[108:109], v[154:155], 1, v[108:109]
	v_cvt_pk_bf16_f32 v104, v94, v95
	v_cvt_pk_bf16_f32 v105, v96, v97
	v_cvt_pk_bf16_f32 v106, v90, v91
	v_cvt_pk_bf16_f32 v107, v92, v93
	global_store_dwordx4 v[108:109], v[104:107], off offset:-4096 sc1

.LBB0_2244:
	s_andn2_b64 vcc, exec, s[56:57]
	s_cbranch_vccnz .LBB0_2246
	v_lshl_add_u64 v[108:109], s[22:23], 0, v[98:99]
	v_mov_b32_e32 v154, v168
	v_lshl_add_u64 v[108:109], v[154:155], 1, v[108:109]
	v_cvt_pk_bf16_f32 v104, v94, v95
	v_cvt_pk_bf16_f32 v105, v96, v97
	v_cvt_pk_bf16_f32 v106, v90, v91
	v_cvt_pk_bf16_f32 v107, v92, v93
	global_store_dwordx4 v[108:109], v[104:107], off offset:-2048 sc1

.LBB0_2247:
	s_andn2_b64 vcc, exec, s[56:57]
	v_lshl_add_u64 v[104:105], s[20:21], 0, v[98:99]
	s_cbranch_vccnz .LBB0_2249
	v_pk_mul_f32 v[94:95], v[94:95], s[38:39] op_sel_hi:[1,0]
	v_pk_mul_f32 v[106:107], v[92:93], s[38:39] op_sel_hi:[1,0]
	v_pk_mul_f32 v[92:93], v[90:91], s[38:39] op_sel_hi:[1,0]
	v_cvt_pk_bf16_f32 v90, v94, v95
	v_lshl_add_u64 v[94:95], v[168:169], 1, v[104:105]
	v_pk_mul_f32 v[96:97], v[96:97], s[38:39] op_sel_hi:[1,0]
	s_nop 0
	v_cvt_pk_bf16_f32 v91, v96, v97
	v_cvt_pk_bf16_f32 v92, v92, v93
	v_cvt_pk_bf16_f32 v93, v106, v107
	global_store_dwordx4 v[94:95], v[90:93], off sc1
.LBB0_2249:
	v_mov_b32_e32 v103, v102
	s_nop 0
	v_mov_b32_e32 v90, v102
	v_mov_b32_e32 v91, v102
	v_pk_fma_f32 v[88:89], v[88:89], v[90:91], v[40:41]
	v_pk_fma_f32 v[86:87], v[86:87], v[102:103], v[38:39]
	v_pk_fma_f32 v[84:85], v[84:85], v[90:91], v[36:37]
	v_pk_fma_f32 v[82:83], v[82:83], v[102:103], v[34:35]
	s_and_b64 vcc, exec, s[4:5]
	s_mov_b64 s[56:57], -1
	s_cbranch_vccnz .LBB0_2261
	s_and_b64 vcc, exec, s[2:3]
	s_cbranch_vccnz .LBB0_2258
	s_andn2_b64 vcc, exec, s[50:51]
	s_cbranch_vccnz .LBB0_2255
	s_andn2_b64 vcc, exec, s[46:47]
	s_cbranch_vccnz .LBB0_2254
	v_lshl_add_u64 v[94:95], s[26:27], 0, v[100:101]
	v_mov_b32_e32 v154, v168
	v_lshl_add_u64 v[94:95], v[154:155], 1, v[94:95]
	v_add_co_u32_e32 v94, vcc, 0xfffff000, v94
	v_cvt_pk_bf16_f32 v90, v86, v87
	v_cvt_pk_bf16_f32 v91, v88, v89
	v_cvt_pk_bf16_f32 v92, v82, v83
	v_cvt_pk_bf16_f32 v93, v84, v85
	s_nop 1
	v_addc_co_u32_e32 v95, vcc, -1, v95, vcc
	global_store_dwordx4 v[94:95], v[90:93], off offset:-3840 sc1

.LBB0_2255:
	s_andn2_b64 vcc, exec, s[56:57]
	s_cbranch_vccnz .LBB0_2257
	v_lshl_add_u64 v[94:95], s[24:25], 0, v[100:101]
	v_mov_b32_e32 v154, v168
	v_lshl_add_u64 v[94:95], v[154:155], 1, v[94:95]
	v_cvt_pk_bf16_f32 v90, v86, v87
	v_cvt_pk_bf16_f32 v91, v88, v89
	v_cvt_pk_bf16_f32 v92, v82, v83
	v_cvt_pk_bf16_f32 v93, v84, v85
	global_store_dwordx4 v[94:95], v[90:93], off offset:-3840 sc1

.LBB0_2258:
	s_andn2_b64 vcc, exec, s[56:57]
	s_cbranch_vccnz .LBB0_2260
	v_lshl_add_u64 v[94:95], s[22:23], 0, v[98:99]
	v_mov_b32_e32 v154, v168
	v_lshl_add_u64 v[94:95], v[154:155], 1, v[94:95]
	v_cvt_pk_bf16_f32 v90, v86, v87
	v_cvt_pk_bf16_f32 v91, v88, v89
	v_cvt_pk_bf16_f32 v92, v82, v83
	v_cvt_pk_bf16_f32 v93, v84, v85
	global_store_dwordx4 v[94:95], v[90:93], off offset:-1792 sc1

.LBB0_2261:
	s_andn2_b64 vcc, exec, s[56:57]
	s_cbranch_vccnz .LBB0_2263
	v_pk_mul_f32 v[86:87], v[86:87], s[38:39] op_sel_hi:[1,0]
	v_pk_mul_f32 v[90:91], v[84:85], s[38:39] op_sel_hi:[1,0]
	v_pk_mul_f32 v[84:85], v[82:83], s[38:39] op_sel_hi:[1,0]
	v_cvt_pk_bf16_f32 v82, v86, v87
	v_lshl_add_u64 v[86:87], v[168:169], 1, v[104:105]
	v_pk_mul_f32 v[88:89], v[88:89], s[38:39] op_sel_hi:[1,0]
	s_nop 0
	v_cvt_pk_bf16_f32 v83, v88, v89
	v_cvt_pk_bf16_f32 v84, v84, v85
	v_cvt_pk_bf16_f32 v85, v90, v91
	global_store_dwordx4 v[86:87], v[82:85], off offset:256 sc1

.LBB0_2267:
	v_lshlrev_b64 v[84:85], 12, v[82:83]
	v_lshlrev_b64 v[82:83], 11, v[82:83]
	s_waitcnt lgkmcnt(0)
	v_pk_fma_f32 v[80:81], v[80:81], v[86:87], v[56:57] op_sel_hi:[1,0,1]
	v_pk_fma_f32 v[78:79], v[78:79], v[86:87], v[54:55] op_sel_hi:[1,0,1]
	v_pk_fma_f32 v[76:77], v[76:77], v[86:87], v[52:53] op_sel_hi:[1,0,1]
	v_pk_fma_f32 v[74:75], v[74:75], v[86:87], v[50:51] op_sel_hi:[1,0,1]
	s_and_b64 vcc, exec, s[4:5]
	s_mov_b64 s[56:57], -1
	s_cbranch_vccnz .LBB0_2283
	s_and_b64 vcc, exec, s[2:3]
	s_cbranch_vccnz .LBB0_2280
	s_andn2_b64 vcc, exec, s[50:51]
	s_cbranch_vccnz .LBB0_2277
	s_andn2_b64 vcc, exec, s[54:55]
	s_cbranch_vccnz .LBB0_2274
	s_andn2_b64 vcc, exec, s[36:37]
	s_cbranch_vccnz .LBB0_2273
	v_lshl_add_u64 v[88:89], v[158:159], 0, v[88:89]
	global_store_dwordx4 v[88:89], v[78:81], off sc1
	global_store_dwordx4 v[88:89], v[74:77], off offset:16 sc1

.LBB0_2274:
	s_andn2_b64 vcc, exec, s[56:57]
	s_cbranch_vccnz .LBB0_2276
	v_lshl_add_u64 v[92:93], s[26:27], 0, v[84:85]
	v_mov_b32_e32 v154, v168
	v_lshl_add_u64 v[92:93], v[154:155], 1, v[92:93]
	v_add_co_u32_e32 v92, vcc, 0xffffe000, v92
	v_cvt_pk_bf16_f32 v88, v78, v79
	v_cvt_pk_bf16_f32 v89, v80, v81
	v_cvt_pk_bf16_f32 v90, v74, v75
	v_cvt_pk_bf16_f32 v91, v76, v77
	s_nop 1
	v_addc_co_u32_e32 v93, vcc, -1, v93, vcc
	global_store_dwordx4 v[92:93], v[88:91], off sc1

.LBB0_2277:
	s_andn2_b64 vcc, exec, s[56:57]
	s_cbranch_vccnz .LBB0_2279
	v_lshl_add_u64 v[92:93], s[24:25], 0, v[84:85]
	v_mov_b32_e32 v154, v168
	v_lshl_add_u64 v[92:93], v[154:155], 1, v[92:93]
	v_cvt_pk_bf16_f32 v88, v78, v79
	v_cvt_pk_bf16_f32 v89, v80, v81
	v_cvt_pk_bf16_f32 v90, v74, v75
	v_cvt_pk_bf16_f32 v91, v76, v77
	global_store_dwordx4 v[92:93], v[88:91], off offset:-4096 sc1

.LBB0_2280:
	s_andn2_b64 vcc, exec, s[56:57]
	s_cbranch_vccnz .LBB0_2282
	v_lshl_add_u64 v[92:93], s[22:23], 0, v[82:83]
	v_mov_b32_e32 v154, v168
	v_lshl_add_u64 v[92:93], v[154:155], 1, v[92:93]
	v_cvt_pk_bf16_f32 v88, v78, v79
	v_cvt_pk_bf16_f32 v89, v80, v81
	v_cvt_pk_bf16_f32 v90, v74, v75
	v_cvt_pk_bf16_f32 v91, v76, v77
	global_store_dwordx4 v[92:93], v[88:91], off offset:-2048 sc1

.LBB0_2283:
	s_andn2_b64 vcc, exec, s[56:57]
	v_lshl_add_u64 v[88:89], s[20:21], 0, v[82:83]
	s_cbranch_vccnz .LBB0_2285
	v_pk_mul_f32 v[78:79], v[78:79], s[38:39] op_sel_hi:[1,0]
	v_pk_mul_f32 v[90:91], v[76:77], s[38:39] op_sel_hi:[1,0]
	v_pk_mul_f32 v[76:77], v[74:75], s[38:39] op_sel_hi:[1,0]
	v_cvt_pk_bf16_f32 v74, v78, v79
	v_lshl_add_u64 v[78:79], v[168:169], 1, v[88:89]
	v_pk_mul_f32 v[80:81], v[80:81], s[38:39] op_sel_hi:[1,0]
	s_nop 0
	v_cvt_pk_bf16_f32 v75, v80, v81
	v_cvt_pk_bf16_f32 v76, v76, v77
	v_cvt_pk_bf16_f32 v77, v90, v91
	global_store_dwordx4 v[78:79], v[74:77], off sc1
.LBB0_2285:
	v_mov_b32_e32 v87, v86
	s_nop 0
	v_mov_b32_e32 v74, v86
	v_mov_b32_e32 v75, v86
	v_pk_fma_f32 v[72:73], v[72:73], v[74:75], v[40:41]
	v_pk_fma_f32 v[70:71], v[70:71], v[86:87], v[38:39]
	v_pk_fma_f32 v[68:69], v[68:69], v[74:75], v[36:37]
	v_pk_fma_f32 v[66:67], v[66:67], v[86:87], v[34:35]
	s_and_b64 vcc, exec, s[4:5]
	s_mov_b64 s[56:57], -1
	s_cbranch_vccnz .LBB0_2297
	s_and_b64 vcc, exec, s[2:3]
	s_cbranch_vccnz .LBB0_2294
	s_andn2_b64 vcc, exec, s[50:51]
	s_cbranch_vccnz .LBB0_2291
	s_andn2_b64 vcc, exec, s[46:47]
	s_cbranch_vccnz .LBB0_2290
	v_lshl_add_u64 v[78:79], s[26:27], 0, v[84:85]
	v_mov_b32_e32 v154, v168
	v_lshl_add_u64 v[78:79], v[154:155], 1, v[78:79]
	v_add_co_u32_e32 v78, vcc, 0xfffff000, v78
	v_cvt_pk_bf16_f32 v74, v70, v71
	v_cvt_pk_bf16_f32 v75, v72, v73
	v_cvt_pk_bf16_f32 v76, v66, v67
	v_cvt_pk_bf16_f32 v77, v68, v69
	s_nop 1
	v_addc_co_u32_e32 v79, vcc, -1, v79, vcc
	global_store_dwordx4 v[78:79], v[74:77], off offset:-3840 sc1

.LBB0_2291:
	s_andn2_b64 vcc, exec, s[56:57]
	s_cbranch_vccnz .LBB0_2293
	v_lshl_add_u64 v[78:79], s[24:25], 0, v[84:85]
	v_mov_b32_e32 v154, v168
	v_lshl_add_u64 v[78:79], v[154:155], 1, v[78:79]
	v_cvt_pk_bf16_f32 v74, v70, v71
	v_cvt_pk_bf16_f32 v75, v72, v73
	v_cvt_pk_bf16_f32 v76, v66, v67
	v_cvt_pk_bf16_f32 v77, v68, v69
	global_store_dwordx4 v[78:79], v[74:77], off offset:-3840 sc1

.LBB0_2294:
	s_andn2_b64 vcc, exec, s[56:57]
	s_cbranch_vccnz .LBB0_2296
	v_lshl_add_u64 v[78:79], s[22:23], 0, v[82:83]
	v_mov_b32_e32 v154, v168
	v_lshl_add_u64 v[78:79], v[154:155], 1, v[78:79]
	v_cvt_pk_bf16_f32 v74, v70, v71
	v_cvt_pk_bf16_f32 v75, v72, v73
	v_cvt_pk_bf16_f32 v76, v66, v67
	v_cvt_pk_bf16_f32 v77, v68, v69
	global_store_dwordx4 v[78:79], v[74:77], off offset:-1792 sc1

.LBB0_2297:
	s_andn2_b64 vcc, exec, s[56:57]
	s_cbranch_vccnz .LBB0_2299
	v_pk_mul_f32 v[70:71], v[70:71], s[38:39] op_sel_hi:[1,0]
	v_pk_mul_f32 v[74:75], v[68:69], s[38:39] op_sel_hi:[1,0]
	v_pk_mul_f32 v[68:69], v[66:67], s[38:39] op_sel_hi:[1,0]
	v_cvt_pk_bf16_f32 v66, v70, v71
	v_lshl_add_u64 v[70:71], v[168:169], 1, v[88:89]
	v_pk_mul_f32 v[72:73], v[72:73], s[38:39] op_sel_hi:[1,0]
	s_nop 0
	v_cvt_pk_bf16_f32 v67, v72, v73
	v_cvt_pk_bf16_f32 v68, v68, v69
	v_cvt_pk_bf16_f32 v69, v74, v75
	global_store_dwordx4 v[70:71], v[66:69], off offset:256 sc1

.LBB0_2303:
	v_lshlrev_b64 v[68:69], 12, v[66:67]
	v_lshlrev_b64 v[66:67], 11, v[66:67]
	s_waitcnt lgkmcnt(0)
	v_pk_fma_f32 v[64:65], v[64:65], v[70:71], v[56:57] op_sel_hi:[1,0,1]
	v_pk_fma_f32 v[62:63], v[62:63], v[70:71], v[54:55] op_sel_hi:[1,0,1]
	v_pk_fma_f32 v[60:61], v[60:61], v[70:71], v[52:53] op_sel_hi:[1,0,1]
	v_pk_fma_f32 v[58:59], v[58:59], v[70:71], v[50:51] op_sel_hi:[1,0,1]
	s_and_b64 vcc, exec, s[4:5]
	s_mov_b64 s[56:57], -1
	s_cbranch_vccnz .LBB0_2319
	s_and_b64 vcc, exec, s[2:3]
	s_cbranch_vccnz .LBB0_2316
	s_andn2_b64 vcc, exec, s[50:51]
	s_cbranch_vccnz .LBB0_2313
	s_andn2_b64 vcc, exec, s[54:55]
	s_cbranch_vccnz .LBB0_2310
	s_andn2_b64 vcc, exec, s[36:37]
	s_cbranch_vccnz .LBB0_2309
	v_lshl_add_u64 v[72:73], v[158:159], 0, v[72:73]
	global_store_dwordx4 v[72:73], v[62:65], off sc1
	global_store_dwordx4 v[72:73], v[58:61], off offset:16 sc1

.LBB0_2310:
	s_andn2_b64 vcc, exec, s[56:57]
	s_cbranch_vccnz .LBB0_2312
	v_lshl_add_u64 v[76:77], s[26:27], 0, v[68:69]
	v_mov_b32_e32 v154, v168
	v_lshl_add_u64 v[76:77], v[154:155], 1, v[76:77]
	v_add_co_u32_e32 v76, vcc, 0xffffe000, v76
	v_cvt_pk_bf16_f32 v72, v62, v63
	v_cvt_pk_bf16_f32 v73, v64, v65
	v_cvt_pk_bf16_f32 v74, v58, v59
	v_cvt_pk_bf16_f32 v75, v60, v61
	s_nop 1
	v_addc_co_u32_e32 v77, vcc, -1, v77, vcc
	global_store_dwordx4 v[76:77], v[72:75], off sc1

.LBB0_2313:
	s_andn2_b64 vcc, exec, s[56:57]
	s_cbranch_vccnz .LBB0_2315
	v_lshl_add_u64 v[76:77], s[24:25], 0, v[68:69]
	v_mov_b32_e32 v154, v168
	v_lshl_add_u64 v[76:77], v[154:155], 1, v[76:77]
	v_cvt_pk_bf16_f32 v72, v62, v63
	v_cvt_pk_bf16_f32 v73, v64, v65
	v_cvt_pk_bf16_f32 v74, v58, v59
	v_cvt_pk_bf16_f32 v75, v60, v61
	global_store_dwordx4 v[76:77], v[72:75], off offset:-4096 sc1

.LBB0_2316:
	s_andn2_b64 vcc, exec, s[56:57]
	s_cbranch_vccnz .LBB0_2318
	v_lshl_add_u64 v[76:77], s[22:23], 0, v[66:67]
	v_mov_b32_e32 v154, v168
	v_lshl_add_u64 v[76:77], v[154:155], 1, v[76:77]
	v_cvt_pk_bf16_f32 v72, v62, v63
	v_cvt_pk_bf16_f32 v73, v64, v65
	v_cvt_pk_bf16_f32 v74, v58, v59
	v_cvt_pk_bf16_f32 v75, v60, v61
	global_store_dwordx4 v[76:77], v[72:75], off offset:-2048 sc1

.LBB0_2319:
	s_andn2_b64 vcc, exec, s[56:57]
	v_lshl_add_u64 v[72:73], s[20:21], 0, v[66:67]
	s_cbranch_vccnz .LBB0_2321
	v_pk_mul_f32 v[62:63], v[62:63], s[38:39] op_sel_hi:[1,0]
	v_pk_mul_f32 v[74:75], v[60:61], s[38:39] op_sel_hi:[1,0]
	v_pk_mul_f32 v[60:61], v[58:59], s[38:39] op_sel_hi:[1,0]
	v_cvt_pk_bf16_f32 v58, v62, v63
	v_lshl_add_u64 v[62:63], v[168:169], 1, v[72:73]
	v_pk_mul_f32 v[64:65], v[64:65], s[38:39] op_sel_hi:[1,0]
	s_nop 0
	v_cvt_pk_bf16_f32 v59, v64, v65
	v_cvt_pk_bf16_f32 v60, v60, v61
	v_cvt_pk_bf16_f32 v61, v74, v75
	global_store_dwordx4 v[62:63], v[58:61], off sc1
.LBB0_2321:
	v_mov_b32_e32 v71, v70
	s_nop 0
	v_mov_b32_e32 v58, v70
	v_mov_b32_e32 v59, v70
	v_pk_fma_f32 v[48:49], v[48:49], v[58:59], v[40:41]
	v_pk_fma_f32 v[46:47], v[46:47], v[70:71], v[38:39]
	v_pk_fma_f32 v[44:45], v[44:45], v[58:59], v[36:37]
	v_pk_fma_f32 v[42:43], v[42:43], v[70:71], v[34:35]
	s_and_b64 vcc, exec, s[4:5]
	s_mov_b64 s[56:57], -1
	s_cbranch_vccnz .LBB0_2333
	s_and_b64 vcc, exec, s[2:3]
	s_cbranch_vccnz .LBB0_2330
	s_andn2_b64 vcc, exec, s[50:51]
	s_cbranch_vccnz .LBB0_2327
	s_andn2_b64 vcc, exec, s[46:47]
	s_cbranch_vccnz .LBB0_2326
	v_lshl_add_u64 v[62:63], s[26:27], 0, v[68:69]
	v_mov_b32_e32 v154, v168
	v_lshl_add_u64 v[62:63], v[154:155], 1, v[62:63]
	v_add_co_u32_e32 v62, vcc, 0xfffff000, v62
	v_cvt_pk_bf16_f32 v58, v46, v47
	v_cvt_pk_bf16_f32 v59, v48, v49
	v_cvt_pk_bf16_f32 v60, v42, v43
	v_cvt_pk_bf16_f32 v61, v44, v45
	s_nop 1
	v_addc_co_u32_e32 v63, vcc, -1, v63, vcc
	global_store_dwordx4 v[62:63], v[58:61], off offset:-3840 sc1

.LBB0_2327:
	s_andn2_b64 vcc, exec, s[56:57]
	s_cbranch_vccnz .LBB0_2329
	v_lshl_add_u64 v[62:63], s[24:25], 0, v[68:69]
	v_mov_b32_e32 v154, v168
	v_lshl_add_u64 v[62:63], v[154:155], 1, v[62:63]
	v_cvt_pk_bf16_f32 v58, v46, v47
	v_cvt_pk_bf16_f32 v59, v48, v49
	v_cvt_pk_bf16_f32 v60, v42, v43
	v_cvt_pk_bf16_f32 v61, v44, v45
	global_store_dwordx4 v[62:63], v[58:61], off offset:-3840 sc1

.LBB0_2330:
	s_andn2_b64 vcc, exec, s[56:57]
	s_cbranch_vccnz .LBB0_2332
	v_lshl_add_u64 v[62:63], s[22:23], 0, v[66:67]
	v_mov_b32_e32 v154, v168
	v_lshl_add_u64 v[62:63], v[154:155], 1, v[62:63]
	v_cvt_pk_bf16_f32 v58, v46, v47
	v_cvt_pk_bf16_f32 v59, v48, v49
	v_cvt_pk_bf16_f32 v60, v42, v43
	v_cvt_pk_bf16_f32 v61, v44, v45
	global_store_dwordx4 v[62:63], v[58:61], off offset:-1792 sc1

.LBB0_2333:
	s_andn2_b64 vcc, exec, s[56:57]
	s_cbranch_vccnz .LBB0_2335
	v_pk_mul_f32 v[46:47], v[46:47], s[38:39] op_sel_hi:[1,0]
	v_pk_mul_f32 v[58:59], v[44:45], s[38:39] op_sel_hi:[1,0]
	v_pk_mul_f32 v[44:45], v[42:43], s[38:39] op_sel_hi:[1,0]
	v_cvt_pk_bf16_f32 v42, v46, v47
	v_lshl_add_u64 v[46:47], v[168:169], 1, v[72:73]
	v_pk_mul_f32 v[48:49], v[48:49], s[38:39] op_sel_hi:[1,0]
	s_nop 0
	v_cvt_pk_bf16_f32 v43, v48, v49
	v_cvt_pk_bf16_f32 v44, v44, v45
	v_cvt_pk_bf16_f32 v45, v58, v59
	global_store_dwordx4 v[46:47], v[42:45], off offset:256 sc1

.LBB0_2339:
	v_lshlrev_b64 v[44:45], 12, v[42:43]
	v_lshlrev_b64 v[42:43], 11, v[42:43]
	s_waitcnt lgkmcnt(0)
	v_pk_fma_f32 v[32:33], v[32:33], v[46:47], v[56:57] op_sel_hi:[1,0,1]
	v_pk_fma_f32 v[30:31], v[30:31], v[46:47], v[54:55] op_sel_hi:[1,0,1]
	v_pk_fma_f32 v[28:29], v[28:29], v[46:47], v[52:53] op_sel_hi:[1,0,1]
	v_pk_fma_f32 v[26:27], v[26:27], v[46:47], v[50:51] op_sel_hi:[1,0,1]
	s_and_b64 vcc, exec, s[4:5]
	s_mov_b64 s[56:57], -1
	s_cbranch_vccnz .LBB0_2355
	s_and_b64 vcc, exec, s[2:3]
	s_cbranch_vccnz .LBB0_2352
	s_andn2_b64 vcc, exec, s[50:51]
	s_cbranch_vccnz .LBB0_2349
	s_andn2_b64 vcc, exec, s[54:55]
	s_cbranch_vccnz .LBB0_2346
	s_andn2_b64 vcc, exec, s[36:37]
	s_cbranch_vccnz .LBB0_2345
	v_lshl_add_u64 v[48:49], v[158:159], 0, v[48:49]
	global_store_dwordx4 v[48:49], v[30:33], off sc1
	global_store_dwordx4 v[48:49], v[26:29], off offset:16 sc1

.LBB0_2346:
	s_andn2_b64 vcc, exec, s[56:57]
	s_cbranch_vccnz .LBB0_2348
	v_lshl_add_u64 v[48:49], s[26:27], 0, v[44:45]
	v_mov_b32_e32 v154, v168
	v_lshl_add_u64 v[48:49], v[154:155], 1, v[48:49]
	v_add_co_u32_e32 v48, vcc, 0xffffe000, v48
	v_cvt_pk_bf16_f32 v58, v30, v31
	v_cvt_pk_bf16_f32 v59, v32, v33
	v_cvt_pk_bf16_f32 v60, v26, v27
	v_cvt_pk_bf16_f32 v61, v28, v29
	s_nop 1
	v_addc_co_u32_e32 v49, vcc, -1, v49, vcc
	global_store_dwordx4 v[48:49], v[58:61], off sc1

.LBB0_2349:
	s_andn2_b64 vcc, exec, s[56:57]
	s_cbranch_vccnz .LBB0_2351
	v_lshl_add_u64 v[48:49], s[24:25], 0, v[44:45]
	v_mov_b32_e32 v154, v168
	v_lshl_add_u64 v[48:49], v[154:155], 1, v[48:49]
	v_cvt_pk_bf16_f32 v58, v30, v31
	v_cvt_pk_bf16_f32 v59, v32, v33
	v_cvt_pk_bf16_f32 v60, v26, v27
	v_cvt_pk_bf16_f32 v61, v28, v29
	global_store_dwordx4 v[48:49], v[58:61], off offset:-4096 sc1

.LBB0_2352:
	s_andn2_b64 vcc, exec, s[56:57]
	s_cbranch_vccnz .LBB0_2354
	v_lshl_add_u64 v[48:49], s[22:23], 0, v[42:43]
	v_mov_b32_e32 v154, v168
	v_lshl_add_u64 v[48:49], v[154:155], 1, v[48:49]
	v_cvt_pk_bf16_f32 v58, v30, v31
	v_cvt_pk_bf16_f32 v59, v32, v33
	v_cvt_pk_bf16_f32 v60, v26, v27
	v_cvt_pk_bf16_f32 v61, v28, v29
	global_store_dwordx4 v[48:49], v[58:61], off offset:-2048 sc1

.LBB0_2355:
	s_andn2_b64 vcc, exec, s[56:57]
	v_lshl_add_u64 v[48:49], s[20:21], 0, v[42:43]
	s_cbranch_vccnz .LBB0_2357
	v_pk_mul_f32 v[30:31], v[30:31], s[38:39] op_sel_hi:[1,0]
	v_pk_mul_f32 v[58:59], v[28:29], s[38:39] op_sel_hi:[1,0]
	v_pk_mul_f32 v[28:29], v[26:27], s[38:39] op_sel_hi:[1,0]
	v_cvt_pk_bf16_f32 v26, v30, v31
	v_lshl_add_u64 v[30:31], v[168:169], 1, v[48:49]
	v_pk_mul_f32 v[32:33], v[32:33], s[38:39] op_sel_hi:[1,0]
	s_nop 0
	v_cvt_pk_bf16_f32 v27, v32, v33
	v_cvt_pk_bf16_f32 v28, v28, v29
	v_cvt_pk_bf16_f32 v29, v58, v59
	global_store_dwordx4 v[30:31], v[26:29], off sc1
.LBB0_2357:
	v_mov_b32_e32 v47, v46
	s_nop 0
	v_mov_b32_e32 v26, v46
	v_mov_b32_e32 v27, v46
	v_pk_fma_f32 v[24:25], v[24:25], v[26:27], v[40:41]
	v_pk_fma_f32 v[22:23], v[22:23], v[46:47], v[38:39]
	v_pk_fma_f32 v[20:21], v[20:21], v[26:27], v[36:37]
	v_pk_fma_f32 v[18:19], v[18:19], v[46:47], v[34:35]
	s_and_b64 vcc, exec, s[4:5]
	s_mov_b64 s[56:57], -1
	s_cbranch_vccnz .LBB0_2369
	s_and_b64 vcc, exec, s[2:3]
	s_cbranch_vccnz .LBB0_2366
	s_andn2_b64 vcc, exec, s[50:51]
	s_cbranch_vccnz .LBB0_2363
	s_andn2_b64 vcc, exec, s[46:47]
	s_cbranch_vccnz .LBB0_2362
	v_lshl_add_u64 v[30:31], s[26:27], 0, v[44:45]
	v_mov_b32_e32 v154, v168
	v_lshl_add_u64 v[30:31], v[154:155], 1, v[30:31]
	v_add_co_u32_e32 v30, vcc, 0xfffff000, v30
	v_cvt_pk_bf16_f32 v26, v22, v23
	v_cvt_pk_bf16_f32 v27, v24, v25
	v_cvt_pk_bf16_f32 v28, v18, v19
	v_cvt_pk_bf16_f32 v29, v20, v21
	s_nop 1
	v_addc_co_u32_e32 v31, vcc, -1, v31, vcc
	global_store_dwordx4 v[30:31], v[26:29], off offset:-3840 sc1

.LBB0_2363:
	s_andn2_b64 vcc, exec, s[56:57]
	s_cbranch_vccnz .LBB0_2365
	v_lshl_add_u64 v[30:31], s[24:25], 0, v[44:45]
	v_mov_b32_e32 v154, v168
	v_lshl_add_u64 v[30:31], v[154:155], 1, v[30:31]
	v_cvt_pk_bf16_f32 v26, v22, v23
	v_cvt_pk_bf16_f32 v27, v24, v25
	v_cvt_pk_bf16_f32 v28, v18, v19
	v_cvt_pk_bf16_f32 v29, v20, v21
	global_store_dwordx4 v[30:31], v[26:29], off offset:-3840 sc1

.LBB0_2366:
	s_andn2_b64 vcc, exec, s[56:57]
	s_cbranch_vccnz .LBB0_2368
	v_lshl_add_u64 v[30:31], s[22:23], 0, v[42:43]
	v_mov_b32_e32 v154, v168
	v_lshl_add_u64 v[30:31], v[154:155], 1, v[30:31]
	v_cvt_pk_bf16_f32 v26, v22, v23
	v_cvt_pk_bf16_f32 v27, v24, v25
	v_cvt_pk_bf16_f32 v28, v18, v19
	v_cvt_pk_bf16_f32 v29, v20, v21
	global_store_dwordx4 v[30:31], v[26:29], off offset:-1792 sc1

.LBB0_2369:
	s_andn2_b64 vcc, exec, s[56:57]
	s_cbranch_vccnz .LBB0_2371
	v_pk_mul_f32 v[22:23], v[22:23], s[38:39] op_sel_hi:[1,0]
	v_pk_mul_f32 v[26:27], v[20:21], s[38:39] op_sel_hi:[1,0]
	v_pk_mul_f32 v[20:21], v[18:19], s[38:39] op_sel_hi:[1,0]
	v_cvt_pk_bf16_f32 v18, v22, v23
	v_lshl_add_u64 v[22:23], v[168:169], 1, v[48:49]
	v_pk_mul_f32 v[24:25], v[24:25], s[38:39] op_sel_hi:[1,0]
	s_nop 0
	v_cvt_pk_bf16_f32 v19, v24, v25
	v_cvt_pk_bf16_f32 v20, v20, v21
	v_cvt_pk_bf16_f32 v21, v26, v27
	global_store_dwordx4 v[22:23], v[18:21], off offset:256 sc1

.LBB0_2375:
	v_lshlrev_b64 v[20:21], 12, v[18:19]
	v_lshlrev_b64 v[18:19], 11, v[18:19]
	s_waitcnt lgkmcnt(0)
	v_pk_fma_f32 v[16:17], v[16:17], v[22:23], v[56:57] op_sel_hi:[1,0,1]
	v_pk_fma_f32 v[14:15], v[14:15], v[22:23], v[54:55] op_sel_hi:[1,0,1]
	v_pk_fma_f32 v[12:13], v[12:13], v[22:23], v[52:53] op_sel_hi:[1,0,1]
	v_pk_fma_f32 v[10:11], v[10:11], v[22:23], v[50:51] op_sel_hi:[1,0,1]
	s_and_b64 vcc, exec, s[4:5]
	s_mov_b64 s[6:7], -1
	s_cbranch_vccnz .LBB0_2391
	s_and_b64 vcc, exec, s[2:3]
	s_cbranch_vccnz .LBB0_2388
	s_andn2_b64 vcc, exec, s[50:51]
	s_cbranch_vccnz .LBB0_2385
	s_andn2_b64 vcc, exec, s[54:55]
	s_cbranch_vccnz .LBB0_2382
	s_andn2_b64 vcc, exec, s[36:37]
	s_cbranch_vccnz .LBB0_2381
	v_lshl_add_u64 v[24:25], v[158:159], 0, v[24:25]
	global_store_dwordx4 v[24:25], v[14:17], off sc1
	global_store_dwordx4 v[24:25], v[10:13], off offset:16 sc1

.LBB0_2382:
	s_andn2_b64 vcc, exec, s[6:7]
	s_cbranch_vccnz .LBB0_2384
	v_lshl_add_u64 v[28:29], s[26:27], 0, v[20:21]
	v_mov_b32_e32 v154, v168
	v_lshl_add_u64 v[28:29], v[154:155], 1, v[28:29]
	v_add_co_u32_e32 v28, vcc, 0xffffe000, v28
	v_cvt_pk_bf16_f32 v24, v14, v15
	v_cvt_pk_bf16_f32 v25, v16, v17
	v_cvt_pk_bf16_f32 v26, v10, v11
	v_cvt_pk_bf16_f32 v27, v12, v13
	s_nop 1
	v_addc_co_u32_e32 v29, vcc, -1, v29, vcc
	global_store_dwordx4 v[28:29], v[24:27], off sc1

.LBB0_2385:
	s_andn2_b64 vcc, exec, s[6:7]
	s_cbranch_vccnz .LBB0_2387
	v_lshl_add_u64 v[28:29], s[24:25], 0, v[20:21]
	v_mov_b32_e32 v154, v168
	v_lshl_add_u64 v[28:29], v[154:155], 1, v[28:29]
	v_cvt_pk_bf16_f32 v24, v14, v15
	v_cvt_pk_bf16_f32 v25, v16, v17
	v_cvt_pk_bf16_f32 v26, v10, v11
	v_cvt_pk_bf16_f32 v27, v12, v13
	global_store_dwordx4 v[28:29], v[24:27], off offset:-4096 sc1

.LBB0_2388:
	s_andn2_b64 vcc, exec, s[6:7]
	s_cbranch_vccnz .LBB0_2390
	v_lshl_add_u64 v[28:29], s[22:23], 0, v[18:19]
	v_mov_b32_e32 v154, v168
	v_lshl_add_u64 v[28:29], v[154:155], 1, v[28:29]
	v_cvt_pk_bf16_f32 v24, v14, v15
	v_cvt_pk_bf16_f32 v25, v16, v17
	v_cvt_pk_bf16_f32 v26, v10, v11
	v_cvt_pk_bf16_f32 v27, v12, v13
	global_store_dwordx4 v[28:29], v[24:27], off offset:-2048 sc1

.LBB0_2391:
	s_andn2_b64 vcc, exec, s[6:7]
	v_lshl_add_u64 v[24:25], s[20:21], 0, v[18:19]
	s_cbranch_vccnz .LBB0_2393
	v_pk_mul_f32 v[14:15], v[14:15], s[38:39] op_sel_hi:[1,0]
	v_pk_mul_f32 v[26:27], v[12:13], s[38:39] op_sel_hi:[1,0]
	v_pk_mul_f32 v[12:13], v[10:11], s[38:39] op_sel_hi:[1,0]
	v_cvt_pk_bf16_f32 v10, v14, v15
	v_lshl_add_u64 v[14:15], v[168:169], 1, v[24:25]
	v_pk_mul_f32 v[16:17], v[16:17], s[38:39] op_sel_hi:[1,0]
	s_nop 0
	v_cvt_pk_bf16_f32 v11, v16, v17
	v_cvt_pk_bf16_f32 v12, v12, v13
	v_cvt_pk_bf16_f32 v13, v26, v27
	global_store_dwordx4 v[14:15], v[10:13], off sc1
.LBB0_2393:
	v_mov_b32_e32 v23, v22
	s_nop 0
	v_mov_b32_e32 v10, v22
	v_mov_b32_e32 v11, v22
	v_pk_fma_f32 v[8:9], v[8:9], v[10:11], v[40:41]
	v_pk_fma_f32 v[6:7], v[6:7], v[22:23], v[38:39]
	v_pk_fma_f32 v[4:5], v[4:5], v[10:11], v[36:37]
	v_pk_fma_f32 v[2:3], v[2:3], v[22:23], v[34:35]
	s_and_b64 vcc, exec, s[4:5]
	s_mov_b64 s[4:5], -1
	s_cbranch_vccnz .LBB0_2406
	s_and_b64 vcc, exec, s[2:3]
	s_mov_b64 s[2:3], -1
	s_cbranch_vccnz .LBB0_2402
	s_andn2_b64 vcc, exec, s[50:51]
	s_cbranch_vccnz .LBB0_2399
	s_andn2_b64 vcc, exec, s[46:47]
	s_cbranch_vccnz .LBB0_2398
	v_lshl_add_u64 v[14:15], s[26:27], 0, v[20:21]
	v_mov_b32_e32 v154, v168
	v_lshl_add_u64 v[14:15], v[154:155], 1, v[14:15]
	v_add_co_u32_e32 v14, vcc, 0xfffff000, v14
	v_cvt_pk_bf16_f32 v10, v6, v7
	v_cvt_pk_bf16_f32 v11, v8, v9
	v_cvt_pk_bf16_f32 v12, v2, v3
	v_cvt_pk_bf16_f32 v13, v4, v5
	s_nop 1
	v_addc_co_u32_e32 v15, vcc, -1, v15, vcc
	global_store_dwordx4 v[14:15], v[10:13], off offset:-3840 sc1

.LBB0_2399:
	s_andn2_b64 vcc, exec, s[2:3]
	s_cbranch_vccnz .LBB0_2401
	v_lshl_add_u64 v[14:15], s[24:25], 0, v[20:21]
	v_mov_b32_e32 v154, v168
	v_lshl_add_u64 v[14:15], v[154:155], 1, v[14:15]
	v_cvt_pk_bf16_f32 v10, v6, v7
	v_cvt_pk_bf16_f32 v11, v8, v9
	v_cvt_pk_bf16_f32 v12, v2, v3
	v_cvt_pk_bf16_f32 v13, v4, v5
	global_store_dwordx4 v[14:15], v[10:13], off offset:-3840 sc1

.LBB0_2402:
	s_andn2_b64 vcc, exec, s[2:3]
	s_cbranch_vccnz .LBB0_2404
	v_lshl_add_u64 v[14:15], s[22:23], 0, v[18:19]
	v_mov_b32_e32 v154, v168
	v_lshl_add_u64 v[14:15], v[154:155], 1, v[14:15]
	v_cvt_pk_bf16_f32 v10, v6, v7
	v_cvt_pk_bf16_f32 v11, v8, v9
	v_cvt_pk_bf16_f32 v12, v2, v3
	v_cvt_pk_bf16_f32 v13, v4, v5
	global_store_dwordx4 v[14:15], v[10:13], off offset:-1792 sc1

.LBB0_2407:
	v_pk_mul_f32 v[6:7], v[6:7], s[38:39] op_sel_hi:[1,0]
	v_pk_mul_f32 v[10:11], v[4:5], s[38:39] op_sel_hi:[1,0]
	v_pk_mul_f32 v[4:5], v[2:3], s[38:39] op_sel_hi:[1,0]
	v_cvt_pk_bf16_f32 v2, v6, v7
	v_lshl_add_u64 v[6:7], v[168:169], 1, v[24:25]
	v_pk_mul_f32 v[8:9], v[8:9], s[38:39] op_sel_hi:[1,0]
	s_nop 0
	v_cvt_pk_bf16_f32 v3, v8, v9
	v_cvt_pk_bf16_f32 v4, v4, v5
	v_cvt_pk_bf16_f32 v5, v10, v11
	global_store_dwordx4 v[6:7], v[2:5], off offset:256 sc1
	s_and_b64 vcc, exec, s[0:1]
	s_mov_b64 s[0:1], -1
	s_cbranch_vccnz .LBB0_2107

.LBB0_2413:
	v_add_u32_e32 v48, s0, v157
	v_ashrrev_i32_e32 v49, 31, v48
	v_lshlrev_b64 v[48:49], 12, v[48:49]
	v_lshl_add_u64 v[96:97], v[2:3], 0, v[48:49]
	global_load_dwordx4 v[32:35], v[4:5], off
	global_load_dwordx4 v[36:39], v[4:5], off offset:16
	global_load_dwordx4 v[40:43], v[10:11], off
	global_load_dwordx4 v[44:47], v[12:13], off
	global_load_dwordx4 v[48:51], v[96:97], off
	global_load_dwordx4 v[52:55], v[96:97], off offset:16
	v_add_co_u32_e32 v98, vcc, 0x10000, v96
	s_add_i32 s3, s3, s96
	s_nop 0
	v_addc_co_u32_e32 v99, vcc, 0, v97, vcc
	v_add_co_u32_e32 v100, vcc, 0x20000, v96
	global_load_dwordx4 v[60:63], v[98:99], off
	global_load_dwordx4 v[64:67], v[98:99], off offset:16
	v_addc_co_u32_e32 v101, vcc, 0, v97, vcc
	v_add_co_u32_e32 v102, vcc, 0x30000, v96
	global_load_dwordx4 v[72:75], v[100:101], off
	global_load_dwordx4 v[76:79], v[100:101], off offset:16
	v_addc_co_u32_e32 v103, vcc, 0, v97, vcc
	global_load_dwordx4 v[84:87], v[102:103], off
	s_waitcnt vmcnt(6)
	v_mfma_f32_16x16x32_bf16 v[56:59], v[48:51], v[32:35], 0
	v_mfma_f32_16x16x32_bf16 v[48:51], v[48:51], v[40:43], 0
	s_waitcnt vmcnt(5)
	v_mfma_f32_16x16x32_bf16 v[56:59], v[52:55], v[36:39], v[56:59]
	v_mfma_f32_16x16x32_bf16 v[48:51], v[52:55], v[44:47], v[48:51]
	global_load_dwordx4 v[52:55], v[102:103], off offset:16
	s_waitcnt vmcnt(5)
	v_mfma_f32_16x16x32_bf16 v[68:71], v[60:63], v[32:35], 0
	v_mfma_f32_16x16x32_bf16 v[60:63], v[60:63], v[40:43], 0
	s_waitcnt vmcnt(3)
	v_mfma_f32_16x16x32_bf16 v[80:83], v[72:75], v[32:35], 0
	v_mfma_f32_16x16x32_bf16 v[72:75], v[72:75], v[40:43], 0
	s_waitcnt vmcnt(1)
	v_mfma_f32_16x16x32_bf16 v[32:35], v[84:87], v[32:35], 0
	v_mfma_f32_16x16x32_bf16 v[40:43], v[84:87], v[40:43], 0
	v_mfma_f32_16x16x32_bf16 v[68:71], v[64:67], v[36:39], v[68:71]
	v_mfma_f32_16x16x32_bf16 v[60:63], v[64:67], v[44:47], v[60:63]
	v_mfma_f32_16x16x32_bf16 v[64:67], v[76:79], v[36:39], v[80:83]
	v_mfma_f32_16x16x32_bf16 v[72:75], v[76:79], v[44:47], v[72:75]
	s_waitcnt vmcnt(0)
	v_mfma_f32_16x16x32_bf16 v[32:35], v[52:55], v[36:39], v[32:35]
	global_load_dwordx4 v[36:39], v[4:5], off offset:128
	global_load_dwordx4 v[76:79], v[4:5], off offset:144
	v_mfma_f32_16x16x32_bf16 v[40:43], v[52:55], v[44:47], v[40:43]
	global_load_dwordx4 v[44:47], v[96:97], off offset:128
	global_load_dwordx4 v[52:55], v[96:97], off offset:144
	global_load_dwordx4 v[80:83], v[14:15], off
	global_load_dwordx4 v[84:87], v[16:17], off
	s_waitcnt vmcnt(3)
	v_mfma_f32_16x16x32_bf16 v[56:59], v[44:47], v[36:39], v[56:59]
	s_waitcnt vmcnt(1)
	v_mfma_f32_16x16x32_bf16 v[44:47], v[44:47], v[80:83], v[48:51]
	s_nop 2
	global_load_dwordx4 v[48:51], v[98:99], off offset:128
	global_load_dwordx4 v[88:91], v[98:99], off offset:144
	v_mfma_f32_16x16x32_bf16 v[56:59], v[52:55], v[76:79], v[56:59]
	s_waitcnt vmcnt(2)
	v_mfma_f32_16x16x32_bf16 v[44:47], v[52:55], v[84:87], v[44:47]
	s_waitcnt vmcnt(1)
	v_mfma_f32_16x16x32_bf16 v[68:71], v[48:51], v[36:39], v[68:71]
	v_mfma_f32_16x16x32_bf16 v[48:51], v[48:51], v[80:83], v[60:63]
	s_nop 2
	global_load_dwordx4 v[60:63], v[100:101], off offset:128
	global_load_dwordx4 v[92:95], v[100:101], off offset:144
	global_load_dwordx4 v[52:55], v[102:103], off offset:144
	s_waitcnt vmcnt(2)
	v_mfma_f32_16x16x32_bf16 v[64:67], v[60:63], v[36:39], v[64:67]
	v_mfma_f32_16x16x32_bf16 v[60:63], v[60:63], v[80:83], v[72:75]
	s_nop 2
	global_load_dwordx4 v[72:75], v[102:103], off offset:128
	v_mfma_f32_16x16x32_bf16 v[48:51], v[88:91], v[84:87], v[48:51]
	s_waitcnt vmcnt(2)
	v_mfma_f32_16x16x32_bf16 v[64:67], v[92:95], v[76:79], v[64:67]
	v_mfma_f32_16x16x32_bf16 v[60:63], v[92:95], v[84:87], v[60:63]
	s_waitcnt vmcnt(0)
	v_mfma_f32_16x16x32_bf16 v[32:35], v[72:75], v[36:39], v[32:35]
	v_mfma_f32_16x16x32_bf16 v[36:39], v[72:75], v[80:83], v[40:43]
	v_mfma_f32_16x16x32_bf16 v[40:43], v[88:91], v[76:79], v[68:71]
	s_nop 2
	global_load_dwordx4 v[68:71], v[4:5], off offset:256
	global_load_dwordx4 v[72:75], v[4:5], off offset:272
	v_mfma_f32_16x16x32_bf16 v[32:35], v[52:55], v[76:79], v[32:35]
	v_mfma_f32_16x16x32_bf16 v[36:39], v[52:55], v[84:87], v[36:39]
	global_load_dwordx4 v[52:55], v[96:97], off offset:256
	global_load_dwordx4 v[76:79], v[96:97], off offset:272
	global_load_dwordx4 v[80:83], v[18:19], off
	global_load_dwordx4 v[84:87], v[20:21], off
	s_waitcnt vmcnt(3)
	v_mfma_f32_16x16x32_bf16 v[56:59], v[52:55], v[68:71], v[56:59]
	s_waitcnt vmcnt(1)
	v_mfma_f32_16x16x32_bf16 v[44:47], v[52:55], v[80:83], v[44:47]
	global_load_dwordx4 v[52:55], v[98:99], off offset:256
	global_load_dwordx4 v[88:91], v[98:99], off offset:272
	v_mfma_f32_16x16x32_bf16 v[56:59], v[76:79], v[72:75], v[56:59]
	s_waitcnt vmcnt(2)
	v_mfma_f32_16x16x32_bf16 v[44:47], v[76:79], v[84:87], v[44:47]
	s_waitcnt vmcnt(1)
	v_mfma_f32_16x16x32_bf16 v[40:43], v[52:55], v[68:71], v[40:43]
	v_mfma_f32_16x16x32_bf16 v[48:51], v[52:55], v[80:83], v[48:51]
	global_load_dwordx4 v[52:55], v[100:101], off offset:256
	global_load_dwordx4 v[92:95], v[100:101], off offset:272
	global_load_dwordx4 v[76:79], v[102:103], off offset:272
	s_waitcnt vmcnt(2)
	v_mfma_f32_16x16x32_bf16 v[64:67], v[52:55], v[68:71], v[64:67]
	v_mfma_f32_16x16x32_bf16 v[52:55], v[52:55], v[80:83], v[60:63]
	s_nop 2
	global_load_dwordx4 v[60:63], v[102:103], off offset:256
	v_mfma_f32_16x16x32_bf16 v[40:43], v[88:91], v[72:75], v[40:43]
	v_mfma_f32_16x16x32_bf16 v[48:51], v[88:91], v[84:87], v[48:51]
	s_waitcnt vmcnt(2)
	v_mfma_f32_16x16x32_bf16 v[52:55], v[92:95], v[84:87], v[52:55]
	s_waitcnt vmcnt(0)
	v_mfma_f32_16x16x32_bf16 v[32:35], v[60:63], v[68:71], v[32:35]
	v_mfma_f32_16x16x32_bf16 v[36:39], v[60:63], v[80:83], v[36:39]
	v_mfma_f32_16x16x32_bf16 v[60:63], v[92:95], v[72:75], v[64:67]
	s_nop 2
	global_load_dwordx4 v[64:67], v[4:5], off offset:384
	global_load_dwordx4 v[68:71], v[4:5], off offset:400
	v_mfma_f32_16x16x32_bf16 v[32:35], v[76:79], v[72:75], v[32:35]
	v_mfma_f32_16x16x32_bf16 v[36:39], v[76:79], v[84:87], v[36:39]
	global_load_dwordx4 v[72:75], v[96:97], off offset:384
	global_load_dwordx4 v[76:79], v[96:97], off offset:400
	global_load_dwordx4 v[80:83], v[22:23], off
	global_load_dwordx4 v[84:87], v[24:25], off
	s_waitcnt vmcnt(3)
	v_mfma_f32_16x16x32_bf16 v[56:59], v[72:75], v[64:67], v[56:59]
	s_waitcnt vmcnt(1)
	v_mfma_f32_16x16x32_bf16 v[44:47], v[72:75], v[80:83], v[44:47]
	global_load_dwordx4 v[72:75], v[98:99], off offset:384
	global_load_dwordx4 v[88:91], v[98:99], off offset:400
	s_waitcnt vmcnt(1)
	v_mfma_f32_16x16x32_bf16 v[40:43], v[72:75], v[64:67], v[40:43]
	v_mfma_f32_16x16x32_bf16 v[48:51], v[72:75], v[80:83], v[48:51]
	global_load_dwordx4 v[72:75], v[100:101], off offset:384
	global_load_dwordx4 v[92:95], v[100:101], off offset:400
	s_waitcnt vmcnt(1)
	v_mfma_f32_16x16x32_bf16 v[60:63], v[72:75], v[64:67], v[60:63]
	v_mfma_f32_16x16x32_bf16 v[52:55], v[72:75], v[80:83], v[52:55]
	global_load_dwordx4 v[72:75], v[102:103], off offset:384
	v_mfma_f32_16x16x32_bf16 v[56:59], v[76:79], v[68:71], v[56:59]
	v_mfma_f32_16x16x32_bf16 v[44:47], v[76:79], v[84:87], v[44:47]
	global_load_dwordx4 v[76:79], v[102:103], off offset:400
	s_waitcnt vmcnt(1)
	v_mfma_f32_16x16x32_bf16 v[32:35], v[72:75], v[64:67], v[32:35]
	v_add_u32_e32 v64, s0, v180
	v_ashrrev_i32_e32 v65, 31, v64
	s_nop 2
	ds_write2_b32 v27, v56, v44 offset1:16
	v_mfma_f32_16x16x32_bf16 v[36:39], v[72:75], v[80:83], v[36:39]
	v_lshlrev_b64 v[72:73], 7, v[64:65]
	v_lshl_add_u64 v[66:67], s[10:11], 0, v[72:73]
	ds_write2_b32 v27, v57, v45 offset0:32 offset1:48
	ds_write2_b32 v27, v58, v46 offset0:64 offset1:80
	ds_write2_b32 v27, v59, v47 offset0:96 offset1:112
	v_mfma_f32_16x16x32_bf16 v[40:43], v[88:91], v[68:71], v[40:43]
	v_ashrrev_i32_e32 v64, 8, v64
	v_lshrrev_b32_e32 v65, 4, v64
	v_add_u32_e32 v65, -1, v65
	v_mfma_f32_16x16x32_bf16 v[48:51], v[88:91], v[84:87], v[48:51]
	v_cmp_lt_i32_e32 vcc, 31, v64
	v_lshl_add_u64 v[100:101], v[8:9], 0, v[72:73]
	s_add_i32 s0, s0, s1
	v_mfma_f32_16x16x32_bf16 v[60:63], v[92:95], v[68:71], v[60:63]
	v_cndmask_b32_e32 v64, 0, v65, vcc
	v_ashrrev_i32_e32 v65, 31, v64
	v_lshlrev_b64 v[64:65], 15, v[64:65]
	v_mfma_f32_16x16x32_bf16 v[52:55], v[92:95], v[84:87], v[52:55]
	v_lshl_add_u64 v[64:65], v[6:7], 0, v[64:65]
	s_cmpk_lt_i32 s3, 0x100
	s_waitcnt vmcnt(0)
	v_mfma_f32_16x16x32_bf16 v[32:35], v[76:79], v[68:71], v[32:35]
	v_mfma_f32_16x16x32_bf16 v[36:39], v[76:79], v[84:87], v[36:39]
	ds_write2_b32 v29, v40, v48 offset1:16
	ds_write2_b32 v29, v41, v49 offset0:32 offset1:48
	ds_write2_b32 v29, v42, v50 offset0:64 offset1:80
	ds_write2_b32 v29, v43, v51 offset0:96 offset1:112
	ds_write2_b32 v30, v60, v52 offset1:16
	ds_write2_b32 v30, v61, v53 offset0:32 offset1:48
	ds_write2_b32 v30, v62, v54 offset0:64 offset1:80
	ds_write2_b32 v30, v63, v55 offset0:96 offset1:112
	ds_write2_b32 v31, v32, v36 offset1:16
	ds_write2_b32 v31, v33, v37 offset0:32 offset1:48
	ds_write2_b32 v31, v34, v38 offset0:64 offset1:80
	ds_write2_b32 v31, v35, v39 offset0:96 offset1:112
	s_waitcnt lgkmcnt(0)
	s_barrier
	global_load_dwordx4 v[32:35], v[66:67], off
	global_load_dwordx4 v[36:39], v[66:67], off offset:16
	global_load_dwordx4 v[40:43], v[66:67], off offset:32
	global_load_dwordx4 v[44:47], v[66:67], off offset:48
	global_load_dwordx4 v[48:51], v[66:67], off offset:64
	global_load_dwordx4 v[52:55], v[66:67], off offset:80
	global_load_dwordx4 v[56:59], v[66:67], off offset:96
	global_load_dwordx4 v[60:63], v[66:67], off offset:112
	s_waitcnt vmcnt(6)
	v_pk_add_f32 v[34:35], v[34:35], v[38:39]
	global_load_dwordx4 v[64:67], v[64:65], off
	v_pk_add_f32 v[32:33], v[32:33], v[36:37]
	s_waitcnt vmcnt(6)
	v_pk_add_f32 v[34:35], v[34:35], v[42:43]
	v_pk_add_f32 v[32:33], v[32:33], v[40:41]
	s_waitcnt vmcnt(5)
	v_pk_add_f32 v[34:35], v[34:35], v[46:47]
	v_pk_add_f32 v[32:33], v[32:33], v[44:45]
	s_waitcnt vmcnt(4)
	v_pk_add_f32 v[34:35], v[34:35], v[50:51]
	v_pk_add_f32 v[32:33], v[32:33], v[48:49]
	s_waitcnt vmcnt(3)
	v_pk_add_f32 v[34:35], v[34:35], v[54:55]
	v_pk_add_f32 v[32:33], v[32:33], v[52:53]
	s_waitcnt vmcnt(2)
	v_pk_add_f32 v[34:35], v[34:35], v[58:59]
	v_pk_add_f32 v[32:33], v[32:33], v[56:57]
	s_waitcnt vmcnt(1)
	v_pk_add_f32 v[34:35], v[34:35], v[62:63]
	v_pk_add_f32 v[32:33], v[32:33], v[60:61]
	ds_read_b128 v[68:71], v26
	ds_read_b128 v[72:75], v26 offset:8192
	ds_read_b128 v[76:79], v26 offset:16384
	ds_read_b128 v[80:83], v26 offset:24576
	ds_read_b128 v[84:87], v26 offset:32768
	ds_read_b128 v[88:91], v26 offset:40960
	ds_read_b128 v[92:95], v26 offset:49152
	ds_read_b128 v[96:99], v26 offset:57344
	v_pk_mov_b32 v[36:37], v[32:33], v[34:35] op_sel:[1,0]
	v_mov_b32_e32 v33, v35
	v_pk_add_f32 v[32:33], v[36:37], v[32:33]
	s_waitcnt lgkmcnt(6)
	v_pk_add_f32 v[70:71], v[70:71], v[74:75]
	v_add_f32_e32 v32, v32, v33
	v_fmamk_f32 v32, v32, 0x3a000000, v28
	v_mul_f32_e32 v33, 0x4b800000, v32
	v_cmp_gt_f32_e32 vcc, s2, v32
	v_pk_add_f32 v[68:69], v[68:69], v[72:73]
	s_waitcnt lgkmcnt(5)
	v_pk_add_f32 v[70:71], v[70:71], v[78:79]
	v_cndmask_b32_e32 v32, v32, v33, vcc
	v_pk_add_f32 v[68:69], v[68:69], v[76:77]
	v_rsq_f32_e32 v32, v32
	s_waitcnt lgkmcnt(4)
	v_pk_add_f32 v[70:71], v[70:71], v[82:83]
	v_pk_add_f32 v[68:69], v[68:69], v[80:81]
	s_waitcnt lgkmcnt(3)
	v_pk_add_f32 v[70:71], v[70:71], v[86:87]
	v_pk_add_f32 v[68:69], v[68:69], v[84:85]
	s_waitcnt lgkmcnt(2)
	v_pk_add_f32 v[70:71], v[70:71], v[90:91]
	v_pk_add_f32 v[68:69], v[68:69], v[88:89]
	s_waitcnt lgkmcnt(1)
	v_pk_add_f32 v[70:71], v[70:71], v[94:95]
	v_pk_add_f32 v[68:69], v[68:69], v[92:93]
	v_mul_f32_e32 v33, 0x45800000, v32
	s_waitcnt lgkmcnt(0)
	v_pk_add_f32 v[70:71], v[70:71], v[98:99]
	v_pk_add_f32 v[68:69], v[68:69], v[96:97]
	v_cndmask_b32_e32 v32, v32, v33, vcc
	s_waitcnt vmcnt(0)
	v_pk_fma_f32 v[34:35], v[70:71], v[32:33], v[66:67] op_sel_hi:[1,0,1]
	v_pk_fma_f32 v[32:33], v[68:69], v[32:33], v[64:65] op_sel_hi:[1,0,1]
	global_store_dwordx4 v[100:101], v[32:35], off sc1
	s_barrier
	s_cbranch_scc1 .LBB0_2413

.LBB0_2471:
	s_or_b64 exec, exec, s[60:61]
	s_and_b32 s54, s57, 0xffffffc0
	s_lshl_b32 s60, s82, 25
	s_add_u32 s64, s67, s60
	s_addc_u32 s65, s68, 0
	s_add_u32 s62, s69, s60
	s_addc_u32 s63, s86, 0
	s_lshl_b64 s[60:61], s[38:39], 13
	s_cmp_eq_u32 s82, 0
	s_cselect_b64 vcc, -1, 0
	v_mul_f32_e32 v2, 0x3d800000, v2
	v_mul_f32_e32 v121, 0x3d800000, v99
	v_mul_f32_e32 v138, 0x3d800000, v112
	v_mul_f32_e32 v139, 0x3d800000, v113
	v_mul_f32_e32 v113, 0x3d800000, v115
	v_mul_f32_e32 v112, 0x3d800000, v116
	v_mul_f32_e32 v99, 0x3d800000, v145
	v_cndmask_b32_e64 v115, 0, v144, s[2:3]
	v_cndmask_b32_e64 v116, 0, v144, s[0:1]
	s_and_b64 s[38:39], vcc, exec
	v_cndmask_b32_e32 v115, v116, v115, vcc
	s_cselect_b32 s38, 0, 31
	v_cndmask_b32_e32 v116, v99, v2, vcc
	v_add_f32_e32 v115, v115, v116
	v_or_b32_e32 v116, s38, v73
	v_mul_f32_e32 v137, 0x3d800000, v111
	v_mul_f32_e32 v111, 0x3d800000, v117
	v_mad_u32_u24 v117, v116, s66, v74
	v_mul_f32_e32 v134, 0x3d800000, v109
	v_mul_f32_e32 v135, 0x3d800000, v110
	v_mul_f32_e32 v110, 0x3d800000, v118
	v_mul_f32_e32 v109, 0x3d800000, v119
	ds_read_u16 v118, v117
	ds_read_u16 v119, v117 offset:33792
	v_mul_f32_e32 v133, 0x3d800000, v108
	v_mul_f32_e32 v108, 0x3d800000, v120
	v_exp_f32_e64 v120, -v115
	s_waitcnt lgkmcnt(1)
	v_lshlrev_b32_e32 v118, 16, v118
	s_waitcnt lgkmcnt(0)
	v_lshlrev_b32_e32 v119, 16, v119
	v_mul_f32_e32 v122, 0x3d800000, v100
	v_mul_f32_e32 v119, v120, v119
	v_exp_f32_e32 v120, v115
	v_mul_f32_e32 v100, 0x3d800000, v143
	v_mad_u32_u24 v116, v116, s66, v75
	s_cselect_b32 s38, 1, 30
	v_mul_f32_e32 v118, v120, v118
	v_cvt_pk_bf16_f32 v118, v118, v119
	v_mul_f32_e32 v119, v98, v119
	v_cvt_pk_bf16_f32 v119, v119, v3
	ds_write_b16 v117, v118
	ds_write_b16_d16_hi v116, v118
	ds_write_b16 v117, v119 offset:33792
	v_cndmask_b32_e32 v116, v100, v121, vcc
	v_add_f32_e32 v115, v116, v115
	v_or_b32_e32 v116, s38, v73
	v_mad_u32_u24 v117, v116, s66, v74
	ds_read_u16 v118, v117
	ds_read_u16 v119, v117 offset:33792
	v_exp_f32_e64 v120, -v115
	v_mul_f32_e32 v124, 0x3d800000, v101
	v_mul_f32_e32 v101, 0x3d800000, v142
	s_waitcnt lgkmcnt(1)
	v_lshlrev_b32_e32 v118, 16, v118
	s_waitcnt lgkmcnt(0)
	v_lshlrev_b32_e32 v119, 16, v119
	v_mul_f32_e32 v119, v120, v119
	v_exp_f32_e32 v120, v115
	v_mad_u32_u24 v116, v116, s66, v75
	s_cselect_b32 s38, 2, 29
	v_mul_f32_e32 v125, 0x3d800000, v102
	v_mul_f32_e32 v118, v120, v118
	v_cvt_pk_bf16_f32 v118, v118, v119
	v_mul_f32_e32 v119, v98, v119
	v_cvt_pk_bf16_f32 v119, v119, v3
	ds_write_b16 v117, v118
	ds_write_b16_d16_hi v116, v118
	ds_write_b16 v117, v119 offset:33792
	v_cndmask_b32_e32 v116, v101, v122, vcc
	v_add_f32_e32 v115, v116, v115
	v_or_b32_e32 v116, s38, v73
	v_mad_u32_u24 v117, v116, s66, v74
	ds_read_u16 v118, v117
	ds_read_u16 v119, v117 offset:33792
	v_exp_f32_e64 v120, -v115
	v_mul_f32_e32 v102, 0x3d800000, v141
	v_mad_u32_u24 v116, v116, s66, v75
	s_waitcnt lgkmcnt(1)
	v_lshlrev_b32_e32 v118, 16, v118
	s_waitcnt lgkmcnt(0)
	v_lshlrev_b32_e32 v119, 16, v119
	v_mul_f32_e32 v119, v120, v119
	v_exp_f32_e32 v120, v115
	s_cselect_b32 s38, 3, 28
	v_mul_f32_e32 v126, 0x3d800000, v103
	v_mul_f32_e32 v103, 0x3d800000, v140
	v_mul_f32_e32 v118, v120, v118
	v_cvt_pk_bf16_f32 v118, v118, v119
	v_mul_f32_e32 v119, v98, v119
	v_cvt_pk_bf16_f32 v119, v119, v3
	ds_write_b16 v117, v118
	ds_write_b16_d16_hi v116, v118
	ds_write_b16 v117, v119 offset:33792
	v_cndmask_b32_e32 v116, v102, v124, vcc
	v_add_f32_e32 v115, v116, v115
	v_or_b32_e32 v116, s38, v73
	v_mad_u32_u24 v117, v116, s66, v74
	ds_read_u16 v118, v117
	ds_read_u16 v119, v117 offset:33792
	v_exp_f32_e64 v120, -v115
	v_mad_u32_u24 v116, v116, s66, v75
	s_cselect_b32 s38, 4, 27
	s_waitcnt lgkmcnt(1)
	v_lshlrev_b32_e32 v118, 16, v118
	s_waitcnt lgkmcnt(0)
	v_lshlrev_b32_e32 v119, 16, v119
	v_mul_f32_e32 v119, v120, v119
	v_exp_f32_e32 v120, v115
	v_mul_f32_e32 v128, 0x3d800000, v104
	v_mul_f32_e32 v104, 0x3d800000, v136
	v_mul_f32_e32 v129, 0x3d800000, v105
	v_mul_f32_e32 v118, v120, v118
	v_cvt_pk_bf16_f32 v118, v118, v119
	v_mul_f32_e32 v119, v98, v119
	v_cvt_pk_bf16_f32 v119, v119, v3
	ds_write_b16 v117, v118
	ds_write_b16_d16_hi v116, v118
	ds_write_b16 v117, v119 offset:33792
	v_cndmask_b32_e32 v116, v103, v125, vcc
	v_add_f32_e32 v115, v116, v115
	v_or_b32_e32 v116, s38, v73
	v_mad_u32_u24 v117, v116, s66, v74
	ds_read_u16 v118, v117
	ds_read_u16 v119, v117 offset:33792
	v_exp_f32_e64 v120, -v115
	v_mad_u32_u24 v116, v116, s66, v75
	s_cselect_b32 s38, 5, 26
	s_waitcnt lgkmcnt(1)
	v_lshlrev_b32_e32 v118, 16, v118
	s_waitcnt lgkmcnt(0)
	v_lshlrev_b32_e32 v119, 16, v119
	v_mul_f32_e32 v119, v120, v119
	v_exp_f32_e32 v120, v115
	v_mul_f32_e32 v105, 0x3d800000, v132
	v_mul_f32_e32 v130, 0x3d800000, v106
	v_mul_f32_e32 v106, 0x3d800000, v127
	v_mul_f32_e32 v118, v120, v118
	v_cvt_pk_bf16_f32 v118, v118, v119
	v_mul_f32_e32 v119, v98, v119
	v_cvt_pk_bf16_f32 v119, v119, v3
	ds_write_b16 v117, v118
	ds_write_b16_d16_hi v116, v118
	ds_write_b16 v117, v119 offset:33792
	v_cndmask_b32_e32 v116, v104, v126, vcc
	v_add_f32_e32 v115, v116, v115
	v_or_b32_e32 v116, s38, v73
	v_mad_u32_u24 v117, v116, s66, v74
	ds_read_u16 v118, v117
	ds_read_u16 v119, v117 offset:33792
	v_exp_f32_e64 v120, -v115
	v_mad_u32_u24 v116, v116, s66, v75
	s_cselect_b32 s38, 6, 25
	s_waitcnt lgkmcnt(1)
	v_lshlrev_b32_e32 v118, 16, v118
	s_waitcnt lgkmcnt(0)
	v_lshlrev_b32_e32 v119, 16, v119
	v_mul_f32_e32 v119, v120, v119
	v_exp_f32_e32 v120, v115
	v_mul_f32_e32 v131, 0x3d800000, v107
	v_mul_f32_e32 v107, 0x3d800000, v123
	v_mul_f32_e32 v114, 0x3d800000, v114
	v_mul_f32_e32 v118, v120, v118
	v_cvt_pk_bf16_f32 v118, v118, v119
	v_mul_f32_e32 v119, v98, v119
	v_cvt_pk_bf16_f32 v119, v119, v3
	ds_write_b16 v117, v118
	ds_write_b16_d16_hi v116, v118
	ds_write_b16 v117, v119 offset:33792
	v_cndmask_b32_e32 v116, v105, v128, vcc
	v_add_f32_e32 v115, v116, v115
	v_or_b32_e32 v116, s38, v73
	v_mad_u32_u24 v117, v116, s66, v74
	ds_read_u16 v118, v117
	ds_read_u16 v119, v117 offset:33792
	v_exp_f32_e64 v120, -v115
	v_mad_u32_u24 v116, v116, s66, v75
	s_cselect_b32 s38, 7, 24
	s_waitcnt lgkmcnt(1)
	v_lshlrev_b32_e32 v118, 16, v118
	s_waitcnt lgkmcnt(0)
	v_lshlrev_b32_e32 v119, 16, v119
	v_mul_f32_e32 v119, v120, v119
	v_exp_f32_e32 v120, v115
	v_cndmask_b32_e32 v105, v128, v105, vcc
	v_cndmask_b32_e32 v104, v126, v104, vcc
	v_cndmask_b32_e32 v103, v125, v103, vcc
	v_mul_f32_e32 v118, v120, v118
	v_cvt_pk_bf16_f32 v118, v118, v119
	v_mul_f32_e32 v119, v98, v119
	v_cvt_pk_bf16_f32 v119, v119, v3
	ds_write_b16 v117, v118
	ds_write_b16_d16_hi v116, v118
	ds_write_b16 v117, v119 offset:33792
	v_cndmask_b32_e32 v116, v106, v129, vcc
	v_add_f32_e32 v115, v116, v115
	v_or_b32_e32 v116, s38, v73
	v_mad_u32_u24 v117, v116, s66, v74
	ds_read_u16 v118, v117
	ds_read_u16 v119, v117 offset:33792
	v_exp_f32_e64 v120, -v115
	v_mad_u32_u24 v116, v116, s66, v75
	s_cselect_b32 s38, 8, 23
	s_waitcnt lgkmcnt(1)
	v_lshlrev_b32_e32 v118, 16, v118
	s_waitcnt lgkmcnt(0)
	v_lshlrev_b32_e32 v119, 16, v119
	v_mul_f32_e32 v119, v120, v119
	v_exp_f32_e32 v120, v115
	v_cndmask_b32_e32 v106, v129, v106, vcc
	v_cndmask_b32_e32 v102, v124, v102, vcc
	v_cndmask_b32_e32 v101, v122, v101, vcc
	v_mul_f32_e32 v118, v120, v118
	v_cvt_pk_bf16_f32 v118, v118, v119
	v_mul_f32_e32 v119, v98, v119
	v_cvt_pk_bf16_f32 v119, v119, v3
	ds_write_b16 v117, v118
	ds_write_b16_d16_hi v116, v118
	ds_write_b16 v117, v119 offset:33792
	v_cndmask_b32_e32 v116, v107, v130, vcc
	v_add_f32_e32 v115, v116, v115
	v_or_b32_e32 v116, s38, v73
	v_mad_u32_u24 v117, v116, s66, v74
	ds_read_u16 v118, v117
	ds_read_u16 v119, v117 offset:33792
	v_exp_f32_e64 v120, -v115
	v_mad_u32_u24 v116, v116, s66, v75
	s_cselect_b32 s38, 9, 22
	s_waitcnt lgkmcnt(1)
	v_lshlrev_b32_e32 v118, 16, v118
	s_waitcnt lgkmcnt(0)
	v_lshlrev_b32_e32 v119, 16, v119
	v_mul_f32_e32 v119, v120, v119
	v_exp_f32_e32 v120, v115
	v_cndmask_b32_e32 v107, v130, v107, vcc
	v_cndmask_b32_e32 v100, v121, v100, vcc
	v_cndmask_b32_e32 v2, v2, v99, vcc
	v_mul_f32_e32 v118, v120, v118
	v_cvt_pk_bf16_f32 v118, v118, v119
	v_mul_f32_e32 v119, v98, v119
	v_cvt_pk_bf16_f32 v119, v119, v3
	ds_write_b16 v117, v118
	ds_write_b16_d16_hi v116, v118
	ds_write_b16 v117, v119 offset:33792
	v_cndmask_b32_e32 v116, v108, v131, vcc
	v_add_f32_e32 v115, v116, v115
	v_or_b32_e32 v116, s38, v73
	v_mad_u32_u24 v117, v116, s66, v74
	ds_read_u16 v118, v117
	ds_read_u16 v119, v117 offset:33792
	v_exp_f32_e64 v120, -v115
	v_mad_u32_u24 v116, v116, s66, v75
	s_cselect_b32 s38, 10, 21
	s_waitcnt lgkmcnt(1)
	v_lshlrev_b32_e32 v118, 16, v118
	s_waitcnt lgkmcnt(0)
	v_lshlrev_b32_e32 v119, 16, v119
	v_mul_f32_e32 v119, v120, v119
	v_exp_f32_e32 v120, v115
	v_cndmask_b32_e32 v108, v131, v108, vcc
	v_mul_f32_e32 v118, v120, v118
	v_cvt_pk_bf16_f32 v118, v118, v119
	v_mul_f32_e32 v119, v98, v119
	v_cvt_pk_bf16_f32 v119, v119, v3
	ds_write_b16 v117, v118
	ds_write_b16_d16_hi v116, v118
	ds_write_b16 v117, v119 offset:33792
	v_cndmask_b32_e32 v116, v109, v133, vcc
	v_add_f32_e32 v115, v116, v115
	v_or_b32_e32 v116, s38, v73
	v_mad_u32_u24 v117, v116, s66, v74
	ds_read_u16 v118, v117
	ds_read_u16 v119, v117 offset:33792
	v_exp_f32_e64 v120, -v115
	v_mad_u32_u24 v116, v116, s66, v75
	s_cselect_b32 s38, 11, 20
	s_waitcnt lgkmcnt(1)
	v_lshlrev_b32_e32 v118, 16, v118
	s_waitcnt lgkmcnt(0)
	v_lshlrev_b32_e32 v119, 16, v119
	v_mul_f32_e32 v119, v120, v119
	v_exp_f32_e32 v120, v115
	v_cndmask_b32_e32 v109, v133, v109, vcc
	v_mul_f32_e32 v118, v120, v118
	v_cvt_pk_bf16_f32 v118, v118, v119
	v_mul_f32_e32 v119, v98, v119
	v_cvt_pk_bf16_f32 v119, v119, v3
	ds_write_b16 v117, v118
	ds_write_b16_d16_hi v116, v118
	ds_write_b16 v117, v119 offset:33792
	v_cndmask_b32_e32 v116, v110, v134, vcc
	v_add_f32_e32 v115, v116, v115
	v_or_b32_e32 v116, s38, v73
	v_mad_u32_u24 v117, v116, s66, v74
	ds_read_u16 v118, v117
	ds_read_u16 v119, v117 offset:33792
	v_exp_f32_e64 v120, -v115
	v_mad_u32_u24 v116, v116, s66, v75
	s_cselect_b32 s38, 12, 19
	s_waitcnt lgkmcnt(1)
	v_lshlrev_b32_e32 v118, 16, v118
	s_waitcnt lgkmcnt(0)
	v_lshlrev_b32_e32 v119, 16, v119
	v_mul_f32_e32 v119, v120, v119
	v_exp_f32_e32 v120, v115
	v_cndmask_b32_e32 v110, v134, v110, vcc
	v_mul_f32_e32 v118, v120, v118
	v_cvt_pk_bf16_f32 v118, v118, v119
	v_mul_f32_e32 v119, v98, v119
	v_cvt_pk_bf16_f32 v119, v119, v3
	ds_write_b16 v117, v118
	ds_write_b16_d16_hi v116, v118
	ds_write_b16 v117, v119 offset:33792
	v_cndmask_b32_e32 v116, v111, v135, vcc
	v_add_f32_e32 v115, v116, v115
	v_or_b32_e32 v116, s38, v73
	v_mad_u32_u24 v117, v116, s66, v74
	ds_read_u16 v118, v117
	ds_read_u16 v119, v117 offset:33792
	v_exp_f32_e64 v120, -v115
	v_mad_u32_u24 v116, v116, s66, v75
	s_cselect_b32 s38, 13, 18
	s_waitcnt lgkmcnt(1)
	v_lshlrev_b32_e32 v118, 16, v118
	s_waitcnt lgkmcnt(0)
	v_lshlrev_b32_e32 v119, 16, v119
	v_mul_f32_e32 v119, v120, v119
	v_exp_f32_e32 v120, v115
	v_cndmask_b32_e32 v111, v135, v111, vcc
	v_mul_f32_e32 v118, v120, v118
	v_cvt_pk_bf16_f32 v118, v118, v119
	v_mul_f32_e32 v119, v98, v119
	v_cvt_pk_bf16_f32 v119, v119, v3
	ds_write_b16 v117, v118
	ds_write_b16_d16_hi v116, v118
	ds_write_b16 v117, v119 offset:33792
	v_cndmask_b32_e32 v116, v112, v137, vcc
	v_add_f32_e32 v115, v116, v115
	v_or_b32_e32 v116, s38, v73
	v_mad_u32_u24 v117, v116, s66, v74
	ds_read_u16 v118, v117
	ds_read_u16 v119, v117 offset:33792
	v_exp_f32_e64 v120, -v115
	v_mad_u32_u24 v116, v116, s66, v75
	s_cselect_b32 s38, 14, 17
	s_waitcnt lgkmcnt(1)
	v_lshlrev_b32_e32 v118, 16, v118
	s_waitcnt lgkmcnt(0)
	v_lshlrev_b32_e32 v119, 16, v119
	v_mul_f32_e32 v119, v120, v119
	v_exp_f32_e32 v120, v115
	v_cndmask_b32_e32 v112, v137, v112, vcc
	v_mul_f32_e32 v118, v120, v118
	v_cvt_pk_bf16_f32 v118, v118, v119
	v_mul_f32_e32 v119, v98, v119
	v_cvt_pk_bf16_f32 v119, v119, v3
	ds_write_b16 v117, v118
	ds_write_b16_d16_hi v116, v118
	ds_write_b16 v117, v119 offset:33792
	v_cndmask_b32_e32 v116, v113, v138, vcc
	v_add_f32_e32 v115, v116, v115
	v_or_b32_e32 v116, s38, v73
	v_mad_u32_u24 v117, v116, s66, v74
	ds_read_u16 v118, v117
	ds_read_u16 v119, v117 offset:33792
	v_exp_f32_e64 v120, -v115
	v_mad_u32_u24 v116, v116, s66, v75
	s_cselect_b32 s38, 17, 14
	s_waitcnt lgkmcnt(1)
	v_lshlrev_b32_e32 v118, 16, v118
	s_waitcnt lgkmcnt(0)
	v_lshlrev_b32_e32 v119, 16, v119
	v_mul_f32_e32 v119, v120, v119
	v_exp_f32_e32 v120, v115
	v_cndmask_b32_e32 v113, v138, v113, vcc
	v_mul_f32_e32 v118, v120, v118
	v_cvt_pk_bf16_f32 v118, v118, v119
	v_mul_f32_e32 v119, v98, v119
	v_cvt_pk_bf16_f32 v119, v119, v3
	ds_write_b16 v117, v118
	ds_write_b16_d16_hi v116, v118
	ds_write_b16 v117, v119 offset:33792
	v_cndmask_b32_e32 v116, v114, v139, vcc
	v_add_f32_e32 v115, v116, v115
	v_add_u32_e32 v116, s82, v92
	v_mad_u32_u24 v117, v116, s66, v74
	ds_read_u16 v118, v117
	ds_read_u16 v119, v117 offset:33792
	v_exp_f32_e64 v120, -v115
	v_cndmask_b32_e32 v114, v139, v114, vcc
	v_mad_u32_u24 v116, v116, s66, v75
	s_waitcnt lgkmcnt(1)
	v_lshlrev_b32_e32 v118, 16, v118
	s_waitcnt lgkmcnt(0)
	v_lshlrev_b32_e32 v119, 16, v119
	v_mul_f32_e32 v119, v120, v119
	v_exp_f32_e32 v120, v115
	v_add_f32_e32 v114, v114, v115
	v_subrev_u32_e32 v115, s82, v73
	v_add_f32_e32 v113, v113, v114
	v_mul_f32_e32 v118, v120, v118
	v_cvt_pk_bf16_f32 v118, v118, v119
	v_mul_f32_e32 v119, v98, v119
	v_cvt_pk_bf16_f32 v119, v119, v3
	ds_write_b16 v117, v118
	ds_write_b16_d16_hi v116, v118
	ds_write_b16 v117, v119 offset:33792
	v_mad_i32_i24 v116, v115, s66, v74
	ds_read_u16 v117, v116 offset:8448
	ds_read_u16 v118, v116 offset:42240
	v_exp_f32_e64 v119, -v114
	v_mad_i32_i24 v115, v115, s66, v75
	v_add_f32_e32 v112, v112, v113
	s_waitcnt lgkmcnt(1)
	v_lshlrev_b32_e32 v117, 16, v117
	s_waitcnt lgkmcnt(0)
	v_lshlrev_b32_e32 v118, 16, v118
	v_mul_f32_e32 v118, v119, v118
	v_exp_f32_e32 v119, v114
	v_or_b32_e32 v114, s38, v73
	s_cselect_b32 s38, 18, 13
	v_add_f32_e32 v111, v111, v112
	v_mul_f32_e32 v117, v119, v117
	v_cvt_pk_bf16_f32 v117, v117, v118
	v_mul_f32_e32 v118, v98, v118
	v_cvt_pk_bf16_f32 v118, v118, v3
	ds_write_b16 v116, v117 offset:8448
	ds_write_b16_d16_hi v115, v117 offset:8448
	ds_write_b16 v116, v118 offset:42240
	v_mad_u32_u24 v115, v114, s66, v74
	ds_read_u16 v116, v115
	ds_read_u16 v117, v115 offset:33792
	v_exp_f32_e64 v118, -v113
	v_mad_u32_u24 v114, v114, s66, v75
	v_add_f32_e32 v110, v110, v111
	s_waitcnt lgkmcnt(1)
	v_lshlrev_b32_e32 v116, 16, v116
	s_waitcnt lgkmcnt(0)
	v_lshlrev_b32_e32 v117, 16, v117
	v_mul_f32_e32 v117, v118, v117
	v_exp_f32_e32 v118, v113
	v_or_b32_e32 v113, s38, v73
	s_cselect_b32 s38, 19, 12
	v_add_f32_e32 v109, v109, v110
	v_mul_f32_e32 v116, v118, v116
	v_cvt_pk_bf16_f32 v116, v116, v117
	v_mul_f32_e32 v117, v98, v117
	v_cvt_pk_bf16_f32 v117, v117, v3
	ds_write_b16 v115, v116
	ds_write_b16_d16_hi v114, v116
	ds_write_b16 v115, v117 offset:33792
	v_mad_u32_u24 v114, v113, s66, v74
	ds_read_u16 v115, v114
	ds_read_u16 v116, v114 offset:33792
	v_exp_f32_e64 v117, -v112
	v_mad_u32_u24 v113, v113, s66, v75
	v_add_f32_e32 v108, v108, v109
	s_waitcnt lgkmcnt(1)
	v_lshlrev_b32_e32 v115, 16, v115
	s_waitcnt lgkmcnt(0)
	v_lshlrev_b32_e32 v116, 16, v116
	v_mul_f32_e32 v116, v117, v116
	v_exp_f32_e32 v117, v112
	v_or_b32_e32 v112, s38, v73
	s_cselect_b32 s38, 20, 11
	v_add_f32_e32 v107, v107, v108
	v_mul_f32_e32 v115, v117, v115
	v_cvt_pk_bf16_f32 v115, v115, v116
	v_mul_f32_e32 v116, v98, v116
	v_cvt_pk_bf16_f32 v116, v116, v3
	ds_write_b16 v114, v115
	ds_write_b16_d16_hi v113, v115
	ds_write_b16 v114, v116 offset:33792
	v_mad_u32_u24 v113, v112, s66, v74
	ds_read_u16 v114, v113
	ds_read_u16 v115, v113 offset:33792
	v_exp_f32_e64 v116, -v111
	v_mad_u32_u24 v112, v112, s66, v75
	v_add_f32_e32 v106, v106, v107
	s_waitcnt lgkmcnt(1)
	v_lshlrev_b32_e32 v114, 16, v114
	s_waitcnt lgkmcnt(0)
	v_lshlrev_b32_e32 v115, 16, v115
	v_mul_f32_e32 v115, v116, v115
	v_exp_f32_e32 v116, v111
	v_or_b32_e32 v111, s38, v73
	s_cselect_b32 s38, 21, 10
	v_add_f32_e32 v105, v105, v106
	v_mul_f32_e32 v114, v116, v114
	v_cvt_pk_bf16_f32 v114, v114, v115
	v_mul_f32_e32 v115, v98, v115
	v_cvt_pk_bf16_f32 v115, v115, v3
	ds_write_b16 v113, v114
	ds_write_b16_d16_hi v112, v114
	ds_write_b16 v113, v115 offset:33792
	v_mad_u32_u24 v112, v111, s66, v74
	ds_read_u16 v113, v112
	ds_read_u16 v114, v112 offset:33792
	v_exp_f32_e64 v115, -v110
	v_mad_u32_u24 v111, v111, s66, v75
	v_add_f32_e32 v104, v104, v105
	s_waitcnt lgkmcnt(1)
	v_lshlrev_b32_e32 v113, 16, v113
	s_waitcnt lgkmcnt(0)
	v_lshlrev_b32_e32 v114, 16, v114
	v_mul_f32_e32 v114, v115, v114
	v_exp_f32_e32 v115, v110
	v_or_b32_e32 v110, s38, v73
	s_cselect_b32 s38, 22, 9
	v_add_f32_e32 v103, v103, v104
	v_mul_f32_e32 v113, v115, v113
	v_cvt_pk_bf16_f32 v113, v113, v114
	v_mul_f32_e32 v114, v98, v114
	v_cvt_pk_bf16_f32 v114, v114, v3
	ds_write_b16 v112, v113
	ds_write_b16_d16_hi v111, v113
	ds_write_b16 v112, v114 offset:33792
	v_mad_u32_u24 v111, v110, s66, v74
	ds_read_u16 v112, v111
	ds_read_u16 v113, v111 offset:33792
	v_exp_f32_e64 v114, -v109
	v_mad_u32_u24 v110, v110, s66, v75
	v_add_f32_e32 v102, v102, v103
	s_waitcnt lgkmcnt(1)
	v_lshlrev_b32_e32 v112, 16, v112
	s_waitcnt lgkmcnt(0)
	v_lshlrev_b32_e32 v113, 16, v113
	v_mul_f32_e32 v113, v114, v113
	v_exp_f32_e32 v114, v109
	v_or_b32_e32 v109, s38, v73
	s_cselect_b32 s38, 23, 8
	v_add_f32_e32 v101, v101, v102
	v_mul_f32_e32 v112, v114, v112
	v_cvt_pk_bf16_f32 v112, v112, v113
	v_mul_f32_e32 v113, v98, v113
	v_cvt_pk_bf16_f32 v113, v113, v3
	ds_write_b16 v111, v112
	ds_write_b16_d16_hi v110, v112
	ds_write_b16 v111, v113 offset:33792
	v_mad_u32_u24 v110, v109, s66, v74
	ds_read_u16 v111, v110
	ds_read_u16 v112, v110 offset:33792
	v_exp_f32_e64 v113, -v108
	v_mad_u32_u24 v109, v109, s66, v75
	v_add_f32_e32 v100, v100, v101
	s_waitcnt lgkmcnt(1)
	v_lshlrev_b32_e32 v111, 16, v111
	s_waitcnt lgkmcnt(0)
	v_lshlrev_b32_e32 v112, 16, v112
	v_mul_f32_e32 v112, v113, v112
	v_exp_f32_e32 v113, v108
	v_or_b32_e32 v108, s38, v73
	s_cselect_b32 s38, 24, 7
	v_add_f32_e32 v2, v2, v100
	v_mul_f32_e32 v111, v113, v111
	v_cvt_pk_bf16_f32 v111, v111, v112
	v_mul_f32_e32 v112, v98, v112
	v_cvt_pk_bf16_f32 v112, v112, v3
	ds_write_b16 v110, v111
	ds_write_b16_d16_hi v109, v111
	ds_write_b16 v110, v112 offset:33792
	v_mad_u32_u24 v109, v108, s66, v74
	ds_read_u16 v110, v109
	ds_read_u16 v111, v109 offset:33792
	v_exp_f32_e64 v112, -v107
	v_mad_u32_u24 v108, v108, s66, v75
	s_waitcnt lgkmcnt(1)
	v_lshlrev_b32_e32 v110, 16, v110
	s_waitcnt lgkmcnt(0)
	v_lshlrev_b32_e32 v111, 16, v111
	v_mul_f32_e32 v111, v112, v111
	v_exp_f32_e32 v112, v107
	v_or_b32_e32 v107, s38, v73
	s_cselect_b32 s38, 25, 6
	v_mul_f32_e32 v110, v112, v110
	v_cvt_pk_bf16_f32 v110, v110, v111
	v_mul_f32_e32 v111, v98, v111
	v_cvt_pk_bf16_f32 v111, v111, v3
	ds_write_b16 v109, v110
	ds_write_b16_d16_hi v108, v110
	ds_write_b16 v109, v111 offset:33792
	v_mad_u32_u24 v108, v107, s66, v74
	ds_read_u16 v109, v108
	ds_read_u16 v110, v108 offset:33792
	v_exp_f32_e64 v111, -v106
	v_mad_u32_u24 v107, v107, s66, v75
	s_waitcnt lgkmcnt(1)
	v_lshlrev_b32_e32 v109, 16, v109
	s_waitcnt lgkmcnt(0)
	v_lshlrev_b32_e32 v110, 16, v110
	v_mul_f32_e32 v110, v111, v110
	v_exp_f32_e32 v111, v106
	v_or_b32_e32 v106, s38, v73
	s_cselect_b32 s38, 26, 5
	v_mul_f32_e32 v109, v111, v109
	v_cvt_pk_bf16_f32 v109, v109, v110
	v_mul_f32_e32 v110, v98, v110
	v_cvt_pk_bf16_f32 v110, v110, v3
	ds_write_b16 v108, v109
	ds_write_b16_d16_hi v107, v109
	ds_write_b16 v108, v110 offset:33792
	v_mad_u32_u24 v107, v106, s66, v74
	ds_read_u16 v108, v107
	ds_read_u16 v109, v107 offset:33792
	v_exp_f32_e64 v110, -v105
	v_mad_u32_u24 v106, v106, s66, v75
	s_waitcnt lgkmcnt(1)
	v_lshlrev_b32_e32 v108, 16, v108
	s_waitcnt lgkmcnt(0)
	v_lshlrev_b32_e32 v109, 16, v109
	v_mul_f32_e32 v109, v110, v109
	v_exp_f32_e32 v110, v105
	v_or_b32_e32 v105, s38, v73
	s_cselect_b32 s38, 27, 4
	v_mul_f32_e32 v108, v110, v108
	v_cvt_pk_bf16_f32 v108, v108, v109
	v_mul_f32_e32 v109, v98, v109
	v_cvt_pk_bf16_f32 v109, v109, v3
	ds_write_b16 v107, v108
	ds_write_b16_d16_hi v106, v108
	ds_write_b16 v107, v109 offset:33792
	v_mad_u32_u24 v106, v105, s66, v74
	ds_read_u16 v107, v106
	ds_read_u16 v108, v106 offset:33792
	v_exp_f32_e64 v109, -v104
	v_mad_u32_u24 v105, v105, s66, v75
	s_waitcnt lgkmcnt(1)
	v_lshlrev_b32_e32 v107, 16, v107
	s_waitcnt lgkmcnt(0)
	v_lshlrev_b32_e32 v108, 16, v108
	v_mul_f32_e32 v108, v109, v108
	v_exp_f32_e32 v109, v104
	v_or_b32_e32 v104, s38, v73
	s_cselect_b32 s38, 28, 3
	v_mul_f32_e32 v107, v109, v107
	v_cvt_pk_bf16_f32 v107, v107, v108
	v_mul_f32_e32 v108, v98, v108
	v_cvt_pk_bf16_f32 v108, v108, v3
	ds_write_b16 v106, v107
	ds_write_b16_d16_hi v105, v107
	ds_write_b16 v106, v108 offset:33792
	v_mad_u32_u24 v105, v104, s66, v74
	ds_read_u16 v106, v105
	ds_read_u16 v107, v105 offset:33792
	v_exp_f32_e64 v108, -v103
	v_mad_u32_u24 v104, v104, s66, v75
	s_waitcnt lgkmcnt(1)
	v_lshlrev_b32_e32 v106, 16, v106
	s_waitcnt lgkmcnt(0)
	v_lshlrev_b32_e32 v107, 16, v107
	v_mul_f32_e32 v107, v108, v107
	v_exp_f32_e32 v108, v103
	v_or_b32_e32 v103, s38, v73
	s_cselect_b32 s38, 29, 2
	v_mul_f32_e32 v106, v108, v106
	v_cvt_pk_bf16_f32 v106, v106, v107
	v_mul_f32_e32 v107, v98, v107
	v_cvt_pk_bf16_f32 v107, v107, v3
	ds_write_b16 v105, v106
	ds_write_b16_d16_hi v104, v106
	ds_write_b16 v105, v107 offset:33792
	v_mad_u32_u24 v104, v103, s66, v74
	ds_read_u16 v105, v104
	ds_read_u16 v106, v104 offset:33792
	v_exp_f32_e64 v107, -v102
	v_mad_u32_u24 v103, v103, s66, v75
	s_waitcnt lgkmcnt(1)
	v_lshlrev_b32_e32 v105, 16, v105
	s_waitcnt lgkmcnt(0)
	v_lshlrev_b32_e32 v106, 16, v106
	v_mul_f32_e32 v106, v107, v106
	v_exp_f32_e32 v107, v102
	v_or_b32_e32 v102, s38, v73
	s_cselect_b32 s38, 30, 1
	v_mul_f32_e32 v105, v107, v105
	v_cvt_pk_bf16_f32 v105, v105, v106
	v_mul_f32_e32 v106, v98, v106
	v_cvt_pk_bf16_f32 v106, v106, v3
	ds_write_b16 v104, v105
	ds_write_b16_d16_hi v103, v105
	ds_write_b16 v104, v106 offset:33792
	v_mad_u32_u24 v103, v102, s66, v74
	ds_read_u16 v104, v103
	ds_read_u16 v105, v103 offset:33792
	v_exp_f32_e64 v106, -v101
	v_mad_u32_u24 v102, v102, s66, v75
	s_waitcnt lgkmcnt(1)
	v_lshlrev_b32_e32 v104, 16, v104
	s_waitcnt lgkmcnt(0)
	v_lshlrev_b32_e32 v105, 16, v105
	v_mul_f32_e32 v105, v106, v105
	v_exp_f32_e32 v106, v101
	v_or_b32_e32 v101, s38, v73
	s_cselect_b32 s38, 31, 0
	v_or_b32_e32 v99, s38, v73
	v_mul_f32_e32 v104, v106, v104
	v_cvt_pk_bf16_f32 v104, v104, v105
	v_mul_f32_e32 v105, v98, v105
	v_cvt_pk_bf16_f32 v105, v105, v3
	ds_write_b16 v103, v104
	ds_write_b16_d16_hi v102, v104
	ds_write_b16 v103, v105 offset:33792
	v_mad_u32_u24 v102, v101, s66, v74
	ds_read_u16 v103, v102
	ds_read_u16 v104, v102 offset:33792
	v_exp_f32_e64 v105, -v100
	v_mad_u32_u24 v101, v101, s66, v75
	s_add_i32 s57, s57, s87
	s_waitcnt lgkmcnt(1)
	v_lshlrev_b32_e32 v103, 16, v103
	s_waitcnt lgkmcnt(0)
	v_lshlrev_b32_e32 v104, 16, v104
	v_mul_f32_e32 v104, v105, v104
	v_exp_f32_e32 v105, v100
	v_mad_u32_u24 v100, v99, s66, v74
	v_mad_u32_u24 v99, v99, s66, v75
	s_add_i32 s90, s90, s91
	v_mul_f32_e32 v103, v105, v103
	v_cvt_pk_bf16_f32 v103, v103, v104
	v_mul_f32_e32 v104, v98, v104
	v_cvt_pk_bf16_f32 v104, v104, v3
	ds_write_b16 v102, v103
	ds_write_b16_d16_hi v101, v103
	ds_write_b16 v102, v104 offset:33792
	ds_read_u16 v101, v100
	ds_read_u16 v102, v100 offset:33792
	v_exp_f32_e64 v103, -v2
	v_exp_f32_e32 v2, v2
	s_add_i32 s92, s92, s93
	s_waitcnt lgkmcnt(1)
	v_lshlrev_b32_e32 v101, 16, v101
	s_waitcnt lgkmcnt(0)
	v_lshlrev_b32_e32 v102, 16, v102
	v_mul_f32_e32 v102, v103, v102
	v_mul_f32_e32 v2, v2, v101
	v_mul_f32_e32 v98, v98, v102
	v_cvt_pk_bf16_f32 v2, v2, v102
	v_cvt_pk_bf16_f32 v98, v98, v3
	ds_write_b16 v100, v2
	ds_write_b16_d16_hi v99, v2
	ds_write_b16 v100, v98 offset:33792
	s_waitcnt lgkmcnt(0)
	s_barrier
	ds_read_b128 v[98:101], v94
	v_add_u32_e32 v2, v82, v76
	ds_read_b128 v[102:105], v2
	s_waitcnt lgkmcnt(0)
	v_mfma_f32_16x16x32_bf16 v[98:101], v[98:101], v[102:105], 0
	ds_read_b128 v[102:105], v94 offset:64
	ds_read_b128 v[106:109], v2 offset:64
	s_waitcnt lgkmcnt(0)
	v_mfma_f32_16x16x32_bf16 v[98:101], v[102:105], v[106:109], v[98:101]
	ds_read_b128 v[102:105], v94 offset:128
	ds_read_b128 v[106:109], v2 offset:128
	s_waitcnt lgkmcnt(0)
	v_mfma_f32_16x16x32_bf16 v[98:101], v[102:105], v[106:109], v[98:101]
	ds_read_b128 v[102:105], v94 offset:192
	ds_read_b128 v[106:109], v2 offset:192
	s_waitcnt lgkmcnt(0)
	v_mfma_f32_16x16x32_bf16 v[98:101], v[102:105], v[106:109], v[98:101]
	ds_read_b128 v[102:105], v94 offset:256
	ds_read_b128 v[106:109], v2 offset:256
	s_waitcnt lgkmcnt(0)
	v_mfma_f32_16x16x32_bf16 v[98:101], v[102:105], v[106:109], v[98:101]
	ds_read_b128 v[102:105], v94 offset:320
	ds_read_b128 v[106:109], v2 offset:320
	s_waitcnt lgkmcnt(0)
	v_mfma_f32_16x16x32_bf16 v[98:101], v[102:105], v[106:109], v[98:101]
	ds_read_b128 v[102:105], v94 offset:384
	ds_read_b128 v[106:109], v2 offset:384
	s_waitcnt lgkmcnt(0)
	v_mfma_f32_16x16x32_bf16 v[98:101], v[102:105], v[106:109], v[98:101]
	ds_read_b128 v[102:105], v94 offset:448
	ds_read_b128 v[106:109], v2 offset:448
	v_cndmask_b32_e64 v2, 0, 1, s[42:43]
	s_waitcnt lgkmcnt(0)
	v_mfma_f32_16x16x32_bf16 v[98:101], v[102:105], v[106:109], v[98:101]
	v_cndmask_b32_e64 v102, 0, 1, s[84:85]
	v_cndmask_b32_e32 v2, v102, v2, vcc
	v_and_b32_e32 v2, 1, v2
	v_cmp_eq_u32_e64 s[38:39], 1, v2
	s_nop 3
	v_cndmask_b32_e64 v2, 0, v98, s[38:39]
	v_bfe_u32 v98, v2, 16, 1
	v_add3_u32 v2, v2, v98, s88
	v_add_u32_e32 v98, v83, v84
	ds_write_b16_d16_hi v98, v2
	v_cndmask_b32_e64 v2, 0, 1, s[94:95]
	v_cndmask_b32_e64 v98, 0, 1, s[50:51]
	v_cndmask_b32_e32 v2, v98, v2, vcc
	v_and_b32_e32 v2, 1, v2
	v_cmp_eq_u32_e64 s[38:39], 1, v2
	s_nop 1
	v_cndmask_b32_e64 v2, 0, v99, s[38:39]
	v_bfe_u32 v98, v2, 16, 1
	v_add3_u32 v2, v2, v98, s88
	v_add_u32_e32 v98, v83, v85
	ds_write_b16_d16_hi v98, v2
	v_cndmask_b32_e64 v2, 0, 1, s[12:13]
	v_cndmask_b32_e64 v98, 0, 1, s[14:15]
	v_cndmask_b32_e32 v2, v98, v2, vcc
	v_and_b32_e32 v2, 1, v2
	v_cmp_eq_u32_e64 s[38:39], 1, v2
	s_nop 1
	v_cndmask_b32_e64 v2, 0, v100, s[38:39]
	v_bfe_u32 v98, v2, 16, 1
	v_add3_u32 v2, v2, v98, s88
	v_add_u32_e32 v98, v83, v86
	ds_write_b16_d16_hi v98, v2
	v_cndmask_b32_e64 v2, 0, 1, s[16:17]
	v_cndmask_b32_e64 v98, 0, 1, s[18:19]
	v_cndmask_b32_e32 v2, v98, v2, vcc
	v_and_b32_e32 v2, 1, v2
	v_cmp_eq_u32_e64 s[38:39], 1, v2
	s_nop 1
	v_cndmask_b32_e64 v2, 0, v101, s[38:39]
	v_bfe_u32 v98, v2, 16, 1
	v_add3_u32 v2, v2, v98, s88
	v_add_u32_e32 v98, v83, v87
	ds_write_b16_d16_hi v98, v2
	ds_read_b128 v[98:101], v94
	ds_read_b128 v[102:105], v95
	s_waitcnt lgkmcnt(0)
	v_mfma_f32_16x16x32_bf16 v[98:101], v[98:101], v[102:105], 0
	ds_read_b128 v[102:105], v94 offset:64
	ds_read_b128 v[106:109], v95 offset:64
	v_cndmask_b32_e64 v2, 0, 1, s[20:21]
	s_waitcnt lgkmcnt(0)
	v_mfma_f32_16x16x32_bf16 v[98:101], v[102:105], v[106:109], v[98:101]
	ds_read_b128 v[102:105], v94 offset:128
	ds_read_b128 v[106:109], v95 offset:128
	s_waitcnt lgkmcnt(0)
	v_mfma_f32_16x16x32_bf16 v[98:101], v[102:105], v[106:109], v[98:101]
	ds_read_b128 v[102:105], v94 offset:192
	ds_read_b128 v[106:109], v95 offset:192
	s_waitcnt lgkmcnt(0)
	v_mfma_f32_16x16x32_bf16 v[98:101], v[102:105], v[106:109], v[98:101]
	ds_read_b128 v[102:105], v94 offset:256
	ds_read_b128 v[106:109], v95 offset:256
	s_waitcnt lgkmcnt(0)
	v_mfma_f32_16x16x32_bf16 v[98:101], v[102:105], v[106:109], v[98:101]
	ds_read_b128 v[102:105], v94 offset:320
	ds_read_b128 v[106:109], v95 offset:320
	s_waitcnt lgkmcnt(0)
	v_mfma_f32_16x16x32_bf16 v[98:101], v[102:105], v[106:109], v[98:101]
	ds_read_b128 v[102:105], v94 offset:384
	ds_read_b128 v[106:109], v95 offset:384
	s_waitcnt lgkmcnt(0)
	v_mfma_f32_16x16x32_bf16 v[98:101], v[102:105], v[106:109], v[98:101]
	ds_read_b128 v[102:105], v94 offset:448
	ds_read_b128 v[106:109], v95 offset:448
	s_waitcnt lgkmcnt(0)
	v_mfma_f32_16x16x32_bf16 v[98:101], v[102:105], v[106:109], v[98:101]
	v_cndmask_b32_e64 v102, 0, 1, s[22:23]
	v_cndmask_b32_e32 v2, v102, v2, vcc
	v_and_b32_e32 v2, 1, v2
	v_cmp_eq_u32_e64 s[38:39], 1, v2
	v_or_b32_e32 v102, s54, v64
	v_ashrrev_i32_e32 v103, 31, v102
	s_nop 1
	v_cndmask_b32_e64 v2, 0, v98, s[38:39]
	v_bfe_u32 v98, v2, 16, 1
	v_add3_u32 v2, v2, v98, s88
	ds_write_b16_d16_hi v88, v2
	v_cndmask_b32_e64 v2, 0, 1, s[24:25]
	v_cndmask_b32_e64 v98, 0, 1, s[26:27]
	v_cndmask_b32_e32 v2, v98, v2, vcc
	v_and_b32_e32 v2, 1, v2
	v_cmp_eq_u32_e64 s[38:39], 1, v2
	v_lshlrev_b64 v[102:103], 11, v[102:103]
	v_lshl_or_b32 v106, s81, 9, v96
	v_cndmask_b32_e64 v2, 0, v99, s[38:39]
	v_bfe_u32 v98, v2, 16, 1
	v_add3_u32 v2, v2, v98, s88
	ds_write_b16_d16_hi v89, v2
	v_cndmask_b32_e64 v2, 0, 1, s[28:29]
	v_cndmask_b32_e64 v98, 0, 1, s[30:31]
	v_cndmask_b32_e32 v2, v98, v2, vcc
	v_and_b32_e32 v2, 1, v2
	v_cmp_eq_u32_e64 s[38:39], 1, v2
	v_or_b32_e32 v102, v102, v106
	v_lshl_add_u64 v[104:105], s[64:65], 0, v[102:103]
	v_cndmask_b32_e64 v2, 0, v100, s[38:39]
	v_bfe_u32 v98, v2, 16, 1
	v_add3_u32 v2, v2, v98, s88
	ds_write_b16_d16_hi v90, v2
	v_cndmask_b32_e64 v2, 0, 1, s[34:35]
	v_cndmask_b32_e64 v98, 0, 1, s[36:37]
	v_cndmask_b32_e32 v2, v98, v2, vcc
	v_and_b32_e32 v2, 1, v2
	v_cmp_eq_u32_e32 vcc, 1, v2
	v_lshl_add_u64 v[102:103], s[62:63], 0, v[102:103]
	v_add_u32_e32 v107, v77, v79
	v_cndmask_b32_e32 v2, 0, v101, vcc
	v_bfe_u32 v98, v2, 16, 1
	v_add3_u32 v2, v2, v98, s88
	ds_write_b16_d16_hi v91, v2
	v_add_u32_e32 v2, v77, v78
	s_waitcnt lgkmcnt(0)
	s_barrier
	ds_read_b128 v[98:101], v2
	s_andn2_b64 vcc, exec, s[58:59]
	s_waitcnt lgkmcnt(0)
	global_store_dwordx4 v[104:105], v[98:101], off sc1
	ds_read_b128 v[98:101], v2 offset:33792
	s_waitcnt lgkmcnt(0)
	global_store_dwordx4 v[102:103], v[98:101], off sc1
	v_or_b32_e32 v102, s54, v65
	ds_read_b128 v[98:101], v107
	v_ashrrev_i32_e32 v103, 31, v102
	v_lshlrev_b64 v[102:103], 11, v[102:103]
	v_or_b32_e32 v102, v102, v106
	v_lshl_add_u64 v[104:105], s[64:65], 0, v[102:103]
	s_waitcnt lgkmcnt(0)
	global_store_dwordx4 v[104:105], v[98:101], off sc1
	ds_read_b128 v[98:101], v107 offset:33792
	v_lshl_add_u64 v[102:103], s[62:63], 0, v[102:103]
	s_waitcnt lgkmcnt(0)
	global_store_dwordx4 v[102:103], v[98:101], off sc1
	v_or_b32_e32 v102, s54, v66
	ds_read_b128 v[98:101], v2 offset:16896
	v_ashrrev_i32_e32 v103, 31, v102
	v_lshlrev_b64 v[102:103], 11, v[102:103]
	v_or_b32_e32 v102, v102, v106
	v_lshl_add_u64 v[104:105], s[64:65], 0, v[102:103]
	s_waitcnt lgkmcnt(0)
	global_store_dwordx4 v[104:105], v[98:101], off sc1
	ds_read_b128 v[98:101], v2 offset:50688
	v_lshl_add_u64 v[102:103], s[62:63], 0, v[102:103]
	v_add_u32_e32 v2, v77, v80
	s_waitcnt lgkmcnt(0)
	global_store_dwordx4 v[102:103], v[98:101], off sc1
	v_or_b32_e32 v102, s54, v67
	ds_read_b128 v[98:101], v2
	v_ashrrev_i32_e32 v103, 31, v102
	v_lshlrev_b64 v[102:103], 11, v[102:103]
	v_or_b32_e32 v102, v102, v106
	v_lshl_add_u64 v[104:105], s[64:65], 0, v[102:103]
	s_waitcnt lgkmcnt(0)
	global_store_dwordx4 v[104:105], v[98:101], off sc1
	ds_read_b128 v[98:101], v2 offset:33792
	v_add_u32_e32 v2, 0, v69
	v_lshl_add_u64 v[102:103], s[62:63], 0, v[102:103]
	v_add_u32_e32 v2, 0x1a400, v2
	s_waitcnt lgkmcnt(0)
	global_store_dwordx4 v[102:103], v[98:101], off sc1
	ds_read_b128 v[98:101], v2
	v_lshl_add_u64 v[102:103], v[62:63], 0, s[60:61]
	s_waitcnt lgkmcnt(0)
	global_store_dwordx4 v[102:103], v[98:101], off sc1
	s_barrier
	s_cbranch_vccz .LBB0_2482

.LBB0_2768:
	s_lshr_b32 s40, s81, 4
	s_add_i32 s40, s40, -1
	s_cmp_gt_i32 s81, 31
	s_cselect_b32 s40, s40, 0
	v_lshl_or_b32 v90, s12, 8, v230
	s_mul_i32 s43, s40, 0xc000
	s_mul_hi_i32 s42, s40, 0xc000
	s_add_u32 s40, s57, s43
	v_ashrrev_i32_e32 v91, 31, v90
	s_addc_u32 s41, s58, s42
	v_lshlrev_b64 v[36:37], 2, v[90:91]
	v_lshl_add_u64 v[26:27], s[40:41], 0, v[36:37]
	v_lshl_add_u64 v[28:29], s[20:21], 0, v[36:37]
	s_waitcnt lgkmcnt(0)
	global_load_dwordx4 v[2:5], v[26:27], off offset:16
	global_load_dwordx4 v[6:9], v[26:27], off
	global_load_dwordx4 v[10:13], v[28:29], off offset:16
	global_load_dwordx4 v[14:17], v[28:29], off
	s_add_u32 s40, s59, s43
	v_lshl_add_u64 v[30:31], s[24:25], 0, v[36:37]
	s_addc_u32 s41, s60, s42
	v_lshl_add_u64 v[32:33], s[40:41], 0, v[36:37]
	v_lshl_add_u32 v210, s81, 8, v228
	v_ashrrev_i32_e32 v211, 31, v210
	v_or_b32_e32 v34, 16, v210
	v_ashrrev_i32_e32 v35, 31, v34
	s_lshl_b32 s40, s12, 2
	s_ashr_i32 s41, s40, 31
	s_waitcnt vmcnt(0)
	v_pk_mul_f32 v[92:93], v[4:5], v[12:13]
	v_pk_mul_f32 v[86:87], v[8:9], v[16:17]
	v_pk_mul_f32 v[88:89], v[6:7], v[14:15]
	global_load_dwordx4 v[6:9], v[30:31], off offset:16
	global_load_dwordx4 v[14:17], v[30:31], off
	global_load_dwordx4 v[18:21], v[32:33], off offset:16
	global_load_dwordx4 v[22:25], v[32:33], off
	v_pk_mul_f32 v[94:95], v[2:3], v[10:11]
	s_waitcnt vmcnt(0)
	v_pk_add_f32 v[2:3], v[20:21], 1.0 op_sel_hi:[1,0]
	v_pk_add_f32 v[24:25], v[24:25], 1.0 op_sel_hi:[1,0]
	v_pk_add_f32 v[22:23], v[22:23], 1.0 op_sel_hi:[1,0]
	v_pk_add_f32 v[4:5], v[18:19], 1.0 op_sel_hi:[1,0]
	v_pk_mul_f32 v[78:79], v[16:17], v[24:25]
	v_pk_mul_f32 v[80:81], v[14:15], v[22:23]
	v_pk_mul_f32 v[82:83], v[8:9], v[2:3]
	v_pk_mul_f32 v[84:85], v[6:7], v[4:5]
	global_load_dwordx4 v[2:5], v[26:27], off offset:528
	global_load_dwordx4 v[6:9], v[26:27], off offset:512
	global_load_dwordx4 v[10:13], v[28:29], off offset:528
	global_load_dwordx4 v[14:17], v[28:29], off offset:512
	s_waitcnt vmcnt(0)
	v_pk_mul_f32 v[108:109], v[2:3], v[10:11]
	v_pk_mul_f32 v[104:105], v[8:9], v[16:17]
	v_pk_mul_f32 v[106:107], v[6:7], v[14:15]
	global_load_dwordx4 v[6:9], v[30:31], off offset:528
	global_load_dwordx4 v[14:17], v[30:31], off offset:512
	global_load_dwordx4 v[18:21], v[32:33], off offset:528
	global_load_dwordx4 v[22:25], v[32:33], off offset:512
	v_pk_mul_f32 v[110:111], v[4:5], v[12:13]
	s_waitcnt vmcnt(0)
	v_pk_add_f32 v[2:3], v[20:21], 1.0 op_sel_hi:[1,0]
	s_nop 0
	v_pk_mul_f32 v[100:101], v[8:9], v[2:3]
	v_lshlrev_b64 v[2:3], 13, v[210:211]
	v_lshl_add_u64 v[2:3], s[16:17], 0, v[2:3]
	v_lshl_add_u64 v[38:39], v[2:3], 0, v[36:37]
	v_lshlrev_b64 v[2:3], 13, v[34:35]
	v_lshl_add_u64 v[2:3], s[16:17], 0, v[2:3]
	v_pk_add_f32 v[24:25], v[24:25], 1.0 op_sel_hi:[1,0]
	v_pk_add_f32 v[22:23], v[22:23], 1.0 op_sel_hi:[1,0]
	v_pk_add_f32 v[4:5], v[18:19], 1.0 op_sel_hi:[1,0]
	v_lshl_add_u64 v[36:37], v[2:3], 0, v[36:37]
	v_pk_mul_f32 v[96:97], v[16:17], v[24:25]
	v_pk_mul_f32 v[98:99], v[14:15], v[22:23]
	v_pk_mul_f32 v[102:103], v[6:7], v[4:5]
	global_load_dwordx4 v[22:25], v[38:39], off offset:16 nt
	global_load_dwordx4 v[30:33], v[38:39], off nt
	global_load_dwordx4 v[18:21], v[38:39], off offset:528 nt
	global_load_dwordx4 v[26:29], v[38:39], off offset:512 nt
	global_load_dwordx4 v[10:13], v[36:37], off offset:16 nt
	global_load_dwordx4 v[14:17], v[36:37], off nt
	global_load_dwordx4 v[2:5], v[36:37], off offset:528 nt
	global_load_dwordx4 v[6:9], v[36:37], off offset:512 nt
	v_lshl_add_u64 v[196:197], v[210:211], 2, s[18:19]
	global_load_dword v40, v[196:197], off
	v_and_b32_e32 v44, 64, v232
	v_xor_b32_e32 v41, 16, v232
	v_add_u32_e32 v234, 64, v44
	v_cmp_lt_i32_e32 vcc, v41, v234
	v_lshlrev_b64 v[42:43], 12, v[210:211]
	v_lshl_add_u64 v[42:43], s[22:23], 0, v[42:43]
	v_cndmask_b32_e32 v41, v232, v41, vcc
	v_lshlrev_b32_e32 v233, 2, v41
	v_lshl_add_u64 v[42:43], v[90:91], 1, v[42:43]
	s_waitcnt vmcnt(0)
	v_pk_mul_f32 v[44:45], v[40:41], v[214:215] op_sel_hi:[0,1]
	v_pk_mul_f32 v[212:213], v[40:41], v[212:213] op_sel_hi:[0,1]
	v_pk_mul_f32 v[214:215], v[40:41], v[218:219] op_sel_hi:[0,1]
	v_pk_mul_f32 v[218:219], v[40:41], v[222:223] op_sel_hi:[0,1]
	v_pk_mul_f32 v[220:221], v[40:41], v[220:221] op_sel_hi:[0,1]
	v_pk_mul_f32 v[216:217], v[40:41], v[216:217] op_sel_hi:[0,1]
	v_pk_mul_f32 v[222:223], v[40:41], v[226:227] op_sel_hi:[0,1]
	v_pk_mul_f32 v[40:41], v[40:41], v[224:225] op_sel_hi:[0,1]
	v_pk_fma_f32 v[32:33], v[86:87], v[212:213], v[32:33]
	v_pk_fma_f32 v[30:31], v[88:89], v[44:45], v[30:31]
	v_pk_fma_f32 v[28:29], v[104:105], v[220:221], v[28:29]
	v_pk_fma_f32 v[26:27], v[106:107], v[218:219], v[26:27]
	v_pk_fma_f32 v[24:25], v[92:93], v[216:217], v[24:25]
	v_pk_fma_f32 v[22:23], v[94:95], v[214:215], v[22:23]
	v_pk_fma_f32 v[20:21], v[110:111], v[40:41], v[20:21]
	v_pk_fma_f32 v[18:19], v[108:109], v[222:223], v[18:19]
	global_store_dwordx4 v[38:39], v[30:33], off nt
	global_store_dwordx4 v[38:39], v[22:25], off offset:16 nt
	v_mul_f32_e32 v224, v31, v31
	v_mul_f32_e32 v225, v33, v33
	v_pk_mul_f32 v[40:41], v[78:79], v[32:33]
	v_pk_mul_f32 v[44:45], v[80:81], v[30:31]
	v_mul_f32_e32 v31, v27, v27
	v_mul_f32_e32 v33, v29, v29
	v_mul_f32_e32 v226, v23, v23
	v_mul_f32_e32 v227, v25, v25
	v_mul_f32_e32 v235, v19, v19
	v_fmac_f32_e32 v224, v30, v30
	v_fmac_f32_e32 v225, v32, v32
	v_fmac_f32_e32 v31, v26, v26
	v_fmac_f32_e32 v33, v28, v28
	v_pk_mul_f32 v[212:213], v[82:83], v[24:25]
	v_pk_mul_f32 v[214:215], v[84:85], v[22:23]
	v_mul_f32_e32 v236, v21, v21
	v_pk_mul_f32 v[222:223], v[102:103], v[18:19]
	v_fmac_f32_e32 v226, v22, v22
	v_fmac_f32_e32 v227, v24, v24
	v_cvt_pk_bf16_f32 v22, v44, v45
	v_cvt_pk_bf16_f32 v23, v40, v41
	v_cvt_pk_bf16_f32 v24, v214, v215
	v_cvt_pk_bf16_f32 v25, v212, v213
	v_fmac_f32_e32 v235, v18, v18
	v_add_f32_e32 v30, v224, v225
	global_store_dwordx4 v[42:43], v[22:25], off sc1
	v_lshlrev_b32_e32 v32, 16, v22
	v_and_b32_e32 v40, 0xffff0000, v22
	global_store_dwordx4 v[38:39], v[26:29], off offset:512 nt
	global_store_dwordx4 v[38:39], v[18:21], off offset:528 nt
	v_pk_mul_f32 v[220:221], v[100:101], v[20:21]
	v_fmac_f32_e32 v236, v20, v20
	v_add_f32_e32 v18, v31, v33
	v_lshlrev_b32_e32 v41, 16, v23
	v_and_b32_e32 v44, 0xffff0000, v23
	v_add_f32_e32 v19, v226, v30
	v_max3_f32 v20, |v32|, 0, |v40|
	v_add_f32_e32 v18, v235, v18
	v_lshlrev_b32_e32 v45, 16, v24
	v_and_b32_e32 v212, 0xffff0000, v24
	v_add_f32_e32 v19, v227, v19
	v_max3_f32 v20, v20, |v41|, |v44|
	v_add_f32_e32 v18, v236, v18
	v_lshlrev_b32_e32 v213, 16, v25
	v_and_b32_e32 v214, 0xffff0000, v25
	v_max3_f32 v20, v20, |v45|, |v212|
	v_add_f32_e32 v18, v19, v18
	v_pk_mul_f32 v[218:219], v[98:99], v[26:27]
	v_max3_f32 v19, v20, |v213|, |v214|
	v_cvt_pk_bf16_f32 v22, v218, v219
	ds_bpermute_b32 v20, v233, v18
	v_lshlrev_b32_e32 v21, 16, v22
	v_and_b32_e32 v26, 0xffff0000, v22
	v_pk_mul_f32 v[216:217], v[96:97], v[28:29]
	v_max3_f32 v19, v19, |v21|, |v26|
	v_cvt_pk_bf16_f32 v23, v216, v217
	v_cvt_pk_bf16_f32 v24, v222, v223
	v_cvt_pk_bf16_f32 v25, v220, v221
	s_waitcnt lgkmcnt(0)
	v_add_f32_e32 v18, v18, v20
	v_lshlrev_b32_e32 v27, 16, v23
	v_and_b32_e32 v28, 0xffff0000, v23
	v_lshlrev_b32_e32 v29, 16, v24
	v_and_b32_e32 v30, 0xffff0000, v24
	v_max3_f32 v19, v19, |v27|, |v28|
	v_max3_f32 v19, v19, |v29|, |v30|
	v_lshlrev_b32_e32 v21, 16, v25
	v_and_b32_e32 v26, 0xffff0000, v25
	v_max3_f32 v21, v19, |v21|, |v26|
	ds_bpermute_b32 v20, v233, v21
	v_xor_b32_e32 v19, 32, v232
	v_cmp_lt_i32_e32 vcc, v19, v234
	global_store_dwordx4 v[42:43], v[22:25], off offset:256 sc1
	s_waitcnt lgkmcnt(0)
	v_max_f32_e32 v20, v20, v20
	v_cndmask_b32_e32 v19, v232, v19, vcc
	v_lshlrev_b32_e32 v216, 2, v19
	v_max_f32_e32 v20, v21, v20
	ds_bpermute_b32 v19, v216, v18
	ds_bpermute_b32 v21, v216, v20
	s_and_saveexec_b64 s[42:43], s[0:1]
	s_cbranch_execz .LBB0_2770
	s_waitcnt lgkmcnt(0)
	v_max_f32_e32 v21, v21, v21
	v_max_f32_e32 v20, v20, v20
	v_add_f32_e32 v23, v18, v19
	v_lshlrev_b64 v[18:19], 7, v[210:211]
	v_max_f32_e32 v22, v20, v21
	v_lshl_add_u64 v[20:21], s[26:27], 0, v[18:19]
	s_lshl_b64 s[82:83], s[40:41], 2
	v_lshl_add_u64 v[18:19], s[28:29], 0, v[18:19]
	v_lshl_add_u64 v[20:21], v[20:21], 0, s[82:83]
	s_lshl_b32 s12, s63, 2
	v_lshl_add_u64 v[18:19], v[18:19], 0, s[82:83]
	v_lshl_add_u64 v[20:21], v[20:21], 0, s[12:13]
	v_lshl_add_u64 v[18:19], v[18:19], 0, s[12:13]
	global_store_dword v[20:21], v23, off
	global_store_dword v[18:19], v22, off
.LBB0_2770:
	s_or_b64 exec, exec, s[42:43]
	v_or_b32_e32 v212, 32, v210
	v_ashrrev_i32_e32 v213, 31, v212
	s_waitcnt lgkmcnt(1)
	v_lshlrev_b64 v[18:19], 13, v[212:213]
	v_lshl_add_u64 v[18:19], s[16:17], 0, v[18:19]
	v_lshl_add_u64 v[214:215], v[90:91], 2, v[18:19]
	global_load_dwordx4 v[26:29], v[214:215], off offset:16 nt
	global_load_dwordx4 v[30:33], v[214:215], off nt
	s_waitcnt lgkmcnt(0)
	global_load_dwordx4 v[18:21], v[214:215], off offset:528 nt
	global_load_dwordx4 v[22:25], v[214:215], off offset:512 nt
	v_lshl_add_u64 v[38:39], v[34:35], 2, s[18:19]
	global_load_dword v38, v[38:39], off
	v_lshlrev_b64 v[40:41], 12, v[34:35]
	v_lshl_add_u64 v[40:41], s[22:23], 0, v[40:41]
	v_lshl_add_u64 v[40:41], v[90:91], 1, v[40:41]
	s_waitcnt vmcnt(0)
	v_pk_mul_f32 v[44:45], v[38:39], v[192:193] op_sel_hi:[0,1]
	v_pk_mul_f32 v[192:193], v[38:39], v[200:201] op_sel_hi:[0,1]
	v_pk_mul_f32 v[42:43], v[38:39], v[194:195] op_sel_hi:[0,1]
	v_pk_mul_f32 v[194:195], v[38:39], v[198:199] op_sel_hi:[0,1]
	v_pk_mul_f32 v[198:199], v[38:39], v[206:207] op_sel_hi:[0,1]
	v_pk_mul_f32 v[200:201], v[38:39], v[202:203] op_sel_hi:[0,1]
	v_pk_fma_f32 v[10:11], v[94:95], v[192:193], v[10:11]
	v_pk_mul_f32 v[202:203], v[38:39], v[208:209] op_sel_hi:[0,1]
	v_pk_mul_f32 v[38:39], v[38:39], v[204:205] op_sel_hi:[0,1]
	v_pk_fma_f32 v[16:17], v[86:87], v[44:45], v[16:17]
	v_pk_fma_f32 v[14:15], v[88:89], v[42:43], v[14:15]
	v_pk_fma_f32 v[12:13], v[92:93], v[194:195], v[12:13]
	v_pk_fma_f32 v[8:9], v[104:105], v[200:201], v[8:9]
	v_pk_fma_f32 v[6:7], v[106:107], v[198:199], v[6:7]
	v_mul_f32_e32 v206, v11, v11
	v_pk_fma_f32 v[4:5], v[110:111], v[38:39], v[4:5]
	v_pk_fma_f32 v[2:3], v[108:109], v[202:203], v[2:3]
	global_store_dwordx4 v[36:37], v[14:17], off nt
	global_store_dwordx4 v[36:37], v[10:13], off offset:16 nt
	v_mul_f32_e32 v204, v15, v15
	v_mul_f32_e32 v205, v17, v17
	v_mul_f32_e32 v207, v13, v13
	v_pk_mul_f32 v[38:39], v[78:79], v[16:17]
	v_pk_mul_f32 v[42:43], v[80:81], v[14:15]
	v_pk_mul_f32 v[192:193], v[84:85], v[10:11]
	v_mul_f32_e32 v15, v7, v7
	v_mul_f32_e32 v17, v9, v9
	v_fmac_f32_e32 v206, v10, v10
	v_cvt_pk_bf16_f32 v10, v42, v43
	v_pk_mul_f32 v[44:45], v[82:83], v[12:13]
	v_mul_f32_e32 v208, v3, v3
	v_mul_f32_e32 v209, v5, v5
	v_fmac_f32_e32 v204, v14, v14
	v_fmac_f32_e32 v205, v16, v16
	v_fmac_f32_e32 v207, v12, v12
	v_cvt_pk_bf16_f32 v11, v38, v39
	v_cvt_pk_bf16_f32 v12, v192, v193
	v_cvt_pk_bf16_f32 v13, v44, v45
	v_fmac_f32_e32 v15, v6, v6
	v_fmac_f32_e32 v17, v8, v8
	global_store_dwordx4 v[40:41], v[10:13], off sc1
	v_lshlrev_b32_e32 v16, 16, v10
	v_pk_mul_f32 v[200:201], v[100:101], v[4:5]
	v_and_b32_e32 v10, 0xffff0000, v10
	v_pk_mul_f32 v[202:203], v[102:103], v[2:3]
	v_fmac_f32_e32 v208, v2, v2
	v_fmac_f32_e32 v209, v4, v4
	v_add_f32_e32 v14, v204, v205
	v_lshlrev_b32_e32 v38, 16, v11
	v_and_b32_e32 v11, 0xffff0000, v11
	global_store_dwordx4 v[36:37], v[6:9], off offset:512 nt
	global_store_dwordx4 v[36:37], v[2:5], off offset:528 nt
	v_lshlrev_b32_e32 v39, 16, v12
	v_and_b32_e32 v12, 0xffff0000, v12
	v_add_f32_e32 v2, v15, v17
	v_max3_f32 v4, |v16|, 0, |v10|
	v_add_f32_e32 v3, v206, v14
	v_add_f32_e32 v2, v208, v2
	v_max3_f32 v4, v4, |v38|, |v11|
	v_lshlrev_b32_e32 v42, 16, v13
	v_and_b32_e32 v13, 0xffff0000, v13
	v_add_f32_e32 v3, v207, v3
	v_add_f32_e32 v2, v209, v2
	v_max3_f32 v4, v4, |v39|, |v12|
	v_pk_mul_f32 v[198:199], v[98:99], v[6:7]
	v_add_f32_e32 v2, v3, v2
	v_cvt_pk_bf16_f32 v6, v198, v199
	v_max3_f32 v3, v4, |v42|, |v13|
	v_lshlrev_b32_e32 v5, 16, v6
	v_and_b32_e32 v10, 0xffff0000, v6
	v_pk_mul_f32 v[194:195], v[96:97], v[8:9]
	v_max3_f32 v3, v3, |v5|, |v10|
	v_cvt_pk_bf16_f32 v7, v194, v195
	v_cvt_pk_bf16_f32 v8, v202, v203
	v_cvt_pk_bf16_f32 v9, v200, v201
	ds_bpermute_b32 v4, v233, v2
	v_lshlrev_b32_e32 v14, 16, v7
	v_and_b32_e32 v15, 0xffff0000, v7
	v_lshlrev_b32_e32 v16, 16, v8
	v_and_b32_e32 v17, 0xffff0000, v8
	v_max3_f32 v3, v3, |v14|, |v15|
	v_lshlrev_b32_e32 v36, 16, v9
	v_and_b32_e32 v37, 0xffff0000, v9
	v_max3_f32 v3, v3, |v16|, |v17|
	v_max3_f32 v5, v3, |v36|, |v37|
	ds_bpermute_b32 v10, v233, v5
	s_waitcnt lgkmcnt(1)
	v_add_f32_e32 v2, v2, v4
	ds_bpermute_b32 v3, v216, v2
	global_store_dwordx4 v[40:41], v[6:9], off offset:256 sc1
	s_waitcnt lgkmcnt(1)
	v_max_f32_e32 v4, v10, v10
	v_max_f32_e32 v4, v5, v4
	ds_bpermute_b32 v5, v216, v4
	s_and_saveexec_b64 s[42:43], s[0:1]
	s_cbranch_execz .LBB0_2772
	s_waitcnt lgkmcnt(0)
	v_max_f32_e32 v5, v5, v5
	v_max_f32_e32 v4, v4, v4
	v_add_f32_e32 v7, v2, v3
	v_lshlrev_b64 v[2:3], 7, v[34:35]
	v_max_f32_e32 v6, v4, v5
	v_lshl_add_u64 v[4:5], s[26:27], 0, v[2:3]
	s_lshl_b64 s[82:83], s[40:41], 2
	v_lshl_add_u64 v[2:3], s[28:29], 0, v[2:3]
	v_lshl_add_u64 v[4:5], v[4:5], 0, s[82:83]
	s_lshl_b32 s12, s63, 2
	v_lshl_add_u64 v[2:3], v[2:3], 0, s[82:83]
	v_lshl_add_u64 v[4:5], v[4:5], 0, s[12:13]
	v_lshl_add_u64 v[2:3], v[2:3], 0, s[12:13]
	global_store_dword v[4:5], v7, off
	global_store_dword v[2:3], v6, off
.LBB0_2772:
	s_or_b64 exec, exec, s[42:43]
	v_or_b32_e32 v192, 48, v210
	v_ashrrev_i32_e32 v193, 31, v192
	s_waitcnt lgkmcnt(1)
	v_lshlrev_b64 v[2:3], 13, v[192:193]
	v_lshl_add_u64 v[2:3], s[16:17], 0, v[2:3]
	v_lshl_add_u64 v[194:195], v[90:91], 2, v[2:3]
	global_load_dwordx4 v[38:41], v[194:195], off offset:16 nt
	global_load_dwordx4 v[42:45], v[194:195], off nt
	global_load_dwordx4 v[6:9], v[194:195], off offset:528 nt
	global_load_dwordx4 v[34:37], v[194:195], off offset:512 nt
	v_lshl_add_u64 v[2:3], v[212:213], 2, s[18:19]
	global_load_dword v2, v[2:3], off
	s_waitcnt lgkmcnt(0)
	v_lshlrev_b64 v[4:5], 12, v[212:213]
	v_lshl_add_u64 v[4:5], s[22:23], 0, v[4:5]
	v_lshl_add_u64 v[198:199], v[90:91], 1, v[4:5]
	s_waitcnt vmcnt(0)
	v_pk_mul_f32 v[10:11], v[2:3], v[178:179] op_sel_hi:[0,1]
	v_pk_mul_f32 v[4:5], v[2:3], v[176:177] op_sel_hi:[0,1]
	v_pk_mul_f32 v[14:15], v[2:3], v[182:183] op_sel_hi:[0,1]
	v_pk_mul_f32 v[12:13], v[2:3], v[180:181] op_sel_hi:[0,1]
	v_pk_mul_f32 v[176:177], v[2:3], v[188:189] op_sel_hi:[0,1]
	v_pk_mul_f32 v[16:17], v[2:3], v[184:185] op_sel_hi:[0,1]
	v_pk_mul_f32 v[178:179], v[2:3], v[190:191] op_sel_hi:[0,1]
	v_pk_mul_f32 v[180:181], v[2:3], v[186:187] op_sel_hi:[0,1]
	v_pk_fma_f32 v[2:3], v[88:89], v[10:11], v[30:31]
	v_pk_fma_f32 v[4:5], v[86:87], v[4:5], v[32:33]
	v_pk_fma_f32 v[20:21], v[110:111], v[180:181], v[20:21]
	v_mul_f32_e32 v180, v3, v3
	v_pk_fma_f32 v[12:13], v[92:93], v[12:13], v[28:29]
	v_pk_fma_f32 v[10:11], v[94:95], v[14:15], v[26:27]
	v_pk_fma_f32 v[16:17], v[104:105], v[16:17], v[24:25]
	v_pk_fma_f32 v[14:15], v[106:107], v[176:177], v[22:23]
	global_store_dwordx4 v[214:215], v[2:5], off nt
	global_store_dwordx4 v[214:215], v[10:13], off offset:16 nt
	v_mul_f32_e32 v181, v5, v5
	v_pk_mul_f32 v[22:23], v[78:79], v[4:5]
	v_pk_mul_f32 v[24:25], v[80:81], v[2:3]
	v_fmac_f32_e32 v180, v2, v2
	v_cvt_pk_bf16_f32 v2, v24, v25
	v_pk_mul_f32 v[26:27], v[82:83], v[12:13]
	v_pk_mul_f32 v[28:29], v[84:85], v[10:11]
	v_fmac_f32_e32 v181, v4, v4
	v_cvt_pk_bf16_f32 v3, v22, v23
	v_cvt_pk_bf16_f32 v4, v28, v29
	v_cvt_pk_bf16_f32 v5, v26, v27
	global_store_dwordx4 v[198:199], v[2:5], off sc1
	v_lshlrev_b32_e32 v23, 16, v2
	v_lshlrev_b32_e32 v24, 16, v3
	v_and_b32_e32 v2, 0xffff0000, v2
	v_and_b32_e32 v3, 0xffff0000, v3
	v_max3_f32 v2, |v23|, 0, |v2|
	v_lshlrev_b32_e32 v25, 16, v4
	v_and_b32_e32 v4, 0xffff0000, v4
	v_max3_f32 v2, v2, |v24|, |v3|
	v_pk_fma_f32 v[18:19], v[108:109], v[178:179], v[18:19]
	v_mul_f32_e32 v182, v11, v11
	v_mul_f32_e32 v183, v13, v13
	v_mul_f32_e32 v11, v15, v15
	v_mul_f32_e32 v13, v17, v17
	v_lshlrev_b32_e32 v26, 16, v5
	v_and_b32_e32 v5, 0xffff0000, v5
	v_max3_f32 v2, v2, |v25|, |v4|
	v_mul_f32_e32 v184, v19, v19
	v_pk_mul_f32 v[30:31], v[96:97], v[16:17]
	v_pk_mul_f32 v[32:33], v[98:99], v[14:15]
	v_fmac_f32_e32 v182, v10, v10
	v_fmac_f32_e32 v11, v14, v14
	v_fmac_f32_e32 v13, v16, v16
	global_store_dwordx4 v[214:215], v[14:17], off offset:512 nt
	global_store_dwordx4 v[214:215], v[18:21], off offset:528 nt
	v_cvt_pk_bf16_f32 v10, v32, v33
	v_max3_f32 v2, v2, |v26|, |v5|
	v_lshlrev_b32_e32 v16, 16, v10
	v_and_b32_e32 v17, 0xffff0000, v10
	v_mul_f32_e32 v185, v21, v21
	v_pk_mul_f32 v[178:179], v[102:103], v[18:19]
	v_fmac_f32_e32 v184, v18, v18
	v_add_f32_e32 v22, v180, v181
	v_add_f32_e32 v14, v11, v13
	v_cvt_pk_bf16_f32 v11, v30, v31
	v_max3_f32 v2, v2, |v16|, |v17|
	v_lshlrev_b32_e32 v18, 16, v11
	v_and_b32_e32 v19, 0xffff0000, v11
	v_pk_mul_f32 v[176:177], v[100:101], v[20:21]
	v_fmac_f32_e32 v183, v12, v12
	v_fmac_f32_e32 v185, v20, v20
	v_cvt_pk_bf16_f32 v12, v178, v179
	v_add_f32_e32 v15, v182, v22
	v_add_f32_e32 v14, v184, v14
	v_lshlrev_b32_e32 v20, 16, v12
	v_and_b32_e32 v21, 0xffff0000, v12
	v_max3_f32 v2, v2, |v18|, |v19|
	v_cvt_pk_bf16_f32 v13, v176, v177
	v_add_f32_e32 v15, v183, v15
	v_lshlrev_b32_e32 v22, 16, v13
	v_and_b32_e32 v23, 0xffff0000, v13
	v_add_f32_e32 v3, v185, v14
	v_max3_f32 v2, v2, |v20|, |v21|
	v_add_f32_e32 v3, v15, v3
	v_max3_f32 v5, v2, |v22|, |v23|
	ds_bpermute_b32 v4, v233, v3
	ds_bpermute_b32 v14, v233, v5
	global_store_dwordx4 v[198:199], v[10:13], off offset:256 sc1
	s_waitcnt lgkmcnt(1)
	v_add_f32_e32 v2, v3, v4
	s_waitcnt lgkmcnt(0)
	v_max_f32_e32 v4, v14, v14
	v_max_f32_e32 v4, v5, v4
	ds_bpermute_b32 v3, v216, v2
	ds_bpermute_b32 v5, v216, v4
	s_and_saveexec_b64 s[42:43], s[0:1]
	s_cbranch_execz .LBB0_2774
	s_waitcnt lgkmcnt(0)
	v_max_f32_e32 v5, v5, v5
	v_max_f32_e32 v4, v4, v4
	v_add_f32_e32 v11, v2, v3
	v_lshlrev_b64 v[2:3], 7, v[212:213]
	v_max_f32_e32 v10, v4, v5
	v_lshl_add_u64 v[4:5], s[26:27], 0, v[2:3]
	s_lshl_b64 s[82:83], s[40:41], 2
	v_lshl_add_u64 v[2:3], s[28:29], 0, v[2:3]
	v_lshl_add_u64 v[4:5], v[4:5], 0, s[82:83]
	s_lshl_b32 s12, s63, 2
	v_lshl_add_u64 v[2:3], v[2:3], 0, s[82:83]
	v_lshl_add_u64 v[4:5], v[4:5], 0, s[12:13]
	v_lshl_add_u64 v[2:3], v[2:3], 0, s[12:13]
	global_store_dword v[4:5], v11, off
	global_store_dword v[2:3], v10, off
.LBB0_2774:
	s_or_b64 exec, exec, s[42:43]
	v_add_u32_e32 v176, 0x80, v210
	v_ashrrev_i32_e32 v177, 31, v176
	s_waitcnt lgkmcnt(1)
	v_lshlrev_b64 v[2:3], 13, v[176:177]
	v_lshl_add_u64 v[2:3], s[16:17], 0, v[2:3]
	v_lshl_add_u64 v[178:179], v[90:91], 2, v[2:3]
	global_load_dwordx4 v[14:17], v[178:179], off offset:16 nt
	global_load_dwordx4 v[18:21], v[178:179], off nt
	s_waitcnt lgkmcnt(0)
	global_load_dwordx4 v[2:5], v[178:179], off offset:528 nt
	global_load_dwordx4 v[10:13], v[178:179], off offset:512 nt
	v_lshl_add_u64 v[22:23], v[192:193], 2, s[18:19]
	global_load_dword v22, v[22:23], off
	v_lshlrev_b64 v[24:25], 12, v[192:193]
	v_lshl_add_u64 v[24:25], s[22:23], 0, v[24:25]
	v_lshl_add_u64 v[180:181], v[90:91], 1, v[24:25]
	s_waitcnt vmcnt(0)
	v_pk_mul_f32 v[26:27], v[22:23], v[162:163] op_sel_hi:[0,1]
	v_pk_mul_f32 v[24:25], v[22:23], v[160:161] op_sel_hi:[0,1]
	v_pk_mul_f32 v[30:31], v[22:23], v[166:167] op_sel_hi:[0,1]
	v_pk_mul_f32 v[28:29], v[22:23], v[164:165] op_sel_hi:[0,1]
	v_pk_mul_f32 v[160:161], v[22:23], v[172:173] op_sel_hi:[0,1]
	v_pk_mul_f32 v[32:33], v[22:23], v[168:169] op_sel_hi:[0,1]
	v_pk_mul_f32 v[162:163], v[22:23], v[174:175] op_sel_hi:[0,1]
	v_pk_mul_f32 v[164:165], v[22:23], v[170:171] op_sel_hi:[0,1]
	v_pk_fma_f32 v[24:25], v[86:87], v[24:25], v[44:45]
	v_pk_fma_f32 v[22:23], v[88:89], v[26:27], v[42:43]
	v_pk_fma_f32 v[28:29], v[92:93], v[28:29], v[40:41]
	v_pk_fma_f32 v[26:27], v[94:95], v[30:31], v[38:39]
	v_pk_fma_f32 v[32:33], v[104:105], v[32:33], v[36:37]
	v_pk_fma_f32 v[30:31], v[106:107], v[160:161], v[34:35]
	v_pk_fma_f32 v[8:9], v[110:111], v[164:165], v[8:9]
	v_pk_fma_f32 v[6:7], v[108:109], v[162:163], v[6:7]
	global_store_dwordx4 v[194:195], v[22:25], off nt
	global_store_dwordx4 v[194:195], v[26:29], off offset:16 nt
	v_mul_f32_e32 v164, v23, v23
	v_mul_f32_e32 v165, v25, v25
	v_mul_f32_e32 v166, v27, v27
	v_mul_f32_e32 v167, v29, v29
	v_pk_mul_f32 v[34:35], v[78:79], v[24:25]
	v_pk_mul_f32 v[38:39], v[82:83], v[28:29]
	v_pk_mul_f32 v[40:41], v[84:85], v[26:27]
	v_mul_f32_e32 v27, v31, v31
	v_mul_f32_e32 v29, v33, v33
	v_pk_mul_f32 v[36:37], v[80:81], v[22:23]
	v_mul_f32_e32 v168, v7, v7
	v_mul_f32_e32 v169, v9, v9
	v_fmac_f32_e32 v164, v22, v22
	v_fmac_f32_e32 v165, v24, v24
	v_fmac_f32_e32 v167, v28, v28
	v_cvt_pk_bf16_f32 v22, v36, v37
	v_cvt_pk_bf16_f32 v23, v34, v35
	v_fmac_f32_e32 v27, v30, v30
	v_fmac_f32_e32 v29, v32, v32
	v_lshlrev_b32_e32 v28, 16, v22
	v_and_b32_e32 v34, 0xffff0000, v22
	v_pk_mul_f32 v[160:161], v[100:101], v[8:9]
	v_pk_mul_f32 v[162:163], v[102:103], v[6:7]
	v_fmac_f32_e32 v166, v26, v26
	v_cvt_pk_bf16_f32 v24, v40, v41
	v_cvt_pk_bf16_f32 v25, v38, v39
	v_fmac_f32_e32 v168, v6, v6
	v_fmac_f32_e32 v169, v8, v8
	v_add_f32_e32 v26, v164, v165
	global_store_dwordx4 v[180:181], v[22:25], off sc1
	v_lshlrev_b32_e32 v35, 16, v23
	v_and_b32_e32 v36, 0xffff0000, v23
	global_store_dwordx4 v[194:195], v[30:33], off offset:512 nt
	global_store_dwordx4 v[194:195], v[6:9], off offset:528 nt
	v_lshlrev_b32_e32 v37, 16, v24
	v_and_b32_e32 v38, 0xffff0000, v24
	v_add_f32_e32 v6, v27, v29
	v_max3_f32 v8, |v28|, 0, |v34|
	v_add_f32_e32 v7, v166, v26
	v_add_f32_e32 v6, v168, v6
	v_max3_f32 v8, v8, |v35|, |v36|
	v_lshlrev_b32_e32 v39, 16, v25
	v_and_b32_e32 v40, 0xffff0000, v25
	v_add_f32_e32 v7, v167, v7
	v_add_f32_e32 v6, v169, v6
	v_max3_f32 v8, v8, |v37|, |v38|
	v_pk_mul_f32 v[44:45], v[98:99], v[30:31]
	v_add_f32_e32 v6, v7, v6
	v_cvt_pk_bf16_f32 v22, v44, v45
	v_max3_f32 v7, v8, |v39|, |v40|
	v_lshlrev_b32_e32 v9, 16, v22
	v_and_b32_e32 v26, 0xffff0000, v22
	v_pk_mul_f32 v[42:43], v[96:97], v[32:33]
	v_max3_f32 v7, v7, |v9|, |v26|
	v_cvt_pk_bf16_f32 v23, v42, v43
	v_cvt_pk_bf16_f32 v24, v162, v163
	v_cvt_pk_bf16_f32 v25, v160, v161
	ds_bpermute_b32 v8, v233, v6
	v_lshlrev_b32_e32 v27, 16, v23
	v_and_b32_e32 v28, 0xffff0000, v23
	v_lshlrev_b32_e32 v29, 16, v24
	v_and_b32_e32 v30, 0xffff0000, v24
	v_max3_f32 v7, v7, |v27|, |v28|
	v_lshlrev_b32_e32 v31, 16, v25
	v_and_b32_e32 v32, 0xffff0000, v25
	v_max3_f32 v7, v7, |v29|, |v30|
	v_max3_f32 v9, v7, |v31|, |v32|
	ds_bpermute_b32 v26, v233, v9
	s_waitcnt lgkmcnt(1)
	v_add_f32_e32 v6, v6, v8
	ds_bpermute_b32 v7, v216, v6
	global_store_dwordx4 v[180:181], v[22:25], off offset:256 sc1
	s_waitcnt lgkmcnt(1)
	v_max_f32_e32 v8, v26, v26
	v_max_f32_e32 v8, v9, v8
	ds_bpermute_b32 v9, v216, v8
	s_and_saveexec_b64 s[42:43], s[0:1]
	s_cbranch_execz .LBB0_2776
	s_waitcnt lgkmcnt(0)
	v_max_f32_e32 v9, v9, v9
	v_max_f32_e32 v8, v8, v8
	v_add_f32_e32 v23, v6, v7
	v_lshlrev_b64 v[6:7], 7, v[192:193]
	v_max_f32_e32 v22, v8, v9
	v_lshl_add_u64 v[8:9], s[26:27], 0, v[6:7]
	s_lshl_b64 s[82:83], s[40:41], 2
	v_lshl_add_u64 v[6:7], s[28:29], 0, v[6:7]
	v_lshl_add_u64 v[8:9], v[8:9], 0, s[82:83]
	s_lshl_b32 s12, s63, 2
	v_lshl_add_u64 v[6:7], v[6:7], 0, s[82:83]
	v_lshl_add_u64 v[8:9], v[8:9], 0, s[12:13]
	v_lshl_add_u64 v[6:7], v[6:7], 0, s[12:13]
	global_store_dword v[8:9], v23, off
	global_store_dword v[6:7], v22, off
.LBB0_2776:
	s_or_b64 exec, exec, s[42:43]
	v_or_b32_e32 v36, 16, v176
	v_ashrrev_i32_e32 v37, 31, v36
	s_waitcnt lgkmcnt(1)
	v_lshlrev_b64 v[6:7], 13, v[36:37]
	v_lshl_add_u64 v[6:7], s[16:17], 0, v[6:7]
	v_lshl_add_u64 v[40:41], v[90:91], 2, v[6:7]
	global_load_dwordx4 v[26:29], v[40:41], off offset:16 nt
	global_load_dwordx4 v[30:33], v[40:41], off nt
	s_waitcnt lgkmcnt(0)
	global_load_dwordx4 v[6:9], v[40:41], off offset:528 nt
	global_load_dwordx4 v[22:25], v[40:41], off offset:512 nt
	global_load_dword v34, v[196:197], off offset:512
	v_lshlrev_b64 v[38:39], 12, v[176:177]
	v_lshl_add_u64 v[38:39], s[22:23], 0, v[38:39]
	v_lshl_add_u64 v[38:39], v[90:91], 1, v[38:39]
	s_waitcnt vmcnt(0)
	v_pk_mul_f32 v[44:45], v[34:35], v[128:129] op_sel_hi:[0,1]
	v_pk_mul_f32 v[128:129], v[34:35], v[150:151] op_sel_hi:[0,1]
	v_pk_mul_f32 v[42:43], v[34:35], v[146:147] op_sel_hi:[0,1]
	v_pk_mul_f32 v[146:147], v[34:35], v[148:149] op_sel_hi:[0,1]
	v_pk_mul_f32 v[148:149], v[34:35], v[156:157] op_sel_hi:[0,1]
	v_pk_mul_f32 v[150:151], v[34:35], v[152:153] op_sel_hi:[0,1]
	v_pk_fma_f32 v[14:15], v[94:95], v[128:129], v[14:15]
	v_pk_mul_f32 v[152:153], v[34:35], v[158:159] op_sel_hi:[0,1]
	v_pk_mul_f32 v[34:35], v[34:35], v[154:155] op_sel_hi:[0,1]
	v_pk_fma_f32 v[20:21], v[86:87], v[44:45], v[20:21]
	v_pk_fma_f32 v[18:19], v[88:89], v[42:43], v[18:19]
	v_pk_fma_f32 v[16:17], v[92:93], v[146:147], v[16:17]
	v_pk_fma_f32 v[12:13], v[104:105], v[150:151], v[12:13]
	v_pk_fma_f32 v[10:11], v[106:107], v[148:149], v[10:11]
	v_mul_f32_e32 v156, v15, v15
	v_pk_fma_f32 v[4:5], v[110:111], v[34:35], v[4:5]
	v_pk_fma_f32 v[2:3], v[108:109], v[152:153], v[2:3]
	global_store_dwordx4 v[178:179], v[18:21], off nt
	global_store_dwordx4 v[178:179], v[14:17], off offset:16 nt
	v_mul_f32_e32 v154, v19, v19
	v_mul_f32_e32 v155, v21, v21
	v_mul_f32_e32 v157, v17, v17
	v_pk_mul_f32 v[34:35], v[78:79], v[20:21]
	v_pk_mul_f32 v[42:43], v[80:81], v[18:19]
	v_pk_mul_f32 v[128:129], v[84:85], v[14:15]
	v_mul_f32_e32 v19, v11, v11
	v_mul_f32_e32 v21, v13, v13
	v_fmac_f32_e32 v156, v14, v14
	v_cvt_pk_bf16_f32 v14, v42, v43
	v_pk_mul_f32 v[44:45], v[82:83], v[16:17]
	v_mul_f32_e32 v158, v3, v3
	v_mul_f32_e32 v159, v5, v5
	v_fmac_f32_e32 v154, v18, v18
	v_fmac_f32_e32 v155, v20, v20
	v_fmac_f32_e32 v157, v16, v16
	v_cvt_pk_bf16_f32 v15, v34, v35
	v_cvt_pk_bf16_f32 v16, v128, v129
	v_cvt_pk_bf16_f32 v17, v44, v45
	v_fmac_f32_e32 v19, v10, v10
	v_fmac_f32_e32 v21, v12, v12
	global_store_dwordx4 v[38:39], v[14:17], off sc1
	v_lshlrev_b32_e32 v20, 16, v14
	v_pk_mul_f32 v[150:151], v[100:101], v[4:5]
	v_and_b32_e32 v14, 0xffff0000, v14
	v_pk_mul_f32 v[152:153], v[102:103], v[2:3]
	v_fmac_f32_e32 v158, v2, v2
	v_fmac_f32_e32 v159, v4, v4
	v_add_f32_e32 v18, v154, v155
	v_lshlrev_b32_e32 v34, 16, v15
	v_and_b32_e32 v15, 0xffff0000, v15
	global_store_dwordx4 v[178:179], v[10:13], off offset:512 nt
	global_store_dwordx4 v[178:179], v[2:5], off offset:528 nt
	v_lshlrev_b32_e32 v35, 16, v16
	v_and_b32_e32 v16, 0xffff0000, v16
	v_add_f32_e32 v2, v19, v21
	v_max3_f32 v4, |v20|, 0, |v14|
	v_add_f32_e32 v3, v156, v18
	v_add_f32_e32 v2, v158, v2
	v_max3_f32 v4, v4, |v34|, |v15|
	v_lshlrev_b32_e32 v42, 16, v17
	v_and_b32_e32 v17, 0xffff0000, v17
	v_add_f32_e32 v3, v157, v3
	v_add_f32_e32 v2, v159, v2
	v_max3_f32 v4, v4, |v35|, |v16|
	v_pk_mul_f32 v[148:149], v[98:99], v[10:11]
	v_add_f32_e32 v2, v3, v2
	v_cvt_pk_bf16_f32 v10, v148, v149
	v_max3_f32 v3, v4, |v42|, |v17|
	v_lshlrev_b32_e32 v5, 16, v10
	v_and_b32_e32 v14, 0xffff0000, v10
	v_pk_mul_f32 v[146:147], v[96:97], v[12:13]
	v_max3_f32 v3, v3, |v5|, |v14|
	v_cvt_pk_bf16_f32 v11, v146, v147
	v_cvt_pk_bf16_f32 v12, v152, v153
	v_cvt_pk_bf16_f32 v13, v150, v151
	ds_bpermute_b32 v4, v233, v2
	v_lshlrev_b32_e32 v18, 16, v11
	v_and_b32_e32 v19, 0xffff0000, v11
	v_lshlrev_b32_e32 v20, 16, v12
	v_and_b32_e32 v21, 0xffff0000, v12
	v_max3_f32 v3, v3, |v18|, |v19|
	v_lshlrev_b32_e32 v43, 16, v13
	v_and_b32_e32 v44, 0xffff0000, v13
	v_max3_f32 v3, v3, |v20|, |v21|
	v_max3_f32 v5, v3, |v43|, |v44|
	ds_bpermute_b32 v14, v233, v5
	s_waitcnt lgkmcnt(1)
	v_add_f32_e32 v2, v2, v4
	ds_bpermute_b32 v3, v216, v2
	global_store_dwordx4 v[38:39], v[10:13], off offset:256 sc1
	s_waitcnt lgkmcnt(1)
	v_max_f32_e32 v4, v14, v14
	v_max_f32_e32 v4, v5, v4
	ds_bpermute_b32 v5, v216, v4
	s_and_saveexec_b64 s[42:43], s[0:1]
	s_cbranch_execz .LBB0_2778
	s_waitcnt lgkmcnt(0)
	v_max_f32_e32 v5, v5, v5
	v_max_f32_e32 v4, v4, v4
	v_add_f32_e32 v11, v2, v3
	v_lshlrev_b64 v[2:3], 7, v[176:177]
	v_max_f32_e32 v10, v4, v5
	v_lshl_add_u64 v[4:5], s[26:27], 0, v[2:3]
	s_lshl_b64 s[82:83], s[40:41], 2
	v_lshl_add_u64 v[2:3], s[28:29], 0, v[2:3]
	v_lshl_add_u64 v[4:5], v[4:5], 0, s[82:83]
	s_lshl_b32 s12, s63, 2
	v_lshl_add_u64 v[2:3], v[2:3], 0, s[82:83]
	v_lshl_add_u64 v[4:5], v[4:5], 0, s[12:13]
	v_lshl_add_u64 v[2:3], v[2:3], 0, s[12:13]
	global_store_dword v[4:5], v11, off
	global_store_dword v[2:3], v10, off
.LBB0_2778:
	s_or_b64 exec, exec, s[42:43]
	v_or_b32_e32 v34, 32, v176
	v_ashrrev_i32_e32 v35, 31, v34
	s_waitcnt lgkmcnt(1)
	v_lshlrev_b64 v[2:3], 13, v[34:35]
	v_lshl_add_u64 v[2:3], s[16:17], 0, v[2:3]
	v_lshl_add_u64 v[38:39], v[90:91], 2, v[2:3]
	global_load_dwordx4 v[14:17], v[38:39], off offset:16 nt
	global_load_dwordx4 v[18:21], v[38:39], off nt
	s_waitcnt lgkmcnt(0)
	global_load_dwordx4 v[2:5], v[38:39], off offset:528 nt
	global_load_dwordx4 v[10:13], v[38:39], off offset:512 nt
	v_lshl_add_u64 v[42:43], v[36:37], 2, s[18:19]
	global_load_dword v42, v[42:43], off
	v_lshlrev_b64 v[44:45], 12, v[36:37]
	v_lshl_add_u64 v[44:45], s[22:23], 0, v[44:45]
	v_lshl_add_u64 v[44:45], v[90:91], 1, v[44:45]
	s_waitcnt vmcnt(0)
	v_pk_mul_f32 v[118:119], v[42:43], v[118:119] op_sel_hi:[0,1]
	v_pk_mul_f32 v[114:115], v[42:43], v[114:115] op_sel_hi:[0,1]
	v_pk_mul_f32 v[112:113], v[42:43], v[112:113] op_sel_hi:[0,1]
	v_pk_mul_f32 v[116:117], v[42:43], v[116:117] op_sel_hi:[0,1]
	v_pk_mul_f32 v[124:125], v[42:43], v[124:125] op_sel_hi:[0,1]
	v_pk_mul_f32 v[120:121], v[42:43], v[120:121] op_sel_hi:[0,1]
	v_pk_fma_f32 v[26:27], v[94:95], v[118:119], v[26:27]
	v_pk_mul_f32 v[126:127], v[42:43], v[126:127] op_sel_hi:[0,1]
	v_pk_mul_f32 v[42:43], v[42:43], v[122:123] op_sel_hi:[0,1]
	v_pk_fma_f32 v[32:33], v[86:87], v[112:113], v[32:33]
	v_pk_fma_f32 v[30:31], v[88:89], v[114:115], v[30:31]
	v_pk_fma_f32 v[28:29], v[92:93], v[116:117], v[28:29]
	v_pk_fma_f32 v[24:25], v[104:105], v[120:121], v[24:25]
	v_pk_fma_f32 v[22:23], v[106:107], v[124:125], v[22:23]
	v_mul_f32_e32 v128, v27, v27
	v_pk_fma_f32 v[8:9], v[110:111], v[42:43], v[8:9]
	v_pk_fma_f32 v[6:7], v[108:109], v[126:127], v[6:7]
	global_store_dwordx4 v[40:41], v[30:33], off nt
	global_store_dwordx4 v[40:41], v[26:29], off offset:16 nt
	v_mul_f32_e32 v126, v31, v31
	v_mul_f32_e32 v127, v33, v33
	v_mul_f32_e32 v129, v29, v29
	v_pk_mul_f32 v[42:43], v[78:79], v[32:33]
	v_pk_mul_f32 v[112:113], v[80:81], v[30:31]
	v_pk_mul_f32 v[116:117], v[84:85], v[26:27]
	v_mul_f32_e32 v31, v23, v23
	v_mul_f32_e32 v33, v25, v25
	v_fmac_f32_e32 v128, v26, v26
	v_cvt_pk_bf16_f32 v26, v112, v113
	v_pk_mul_f32 v[114:115], v[82:83], v[28:29]
	v_mul_f32_e32 v146, v7, v7
	v_mul_f32_e32 v147, v9, v9
	v_fmac_f32_e32 v126, v30, v30
	v_fmac_f32_e32 v127, v32, v32
	v_fmac_f32_e32 v129, v28, v28
	v_cvt_pk_bf16_f32 v27, v42, v43
	v_cvt_pk_bf16_f32 v28, v116, v117
	v_cvt_pk_bf16_f32 v29, v114, v115
	v_fmac_f32_e32 v31, v22, v22
	v_fmac_f32_e32 v33, v24, v24
	global_store_dwordx4 v[44:45], v[26:29], off sc1
	v_lshlrev_b32_e32 v32, 16, v26
	v_pk_mul_f32 v[122:123], v[100:101], v[8:9]
	v_and_b32_e32 v26, 0xffff0000, v26
	v_pk_mul_f32 v[124:125], v[102:103], v[6:7]
	v_fmac_f32_e32 v146, v6, v6
	v_fmac_f32_e32 v147, v8, v8
	v_add_f32_e32 v30, v126, v127
	v_lshlrev_b32_e32 v42, 16, v27
	v_and_b32_e32 v27, 0xffff0000, v27
	global_store_dwordx4 v[40:41], v[22:25], off offset:512 nt
	global_store_dwordx4 v[40:41], v[6:9], off offset:528 nt
	v_lshlrev_b32_e32 v43, 16, v28
	v_and_b32_e32 v28, 0xffff0000, v28
	v_add_f32_e32 v6, v31, v33
	v_max3_f32 v8, |v32|, 0, |v26|
	v_add_f32_e32 v7, v128, v30
	v_add_f32_e32 v6, v146, v6
	v_max3_f32 v8, v8, |v42|, |v27|
	v_lshlrev_b32_e32 v112, 16, v29
	v_and_b32_e32 v29, 0xffff0000, v29
	v_add_f32_e32 v7, v129, v7
	v_add_f32_e32 v6, v147, v6
	v_max3_f32 v8, v8, |v43|, |v28|
	v_pk_mul_f32 v[120:121], v[98:99], v[22:23]
	v_add_f32_e32 v6, v7, v6
	v_cvt_pk_bf16_f32 v22, v120, v121
	v_max3_f32 v7, v8, |v112|, |v29|
	v_lshlrev_b32_e32 v9, 16, v22
	v_and_b32_e32 v26, 0xffff0000, v22
	v_pk_mul_f32 v[118:119], v[96:97], v[24:25]
	v_max3_f32 v7, v7, |v9|, |v26|
	v_cvt_pk_bf16_f32 v23, v118, v119
	v_cvt_pk_bf16_f32 v24, v124, v125
	v_cvt_pk_bf16_f32 v25, v122, v123
	ds_bpermute_b32 v8, v233, v6
	v_lshlrev_b32_e32 v30, 16, v23
	v_and_b32_e32 v31, 0xffff0000, v23
	v_lshlrev_b32_e32 v32, 16, v24
	v_and_b32_e32 v33, 0xffff0000, v24
	v_max3_f32 v7, v7, |v30|, |v31|
	v_lshlrev_b32_e32 v40, 16, v25
	v_and_b32_e32 v41, 0xffff0000, v25
	v_max3_f32 v7, v7, |v32|, |v33|
	v_max3_f32 v9, v7, |v40|, |v41|
	ds_bpermute_b32 v26, v233, v9
	s_waitcnt lgkmcnt(1)
	v_add_f32_e32 v6, v6, v8
	ds_bpermute_b32 v7, v216, v6
	global_store_dwordx4 v[44:45], v[22:25], off offset:256 sc1
	s_waitcnt lgkmcnt(1)
	v_max_f32_e32 v8, v26, v26
	v_max_f32_e32 v8, v9, v8
	ds_bpermute_b32 v9, v216, v8
	s_and_saveexec_b64 s[42:43], s[0:1]
	s_cbranch_execz .LBB0_2780
	s_waitcnt lgkmcnt(0)
	v_max_f32_e32 v9, v9, v9
	v_max_f32_e32 v8, v8, v8
	v_add_f32_e32 v23, v6, v7
	v_lshlrev_b64 v[6:7], 7, v[36:37]
	v_max_f32_e32 v22, v8, v9
	v_lshl_add_u64 v[8:9], s[26:27], 0, v[6:7]
	s_lshl_b64 s[82:83], s[40:41], 2
	v_lshl_add_u64 v[6:7], s[28:29], 0, v[6:7]
	v_lshl_add_u64 v[8:9], v[8:9], 0, s[82:83]
	s_lshl_b32 s12, s63, 2
	v_lshl_add_u64 v[6:7], v[6:7], 0, s[82:83]
	v_lshl_add_u64 v[8:9], v[8:9], 0, s[12:13]
	v_lshl_add_u64 v[6:7], v[6:7], 0, s[12:13]
	global_store_dword v[8:9], v23, off
	global_store_dword v[6:7], v22, off
.LBB0_2780:
	s_or_b64 exec, exec, s[42:43]
	v_or_b32_e32 v36, 48, v176
	v_ashrrev_i32_e32 v37, 31, v36
	s_waitcnt lgkmcnt(1)
	v_lshlrev_b64 v[6:7], 13, v[36:37]
	v_lshl_add_u64 v[6:7], s[16:17], 0, v[6:7]
	v_lshl_add_u64 v[40:41], v[90:91], 2, v[6:7]
	global_load_dwordx4 v[26:29], v[40:41], off offset:16 nt
	global_load_dwordx4 v[30:33], v[40:41], off nt
	s_waitcnt lgkmcnt(0)
	global_load_dwordx4 v[6:9], v[40:41], off offset:528 nt
	global_load_dwordx4 v[22:25], v[40:41], off offset:512 nt
	v_lshl_add_u64 v[42:43], v[34:35], 2, s[18:19]
	global_load_dword v42, v[42:43], off
	v_lshlrev_b64 v[44:45], 12, v[34:35]
	v_lshl_add_u64 v[44:45], s[22:23], 0, v[44:45]
	v_lshl_add_u64 v[44:45], v[90:91], 1, v[44:45]
	s_waitcnt vmcnt(0)
	v_pk_mul_f32 v[68:69], v[42:43], v[68:69] op_sel_hi:[0,1]
	v_pk_mul_f32 v[64:65], v[42:43], v[64:65] op_sel_hi:[0,1]
	v_pk_mul_f32 v[62:63], v[42:43], v[62:63] op_sel_hi:[0,1]
	v_pk_mul_f32 v[66:67], v[42:43], v[66:67] op_sel_hi:[0,1]
	v_pk_mul_f32 v[74:75], v[42:43], v[74:75] op_sel_hi:[0,1]
	v_pk_mul_f32 v[70:71], v[42:43], v[70:71] op_sel_hi:[0,1]
	v_pk_fma_f32 v[14:15], v[94:95], v[68:69], v[14:15]
	v_pk_mul_f32 v[76:77], v[42:43], v[76:77] op_sel_hi:[0,1]
	v_pk_mul_f32 v[42:43], v[42:43], v[72:73] op_sel_hi:[0,1]
	v_pk_fma_f32 v[20:21], v[86:87], v[62:63], v[20:21]
	v_pk_fma_f32 v[18:19], v[88:89], v[64:65], v[18:19]
	v_pk_fma_f32 v[16:17], v[92:93], v[66:67], v[16:17]
	v_pk_fma_f32 v[12:13], v[104:105], v[70:71], v[12:13]
	v_pk_fma_f32 v[10:11], v[106:107], v[74:75], v[10:11]
	v_mul_f32_e32 v112, v15, v15
	v_pk_fma_f32 v[4:5], v[110:111], v[42:43], v[4:5]
	v_pk_fma_f32 v[2:3], v[108:109], v[76:77], v[2:3]
	global_store_dwordx4 v[38:39], v[18:21], off nt
	global_store_dwordx4 v[38:39], v[14:17], off offset:16 nt
	v_mul_f32_e32 v76, v19, v19
	v_mul_f32_e32 v77, v21, v21
	v_mul_f32_e32 v113, v17, v17
	v_pk_mul_f32 v[42:43], v[78:79], v[20:21]
	v_pk_mul_f32 v[62:63], v[80:81], v[18:19]
	v_pk_mul_f32 v[66:67], v[84:85], v[14:15]
	v_mul_f32_e32 v19, v11, v11
	v_mul_f32_e32 v21, v13, v13
	v_fmac_f32_e32 v112, v14, v14
	v_cvt_pk_bf16_f32 v14, v62, v63
	v_pk_mul_f32 v[64:65], v[82:83], v[16:17]
	v_mul_f32_e32 v114, v3, v3
	v_mul_f32_e32 v115, v5, v5
	v_fmac_f32_e32 v76, v18, v18
	v_fmac_f32_e32 v77, v20, v20
	v_fmac_f32_e32 v113, v16, v16
	v_cvt_pk_bf16_f32 v15, v42, v43
	v_cvt_pk_bf16_f32 v16, v66, v67
	v_cvt_pk_bf16_f32 v17, v64, v65
	v_fmac_f32_e32 v19, v10, v10
	v_fmac_f32_e32 v21, v12, v12
	global_store_dwordx4 v[44:45], v[14:17], off sc1
	v_lshlrev_b32_e32 v20, 16, v14
	v_pk_mul_f32 v[72:73], v[100:101], v[4:5]
	v_and_b32_e32 v14, 0xffff0000, v14
	v_pk_mul_f32 v[74:75], v[102:103], v[2:3]
	v_fmac_f32_e32 v114, v2, v2
	v_fmac_f32_e32 v115, v4, v4
	v_add_f32_e32 v18, v76, v77
	v_lshlrev_b32_e32 v42, 16, v15
	v_and_b32_e32 v15, 0xffff0000, v15
	global_store_dwordx4 v[38:39], v[10:13], off offset:512 nt
	global_store_dwordx4 v[38:39], v[2:5], off offset:528 nt
	v_lshlrev_b32_e32 v43, 16, v16
	v_and_b32_e32 v16, 0xffff0000, v16
	v_add_f32_e32 v2, v19, v21
	v_max3_f32 v4, |v20|, 0, |v14|
	v_add_f32_e32 v3, v112, v18
	v_add_f32_e32 v2, v114, v2
	v_max3_f32 v4, v4, |v42|, |v15|
	v_lshlrev_b32_e32 v62, 16, v17
	v_and_b32_e32 v17, 0xffff0000, v17
	v_add_f32_e32 v3, v113, v3
	v_add_f32_e32 v2, v115, v2
	v_max3_f32 v4, v4, |v43|, |v16|
	v_pk_mul_f32 v[70:71], v[98:99], v[10:11]
	v_add_f32_e32 v2, v3, v2
	v_cvt_pk_bf16_f32 v10, v70, v71
	v_max3_f32 v3, v4, |v62|, |v17|
	v_lshlrev_b32_e32 v5, 16, v10
	v_and_b32_e32 v14, 0xffff0000, v10
	v_pk_mul_f32 v[68:69], v[96:97], v[12:13]
	v_max3_f32 v3, v3, |v5|, |v14|
	v_cvt_pk_bf16_f32 v11, v68, v69
	v_cvt_pk_bf16_f32 v12, v74, v75
	v_cvt_pk_bf16_f32 v13, v72, v73
	ds_bpermute_b32 v4, v233, v2
	v_lshlrev_b32_e32 v18, 16, v11
	v_and_b32_e32 v19, 0xffff0000, v11
	v_lshlrev_b32_e32 v20, 16, v12
	v_and_b32_e32 v21, 0xffff0000, v12
	v_max3_f32 v3, v3, |v18|, |v19|
	v_lshlrev_b32_e32 v38, 16, v13
	v_and_b32_e32 v39, 0xffff0000, v13
	v_max3_f32 v3, v3, |v20|, |v21|
	v_max3_f32 v5, v3, |v38|, |v39|
	ds_bpermute_b32 v14, v233, v5
	s_waitcnt lgkmcnt(1)
	v_add_f32_e32 v2, v2, v4
	ds_bpermute_b32 v3, v216, v2
	global_store_dwordx4 v[44:45], v[10:13], off offset:256 sc1
	s_waitcnt lgkmcnt(1)
	v_max_f32_e32 v4, v14, v14
	v_max_f32_e32 v4, v5, v4
	ds_bpermute_b32 v5, v216, v4
	s_and_saveexec_b64 s[42:43], s[0:1]
	s_cbranch_execz .LBB0_2782
	s_waitcnt lgkmcnt(0)
	v_max_f32_e32 v5, v5, v5
	v_max_f32_e32 v4, v4, v4
	v_add_f32_e32 v11, v2, v3
	v_lshlrev_b64 v[2:3], 7, v[34:35]
	v_max_f32_e32 v10, v4, v5
	v_lshl_add_u64 v[4:5], s[26:27], 0, v[2:3]
	s_lshl_b64 s[82:83], s[40:41], 2
	v_lshl_add_u64 v[2:3], s[28:29], 0, v[2:3]
	v_lshl_add_u64 v[4:5], v[4:5], 0, s[82:83]
	s_lshl_b32 s12, s63, 2
	v_lshl_add_u64 v[2:3], v[2:3], 0, s[82:83]
	v_lshl_add_u64 v[4:5], v[4:5], 0, s[12:13]
	v_lshl_add_u64 v[2:3], v[2:3], 0, s[12:13]
	global_store_dword v[4:5], v11, off
	global_store_dword v[2:3], v10, off
.LBB0_2782:
	s_or_b64 exec, exec, s[42:43]
	s_waitcnt lgkmcnt(1)
	v_lshl_add_u64 v[2:3], v[36:37], 2, s[18:19]
	global_load_dword v2, v[2:3], off
	s_waitcnt lgkmcnt(0)
	v_lshlrev_b64 v[4:5], 12, v[36:37]
	v_lshl_add_u64 v[4:5], s[22:23], 0, v[4:5]
	v_lshl_add_u64 v[18:19], v[90:91], 1, v[4:5]
	s_waitcnt vmcnt(0)
	v_pk_mul_f32 v[10:11], v[2:3], v[48:49] op_sel_hi:[0,1]
	v_pk_mul_f32 v[4:5], v[2:3], v[46:47] op_sel_hi:[0,1]
	v_pk_mul_f32 v[14:15], v[2:3], v[52:53] op_sel_hi:[0,1]
	v_pk_mul_f32 v[12:13], v[2:3], v[50:51] op_sel_hi:[0,1]
	v_pk_mul_f32 v[20:21], v[2:3], v[58:59] op_sel_hi:[0,1]
	v_pk_mul_f32 v[16:17], v[2:3], v[54:55] op_sel_hi:[0,1]
	v_pk_mul_f32 v[34:35], v[2:3], v[60:61] op_sel_hi:[0,1]
	v_pk_mul_f32 v[38:39], v[2:3], v[56:57] op_sel_hi:[0,1]
	v_pk_fma_f32 v[2:3], v[88:89], v[10:11], v[30:31]
	v_pk_fma_f32 v[4:5], v[86:87], v[4:5], v[32:33]
	v_pk_fma_f32 v[12:13], v[92:93], v[12:13], v[28:29]
	v_pk_fma_f32 v[8:9], v[110:111], v[38:39], v[8:9]
	v_mul_f32_e32 v38, v3, v3
	v_pk_fma_f32 v[10:11], v[94:95], v[14:15], v[26:27]
	v_pk_fma_f32 v[14:15], v[106:107], v[20:21], v[22:23]
	global_store_dwordx4 v[40:41], v[2:5], off nt
	global_store_dwordx4 v[40:41], v[10:13], off offset:16 nt
	v_mul_f32_e32 v39, v5, v5
	v_mul_f32_e32 v43, v13, v13
	v_pk_mul_f32 v[22:23], v[80:81], v[2:3]
	v_fmac_f32_e32 v38, v2, v2
	v_cvt_pk_bf16_f32 v2, v22, v23
	v_pk_fma_f32 v[16:17], v[104:105], v[16:17], v[24:25]
	v_pk_mul_f32 v[20:21], v[78:79], v[4:5]
	v_pk_mul_f32 v[24:25], v[82:83], v[12:13]
	v_pk_mul_f32 v[26:27], v[84:85], v[10:11]
	v_fmac_f32_e32 v39, v4, v4
	v_fmac_f32_e32 v43, v12, v12
	v_cvt_pk_bf16_f32 v3, v20, v21
	v_cvt_pk_bf16_f32 v4, v26, v27
	v_cvt_pk_bf16_f32 v5, v24, v25
	global_store_dwordx4 v[18:19], v[2:5], off sc1
	v_lshlrev_b32_e32 v12, 16, v2
	v_lshlrev_b32_e32 v20, 16, v3
	v_and_b32_e32 v2, 0xffff0000, v2
	v_and_b32_e32 v3, 0xffff0000, v3
	v_max3_f32 v2, |v12|, 0, |v2|
	v_pk_fma_f32 v[6:7], v[108:109], v[34:35], v[6:7]
	v_mul_f32_e32 v42, v11, v11
	v_mul_f32_e32 v11, v15, v15
	v_mul_f32_e32 v13, v17, v17
	v_lshlrev_b32_e32 v21, 16, v4
	v_and_b32_e32 v4, 0xffff0000, v4
	v_max3_f32 v2, v2, |v20|, |v3|
	v_mul_f32_e32 v44, v7, v7
	v_fmac_f32_e32 v11, v14, v14
	v_fmac_f32_e32 v13, v16, v16
	v_lshlrev_b32_e32 v22, 16, v5
	v_and_b32_e32 v5, 0xffff0000, v5
	v_max3_f32 v2, v2, |v21|, |v4|
	v_pk_mul_f32 v[30:31], v[98:99], v[14:15]
	v_pk_mul_f32 v[34:35], v[102:103], v[6:7]
	v_fmac_f32_e32 v44, v6, v6
	global_store_dwordx4 v[40:41], v[14:17], off offset:512 nt
	global_store_dwordx4 v[40:41], v[6:9], off offset:528 nt
	v_add_f32_e32 v11, v11, v13
	v_max3_f32 v2, v2, |v22|, |v5|
	v_cvt_pk_bf16_f32 v6, v30, v31
	v_mul_f32_e32 v45, v9, v9
	v_lshlrev_b32_e32 v12, 16, v6
	v_and_b32_e32 v13, 0xffff0000, v6
	v_pk_mul_f32 v[28:29], v[96:97], v[16:17]
	v_fmac_f32_e32 v42, v10, v10
	v_add_f32_e32 v10, v38, v39
	v_cvt_pk_bf16_f32 v7, v28, v29
	v_max3_f32 v2, v2, |v12|, |v13|
	v_lshlrev_b32_e32 v14, 16, v7
	v_and_b32_e32 v15, 0xffff0000, v7
	v_pk_mul_f32 v[32:33], v[100:101], v[8:9]
	v_fmac_f32_e32 v45, v8, v8
	v_cvt_pk_bf16_f32 v8, v34, v35
	v_add_f32_e32 v10, v42, v10
	v_add_f32_e32 v11, v44, v11
	v_lshlrev_b32_e32 v16, 16, v8
	v_and_b32_e32 v17, 0xffff0000, v8
	v_max3_f32 v2, v2, |v14|, |v15|
	v_cvt_pk_bf16_f32 v9, v32, v33
	v_add_f32_e32 v10, v43, v10
	v_lshlrev_b32_e32 v23, 16, v9
	v_and_b32_e32 v24, 0xffff0000, v9
	v_add_f32_e32 v3, v45, v11
	v_max3_f32 v2, v2, |v16|, |v17|
	v_add_f32_e32 v3, v10, v3
	v_max3_f32 v5, v2, |v23|, |v24|
	ds_bpermute_b32 v4, v233, v3
	ds_bpermute_b32 v10, v233, v5
	global_store_dwordx4 v[18:19], v[6:9], off offset:256 sc1
	s_waitcnt lgkmcnt(1)
	v_add_f32_e32 v2, v3, v4
	s_waitcnt lgkmcnt(0)
	v_max_f32_e32 v4, v10, v10
	v_max_f32_e32 v4, v5, v4
	ds_bpermute_b32 v3, v216, v2
	ds_bpermute_b32 v5, v216, v4
	s_and_saveexec_b64 s[42:43], s[0:1]
	s_cbranch_execz .LBB0_2784
	s_waitcnt lgkmcnt(0)
	v_max_f32_e32 v5, v5, v5
	v_max_f32_e32 v4, v4, v4
	v_add_f32_e32 v7, v2, v3
	v_lshlrev_b64 v[2:3], 7, v[36:37]
	v_max_f32_e32 v6, v4, v5
	v_lshl_add_u64 v[4:5], s[26:27], 0, v[2:3]
	s_lshl_b64 s[40:41], s[40:41], 2
	v_lshl_add_u64 v[2:3], s[28:29], 0, v[2:3]
	v_lshl_add_u64 v[4:5], v[4:5], 0, s[40:41]
	s_lshl_b32 s12, s63, 2
	v_lshl_add_u64 v[2:3], v[2:3], 0, s[40:41]
	v_lshl_add_u64 v[4:5], v[4:5], 0, s[12:13]
	v_lshl_add_u64 v[2:3], v[2:3], 0, s[12:13]
	global_store_dword v[4:5], v7, off
	global_store_dword v[2:3], v6, off

.LBB0_2953:
	s_lshl_b32 s26, s30, 8
	s_add_i32 s28, s26, s56
	s_lshl_b32 s26, s31, 8
	s_or_b32 s29, s26, s57
	s_lshr_b32 s26, s30, 4
	s_add_i32 s26, s26, -1
	v_or_b32_e32 v2, s29, v186
	s_cmp_gt_i32 s30, 31
	s_cselect_b32 s26, s26, 0
	v_ashrrev_i32_e32 v3, 31, v2
	v_or_b32_e32 v168, s28, v187
	v_lshlrev_b64 v[10:11], 2, v[2:3]
	v_ashrrev_i32_e32 v169, 31, v168
	s_ashr_i32 s27, s26, 31
	v_lshl_add_u64 v[12:13], s[16:17], 0, v[10:11]
	v_lshl_add_u64 v[100:101], v[168:169], 2, s[14:15]
	s_lshl_b64 s[26:27], s[26:27], 15
	global_load_dwordx4 v[2:5], v[12:13], off offset:16
	global_load_dwordx4 v[6:9], v[12:13], off
	global_load_dword v190, v[100:101], off
	s_add_u32 s26, s47, s26
	global_load_dwordx4 v[14:17], v[12:13], off offset:528
	global_load_dwordx4 v[30:33], v[12:13], off offset:512
	s_addc_u32 s27, s50, s27
	v_lshl_add_u64 v[10:11], s[26:27], 0, v[10:11]
	global_load_dwordx4 v[26:29], v[10:11], off
	global_load_dwordx4 v[22:25], v[10:11], off offset:16
	global_load_dwordx4 v[18:21], v[10:11], off offset:512
	s_nop 0
	global_load_dwordx4 v[10:13], v[10:11], off offset:528
	s_ashr_i32 s28, s28, 8
	v_bitop3_b32 v90, s29, 56, v186 bitop3:0xc8
	s_ashr_i32 s26, s29, 6
	s_ashr_i32 s29, s28, 31
	s_ashr_i32 s27, s26, 31
	s_lshl_b64 s[34:35], s[28:29], 7
	s_add_u32 s28, s34, s26
	s_addc_u32 s29, s35, s27
	s_lshl_b64 s[28:29], s[28:29], 15
	s_add_u32 s30, s12, s28
	s_addc_u32 s31, s13, s29
	s_or_b32 s28, s26, 2
	s_ashr_i32 s29, s28, 31
	s_add_u32 s34, s34, s28
	v_lshlrev_b32_e32 v169, 7, v168
	s_addc_u32 s35, s35, s29
	v_and_b32_e32 v138, 0x6780, v169
	s_lshl_b64 s[34:35], s[34:35], 15
	v_mov_b32_e32 v91, v139
	v_lshlrev_b32_e32 v90, 1, v90
	v_lshl_add_u64 v[192:193], s[30:31], 0, v[138:139]
	s_add_u32 s34, s12, s34
	v_lshl_add_u64 v[192:193], v[192:193], 0, v[90:91]
	s_addc_u32 s35, s13, s35
	s_and_b64 vcc, exec, s[0:1]
	s_mov_b64 s[0:1], -1
	s_waitcnt vmcnt(0)
	v_pk_mul_f32 v[194:195], v[6:7], v[190:191] op_sel_hi:[1,0]
	v_pk_mul_f32 v[196:197], v[8:9], v[190:191] op_sel_hi:[1,0]
	v_pk_mul_f32 v[198:199], v[2:3], v[190:191] op_sel_hi:[1,0]
	v_pk_mul_f32 v[204:205], v[32:33], v[190:191] op_sel_hi:[1,0]
	v_pk_fma_f32 v[170:171], v[196:197], v[170:171], v[28:29]
	v_pk_fma_f32 v[172:173], v[194:195], v[172:173], v[26:27]
	v_pk_mul_f32 v[200:201], v[4:5], v[190:191] op_sel_hi:[1,0]
	v_pk_mul_f32 v[202:203], v[30:31], v[190:191] op_sel_hi:[1,0]
	v_pk_mul_f32 v[206:207], v[14:15], v[190:191] op_sel_hi:[1,0]
	v_pk_mul_f32 v[190:191], v[16:17], v[190:191] op_sel_hi:[1,0]
	v_pk_fma_f32 v[174:175], v[198:199], v[174:175], v[22:23]
	v_pk_fma_f32 v[182:183], v[204:205], v[182:183], v[20:21]
	v_max_f32_e32 v173, 0, v173
	v_max_f32_e32 v172, 0, v172
	v_max_f32_e32 v171, 0, v171
	v_max_f32_e32 v170, 0, v170
	v_pk_fma_f32 v[176:177], v[200:201], v[176:177], v[24:25]
	v_pk_fma_f32 v[180:181], v[202:203], v[180:181], v[18:19]
	v_pk_fma_f32 v[184:185], v[190:191], v[184:185], v[12:13]
	v_max_f32_e32 v175, 0, v175
	v_max_f32_e32 v174, 0, v174
	v_max_f32_e32 v183, 0, v183
	v_max_f32_e32 v182, 0, v182
	v_pk_mul_f32 v[190:191], v[170:171], v[170:171]
	v_pk_mul_f32 v[170:171], v[172:173], v[172:173]
	v_max_f32_e32 v177, 0, v177
	v_max_f32_e32 v176, 0, v176
	v_max_f32_e32 v181, 0, v181
	v_max_f32_e32 v180, 0, v180
	v_pk_mul_f32 v[172:173], v[174:175], v[174:175]
	v_pk_mul_f32 v[174:175], v[182:183], v[182:183]
	v_cvt_pk_bf16_f32 v170, v170, v171
	v_cvt_pk_bf16_f32 v171, v190, v191
	v_pk_fma_f32 v[178:179], v[206:207], v[178:179], v[10:11]
	v_pk_mul_f32 v[176:177], v[176:177], v[176:177]
	v_pk_mul_f32 v[180:181], v[180:181], v[180:181]
	v_cvt_pk_bf16_f32 v172, v172, v173
	v_cvt_pk_bf16_f32 v173, v176, v177
	global_store_dwordx4 v[192:193], v[170:173], off sc1
	v_max_f32_e32 v179, 0, v179
	v_max_f32_e32 v178, 0, v178
	v_cvt_pk_bf16_f32 v170, v180, v181
	v_cvt_pk_bf16_f32 v171, v174, v175
	v_lshl_add_u64 v[174:175], s[34:35], 0, v[138:139]
	v_max_f32_e32 v185, 0, v185
	v_max_f32_e32 v184, 0, v184
	v_lshl_add_u64 v[174:175], v[174:175], 0, v[90:91]
	v_pk_mul_f32 v[182:183], v[184:185], v[184:185]
	v_pk_mul_f32 v[178:179], v[178:179], v[178:179]
	s_nop 0
	v_cvt_pk_bf16_f32 v172, v178, v179
	v_cvt_pk_bf16_f32 v173, v182, v183
	global_store_dwordx4 v[174:175], v[170:173], off sc1
	v_or_b32_e32 v174, 32, v168
	v_ashrrev_i32_e32 v175, 31, v174
	v_or_b32_e32 v170, 16, v168
	v_ashrrev_i32_e32 v171, 31, v170
	v_lshl_add_u64 v[172:173], v[170:171], 2, s[14:15]
	global_load_dword v172, v[172:173], off
	v_lshlrev_b32_e32 v138, 7, v170
	v_and_b32_e32 v138, 0x6f80, v138
	v_lshl_add_u64 v[176:177], s[30:31], 0, v[138:139]
	v_lshl_add_u64 v[178:179], s[34:35], 0, v[138:139]
	v_lshl_add_u64 v[176:177], v[176:177], 0, v[90:91]
	v_lshl_add_u64 v[178:179], v[178:179], 0, v[90:91]
	v_lshl_add_u64 v[170:171], v[174:175], 2, s[14:15]
	v_lshlrev_b32_e32 v138, 7, v174
	v_and_b32_e32 v138, 0x7780, v138
	s_waitcnt vmcnt(0)
	v_pk_mul_f32 v[180:181], v[6:7], v[172:173] op_sel_hi:[1,0]
	v_pk_mul_f32 v[182:183], v[8:9], v[172:173] op_sel_hi:[1,0]
	v_pk_mul_f32 v[184:185], v[2:3], v[172:173] op_sel_hi:[1,0]
	v_pk_mul_f32 v[190:191], v[4:5], v[172:173] op_sel_hi:[1,0]
	v_pk_fma_f32 v[154:155], v[182:183], v[154:155], v[28:29]
	v_pk_fma_f32 v[152:153], v[180:181], v[152:153], v[26:27]
	v_pk_mul_f32 v[192:193], v[30:31], v[172:173] op_sel_hi:[1,0]
	v_pk_mul_f32 v[194:195], v[32:33], v[172:173] op_sel_hi:[1,0]
	v_pk_mul_f32 v[196:197], v[14:15], v[172:173] op_sel_hi:[1,0]
	v_pk_mul_f32 v[172:173], v[16:17], v[172:173] op_sel_hi:[1,0]
	v_pk_fma_f32 v[158:159], v[190:191], v[158:159], v[24:25]
	v_pk_fma_f32 v[156:157], v[184:185], v[156:157], v[22:23]
	v_max_f32_e32 v153, 0, v153
	v_max_f32_e32 v152, 0, v152
	v_max_f32_e32 v155, 0, v155
	v_max_f32_e32 v154, 0, v154
	v_pk_fma_f32 v[162:163], v[194:195], v[162:163], v[20:21]
	v_pk_fma_f32 v[160:161], v[192:193], v[160:161], v[18:19]
	v_pk_fma_f32 v[166:167], v[172:173], v[166:167], v[12:13]
	v_pk_fma_f32 v[164:165], v[196:197], v[164:165], v[10:11]
	v_max_f32_e32 v157, 0, v157
	v_max_f32_e32 v156, 0, v156
	v_max_f32_e32 v159, 0, v159
	v_max_f32_e32 v158, 0, v158
	v_pk_mul_f32 v[154:155], v[154:155], v[154:155]
	v_pk_mul_f32 v[152:153], v[152:153], v[152:153]
	v_max_f32_e32 v161, 0, v161
	v_max_f32_e32 v160, 0, v160
	v_max_f32_e32 v163, 0, v163
	v_max_f32_e32 v162, 0, v162
	v_max_f32_e32 v165, 0, v165
	v_max_f32_e32 v164, 0, v164
	v_max_f32_e32 v167, 0, v167
	v_max_f32_e32 v166, 0, v166
	v_pk_mul_f32 v[158:159], v[158:159], v[158:159]
	v_pk_mul_f32 v[156:157], v[156:157], v[156:157]
	v_cvt_pk_bf16_f32 v152, v152, v153
	v_cvt_pk_bf16_f32 v153, v154, v155
	v_pk_mul_f32 v[162:163], v[162:163], v[162:163]
	v_cvt_pk_bf16_f32 v154, v156, v157
	v_cvt_pk_bf16_f32 v155, v158, v159
	v_pk_mul_f32 v[160:161], v[160:161], v[160:161]
	v_pk_mul_f32 v[166:167], v[166:167], v[166:167]
	v_pk_mul_f32 v[164:165], v[164:165], v[164:165]
	global_store_dwordx4 v[176:177], v[152:155], off sc1
	v_lshl_add_u64 v[158:159], s[30:31], 0, v[138:139]
	v_lshl_add_u64 v[158:159], v[158:159], 0, v[90:91]
	v_cvt_pk_bf16_f32 v152, v160, v161
	v_cvt_pk_bf16_f32 v153, v162, v163
	v_cvt_pk_bf16_f32 v154, v164, v165
	v_cvt_pk_bf16_f32 v155, v166, v167
	global_store_dwordx4 v[178:179], v[152:155], off sc1
	global_load_dword v152, v[170:171], off
	v_lshl_add_u64 v[160:161], s[34:35], 0, v[138:139]
	v_or_b32_e32 v154, 48, v168
	v_ashrrev_i32_e32 v155, 31, v154
	v_lshl_add_u64 v[160:161], v[160:161], 0, v[90:91]
	v_lshl_add_u64 v[156:157], v[154:155], 2, s[14:15]
	s_waitcnt vmcnt(0)
	v_pk_mul_f32 v[162:163], v[6:7], v[152:153] op_sel_hi:[1,0]
	v_pk_mul_f32 v[164:165], v[8:9], v[152:153] op_sel_hi:[1,0]
	v_pk_mul_f32 v[166:167], v[2:3], v[152:153] op_sel_hi:[1,0]
	v_pk_mul_f32 v[170:171], v[4:5], v[152:153] op_sel_hi:[1,0]
	v_pk_fma_f32 v[120:121], v[164:165], v[120:121], v[28:29]
	v_pk_fma_f32 v[118:119], v[162:163], v[118:119], v[26:27]
	v_pk_mul_f32 v[172:173], v[30:31], v[152:153] op_sel_hi:[1,0]
	v_pk_mul_f32 v[174:175], v[32:33], v[152:153] op_sel_hi:[1,0]
	v_pk_mul_f32 v[176:177], v[14:15], v[152:153] op_sel_hi:[1,0]
	v_pk_mul_f32 v[152:153], v[16:17], v[152:153] op_sel_hi:[1,0]
	v_pk_fma_f32 v[124:125], v[170:171], v[124:125], v[24:25]
	v_pk_fma_f32 v[122:123], v[166:167], v[122:123], v[22:23]
	v_max_f32_e32 v119, 0, v119
	v_max_f32_e32 v118, 0, v118
	v_max_f32_e32 v121, 0, v121
	v_max_f32_e32 v120, 0, v120
	v_pk_fma_f32 v[128:129], v[174:175], v[128:129], v[20:21]
	v_pk_fma_f32 v[126:127], v[172:173], v[126:127], v[18:19]
	v_pk_fma_f32 v[150:151], v[152:153], v[150:151], v[12:13]
	v_pk_fma_f32 v[148:149], v[176:177], v[148:149], v[10:11]
	v_max_f32_e32 v123, 0, v123
	v_max_f32_e32 v122, 0, v122
	v_max_f32_e32 v125, 0, v125
	v_max_f32_e32 v124, 0, v124
	v_pk_mul_f32 v[120:121], v[120:121], v[120:121]
	v_pk_mul_f32 v[118:119], v[118:119], v[118:119]
	v_max_f32_e32 v127, 0, v127
	v_max_f32_e32 v126, 0, v126
	v_max_f32_e32 v129, 0, v129
	v_max_f32_e32 v128, 0, v128
	v_max_f32_e32 v149, 0, v149
	v_max_f32_e32 v148, 0, v148
	v_max_f32_e32 v151, 0, v151
	v_max_f32_e32 v150, 0, v150
	v_pk_mul_f32 v[124:125], v[124:125], v[124:125]
	v_pk_mul_f32 v[122:123], v[122:123], v[122:123]
	v_cvt_pk_bf16_f32 v118, v118, v119
	v_cvt_pk_bf16_f32 v119, v120, v121
	v_pk_mul_f32 v[128:129], v[128:129], v[128:129]
	v_cvt_pk_bf16_f32 v120, v122, v123
	v_cvt_pk_bf16_f32 v121, v124, v125
	v_pk_mul_f32 v[126:127], v[126:127], v[126:127]
	v_pk_mul_f32 v[150:151], v[150:151], v[150:151]
	v_pk_mul_f32 v[148:149], v[148:149], v[148:149]
	global_store_dwordx4 v[158:159], v[118:121], off sc1
	s_nop 1
	v_cvt_pk_bf16_f32 v118, v126, v127
	v_cvt_pk_bf16_f32 v119, v128, v129
	v_cvt_pk_bf16_f32 v120, v148, v149
	v_cvt_pk_bf16_f32 v121, v150, v151
	global_store_dwordx4 v[160:161], v[118:121], off sc1
	global_load_dword v118, v[156:157], off
	s_nop 0
	v_lshlrev_b32_e32 v119, 7, v154
	v_and_b32_e32 v138, 0x7f80, v119
	v_lshl_add_u64 v[120:121], s[30:31], 0, v[138:139]
	v_lshl_add_u64 v[122:123], s[34:35], 0, v[138:139]
	v_lshl_add_u64 v[120:121], v[120:121], 0, v[90:91]
	v_lshl_add_u64 v[122:123], v[122:123], 0, v[90:91]
	s_waitcnt vmcnt(0)
	v_pk_mul_f32 v[124:125], v[6:7], v[118:119] op_sel_hi:[1,0]
	v_pk_mul_f32 v[126:127], v[8:9], v[118:119] op_sel_hi:[1,0]
	v_pk_mul_f32 v[128:129], v[2:3], v[118:119] op_sel_hi:[1,0]
	v_pk_mul_f32 v[148:149], v[4:5], v[118:119] op_sel_hi:[1,0]
	v_pk_fma_f32 v[104:105], v[126:127], v[104:105], v[28:29]
	v_pk_fma_f32 v[102:103], v[124:125], v[102:103], v[26:27]
	v_pk_mul_f32 v[150:151], v[30:31], v[118:119] op_sel_hi:[1,0]
	v_pk_mul_f32 v[152:153], v[32:33], v[118:119] op_sel_hi:[1,0]
	v_pk_mul_f32 v[154:155], v[14:15], v[118:119] op_sel_hi:[1,0]
	v_pk_mul_f32 v[118:119], v[16:17], v[118:119] op_sel_hi:[1,0]
	v_pk_fma_f32 v[108:109], v[148:149], v[108:109], v[24:25]
	v_pk_fma_f32 v[106:107], v[128:129], v[106:107], v[22:23]
	v_max_f32_e32 v103, 0, v103
	v_max_f32_e32 v102, 0, v102
	v_max_f32_e32 v105, 0, v105
	v_max_f32_e32 v104, 0, v104
	v_pk_fma_f32 v[112:113], v[152:153], v[112:113], v[20:21]
	v_pk_fma_f32 v[110:111], v[150:151], v[110:111], v[18:19]
	v_pk_fma_f32 v[116:117], v[118:119], v[116:117], v[12:13]
	v_pk_fma_f32 v[114:115], v[154:155], v[114:115], v[10:11]
	v_max_f32_e32 v107, 0, v107
	v_max_f32_e32 v106, 0, v106
	v_max_f32_e32 v109, 0, v109
	v_max_f32_e32 v108, 0, v108
	v_pk_mul_f32 v[104:105], v[104:105], v[104:105]
	v_pk_mul_f32 v[102:103], v[102:103], v[102:103]
	v_max_f32_e32 v111, 0, v111
	v_max_f32_e32 v110, 0, v110
	v_max_f32_e32 v113, 0, v113
	v_max_f32_e32 v112, 0, v112
	v_max_f32_e32 v115, 0, v115
	v_max_f32_e32 v114, 0, v114
	v_max_f32_e32 v117, 0, v117
	v_max_f32_e32 v116, 0, v116
	v_pk_mul_f32 v[108:109], v[108:109], v[108:109]
	v_pk_mul_f32 v[106:107], v[106:107], v[106:107]
	v_cvt_pk_bf16_f32 v102, v102, v103
	v_cvt_pk_bf16_f32 v103, v104, v105
	v_pk_mul_f32 v[112:113], v[112:113], v[112:113]
	v_cvt_pk_bf16_f32 v104, v106, v107
	v_cvt_pk_bf16_f32 v105, v108, v109
	v_pk_mul_f32 v[110:111], v[110:111], v[110:111]
	v_pk_mul_f32 v[116:117], v[116:117], v[116:117]
	v_pk_mul_f32 v[114:115], v[114:115], v[114:115]
	global_store_dwordx4 v[120:121], v[102:105], off sc1
	s_nop 1
	v_cvt_pk_bf16_f32 v102, v110, v111
	v_cvt_pk_bf16_f32 v103, v112, v113
	v_cvt_pk_bf16_f32 v104, v114, v115
	v_cvt_pk_bf16_f32 v105, v116, v117
	global_store_dwordx4 v[122:123], v[102:105], off sc1
	global_load_dword v106, v[100:101], off offset:512
	s_nop 0
	v_add_u32_e32 v103, 0x80, v168
	v_ashrrev_i32_e32 v102, 8, v103
	v_lshlrev_b32_e32 v107, 7, v103
	v_ashrrev_i32_e32 v103, 31, v102
	v_lshlrev_b64 v[104:105], 7, v[102:103]
	v_lshl_add_u64 v[102:103], v[104:105], 0, s[26:27]
	v_lshl_add_u64 v[104:105], v[104:105], 0, s[28:29]
	v_lshlrev_b64 v[102:103], 15, v[102:103]
	v_lshlrev_b64 v[104:105], 15, v[104:105]
	v_lshl_add_u64 v[102:103], s[12:13], 0, v[102:103]
	v_lshl_add_u64 v[104:105], s[12:13], 0, v[104:105]
	v_and_b32_e32 v138, 0x6780, v107
	v_lshl_add_u64 v[108:109], v[102:103], 0, v[138:139]
	v_lshl_add_u64 v[110:111], v[104:105], 0, v[138:139]
	v_lshl_add_u64 v[108:109], v[108:109], 0, v[90:91]
	v_lshl_add_u64 v[110:111], v[110:111], 0, v[90:91]
	s_waitcnt vmcnt(0)
	v_pk_mul_f32 v[112:113], v[6:7], v[106:107] op_sel_hi:[1,0]
	v_pk_mul_f32 v[114:115], v[8:9], v[106:107] op_sel_hi:[1,0]
	v_pk_mul_f32 v[116:117], v[2:3], v[106:107] op_sel_hi:[1,0]
	v_pk_mul_f32 v[118:119], v[4:5], v[106:107] op_sel_hi:[1,0]
	v_pk_fma_f32 v[84:85], v[114:115], v[84:85], v[28:29]
	v_pk_fma_f32 v[82:83], v[112:113], v[82:83], v[26:27]
	v_pk_mul_f32 v[120:121], v[30:31], v[106:107] op_sel_hi:[1,0]
	v_pk_mul_f32 v[122:123], v[32:33], v[106:107] op_sel_hi:[1,0]
	v_pk_mul_f32 v[124:125], v[14:15], v[106:107] op_sel_hi:[1,0]
	v_pk_mul_f32 v[106:107], v[16:17], v[106:107] op_sel_hi:[1,0]
	v_pk_fma_f32 v[88:89], v[118:119], v[88:89], v[24:25]
	v_pk_fma_f32 v[86:87], v[116:117], v[86:87], v[22:23]
	v_max_f32_e32 v83, 0, v83
	v_max_f32_e32 v82, 0, v82
	v_max_f32_e32 v85, 0, v85
	v_max_f32_e32 v84, 0, v84
	v_pk_fma_f32 v[94:95], v[122:123], v[94:95], v[20:21]
	v_pk_fma_f32 v[92:93], v[120:121], v[92:93], v[18:19]
	v_pk_fma_f32 v[98:99], v[106:107], v[98:99], v[12:13]
	v_pk_fma_f32 v[96:97], v[124:125], v[96:97], v[10:11]
	v_max_f32_e32 v87, 0, v87
	v_max_f32_e32 v86, 0, v86
	v_max_f32_e32 v89, 0, v89
	v_max_f32_e32 v88, 0, v88
	v_pk_mul_f32 v[84:85], v[84:85], v[84:85]
	v_pk_mul_f32 v[82:83], v[82:83], v[82:83]
	v_max_f32_e32 v93, 0, v93
	v_max_f32_e32 v92, 0, v92
	v_max_f32_e32 v95, 0, v95
	v_max_f32_e32 v94, 0, v94
	v_max_f32_e32 v97, 0, v97
	v_max_f32_e32 v96, 0, v96
	v_max_f32_e32 v99, 0, v99
	v_max_f32_e32 v98, 0, v98
	v_pk_mul_f32 v[88:89], v[88:89], v[88:89]
	v_pk_mul_f32 v[86:87], v[86:87], v[86:87]
	v_cvt_pk_bf16_f32 v82, v82, v83
	v_cvt_pk_bf16_f32 v83, v84, v85
	v_pk_mul_f32 v[94:95], v[94:95], v[94:95]
	v_cvt_pk_bf16_f32 v84, v86, v87
	v_cvt_pk_bf16_f32 v85, v88, v89
	v_pk_mul_f32 v[92:93], v[92:93], v[92:93]
	v_pk_mul_f32 v[98:99], v[98:99], v[98:99]
	v_pk_mul_f32 v[96:97], v[96:97], v[96:97]
	global_store_dwordx4 v[108:109], v[82:85], off sc1
	s_nop 1
	v_cvt_pk_bf16_f32 v82, v92, v93
	v_cvt_pk_bf16_f32 v83, v94, v95
	v_cvt_pk_bf16_f32 v84, v96, v97
	v_cvt_pk_bf16_f32 v85, v98, v99
	global_store_dwordx4 v[110:111], v[82:85], off sc1
	global_load_dword v82, v[100:101], off offset:576
	s_nop 0
	v_add_u32_e32 v83, 0x4800, v169
	v_and_b32_e32 v138, 0x6f80, v83
	v_lshl_add_u64 v[84:85], v[102:103], 0, v[138:139]
	v_lshl_add_u64 v[86:87], v[104:105], 0, v[138:139]
	v_lshl_add_u64 v[84:85], v[84:85], 0, v[90:91]
	v_lshl_add_u64 v[86:87], v[86:87], 0, v[90:91]
	s_waitcnt vmcnt(0)
	v_pk_mul_f32 v[88:89], v[6:7], v[82:83] op_sel_hi:[1,0]
	v_pk_mul_f32 v[92:93], v[8:9], v[82:83] op_sel_hi:[1,0]
	v_pk_mul_f32 v[94:95], v[2:3], v[82:83] op_sel_hi:[1,0]
	v_pk_mul_f32 v[96:97], v[4:5], v[82:83] op_sel_hi:[1,0]
	v_pk_fma_f32 v[68:69], v[92:93], v[68:69], v[28:29]
	v_pk_fma_f32 v[66:67], v[88:89], v[66:67], v[26:27]
	v_pk_mul_f32 v[98:99], v[30:31], v[82:83] op_sel_hi:[1,0]
	v_pk_mul_f32 v[106:107], v[32:33], v[82:83] op_sel_hi:[1,0]
	v_pk_mul_f32 v[108:109], v[14:15], v[82:83] op_sel_hi:[1,0]
	v_pk_mul_f32 v[82:83], v[16:17], v[82:83] op_sel_hi:[1,0]
	v_pk_fma_f32 v[72:73], v[96:97], v[72:73], v[24:25]
	v_pk_fma_f32 v[70:71], v[94:95], v[70:71], v[22:23]
	v_max_f32_e32 v67, 0, v67
	v_max_f32_e32 v66, 0, v66
	v_max_f32_e32 v69, 0, v69
	v_max_f32_e32 v68, 0, v68
	v_pk_fma_f32 v[76:77], v[106:107], v[76:77], v[20:21]
	v_pk_fma_f32 v[74:75], v[98:99], v[74:75], v[18:19]
	v_pk_fma_f32 v[80:81], v[82:83], v[80:81], v[12:13]
	v_pk_fma_f32 v[78:79], v[108:109], v[78:79], v[10:11]
	v_max_f32_e32 v71, 0, v71
	v_max_f32_e32 v70, 0, v70
	v_max_f32_e32 v73, 0, v73
	v_max_f32_e32 v72, 0, v72
	v_pk_mul_f32 v[68:69], v[68:69], v[68:69]
	v_pk_mul_f32 v[66:67], v[66:67], v[66:67]
	v_max_f32_e32 v75, 0, v75
	v_max_f32_e32 v74, 0, v74
	v_max_f32_e32 v77, 0, v77
	v_max_f32_e32 v76, 0, v76
	v_max_f32_e32 v79, 0, v79
	v_max_f32_e32 v78, 0, v78
	v_max_f32_e32 v81, 0, v81
	v_max_f32_e32 v80, 0, v80
	v_pk_mul_f32 v[72:73], v[72:73], v[72:73]
	v_pk_mul_f32 v[70:71], v[70:71], v[70:71]
	v_cvt_pk_bf16_f32 v66, v66, v67
	v_cvt_pk_bf16_f32 v67, v68, v69
	v_pk_mul_f32 v[76:77], v[76:77], v[76:77]
	v_cvt_pk_bf16_f32 v68, v70, v71
	v_cvt_pk_bf16_f32 v69, v72, v73
	v_pk_mul_f32 v[74:75], v[74:75], v[74:75]
	v_pk_mul_f32 v[80:81], v[80:81], v[80:81]
	v_pk_mul_f32 v[78:79], v[78:79], v[78:79]
	global_store_dwordx4 v[84:85], v[66:69], off sc1
	s_nop 1
	v_cvt_pk_bf16_f32 v66, v74, v75
	v_cvt_pk_bf16_f32 v67, v76, v77
	v_cvt_pk_bf16_f32 v68, v78, v79
	v_cvt_pk_bf16_f32 v69, v80, v81
	global_store_dwordx4 v[86:87], v[66:69], off sc1
	global_load_dword v66, v[100:101], off offset:640
	s_nop 0
	v_add_u32_e32 v67, 0x5000, v169
	v_and_b32_e32 v138, 0x7780, v67
	v_lshl_add_u64 v[68:69], v[102:103], 0, v[138:139]
	v_lshl_add_u64 v[70:71], v[104:105], 0, v[138:139]
	v_lshl_add_u64 v[68:69], v[68:69], 0, v[90:91]
	v_lshl_add_u64 v[70:71], v[70:71], 0, v[90:91]
	s_waitcnt vmcnt(0)
	v_pk_mul_f32 v[72:73], v[6:7], v[66:67] op_sel_hi:[1,0]
	v_pk_mul_f32 v[74:75], v[8:9], v[66:67] op_sel_hi:[1,0]
	v_pk_mul_f32 v[76:77], v[2:3], v[66:67] op_sel_hi:[1,0]
	v_pk_mul_f32 v[78:79], v[4:5], v[66:67] op_sel_hi:[1,0]
	v_pk_fma_f32 v[52:53], v[74:75], v[52:53], v[28:29]
	v_pk_fma_f32 v[50:51], v[72:73], v[50:51], v[26:27]
	v_pk_mul_f32 v[80:81], v[30:31], v[66:67] op_sel_hi:[1,0]
	v_pk_mul_f32 v[82:83], v[32:33], v[66:67] op_sel_hi:[1,0]
	v_pk_mul_f32 v[84:85], v[14:15], v[66:67] op_sel_hi:[1,0]
	v_pk_mul_f32 v[66:67], v[16:17], v[66:67] op_sel_hi:[1,0]
	v_pk_fma_f32 v[56:57], v[78:79], v[56:57], v[24:25]
	v_pk_fma_f32 v[54:55], v[76:77], v[54:55], v[22:23]
	v_max_f32_e32 v51, 0, v51
	v_max_f32_e32 v50, 0, v50
	v_max_f32_e32 v53, 0, v53
	v_max_f32_e32 v52, 0, v52
	v_pk_fma_f32 v[60:61], v[82:83], v[60:61], v[20:21]
	v_pk_fma_f32 v[58:59], v[80:81], v[58:59], v[18:19]
	v_pk_fma_f32 v[64:65], v[66:67], v[64:65], v[12:13]
	v_pk_fma_f32 v[62:63], v[84:85], v[62:63], v[10:11]
	v_max_f32_e32 v55, 0, v55
	v_max_f32_e32 v54, 0, v54
	v_max_f32_e32 v57, 0, v57
	v_max_f32_e32 v56, 0, v56
	v_pk_mul_f32 v[52:53], v[52:53], v[52:53]
	v_pk_mul_f32 v[50:51], v[50:51], v[50:51]
	v_max_f32_e32 v59, 0, v59
	v_max_f32_e32 v58, 0, v58
	v_max_f32_e32 v61, 0, v61
	v_max_f32_e32 v60, 0, v60
	v_max_f32_e32 v63, 0, v63
	v_max_f32_e32 v62, 0, v62
	v_max_f32_e32 v65, 0, v65
	v_max_f32_e32 v64, 0, v64
	v_pk_mul_f32 v[56:57], v[56:57], v[56:57]
	v_pk_mul_f32 v[54:55], v[54:55], v[54:55]
	v_cvt_pk_bf16_f32 v50, v50, v51
	v_cvt_pk_bf16_f32 v51, v52, v53
	v_pk_mul_f32 v[60:61], v[60:61], v[60:61]
	v_cvt_pk_bf16_f32 v52, v54, v55
	v_cvt_pk_bf16_f32 v53, v56, v57
	v_pk_mul_f32 v[58:59], v[58:59], v[58:59]
	v_pk_mul_f32 v[64:65], v[64:65], v[64:65]
	v_pk_mul_f32 v[62:63], v[62:63], v[62:63]
	global_store_dwordx4 v[68:69], v[50:53], off sc1
	s_nop 1
	v_cvt_pk_bf16_f32 v50, v58, v59
	v_cvt_pk_bf16_f32 v51, v60, v61
	v_cvt_pk_bf16_f32 v52, v62, v63
	v_cvt_pk_bf16_f32 v53, v64, v65
	global_store_dwordx4 v[70:71], v[50:53], off sc1
	global_load_dword v50, v[100:101], off offset:704
	s_nop 0
	v_add_u32_e32 v51, 0x5800, v169
	v_and_b32_e32 v138, 0x7f80, v51
	v_lshl_add_u64 v[52:53], v[102:103], 0, v[138:139]
	v_lshl_add_u64 v[54:55], v[104:105], 0, v[138:139]
	v_lshl_add_u64 v[52:53], v[52:53], 0, v[90:91]
	v_lshl_add_u64 v[54:55], v[54:55], 0, v[90:91]
	s_waitcnt vmcnt(0)
	v_pk_mul_f32 v[2:3], v[2:3], v[50:51] op_sel_hi:[1,0]
	v_pk_mul_f32 v[4:5], v[4:5], v[50:51] op_sel_hi:[1,0]
	v_pk_mul_f32 v[6:7], v[6:7], v[50:51] op_sel_hi:[1,0]
	v_pk_mul_f32 v[8:9], v[8:9], v[50:51] op_sel_hi:[1,0]
	v_pk_mul_f32 v[30:31], v[30:31], v[50:51] op_sel_hi:[1,0]
	v_pk_fma_f32 v[4:5], v[4:5], v[40:41], v[24:25]
	v_pk_fma_f32 v[2:3], v[2:3], v[38:39], v[22:23]
	v_pk_mul_f32 v[32:33], v[32:33], v[50:51] op_sel_hi:[1,0]
	v_pk_mul_f32 v[14:15], v[14:15], v[50:51] op_sel_hi:[1,0]
	v_pk_mul_f32 v[16:17], v[16:17], v[50:51] op_sel_hi:[1,0]
	v_pk_fma_f32 v[8:9], v[8:9], v[36:37], v[28:29]
	v_pk_fma_f32 v[6:7], v[6:7], v[34:35], v[26:27]
	v_pk_fma_f32 v[18:19], v[30:31], v[42:43], v[18:19]
	v_max_f32_e32 v3, 0, v3
	v_max_f32_e32 v2, 0, v2
	v_max_f32_e32 v5, 0, v5
	v_max_f32_e32 v4, 0, v4
	v_pk_fma_f32 v[20:21], v[32:33], v[44:45], v[20:21]
	v_pk_fma_f32 v[12:13], v[16:17], v[48:49], v[12:13]
	v_pk_fma_f32 v[10:11], v[14:15], v[46:47], v[10:11]
	v_max_f32_e32 v7, 0, v7
	v_max_f32_e32 v6, 0, v6
	v_max_f32_e32 v9, 0, v9
	v_max_f32_e32 v8, 0, v8
	v_max_f32_e32 v15, 0, v19
	v_max_f32_e32 v14, 0, v18
	v_pk_mul_f32 v[18:19], v[4:5], v[4:5]
	v_pk_mul_f32 v[4:5], v[2:3], v[2:3]
	v_max_f32_e32 v17, 0, v21
	v_max_f32_e32 v16, 0, v20
	v_max_f32_e32 v11, 0, v11
	v_max_f32_e32 v10, 0, v10
	v_max_f32_e32 v13, 0, v13
	v_max_f32_e32 v12, 0, v12
	v_pk_mul_f32 v[8:9], v[8:9], v[8:9]
	v_pk_mul_f32 v[6:7], v[6:7], v[6:7]
	v_pk_mul_f32 v[16:17], v[16:17], v[16:17]
	v_cvt_pk_bf16_f32 v2, v6, v7
	v_cvt_pk_bf16_f32 v3, v8, v9
	v_cvt_pk_bf16_f32 v4, v4, v5
	v_cvt_pk_bf16_f32 v5, v18, v19
	v_pk_mul_f32 v[14:15], v[14:15], v[14:15]
	v_pk_mul_f32 v[12:13], v[12:13], v[12:13]
	v_pk_mul_f32 v[10:11], v[10:11], v[10:11]
	global_store_dwordx4 v[52:53], v[2:5], off sc1
	s_nop 1
	v_cvt_pk_bf16_f32 v2, v14, v15
	v_cvt_pk_bf16_f32 v3, v16, v17
	v_cvt_pk_bf16_f32 v4, v10, v11
	v_cvt_pk_bf16_f32 v5, v12, v13
	global_store_dwordx4 v[54:55], v[2:5], off sc1
	s_cbranch_vccnz .LBB0_2936
	s_andn2_b64 vcc, exec, s[10:11]
	s_cbranch_vccnz .LBB0_2935
	s_barrier
	s_branch .LBB0_2935

.LBB0_3035:
	s_lshr_b32 s34, s69, 4
	s_add_i32 s34, s34, -1
	s_cmp_gt_i32 s69, 31
	s_cselect_b32 s34, s34, 0
	v_lshl_or_b32 v178, s12, 8, v208
	s_mul_i32 s37, s34, 0xc000
	s_mul_hi_i32 s36, s34, 0xc000
	s_add_u32 s34, s51, s37
	v_ashrrev_i32_e32 v179, 31, v178
	s_addc_u32 s35, s54, s36
	v_lshlrev_b64 v[114:115], 2, v[178:179]
	v_lshl_add_u64 v[122:123], s[34:35], 0, v[114:115]
	s_add_u32 s34, s55, s37
	v_lshl_add_u32 v196, s69, 8, v206
	v_lshl_add_u64 v[116:117], s[20:21], 0, v[114:115]
	s_addc_u32 s35, s56, s36
	v_ashrrev_i32_e32 v197, 31, v196
	v_lshl_add_u64 v[124:125], s[34:35], 0, v[114:115]
	global_load_dwordx4 v[118:121], v[122:123], off offset:16
	global_load_dwordx4 v[126:129], v[122:123], off
	global_load_dwordx4 v[180:183], v[116:117], off offset:16
	global_load_dwordx4 v[184:187], v[116:117], off
	global_load_dwordx4 v[188:191], v[124:125], off offset:16
	global_load_dwordx4 v[192:195], v[124:125], off
	global_load_dwordx4 v[214:217], v[116:117], off offset:528
	global_load_dwordx4 v[218:221], v[116:117], off offset:512
	global_load_dwordx4 v[222:225], v[124:125], off offset:528
	global_load_dwordx4 v[226:229], v[124:125], off offset:512
	v_lshlrev_b64 v[116:117], 13, v[196:197]
	v_or_b32_e32 v198, 16, v196
	v_lshl_add_u64 v[116:117], s[16:17], 0, v[116:117]
	v_ashrrev_i32_e32 v199, 31, v198
	v_lshl_add_u64 v[200:201], v[116:117], 0, v[114:115]
	v_lshlrev_b64 v[116:117], 13, v[198:199]
	v_lshl_add_u64 v[116:117], s[16:17], 0, v[116:117]
	v_lshl_add_u64 v[202:203], v[116:117], 0, v[114:115]
	global_load_dwordx4 v[230:233], v[200:201], off offset:16 nt
	global_load_dwordx4 v[234:237], v[200:201], off nt
	global_load_dwordx4 v[238:241], v[200:201], off offset:528 nt
	global_load_dwordx4 v[242:245], v[200:201], off offset:512 nt
	global_load_dwordx4 v[154:157], v[202:203], off offset:16 nt
	global_load_dwordx4 v[158:161], v[202:203], off nt
	global_load_dwordx4 v[146:149], v[202:203], off offset:528 nt
	global_load_dwordx4 v[150:153], v[202:203], off offset:512 nt
	global_load_dwordx4 v[114:117], v[122:123], off offset:528
	s_nop 0
	global_load_dwordx4 v[122:125], v[122:123], off offset:512
	s_lshl_b32 s34, s12, 2
	s_ashr_i32 s35, s34, 31
	s_waitcnt vmcnt(0)
	v_pk_add_f32 v[190:191], v[190:191], 1.0 op_sel_hi:[1,0]
	v_pk_add_f32 v[194:195], v[194:195], 1.0 op_sel_hi:[1,0]
	v_pk_add_f32 v[204:205], v[192:193], 1.0 op_sel_hi:[1,0]
	v_pk_add_f32 v[246:247], v[188:189], 1.0 op_sel_hi:[1,0]
	v_pk_add_f32 v[224:225], v[224:225], 1.0 op_sel_hi:[1,0]
	v_pk_add_f32 v[228:229], v[228:229], 1.0 op_sel_hi:[1,0]
	v_pk_add_f32 v[226:227], v[226:227], 1.0 op_sel_hi:[1,0]
	v_pk_add_f32 v[222:223], v[222:223], 1.0 op_sel_hi:[1,0]
	v_pk_mul_f32 v[192:193], v[186:187], v[194:195]
	v_pk_mul_f32 v[194:195], v[184:185], v[204:205]
	v_pk_mul_f32 v[188:189], v[182:183], v[190:191]
	v_pk_mul_f32 v[190:191], v[180:181], v[246:247]
	v_pk_mul_f32 v[186:187], v[220:221], v[228:229]
	v_pk_mul_f32 v[184:185], v[218:219], v[226:227]
	v_pk_mul_f32 v[180:181], v[216:217], v[224:225]
	v_pk_mul_f32 v[182:183], v[214:215], v[222:223]
	v_pk_fma_f32 v[144:145], v[144:145], v[128:129], v[236:237]
	v_pk_fma_f32 v[142:143], v[142:143], v[126:127], v[234:235]
	v_mul_f32_e32 v205, v145, v145
	v_mul_f32_e32 v204, v143, v143
	v_pk_fma_f32 v[138:139], v[138:139], v[118:119], v[230:231]
	v_fmac_f32_e32 v204, v142, v142
	v_fmac_f32_e32 v205, v144, v144
	v_add_f32_e32 v204, v204, v205
	v_mul_f32_e32 v205, v139, v139
	v_pk_fma_f32 v[140:141], v[140:141], v[120:121], v[232:233]
	v_fmac_f32_e32 v205, v138, v138
	v_add_f32_e32 v204, v204, v205
	v_mul_f32_e32 v205, v141, v141
	global_store_dwordx4 v[200:201], v[142:145], off nt
	global_store_dwordx4 v[200:201], v[138:141], off offset:16 nt
	v_fmac_f32_e32 v205, v140, v140
	v_pk_mul_f32 v[142:143], v[194:195], v[142:143]
	v_add_f32_e32 v213, v205, v204
	v_pk_mul_f32 v[204:205], v[188:189], v[140:141]
	v_pk_mul_f32 v[140:141], v[190:191], v[138:139]
	v_cvt_pk_bf16_f32 v138, v142, v143
	v_lshlrev_b64 v[142:143], 12, v[196:197]
	v_lshl_add_u64 v[142:143], s[18:19], 0, v[142:143]
	v_pk_mul_f32 v[144:145], v[192:193], v[144:145]
	v_lshl_add_u64 v[142:143], v[178:179], 1, v[142:143]
	v_cvt_pk_bf16_f32 v139, v144, v145
	v_pk_fma_f32 v[136:137], v[136:137], v[124:125], v[244:245]
	v_pk_fma_f32 v[134:135], v[134:135], v[122:123], v[242:243]
	v_cvt_pk_bf16_f32 v140, v140, v141
	v_cvt_pk_bf16_f32 v141, v204, v205
	global_store_dwordx4 v[142:143], v[138:141], off sc1
	v_pk_fma_f32 v[130:131], v[130:131], v[114:115], v[238:239]
	v_pk_fma_f32 v[132:133], v[132:133], v[116:117], v[240:241]
	v_mul_f32_e32 v138, v135, v135
	v_mul_f32_e32 v139, v137, v137
	v_fmac_f32_e32 v138, v134, v134
	v_fmac_f32_e32 v139, v136, v136
	v_add_f32_e32 v138, v138, v139
	v_mul_f32_e32 v139, v131, v131
	v_fmac_f32_e32 v139, v130, v130
	v_add_f32_e32 v138, v138, v139
	v_mul_f32_e32 v139, v133, v133
	v_fmac_f32_e32 v139, v132, v132
	v_add_f32_e32 v138, v139, v138
	v_and_b32_e32 v139, 64, v212
	v_add_f32_e32 v144, v213, v138
	v_xor_b32_e32 v138, 16, v212
	v_add_u32_e32 v145, 64, v139
	v_cmp_lt_i32_e32 vcc, v138, v145
	global_store_dwordx4 v[200:201], v[134:137], off offset:512 nt
	global_store_dwordx4 v[200:201], v[130:133], off offset:528 nt
	v_cndmask_b32_e32 v138, v212, v138, vcc
	v_lshlrev_b32_e32 v213, 2, v138
	ds_bpermute_b32 v200, v213, v144
	v_pk_mul_f32 v[140:141], v[182:183], v[130:131]
	v_xor_b32_e32 v131, 32, v212
	v_cmp_lt_i32_e32 vcc, v131, v145
	v_pk_mul_f32 v[134:135], v[184:185], v[134:135]
	s_waitcnt lgkmcnt(0)
	v_add_f32_e32 v130, v144, v200
	v_cndmask_b32_e32 v131, v212, v131, vcc
	v_lshlrev_b32_e32 v214, 2, v131
	ds_bpermute_b32 v131, v214, v130
	v_pk_mul_f32 v[136:137], v[186:187], v[136:137]
	v_pk_mul_f32 v[138:139], v[180:181], v[132:133]
	v_cvt_pk_bf16_f32 v132, v134, v135
	v_cvt_pk_bf16_f32 v133, v136, v137
	v_cvt_pk_bf16_f32 v134, v140, v141
	s_nop 0
	v_cvt_pk_bf16_f32 v135, v138, v139
	global_store_dwordx4 v[142:143], v[132:135], off offset:256 sc1
	s_and_saveexec_b64 s[36:37], s[0:1]
	s_cbranch_execz .LBB0_3037
	s_waitcnt lgkmcnt(0)
	v_add_f32_e32 v132, v130, v131
	v_lshlrev_b64 v[130:131], 7, v[196:197]
	v_lshl_add_u64 v[130:131], s[22:23], 0, v[130:131]
	v_lshl_add_u64 v[130:131], s[34:35], 2, v[130:131]
	s_lshl_b32 s12, s57, 2
	v_lshl_add_u64 v[130:131], v[130:131], 0, s[12:13]
	global_store_dword v[130:131], v132, off
.LBB0_3037:
	s_or_b64 exec, exec, s[36:37]
	v_or_b32_e32 v200, 32, v196
	v_ashrrev_i32_e32 v201, 31, v200
	s_waitcnt lgkmcnt(0)
	v_lshlrev_b64 v[130:131], 13, v[200:201]
	v_lshl_add_u64 v[130:131], s[16:17], 0, v[130:131]
	v_lshl_add_u64 v[204:205], v[178:179], 2, v[130:131]
	global_load_dwordx4 v[138:141], v[204:205], off offset:16 nt
	global_load_dwordx4 v[142:145], v[204:205], off nt
	global_load_dwordx4 v[130:133], v[204:205], off offset:528 nt
	global_load_dwordx4 v[134:137], v[204:205], off offset:512 nt
	v_pk_fma_f32 v[112:113], v[112:113], v[128:129], v[160:161]
	v_pk_fma_f32 v[110:111], v[110:111], v[126:127], v[158:159]
	v_pk_fma_f32 v[106:107], v[106:107], v[118:119], v[154:155]
	v_mul_f32_e32 v154, v111, v111
	v_mul_f32_e32 v155, v113, v113
	v_fmac_f32_e32 v154, v110, v110
	v_fmac_f32_e32 v155, v112, v112
	v_add_f32_e32 v154, v154, v155
	v_mul_f32_e32 v155, v107, v107
	v_pk_fma_f32 v[108:109], v[108:109], v[120:121], v[156:157]
	v_fmac_f32_e32 v155, v106, v106
	v_add_f32_e32 v154, v154, v155
	v_mul_f32_e32 v155, v109, v109
	global_store_dwordx4 v[202:203], v[110:113], off nt
	global_store_dwordx4 v[202:203], v[106:109], off offset:16 nt
	v_fmac_f32_e32 v155, v108, v108
	v_pk_mul_f32 v[110:111], v[194:195], v[110:111]
	v_add_f32_e32 v156, v155, v154
	v_pk_mul_f32 v[154:155], v[188:189], v[108:109]
	v_pk_mul_f32 v[108:109], v[190:191], v[106:107]
	v_cvt_pk_bf16_f32 v106, v110, v111
	v_lshlrev_b64 v[110:111], 12, v[198:199]
	v_lshl_add_u64 v[110:111], s[18:19], 0, v[110:111]
	v_pk_mul_f32 v[112:113], v[192:193], v[112:113]
	v_lshl_add_u64 v[110:111], v[178:179], 1, v[110:111]
	v_cvt_pk_bf16_f32 v107, v112, v113
	v_pk_fma_f32 v[104:105], v[104:105], v[124:125], v[152:153]
	v_pk_fma_f32 v[102:103], v[102:103], v[122:123], v[150:151]
	v_cvt_pk_bf16_f32 v108, v108, v109
	v_cvt_pk_bf16_f32 v109, v154, v155
	global_store_dwordx4 v[110:111], v[106:109], off sc1
	v_pk_fma_f32 v[98:99], v[98:99], v[114:115], v[146:147]
	v_pk_fma_f32 v[100:101], v[100:101], v[116:117], v[148:149]
	v_mul_f32_e32 v106, v103, v103
	v_mul_f32_e32 v107, v105, v105
	v_fmac_f32_e32 v106, v102, v102
	v_fmac_f32_e32 v107, v104, v104
	v_add_f32_e32 v106, v106, v107
	v_mul_f32_e32 v107, v99, v99
	v_fmac_f32_e32 v107, v98, v98
	v_add_f32_e32 v106, v106, v107
	v_mul_f32_e32 v107, v101, v101
	v_fmac_f32_e32 v107, v100, v100
	v_add_f32_e32 v106, v107, v106
	v_add_f32_e32 v112, v156, v106
	ds_bpermute_b32 v113, v213, v112
	global_store_dwordx4 v[202:203], v[102:105], off offset:512 nt
	global_store_dwordx4 v[202:203], v[98:101], off offset:528 nt
	v_pk_mul_f32 v[108:109], v[182:183], v[98:99]
	v_pk_mul_f32 v[102:103], v[184:185], v[102:103]
	v_pk_mul_f32 v[104:105], v[186:187], v[104:105]
	s_waitcnt lgkmcnt(0)
	v_add_f32_e32 v98, v112, v113
	ds_bpermute_b32 v99, v214, v98
	v_pk_mul_f32 v[106:107], v[180:181], v[100:101]
	v_cvt_pk_bf16_f32 v100, v102, v103
	v_cvt_pk_bf16_f32 v101, v104, v105
	v_cvt_pk_bf16_f32 v102, v108, v109
	s_nop 0
	v_cvt_pk_bf16_f32 v103, v106, v107
	global_store_dwordx4 v[110:111], v[100:103], off offset:256 sc1
	s_and_saveexec_b64 s[36:37], s[0:1]
	s_cbranch_execz .LBB0_3039
	s_waitcnt lgkmcnt(0)
	v_add_f32_e32 v100, v98, v99
	v_lshlrev_b64 v[98:99], 7, v[198:199]
	v_lshl_add_u64 v[98:99], s[22:23], 0, v[98:99]
	v_lshl_add_u64 v[98:99], s[34:35], 2, v[98:99]
	s_lshl_b32 s12, s57, 2
	v_lshl_add_u64 v[98:99], v[98:99], 0, s[12:13]
	global_store_dword v[98:99], v100, off
.LBB0_3039:
	s_or_b64 exec, exec, s[36:37]
	v_or_b32_e32 v146, 48, v196
	v_ashrrev_i32_e32 v147, 31, v146
	s_waitcnt lgkmcnt(0)
	v_lshlrev_b64 v[98:99], 13, v[146:147]
	v_lshl_add_u64 v[98:99], s[16:17], 0, v[98:99]
	v_lshl_add_u64 v[148:149], v[178:179], 2, v[98:99]
	global_load_dwordx4 v[106:109], v[148:149], off offset:16 nt
	global_load_dwordx4 v[110:113], v[148:149], off nt
	global_load_dwordx4 v[98:101], v[148:149], off offset:528 nt
	global_load_dwordx4 v[102:105], v[148:149], off offset:512 nt
	s_waitcnt vmcnt(12)
	v_pk_fma_f32 v[96:97], v[96:97], v[128:129], v[144:145]
	v_pk_fma_f32 v[94:95], v[94:95], v[126:127], v[142:143]
	v_pk_fma_f32 v[90:91], v[90:91], v[118:119], v[138:139]
	v_mul_f32_e32 v138, v95, v95
	v_mul_f32_e32 v139, v97, v97
	v_fmac_f32_e32 v138, v94, v94
	v_fmac_f32_e32 v139, v96, v96
	v_add_f32_e32 v138, v138, v139
	v_mul_f32_e32 v139, v91, v91
	v_pk_fma_f32 v[92:93], v[92:93], v[120:121], v[140:141]
	v_fmac_f32_e32 v139, v90, v90
	v_add_f32_e32 v138, v138, v139
	v_mul_f32_e32 v139, v93, v93
	global_store_dwordx4 v[204:205], v[94:97], off nt
	global_store_dwordx4 v[204:205], v[90:93], off offset:16 nt
	v_fmac_f32_e32 v139, v92, v92
	v_pk_mul_f32 v[94:95], v[194:195], v[94:95]
	v_add_f32_e32 v140, v139, v138
	v_pk_mul_f32 v[138:139], v[188:189], v[92:93]
	v_pk_mul_f32 v[92:93], v[190:191], v[90:91]
	v_cvt_pk_bf16_f32 v90, v94, v95
	v_lshlrev_b64 v[94:95], 12, v[200:201]
	v_lshl_add_u64 v[94:95], s[18:19], 0, v[94:95]
	v_pk_mul_f32 v[96:97], v[192:193], v[96:97]
	v_lshl_add_u64 v[94:95], v[178:179], 1, v[94:95]
	v_cvt_pk_bf16_f32 v91, v96, v97
	s_waitcnt vmcnt(12)
	v_pk_fma_f32 v[88:89], v[88:89], v[124:125], v[136:137]
	v_pk_fma_f32 v[86:87], v[86:87], v[122:123], v[134:135]
	v_cvt_pk_bf16_f32 v92, v92, v93
	v_cvt_pk_bf16_f32 v93, v138, v139
	global_store_dwordx4 v[94:95], v[90:93], off sc1
	v_pk_fma_f32 v[82:83], v[82:83], v[114:115], v[130:131]
	v_pk_fma_f32 v[84:85], v[84:85], v[116:117], v[132:133]
	v_mul_f32_e32 v90, v87, v87
	v_mul_f32_e32 v91, v89, v89
	v_fmac_f32_e32 v90, v86, v86
	v_fmac_f32_e32 v91, v88, v88
	v_add_f32_e32 v90, v90, v91
	v_mul_f32_e32 v91, v83, v83
	v_fmac_f32_e32 v91, v82, v82
	v_add_f32_e32 v90, v90, v91
	v_mul_f32_e32 v91, v85, v85
	v_fmac_f32_e32 v91, v84, v84
	v_add_f32_e32 v90, v91, v90
	v_add_f32_e32 v96, v140, v90
	ds_bpermute_b32 v97, v213, v96
	global_store_dwordx4 v[204:205], v[86:89], off offset:512 nt
	global_store_dwordx4 v[204:205], v[82:85], off offset:528 nt
	v_pk_mul_f32 v[92:93], v[182:183], v[82:83]
	v_pk_mul_f32 v[86:87], v[184:185], v[86:87]
	v_pk_mul_f32 v[88:89], v[186:187], v[88:89]
	s_waitcnt lgkmcnt(0)
	v_add_f32_e32 v82, v96, v97
	ds_bpermute_b32 v83, v214, v82
	v_pk_mul_f32 v[90:91], v[180:181], v[84:85]
	v_cvt_pk_bf16_f32 v84, v86, v87
	v_cvt_pk_bf16_f32 v85, v88, v89
	v_cvt_pk_bf16_f32 v86, v92, v93
	s_nop 0
	v_cvt_pk_bf16_f32 v87, v90, v91
	global_store_dwordx4 v[94:95], v[84:87], off offset:256 sc1
	s_and_saveexec_b64 s[36:37], s[0:1]
	s_cbranch_execz .LBB0_3041
	s_waitcnt lgkmcnt(0)
	v_add_f32_e32 v84, v82, v83
	v_lshlrev_b64 v[82:83], 7, v[200:201]
	v_lshl_add_u64 v[82:83], s[22:23], 0, v[82:83]
	v_lshl_add_u64 v[82:83], s[34:35], 2, v[82:83]
	s_lshl_b32 s12, s57, 2
	v_lshl_add_u64 v[82:83], v[82:83], 0, s[12:13]
	global_store_dword v[82:83], v84, off
.LBB0_3041:
	s_or_b64 exec, exec, s[36:37]
	v_add_u32_e32 v130, 0x80, v196
	v_ashrrev_i32_e32 v131, 31, v130
	s_waitcnt lgkmcnt(0)
	v_lshlrev_b64 v[82:83], 13, v[130:131]
	v_lshl_add_u64 v[82:83], s[16:17], 0, v[82:83]
	v_lshl_add_u64 v[132:133], v[178:179], 2, v[82:83]
	global_load_dwordx4 v[90:93], v[132:133], off offset:16 nt
	global_load_dwordx4 v[94:97], v[132:133], off nt
	global_load_dwordx4 v[82:85], v[132:133], off offset:528 nt
	global_load_dwordx4 v[86:89], v[132:133], off offset:512 nt
	s_waitcnt vmcnt(12)
	v_pk_fma_f32 v[80:81], v[80:81], v[128:129], v[112:113]
	v_pk_fma_f32 v[78:79], v[78:79], v[126:127], v[110:111]
	v_pk_fma_f32 v[74:75], v[74:75], v[118:119], v[106:107]
	v_mul_f32_e32 v106, v79, v79
	v_mul_f32_e32 v107, v81, v81
	v_fmac_f32_e32 v106, v78, v78
	v_fmac_f32_e32 v107, v80, v80
	v_add_f32_e32 v106, v106, v107
	v_mul_f32_e32 v107, v75, v75
	v_pk_fma_f32 v[76:77], v[76:77], v[120:121], v[108:109]
	v_fmac_f32_e32 v107, v74, v74
	v_add_f32_e32 v106, v106, v107
	v_mul_f32_e32 v107, v77, v77
	global_store_dwordx4 v[148:149], v[78:81], off nt
	global_store_dwordx4 v[148:149], v[74:77], off offset:16 nt
	v_fmac_f32_e32 v107, v76, v76
	v_pk_mul_f32 v[78:79], v[194:195], v[78:79]
	v_add_f32_e32 v108, v107, v106
	v_pk_mul_f32 v[106:107], v[188:189], v[76:77]
	v_pk_mul_f32 v[76:77], v[190:191], v[74:75]
	v_cvt_pk_bf16_f32 v74, v78, v79
	v_lshlrev_b64 v[78:79], 12, v[146:147]
	v_lshl_add_u64 v[78:79], s[18:19], 0, v[78:79]
	v_pk_mul_f32 v[80:81], v[192:193], v[80:81]
	v_lshl_add_u64 v[78:79], v[178:179], 1, v[78:79]
	v_cvt_pk_bf16_f32 v75, v80, v81
	s_waitcnt vmcnt(12)
	v_pk_fma_f32 v[72:73], v[72:73], v[124:125], v[104:105]
	v_pk_fma_f32 v[70:71], v[70:71], v[122:123], v[102:103]
	v_cvt_pk_bf16_f32 v76, v76, v77
	v_cvt_pk_bf16_f32 v77, v106, v107
	global_store_dwordx4 v[78:79], v[74:77], off sc1
	v_pk_fma_f32 v[66:67], v[66:67], v[114:115], v[98:99]
	v_pk_fma_f32 v[68:69], v[68:69], v[116:117], v[100:101]
	v_mul_f32_e32 v74, v71, v71
	v_mul_f32_e32 v75, v73, v73
	v_fmac_f32_e32 v74, v70, v70
	v_fmac_f32_e32 v75, v72, v72
	v_add_f32_e32 v74, v74, v75
	v_mul_f32_e32 v75, v67, v67
	v_fmac_f32_e32 v75, v66, v66
	v_add_f32_e32 v74, v74, v75
	v_mul_f32_e32 v75, v69, v69
	v_fmac_f32_e32 v75, v68, v68
	v_add_f32_e32 v74, v75, v74
	v_add_f32_e32 v80, v108, v74
	ds_bpermute_b32 v81, v213, v80
	global_store_dwordx4 v[148:149], v[70:73], off offset:512 nt
	global_store_dwordx4 v[148:149], v[66:69], off offset:528 nt
	v_pk_mul_f32 v[76:77], v[182:183], v[66:67]
	v_pk_mul_f32 v[70:71], v[184:185], v[70:71]
	v_pk_mul_f32 v[72:73], v[186:187], v[72:73]
	s_waitcnt lgkmcnt(0)
	v_add_f32_e32 v66, v80, v81
	ds_bpermute_b32 v67, v214, v66
	v_pk_mul_f32 v[74:75], v[180:181], v[68:69]
	v_cvt_pk_bf16_f32 v68, v70, v71
	v_cvt_pk_bf16_f32 v69, v72, v73
	v_cvt_pk_bf16_f32 v70, v76, v77
	s_nop 0
	v_cvt_pk_bf16_f32 v71, v74, v75
	global_store_dwordx4 v[78:79], v[68:71], off offset:256 sc1
	s_and_saveexec_b64 s[36:37], s[0:1]
	s_cbranch_execz .LBB0_3043
	s_waitcnt lgkmcnt(0)
	v_add_f32_e32 v68, v66, v67
	v_lshlrev_b64 v[66:67], 7, v[146:147]
	v_lshl_add_u64 v[66:67], s[22:23], 0, v[66:67]
	v_lshl_add_u64 v[66:67], s[34:35], 2, v[66:67]
	s_lshl_b32 s12, s57, 2
	v_lshl_add_u64 v[66:67], v[66:67], 0, s[12:13]
	global_store_dword v[66:67], v68, off
.LBB0_3043:
	s_or_b64 exec, exec, s[36:37]
	v_or_b32_e32 v98, 16, v130
	v_ashrrev_i32_e32 v99, 31, v98
	s_waitcnt lgkmcnt(0)
	v_lshlrev_b64 v[66:67], 13, v[98:99]
	v_lshl_add_u64 v[66:67], s[16:17], 0, v[66:67]
	v_lshl_add_u64 v[100:101], v[178:179], 2, v[66:67]
	global_load_dwordx4 v[74:77], v[100:101], off offset:16 nt
	global_load_dwordx4 v[78:81], v[100:101], off nt
	global_load_dwordx4 v[66:69], v[100:101], off offset:528 nt
	global_load_dwordx4 v[70:73], v[100:101], off offset:512 nt
	s_waitcnt vmcnt(12)
	v_pk_fma_f32 v[64:65], v[64:65], v[128:129], v[96:97]
	v_pk_fma_f32 v[62:63], v[62:63], v[126:127], v[94:95]
	v_pk_fma_f32 v[58:59], v[58:59], v[118:119], v[90:91]
	v_mul_f32_e32 v90, v63, v63
	v_mul_f32_e32 v91, v65, v65
	v_fmac_f32_e32 v90, v62, v62
	v_fmac_f32_e32 v91, v64, v64
	v_add_f32_e32 v90, v90, v91
	v_mul_f32_e32 v91, v59, v59
	v_pk_fma_f32 v[60:61], v[60:61], v[120:121], v[92:93]
	v_fmac_f32_e32 v91, v58, v58
	v_add_f32_e32 v90, v90, v91
	v_mul_f32_e32 v91, v61, v61
	global_store_dwordx4 v[132:133], v[62:65], off nt
	global_store_dwordx4 v[132:133], v[58:61], off offset:16 nt
	v_fmac_f32_e32 v91, v60, v60
	v_pk_mul_f32 v[62:63], v[194:195], v[62:63]
	v_add_f32_e32 v92, v91, v90
	v_pk_mul_f32 v[90:91], v[188:189], v[60:61]
	v_pk_mul_f32 v[60:61], v[190:191], v[58:59]
	v_cvt_pk_bf16_f32 v58, v62, v63
	v_lshlrev_b64 v[62:63], 12, v[130:131]
	v_lshl_add_u64 v[62:63], s[18:19], 0, v[62:63]
	v_pk_mul_f32 v[64:65], v[192:193], v[64:65]
	v_lshl_add_u64 v[62:63], v[178:179], 1, v[62:63]
	v_cvt_pk_bf16_f32 v59, v64, v65
	s_waitcnt vmcnt(12)
	v_pk_fma_f32 v[56:57], v[56:57], v[124:125], v[88:89]
	v_pk_fma_f32 v[54:55], v[54:55], v[122:123], v[86:87]
	v_cvt_pk_bf16_f32 v60, v60, v61
	v_cvt_pk_bf16_f32 v61, v90, v91
	global_store_dwordx4 v[62:63], v[58:61], off sc1
	v_pk_fma_f32 v[50:51], v[50:51], v[114:115], v[82:83]
	v_pk_fma_f32 v[52:53], v[52:53], v[116:117], v[84:85]
	v_mul_f32_e32 v58, v55, v55
	v_mul_f32_e32 v59, v57, v57
	v_fmac_f32_e32 v58, v54, v54
	v_fmac_f32_e32 v59, v56, v56
	v_add_f32_e32 v58, v58, v59
	v_mul_f32_e32 v59, v51, v51
	v_fmac_f32_e32 v59, v50, v50
	v_add_f32_e32 v58, v58, v59
	v_mul_f32_e32 v59, v53, v53
	v_fmac_f32_e32 v59, v52, v52
	v_add_f32_e32 v58, v59, v58
	v_add_f32_e32 v64, v92, v58
	ds_bpermute_b32 v65, v213, v64
	global_store_dwordx4 v[132:133], v[54:57], off offset:512 nt
	global_store_dwordx4 v[132:133], v[50:53], off offset:528 nt
	v_pk_mul_f32 v[60:61], v[182:183], v[50:51]
	v_pk_mul_f32 v[54:55], v[184:185], v[54:55]
	v_pk_mul_f32 v[56:57], v[186:187], v[56:57]
	s_waitcnt lgkmcnt(0)
	v_add_f32_e32 v50, v64, v65
	ds_bpermute_b32 v51, v214, v50
	v_pk_mul_f32 v[58:59], v[180:181], v[52:53]
	v_cvt_pk_bf16_f32 v52, v54, v55
	v_cvt_pk_bf16_f32 v53, v56, v57
	v_cvt_pk_bf16_f32 v54, v60, v61
	s_nop 0
	v_cvt_pk_bf16_f32 v55, v58, v59
	global_store_dwordx4 v[62:63], v[52:55], off offset:256 sc1
	s_and_saveexec_b64 s[36:37], s[0:1]
	s_cbranch_execz .LBB0_3045
	s_waitcnt lgkmcnt(0)
	v_add_f32_e32 v52, v50, v51
	v_lshlrev_b64 v[50:51], 7, v[130:131]
	v_lshl_add_u64 v[50:51], s[22:23], 0, v[50:51]
	v_lshl_add_u64 v[50:51], s[34:35], 2, v[50:51]
	s_lshl_b32 s12, s57, 2
	v_lshl_add_u64 v[50:51], v[50:51], 0, s[12:13]
	global_store_dword v[50:51], v52, off
.LBB0_3045:
	s_or_b64 exec, exec, s[36:37]
	v_or_b32_e32 v82, 32, v130
	v_ashrrev_i32_e32 v83, 31, v82
	s_waitcnt lgkmcnt(0)
	v_lshlrev_b64 v[50:51], 13, v[82:83]
	v_lshl_add_u64 v[50:51], s[16:17], 0, v[50:51]
	v_lshl_add_u64 v[84:85], v[178:179], 2, v[50:51]
	global_load_dwordx4 v[58:61], v[84:85], off offset:16 nt
	global_load_dwordx4 v[62:65], v[84:85], off nt
	global_load_dwordx4 v[50:53], v[84:85], off offset:528 nt
	global_load_dwordx4 v[54:57], v[84:85], off offset:512 nt
	s_waitcnt vmcnt(12)
	v_pk_fma_f32 v[48:49], v[48:49], v[128:129], v[80:81]
	v_pk_fma_f32 v[46:47], v[46:47], v[126:127], v[78:79]
	v_pk_fma_f32 v[42:43], v[42:43], v[118:119], v[74:75]
	v_mul_f32_e32 v74, v47, v47
	v_mul_f32_e32 v75, v49, v49
	v_fmac_f32_e32 v74, v46, v46
	v_fmac_f32_e32 v75, v48, v48
	v_add_f32_e32 v74, v74, v75
	v_mul_f32_e32 v75, v43, v43
	v_pk_fma_f32 v[44:45], v[44:45], v[120:121], v[76:77]
	v_fmac_f32_e32 v75, v42, v42
	v_add_f32_e32 v74, v74, v75
	v_mul_f32_e32 v75, v45, v45
	global_store_dwordx4 v[100:101], v[46:49], off nt
	global_store_dwordx4 v[100:101], v[42:45], off offset:16 nt
	v_fmac_f32_e32 v75, v44, v44
	v_pk_mul_f32 v[46:47], v[194:195], v[46:47]
	v_add_f32_e32 v76, v75, v74
	v_pk_mul_f32 v[74:75], v[188:189], v[44:45]
	v_pk_mul_f32 v[44:45], v[190:191], v[42:43]
	v_cvt_pk_bf16_f32 v42, v46, v47
	v_lshlrev_b64 v[46:47], 12, v[98:99]
	v_lshl_add_u64 v[46:47], s[18:19], 0, v[46:47]
	v_pk_mul_f32 v[48:49], v[192:193], v[48:49]
	v_lshl_add_u64 v[46:47], v[178:179], 1, v[46:47]
	v_cvt_pk_bf16_f32 v43, v48, v49
	s_waitcnt vmcnt(12)
	v_pk_fma_f32 v[40:41], v[40:41], v[124:125], v[72:73]
	v_pk_fma_f32 v[38:39], v[38:39], v[122:123], v[70:71]
	v_cvt_pk_bf16_f32 v44, v44, v45
	v_cvt_pk_bf16_f32 v45, v74, v75
	global_store_dwordx4 v[46:47], v[42:45], off sc1
	v_pk_fma_f32 v[34:35], v[34:35], v[114:115], v[66:67]
	v_pk_fma_f32 v[36:37], v[36:37], v[116:117], v[68:69]
	v_mul_f32_e32 v42, v39, v39
	v_mul_f32_e32 v43, v41, v41
	v_fmac_f32_e32 v42, v38, v38
	v_fmac_f32_e32 v43, v40, v40
	v_add_f32_e32 v42, v42, v43
	v_mul_f32_e32 v43, v35, v35
	v_fmac_f32_e32 v43, v34, v34
	v_add_f32_e32 v42, v42, v43
	v_mul_f32_e32 v43, v37, v37
	v_fmac_f32_e32 v43, v36, v36
	v_add_f32_e32 v42, v43, v42
	v_add_f32_e32 v48, v76, v42
	ds_bpermute_b32 v49, v213, v48
	global_store_dwordx4 v[100:101], v[38:41], off offset:512 nt
	global_store_dwordx4 v[100:101], v[34:37], off offset:528 nt
	v_pk_mul_f32 v[44:45], v[182:183], v[34:35]
	v_pk_mul_f32 v[38:39], v[184:185], v[38:39]
	v_pk_mul_f32 v[40:41], v[186:187], v[40:41]
	s_waitcnt lgkmcnt(0)
	v_add_f32_e32 v34, v48, v49
	ds_bpermute_b32 v35, v214, v34
	v_pk_mul_f32 v[42:43], v[180:181], v[36:37]
	v_cvt_pk_bf16_f32 v36, v38, v39
	v_cvt_pk_bf16_f32 v37, v40, v41
	v_cvt_pk_bf16_f32 v38, v44, v45
	s_nop 0
	v_cvt_pk_bf16_f32 v39, v42, v43
	global_store_dwordx4 v[46:47], v[36:39], off offset:256 sc1
	s_and_saveexec_b64 s[36:37], s[0:1]
	s_cbranch_execz .LBB0_3047
	s_waitcnt lgkmcnt(0)
	v_add_f32_e32 v36, v34, v35
	v_lshlrev_b64 v[34:35], 7, v[98:99]
	v_lshl_add_u64 v[34:35], s[22:23], 0, v[34:35]
	v_lshl_add_u64 v[34:35], s[34:35], 2, v[34:35]
	s_lshl_b32 s12, s57, 2
	v_lshl_add_u64 v[34:35], v[34:35], 0, s[12:13]
	global_store_dword v[34:35], v36, off
.LBB0_3047:
	s_or_b64 exec, exec, s[36:37]
	v_or_b32_e32 v66, 48, v130
	v_ashrrev_i32_e32 v67, 31, v66
	s_waitcnt lgkmcnt(0)
	v_lshlrev_b64 v[34:35], 13, v[66:67]
	v_lshl_add_u64 v[34:35], s[16:17], 0, v[34:35]
	v_lshl_add_u64 v[68:69], v[178:179], 2, v[34:35]
	global_load_dwordx4 v[42:45], v[68:69], off offset:16 nt
	global_load_dwordx4 v[46:49], v[68:69], off nt
	global_load_dwordx4 v[34:37], v[68:69], off offset:528 nt
	global_load_dwordx4 v[38:41], v[68:69], off offset:512 nt
	s_waitcnt vmcnt(12)
	v_pk_fma_f32 v[32:33], v[32:33], v[128:129], v[64:65]
	v_pk_fma_f32 v[30:31], v[30:31], v[126:127], v[62:63]
	v_pk_fma_f32 v[26:27], v[26:27], v[118:119], v[58:59]
	v_mul_f32_e32 v58, v31, v31
	v_mul_f32_e32 v59, v33, v33
	v_fmac_f32_e32 v58, v30, v30
	v_fmac_f32_e32 v59, v32, v32
	v_add_f32_e32 v58, v58, v59
	v_mul_f32_e32 v59, v27, v27
	v_pk_fma_f32 v[28:29], v[28:29], v[120:121], v[60:61]
	v_fmac_f32_e32 v59, v26, v26
	v_add_f32_e32 v58, v58, v59
	v_mul_f32_e32 v59, v29, v29
	global_store_dwordx4 v[84:85], v[30:33], off nt
	global_store_dwordx4 v[84:85], v[26:29], off offset:16 nt
	v_fmac_f32_e32 v59, v28, v28
	v_pk_mul_f32 v[30:31], v[194:195], v[30:31]
	v_add_f32_e32 v60, v59, v58
	v_pk_mul_f32 v[58:59], v[188:189], v[28:29]
	v_pk_mul_f32 v[28:29], v[190:191], v[26:27]
	v_cvt_pk_bf16_f32 v26, v30, v31
	v_lshlrev_b64 v[30:31], 12, v[82:83]
	v_lshl_add_u64 v[30:31], s[18:19], 0, v[30:31]
	v_pk_mul_f32 v[32:33], v[192:193], v[32:33]
	v_lshl_add_u64 v[30:31], v[178:179], 1, v[30:31]
	v_cvt_pk_bf16_f32 v27, v32, v33
	s_waitcnt vmcnt(12)
	v_pk_fma_f32 v[24:25], v[24:25], v[124:125], v[56:57]
	v_pk_fma_f32 v[22:23], v[22:23], v[122:123], v[54:55]
	v_cvt_pk_bf16_f32 v28, v28, v29
	v_cvt_pk_bf16_f32 v29, v58, v59
	global_store_dwordx4 v[30:31], v[26:29], off sc1
	v_pk_fma_f32 v[18:19], v[18:19], v[114:115], v[50:51]
	v_pk_fma_f32 v[20:21], v[20:21], v[116:117], v[52:53]
	v_mul_f32_e32 v26, v23, v23
	v_mul_f32_e32 v27, v25, v25
	v_fmac_f32_e32 v26, v22, v22
	v_fmac_f32_e32 v27, v24, v24
	v_add_f32_e32 v26, v26, v27
	v_mul_f32_e32 v27, v19, v19
	v_fmac_f32_e32 v27, v18, v18
	v_add_f32_e32 v26, v26, v27
	v_mul_f32_e32 v27, v21, v21
	v_fmac_f32_e32 v27, v20, v20
	v_add_f32_e32 v26, v27, v26
	v_add_f32_e32 v32, v60, v26
	ds_bpermute_b32 v33, v213, v32
	global_store_dwordx4 v[84:85], v[22:25], off offset:512 nt
	global_store_dwordx4 v[84:85], v[18:21], off offset:528 nt
	v_pk_mul_f32 v[28:29], v[182:183], v[18:19]
	v_pk_mul_f32 v[22:23], v[184:185], v[22:23]
	v_pk_mul_f32 v[24:25], v[186:187], v[24:25]
	s_waitcnt lgkmcnt(0)
	v_add_f32_e32 v18, v32, v33
	ds_bpermute_b32 v19, v214, v18
	v_pk_mul_f32 v[26:27], v[180:181], v[20:21]
	v_cvt_pk_bf16_f32 v20, v22, v23
	v_cvt_pk_bf16_f32 v21, v24, v25
	v_cvt_pk_bf16_f32 v22, v28, v29
	s_nop 0
	v_cvt_pk_bf16_f32 v23, v26, v27
	global_store_dwordx4 v[30:31], v[20:23], off offset:256 sc1
	s_and_saveexec_b64 s[36:37], s[0:1]
	s_cbranch_execz .LBB0_3049
	s_waitcnt lgkmcnt(0)
	v_add_f32_e32 v20, v18, v19
	v_lshlrev_b64 v[18:19], 7, v[82:83]
	v_lshl_add_u64 v[18:19], s[22:23], 0, v[18:19]
	v_lshl_add_u64 v[18:19], s[34:35], 2, v[18:19]
	s_lshl_b32 s12, s57, 2
	v_lshl_add_u64 v[18:19], v[18:19], 0, s[12:13]
	global_store_dword v[18:19], v20, off
.LBB0_3049:
	s_or_b64 exec, exec, s[36:37]
	s_waitcnt vmcnt(8)
	v_pk_fma_f32 v[16:17], v[16:17], v[128:129], v[48:49]
	v_pk_fma_f32 v[14:15], v[14:15], v[126:127], v[46:47]
	s_waitcnt lgkmcnt(0)
	v_mul_f32_e32 v19, v17, v17
	v_mul_f32_e32 v18, v15, v15
	v_pk_fma_f32 v[10:11], v[10:11], v[118:119], v[42:43]
	v_fmac_f32_e32 v18, v14, v14
	v_fmac_f32_e32 v19, v16, v16
	v_add_f32_e32 v18, v18, v19
	v_mul_f32_e32 v19, v11, v11
	v_pk_fma_f32 v[12:13], v[12:13], v[120:121], v[44:45]
	v_fmac_f32_e32 v19, v10, v10
	v_add_f32_e32 v18, v18, v19
	v_mul_f32_e32 v19, v13, v13
	global_store_dwordx4 v[68:69], v[14:17], off nt
	global_store_dwordx4 v[68:69], v[10:13], off offset:16 nt
	v_fmac_f32_e32 v19, v12, v12
	v_pk_mul_f32 v[14:15], v[194:195], v[14:15]
	v_add_f32_e32 v20, v19, v18
	v_pk_mul_f32 v[18:19], v[188:189], v[12:13]
	v_pk_mul_f32 v[12:13], v[190:191], v[10:11]
	v_cvt_pk_bf16_f32 v10, v14, v15
	v_lshlrev_b64 v[14:15], 12, v[66:67]
	v_lshl_add_u64 v[14:15], s[18:19], 0, v[14:15]
	v_pk_mul_f32 v[16:17], v[192:193], v[16:17]
	v_lshl_add_u64 v[14:15], v[178:179], 1, v[14:15]
	v_cvt_pk_bf16_f32 v11, v16, v17
	s_waitcnt vmcnt(8)
	v_pk_fma_f32 v[8:9], v[8:9], v[124:125], v[40:41]
	v_pk_fma_f32 v[6:7], v[6:7], v[122:123], v[38:39]
	v_cvt_pk_bf16_f32 v12, v12, v13
	v_cvt_pk_bf16_f32 v13, v18, v19
	global_store_dwordx4 v[14:15], v[10:13], off sc1
	v_pk_fma_f32 v[2:3], v[2:3], v[114:115], v[34:35]
	v_pk_fma_f32 v[4:5], v[4:5], v[116:117], v[36:37]
	v_mul_f32_e32 v10, v7, v7
	v_mul_f32_e32 v11, v9, v9
	v_fmac_f32_e32 v10, v6, v6
	v_fmac_f32_e32 v11, v8, v8
	v_add_f32_e32 v10, v10, v11
	v_mul_f32_e32 v11, v3, v3
	v_fmac_f32_e32 v11, v2, v2
	v_add_f32_e32 v10, v10, v11
	v_mul_f32_e32 v11, v5, v5
	v_fmac_f32_e32 v11, v4, v4
	v_add_f32_e32 v10, v11, v10
	v_add_f32_e32 v16, v20, v10
	ds_bpermute_b32 v17, v213, v16
	global_store_dwordx4 v[68:69], v[6:9], off offset:512 nt
	global_store_dwordx4 v[68:69], v[2:5], off offset:528 nt
	v_pk_mul_f32 v[12:13], v[182:183], v[2:3]
	v_pk_mul_f32 v[6:7], v[184:185], v[6:7]
	v_pk_mul_f32 v[8:9], v[186:187], v[8:9]
	s_waitcnt lgkmcnt(0)
	v_add_f32_e32 v2, v16, v17
	ds_bpermute_b32 v3, v214, v2
	v_pk_mul_f32 v[10:11], v[180:181], v[4:5]
	v_cvt_pk_bf16_f32 v4, v6, v7
	v_cvt_pk_bf16_f32 v5, v8, v9
	v_cvt_pk_bf16_f32 v6, v12, v13
	s_nop 0
	v_cvt_pk_bf16_f32 v7, v10, v11
	global_store_dwordx4 v[14:15], v[4:7], off offset:256 sc1
	s_and_saveexec_b64 s[36:37], s[0:1]
	s_cbranch_execz .LBB0_3051
	s_waitcnt lgkmcnt(0)
	v_add_f32_e32 v4, v2, v3
	v_lshlrev_b64 v[2:3], 7, v[66:67]
	v_lshl_add_u64 v[2:3], s[22:23], 0, v[2:3]
	v_lshl_add_u64 v[2:3], s[34:35], 2, v[2:3]
	s_lshl_b32 s12, s57, 2
	v_lshl_add_u64 v[2:3], v[2:3], 0, s[12:13]
	global_store_dword v[2:3], v4, off

.LBB0_3136:
	s_lshl_b32 s94, s10, 1
	s_sub_i32 s95, s94, 20
	s_cmp_gt_i32 s10, 7
	v_lshlrev_b64 v[148:149], 10, v[184:185]
	s_cselect_b64 s[12:13], -1, 0
	s_waitcnt vmcnt(0) lgkmcnt(0)
	v_pk_fma_f32 v[144:145], v[144:145], v[190:191], v[56:57] op_sel_hi:[1,0,1]
	v_pk_fma_f32 v[142:143], v[142:143], v[190:191], v[54:55] op_sel_hi:[1,0,1]
	v_pk_fma_f32 v[140:141], v[140:141], v[190:191], v[52:53] op_sel_hi:[1,0,1]
	v_pk_fma_f32 v[138:139], v[138:139], v[190:191], v[50:51] op_sel_hi:[1,0,1]
	s_mov_b64 s[10:11], -1
	s_and_b64 vcc, exec, s[6:7]
	v_lshl_add_u64 v[192:193], s[28:29], 0, v[148:149]
	v_lshlrev_b32_e32 v162, 1, v164
	s_cbranch_vccz .LBB0_3140
	s_lshl_b32 s20, s95, 7
	v_lshl_add_u64 v[152:153], s[20:21], 1, v[192:193]
	v_lshl_add_u64 v[152:153], v[152:153], 0, v[162:163]
	s_andn2_b64 vcc, exec, s[54:55]
	v_cvt_pk_bf16_f32 v202, v142, v143
	v_cvt_pk_bf16_f32 v203, v144, v145
	v_cvt_pk_bf16_f32 v204, v138, v139
	v_cvt_pk_bf16_f32 v205, v140, v141
	global_store_dwordx4 v[152:153], v[202:205], off sc1
	s_cbranch_vccnz .LBB0_3139
	s_lshl_b32 s10, s67, 1
	s_or_b32 s10, s10, 1
	s_ashr_i32 s11, s10, 31
	s_lshl_b64 s[10:11], s[10:11], 19
	v_lshl_add_u64 v[152:153], v[170:171], 0, s[10:11]
	v_lshl_add_u64 v[152:153], s[20:21], 2, v[152:153]
	v_mov_b32_e32 v183, v163
	v_lshl_add_u64 v[152:153], v[152:153], 0, v[182:183]
	global_store_dwordx4 v[152:153], v[142:145], off sc1
	global_store_dwordx4 v[152:153], v[138:141], off offset:16 sc1

.LBB0_3140:
	s_add_i32 s94, s94, -16
	s_andn2_b64 vcc, exec, s[10:11]
	v_lshlrev_b64 v[152:153], 12, v[184:185]
	s_cbranch_vccnz .LBB0_3147
	v_pk_mul_f32 v[202:203], v[140:141], v[186:187]
	v_pk_mul_f32 v[204:205], v[138:139], v[188:189]
	v_pk_mul_f32 v[206:207], v[140:141], v[146:147]
	v_pk_mul_f32 v[208:209], v[138:139], v[150:151]
	v_pk_fma_f32 v[202:203], v[144:145], v[146:147], v[202:203] neg_lo:[0,0,1] neg_hi:[0,0,1]
	v_pk_fma_f32 v[204:205], v[142:143], v[150:151], v[204:205] neg_lo:[0,0,1] neg_hi:[0,0,1]
	v_pk_fma_f32 v[206:207], v[144:145], v[186:187], v[206:207]
	v_pk_fma_f32 v[208:209], v[142:143], v[188:189], v[208:209]
	v_cndmask_b32_e64 v141, v141, v207, s[4:5]
	v_cndmask_b32_e64 v140, v140, v206, s[4:5]
	v_cndmask_b32_e64 v139, v139, v209, s[4:5]
	v_cndmask_b32_e64 v138, v138, v208, s[4:5]
	v_cndmask_b32_e64 v145, v145, v203, s[4:5]
	v_cndmask_b32_e64 v144, v144, v202, s[4:5]
	v_cndmask_b32_e64 v143, v143, v205, s[4:5]
	v_cndmask_b32_e64 v142, v142, v204, s[4:5]
	s_mov_b64 s[10:11], -1
	s_and_b64 vcc, exec, s[12:13]
	s_cbranch_vccz .LBB0_3145
	v_lshl_add_u64 v[206:207], s[26:27], 0, v[148:149]
	s_lshl_b32 s20, s94, 8
	v_lshl_add_u64 v[206:207], v[206:207], 0, s[20:21]
	v_lshl_add_u64 v[206:207], v[206:207], 0, v[162:163]
	s_andn2_b64 vcc, exec, s[54:55]
	v_cvt_pk_bf16_f32 v202, v142, v143
	v_cvt_pk_bf16_f32 v203, v144, v145
	v_cvt_pk_bf16_f32 v204, v138, v139
	v_cvt_pk_bf16_f32 v205, v140, v141
	global_store_dwordx4 v[206:207], v[202:205], off sc1
	s_cbranch_vccnz .LBB0_3144
	s_lshl_b32 s10, s67, 1
	s_or_b32 s10, s10, 1
	s_ashr_i32 s11, s10, 31
	s_lshl_b64 s[10:11], s[10:11], 19
	s_lshl_b32 s20, s94, 7
	v_lshl_add_u64 v[202:203], v[172:173], 0, s[10:11]
	v_lshl_add_u64 v[202:203], s[20:21], 2, v[202:203]
	v_lshlrev_b32_e32 v204, 2, v166
	v_mov_b32_e32 v205, v163
	v_lshl_add_u64 v[202:203], v[202:203], 0, v[204:205]
	global_store_dwordx4 v[202:203], v[142:145], off sc1
	global_store_dwordx4 v[202:203], v[138:141], off offset:128 sc1

.LBB0_3145:
	s_andn2_b64 vcc, exec, s[10:11]
	s_cbranch_vccnz .LBB0_3147
	v_cvt_pk_bf16_f32 v142, v142, v143
	v_cvt_pk_bf16_f32 v143, v144, v145
	v_cvt_pk_bf16_f32 v144, v138, v139
	v_lshl_add_u64 v[138:139], s[24:25], 0, v[152:153]
	v_lshl_add_u64 v[138:139], s[50:51], 1, v[138:139]
	v_lshl_add_u64 v[138:139], v[138:139], 0, v[162:163]
	v_cvt_pk_bf16_f32 v145, v140, v141
	global_store_dwordx4 v[138:139], v[142:145], off sc1
.LBB0_3147:
	v_mov_b32_e32 v138, v190
	v_mov_b32_e32 v139, v190
	v_mov_b32_e32 v191, v190
	v_pk_fma_f32 v[136:137], v[136:137], v[138:139], v[40:41]
	v_pk_fma_f32 v[132:133], v[132:133], v[138:139], v[36:37]
	v_cndmask_b32_e64 v138, 0, 1, s[6:7]
	v_pk_fma_f32 v[134:135], v[134:135], v[190:191], v[38:39]
	v_pk_fma_f32 v[130:131], v[130:131], v[190:191], v[34:35]
	v_cmp_ne_u32_e64 s[10:11], 1, v138
	s_andn2_b64 vcc, exec, s[6:7]
	s_mov_b64 s[6:7], -1
	s_cbranch_vccnz .LBB0_3151
	s_add_i32 s20, s50, 0xfffff680
	v_lshl_add_u64 v[142:143], s[20:21], 1, v[192:193]
	v_lshl_add_u64 v[142:143], v[142:143], 0, v[162:163]
	s_andn2_b64 vcc, exec, s[54:55]
	v_cvt_pk_bf16_f32 v138, v134, v135
	v_cvt_pk_bf16_f32 v139, v136, v137
	v_cvt_pk_bf16_f32 v140, v130, v131
	v_cvt_pk_bf16_f32 v141, v132, v133
	global_store_dwordx4 v[142:143], v[138:141], off sc1
	s_cbranch_vccnz .LBB0_3150
	s_lshl_b32 s6, s67, 1
	s_or_b32 s6, s6, 1
	s_ashr_i32 s7, s6, 31
	s_lshl_b64 s[6:7], s[6:7], 19
	v_lshl_add_u64 v[138:139], v[170:171], 0, s[6:7]
	v_lshl_add_u64 v[138:139], s[20:21], 2, v[138:139]
	v_mov_b32_e32 v183, v163
	v_lshl_add_u64 v[138:139], v[138:139], 0, v[182:183]
	global_store_dwordx4 v[138:139], v[134:137], off sc1
	global_store_dwordx4 v[138:139], v[130:133], off offset:16 sc1

.LBB0_3151:
	v_cndmask_b32_e64 v138, 0, 1, s[12:13]
	s_andn2_b64 vcc, exec, s[6:7]
	v_cmp_ne_u32_e64 s[6:7], 1, v138
	s_cbranch_vccnz .LBB0_3158
	v_pk_mul_f32 v[138:139], v[132:133], v[186:187]
	v_pk_mul_f32 v[140:141], v[130:131], v[188:189]
	v_pk_mul_f32 v[142:143], v[132:133], v[146:147]
	v_pk_mul_f32 v[144:145], v[130:131], v[150:151]
	v_pk_fma_f32 v[138:139], v[136:137], v[146:147], v[138:139] neg_lo:[0,0,1] neg_hi:[0,0,1]
	v_pk_fma_f32 v[140:141], v[134:135], v[150:151], v[140:141] neg_lo:[0,0,1] neg_hi:[0,0,1]
	v_pk_fma_f32 v[142:143], v[136:137], v[186:187], v[142:143]
	v_pk_fma_f32 v[144:145], v[134:135], v[188:189], v[144:145]
	v_cndmask_b32_e64 v133, v133, v143, s[4:5]
	v_cndmask_b32_e64 v132, v132, v142, s[4:5]
	v_cndmask_b32_e64 v131, v131, v145, s[4:5]
	v_cndmask_b32_e64 v130, v130, v144, s[4:5]
	v_cndmask_b32_e64 v137, v137, v139, s[4:5]
	v_cndmask_b32_e64 v136, v136, v138, s[4:5]
	v_cndmask_b32_e64 v135, v135, v141, s[4:5]
	v_cndmask_b32_e64 v134, v134, v140, s[4:5]
	s_and_b64 vcc, exec, s[6:7]
	s_mov_b64 s[12:13], -1
	s_cbranch_vccnz .LBB0_3156
	v_lshl_add_u64 v[142:143], s[26:27], 0, v[148:149]
	s_add_i32 s20, s50, 0xfffff880
	v_lshl_add_u64 v[142:143], s[20:21], 1, v[142:143]
	v_lshl_add_u64 v[142:143], v[142:143], 0, v[162:163]
	s_andn2_b64 vcc, exec, s[54:55]
	v_cvt_pk_bf16_f32 v138, v134, v135
	v_cvt_pk_bf16_f32 v139, v136, v137
	v_cvt_pk_bf16_f32 v140, v130, v131
	v_cvt_pk_bf16_f32 v141, v132, v133
	global_store_dwordx4 v[142:143], v[138:141], off sc1
	s_cbranch_vccnz .LBB0_3155
	s_lshl_b32 s12, s67, 1
	s_or_b32 s12, s12, 1
	s_ashr_i32 s13, s12, 31
	s_lshl_b64 s[12:13], s[12:13], 19
	v_lshl_add_u64 v[138:139], v[172:173], 0, s[12:13]
	v_lshl_add_u64 v[138:139], s[20:21], 2, v[138:139]
	v_lshlrev_b32_e32 v140, 2, v166
	v_mov_b32_e32 v141, v163
	v_lshl_add_u64 v[138:139], v[138:139], 0, v[140:141]
	global_store_dwordx4 v[138:139], v[134:137], off sc1
	global_store_dwordx4 v[138:139], v[130:133], off offset:128 sc1

.LBB0_3156:
	s_andn2_b64 vcc, exec, s[12:13]
	s_cbranch_vccnz .LBB0_3158
	v_cvt_pk_bf16_f32 v134, v134, v135
	v_cvt_pk_bf16_f32 v135, v136, v137
	v_cvt_pk_bf16_f32 v136, v130, v131
	v_lshl_add_u64 v[130:131], s[24:25], 0, v[152:153]
	v_lshl_add_u64 v[130:131], s[50:51], 1, v[130:131]
	v_lshl_add_u64 v[130:131], v[130:131], 0, v[162:163]
	v_cvt_pk_bf16_f32 v137, v132, v133
	global_store_dwordx4 v[130:131], v[134:137], off offset:256 sc1

.LBB0_3165:
	v_lshlrev_b64 v[132:133], 10, v[146:147]
	v_lshlrev_b32_e32 v136, 9, v146
	v_and_b32_e32 v148, 0x1be00, v136
	s_waitcnt lgkmcnt(0)
	v_pk_fma_f32 v[128:129], v[128:129], v[142:143], v[56:57] op_sel_hi:[1,0,1]
	v_pk_fma_f32 v[126:127], v[126:127], v[142:143], v[54:55] op_sel_hi:[1,0,1]
	v_pk_fma_f32 v[124:125], v[124:125], v[142:143], v[52:53] op_sel_hi:[1,0,1]
	v_pk_fma_f32 v[122:123], v[122:123], v[142:143], v[50:51] op_sel_hi:[1,0,1]
	s_mov_b64 s[56:57], -1
	s_and_b64 vcc, exec, s[10:11]
	v_lshl_add_u64 v[144:145], s[28:29], 0, v[132:133]
	s_cbranch_vccnz .LBB0_3169
	s_lshl_b32 s20, s95, 7
	v_lshl_add_u64 v[136:137], s[20:21], 1, v[144:145]
	v_lshl_add_u64 v[136:137], v[136:137], 0, v[162:163]
	s_andn2_b64 vcc, exec, s[54:55]
	v_cvt_pk_bf16_f32 v150, v126, v127
	v_cvt_pk_bf16_f32 v151, v128, v129
	v_cvt_pk_bf16_f32 v152, v122, v123
	v_cvt_pk_bf16_f32 v153, v124, v125
	global_store_dwordx4 v[136:137], v[150:153], off sc1
	s_cbranch_vccnz .LBB0_3168
	s_lshl_b32 s56, s67, 1
	s_or_b32 s56, s56, 1
	s_ashr_i32 s57, s56, 31
	s_lshl_b64 s[56:57], s[56:57], 19
	s_add_u32 s56, s34, s56
	s_addc_u32 s57, s35, s57
	v_lshlrev_b32_e32 v136, 2, v148
	v_mov_b32_e32 v137, v163
	v_lshl_add_u64 v[136:137], s[56:57], 0, v[136:137]
	v_lshl_add_u64 v[136:137], s[20:21], 2, v[136:137]
	v_mov_b32_e32 v183, v163
	v_lshl_add_u64 v[136:137], v[136:137], 0, v[182:183]
	global_store_dwordx4 v[136:137], v[126:129], off sc1
	global_store_dwordx4 v[136:137], v[122:125], off offset:16 sc1

.LBB0_3169:
	s_andn2_b64 vcc, exec, s[56:57]
	v_lshlrev_b64 v[136:137], 12, v[146:147]
	s_cbranch_vccnz .LBB0_3176
	v_pk_mul_f32 v[146:147], v[124:125], v[138:139]
	v_pk_mul_f32 v[150:151], v[122:123], v[140:141]
	v_pk_mul_f32 v[152:153], v[124:125], v[130:131]
	v_pk_mul_f32 v[186:187], v[122:123], v[134:135]
	v_pk_fma_f32 v[146:147], v[128:129], v[130:131], v[146:147] neg_lo:[0,0,1] neg_hi:[0,0,1]
	v_pk_fma_f32 v[150:151], v[126:127], v[134:135], v[150:151] neg_lo:[0,0,1] neg_hi:[0,0,1]
	v_pk_fma_f32 v[152:153], v[128:129], v[138:139], v[152:153]
	v_pk_fma_f32 v[186:187], v[126:127], v[140:141], v[186:187]
	v_cndmask_b32_e64 v125, v125, v153, s[4:5]
	v_cndmask_b32_e64 v124, v124, v152, s[4:5]
	v_cndmask_b32_e64 v123, v123, v187, s[4:5]
	v_cndmask_b32_e64 v122, v122, v186, s[4:5]
	v_cndmask_b32_e64 v129, v129, v147, s[4:5]
	v_cndmask_b32_e64 v128, v128, v146, s[4:5]
	v_cndmask_b32_e64 v127, v127, v151, s[4:5]
	v_cndmask_b32_e64 v126, v126, v150, s[4:5]
	s_and_b64 vcc, exec, s[6:7]
	s_mov_b64 s[56:57], -1
	s_cbranch_vccnz .LBB0_3174
	v_lshl_add_u64 v[146:147], s[26:27], 0, v[132:133]
	s_lshl_b32 s20, s94, 8
	v_lshl_add_u64 v[146:147], v[146:147], 0, s[20:21]
	v_lshl_add_u64 v[146:147], v[146:147], 0, v[162:163]
	s_andn2_b64 vcc, exec, s[54:55]
	v_cvt_pk_bf16_f32 v150, v126, v127
	v_cvt_pk_bf16_f32 v151, v128, v129
	v_cvt_pk_bf16_f32 v152, v122, v123
	v_cvt_pk_bf16_f32 v153, v124, v125
	global_store_dwordx4 v[146:147], v[150:153], off sc1
	s_cbranch_vccnz .LBB0_3173
	s_lshl_b32 s56, s67, 1
	s_or_b32 s56, s56, 1
	s_ashr_i32 s57, s56, 31
	s_lshl_b32 s20, s94, 7
	s_lshl_b64 s[56:57], s[56:57], 19
	s_add_u32 s56, s30, s56
	s_addc_u32 s57, s31, s57
	v_lshlrev_b32_e32 v146, 2, v148
	v_mov_b32_e32 v147, v163
	v_lshl_add_u64 v[146:147], s[56:57], 0, v[146:147]
	v_lshl_add_u64 v[146:147], s[20:21], 2, v[146:147]
	v_lshlrev_b32_e32 v150, 2, v166
	v_mov_b32_e32 v151, v163
	v_lshl_add_u64 v[146:147], v[146:147], 0, v[150:151]
	global_store_dwordx4 v[146:147], v[126:129], off sc1
	global_store_dwordx4 v[146:147], v[122:125], off offset:128 sc1

.LBB0_3174:
	s_andn2_b64 vcc, exec, s[56:57]
	s_cbranch_vccnz .LBB0_3176
	v_cvt_pk_bf16_f32 v126, v126, v127
	v_cvt_pk_bf16_f32 v127, v128, v129
	v_cvt_pk_bf16_f32 v128, v122, v123
	v_lshl_add_u64 v[122:123], s[24:25], 0, v[136:137]
	v_lshl_add_u64 v[122:123], s[50:51], 1, v[122:123]
	v_lshl_add_u64 v[122:123], v[122:123], 0, v[162:163]
	v_cvt_pk_bf16_f32 v129, v124, v125
	global_store_dwordx4 v[122:123], v[126:129], off sc1
.LBB0_3176:
	v_mov_b32_e32 v143, v142
	v_mov_b32_e32 v122, v142
	v_mov_b32_e32 v123, v142
	v_pk_fma_f32 v[120:121], v[120:121], v[122:123], v[40:41]
	v_pk_fma_f32 v[118:119], v[118:119], v[142:143], v[38:39]
	v_pk_fma_f32 v[116:117], v[116:117], v[122:123], v[36:37]
	v_pk_fma_f32 v[114:115], v[114:115], v[142:143], v[34:35]
	s_and_b64 vcc, exec, s[10:11]
	s_mov_b64 s[56:57], -1
	s_cbranch_vccnz .LBB0_3180
	s_add_i32 s20, s50, 0xfffff680
	v_lshl_add_u64 v[126:127], s[20:21], 1, v[144:145]
	v_lshl_add_u64 v[126:127], v[126:127], 0, v[162:163]
	s_andn2_b64 vcc, exec, s[54:55]
	v_cvt_pk_bf16_f32 v122, v118, v119
	v_cvt_pk_bf16_f32 v123, v120, v121
	v_cvt_pk_bf16_f32 v124, v114, v115
	v_cvt_pk_bf16_f32 v125, v116, v117
	global_store_dwordx4 v[126:127], v[122:125], off sc1
	s_cbranch_vccnz .LBB0_3179
	s_lshl_b32 s56, s67, 1
	s_or_b32 s56, s56, 1
	s_ashr_i32 s57, s56, 31
	s_lshl_b64 s[56:57], s[56:57], 19
	s_add_u32 s56, s34, s56
	s_addc_u32 s57, s35, s57
	v_lshlrev_b32_e32 v122, 2, v148
	v_mov_b32_e32 v123, v163
	v_lshl_add_u64 v[122:123], s[56:57], 0, v[122:123]
	v_lshl_add_u64 v[122:123], s[20:21], 2, v[122:123]
	v_mov_b32_e32 v183, v163
	v_lshl_add_u64 v[122:123], v[122:123], 0, v[182:183]
	global_store_dwordx4 v[122:123], v[118:121], off sc1
	global_store_dwordx4 v[122:123], v[114:117], off offset:16 sc1

.LBB0_3180:
	s_andn2_b64 vcc, exec, s[56:57]
	s_cbranch_vccnz .LBB0_3187
	v_pk_mul_f32 v[122:123], v[116:117], v[138:139]
	v_pk_mul_f32 v[124:125], v[114:115], v[140:141]
	v_pk_mul_f32 v[126:127], v[116:117], v[130:131]
	v_pk_mul_f32 v[128:129], v[114:115], v[134:135]
	v_pk_fma_f32 v[122:123], v[120:121], v[130:131], v[122:123] neg_lo:[0,0,1] neg_hi:[0,0,1]
	v_pk_fma_f32 v[124:125], v[118:119], v[134:135], v[124:125] neg_lo:[0,0,1] neg_hi:[0,0,1]
	v_pk_fma_f32 v[126:127], v[120:121], v[138:139], v[126:127]
	v_pk_fma_f32 v[128:129], v[118:119], v[140:141], v[128:129]
	v_cndmask_b32_e64 v117, v117, v127, s[4:5]
	v_cndmask_b32_e64 v116, v116, v126, s[4:5]
	v_cndmask_b32_e64 v115, v115, v129, s[4:5]
	v_cndmask_b32_e64 v114, v114, v128, s[4:5]
	v_cndmask_b32_e64 v121, v121, v123, s[4:5]
	v_cndmask_b32_e64 v120, v120, v122, s[4:5]
	v_cndmask_b32_e64 v119, v119, v125, s[4:5]
	v_cndmask_b32_e64 v118, v118, v124, s[4:5]
	s_and_b64 vcc, exec, s[6:7]
	s_mov_b64 s[56:57], -1
	s_cbranch_vccnz .LBB0_3185
	v_lshl_add_u64 v[126:127], s[26:27], 0, v[132:133]
	s_add_i32 s20, s50, 0xfffff880
	v_lshl_add_u64 v[126:127], s[20:21], 1, v[126:127]
	v_lshl_add_u64 v[126:127], v[126:127], 0, v[162:163]
	s_andn2_b64 vcc, exec, s[54:55]
	v_cvt_pk_bf16_f32 v122, v118, v119
	v_cvt_pk_bf16_f32 v123, v120, v121
	v_cvt_pk_bf16_f32 v124, v114, v115
	v_cvt_pk_bf16_f32 v125, v116, v117
	global_store_dwordx4 v[126:127], v[122:125], off sc1
	s_cbranch_vccnz .LBB0_3184
	s_lshl_b32 s56, s67, 1
	s_or_b32 s56, s56, 1
	s_ashr_i32 s57, s56, 31
	s_lshl_b64 s[56:57], s[56:57], 19
	s_add_u32 s56, s30, s56
	s_addc_u32 s57, s31, s57
	v_lshlrev_b32_e32 v122, 2, v148
	v_mov_b32_e32 v123, v163
	v_lshl_add_u64 v[122:123], s[56:57], 0, v[122:123]
	v_lshl_add_u64 v[122:123], s[20:21], 2, v[122:123]
	v_lshlrev_b32_e32 v124, 2, v166
	v_mov_b32_e32 v125, v163
	v_lshl_add_u64 v[122:123], v[122:123], 0, v[124:125]
	global_store_dwordx4 v[122:123], v[118:121], off sc1
	global_store_dwordx4 v[122:123], v[114:117], off offset:128 sc1

.LBB0_3185:
	s_andn2_b64 vcc, exec, s[56:57]
	s_cbranch_vccnz .LBB0_3187
	v_cvt_pk_bf16_f32 v118, v118, v119
	v_cvt_pk_bf16_f32 v119, v120, v121
	v_cvt_pk_bf16_f32 v120, v114, v115
	v_lshl_add_u64 v[114:115], s[24:25], 0, v[136:137]
	v_lshl_add_u64 v[114:115], s[50:51], 1, v[114:115]
	v_lshl_add_u64 v[114:115], v[114:115], 0, v[162:163]
	v_cvt_pk_bf16_f32 v121, v116, v117
	global_store_dwordx4 v[114:115], v[118:121], off offset:256 sc1

.LBB0_3194:
	v_lshlrev_b64 v[116:117], 10, v[130:131]
	v_lshlrev_b32_e32 v120, 9, v130
	v_and_b32_e32 v132, 0x1de00, v120
	s_waitcnt lgkmcnt(0)
	v_pk_fma_f32 v[112:113], v[112:113], v[126:127], v[56:57] op_sel_hi:[1,0,1]
	v_pk_fma_f32 v[110:111], v[110:111], v[126:127], v[54:55] op_sel_hi:[1,0,1]
	v_pk_fma_f32 v[108:109], v[108:109], v[126:127], v[52:53] op_sel_hi:[1,0,1]
	v_pk_fma_f32 v[106:107], v[106:107], v[126:127], v[50:51] op_sel_hi:[1,0,1]
	s_mov_b64 s[56:57], -1
	s_and_b64 vcc, exec, s[10:11]
	v_lshl_add_u64 v[128:129], s[28:29], 0, v[116:117]
	s_cbranch_vccnz .LBB0_3198
	s_lshl_b32 s20, s95, 7
	v_lshl_add_u64 v[120:121], s[20:21], 1, v[128:129]
	v_lshl_add_u64 v[120:121], v[120:121], 0, v[162:163]
	s_andn2_b64 vcc, exec, s[54:55]
	v_cvt_pk_bf16_f32 v134, v110, v111
	v_cvt_pk_bf16_f32 v135, v112, v113
	v_cvt_pk_bf16_f32 v136, v106, v107
	v_cvt_pk_bf16_f32 v137, v108, v109
	global_store_dwordx4 v[120:121], v[134:137], off sc1
	s_cbranch_vccnz .LBB0_3197
	s_lshl_b32 s56, s67, 1
	s_or_b32 s56, s56, 1
	s_ashr_i32 s57, s56, 31
	s_lshl_b64 s[56:57], s[56:57], 19
	s_add_u32 s56, s34, s56
	s_addc_u32 s57, s35, s57
	v_lshlrev_b32_e32 v120, 2, v132
	v_mov_b32_e32 v121, v163
	v_lshl_add_u64 v[120:121], s[56:57], 0, v[120:121]
	v_lshl_add_u64 v[120:121], s[20:21], 2, v[120:121]
	v_mov_b32_e32 v183, v163
	v_lshl_add_u64 v[120:121], v[120:121], 0, v[182:183]
	global_store_dwordx4 v[120:121], v[110:113], off sc1
	global_store_dwordx4 v[120:121], v[106:109], off offset:16 sc1

.LBB0_3198:
	s_andn2_b64 vcc, exec, s[56:57]
	v_lshlrev_b64 v[120:121], 12, v[130:131]
	s_cbranch_vccnz .LBB0_3205
	v_pk_mul_f32 v[130:131], v[108:109], v[122:123]
	v_pk_mul_f32 v[134:135], v[106:107], v[124:125]
	v_pk_mul_f32 v[136:137], v[108:109], v[114:115]
	v_pk_mul_f32 v[138:139], v[106:107], v[118:119]
	v_pk_fma_f32 v[130:131], v[112:113], v[114:115], v[130:131] neg_lo:[0,0,1] neg_hi:[0,0,1]
	v_pk_fma_f32 v[134:135], v[110:111], v[118:119], v[134:135] neg_lo:[0,0,1] neg_hi:[0,0,1]
	v_pk_fma_f32 v[136:137], v[112:113], v[122:123], v[136:137]
	v_pk_fma_f32 v[138:139], v[110:111], v[124:125], v[138:139]
	v_cndmask_b32_e64 v109, v109, v137, s[4:5]
	v_cndmask_b32_e64 v108, v108, v136, s[4:5]
	v_cndmask_b32_e64 v107, v107, v139, s[4:5]
	v_cndmask_b32_e64 v106, v106, v138, s[4:5]
	v_cndmask_b32_e64 v113, v113, v131, s[4:5]
	v_cndmask_b32_e64 v112, v112, v130, s[4:5]
	v_cndmask_b32_e64 v111, v111, v135, s[4:5]
	v_cndmask_b32_e64 v110, v110, v134, s[4:5]
	s_and_b64 vcc, exec, s[6:7]
	s_mov_b64 s[56:57], -1
	s_cbranch_vccnz .LBB0_3203
	v_lshl_add_u64 v[130:131], s[26:27], 0, v[116:117]
	s_lshl_b32 s20, s94, 8
	v_lshl_add_u64 v[130:131], v[130:131], 0, s[20:21]
	v_lshl_add_u64 v[130:131], v[130:131], 0, v[162:163]
	s_andn2_b64 vcc, exec, s[54:55]
	v_cvt_pk_bf16_f32 v134, v110, v111
	v_cvt_pk_bf16_f32 v135, v112, v113
	v_cvt_pk_bf16_f32 v136, v106, v107
	v_cvt_pk_bf16_f32 v137, v108, v109
	global_store_dwordx4 v[130:131], v[134:137], off sc1
	s_cbranch_vccnz .LBB0_3202
	s_lshl_b32 s56, s67, 1
	s_or_b32 s56, s56, 1
	s_ashr_i32 s57, s56, 31
	s_lshl_b32 s20, s94, 7
	s_lshl_b64 s[56:57], s[56:57], 19
	s_add_u32 s56, s30, s56
	s_addc_u32 s57, s31, s57
	v_lshlrev_b32_e32 v130, 2, v132
	v_mov_b32_e32 v131, v163
	v_lshl_add_u64 v[130:131], s[56:57], 0, v[130:131]
	v_lshl_add_u64 v[130:131], s[20:21], 2, v[130:131]
	v_lshlrev_b32_e32 v134, 2, v166
	v_mov_b32_e32 v135, v163
	v_lshl_add_u64 v[130:131], v[130:131], 0, v[134:135]
	global_store_dwordx4 v[130:131], v[110:113], off sc1
	global_store_dwordx4 v[130:131], v[106:109], off offset:128 sc1

.LBB0_3203:
	s_andn2_b64 vcc, exec, s[56:57]
	s_cbranch_vccnz .LBB0_3205
	v_cvt_pk_bf16_f32 v110, v110, v111
	v_cvt_pk_bf16_f32 v111, v112, v113
	v_cvt_pk_bf16_f32 v112, v106, v107
	v_lshl_add_u64 v[106:107], s[24:25], 0, v[120:121]
	v_lshl_add_u64 v[106:107], s[50:51], 1, v[106:107]
	v_lshl_add_u64 v[106:107], v[106:107], 0, v[162:163]
	v_cvt_pk_bf16_f32 v113, v108, v109
	global_store_dwordx4 v[106:107], v[110:113], off sc1
.LBB0_3205:
	v_mov_b32_e32 v127, v126
	v_mov_b32_e32 v106, v126
	v_mov_b32_e32 v107, v126
	v_pk_fma_f32 v[104:105], v[104:105], v[106:107], v[40:41]
	v_pk_fma_f32 v[102:103], v[102:103], v[126:127], v[38:39]
	v_pk_fma_f32 v[100:101], v[100:101], v[106:107], v[36:37]
	v_pk_fma_f32 v[98:99], v[98:99], v[126:127], v[34:35]
	s_and_b64 vcc, exec, s[10:11]
	s_mov_b64 s[56:57], -1
	s_cbranch_vccnz .LBB0_3209
	s_add_i32 s20, s50, 0xfffff680
	v_lshl_add_u64 v[110:111], s[20:21], 1, v[128:129]
	v_lshl_add_u64 v[110:111], v[110:111], 0, v[162:163]
	s_andn2_b64 vcc, exec, s[54:55]
	v_cvt_pk_bf16_f32 v106, v102, v103
	v_cvt_pk_bf16_f32 v107, v104, v105
	v_cvt_pk_bf16_f32 v108, v98, v99
	v_cvt_pk_bf16_f32 v109, v100, v101
	global_store_dwordx4 v[110:111], v[106:109], off sc1
	s_cbranch_vccnz .LBB0_3208
	s_lshl_b32 s56, s67, 1
	s_or_b32 s56, s56, 1
	s_ashr_i32 s57, s56, 31
	s_lshl_b64 s[56:57], s[56:57], 19
	s_add_u32 s56, s34, s56
	s_addc_u32 s57, s35, s57
	v_lshlrev_b32_e32 v106, 2, v132
	v_mov_b32_e32 v107, v163
	v_lshl_add_u64 v[106:107], s[56:57], 0, v[106:107]
	v_lshl_add_u64 v[106:107], s[20:21], 2, v[106:107]
	v_mov_b32_e32 v183, v163
	v_lshl_add_u64 v[106:107], v[106:107], 0, v[182:183]
	global_store_dwordx4 v[106:107], v[102:105], off sc1
	global_store_dwordx4 v[106:107], v[98:101], off offset:16 sc1

.LBB0_3209:
	s_andn2_b64 vcc, exec, s[56:57]
	s_cbranch_vccnz .LBB0_3216
	v_pk_mul_f32 v[106:107], v[100:101], v[122:123]
	v_pk_mul_f32 v[108:109], v[98:99], v[124:125]
	v_pk_mul_f32 v[110:111], v[100:101], v[114:115]
	v_pk_mul_f32 v[112:113], v[98:99], v[118:119]
	v_pk_fma_f32 v[106:107], v[104:105], v[114:115], v[106:107] neg_lo:[0,0,1] neg_hi:[0,0,1]
	v_pk_fma_f32 v[108:109], v[102:103], v[118:119], v[108:109] neg_lo:[0,0,1] neg_hi:[0,0,1]
	v_pk_fma_f32 v[110:111], v[104:105], v[122:123], v[110:111]
	v_pk_fma_f32 v[112:113], v[102:103], v[124:125], v[112:113]
	v_cndmask_b32_e64 v101, v101, v111, s[4:5]
	v_cndmask_b32_e64 v100, v100, v110, s[4:5]
	v_cndmask_b32_e64 v99, v99, v113, s[4:5]
	v_cndmask_b32_e64 v98, v98, v112, s[4:5]
	v_cndmask_b32_e64 v105, v105, v107, s[4:5]
	v_cndmask_b32_e64 v104, v104, v106, s[4:5]
	v_cndmask_b32_e64 v103, v103, v109, s[4:5]
	v_cndmask_b32_e64 v102, v102, v108, s[4:5]
	s_and_b64 vcc, exec, s[6:7]
	s_mov_b64 s[56:57], -1
	s_cbranch_vccnz .LBB0_3214
	v_lshl_add_u64 v[110:111], s[26:27], 0, v[116:117]
	s_add_i32 s20, s50, 0xfffff880
	v_lshl_add_u64 v[110:111], s[20:21], 1, v[110:111]
	v_lshl_add_u64 v[110:111], v[110:111], 0, v[162:163]
	s_andn2_b64 vcc, exec, s[54:55]
	v_cvt_pk_bf16_f32 v106, v102, v103
	v_cvt_pk_bf16_f32 v107, v104, v105
	v_cvt_pk_bf16_f32 v108, v98, v99
	v_cvt_pk_bf16_f32 v109, v100, v101
	global_store_dwordx4 v[110:111], v[106:109], off sc1
	s_cbranch_vccnz .LBB0_3213
	s_lshl_b32 s56, s67, 1
	s_or_b32 s56, s56, 1
	s_ashr_i32 s57, s56, 31
	s_lshl_b64 s[56:57], s[56:57], 19
	s_add_u32 s56, s30, s56
	s_addc_u32 s57, s31, s57
	v_lshlrev_b32_e32 v106, 2, v132
	v_mov_b32_e32 v107, v163
	v_lshl_add_u64 v[106:107], s[56:57], 0, v[106:107]
	v_lshl_add_u64 v[106:107], s[20:21], 2, v[106:107]
	v_lshlrev_b32_e32 v108, 2, v166
	v_mov_b32_e32 v109, v163
	v_lshl_add_u64 v[106:107], v[106:107], 0, v[108:109]
	global_store_dwordx4 v[106:107], v[102:105], off sc1
	global_store_dwordx4 v[106:107], v[98:101], off offset:128 sc1

.LBB0_3214:
	s_andn2_b64 vcc, exec, s[56:57]
	s_cbranch_vccnz .LBB0_3216
	v_cvt_pk_bf16_f32 v102, v102, v103
	v_cvt_pk_bf16_f32 v103, v104, v105
	v_cvt_pk_bf16_f32 v104, v98, v99
	v_lshl_add_u64 v[98:99], s[24:25], 0, v[120:121]
	v_lshl_add_u64 v[98:99], s[50:51], 1, v[98:99]
	v_lshl_add_u64 v[98:99], v[98:99], 0, v[162:163]
	v_cvt_pk_bf16_f32 v105, v100, v101
	global_store_dwordx4 v[98:99], v[102:105], off offset:256 sc1

.LBB0_3223:
	v_lshlrev_b64 v[100:101], 10, v[114:115]
	v_lshlrev_b32_e32 v104, 9, v114
	v_and_b32_e32 v116, 0x1fe00, v104
	s_waitcnt lgkmcnt(0)
	v_pk_fma_f32 v[96:97], v[96:97], v[110:111], v[56:57] op_sel_hi:[1,0,1]
	v_pk_fma_f32 v[94:95], v[94:95], v[110:111], v[54:55] op_sel_hi:[1,0,1]
	v_pk_fma_f32 v[92:93], v[92:93], v[110:111], v[52:53] op_sel_hi:[1,0,1]
	v_pk_fma_f32 v[90:91], v[90:91], v[110:111], v[50:51] op_sel_hi:[1,0,1]
	s_mov_b64 s[56:57], -1
	s_and_b64 vcc, exec, s[10:11]
	v_lshl_add_u64 v[112:113], s[28:29], 0, v[100:101]
	s_cbranch_vccnz .LBB0_3227
	s_lshl_b32 s20, s95, 7
	v_lshl_add_u64 v[104:105], s[20:21], 1, v[112:113]
	v_lshl_add_u64 v[104:105], v[104:105], 0, v[162:163]
	s_andn2_b64 vcc, exec, s[54:55]
	v_cvt_pk_bf16_f32 v118, v94, v95
	v_cvt_pk_bf16_f32 v119, v96, v97
	v_cvt_pk_bf16_f32 v120, v90, v91
	v_cvt_pk_bf16_f32 v121, v92, v93
	global_store_dwordx4 v[104:105], v[118:121], off sc1
	s_cbranch_vccnz .LBB0_3226
	s_lshl_b32 s56, s67, 1
	s_or_b32 s56, s56, 1
	s_ashr_i32 s57, s56, 31
	s_lshl_b64 s[56:57], s[56:57], 19
	s_add_u32 s56, s34, s56
	s_addc_u32 s57, s35, s57
	v_lshlrev_b32_e32 v104, 2, v116
	v_mov_b32_e32 v105, v163
	v_lshl_add_u64 v[104:105], s[56:57], 0, v[104:105]
	v_lshl_add_u64 v[104:105], s[20:21], 2, v[104:105]
	v_mov_b32_e32 v183, v163
	v_lshl_add_u64 v[104:105], v[104:105], 0, v[182:183]
	global_store_dwordx4 v[104:105], v[94:97], off sc1
	global_store_dwordx4 v[104:105], v[90:93], off offset:16 sc1

.LBB0_3227:
	s_andn2_b64 vcc, exec, s[56:57]
	v_lshlrev_b64 v[104:105], 12, v[114:115]
	s_cbranch_vccnz .LBB0_3234
	v_pk_mul_f32 v[114:115], v[92:93], v[106:107]
	v_pk_mul_f32 v[118:119], v[90:91], v[108:109]
	v_pk_mul_f32 v[120:121], v[92:93], v[98:99]
	v_pk_mul_f32 v[122:123], v[90:91], v[102:103]
	v_pk_fma_f32 v[114:115], v[96:97], v[98:99], v[114:115] neg_lo:[0,0,1] neg_hi:[0,0,1]
	v_pk_fma_f32 v[118:119], v[94:95], v[102:103], v[118:119] neg_lo:[0,0,1] neg_hi:[0,0,1]
	v_pk_fma_f32 v[120:121], v[96:97], v[106:107], v[120:121]
	v_pk_fma_f32 v[122:123], v[94:95], v[108:109], v[122:123]
	v_cndmask_b32_e64 v93, v93, v121, s[4:5]
	v_cndmask_b32_e64 v92, v92, v120, s[4:5]
	v_cndmask_b32_e64 v91, v91, v123, s[4:5]
	v_cndmask_b32_e64 v90, v90, v122, s[4:5]
	v_cndmask_b32_e64 v97, v97, v115, s[4:5]
	v_cndmask_b32_e64 v96, v96, v114, s[4:5]
	v_cndmask_b32_e64 v95, v95, v119, s[4:5]
	v_cndmask_b32_e64 v94, v94, v118, s[4:5]
	s_and_b64 vcc, exec, s[6:7]
	s_mov_b64 s[56:57], -1
	s_cbranch_vccnz .LBB0_3232
	v_lshl_add_u64 v[114:115], s[26:27], 0, v[100:101]
	s_lshl_b32 s20, s94, 8
	v_lshl_add_u64 v[114:115], v[114:115], 0, s[20:21]
	v_lshl_add_u64 v[114:115], v[114:115], 0, v[162:163]
	s_andn2_b64 vcc, exec, s[54:55]
	v_cvt_pk_bf16_f32 v118, v94, v95
	v_cvt_pk_bf16_f32 v119, v96, v97
	v_cvt_pk_bf16_f32 v120, v90, v91
	v_cvt_pk_bf16_f32 v121, v92, v93
	global_store_dwordx4 v[114:115], v[118:121], off sc1
	s_cbranch_vccnz .LBB0_3231
	s_lshl_b32 s56, s67, 1
	s_or_b32 s56, s56, 1
	s_ashr_i32 s57, s56, 31
	s_lshl_b32 s20, s94, 7
	s_lshl_b64 s[56:57], s[56:57], 19
	s_add_u32 s56, s30, s56
	s_addc_u32 s57, s31, s57
	v_lshlrev_b32_e32 v114, 2, v116
	v_mov_b32_e32 v115, v163
	v_lshl_add_u64 v[114:115], s[56:57], 0, v[114:115]
	v_lshl_add_u64 v[114:115], s[20:21], 2, v[114:115]
	v_lshlrev_b32_e32 v118, 2, v166
	v_mov_b32_e32 v119, v163
	v_lshl_add_u64 v[114:115], v[114:115], 0, v[118:119]
	global_store_dwordx4 v[114:115], v[94:97], off sc1
	global_store_dwordx4 v[114:115], v[90:93], off offset:128 sc1

.LBB0_3232:
	s_andn2_b64 vcc, exec, s[56:57]
	s_cbranch_vccnz .LBB0_3234
	v_cvt_pk_bf16_f32 v94, v94, v95
	v_cvt_pk_bf16_f32 v95, v96, v97
	v_cvt_pk_bf16_f32 v96, v90, v91
	v_lshl_add_u64 v[90:91], s[24:25], 0, v[104:105]
	v_lshl_add_u64 v[90:91], s[50:51], 1, v[90:91]
	v_lshl_add_u64 v[90:91], v[90:91], 0, v[162:163]
	v_cvt_pk_bf16_f32 v97, v92, v93
	global_store_dwordx4 v[90:91], v[94:97], off sc1
.LBB0_3234:
	v_mov_b32_e32 v111, v110
	v_mov_b32_e32 v90, v110
	v_mov_b32_e32 v91, v110
	v_pk_fma_f32 v[88:89], v[88:89], v[90:91], v[40:41]
	v_pk_fma_f32 v[86:87], v[86:87], v[110:111], v[38:39]
	v_pk_fma_f32 v[84:85], v[84:85], v[90:91], v[36:37]
	v_pk_fma_f32 v[82:83], v[82:83], v[110:111], v[34:35]
	s_and_b64 vcc, exec, s[10:11]
	s_mov_b64 s[56:57], -1
	s_cbranch_vccnz .LBB0_3238
	s_add_i32 s20, s50, 0xfffff680
	v_lshl_add_u64 v[94:95], s[20:21], 1, v[112:113]
	v_lshl_add_u64 v[94:95], v[94:95], 0, v[162:163]
	s_andn2_b64 vcc, exec, s[54:55]
	v_cvt_pk_bf16_f32 v90, v86, v87
	v_cvt_pk_bf16_f32 v91, v88, v89
	v_cvt_pk_bf16_f32 v92, v82, v83
	v_cvt_pk_bf16_f32 v93, v84, v85
	global_store_dwordx4 v[94:95], v[90:93], off sc1
	s_cbranch_vccnz .LBB0_3237
	s_lshl_b32 s56, s67, 1
	s_or_b32 s56, s56, 1
	s_ashr_i32 s57, s56, 31
	s_lshl_b64 s[56:57], s[56:57], 19
	s_add_u32 s56, s34, s56
	s_addc_u32 s57, s35, s57
	v_lshlrev_b32_e32 v90, 2, v116
	v_mov_b32_e32 v91, v163
	v_lshl_add_u64 v[90:91], s[56:57], 0, v[90:91]
	v_lshl_add_u64 v[90:91], s[20:21], 2, v[90:91]
	v_mov_b32_e32 v183, v163
	v_lshl_add_u64 v[90:91], v[90:91], 0, v[182:183]
	global_store_dwordx4 v[90:91], v[86:89], off sc1
	global_store_dwordx4 v[90:91], v[82:85], off offset:16 sc1

.LBB0_3238:
	s_andn2_b64 vcc, exec, s[56:57]
	s_cbranch_vccnz .LBB0_3245
	v_pk_mul_f32 v[90:91], v[84:85], v[106:107]
	v_pk_mul_f32 v[92:93], v[82:83], v[108:109]
	v_pk_mul_f32 v[94:95], v[84:85], v[98:99]
	v_pk_mul_f32 v[96:97], v[82:83], v[102:103]
	v_pk_fma_f32 v[90:91], v[88:89], v[98:99], v[90:91] neg_lo:[0,0,1] neg_hi:[0,0,1]
	v_pk_fma_f32 v[92:93], v[86:87], v[102:103], v[92:93] neg_lo:[0,0,1] neg_hi:[0,0,1]
	v_pk_fma_f32 v[94:95], v[88:89], v[106:107], v[94:95]
	v_pk_fma_f32 v[96:97], v[86:87], v[108:109], v[96:97]
	v_cndmask_b32_e64 v85, v85, v95, s[4:5]
	v_cndmask_b32_e64 v84, v84, v94, s[4:5]
	v_cndmask_b32_e64 v83, v83, v97, s[4:5]
	v_cndmask_b32_e64 v82, v82, v96, s[4:5]
	v_cndmask_b32_e64 v89, v89, v91, s[4:5]
	v_cndmask_b32_e64 v88, v88, v90, s[4:5]
	v_cndmask_b32_e64 v87, v87, v93, s[4:5]
	v_cndmask_b32_e64 v86, v86, v92, s[4:5]
	s_and_b64 vcc, exec, s[6:7]
	s_mov_b64 s[56:57], -1
	s_cbranch_vccnz .LBB0_3243
	v_lshl_add_u64 v[94:95], s[26:27], 0, v[100:101]
	s_add_i32 s20, s50, 0xfffff880
	v_lshl_add_u64 v[94:95], s[20:21], 1, v[94:95]
	v_lshl_add_u64 v[94:95], v[94:95], 0, v[162:163]
	s_andn2_b64 vcc, exec, s[54:55]
	v_cvt_pk_bf16_f32 v90, v86, v87
	v_cvt_pk_bf16_f32 v91, v88, v89
	v_cvt_pk_bf16_f32 v92, v82, v83
	v_cvt_pk_bf16_f32 v93, v84, v85
	global_store_dwordx4 v[94:95], v[90:93], off sc1
	s_cbranch_vccnz .LBB0_3242
	s_lshl_b32 s56, s67, 1
	s_or_b32 s56, s56, 1
	s_ashr_i32 s57, s56, 31
	s_lshl_b64 s[56:57], s[56:57], 19
	s_add_u32 s56, s30, s56
	s_addc_u32 s57, s31, s57
	v_lshlrev_b32_e32 v90, 2, v116
	v_mov_b32_e32 v91, v163
	v_lshl_add_u64 v[90:91], s[56:57], 0, v[90:91]
	v_lshl_add_u64 v[90:91], s[20:21], 2, v[90:91]
	v_lshlrev_b32_e32 v92, 2, v166
	v_mov_b32_e32 v93, v163
	v_lshl_add_u64 v[90:91], v[90:91], 0, v[92:93]
	global_store_dwordx4 v[90:91], v[86:89], off sc1
	global_store_dwordx4 v[90:91], v[82:85], off offset:128 sc1

.LBB0_3243:
	s_andn2_b64 vcc, exec, s[56:57]
	s_cbranch_vccnz .LBB0_3245
	v_cvt_pk_bf16_f32 v86, v86, v87
	v_cvt_pk_bf16_f32 v87, v88, v89
	v_cvt_pk_bf16_f32 v88, v82, v83
	v_lshl_add_u64 v[82:83], s[24:25], 0, v[104:105]
	v_lshl_add_u64 v[82:83], s[50:51], 1, v[82:83]
	v_lshl_add_u64 v[82:83], v[82:83], 0, v[162:163]
	v_cvt_pk_bf16_f32 v89, v84, v85
	global_store_dwordx4 v[82:83], v[86:89], off offset:256 sc1

.LBB0_3252:
	v_lshlrev_b64 v[84:85], 10, v[98:99]
	v_lshlrev_b32_e32 v88, 9, v98
	v_and_b32_e32 v101, 0x19e00, v88
	s_waitcnt lgkmcnt(0)
	v_pk_fma_f32 v[80:81], v[80:81], v[94:95], v[56:57] op_sel_hi:[1,0,1]
	v_pk_fma_f32 v[78:79], v[78:79], v[94:95], v[54:55] op_sel_hi:[1,0,1]
	v_pk_fma_f32 v[76:77], v[76:77], v[94:95], v[52:53] op_sel_hi:[1,0,1]
	v_pk_fma_f32 v[74:75], v[74:75], v[94:95], v[50:51] op_sel_hi:[1,0,1]
	s_mov_b64 s[56:57], -1
	s_and_b64 vcc, exec, s[10:11]
	v_lshl_add_u64 v[96:97], s[28:29], 0, v[84:85]
	s_cbranch_vccnz .LBB0_3256
	s_lshl_b32 s20, s95, 7
	v_lshl_add_u64 v[88:89], s[20:21], 1, v[96:97]
	v_lshl_add_u64 v[88:89], v[88:89], 0, v[162:163]
	s_andn2_b64 vcc, exec, s[54:55]
	v_cvt_pk_bf16_f32 v102, v78, v79
	v_cvt_pk_bf16_f32 v103, v80, v81
	v_cvt_pk_bf16_f32 v104, v74, v75
	v_cvt_pk_bf16_f32 v105, v76, v77
	global_store_dwordx4 v[88:89], v[102:105], off sc1
	s_cbranch_vccnz .LBB0_3255
	s_lshl_b32 s56, s67, 1
	s_or_b32 s56, s56, 1
	s_ashr_i32 s57, s56, 31
	s_lshl_b64 s[56:57], s[56:57], 19
	s_add_u32 s56, s34, s56
	s_addc_u32 s57, s35, s57
	v_lshlrev_b32_e32 v88, 2, v101
	v_mov_b32_e32 v89, v163
	v_lshl_add_u64 v[88:89], s[56:57], 0, v[88:89]
	v_lshl_add_u64 v[88:89], s[20:21], 2, v[88:89]
	v_mov_b32_e32 v183, v163
	v_lshl_add_u64 v[88:89], v[88:89], 0, v[182:183]
	global_store_dwordx4 v[88:89], v[78:81], off sc1
	global_store_dwordx4 v[88:89], v[74:77], off offset:16 sc1

.LBB0_3256:
	s_andn2_b64 vcc, exec, s[56:57]
	v_lshlrev_b64 v[88:89], 12, v[98:99]
	s_cbranch_vccnz .LBB0_3263
	v_pk_mul_f32 v[98:99], v[76:77], v[90:91]
	v_pk_mul_f32 v[102:103], v[74:75], v[92:93]
	v_pk_mul_f32 v[104:105], v[76:77], v[82:83]
	v_pk_mul_f32 v[106:107], v[74:75], v[86:87]
	v_pk_fma_f32 v[98:99], v[80:81], v[82:83], v[98:99] neg_lo:[0,0,1] neg_hi:[0,0,1]
	v_pk_fma_f32 v[102:103], v[78:79], v[86:87], v[102:103] neg_lo:[0,0,1] neg_hi:[0,0,1]
	v_pk_fma_f32 v[104:105], v[80:81], v[90:91], v[104:105]
	v_pk_fma_f32 v[106:107], v[78:79], v[92:93], v[106:107]
	v_cndmask_b32_e64 v77, v77, v105, s[4:5]
	v_cndmask_b32_e64 v76, v76, v104, s[4:5]
	v_cndmask_b32_e64 v75, v75, v107, s[4:5]
	v_cndmask_b32_e64 v74, v74, v106, s[4:5]
	v_cndmask_b32_e64 v81, v81, v99, s[4:5]
	v_cndmask_b32_e64 v80, v80, v98, s[4:5]
	v_cndmask_b32_e64 v79, v79, v103, s[4:5]
	v_cndmask_b32_e64 v78, v78, v102, s[4:5]
	s_and_b64 vcc, exec, s[6:7]
	s_mov_b64 s[56:57], -1
	s_cbranch_vccnz .LBB0_3261
	v_lshl_add_u64 v[98:99], s[26:27], 0, v[84:85]
	s_lshl_b32 s20, s94, 8
	v_lshl_add_u64 v[98:99], v[98:99], 0, s[20:21]
	v_lshl_add_u64 v[98:99], v[98:99], 0, v[162:163]
	s_andn2_b64 vcc, exec, s[54:55]
	v_cvt_pk_bf16_f32 v102, v78, v79
	v_cvt_pk_bf16_f32 v103, v80, v81
	v_cvt_pk_bf16_f32 v104, v74, v75
	v_cvt_pk_bf16_f32 v105, v76, v77
	global_store_dwordx4 v[98:99], v[102:105], off sc1
	s_cbranch_vccnz .LBB0_3260
	s_lshl_b32 s56, s67, 1
	s_or_b32 s56, s56, 1
	s_ashr_i32 s57, s56, 31
	s_lshl_b32 s20, s94, 7
	s_lshl_b64 s[56:57], s[56:57], 19
	s_add_u32 s56, s30, s56
	s_addc_u32 s57, s31, s57
	v_lshlrev_b32_e32 v98, 2, v101
	v_mov_b32_e32 v99, v163
	v_lshl_add_u64 v[98:99], s[56:57], 0, v[98:99]
	v_lshl_add_u64 v[98:99], s[20:21], 2, v[98:99]
	v_lshlrev_b32_e32 v102, 2, v166
	v_mov_b32_e32 v103, v163
	v_lshl_add_u64 v[98:99], v[98:99], 0, v[102:103]
	global_store_dwordx4 v[98:99], v[78:81], off sc1
	global_store_dwordx4 v[98:99], v[74:77], off offset:128 sc1

.LBB0_3261:
	s_andn2_b64 vcc, exec, s[56:57]
	s_cbranch_vccnz .LBB0_3263
	v_cvt_pk_bf16_f32 v78, v78, v79
	v_cvt_pk_bf16_f32 v79, v80, v81
	v_cvt_pk_bf16_f32 v80, v74, v75
	v_lshl_add_u64 v[74:75], s[24:25], 0, v[88:89]
	v_lshl_add_u64 v[74:75], s[50:51], 1, v[74:75]
	v_lshl_add_u64 v[74:75], v[74:75], 0, v[162:163]
	v_cvt_pk_bf16_f32 v81, v76, v77
	global_store_dwordx4 v[74:75], v[78:81], off sc1
.LBB0_3263:
	v_mov_b32_e32 v95, v94
	v_mov_b32_e32 v74, v94
	v_mov_b32_e32 v75, v94
	v_pk_fma_f32 v[72:73], v[72:73], v[74:75], v[40:41]
	v_pk_fma_f32 v[70:71], v[70:71], v[94:95], v[38:39]
	v_pk_fma_f32 v[68:69], v[68:69], v[74:75], v[36:37]
	v_pk_fma_f32 v[66:67], v[66:67], v[94:95], v[34:35]
	s_and_b64 vcc, exec, s[10:11]
	s_mov_b64 s[56:57], -1
	s_cbranch_vccnz .LBB0_3267
	s_add_i32 s20, s50, 0xfffff680
	v_lshl_add_u64 v[78:79], s[20:21], 1, v[96:97]
	v_lshl_add_u64 v[78:79], v[78:79], 0, v[162:163]
	s_andn2_b64 vcc, exec, s[54:55]
	v_cvt_pk_bf16_f32 v74, v70, v71
	v_cvt_pk_bf16_f32 v75, v72, v73
	v_cvt_pk_bf16_f32 v76, v66, v67
	v_cvt_pk_bf16_f32 v77, v68, v69
	global_store_dwordx4 v[78:79], v[74:77], off sc1
	s_cbranch_vccnz .LBB0_3266
	s_lshl_b32 s56, s67, 1
	s_or_b32 s56, s56, 1
	s_ashr_i32 s57, s56, 31
	s_lshl_b64 s[56:57], s[56:57], 19
	s_add_u32 s56, s34, s56
	s_addc_u32 s57, s35, s57
	v_lshlrev_b32_e32 v74, 2, v101
	v_mov_b32_e32 v75, v163
	v_lshl_add_u64 v[74:75], s[56:57], 0, v[74:75]
	v_lshl_add_u64 v[74:75], s[20:21], 2, v[74:75]
	v_mov_b32_e32 v183, v163
	v_lshl_add_u64 v[74:75], v[74:75], 0, v[182:183]
	global_store_dwordx4 v[74:75], v[70:73], off sc1
	global_store_dwordx4 v[74:75], v[66:69], off offset:16 sc1

.LBB0_3267:
	s_andn2_b64 vcc, exec, s[56:57]
	s_cbranch_vccnz .LBB0_3274
	v_pk_mul_f32 v[74:75], v[68:69], v[90:91]
	v_pk_mul_f32 v[76:77], v[66:67], v[92:93]
	v_pk_mul_f32 v[78:79], v[68:69], v[82:83]
	v_pk_mul_f32 v[80:81], v[66:67], v[86:87]
	v_pk_fma_f32 v[74:75], v[72:73], v[82:83], v[74:75] neg_lo:[0,0,1] neg_hi:[0,0,1]
	v_pk_fma_f32 v[76:77], v[70:71], v[86:87], v[76:77] neg_lo:[0,0,1] neg_hi:[0,0,1]
	v_pk_fma_f32 v[78:79], v[72:73], v[90:91], v[78:79]
	v_pk_fma_f32 v[80:81], v[70:71], v[92:93], v[80:81]
	v_cndmask_b32_e64 v69, v69, v79, s[4:5]
	v_cndmask_b32_e64 v68, v68, v78, s[4:5]
	v_cndmask_b32_e64 v67, v67, v81, s[4:5]
	v_cndmask_b32_e64 v66, v66, v80, s[4:5]
	v_cndmask_b32_e64 v73, v73, v75, s[4:5]
	v_cndmask_b32_e64 v72, v72, v74, s[4:5]
	v_cndmask_b32_e64 v71, v71, v77, s[4:5]
	v_cndmask_b32_e64 v70, v70, v76, s[4:5]
	s_and_b64 vcc, exec, s[6:7]
	s_mov_b64 s[56:57], -1
	s_cbranch_vccnz .LBB0_3272
	v_lshl_add_u64 v[78:79], s[26:27], 0, v[84:85]
	s_add_i32 s20, s50, 0xfffff880
	v_lshl_add_u64 v[78:79], s[20:21], 1, v[78:79]
	v_lshl_add_u64 v[78:79], v[78:79], 0, v[162:163]
	s_andn2_b64 vcc, exec, s[54:55]
	v_cvt_pk_bf16_f32 v74, v70, v71
	v_cvt_pk_bf16_f32 v75, v72, v73
	v_cvt_pk_bf16_f32 v76, v66, v67
	v_cvt_pk_bf16_f32 v77, v68, v69
	global_store_dwordx4 v[78:79], v[74:77], off sc1
	s_cbranch_vccnz .LBB0_3271
	s_lshl_b32 s56, s67, 1
	s_or_b32 s56, s56, 1
	s_ashr_i32 s57, s56, 31
	s_lshl_b64 s[56:57], s[56:57], 19
	s_add_u32 s56, s30, s56
	s_addc_u32 s57, s31, s57
	v_lshlrev_b32_e32 v74, 2, v101
	v_mov_b32_e32 v75, v163
	v_lshl_add_u64 v[74:75], s[56:57], 0, v[74:75]
	v_lshl_add_u64 v[74:75], s[20:21], 2, v[74:75]
	v_lshlrev_b32_e32 v76, 2, v166
	v_mov_b32_e32 v77, v163
	v_lshl_add_u64 v[74:75], v[74:75], 0, v[76:77]
	global_store_dwordx4 v[74:75], v[70:73], off sc1
	global_store_dwordx4 v[74:75], v[66:69], off offset:128 sc1

.LBB0_3272:
	s_andn2_b64 vcc, exec, s[56:57]
	s_cbranch_vccnz .LBB0_3274
	v_cvt_pk_bf16_f32 v70, v70, v71
	v_cvt_pk_bf16_f32 v71, v72, v73
	v_cvt_pk_bf16_f32 v72, v66, v67
	v_lshl_add_u64 v[66:67], s[24:25], 0, v[88:89]
	v_lshl_add_u64 v[66:67], s[50:51], 1, v[66:67]
	v_lshl_add_u64 v[66:67], v[66:67], 0, v[162:163]
	v_cvt_pk_bf16_f32 v73, v68, v69
	global_store_dwordx4 v[66:67], v[70:73], off offset:256 sc1

.LBB0_3281:
	v_lshlrev_b64 v[68:69], 10, v[82:83]
	v_lshlrev_b32_e32 v72, 9, v82
	v_and_b32_e32 v84, 0x1be00, v72
	s_waitcnt lgkmcnt(0)
	v_pk_fma_f32 v[64:65], v[64:65], v[78:79], v[56:57] op_sel_hi:[1,0,1]
	v_pk_fma_f32 v[62:63], v[62:63], v[78:79], v[54:55] op_sel_hi:[1,0,1]
	v_pk_fma_f32 v[60:61], v[60:61], v[78:79], v[52:53] op_sel_hi:[1,0,1]
	v_pk_fma_f32 v[58:59], v[58:59], v[78:79], v[50:51] op_sel_hi:[1,0,1]
	s_mov_b64 s[56:57], -1
	s_and_b64 vcc, exec, s[10:11]
	v_lshl_add_u64 v[80:81], s[28:29], 0, v[68:69]
	s_cbranch_vccnz .LBB0_3285
	s_lshl_b32 s20, s95, 7
	v_lshl_add_u64 v[72:73], s[20:21], 1, v[80:81]
	v_lshl_add_u64 v[72:73], v[72:73], 0, v[162:163]
	s_andn2_b64 vcc, exec, s[54:55]
	v_cvt_pk_bf16_f32 v86, v62, v63
	v_cvt_pk_bf16_f32 v87, v64, v65
	v_cvt_pk_bf16_f32 v88, v58, v59
	v_cvt_pk_bf16_f32 v89, v60, v61
	global_store_dwordx4 v[72:73], v[86:89], off sc1
	s_cbranch_vccnz .LBB0_3284
	s_lshl_b32 s56, s67, 1
	s_or_b32 s56, s56, 1
	s_ashr_i32 s57, s56, 31
	s_lshl_b64 s[56:57], s[56:57], 19
	s_add_u32 s56, s34, s56
	s_addc_u32 s57, s35, s57
	v_lshlrev_b32_e32 v72, 2, v84
	v_mov_b32_e32 v73, v163
	v_lshl_add_u64 v[72:73], s[56:57], 0, v[72:73]
	v_lshl_add_u64 v[72:73], s[20:21], 2, v[72:73]
	v_mov_b32_e32 v183, v163
	v_lshl_add_u64 v[72:73], v[72:73], 0, v[182:183]
	global_store_dwordx4 v[72:73], v[62:65], off sc1
	global_store_dwordx4 v[72:73], v[58:61], off offset:16 sc1

.LBB0_3285:
	s_andn2_b64 vcc, exec, s[56:57]
	v_lshlrev_b64 v[72:73], 12, v[82:83]
	s_cbranch_vccnz .LBB0_3292
	v_pk_mul_f32 v[82:83], v[60:61], v[74:75]
	v_pk_mul_f32 v[86:87], v[58:59], v[76:77]
	v_pk_mul_f32 v[88:89], v[60:61], v[66:67]
	v_pk_mul_f32 v[90:91], v[58:59], v[70:71]
	v_pk_fma_f32 v[82:83], v[64:65], v[66:67], v[82:83] neg_lo:[0,0,1] neg_hi:[0,0,1]
	v_pk_fma_f32 v[86:87], v[62:63], v[70:71], v[86:87] neg_lo:[0,0,1] neg_hi:[0,0,1]
	v_pk_fma_f32 v[88:89], v[64:65], v[74:75], v[88:89]
	v_pk_fma_f32 v[90:91], v[62:63], v[76:77], v[90:91]
	v_cndmask_b32_e64 v61, v61, v89, s[4:5]
	v_cndmask_b32_e64 v60, v60, v88, s[4:5]
	v_cndmask_b32_e64 v59, v59, v91, s[4:5]
	v_cndmask_b32_e64 v58, v58, v90, s[4:5]
	v_cndmask_b32_e64 v65, v65, v83, s[4:5]
	v_cndmask_b32_e64 v64, v64, v82, s[4:5]
	v_cndmask_b32_e64 v63, v63, v87, s[4:5]
	v_cndmask_b32_e64 v62, v62, v86, s[4:5]
	s_and_b64 vcc, exec, s[6:7]
	s_mov_b64 s[56:57], -1
	s_cbranch_vccnz .LBB0_3290
	v_lshl_add_u64 v[82:83], s[26:27], 0, v[68:69]
	s_lshl_b32 s20, s94, 8
	v_lshl_add_u64 v[82:83], v[82:83], 0, s[20:21]
	v_lshl_add_u64 v[82:83], v[82:83], 0, v[162:163]
	s_andn2_b64 vcc, exec, s[54:55]
	v_cvt_pk_bf16_f32 v86, v62, v63
	v_cvt_pk_bf16_f32 v87, v64, v65
	v_cvt_pk_bf16_f32 v88, v58, v59
	v_cvt_pk_bf16_f32 v89, v60, v61
	global_store_dwordx4 v[82:83], v[86:89], off sc1
	s_cbranch_vccnz .LBB0_3289
	s_lshl_b32 s56, s67, 1
	s_or_b32 s56, s56, 1
	s_ashr_i32 s57, s56, 31
	s_lshl_b32 s20, s94, 7
	s_lshl_b64 s[56:57], s[56:57], 19
	s_add_u32 s56, s30, s56
	s_addc_u32 s57, s31, s57
	v_lshlrev_b32_e32 v82, 2, v84
	v_mov_b32_e32 v83, v163
	v_lshl_add_u64 v[82:83], s[56:57], 0, v[82:83]
	v_lshl_add_u64 v[82:83], s[20:21], 2, v[82:83]
	v_lshlrev_b32_e32 v86, 2, v166
	v_mov_b32_e32 v87, v163
	v_lshl_add_u64 v[82:83], v[82:83], 0, v[86:87]
	global_store_dwordx4 v[82:83], v[62:65], off sc1
	global_store_dwordx4 v[82:83], v[58:61], off offset:128 sc1

.LBB0_3290:
	s_andn2_b64 vcc, exec, s[56:57]
	s_cbranch_vccnz .LBB0_3292
	v_cvt_pk_bf16_f32 v62, v62, v63
	v_cvt_pk_bf16_f32 v63, v64, v65
	v_cvt_pk_bf16_f32 v64, v58, v59
	v_lshl_add_u64 v[58:59], s[24:25], 0, v[72:73]
	v_lshl_add_u64 v[58:59], s[50:51], 1, v[58:59]
	v_lshl_add_u64 v[58:59], v[58:59], 0, v[162:163]
	v_cvt_pk_bf16_f32 v65, v60, v61
	global_store_dwordx4 v[58:59], v[62:65], off sc1
.LBB0_3292:
	v_mov_b32_e32 v79, v78
	v_mov_b32_e32 v58, v78
	v_mov_b32_e32 v59, v78
	v_pk_fma_f32 v[48:49], v[48:49], v[58:59], v[40:41]
	v_pk_fma_f32 v[46:47], v[46:47], v[78:79], v[38:39]
	v_pk_fma_f32 v[44:45], v[44:45], v[58:59], v[36:37]
	v_pk_fma_f32 v[42:43], v[42:43], v[78:79], v[34:35]
	s_and_b64 vcc, exec, s[10:11]
	s_mov_b64 s[56:57], -1
	s_cbranch_vccnz .LBB0_3296
	s_add_i32 s20, s50, 0xfffff680
	v_lshl_add_u64 v[62:63], s[20:21], 1, v[80:81]
	v_lshl_add_u64 v[62:63], v[62:63], 0, v[162:163]
	s_andn2_b64 vcc, exec, s[54:55]
	v_cvt_pk_bf16_f32 v58, v46, v47
	v_cvt_pk_bf16_f32 v59, v48, v49
	v_cvt_pk_bf16_f32 v60, v42, v43
	v_cvt_pk_bf16_f32 v61, v44, v45
	global_store_dwordx4 v[62:63], v[58:61], off sc1
	s_cbranch_vccnz .LBB0_3295
	s_lshl_b32 s56, s67, 1
	s_or_b32 s56, s56, 1
	s_ashr_i32 s57, s56, 31
	s_lshl_b64 s[56:57], s[56:57], 19
	s_add_u32 s56, s34, s56
	s_addc_u32 s57, s35, s57
	v_lshlrev_b32_e32 v58, 2, v84
	v_mov_b32_e32 v59, v163
	v_lshl_add_u64 v[58:59], s[56:57], 0, v[58:59]
	v_lshl_add_u64 v[58:59], s[20:21], 2, v[58:59]
	v_mov_b32_e32 v183, v163
	v_lshl_add_u64 v[58:59], v[58:59], 0, v[182:183]
	global_store_dwordx4 v[58:59], v[46:49], off sc1
	global_store_dwordx4 v[58:59], v[42:45], off offset:16 sc1

.LBB0_3296:
	s_andn2_b64 vcc, exec, s[56:57]
	s_cbranch_vccnz .LBB0_3303
	v_pk_mul_f32 v[58:59], v[44:45], v[74:75]
	v_pk_mul_f32 v[60:61], v[42:43], v[76:77]
	v_pk_mul_f32 v[62:63], v[44:45], v[66:67]
	v_pk_mul_f32 v[64:65], v[42:43], v[70:71]
	v_pk_fma_f32 v[58:59], v[48:49], v[66:67], v[58:59] neg_lo:[0,0,1] neg_hi:[0,0,1]
	v_pk_fma_f32 v[60:61], v[46:47], v[70:71], v[60:61] neg_lo:[0,0,1] neg_hi:[0,0,1]
	v_pk_fma_f32 v[62:63], v[48:49], v[74:75], v[62:63]
	v_pk_fma_f32 v[64:65], v[46:47], v[76:77], v[64:65]
	v_cndmask_b32_e64 v45, v45, v63, s[4:5]
	v_cndmask_b32_e64 v44, v44, v62, s[4:5]
	v_cndmask_b32_e64 v43, v43, v65, s[4:5]
	v_cndmask_b32_e64 v42, v42, v64, s[4:5]
	v_cndmask_b32_e64 v49, v49, v59, s[4:5]
	v_cndmask_b32_e64 v48, v48, v58, s[4:5]
	v_cndmask_b32_e64 v47, v47, v61, s[4:5]
	v_cndmask_b32_e64 v46, v46, v60, s[4:5]
	s_and_b64 vcc, exec, s[6:7]
	s_mov_b64 s[56:57], -1
	s_cbranch_vccnz .LBB0_3301
	v_lshl_add_u64 v[62:63], s[26:27], 0, v[68:69]
	s_add_i32 s20, s50, 0xfffff880
	v_lshl_add_u64 v[62:63], s[20:21], 1, v[62:63]
	v_lshl_add_u64 v[62:63], v[62:63], 0, v[162:163]
	s_andn2_b64 vcc, exec, s[54:55]
	v_cvt_pk_bf16_f32 v58, v46, v47
	v_cvt_pk_bf16_f32 v59, v48, v49
	v_cvt_pk_bf16_f32 v60, v42, v43
	v_cvt_pk_bf16_f32 v61, v44, v45
	global_store_dwordx4 v[62:63], v[58:61], off sc1
	s_cbranch_vccnz .LBB0_3300
	s_lshl_b32 s56, s67, 1
	s_or_b32 s56, s56, 1
	s_ashr_i32 s57, s56, 31
	s_lshl_b64 s[56:57], s[56:57], 19
	s_add_u32 s56, s30, s56
	s_addc_u32 s57, s31, s57
	v_lshlrev_b32_e32 v58, 2, v84
	v_mov_b32_e32 v59, v163
	v_lshl_add_u64 v[58:59], s[56:57], 0, v[58:59]
	v_lshl_add_u64 v[58:59], s[20:21], 2, v[58:59]
	v_lshlrev_b32_e32 v60, 2, v166
	v_mov_b32_e32 v61, v163
	v_lshl_add_u64 v[58:59], v[58:59], 0, v[60:61]
	global_store_dwordx4 v[58:59], v[46:49], off sc1
	global_store_dwordx4 v[58:59], v[42:45], off offset:128 sc1

.LBB0_3301:
	s_andn2_b64 vcc, exec, s[56:57]
	s_cbranch_vccnz .LBB0_3303
	v_cvt_pk_bf16_f32 v46, v46, v47
	v_cvt_pk_bf16_f32 v47, v48, v49
	v_cvt_pk_bf16_f32 v48, v42, v43
	v_lshl_add_u64 v[42:43], s[24:25], 0, v[72:73]
	v_lshl_add_u64 v[42:43], s[50:51], 1, v[42:43]
	v_lshl_add_u64 v[42:43], v[42:43], 0, v[162:163]
	v_cvt_pk_bf16_f32 v49, v44, v45
	global_store_dwordx4 v[42:43], v[46:49], off offset:256 sc1

.LBB0_3310:
	v_lshlrev_b64 v[44:45], 10, v[66:67]
	v_lshlrev_b32_e32 v48, 9, v66
	v_and_b32_e32 v68, 0x1de00, v48
	s_waitcnt lgkmcnt(0)
	v_pk_fma_f32 v[32:33], v[32:33], v[62:63], v[56:57] op_sel_hi:[1,0,1]
	v_pk_fma_f32 v[30:31], v[30:31], v[62:63], v[54:55] op_sel_hi:[1,0,1]
	v_pk_fma_f32 v[28:29], v[28:29], v[62:63], v[52:53] op_sel_hi:[1,0,1]
	v_pk_fma_f32 v[26:27], v[26:27], v[62:63], v[50:51] op_sel_hi:[1,0,1]
	s_mov_b64 s[56:57], -1
	s_and_b64 vcc, exec, s[10:11]
	v_lshl_add_u64 v[64:65], s[28:29], 0, v[44:45]
	s_cbranch_vccnz .LBB0_3314
	s_lshl_b32 s20, s95, 7
	v_lshl_add_u64 v[48:49], s[20:21], 1, v[64:65]
	v_lshl_add_u64 v[48:49], v[48:49], 0, v[162:163]
	s_andn2_b64 vcc, exec, s[54:55]
	v_cvt_pk_bf16_f32 v70, v30, v31
	v_cvt_pk_bf16_f32 v71, v32, v33
	v_cvt_pk_bf16_f32 v72, v26, v27
	v_cvt_pk_bf16_f32 v73, v28, v29
	global_store_dwordx4 v[48:49], v[70:73], off sc1
	s_cbranch_vccnz .LBB0_3313
	s_lshl_b32 s56, s67, 1
	s_or_b32 s56, s56, 1
	s_ashr_i32 s57, s56, 31
	s_lshl_b64 s[56:57], s[56:57], 19
	s_add_u32 s56, s34, s56
	s_addc_u32 s57, s35, s57
	v_lshlrev_b32_e32 v48, 2, v68
	v_mov_b32_e32 v49, v163
	v_lshl_add_u64 v[48:49], s[56:57], 0, v[48:49]
	v_lshl_add_u64 v[48:49], s[20:21], 2, v[48:49]
	v_mov_b32_e32 v183, v163
	v_lshl_add_u64 v[48:49], v[48:49], 0, v[182:183]
	global_store_dwordx4 v[48:49], v[30:33], off sc1
	global_store_dwordx4 v[48:49], v[26:29], off offset:16 sc1

.LBB0_3314:
	s_andn2_b64 vcc, exec, s[56:57]
	v_lshlrev_b64 v[48:49], 12, v[66:67]
	s_cbranch_vccnz .LBB0_3321
	v_pk_mul_f32 v[66:67], v[28:29], v[58:59]
	v_pk_mul_f32 v[70:71], v[26:27], v[60:61]
	v_pk_mul_f32 v[72:73], v[28:29], v[42:43]
	v_pk_mul_f32 v[74:75], v[26:27], v[46:47]
	v_pk_fma_f32 v[66:67], v[32:33], v[42:43], v[66:67] neg_lo:[0,0,1] neg_hi:[0,0,1]
	v_pk_fma_f32 v[70:71], v[30:31], v[46:47], v[70:71] neg_lo:[0,0,1] neg_hi:[0,0,1]
	v_pk_fma_f32 v[72:73], v[32:33], v[58:59], v[72:73]
	v_pk_fma_f32 v[74:75], v[30:31], v[60:61], v[74:75]
	v_cndmask_b32_e64 v29, v29, v73, s[4:5]
	v_cndmask_b32_e64 v28, v28, v72, s[4:5]
	v_cndmask_b32_e64 v27, v27, v75, s[4:5]
	v_cndmask_b32_e64 v26, v26, v74, s[4:5]
	v_cndmask_b32_e64 v33, v33, v67, s[4:5]
	v_cndmask_b32_e64 v32, v32, v66, s[4:5]
	v_cndmask_b32_e64 v31, v31, v71, s[4:5]
	v_cndmask_b32_e64 v30, v30, v70, s[4:5]
	s_and_b64 vcc, exec, s[6:7]
	s_mov_b64 s[56:57], -1
	s_cbranch_vccnz .LBB0_3319
	v_lshl_add_u64 v[66:67], s[26:27], 0, v[44:45]
	s_lshl_b32 s20, s94, 8
	v_lshl_add_u64 v[66:67], v[66:67], 0, s[20:21]
	v_lshl_add_u64 v[66:67], v[66:67], 0, v[162:163]
	s_andn2_b64 vcc, exec, s[54:55]
	v_cvt_pk_bf16_f32 v70, v30, v31
	v_cvt_pk_bf16_f32 v71, v32, v33
	v_cvt_pk_bf16_f32 v72, v26, v27
	v_cvt_pk_bf16_f32 v73, v28, v29
	global_store_dwordx4 v[66:67], v[70:73], off sc1
	s_cbranch_vccnz .LBB0_3318
	s_lshl_b32 s56, s67, 1
	s_or_b32 s56, s56, 1
	s_ashr_i32 s57, s56, 31
	s_lshl_b32 s20, s94, 7
	s_lshl_b64 s[56:57], s[56:57], 19
	s_add_u32 s56, s30, s56
	s_addc_u32 s57, s31, s57
	v_lshlrev_b32_e32 v66, 2, v68
	v_mov_b32_e32 v67, v163
	v_lshl_add_u64 v[66:67], s[56:57], 0, v[66:67]
	v_lshl_add_u64 v[66:67], s[20:21], 2, v[66:67]
	v_lshlrev_b32_e32 v70, 2, v166
	v_mov_b32_e32 v71, v163
	v_lshl_add_u64 v[66:67], v[66:67], 0, v[70:71]
	global_store_dwordx4 v[66:67], v[30:33], off sc1
	global_store_dwordx4 v[66:67], v[26:29], off offset:128 sc1

.LBB0_3319:
	s_andn2_b64 vcc, exec, s[56:57]
	s_cbranch_vccnz .LBB0_3321
	v_cvt_pk_bf16_f32 v30, v30, v31
	v_cvt_pk_bf16_f32 v31, v32, v33
	v_cvt_pk_bf16_f32 v32, v26, v27
	v_lshl_add_u64 v[26:27], s[24:25], 0, v[48:49]
	v_lshl_add_u64 v[26:27], s[50:51], 1, v[26:27]
	v_lshl_add_u64 v[26:27], v[26:27], 0, v[162:163]
	v_cvt_pk_bf16_f32 v33, v28, v29
	global_store_dwordx4 v[26:27], v[30:33], off sc1
.LBB0_3321:
	v_mov_b32_e32 v63, v62
	v_mov_b32_e32 v26, v62
	v_mov_b32_e32 v27, v62
	v_pk_fma_f32 v[24:25], v[24:25], v[26:27], v[40:41]
	v_pk_fma_f32 v[22:23], v[22:23], v[62:63], v[38:39]
	v_pk_fma_f32 v[20:21], v[20:21], v[26:27], v[36:37]
	v_pk_fma_f32 v[18:19], v[18:19], v[62:63], v[34:35]
	s_and_b64 vcc, exec, s[10:11]
	s_mov_b64 s[56:57], -1
	s_cbranch_vccnz .LBB0_3325
	s_add_i32 s20, s50, 0xfffff680
	v_lshl_add_u64 v[30:31], s[20:21], 1, v[64:65]
	v_lshl_add_u64 v[30:31], v[30:31], 0, v[162:163]
	s_andn2_b64 vcc, exec, s[54:55]
	v_cvt_pk_bf16_f32 v26, v22, v23
	v_cvt_pk_bf16_f32 v27, v24, v25
	v_cvt_pk_bf16_f32 v28, v18, v19
	v_cvt_pk_bf16_f32 v29, v20, v21
	global_store_dwordx4 v[30:31], v[26:29], off sc1
	s_cbranch_vccnz .LBB0_3324
	s_lshl_b32 s56, s67, 1
	s_or_b32 s56, s56, 1
	s_ashr_i32 s57, s56, 31
	s_lshl_b64 s[56:57], s[56:57], 19
	s_add_u32 s56, s34, s56
	s_addc_u32 s57, s35, s57
	v_lshlrev_b32_e32 v26, 2, v68
	v_mov_b32_e32 v27, v163
	v_lshl_add_u64 v[26:27], s[56:57], 0, v[26:27]
	v_lshl_add_u64 v[26:27], s[20:21], 2, v[26:27]
	v_mov_b32_e32 v183, v163
	v_lshl_add_u64 v[26:27], v[26:27], 0, v[182:183]
	global_store_dwordx4 v[26:27], v[22:25], off sc1
	global_store_dwordx4 v[26:27], v[18:21], off offset:16 sc1

.LBB0_3325:
	s_andn2_b64 vcc, exec, s[56:57]
	s_cbranch_vccnz .LBB0_3332
	v_pk_mul_f32 v[26:27], v[20:21], v[58:59]
	v_pk_mul_f32 v[28:29], v[18:19], v[60:61]
	v_pk_mul_f32 v[30:31], v[20:21], v[42:43]
	v_pk_mul_f32 v[32:33], v[18:19], v[46:47]
	v_pk_fma_f32 v[26:27], v[24:25], v[42:43], v[26:27] neg_lo:[0,0,1] neg_hi:[0,0,1]
	v_pk_fma_f32 v[28:29], v[22:23], v[46:47], v[28:29] neg_lo:[0,0,1] neg_hi:[0,0,1]
	v_pk_fma_f32 v[30:31], v[24:25], v[58:59], v[30:31]
	v_pk_fma_f32 v[32:33], v[22:23], v[60:61], v[32:33]
	v_cndmask_b32_e64 v21, v21, v31, s[4:5]
	v_cndmask_b32_e64 v20, v20, v30, s[4:5]
	v_cndmask_b32_e64 v19, v19, v33, s[4:5]
	v_cndmask_b32_e64 v18, v18, v32, s[4:5]
	v_cndmask_b32_e64 v25, v25, v27, s[4:5]
	v_cndmask_b32_e64 v24, v24, v26, s[4:5]
	v_cndmask_b32_e64 v23, v23, v29, s[4:5]
	v_cndmask_b32_e64 v22, v22, v28, s[4:5]
	s_and_b64 vcc, exec, s[6:7]
	s_mov_b64 s[56:57], -1
	s_cbranch_vccnz .LBB0_3330
	v_lshl_add_u64 v[30:31], s[26:27], 0, v[44:45]
	s_add_i32 s20, s50, 0xfffff880
	v_lshl_add_u64 v[30:31], s[20:21], 1, v[30:31]
	v_lshl_add_u64 v[30:31], v[30:31], 0, v[162:163]
	s_andn2_b64 vcc, exec, s[54:55]
	v_cvt_pk_bf16_f32 v26, v22, v23
	v_cvt_pk_bf16_f32 v27, v24, v25
	v_cvt_pk_bf16_f32 v28, v18, v19
	v_cvt_pk_bf16_f32 v29, v20, v21
	global_store_dwordx4 v[30:31], v[26:29], off sc1
	s_cbranch_vccnz .LBB0_3329
	s_lshl_b32 s56, s67, 1
	s_or_b32 s56, s56, 1
	s_ashr_i32 s57, s56, 31
	s_lshl_b64 s[56:57], s[56:57], 19
	s_add_u32 s56, s30, s56
	s_addc_u32 s57, s31, s57
	v_lshlrev_b32_e32 v26, 2, v68
	v_mov_b32_e32 v27, v163
	v_lshl_add_u64 v[26:27], s[56:57], 0, v[26:27]
	v_lshl_add_u64 v[26:27], s[20:21], 2, v[26:27]
	v_lshlrev_b32_e32 v28, 2, v166
	v_mov_b32_e32 v29, v163
	v_lshl_add_u64 v[26:27], v[26:27], 0, v[28:29]
	global_store_dwordx4 v[26:27], v[22:25], off sc1
	global_store_dwordx4 v[26:27], v[18:21], off offset:128 sc1

.LBB0_3330:
	s_andn2_b64 vcc, exec, s[56:57]
	s_cbranch_vccnz .LBB0_3332
	v_cvt_pk_bf16_f32 v22, v22, v23
	v_cvt_pk_bf16_f32 v23, v24, v25
	v_cvt_pk_bf16_f32 v24, v18, v19
	v_lshl_add_u64 v[18:19], s[24:25], 0, v[48:49]
	v_lshl_add_u64 v[18:19], s[50:51], 1, v[18:19]
	v_lshl_add_u64 v[18:19], v[18:19], 0, v[162:163]
	v_cvt_pk_bf16_f32 v25, v20, v21
	global_store_dwordx4 v[18:19], v[22:25], off offset:256 sc1

.LBB0_3339:
	v_lshlrev_b64 v[20:21], 10, v[42:43]
	v_lshlrev_b32_e32 v24, 9, v42
	v_and_b32_e32 v44, 0x1fe00, v24
	s_waitcnt lgkmcnt(0)
	v_pk_fma_f32 v[16:17], v[16:17], v[30:31], v[56:57] op_sel_hi:[1,0,1]
	v_pk_fma_f32 v[14:15], v[14:15], v[30:31], v[54:55] op_sel_hi:[1,0,1]
	v_pk_fma_f32 v[12:13], v[12:13], v[30:31], v[52:53] op_sel_hi:[1,0,1]
	v_pk_fma_f32 v[10:11], v[10:11], v[30:31], v[50:51] op_sel_hi:[1,0,1]
	s_mov_b64 s[8:9], -1
	s_and_b64 vcc, exec, s[10:11]
	v_lshl_add_u64 v[32:33], s[28:29], 0, v[20:21]
	s_cbranch_vccnz .LBB0_3343
	s_lshl_b32 s20, s95, 7
	v_lshl_add_u64 v[24:25], s[20:21], 1, v[32:33]
	v_lshl_add_u64 v[24:25], v[24:25], 0, v[162:163]
	s_andn2_b64 vcc, exec, s[54:55]
	v_cvt_pk_bf16_f32 v46, v14, v15
	v_cvt_pk_bf16_f32 v47, v16, v17
	v_cvt_pk_bf16_f32 v48, v10, v11
	v_cvt_pk_bf16_f32 v49, v12, v13
	global_store_dwordx4 v[24:25], v[46:49], off sc1
	s_cbranch_vccnz .LBB0_3342
	s_lshl_b32 s8, s67, 1
	s_or_b32 s8, s8, 1
	s_ashr_i32 s9, s8, 31
	s_lshl_b64 s[8:9], s[8:9], 19
	s_add_u32 s8, s34, s8
	s_addc_u32 s9, s35, s9
	v_lshlrev_b32_e32 v24, 2, v44
	v_mov_b32_e32 v25, v163
	v_lshl_add_u64 v[24:25], s[8:9], 0, v[24:25]
	v_lshl_add_u64 v[24:25], s[20:21], 2, v[24:25]
	v_mov_b32_e32 v183, v163
	v_lshl_add_u64 v[24:25], v[24:25], 0, v[182:183]
	global_store_dwordx4 v[24:25], v[14:17], off sc1
	global_store_dwordx4 v[24:25], v[10:13], off offset:16 sc1

.LBB0_3343:
	s_andn2_b64 vcc, exec, s[8:9]
	v_lshlrev_b64 v[24:25], 12, v[42:43]
	s_cbranch_vccnz .LBB0_3350
	v_pk_mul_f32 v[42:43], v[12:13], v[26:27]
	v_pk_mul_f32 v[46:47], v[10:11], v[28:29]
	v_pk_mul_f32 v[48:49], v[12:13], v[18:19]
	v_pk_mul_f32 v[50:51], v[10:11], v[22:23]
	v_pk_fma_f32 v[42:43], v[16:17], v[18:19], v[42:43] neg_lo:[0,0,1] neg_hi:[0,0,1]
	v_pk_fma_f32 v[46:47], v[14:15], v[22:23], v[46:47] neg_lo:[0,0,1] neg_hi:[0,0,1]
	v_pk_fma_f32 v[48:49], v[16:17], v[26:27], v[48:49]
	v_pk_fma_f32 v[50:51], v[14:15], v[28:29], v[50:51]
	v_cndmask_b32_e64 v13, v13, v49, s[4:5]
	v_cndmask_b32_e64 v12, v12, v48, s[4:5]
	v_cndmask_b32_e64 v11, v11, v51, s[4:5]
	v_cndmask_b32_e64 v10, v10, v50, s[4:5]
	v_cndmask_b32_e64 v17, v17, v43, s[4:5]
	v_cndmask_b32_e64 v16, v16, v42, s[4:5]
	v_cndmask_b32_e64 v15, v15, v47, s[4:5]
	v_cndmask_b32_e64 v14, v14, v46, s[4:5]
	s_and_b64 vcc, exec, s[6:7]
	s_mov_b64 s[8:9], -1
	s_cbranch_vccnz .LBB0_3348
	v_lshl_add_u64 v[42:43], s[26:27], 0, v[20:21]
	s_lshl_b32 s20, s94, 8
	v_lshl_add_u64 v[42:43], v[42:43], 0, s[20:21]
	v_lshl_add_u64 v[42:43], v[42:43], 0, v[162:163]
	s_andn2_b64 vcc, exec, s[54:55]
	v_cvt_pk_bf16_f32 v46, v14, v15
	v_cvt_pk_bf16_f32 v47, v16, v17
	v_cvt_pk_bf16_f32 v48, v10, v11
	v_cvt_pk_bf16_f32 v49, v12, v13
	global_store_dwordx4 v[42:43], v[46:49], off sc1
	s_cbranch_vccnz .LBB0_3347
	s_lshl_b32 s8, s67, 1
	s_or_b32 s8, s8, 1
	s_ashr_i32 s9, s8, 31
	s_lshl_b32 s20, s94, 7
	s_lshl_b64 s[8:9], s[8:9], 19
	s_add_u32 s8, s30, s8
	s_addc_u32 s9, s31, s9
	v_lshlrev_b32_e32 v42, 2, v44
	v_mov_b32_e32 v43, v163
	v_lshl_add_u64 v[42:43], s[8:9], 0, v[42:43]
	v_lshl_add_u64 v[42:43], s[20:21], 2, v[42:43]
	v_lshlrev_b32_e32 v46, 2, v166
	v_mov_b32_e32 v47, v163
	v_lshl_add_u64 v[42:43], v[42:43], 0, v[46:47]
	global_store_dwordx4 v[42:43], v[14:17], off sc1
	global_store_dwordx4 v[42:43], v[10:13], off offset:128 sc1

.LBB0_3348:
	s_andn2_b64 vcc, exec, s[8:9]
	s_cbranch_vccnz .LBB0_3350
	v_cvt_pk_bf16_f32 v14, v14, v15
	v_cvt_pk_bf16_f32 v15, v16, v17
	v_cvt_pk_bf16_f32 v16, v10, v11
	v_lshl_add_u64 v[10:11], s[24:25], 0, v[24:25]
	v_lshl_add_u64 v[10:11], s[50:51], 1, v[10:11]
	v_lshl_add_u64 v[10:11], v[10:11], 0, v[162:163]
	v_cvt_pk_bf16_f32 v17, v12, v13
	global_store_dwordx4 v[10:11], v[14:17], off sc1
.LBB0_3350:
	v_mov_b32_e32 v31, v30
	v_mov_b32_e32 v10, v30
	v_mov_b32_e32 v11, v30
	v_pk_fma_f32 v[8:9], v[8:9], v[10:11], v[40:41]
	v_pk_fma_f32 v[6:7], v[6:7], v[30:31], v[38:39]
	v_pk_fma_f32 v[4:5], v[4:5], v[10:11], v[36:37]
	v_pk_fma_f32 v[2:3], v[2:3], v[30:31], v[34:35]
	s_and_b64 vcc, exec, s[10:11]
	s_mov_b64 s[8:9], -1
	s_cbranch_vccnz .LBB0_3354
	s_add_i32 s20, s50, 0xfffff680
	v_lshl_add_u64 v[14:15], s[20:21], 1, v[32:33]
	v_lshl_add_u64 v[14:15], v[14:15], 0, v[162:163]
	s_andn2_b64 vcc, exec, s[54:55]
	v_cvt_pk_bf16_f32 v10, v6, v7
	v_cvt_pk_bf16_f32 v11, v8, v9
	v_cvt_pk_bf16_f32 v12, v2, v3
	v_cvt_pk_bf16_f32 v13, v4, v5
	global_store_dwordx4 v[14:15], v[10:13], off sc1
	s_cbranch_vccnz .LBB0_3353
	s_lshl_b32 s8, s67, 1
	s_or_b32 s8, s8, 1
	s_ashr_i32 s9, s8, 31
	s_lshl_b64 s[8:9], s[8:9], 19
	s_add_u32 s8, s34, s8
	s_addc_u32 s9, s35, s9
	v_lshlrev_b32_e32 v10, 2, v44
	v_mov_b32_e32 v11, v163
	v_lshl_add_u64 v[10:11], s[8:9], 0, v[10:11]
	v_lshl_add_u64 v[10:11], s[20:21], 2, v[10:11]
	v_mov_b32_e32 v183, v163
	v_lshl_add_u64 v[10:11], v[10:11], 0, v[182:183]
	global_store_dwordx4 v[10:11], v[6:9], off sc1
	global_store_dwordx4 v[10:11], v[2:5], off offset:16 sc1

.LBB0_3354:
	s_andn2_b64 vcc, exec, s[8:9]
	s_cbranch_vccnz .LBB0_3361
	v_pk_mul_f32 v[10:11], v[4:5], v[26:27]
	v_pk_mul_f32 v[12:13], v[2:3], v[28:29]
	v_pk_mul_f32 v[14:15], v[4:5], v[18:19]
	v_pk_mul_f32 v[16:17], v[2:3], v[22:23]
	v_pk_fma_f32 v[10:11], v[8:9], v[18:19], v[10:11] neg_lo:[0,0,1] neg_hi:[0,0,1]
	v_pk_fma_f32 v[12:13], v[6:7], v[22:23], v[12:13] neg_lo:[0,0,1] neg_hi:[0,0,1]
	v_pk_fma_f32 v[14:15], v[8:9], v[26:27], v[14:15]
	v_pk_fma_f32 v[16:17], v[6:7], v[28:29], v[16:17]
	v_cndmask_b32_e64 v5, v5, v15, s[4:5]
	v_cndmask_b32_e64 v4, v4, v14, s[4:5]
	v_cndmask_b32_e64 v3, v3, v17, s[4:5]
	v_cndmask_b32_e64 v2, v2, v16, s[4:5]
	v_cndmask_b32_e64 v9, v9, v11, s[4:5]
	v_cndmask_b32_e64 v8, v8, v10, s[4:5]
	v_cndmask_b32_e64 v7, v7, v13, s[4:5]
	v_cndmask_b32_e64 v6, v6, v12, s[4:5]
	s_and_b64 vcc, exec, s[6:7]
	s_mov_b64 s[4:5], -1
	s_cbranch_vccnz .LBB0_3359
	v_lshl_add_u64 v[14:15], s[26:27], 0, v[20:21]
	s_add_i32 s20, s50, 0xfffff880
	v_lshl_add_u64 v[14:15], s[20:21], 1, v[14:15]
	v_lshl_add_u64 v[14:15], v[14:15], 0, v[162:163]
	s_andn2_b64 vcc, exec, s[54:55]
	v_cvt_pk_bf16_f32 v10, v6, v7
	v_cvt_pk_bf16_f32 v11, v8, v9
	v_cvt_pk_bf16_f32 v12, v2, v3
	v_cvt_pk_bf16_f32 v13, v4, v5
	global_store_dwordx4 v[14:15], v[10:13], off sc1
	s_cbranch_vccnz .LBB0_3358
	s_lshl_b32 s4, s67, 1
	s_or_b32 s4, s4, 1
	s_ashr_i32 s5, s4, 31
	s_lshl_b64 s[4:5], s[4:5], 19
	s_add_u32 s4, s30, s4
	s_addc_u32 s5, s31, s5
	v_lshlrev_b32_e32 v10, 2, v44
	v_mov_b32_e32 v11, v163
	v_lshl_add_u64 v[10:11], s[4:5], 0, v[10:11]
	v_lshl_add_u64 v[10:11], s[20:21], 2, v[10:11]
	v_lshlrev_b32_e32 v12, 2, v166
	v_mov_b32_e32 v13, v163
	v_lshl_add_u64 v[10:11], v[10:11], 0, v[12:13]
	global_store_dwordx4 v[10:11], v[6:9], off sc1
	global_store_dwordx4 v[10:11], v[2:5], off offset:128 sc1

.LBB0_3359:
	s_andn2_b64 vcc, exec, s[4:5]
	s_cbranch_vccnz .LBB0_3361
	v_cvt_pk_bf16_f32 v6, v6, v7
	v_cvt_pk_bf16_f32 v7, v8, v9
	v_cvt_pk_bf16_f32 v8, v2, v3
	v_lshl_add_u64 v[2:3], s[24:25], 0, v[24:25]
	v_lshl_add_u64 v[2:3], s[50:51], 1, v[2:3]
	v_lshl_add_u64 v[2:3], v[2:3], 0, v[162:163]
	v_cvt_pk_bf16_f32 v9, v4, v5
	global_store_dwordx4 v[2:3], v[6:9], off offset:256 sc1

.LBB0_3617:
	s_lshr_b32 s40, s69, 4
	s_add_i32 s40, s40, -1
	s_cmp_gt_i32 s69, 31
	s_cselect_b32 s40, s40, 0
	v_lshl_or_b32 v90, s12, 8, v230
	s_mul_i32 s43, s40, 0xc000
	s_mul_hi_i32 s42, s40, 0xc000
	s_add_u32 s40, s55, s43
	v_ashrrev_i32_e32 v91, 31, v90
	s_addc_u32 s41, s56, s42
	v_lshlrev_b64 v[36:37], 2, v[90:91]
	v_lshl_add_u64 v[26:27], s[40:41], 0, v[36:37]
	v_lshl_add_u64 v[28:29], s[20:21], 0, v[36:37]
	s_waitcnt lgkmcnt(0)
	global_load_dwordx4 v[2:5], v[26:27], off offset:16
	global_load_dwordx4 v[6:9], v[26:27], off
	global_load_dwordx4 v[10:13], v[28:29], off offset:16
	global_load_dwordx4 v[14:17], v[28:29], off
	s_add_u32 s40, s48, s43
	v_lshl_add_u64 v[30:31], s[24:25], 0, v[36:37]
	s_addc_u32 s41, s49, s42
	v_lshl_add_u64 v[32:33], s[40:41], 0, v[36:37]
	v_lshl_add_u32 v210, s69, 8, v228
	v_ashrrev_i32_e32 v211, 31, v210
	v_or_b32_e32 v34, 16, v210
	v_ashrrev_i32_e32 v35, 31, v34
	s_lshl_b32 s40, s12, 2
	s_ashr_i32 s41, s40, 31
	s_waitcnt vmcnt(0)
	v_pk_mul_f32 v[92:93], v[4:5], v[12:13]
	v_pk_mul_f32 v[86:87], v[8:9], v[16:17]
	v_pk_mul_f32 v[88:89], v[6:7], v[14:15]
	global_load_dwordx4 v[6:9], v[30:31], off offset:16
	global_load_dwordx4 v[14:17], v[30:31], off
	global_load_dwordx4 v[18:21], v[32:33], off offset:16
	global_load_dwordx4 v[22:25], v[32:33], off
	v_pk_mul_f32 v[94:95], v[2:3], v[10:11]
	s_waitcnt vmcnt(0)
	v_pk_add_f32 v[2:3], v[20:21], 1.0 op_sel_hi:[1,0]
	v_pk_add_f32 v[24:25], v[24:25], 1.0 op_sel_hi:[1,0]
	v_pk_add_f32 v[22:23], v[22:23], 1.0 op_sel_hi:[1,0]
	v_pk_add_f32 v[4:5], v[18:19], 1.0 op_sel_hi:[1,0]
	v_pk_mul_f32 v[78:79], v[16:17], v[24:25]
	v_pk_mul_f32 v[80:81], v[14:15], v[22:23]
	v_pk_mul_f32 v[82:83], v[8:9], v[2:3]
	v_pk_mul_f32 v[84:85], v[6:7], v[4:5]
	global_load_dwordx4 v[2:5], v[26:27], off offset:528
	global_load_dwordx4 v[6:9], v[26:27], off offset:512
	global_load_dwordx4 v[10:13], v[28:29], off offset:528
	global_load_dwordx4 v[14:17], v[28:29], off offset:512
	s_waitcnt vmcnt(0)
	v_pk_mul_f32 v[108:109], v[2:3], v[10:11]
	v_pk_mul_f32 v[104:105], v[8:9], v[16:17]
	v_pk_mul_f32 v[106:107], v[6:7], v[14:15]
	global_load_dwordx4 v[6:9], v[30:31], off offset:528
	global_load_dwordx4 v[14:17], v[30:31], off offset:512
	global_load_dwordx4 v[18:21], v[32:33], off offset:528
	global_load_dwordx4 v[22:25], v[32:33], off offset:512
	v_pk_mul_f32 v[110:111], v[4:5], v[12:13]
	s_waitcnt vmcnt(0)
	v_pk_add_f32 v[2:3], v[20:21], 1.0 op_sel_hi:[1,0]
	s_nop 0
	v_pk_mul_f32 v[100:101], v[8:9], v[2:3]
	v_lshlrev_b64 v[2:3], 13, v[210:211]
	v_lshl_add_u64 v[2:3], s[16:17], 0, v[2:3]
	v_lshl_add_u64 v[38:39], v[2:3], 0, v[36:37]
	v_lshlrev_b64 v[2:3], 13, v[34:35]
	v_lshl_add_u64 v[2:3], s[16:17], 0, v[2:3]
	v_pk_add_f32 v[24:25], v[24:25], 1.0 op_sel_hi:[1,0]
	v_pk_add_f32 v[22:23], v[22:23], 1.0 op_sel_hi:[1,0]
	v_pk_add_f32 v[4:5], v[18:19], 1.0 op_sel_hi:[1,0]
	v_lshl_add_u64 v[36:37], v[2:3], 0, v[36:37]
	v_pk_mul_f32 v[96:97], v[16:17], v[24:25]
	v_pk_mul_f32 v[98:99], v[14:15], v[22:23]
	v_pk_mul_f32 v[102:103], v[6:7], v[4:5]
	global_load_dwordx4 v[22:25], v[38:39], off offset:16 nt
	global_load_dwordx4 v[30:33], v[38:39], off nt
	global_load_dwordx4 v[18:21], v[38:39], off offset:528 nt
	global_load_dwordx4 v[26:29], v[38:39], off offset:512 nt
	global_load_dwordx4 v[10:13], v[36:37], off offset:16 nt
	global_load_dwordx4 v[14:17], v[36:37], off nt
	global_load_dwordx4 v[2:5], v[36:37], off offset:528 nt
	global_load_dwordx4 v[6:9], v[36:37], off offset:512 nt
	v_lshl_add_u64 v[196:197], v[210:211], 2, s[18:19]
	global_load_dword v40, v[196:197], off
	v_and_b32_e32 v44, 64, v232
	v_xor_b32_e32 v41, 16, v232
	v_add_u32_e32 v234, 64, v44
	v_cmp_lt_i32_e32 vcc, v41, v234
	v_lshlrev_b64 v[42:43], 12, v[210:211]
	v_lshl_add_u64 v[42:43], s[22:23], 0, v[42:43]
	v_cndmask_b32_e32 v41, v232, v41, vcc
	v_lshlrev_b32_e32 v233, 2, v41
	v_lshl_add_u64 v[42:43], v[90:91], 1, v[42:43]
	s_waitcnt vmcnt(0)
	v_pk_mul_f32 v[44:45], v[40:41], v[214:215] op_sel_hi:[0,1]
	v_pk_mul_f32 v[212:213], v[40:41], v[212:213] op_sel_hi:[0,1]
	v_pk_mul_f32 v[214:215], v[40:41], v[218:219] op_sel_hi:[0,1]
	v_pk_mul_f32 v[218:219], v[40:41], v[222:223] op_sel_hi:[0,1]
	v_pk_mul_f32 v[220:221], v[40:41], v[220:221] op_sel_hi:[0,1]
	v_pk_mul_f32 v[216:217], v[40:41], v[216:217] op_sel_hi:[0,1]
	v_pk_mul_f32 v[222:223], v[40:41], v[226:227] op_sel_hi:[0,1]
	v_pk_mul_f32 v[40:41], v[40:41], v[224:225] op_sel_hi:[0,1]
	v_pk_fma_f32 v[32:33], v[86:87], v[212:213], v[32:33]
	v_pk_fma_f32 v[30:31], v[88:89], v[44:45], v[30:31]
	v_pk_fma_f32 v[28:29], v[104:105], v[220:221], v[28:29]
	v_pk_fma_f32 v[26:27], v[106:107], v[218:219], v[26:27]
	v_pk_fma_f32 v[24:25], v[92:93], v[216:217], v[24:25]
	v_pk_fma_f32 v[22:23], v[94:95], v[214:215], v[22:23]
	v_pk_fma_f32 v[20:21], v[110:111], v[40:41], v[20:21]
	v_pk_fma_f32 v[18:19], v[108:109], v[222:223], v[18:19]
	global_store_dwordx4 v[38:39], v[30:33], off nt
	global_store_dwordx4 v[38:39], v[22:25], off offset:16 nt
	v_mul_f32_e32 v224, v31, v31
	v_mul_f32_e32 v225, v33, v33
	v_pk_mul_f32 v[40:41], v[78:79], v[32:33]
	v_pk_mul_f32 v[44:45], v[80:81], v[30:31]
	v_mul_f32_e32 v31, v27, v27
	v_mul_f32_e32 v33, v29, v29
	v_mul_f32_e32 v226, v23, v23
	v_mul_f32_e32 v227, v25, v25
	v_mul_f32_e32 v235, v19, v19
	v_fmac_f32_e32 v224, v30, v30
	v_fmac_f32_e32 v225, v32, v32
	v_fmac_f32_e32 v31, v26, v26
	v_fmac_f32_e32 v33, v28, v28
	v_pk_mul_f32 v[212:213], v[82:83], v[24:25]
	v_pk_mul_f32 v[214:215], v[84:85], v[22:23]
	v_mul_f32_e32 v236, v21, v21
	v_pk_mul_f32 v[222:223], v[102:103], v[18:19]
	v_fmac_f32_e32 v226, v22, v22
	v_fmac_f32_e32 v227, v24, v24
	v_cvt_pk_bf16_f32 v22, v44, v45
	v_cvt_pk_bf16_f32 v23, v40, v41
	v_cvt_pk_bf16_f32 v24, v214, v215
	v_cvt_pk_bf16_f32 v25, v212, v213
	v_fmac_f32_e32 v235, v18, v18
	v_add_f32_e32 v30, v224, v225
	global_store_dwordx4 v[42:43], v[22:25], off sc1
	v_lshlrev_b32_e32 v32, 16, v22
	v_and_b32_e32 v40, 0xffff0000, v22
	global_store_dwordx4 v[38:39], v[26:29], off offset:512 nt
	global_store_dwordx4 v[38:39], v[18:21], off offset:528 nt
	v_pk_mul_f32 v[220:221], v[100:101], v[20:21]
	v_fmac_f32_e32 v236, v20, v20
	v_add_f32_e32 v18, v31, v33
	v_lshlrev_b32_e32 v41, 16, v23
	v_and_b32_e32 v44, 0xffff0000, v23
	v_add_f32_e32 v19, v226, v30
	v_max3_f32 v20, |v32|, 0, |v40|
	v_add_f32_e32 v18, v235, v18
	v_lshlrev_b32_e32 v45, 16, v24
	v_and_b32_e32 v212, 0xffff0000, v24
	v_add_f32_e32 v19, v227, v19
	v_max3_f32 v20, v20, |v41|, |v44|
	v_add_f32_e32 v18, v236, v18
	v_lshlrev_b32_e32 v213, 16, v25
	v_and_b32_e32 v214, 0xffff0000, v25
	v_max3_f32 v20, v20, |v45|, |v212|
	v_add_f32_e32 v18, v19, v18
	v_pk_mul_f32 v[218:219], v[98:99], v[26:27]
	v_max3_f32 v19, v20, |v213|, |v214|
	v_cvt_pk_bf16_f32 v22, v218, v219
	ds_bpermute_b32 v20, v233, v18
	v_lshlrev_b32_e32 v21, 16, v22
	v_and_b32_e32 v26, 0xffff0000, v22
	v_pk_mul_f32 v[216:217], v[96:97], v[28:29]
	v_max3_f32 v19, v19, |v21|, |v26|
	v_cvt_pk_bf16_f32 v23, v216, v217
	v_cvt_pk_bf16_f32 v24, v222, v223
	v_cvt_pk_bf16_f32 v25, v220, v221
	s_waitcnt lgkmcnt(0)
	v_add_f32_e32 v18, v18, v20
	v_lshlrev_b32_e32 v27, 16, v23
	v_and_b32_e32 v28, 0xffff0000, v23
	v_lshlrev_b32_e32 v29, 16, v24
	v_and_b32_e32 v30, 0xffff0000, v24
	v_max3_f32 v19, v19, |v27|, |v28|
	v_max3_f32 v19, v19, |v29|, |v30|
	v_lshlrev_b32_e32 v21, 16, v25
	v_and_b32_e32 v26, 0xffff0000, v25
	v_max3_f32 v21, v19, |v21|, |v26|
	ds_bpermute_b32 v20, v233, v21
	v_xor_b32_e32 v19, 32, v232
	v_cmp_lt_i32_e32 vcc, v19, v234
	global_store_dwordx4 v[42:43], v[22:25], off offset:256 sc1
	s_waitcnt lgkmcnt(0)
	v_max_f32_e32 v20, v20, v20
	v_cndmask_b32_e32 v19, v232, v19, vcc
	v_lshlrev_b32_e32 v216, 2, v19
	v_max_f32_e32 v20, v21, v20
	ds_bpermute_b32 v19, v216, v18
	ds_bpermute_b32 v21, v216, v20
	s_and_saveexec_b64 s[42:43], s[0:1]
	s_cbranch_execz .LBB0_3619
	s_waitcnt lgkmcnt(0)
	v_max_f32_e32 v21, v21, v21
	v_max_f32_e32 v20, v20, v20
	v_add_f32_e32 v23, v18, v19
	v_lshlrev_b64 v[18:19], 7, v[210:211]
	v_max_f32_e32 v22, v20, v21
	v_lshl_add_u64 v[20:21], s[26:27], 0, v[18:19]
	s_lshl_b64 s[70:71], s[40:41], 2
	v_lshl_add_u64 v[18:19], s[28:29], 0, v[18:19]
	v_lshl_add_u64 v[20:21], v[20:21], 0, s[70:71]
	s_lshl_b32 s12, s59, 2
	v_lshl_add_u64 v[18:19], v[18:19], 0, s[70:71]
	v_lshl_add_u64 v[20:21], v[20:21], 0, s[12:13]
	v_lshl_add_u64 v[18:19], v[18:19], 0, s[12:13]
	global_store_dword v[20:21], v23, off
	global_store_dword v[18:19], v22, off
.LBB0_3619:
	s_or_b64 exec, exec, s[42:43]
	v_or_b32_e32 v212, 32, v210
	v_ashrrev_i32_e32 v213, 31, v212
	s_waitcnt lgkmcnt(1)
	v_lshlrev_b64 v[18:19], 13, v[212:213]
	v_lshl_add_u64 v[18:19], s[16:17], 0, v[18:19]
	v_lshl_add_u64 v[214:215], v[90:91], 2, v[18:19]
	global_load_dwordx4 v[26:29], v[214:215], off offset:16 nt
	global_load_dwordx4 v[30:33], v[214:215], off nt
	s_waitcnt lgkmcnt(0)
	global_load_dwordx4 v[18:21], v[214:215], off offset:528 nt
	global_load_dwordx4 v[22:25], v[214:215], off offset:512 nt
	v_lshl_add_u64 v[38:39], v[34:35], 2, s[18:19]
	global_load_dword v38, v[38:39], off
	v_lshlrev_b64 v[40:41], 12, v[34:35]
	v_lshl_add_u64 v[40:41], s[22:23], 0, v[40:41]
	v_lshl_add_u64 v[40:41], v[90:91], 1, v[40:41]
	s_waitcnt vmcnt(0)
	v_pk_mul_f32 v[44:45], v[38:39], v[192:193] op_sel_hi:[0,1]
	v_pk_mul_f32 v[192:193], v[38:39], v[200:201] op_sel_hi:[0,1]
	v_pk_mul_f32 v[42:43], v[38:39], v[194:195] op_sel_hi:[0,1]
	v_pk_mul_f32 v[194:195], v[38:39], v[198:199] op_sel_hi:[0,1]
	v_pk_mul_f32 v[198:199], v[38:39], v[206:207] op_sel_hi:[0,1]
	v_pk_mul_f32 v[200:201], v[38:39], v[202:203] op_sel_hi:[0,1]
	v_pk_fma_f32 v[10:11], v[94:95], v[192:193], v[10:11]
	v_pk_mul_f32 v[202:203], v[38:39], v[208:209] op_sel_hi:[0,1]
	v_pk_mul_f32 v[38:39], v[38:39], v[204:205] op_sel_hi:[0,1]
	v_pk_fma_f32 v[16:17], v[86:87], v[44:45], v[16:17]
	v_pk_fma_f32 v[14:15], v[88:89], v[42:43], v[14:15]
	v_pk_fma_f32 v[12:13], v[92:93], v[194:195], v[12:13]
	v_pk_fma_f32 v[8:9], v[104:105], v[200:201], v[8:9]
	v_pk_fma_f32 v[6:7], v[106:107], v[198:199], v[6:7]
	v_mul_f32_e32 v206, v11, v11
	v_pk_fma_f32 v[4:5], v[110:111], v[38:39], v[4:5]
	v_pk_fma_f32 v[2:3], v[108:109], v[202:203], v[2:3]
	global_store_dwordx4 v[36:37], v[14:17], off nt
	global_store_dwordx4 v[36:37], v[10:13], off offset:16 nt
	v_mul_f32_e32 v204, v15, v15
	v_mul_f32_e32 v205, v17, v17
	v_mul_f32_e32 v207, v13, v13
	v_pk_mul_f32 v[38:39], v[78:79], v[16:17]
	v_pk_mul_f32 v[42:43], v[80:81], v[14:15]
	v_pk_mul_f32 v[192:193], v[84:85], v[10:11]
	v_mul_f32_e32 v15, v7, v7
	v_mul_f32_e32 v17, v9, v9
	v_fmac_f32_e32 v206, v10, v10
	v_cvt_pk_bf16_f32 v10, v42, v43
	v_pk_mul_f32 v[44:45], v[82:83], v[12:13]
	v_mul_f32_e32 v208, v3, v3
	v_mul_f32_e32 v209, v5, v5
	v_fmac_f32_e32 v204, v14, v14
	v_fmac_f32_e32 v205, v16, v16
	v_fmac_f32_e32 v207, v12, v12
	v_cvt_pk_bf16_f32 v11, v38, v39
	v_cvt_pk_bf16_f32 v12, v192, v193
	v_cvt_pk_bf16_f32 v13, v44, v45
	v_fmac_f32_e32 v15, v6, v6
	v_fmac_f32_e32 v17, v8, v8
	global_store_dwordx4 v[40:41], v[10:13], off sc1
	v_lshlrev_b32_e32 v16, 16, v10
	v_pk_mul_f32 v[200:201], v[100:101], v[4:5]
	v_and_b32_e32 v10, 0xffff0000, v10
	v_pk_mul_f32 v[202:203], v[102:103], v[2:3]
	v_fmac_f32_e32 v208, v2, v2
	v_fmac_f32_e32 v209, v4, v4
	v_add_f32_e32 v14, v204, v205
	v_lshlrev_b32_e32 v38, 16, v11
	v_and_b32_e32 v11, 0xffff0000, v11
	global_store_dwordx4 v[36:37], v[6:9], off offset:512 nt
	global_store_dwordx4 v[36:37], v[2:5], off offset:528 nt
	v_lshlrev_b32_e32 v39, 16, v12
	v_and_b32_e32 v12, 0xffff0000, v12
	v_add_f32_e32 v2, v15, v17
	v_max3_f32 v4, |v16|, 0, |v10|
	v_add_f32_e32 v3, v206, v14
	v_add_f32_e32 v2, v208, v2
	v_max3_f32 v4, v4, |v38|, |v11|
	v_lshlrev_b32_e32 v42, 16, v13
	v_and_b32_e32 v13, 0xffff0000, v13
	v_add_f32_e32 v3, v207, v3
	v_add_f32_e32 v2, v209, v2
	v_max3_f32 v4, v4, |v39|, |v12|
	v_pk_mul_f32 v[198:199], v[98:99], v[6:7]
	v_add_f32_e32 v2, v3, v2
	v_cvt_pk_bf16_f32 v6, v198, v199
	v_max3_f32 v3, v4, |v42|, |v13|
	v_lshlrev_b32_e32 v5, 16, v6
	v_and_b32_e32 v10, 0xffff0000, v6
	v_pk_mul_f32 v[194:195], v[96:97], v[8:9]
	v_max3_f32 v3, v3, |v5|, |v10|
	v_cvt_pk_bf16_f32 v7, v194, v195
	v_cvt_pk_bf16_f32 v8, v202, v203
	v_cvt_pk_bf16_f32 v9, v200, v201
	ds_bpermute_b32 v4, v233, v2
	v_lshlrev_b32_e32 v14, 16, v7
	v_and_b32_e32 v15, 0xffff0000, v7
	v_lshlrev_b32_e32 v16, 16, v8
	v_and_b32_e32 v17, 0xffff0000, v8
	v_max3_f32 v3, v3, |v14|, |v15|
	v_lshlrev_b32_e32 v36, 16, v9
	v_and_b32_e32 v37, 0xffff0000, v9
	v_max3_f32 v3, v3, |v16|, |v17|
	v_max3_f32 v5, v3, |v36|, |v37|
	ds_bpermute_b32 v10, v233, v5
	s_waitcnt lgkmcnt(1)
	v_add_f32_e32 v2, v2, v4
	ds_bpermute_b32 v3, v216, v2
	global_store_dwordx4 v[40:41], v[6:9], off offset:256 sc1
	s_waitcnt lgkmcnt(1)
	v_max_f32_e32 v4, v10, v10
	v_max_f32_e32 v4, v5, v4
	ds_bpermute_b32 v5, v216, v4
	s_and_saveexec_b64 s[42:43], s[0:1]
	s_cbranch_execz .LBB0_3621
	s_waitcnt lgkmcnt(0)
	v_max_f32_e32 v5, v5, v5
	v_max_f32_e32 v4, v4, v4
	v_add_f32_e32 v7, v2, v3
	v_lshlrev_b64 v[2:3], 7, v[34:35]
	v_max_f32_e32 v6, v4, v5
	v_lshl_add_u64 v[4:5], s[26:27], 0, v[2:3]
	s_lshl_b64 s[70:71], s[40:41], 2
	v_lshl_add_u64 v[2:3], s[28:29], 0, v[2:3]
	v_lshl_add_u64 v[4:5], v[4:5], 0, s[70:71]
	s_lshl_b32 s12, s59, 2
	v_lshl_add_u64 v[2:3], v[2:3], 0, s[70:71]
	v_lshl_add_u64 v[4:5], v[4:5], 0, s[12:13]
	v_lshl_add_u64 v[2:3], v[2:3], 0, s[12:13]
	global_store_dword v[4:5], v7, off
	global_store_dword v[2:3], v6, off
.LBB0_3621:
	s_or_b64 exec, exec, s[42:43]
	v_or_b32_e32 v192, 48, v210
	v_ashrrev_i32_e32 v193, 31, v192
	s_waitcnt lgkmcnt(1)
	v_lshlrev_b64 v[2:3], 13, v[192:193]
	v_lshl_add_u64 v[2:3], s[16:17], 0, v[2:3]
	v_lshl_add_u64 v[194:195], v[90:91], 2, v[2:3]
	global_load_dwordx4 v[38:41], v[194:195], off offset:16 nt
	global_load_dwordx4 v[42:45], v[194:195], off nt
	global_load_dwordx4 v[6:9], v[194:195], off offset:528 nt
	global_load_dwordx4 v[34:37], v[194:195], off offset:512 nt
	v_lshl_add_u64 v[2:3], v[212:213], 2, s[18:19]
	global_load_dword v2, v[2:3], off
	s_waitcnt lgkmcnt(0)
	v_lshlrev_b64 v[4:5], 12, v[212:213]
	v_lshl_add_u64 v[4:5], s[22:23], 0, v[4:5]
	v_lshl_add_u64 v[198:199], v[90:91], 1, v[4:5]
	s_waitcnt vmcnt(0)
	v_pk_mul_f32 v[10:11], v[2:3], v[178:179] op_sel_hi:[0,1]
	v_pk_mul_f32 v[4:5], v[2:3], v[176:177] op_sel_hi:[0,1]
	v_pk_mul_f32 v[14:15], v[2:3], v[182:183] op_sel_hi:[0,1]
	v_pk_mul_f32 v[12:13], v[2:3], v[180:181] op_sel_hi:[0,1]
	v_pk_mul_f32 v[176:177], v[2:3], v[188:189] op_sel_hi:[0,1]
	v_pk_mul_f32 v[16:17], v[2:3], v[184:185] op_sel_hi:[0,1]
	v_pk_mul_f32 v[178:179], v[2:3], v[190:191] op_sel_hi:[0,1]
	v_pk_mul_f32 v[180:181], v[2:3], v[186:187] op_sel_hi:[0,1]
	v_pk_fma_f32 v[2:3], v[88:89], v[10:11], v[30:31]
	v_pk_fma_f32 v[4:5], v[86:87], v[4:5], v[32:33]
	v_pk_fma_f32 v[20:21], v[110:111], v[180:181], v[20:21]
	v_mul_f32_e32 v180, v3, v3
	v_pk_fma_f32 v[12:13], v[92:93], v[12:13], v[28:29]
	v_pk_fma_f32 v[10:11], v[94:95], v[14:15], v[26:27]
	v_pk_fma_f32 v[16:17], v[104:105], v[16:17], v[24:25]
	v_pk_fma_f32 v[14:15], v[106:107], v[176:177], v[22:23]
	global_store_dwordx4 v[214:215], v[2:5], off nt
	global_store_dwordx4 v[214:215], v[10:13], off offset:16 nt
	v_mul_f32_e32 v181, v5, v5
	v_pk_mul_f32 v[22:23], v[78:79], v[4:5]
	v_pk_mul_f32 v[24:25], v[80:81], v[2:3]
	v_fmac_f32_e32 v180, v2, v2
	v_cvt_pk_bf16_f32 v2, v24, v25
	v_pk_mul_f32 v[26:27], v[82:83], v[12:13]
	v_pk_mul_f32 v[28:29], v[84:85], v[10:11]
	v_fmac_f32_e32 v181, v4, v4
	v_cvt_pk_bf16_f32 v3, v22, v23
	v_cvt_pk_bf16_f32 v4, v28, v29
	v_cvt_pk_bf16_f32 v5, v26, v27
	global_store_dwordx4 v[198:199], v[2:5], off sc1
	v_lshlrev_b32_e32 v23, 16, v2
	v_lshlrev_b32_e32 v24, 16, v3
	v_and_b32_e32 v2, 0xffff0000, v2
	v_and_b32_e32 v3, 0xffff0000, v3
	v_max3_f32 v2, |v23|, 0, |v2|
	v_lshlrev_b32_e32 v25, 16, v4
	v_and_b32_e32 v4, 0xffff0000, v4
	v_max3_f32 v2, v2, |v24|, |v3|
	v_pk_fma_f32 v[18:19], v[108:109], v[178:179], v[18:19]
	v_mul_f32_e32 v182, v11, v11
	v_mul_f32_e32 v183, v13, v13
	v_mul_f32_e32 v11, v15, v15
	v_mul_f32_e32 v13, v17, v17
	v_lshlrev_b32_e32 v26, 16, v5
	v_and_b32_e32 v5, 0xffff0000, v5
	v_max3_f32 v2, v2, |v25|, |v4|
	v_mul_f32_e32 v184, v19, v19
	v_pk_mul_f32 v[30:31], v[96:97], v[16:17]
	v_pk_mul_f32 v[32:33], v[98:99], v[14:15]
	v_fmac_f32_e32 v182, v10, v10
	v_fmac_f32_e32 v11, v14, v14
	v_fmac_f32_e32 v13, v16, v16
	global_store_dwordx4 v[214:215], v[14:17], off offset:512 nt
	global_store_dwordx4 v[214:215], v[18:21], off offset:528 nt
	v_cvt_pk_bf16_f32 v10, v32, v33
	v_max3_f32 v2, v2, |v26|, |v5|
	v_lshlrev_b32_e32 v16, 16, v10
	v_and_b32_e32 v17, 0xffff0000, v10
	v_mul_f32_e32 v185, v21, v21
	v_pk_mul_f32 v[178:179], v[102:103], v[18:19]
	v_fmac_f32_e32 v184, v18, v18
	v_add_f32_e32 v22, v180, v181
	v_add_f32_e32 v14, v11, v13
	v_cvt_pk_bf16_f32 v11, v30, v31
	v_max3_f32 v2, v2, |v16|, |v17|
	v_lshlrev_b32_e32 v18, 16, v11
	v_and_b32_e32 v19, 0xffff0000, v11
	v_pk_mul_f32 v[176:177], v[100:101], v[20:21]
	v_fmac_f32_e32 v183, v12, v12
	v_fmac_f32_e32 v185, v20, v20
	v_cvt_pk_bf16_f32 v12, v178, v179
	v_add_f32_e32 v15, v182, v22
	v_add_f32_e32 v14, v184, v14
	v_lshlrev_b32_e32 v20, 16, v12
	v_and_b32_e32 v21, 0xffff0000, v12
	v_max3_f32 v2, v2, |v18|, |v19|
	v_cvt_pk_bf16_f32 v13, v176, v177
	v_add_f32_e32 v15, v183, v15
	v_lshlrev_b32_e32 v22, 16, v13
	v_and_b32_e32 v23, 0xffff0000, v13
	v_add_f32_e32 v3, v185, v14
	v_max3_f32 v2, v2, |v20|, |v21|
	v_add_f32_e32 v3, v15, v3
	v_max3_f32 v5, v2, |v22|, |v23|
	ds_bpermute_b32 v4, v233, v3
	ds_bpermute_b32 v14, v233, v5
	global_store_dwordx4 v[198:199], v[10:13], off offset:256 sc1
	s_waitcnt lgkmcnt(1)
	v_add_f32_e32 v2, v3, v4
	s_waitcnt lgkmcnt(0)
	v_max_f32_e32 v4, v14, v14
	v_max_f32_e32 v4, v5, v4
	ds_bpermute_b32 v3, v216, v2
	ds_bpermute_b32 v5, v216, v4
	s_and_saveexec_b64 s[42:43], s[0:1]
	s_cbranch_execz .LBB0_3623
	s_waitcnt lgkmcnt(0)
	v_max_f32_e32 v5, v5, v5
	v_max_f32_e32 v4, v4, v4
	v_add_f32_e32 v11, v2, v3
	v_lshlrev_b64 v[2:3], 7, v[212:213]
	v_max_f32_e32 v10, v4, v5
	v_lshl_add_u64 v[4:5], s[26:27], 0, v[2:3]
	s_lshl_b64 s[70:71], s[40:41], 2
	v_lshl_add_u64 v[2:3], s[28:29], 0, v[2:3]
	v_lshl_add_u64 v[4:5], v[4:5], 0, s[70:71]
	s_lshl_b32 s12, s59, 2
	v_lshl_add_u64 v[2:3], v[2:3], 0, s[70:71]
	v_lshl_add_u64 v[4:5], v[4:5], 0, s[12:13]
	v_lshl_add_u64 v[2:3], v[2:3], 0, s[12:13]
	global_store_dword v[4:5], v11, off
	global_store_dword v[2:3], v10, off
.LBB0_3623:
	s_or_b64 exec, exec, s[42:43]
	v_add_u32_e32 v176, 0x80, v210
	v_ashrrev_i32_e32 v177, 31, v176
	s_waitcnt lgkmcnt(1)
	v_lshlrev_b64 v[2:3], 13, v[176:177]
	v_lshl_add_u64 v[2:3], s[16:17], 0, v[2:3]
	v_lshl_add_u64 v[178:179], v[90:91], 2, v[2:3]
	global_load_dwordx4 v[14:17], v[178:179], off offset:16 nt
	global_load_dwordx4 v[18:21], v[178:179], off nt
	s_waitcnt lgkmcnt(0)
	global_load_dwordx4 v[2:5], v[178:179], off offset:528 nt
	global_load_dwordx4 v[10:13], v[178:179], off offset:512 nt
	v_lshl_add_u64 v[22:23], v[192:193], 2, s[18:19]
	global_load_dword v22, v[22:23], off
	v_lshlrev_b64 v[24:25], 12, v[192:193]
	v_lshl_add_u64 v[24:25], s[22:23], 0, v[24:25]
	v_lshl_add_u64 v[180:181], v[90:91], 1, v[24:25]
	s_waitcnt vmcnt(0)
	v_pk_mul_f32 v[26:27], v[22:23], v[162:163] op_sel_hi:[0,1]
	v_pk_mul_f32 v[24:25], v[22:23], v[160:161] op_sel_hi:[0,1]
	v_pk_mul_f32 v[30:31], v[22:23], v[166:167] op_sel_hi:[0,1]
	v_pk_mul_f32 v[28:29], v[22:23], v[164:165] op_sel_hi:[0,1]
	v_pk_mul_f32 v[160:161], v[22:23], v[172:173] op_sel_hi:[0,1]
	v_pk_mul_f32 v[32:33], v[22:23], v[168:169] op_sel_hi:[0,1]
	v_pk_mul_f32 v[162:163], v[22:23], v[174:175] op_sel_hi:[0,1]
	v_pk_mul_f32 v[164:165], v[22:23], v[170:171] op_sel_hi:[0,1]
	v_pk_fma_f32 v[24:25], v[86:87], v[24:25], v[44:45]
	v_pk_fma_f32 v[22:23], v[88:89], v[26:27], v[42:43]
	v_pk_fma_f32 v[28:29], v[92:93], v[28:29], v[40:41]
	v_pk_fma_f32 v[26:27], v[94:95], v[30:31], v[38:39]
	v_pk_fma_f32 v[32:33], v[104:105], v[32:33], v[36:37]
	v_pk_fma_f32 v[30:31], v[106:107], v[160:161], v[34:35]
	v_pk_fma_f32 v[8:9], v[110:111], v[164:165], v[8:9]
	v_pk_fma_f32 v[6:7], v[108:109], v[162:163], v[6:7]
	global_store_dwordx4 v[194:195], v[22:25], off nt
	global_store_dwordx4 v[194:195], v[26:29], off offset:16 nt
	v_mul_f32_e32 v164, v23, v23
	v_mul_f32_e32 v165, v25, v25
	v_mul_f32_e32 v166, v27, v27
	v_mul_f32_e32 v167, v29, v29
	v_pk_mul_f32 v[34:35], v[78:79], v[24:25]
	v_pk_mul_f32 v[38:39], v[82:83], v[28:29]
	v_pk_mul_f32 v[40:41], v[84:85], v[26:27]
	v_mul_f32_e32 v27, v31, v31
	v_mul_f32_e32 v29, v33, v33
	v_pk_mul_f32 v[36:37], v[80:81], v[22:23]
	v_mul_f32_e32 v168, v7, v7
	v_mul_f32_e32 v169, v9, v9
	v_fmac_f32_e32 v164, v22, v22
	v_fmac_f32_e32 v165, v24, v24
	v_fmac_f32_e32 v167, v28, v28
	v_cvt_pk_bf16_f32 v22, v36, v37
	v_cvt_pk_bf16_f32 v23, v34, v35
	v_fmac_f32_e32 v27, v30, v30
	v_fmac_f32_e32 v29, v32, v32
	v_lshlrev_b32_e32 v28, 16, v22
	v_and_b32_e32 v34, 0xffff0000, v22
	v_pk_mul_f32 v[160:161], v[100:101], v[8:9]
	v_pk_mul_f32 v[162:163], v[102:103], v[6:7]
	v_fmac_f32_e32 v166, v26, v26
	v_cvt_pk_bf16_f32 v24, v40, v41
	v_cvt_pk_bf16_f32 v25, v38, v39
	v_fmac_f32_e32 v168, v6, v6
	v_fmac_f32_e32 v169, v8, v8
	v_add_f32_e32 v26, v164, v165
	global_store_dwordx4 v[180:181], v[22:25], off sc1
	v_lshlrev_b32_e32 v35, 16, v23
	v_and_b32_e32 v36, 0xffff0000, v23
	global_store_dwordx4 v[194:195], v[30:33], off offset:512 nt
	global_store_dwordx4 v[194:195], v[6:9], off offset:528 nt
	v_lshlrev_b32_e32 v37, 16, v24
	v_and_b32_e32 v38, 0xffff0000, v24
	v_add_f32_e32 v6, v27, v29
	v_max3_f32 v8, |v28|, 0, |v34|
	v_add_f32_e32 v7, v166, v26
	v_add_f32_e32 v6, v168, v6
	v_max3_f32 v8, v8, |v35|, |v36|
	v_lshlrev_b32_e32 v39, 16, v25
	v_and_b32_e32 v40, 0xffff0000, v25
	v_add_f32_e32 v7, v167, v7
	v_add_f32_e32 v6, v169, v6
	v_max3_f32 v8, v8, |v37|, |v38|
	v_pk_mul_f32 v[44:45], v[98:99], v[30:31]
	v_add_f32_e32 v6, v7, v6
	v_cvt_pk_bf16_f32 v22, v44, v45
	v_max3_f32 v7, v8, |v39|, |v40|
	v_lshlrev_b32_e32 v9, 16, v22
	v_and_b32_e32 v26, 0xffff0000, v22
	v_pk_mul_f32 v[42:43], v[96:97], v[32:33]
	v_max3_f32 v7, v7, |v9|, |v26|
	v_cvt_pk_bf16_f32 v23, v42, v43
	v_cvt_pk_bf16_f32 v24, v162, v163
	v_cvt_pk_bf16_f32 v25, v160, v161
	ds_bpermute_b32 v8, v233, v6
	v_lshlrev_b32_e32 v27, 16, v23
	v_and_b32_e32 v28, 0xffff0000, v23
	v_lshlrev_b32_e32 v29, 16, v24
	v_and_b32_e32 v30, 0xffff0000, v24
	v_max3_f32 v7, v7, |v27|, |v28|
	v_lshlrev_b32_e32 v31, 16, v25
	v_and_b32_e32 v32, 0xffff0000, v25
	v_max3_f32 v7, v7, |v29|, |v30|
	v_max3_f32 v9, v7, |v31|, |v32|
	ds_bpermute_b32 v26, v233, v9
	s_waitcnt lgkmcnt(1)
	v_add_f32_e32 v6, v6, v8
	ds_bpermute_b32 v7, v216, v6
	global_store_dwordx4 v[180:181], v[22:25], off offset:256 sc1
	s_waitcnt lgkmcnt(1)
	v_max_f32_e32 v8, v26, v26
	v_max_f32_e32 v8, v9, v8
	ds_bpermute_b32 v9, v216, v8
	s_and_saveexec_b64 s[42:43], s[0:1]
	s_cbranch_execz .LBB0_3625
	s_waitcnt lgkmcnt(0)
	v_max_f32_e32 v9, v9, v9
	v_max_f32_e32 v8, v8, v8
	v_add_f32_e32 v23, v6, v7
	v_lshlrev_b64 v[6:7], 7, v[192:193]
	v_max_f32_e32 v22, v8, v9
	v_lshl_add_u64 v[8:9], s[26:27], 0, v[6:7]
	s_lshl_b64 s[70:71], s[40:41], 2
	v_lshl_add_u64 v[6:7], s[28:29], 0, v[6:7]
	v_lshl_add_u64 v[8:9], v[8:9], 0, s[70:71]
	s_lshl_b32 s12, s59, 2
	v_lshl_add_u64 v[6:7], v[6:7], 0, s[70:71]
	v_lshl_add_u64 v[8:9], v[8:9], 0, s[12:13]
	v_lshl_add_u64 v[6:7], v[6:7], 0, s[12:13]
	global_store_dword v[8:9], v23, off
	global_store_dword v[6:7], v22, off
.LBB0_3625:
	s_or_b64 exec, exec, s[42:43]
	v_or_b32_e32 v36, 16, v176
	v_ashrrev_i32_e32 v37, 31, v36
	s_waitcnt lgkmcnt(1)
	v_lshlrev_b64 v[6:7], 13, v[36:37]
	v_lshl_add_u64 v[6:7], s[16:17], 0, v[6:7]
	v_lshl_add_u64 v[40:41], v[90:91], 2, v[6:7]
	global_load_dwordx4 v[26:29], v[40:41], off offset:16 nt
	global_load_dwordx4 v[30:33], v[40:41], off nt
	s_waitcnt lgkmcnt(0)
	global_load_dwordx4 v[6:9], v[40:41], off offset:528 nt
	global_load_dwordx4 v[22:25], v[40:41], off offset:512 nt
	global_load_dword v34, v[196:197], off offset:512
	v_lshlrev_b64 v[38:39], 12, v[176:177]
	v_lshl_add_u64 v[38:39], s[22:23], 0, v[38:39]
	v_lshl_add_u64 v[38:39], v[90:91], 1, v[38:39]
	s_waitcnt vmcnt(0)
	v_pk_mul_f32 v[44:45], v[34:35], v[128:129] op_sel_hi:[0,1]
	v_pk_mul_f32 v[128:129], v[34:35], v[150:151] op_sel_hi:[0,1]
	v_pk_mul_f32 v[42:43], v[34:35], v[146:147] op_sel_hi:[0,1]
	v_pk_mul_f32 v[146:147], v[34:35], v[148:149] op_sel_hi:[0,1]
	v_pk_mul_f32 v[148:149], v[34:35], v[156:157] op_sel_hi:[0,1]
	v_pk_mul_f32 v[150:151], v[34:35], v[152:153] op_sel_hi:[0,1]
	v_pk_fma_f32 v[14:15], v[94:95], v[128:129], v[14:15]
	v_pk_mul_f32 v[152:153], v[34:35], v[158:159] op_sel_hi:[0,1]
	v_pk_mul_f32 v[34:35], v[34:35], v[154:155] op_sel_hi:[0,1]
	v_pk_fma_f32 v[20:21], v[86:87], v[44:45], v[20:21]
	v_pk_fma_f32 v[18:19], v[88:89], v[42:43], v[18:19]
	v_pk_fma_f32 v[16:17], v[92:93], v[146:147], v[16:17]
	v_pk_fma_f32 v[12:13], v[104:105], v[150:151], v[12:13]
	v_pk_fma_f32 v[10:11], v[106:107], v[148:149], v[10:11]
	v_mul_f32_e32 v156, v15, v15
	v_pk_fma_f32 v[4:5], v[110:111], v[34:35], v[4:5]
	v_pk_fma_f32 v[2:3], v[108:109], v[152:153], v[2:3]
	global_store_dwordx4 v[178:179], v[18:21], off nt
	global_store_dwordx4 v[178:179], v[14:17], off offset:16 nt
	v_mul_f32_e32 v154, v19, v19
	v_mul_f32_e32 v155, v21, v21
	v_mul_f32_e32 v157, v17, v17
	v_pk_mul_f32 v[34:35], v[78:79], v[20:21]
	v_pk_mul_f32 v[42:43], v[80:81], v[18:19]
	v_pk_mul_f32 v[128:129], v[84:85], v[14:15]
	v_mul_f32_e32 v19, v11, v11
	v_mul_f32_e32 v21, v13, v13
	v_fmac_f32_e32 v156, v14, v14
	v_cvt_pk_bf16_f32 v14, v42, v43
	v_pk_mul_f32 v[44:45], v[82:83], v[16:17]
	v_mul_f32_e32 v158, v3, v3
	v_mul_f32_e32 v159, v5, v5
	v_fmac_f32_e32 v154, v18, v18
	v_fmac_f32_e32 v155, v20, v20
	v_fmac_f32_e32 v157, v16, v16
	v_cvt_pk_bf16_f32 v15, v34, v35
	v_cvt_pk_bf16_f32 v16, v128, v129
	v_cvt_pk_bf16_f32 v17, v44, v45
	v_fmac_f32_e32 v19, v10, v10
	v_fmac_f32_e32 v21, v12, v12
	global_store_dwordx4 v[38:39], v[14:17], off sc1
	v_lshlrev_b32_e32 v20, 16, v14
	v_pk_mul_f32 v[150:151], v[100:101], v[4:5]
	v_and_b32_e32 v14, 0xffff0000, v14
	v_pk_mul_f32 v[152:153], v[102:103], v[2:3]
	v_fmac_f32_e32 v158, v2, v2
	v_fmac_f32_e32 v159, v4, v4
	v_add_f32_e32 v18, v154, v155
	v_lshlrev_b32_e32 v34, 16, v15
	v_and_b32_e32 v15, 0xffff0000, v15
	global_store_dwordx4 v[178:179], v[10:13], off offset:512 nt
	global_store_dwordx4 v[178:179], v[2:5], off offset:528 nt
	v_lshlrev_b32_e32 v35, 16, v16
	v_and_b32_e32 v16, 0xffff0000, v16
	v_add_f32_e32 v2, v19, v21
	v_max3_f32 v4, |v20|, 0, |v14|
	v_add_f32_e32 v3, v156, v18
	v_add_f32_e32 v2, v158, v2
	v_max3_f32 v4, v4, |v34|, |v15|
	v_lshlrev_b32_e32 v42, 16, v17
	v_and_b32_e32 v17, 0xffff0000, v17
	v_add_f32_e32 v3, v157, v3
	v_add_f32_e32 v2, v159, v2
	v_max3_f32 v4, v4, |v35|, |v16|
	v_pk_mul_f32 v[148:149], v[98:99], v[10:11]
	v_add_f32_e32 v2, v3, v2
	v_cvt_pk_bf16_f32 v10, v148, v149
	v_max3_f32 v3, v4, |v42|, |v17|
	v_lshlrev_b32_e32 v5, 16, v10
	v_and_b32_e32 v14, 0xffff0000, v10
	v_pk_mul_f32 v[146:147], v[96:97], v[12:13]
	v_max3_f32 v3, v3, |v5|, |v14|
	v_cvt_pk_bf16_f32 v11, v146, v147
	v_cvt_pk_bf16_f32 v12, v152, v153
	v_cvt_pk_bf16_f32 v13, v150, v151
	ds_bpermute_b32 v4, v233, v2
	v_lshlrev_b32_e32 v18, 16, v11
	v_and_b32_e32 v19, 0xffff0000, v11
	v_lshlrev_b32_e32 v20, 16, v12
	v_and_b32_e32 v21, 0xffff0000, v12
	v_max3_f32 v3, v3, |v18|, |v19|
	v_lshlrev_b32_e32 v43, 16, v13
	v_and_b32_e32 v44, 0xffff0000, v13
	v_max3_f32 v3, v3, |v20|, |v21|
	v_max3_f32 v5, v3, |v43|, |v44|
	ds_bpermute_b32 v14, v233, v5
	s_waitcnt lgkmcnt(1)
	v_add_f32_e32 v2, v2, v4
	ds_bpermute_b32 v3, v216, v2
	global_store_dwordx4 v[38:39], v[10:13], off offset:256 sc1
	s_waitcnt lgkmcnt(1)
	v_max_f32_e32 v4, v14, v14
	v_max_f32_e32 v4, v5, v4
	ds_bpermute_b32 v5, v216, v4
	s_and_saveexec_b64 s[42:43], s[0:1]
	s_cbranch_execz .LBB0_3627
	s_waitcnt lgkmcnt(0)
	v_max_f32_e32 v5, v5, v5
	v_max_f32_e32 v4, v4, v4
	v_add_f32_e32 v11, v2, v3
	v_lshlrev_b64 v[2:3], 7, v[176:177]
	v_max_f32_e32 v10, v4, v5
	v_lshl_add_u64 v[4:5], s[26:27], 0, v[2:3]
	s_lshl_b64 s[70:71], s[40:41], 2
	v_lshl_add_u64 v[2:3], s[28:29], 0, v[2:3]
	v_lshl_add_u64 v[4:5], v[4:5], 0, s[70:71]
	s_lshl_b32 s12, s59, 2
	v_lshl_add_u64 v[2:3], v[2:3], 0, s[70:71]
	v_lshl_add_u64 v[4:5], v[4:5], 0, s[12:13]
	v_lshl_add_u64 v[2:3], v[2:3], 0, s[12:13]
	global_store_dword v[4:5], v11, off
	global_store_dword v[2:3], v10, off
.LBB0_3627:
	s_or_b64 exec, exec, s[42:43]
	v_or_b32_e32 v34, 32, v176
	v_ashrrev_i32_e32 v35, 31, v34
	s_waitcnt lgkmcnt(1)
	v_lshlrev_b64 v[2:3], 13, v[34:35]
	v_lshl_add_u64 v[2:3], s[16:17], 0, v[2:3]
	v_lshl_add_u64 v[38:39], v[90:91], 2, v[2:3]
	global_load_dwordx4 v[14:17], v[38:39], off offset:16 nt
	global_load_dwordx4 v[18:21], v[38:39], off nt
	s_waitcnt lgkmcnt(0)
	global_load_dwordx4 v[2:5], v[38:39], off offset:528 nt
	global_load_dwordx4 v[10:13], v[38:39], off offset:512 nt
	v_lshl_add_u64 v[42:43], v[36:37], 2, s[18:19]
	global_load_dword v42, v[42:43], off
	v_lshlrev_b64 v[44:45], 12, v[36:37]
	v_lshl_add_u64 v[44:45], s[22:23], 0, v[44:45]
	v_lshl_add_u64 v[44:45], v[90:91], 1, v[44:45]
	s_waitcnt vmcnt(0)
	v_pk_mul_f32 v[118:119], v[42:43], v[118:119] op_sel_hi:[0,1]
	v_pk_mul_f32 v[114:115], v[42:43], v[114:115] op_sel_hi:[0,1]
	v_pk_mul_f32 v[112:113], v[42:43], v[112:113] op_sel_hi:[0,1]
	v_pk_mul_f32 v[116:117], v[42:43], v[116:117] op_sel_hi:[0,1]
	v_pk_mul_f32 v[124:125], v[42:43], v[124:125] op_sel_hi:[0,1]
	v_pk_mul_f32 v[120:121], v[42:43], v[120:121] op_sel_hi:[0,1]
	v_pk_fma_f32 v[26:27], v[94:95], v[118:119], v[26:27]
	v_pk_mul_f32 v[126:127], v[42:43], v[126:127] op_sel_hi:[0,1]
	v_pk_mul_f32 v[42:43], v[42:43], v[122:123] op_sel_hi:[0,1]
	v_pk_fma_f32 v[32:33], v[86:87], v[112:113], v[32:33]
	v_pk_fma_f32 v[30:31], v[88:89], v[114:115], v[30:31]
	v_pk_fma_f32 v[28:29], v[92:93], v[116:117], v[28:29]
	v_pk_fma_f32 v[24:25], v[104:105], v[120:121], v[24:25]
	v_pk_fma_f32 v[22:23], v[106:107], v[124:125], v[22:23]
	v_mul_f32_e32 v128, v27, v27
	v_pk_fma_f32 v[8:9], v[110:111], v[42:43], v[8:9]
	v_pk_fma_f32 v[6:7], v[108:109], v[126:127], v[6:7]
	global_store_dwordx4 v[40:41], v[30:33], off nt
	global_store_dwordx4 v[40:41], v[26:29], off offset:16 nt
	v_mul_f32_e32 v126, v31, v31
	v_mul_f32_e32 v127, v33, v33
	v_mul_f32_e32 v129, v29, v29
	v_pk_mul_f32 v[42:43], v[78:79], v[32:33]
	v_pk_mul_f32 v[112:113], v[80:81], v[30:31]
	v_pk_mul_f32 v[116:117], v[84:85], v[26:27]
	v_mul_f32_e32 v31, v23, v23
	v_mul_f32_e32 v33, v25, v25
	v_fmac_f32_e32 v128, v26, v26
	v_cvt_pk_bf16_f32 v26, v112, v113
	v_pk_mul_f32 v[114:115], v[82:83], v[28:29]
	v_mul_f32_e32 v146, v7, v7
	v_mul_f32_e32 v147, v9, v9
	v_fmac_f32_e32 v126, v30, v30
	v_fmac_f32_e32 v127, v32, v32
	v_fmac_f32_e32 v129, v28, v28
	v_cvt_pk_bf16_f32 v27, v42, v43
	v_cvt_pk_bf16_f32 v28, v116, v117
	v_cvt_pk_bf16_f32 v29, v114, v115
	v_fmac_f32_e32 v31, v22, v22
	v_fmac_f32_e32 v33, v24, v24
	global_store_dwordx4 v[44:45], v[26:29], off sc1
	v_lshlrev_b32_e32 v32, 16, v26
	v_pk_mul_f32 v[122:123], v[100:101], v[8:9]
	v_and_b32_e32 v26, 0xffff0000, v26
	v_pk_mul_f32 v[124:125], v[102:103], v[6:7]
	v_fmac_f32_e32 v146, v6, v6
	v_fmac_f32_e32 v147, v8, v8
	v_add_f32_e32 v30, v126, v127
	v_lshlrev_b32_e32 v42, 16, v27
	v_and_b32_e32 v27, 0xffff0000, v27
	global_store_dwordx4 v[40:41], v[22:25], off offset:512 nt
	global_store_dwordx4 v[40:41], v[6:9], off offset:528 nt
	v_lshlrev_b32_e32 v43, 16, v28
	v_and_b32_e32 v28, 0xffff0000, v28
	v_add_f32_e32 v6, v31, v33
	v_max3_f32 v8, |v32|, 0, |v26|
	v_add_f32_e32 v7, v128, v30
	v_add_f32_e32 v6, v146, v6
	v_max3_f32 v8, v8, |v42|, |v27|
	v_lshlrev_b32_e32 v112, 16, v29
	v_and_b32_e32 v29, 0xffff0000, v29
	v_add_f32_e32 v7, v129, v7
	v_add_f32_e32 v6, v147, v6
	v_max3_f32 v8, v8, |v43|, |v28|
	v_pk_mul_f32 v[120:121], v[98:99], v[22:23]
	v_add_f32_e32 v6, v7, v6
	v_cvt_pk_bf16_f32 v22, v120, v121
	v_max3_f32 v7, v8, |v112|, |v29|
	v_lshlrev_b32_e32 v9, 16, v22
	v_and_b32_e32 v26, 0xffff0000, v22
	v_pk_mul_f32 v[118:119], v[96:97], v[24:25]
	v_max3_f32 v7, v7, |v9|, |v26|
	v_cvt_pk_bf16_f32 v23, v118, v119
	v_cvt_pk_bf16_f32 v24, v124, v125
	v_cvt_pk_bf16_f32 v25, v122, v123
	ds_bpermute_b32 v8, v233, v6
	v_lshlrev_b32_e32 v30, 16, v23
	v_and_b32_e32 v31, 0xffff0000, v23
	v_lshlrev_b32_e32 v32, 16, v24
	v_and_b32_e32 v33, 0xffff0000, v24
	v_max3_f32 v7, v7, |v30|, |v31|
	v_lshlrev_b32_e32 v40, 16, v25
	v_and_b32_e32 v41, 0xffff0000, v25
	v_max3_f32 v7, v7, |v32|, |v33|
	v_max3_f32 v9, v7, |v40|, |v41|
	ds_bpermute_b32 v26, v233, v9
	s_waitcnt lgkmcnt(1)
	v_add_f32_e32 v6, v6, v8
	ds_bpermute_b32 v7, v216, v6
	global_store_dwordx4 v[44:45], v[22:25], off offset:256 sc1
	s_waitcnt lgkmcnt(1)
	v_max_f32_e32 v8, v26, v26
	v_max_f32_e32 v8, v9, v8
	ds_bpermute_b32 v9, v216, v8
	s_and_saveexec_b64 s[42:43], s[0:1]
	s_cbranch_execz .LBB0_3629
	s_waitcnt lgkmcnt(0)
	v_max_f32_e32 v9, v9, v9
	v_max_f32_e32 v8, v8, v8
	v_add_f32_e32 v23, v6, v7
	v_lshlrev_b64 v[6:7], 7, v[36:37]
	v_max_f32_e32 v22, v8, v9
	v_lshl_add_u64 v[8:9], s[26:27], 0, v[6:7]
	s_lshl_b64 s[70:71], s[40:41], 2
	v_lshl_add_u64 v[6:7], s[28:29], 0, v[6:7]
	v_lshl_add_u64 v[8:9], v[8:9], 0, s[70:71]
	s_lshl_b32 s12, s59, 2
	v_lshl_add_u64 v[6:7], v[6:7], 0, s[70:71]
	v_lshl_add_u64 v[8:9], v[8:9], 0, s[12:13]
	v_lshl_add_u64 v[6:7], v[6:7], 0, s[12:13]
	global_store_dword v[8:9], v23, off
	global_store_dword v[6:7], v22, off
.LBB0_3629:
	s_or_b64 exec, exec, s[42:43]
	v_or_b32_e32 v36, 48, v176
	v_ashrrev_i32_e32 v37, 31, v36
	s_waitcnt lgkmcnt(1)
	v_lshlrev_b64 v[6:7], 13, v[36:37]
	v_lshl_add_u64 v[6:7], s[16:17], 0, v[6:7]
	v_lshl_add_u64 v[40:41], v[90:91], 2, v[6:7]
	global_load_dwordx4 v[26:29], v[40:41], off offset:16 nt
	global_load_dwordx4 v[30:33], v[40:41], off nt
	s_waitcnt lgkmcnt(0)
	global_load_dwordx4 v[6:9], v[40:41], off offset:528 nt
	global_load_dwordx4 v[22:25], v[40:41], off offset:512 nt
	v_lshl_add_u64 v[42:43], v[34:35], 2, s[18:19]
	global_load_dword v42, v[42:43], off
	v_lshlrev_b64 v[44:45], 12, v[34:35]
	v_lshl_add_u64 v[44:45], s[22:23], 0, v[44:45]
	v_lshl_add_u64 v[44:45], v[90:91], 1, v[44:45]
	s_waitcnt vmcnt(0)
	v_pk_mul_f32 v[68:69], v[42:43], v[68:69] op_sel_hi:[0,1]
	v_pk_mul_f32 v[64:65], v[42:43], v[64:65] op_sel_hi:[0,1]
	v_pk_mul_f32 v[62:63], v[42:43], v[62:63] op_sel_hi:[0,1]
	v_pk_mul_f32 v[66:67], v[42:43], v[66:67] op_sel_hi:[0,1]
	v_pk_mul_f32 v[74:75], v[42:43], v[74:75] op_sel_hi:[0,1]
	v_pk_mul_f32 v[70:71], v[42:43], v[70:71] op_sel_hi:[0,1]
	v_pk_fma_f32 v[14:15], v[94:95], v[68:69], v[14:15]
	v_pk_mul_f32 v[76:77], v[42:43], v[76:77] op_sel_hi:[0,1]
	v_pk_mul_f32 v[42:43], v[42:43], v[72:73] op_sel_hi:[0,1]
	v_pk_fma_f32 v[20:21], v[86:87], v[62:63], v[20:21]
	v_pk_fma_f32 v[18:19], v[88:89], v[64:65], v[18:19]
	v_pk_fma_f32 v[16:17], v[92:93], v[66:67], v[16:17]
	v_pk_fma_f32 v[12:13], v[104:105], v[70:71], v[12:13]
	v_pk_fma_f32 v[10:11], v[106:107], v[74:75], v[10:11]
	v_mul_f32_e32 v112, v15, v15
	v_pk_fma_f32 v[4:5], v[110:111], v[42:43], v[4:5]
	v_pk_fma_f32 v[2:3], v[108:109], v[76:77], v[2:3]
	global_store_dwordx4 v[38:39], v[18:21], off nt
	global_store_dwordx4 v[38:39], v[14:17], off offset:16 nt
	v_mul_f32_e32 v76, v19, v19
	v_mul_f32_e32 v77, v21, v21
	v_mul_f32_e32 v113, v17, v17
	v_pk_mul_f32 v[42:43], v[78:79], v[20:21]
	v_pk_mul_f32 v[62:63], v[80:81], v[18:19]
	v_pk_mul_f32 v[66:67], v[84:85], v[14:15]
	v_mul_f32_e32 v19, v11, v11
	v_mul_f32_e32 v21, v13, v13
	v_fmac_f32_e32 v112, v14, v14
	v_cvt_pk_bf16_f32 v14, v62, v63
	v_pk_mul_f32 v[64:65], v[82:83], v[16:17]
	v_mul_f32_e32 v114, v3, v3
	v_mul_f32_e32 v115, v5, v5
	v_fmac_f32_e32 v76, v18, v18
	v_fmac_f32_e32 v77, v20, v20
	v_fmac_f32_e32 v113, v16, v16
	v_cvt_pk_bf16_f32 v15, v42, v43
	v_cvt_pk_bf16_f32 v16, v66, v67
	v_cvt_pk_bf16_f32 v17, v64, v65
	v_fmac_f32_e32 v19, v10, v10
	v_fmac_f32_e32 v21, v12, v12
	global_store_dwordx4 v[44:45], v[14:17], off sc1
	v_lshlrev_b32_e32 v20, 16, v14
	v_pk_mul_f32 v[72:73], v[100:101], v[4:5]
	v_and_b32_e32 v14, 0xffff0000, v14
	v_pk_mul_f32 v[74:75], v[102:103], v[2:3]
	v_fmac_f32_e32 v114, v2, v2
	v_fmac_f32_e32 v115, v4, v4
	v_add_f32_e32 v18, v76, v77
	v_lshlrev_b32_e32 v42, 16, v15
	v_and_b32_e32 v15, 0xffff0000, v15
	global_store_dwordx4 v[38:39], v[10:13], off offset:512 nt
	global_store_dwordx4 v[38:39], v[2:5], off offset:528 nt
	v_lshlrev_b32_e32 v43, 16, v16
	v_and_b32_e32 v16, 0xffff0000, v16
	v_add_f32_e32 v2, v19, v21
	v_max3_f32 v4, |v20|, 0, |v14|
	v_add_f32_e32 v3, v112, v18
	v_add_f32_e32 v2, v114, v2
	v_max3_f32 v4, v4, |v42|, |v15|
	v_lshlrev_b32_e32 v62, 16, v17
	v_and_b32_e32 v17, 0xffff0000, v17
	v_add_f32_e32 v3, v113, v3
	v_add_f32_e32 v2, v115, v2
	v_max3_f32 v4, v4, |v43|, |v16|
	v_pk_mul_f32 v[70:71], v[98:99], v[10:11]
	v_add_f32_e32 v2, v3, v2
	v_cvt_pk_bf16_f32 v10, v70, v71
	v_max3_f32 v3, v4, |v62|, |v17|
	v_lshlrev_b32_e32 v5, 16, v10
	v_and_b32_e32 v14, 0xffff0000, v10
	v_pk_mul_f32 v[68:69], v[96:97], v[12:13]
	v_max3_f32 v3, v3, |v5|, |v14|
	v_cvt_pk_bf16_f32 v11, v68, v69
	v_cvt_pk_bf16_f32 v12, v74, v75
	v_cvt_pk_bf16_f32 v13, v72, v73
	ds_bpermute_b32 v4, v233, v2
	v_lshlrev_b32_e32 v18, 16, v11
	v_and_b32_e32 v19, 0xffff0000, v11
	v_lshlrev_b32_e32 v20, 16, v12
	v_and_b32_e32 v21, 0xffff0000, v12
	v_max3_f32 v3, v3, |v18|, |v19|
	v_lshlrev_b32_e32 v38, 16, v13
	v_and_b32_e32 v39, 0xffff0000, v13
	v_max3_f32 v3, v3, |v20|, |v21|
	v_max3_f32 v5, v3, |v38|, |v39|
	ds_bpermute_b32 v14, v233, v5
	s_waitcnt lgkmcnt(1)
	v_add_f32_e32 v2, v2, v4
	ds_bpermute_b32 v3, v216, v2
	global_store_dwordx4 v[44:45], v[10:13], off offset:256 sc1
	s_waitcnt lgkmcnt(1)
	v_max_f32_e32 v4, v14, v14
	v_max_f32_e32 v4, v5, v4
	ds_bpermute_b32 v5, v216, v4
	s_and_saveexec_b64 s[42:43], s[0:1]
	s_cbranch_execz .LBB0_3631
	s_waitcnt lgkmcnt(0)
	v_max_f32_e32 v5, v5, v5
	v_max_f32_e32 v4, v4, v4
	v_add_f32_e32 v11, v2, v3
	v_lshlrev_b64 v[2:3], 7, v[34:35]
	v_max_f32_e32 v10, v4, v5
	v_lshl_add_u64 v[4:5], s[26:27], 0, v[2:3]
	s_lshl_b64 s[70:71], s[40:41], 2
	v_lshl_add_u64 v[2:3], s[28:29], 0, v[2:3]
	v_lshl_add_u64 v[4:5], v[4:5], 0, s[70:71]
	s_lshl_b32 s12, s59, 2
	v_lshl_add_u64 v[2:3], v[2:3], 0, s[70:71]
	v_lshl_add_u64 v[4:5], v[4:5], 0, s[12:13]
	v_lshl_add_u64 v[2:3], v[2:3], 0, s[12:13]
	global_store_dword v[4:5], v11, off
	global_store_dword v[2:3], v10, off
.LBB0_3631:
	s_or_b64 exec, exec, s[42:43]
	s_waitcnt lgkmcnt(1)
	v_lshl_add_u64 v[2:3], v[36:37], 2, s[18:19]
	global_load_dword v2, v[2:3], off
	s_waitcnt lgkmcnt(0)
	v_lshlrev_b64 v[4:5], 12, v[36:37]
	v_lshl_add_u64 v[4:5], s[22:23], 0, v[4:5]
	v_lshl_add_u64 v[18:19], v[90:91], 1, v[4:5]
	s_waitcnt vmcnt(0)
	v_pk_mul_f32 v[10:11], v[2:3], v[48:49] op_sel_hi:[0,1]
	v_pk_mul_f32 v[4:5], v[2:3], v[46:47] op_sel_hi:[0,1]
	v_pk_mul_f32 v[14:15], v[2:3], v[52:53] op_sel_hi:[0,1]
	v_pk_mul_f32 v[12:13], v[2:3], v[50:51] op_sel_hi:[0,1]
	v_pk_mul_f32 v[20:21], v[2:3], v[58:59] op_sel_hi:[0,1]
	v_pk_mul_f32 v[16:17], v[2:3], v[54:55] op_sel_hi:[0,1]
	v_pk_mul_f32 v[34:35], v[2:3], v[60:61] op_sel_hi:[0,1]
	v_pk_mul_f32 v[38:39], v[2:3], v[56:57] op_sel_hi:[0,1]
	v_pk_fma_f32 v[2:3], v[88:89], v[10:11], v[30:31]
	v_pk_fma_f32 v[4:5], v[86:87], v[4:5], v[32:33]
	v_pk_fma_f32 v[12:13], v[92:93], v[12:13], v[28:29]
	v_pk_fma_f32 v[8:9], v[110:111], v[38:39], v[8:9]
	v_mul_f32_e32 v38, v3, v3
	v_pk_fma_f32 v[10:11], v[94:95], v[14:15], v[26:27]
	v_pk_fma_f32 v[14:15], v[106:107], v[20:21], v[22:23]
	global_store_dwordx4 v[40:41], v[2:5], off nt
	global_store_dwordx4 v[40:41], v[10:13], off offset:16 nt
	v_mul_f32_e32 v39, v5, v5
	v_mul_f32_e32 v43, v13, v13
	v_pk_mul_f32 v[22:23], v[80:81], v[2:3]
	v_fmac_f32_e32 v38, v2, v2
	v_cvt_pk_bf16_f32 v2, v22, v23
	v_pk_fma_f32 v[16:17], v[104:105], v[16:17], v[24:25]
	v_pk_mul_f32 v[20:21], v[78:79], v[4:5]
	v_pk_mul_f32 v[24:25], v[82:83], v[12:13]
	v_pk_mul_f32 v[26:27], v[84:85], v[10:11]
	v_fmac_f32_e32 v39, v4, v4
	v_fmac_f32_e32 v43, v12, v12
	v_cvt_pk_bf16_f32 v3, v20, v21
	v_cvt_pk_bf16_f32 v4, v26, v27
	v_cvt_pk_bf16_f32 v5, v24, v25
	global_store_dwordx4 v[18:19], v[2:5], off sc1
	v_lshlrev_b32_e32 v12, 16, v2
	v_lshlrev_b32_e32 v20, 16, v3
	v_and_b32_e32 v2, 0xffff0000, v2
	v_and_b32_e32 v3, 0xffff0000, v3
	v_max3_f32 v2, |v12|, 0, |v2|
	v_pk_fma_f32 v[6:7], v[108:109], v[34:35], v[6:7]
	v_mul_f32_e32 v42, v11, v11
	v_mul_f32_e32 v11, v15, v15
	v_mul_f32_e32 v13, v17, v17
	v_lshlrev_b32_e32 v21, 16, v4
	v_and_b32_e32 v4, 0xffff0000, v4
	v_max3_f32 v2, v2, |v20|, |v3|
	v_mul_f32_e32 v44, v7, v7
	v_fmac_f32_e32 v11, v14, v14
	v_fmac_f32_e32 v13, v16, v16
	v_lshlrev_b32_e32 v22, 16, v5
	v_and_b32_e32 v5, 0xffff0000, v5
	v_max3_f32 v2, v2, |v21|, |v4|
	v_pk_mul_f32 v[30:31], v[98:99], v[14:15]
	v_pk_mul_f32 v[34:35], v[102:103], v[6:7]
	v_fmac_f32_e32 v44, v6, v6
	global_store_dwordx4 v[40:41], v[14:17], off offset:512 nt
	global_store_dwordx4 v[40:41], v[6:9], off offset:528 nt
	v_add_f32_e32 v11, v11, v13
	v_max3_f32 v2, v2, |v22|, |v5|
	v_cvt_pk_bf16_f32 v6, v30, v31
	v_mul_f32_e32 v45, v9, v9
	v_lshlrev_b32_e32 v12, 16, v6
	v_and_b32_e32 v13, 0xffff0000, v6
	v_pk_mul_f32 v[28:29], v[96:97], v[16:17]
	v_fmac_f32_e32 v42, v10, v10
	v_add_f32_e32 v10, v38, v39
	v_cvt_pk_bf16_f32 v7, v28, v29
	v_max3_f32 v2, v2, |v12|, |v13|
	v_lshlrev_b32_e32 v14, 16, v7
	v_and_b32_e32 v15, 0xffff0000, v7
	v_pk_mul_f32 v[32:33], v[100:101], v[8:9]
	v_fmac_f32_e32 v45, v8, v8
	v_cvt_pk_bf16_f32 v8, v34, v35
	v_add_f32_e32 v10, v42, v10
	v_add_f32_e32 v11, v44, v11
	v_lshlrev_b32_e32 v16, 16, v8
	v_and_b32_e32 v17, 0xffff0000, v8
	v_max3_f32 v2, v2, |v14|, |v15|
	v_cvt_pk_bf16_f32 v9, v32, v33
	v_add_f32_e32 v10, v43, v10
	v_lshlrev_b32_e32 v23, 16, v9
	v_and_b32_e32 v24, 0xffff0000, v9
	v_add_f32_e32 v3, v45, v11
	v_max3_f32 v2, v2, |v16|, |v17|
	v_add_f32_e32 v3, v10, v3
	v_max3_f32 v5, v2, |v23|, |v24|
	ds_bpermute_b32 v4, v233, v3
	ds_bpermute_b32 v10, v233, v5
	global_store_dwordx4 v[18:19], v[6:9], off offset:256 sc1
	s_waitcnt lgkmcnt(1)
	v_add_f32_e32 v2, v3, v4
	s_waitcnt lgkmcnt(0)
	v_max_f32_e32 v4, v10, v10
	v_max_f32_e32 v4, v5, v4
	ds_bpermute_b32 v3, v216, v2
	ds_bpermute_b32 v5, v216, v4
	s_and_saveexec_b64 s[42:43], s[0:1]
	s_cbranch_execz .LBB0_3633
	s_waitcnt lgkmcnt(0)
	v_max_f32_e32 v5, v5, v5
	v_max_f32_e32 v4, v4, v4
	v_add_f32_e32 v7, v2, v3
	v_lshlrev_b64 v[2:3], 7, v[36:37]
	v_max_f32_e32 v6, v4, v5
	v_lshl_add_u64 v[4:5], s[26:27], 0, v[2:3]
	s_lshl_b64 s[40:41], s[40:41], 2
	v_lshl_add_u64 v[2:3], s[28:29], 0, v[2:3]
	v_lshl_add_u64 v[4:5], v[4:5], 0, s[40:41]
	s_lshl_b32 s12, s59, 2
	v_lshl_add_u64 v[2:3], v[2:3], 0, s[40:41]
	v_lshl_add_u64 v[4:5], v[4:5], 0, s[12:13]
	v_lshl_add_u64 v[2:3], v[2:3], 0, s[12:13]
	global_store_dword v[4:5], v7, off
	global_store_dword v[2:3], v6, off

.LBB0_3802:
	s_lshl_b32 s26, s30, 8
	s_add_i32 s28, s26, s52
	s_lshl_b32 s26, s31, 8
	s_or_b32 s29, s26, s53
	s_lshr_b32 s26, s30, 4
	s_add_i32 s26, s26, -1
	v_or_b32_e32 v2, s29, v186
	s_cmp_gt_i32 s30, 31
	s_cselect_b32 s26, s26, 0
	v_ashrrev_i32_e32 v3, 31, v2
	v_or_b32_e32 v168, s28, v187
	v_lshlrev_b64 v[10:11], 2, v[2:3]
	v_ashrrev_i32_e32 v169, 31, v168
	s_ashr_i32 s27, s26, 31
	v_lshl_add_u64 v[12:13], s[16:17], 0, v[10:11]
	v_lshl_add_u64 v[100:101], v[168:169], 2, s[14:15]
	s_lshl_b64 s[26:27], s[26:27], 15
	global_load_dwordx4 v[2:5], v[12:13], off offset:16
	global_load_dwordx4 v[6:9], v[12:13], off
	global_load_dword v190, v[100:101], off
	s_add_u32 s26, s47, s26
	global_load_dwordx4 v[14:17], v[12:13], off offset:528
	global_load_dwordx4 v[30:33], v[12:13], off offset:512
	s_addc_u32 s27, s48, s27
	v_lshl_add_u64 v[10:11], s[26:27], 0, v[10:11]
	global_load_dwordx4 v[26:29], v[10:11], off
	global_load_dwordx4 v[22:25], v[10:11], off offset:16
	global_load_dwordx4 v[18:21], v[10:11], off offset:512
	s_nop 0
	global_load_dwordx4 v[10:13], v[10:11], off offset:528
	s_ashr_i32 s28, s28, 8
	v_bitop3_b32 v90, s29, 56, v186 bitop3:0xc8
	s_ashr_i32 s26, s29, 6
	s_ashr_i32 s29, s28, 31
	s_ashr_i32 s27, s26, 31
	s_lshl_b64 s[34:35], s[28:29], 7
	s_add_u32 s28, s34, s26
	s_addc_u32 s29, s35, s27
	s_lshl_b64 s[28:29], s[28:29], 15
	s_add_u32 s30, s12, s28
	s_addc_u32 s31, s13, s29
	s_or_b32 s28, s26, 2
	s_ashr_i32 s29, s28, 31
	s_add_u32 s34, s34, s28
	v_lshlrev_b32_e32 v169, 7, v168
	s_addc_u32 s35, s35, s29
	v_and_b32_e32 v138, 0x6780, v169
	s_lshl_b64 s[34:35], s[34:35], 15
	v_mov_b32_e32 v91, v139
	v_lshlrev_b32_e32 v90, 1, v90
	v_lshl_add_u64 v[192:193], s[30:31], 0, v[138:139]
	s_add_u32 s34, s12, s34
	v_lshl_add_u64 v[192:193], v[192:193], 0, v[90:91]
	s_addc_u32 s35, s13, s35
	s_and_b64 vcc, exec, s[0:1]
	s_mov_b64 s[0:1], -1
	s_waitcnt vmcnt(0)
	v_pk_mul_f32 v[194:195], v[6:7], v[190:191] op_sel_hi:[1,0]
	v_pk_mul_f32 v[196:197], v[8:9], v[190:191] op_sel_hi:[1,0]
	v_pk_mul_f32 v[198:199], v[2:3], v[190:191] op_sel_hi:[1,0]
	v_pk_mul_f32 v[204:205], v[32:33], v[190:191] op_sel_hi:[1,0]
	v_pk_fma_f32 v[170:171], v[196:197], v[170:171], v[28:29]
	v_pk_fma_f32 v[172:173], v[194:195], v[172:173], v[26:27]
	v_pk_mul_f32 v[200:201], v[4:5], v[190:191] op_sel_hi:[1,0]
	v_pk_mul_f32 v[202:203], v[30:31], v[190:191] op_sel_hi:[1,0]
	v_pk_mul_f32 v[206:207], v[14:15], v[190:191] op_sel_hi:[1,0]
	v_pk_mul_f32 v[190:191], v[16:17], v[190:191] op_sel_hi:[1,0]
	v_pk_fma_f32 v[174:175], v[198:199], v[174:175], v[22:23]
	v_pk_fma_f32 v[182:183], v[204:205], v[182:183], v[20:21]
	v_max_f32_e32 v173, 0, v173
	v_max_f32_e32 v172, 0, v172
	v_max_f32_e32 v171, 0, v171
	v_max_f32_e32 v170, 0, v170
	v_pk_fma_f32 v[176:177], v[200:201], v[176:177], v[24:25]
	v_pk_fma_f32 v[180:181], v[202:203], v[180:181], v[18:19]
	v_pk_fma_f32 v[184:185], v[190:191], v[184:185], v[12:13]
	v_max_f32_e32 v175, 0, v175
	v_max_f32_e32 v174, 0, v174
	v_max_f32_e32 v183, 0, v183
	v_max_f32_e32 v182, 0, v182
	v_pk_mul_f32 v[190:191], v[170:171], v[170:171]
	v_pk_mul_f32 v[170:171], v[172:173], v[172:173]
	v_max_f32_e32 v177, 0, v177
	v_max_f32_e32 v176, 0, v176
	v_max_f32_e32 v181, 0, v181
	v_max_f32_e32 v180, 0, v180
	v_pk_mul_f32 v[172:173], v[174:175], v[174:175]
	v_pk_mul_f32 v[174:175], v[182:183], v[182:183]
	v_cvt_pk_bf16_f32 v170, v170, v171
	v_cvt_pk_bf16_f32 v171, v190, v191
	v_pk_fma_f32 v[178:179], v[206:207], v[178:179], v[10:11]
	v_pk_mul_f32 v[176:177], v[176:177], v[176:177]
	v_pk_mul_f32 v[180:181], v[180:181], v[180:181]
	v_cvt_pk_bf16_f32 v172, v172, v173
	v_cvt_pk_bf16_f32 v173, v176, v177
	global_store_dwordx4 v[192:193], v[170:173], off sc1
	v_max_f32_e32 v179, 0, v179
	v_max_f32_e32 v178, 0, v178
	v_cvt_pk_bf16_f32 v170, v180, v181
	v_cvt_pk_bf16_f32 v171, v174, v175
	v_lshl_add_u64 v[174:175], s[34:35], 0, v[138:139]
	v_max_f32_e32 v185, 0, v185
	v_max_f32_e32 v184, 0, v184
	v_lshl_add_u64 v[174:175], v[174:175], 0, v[90:91]
	v_pk_mul_f32 v[182:183], v[184:185], v[184:185]
	v_pk_mul_f32 v[178:179], v[178:179], v[178:179]
	s_nop 0
	v_cvt_pk_bf16_f32 v172, v178, v179
	v_cvt_pk_bf16_f32 v173, v182, v183
	global_store_dwordx4 v[174:175], v[170:173], off sc1
	v_or_b32_e32 v174, 32, v168
	v_ashrrev_i32_e32 v175, 31, v174
	v_or_b32_e32 v170, 16, v168
	v_ashrrev_i32_e32 v171, 31, v170
	v_lshl_add_u64 v[172:173], v[170:171], 2, s[14:15]
	global_load_dword v172, v[172:173], off
	v_lshlrev_b32_e32 v138, 7, v170
	v_and_b32_e32 v138, 0x6f80, v138
	v_lshl_add_u64 v[176:177], s[30:31], 0, v[138:139]
	v_lshl_add_u64 v[178:179], s[34:35], 0, v[138:139]
	v_lshl_add_u64 v[176:177], v[176:177], 0, v[90:91]
	v_lshl_add_u64 v[178:179], v[178:179], 0, v[90:91]
	v_lshl_add_u64 v[170:171], v[174:175], 2, s[14:15]
	v_lshlrev_b32_e32 v138, 7, v174
	v_and_b32_e32 v138, 0x7780, v138
	s_waitcnt vmcnt(0)
	v_pk_mul_f32 v[180:181], v[6:7], v[172:173] op_sel_hi:[1,0]
	v_pk_mul_f32 v[182:183], v[8:9], v[172:173] op_sel_hi:[1,0]
	v_pk_mul_f32 v[184:185], v[2:3], v[172:173] op_sel_hi:[1,0]
	v_pk_mul_f32 v[190:191], v[4:5], v[172:173] op_sel_hi:[1,0]
	v_pk_fma_f32 v[154:155], v[182:183], v[154:155], v[28:29]
	v_pk_fma_f32 v[152:153], v[180:181], v[152:153], v[26:27]
	v_pk_mul_f32 v[192:193], v[30:31], v[172:173] op_sel_hi:[1,0]
	v_pk_mul_f32 v[194:195], v[32:33], v[172:173] op_sel_hi:[1,0]
	v_pk_mul_f32 v[196:197], v[14:15], v[172:173] op_sel_hi:[1,0]
	v_pk_mul_f32 v[172:173], v[16:17], v[172:173] op_sel_hi:[1,0]
	v_pk_fma_f32 v[158:159], v[190:191], v[158:159], v[24:25]
	v_pk_fma_f32 v[156:157], v[184:185], v[156:157], v[22:23]
	v_max_f32_e32 v153, 0, v153
	v_max_f32_e32 v152, 0, v152
	v_max_f32_e32 v155, 0, v155
	v_max_f32_e32 v154, 0, v154
	v_pk_fma_f32 v[162:163], v[194:195], v[162:163], v[20:21]
	v_pk_fma_f32 v[160:161], v[192:193], v[160:161], v[18:19]
	v_pk_fma_f32 v[166:167], v[172:173], v[166:167], v[12:13]
	v_pk_fma_f32 v[164:165], v[196:197], v[164:165], v[10:11]
	v_max_f32_e32 v157, 0, v157
	v_max_f32_e32 v156, 0, v156
	v_max_f32_e32 v159, 0, v159
	v_max_f32_e32 v158, 0, v158
	v_pk_mul_f32 v[154:155], v[154:155], v[154:155]
	v_pk_mul_f32 v[152:153], v[152:153], v[152:153]
	v_max_f32_e32 v161, 0, v161
	v_max_f32_e32 v160, 0, v160
	v_max_f32_e32 v163, 0, v163
	v_max_f32_e32 v162, 0, v162
	v_max_f32_e32 v165, 0, v165
	v_max_f32_e32 v164, 0, v164
	v_max_f32_e32 v167, 0, v167
	v_max_f32_e32 v166, 0, v166
	v_pk_mul_f32 v[158:159], v[158:159], v[158:159]
	v_pk_mul_f32 v[156:157], v[156:157], v[156:157]
	v_cvt_pk_bf16_f32 v152, v152, v153
	v_cvt_pk_bf16_f32 v153, v154, v155
	v_pk_mul_f32 v[162:163], v[162:163], v[162:163]
	v_cvt_pk_bf16_f32 v154, v156, v157
	v_cvt_pk_bf16_f32 v155, v158, v159
	v_pk_mul_f32 v[160:161], v[160:161], v[160:161]
	v_pk_mul_f32 v[166:167], v[166:167], v[166:167]
	v_pk_mul_f32 v[164:165], v[164:165], v[164:165]
	global_store_dwordx4 v[176:177], v[152:155], off sc1
	v_lshl_add_u64 v[158:159], s[30:31], 0, v[138:139]
	v_lshl_add_u64 v[158:159], v[158:159], 0, v[90:91]
	v_cvt_pk_bf16_f32 v152, v160, v161
	v_cvt_pk_bf16_f32 v153, v162, v163
	v_cvt_pk_bf16_f32 v154, v164, v165
	v_cvt_pk_bf16_f32 v155, v166, v167
	global_store_dwordx4 v[178:179], v[152:155], off sc1
	global_load_dword v152, v[170:171], off
	v_lshl_add_u64 v[160:161], s[34:35], 0, v[138:139]
	v_or_b32_e32 v154, 48, v168
	v_ashrrev_i32_e32 v155, 31, v154
	v_lshl_add_u64 v[160:161], v[160:161], 0, v[90:91]
	v_lshl_add_u64 v[156:157], v[154:155], 2, s[14:15]
	s_waitcnt vmcnt(0)
	v_pk_mul_f32 v[162:163], v[6:7], v[152:153] op_sel_hi:[1,0]
	v_pk_mul_f32 v[164:165], v[8:9], v[152:153] op_sel_hi:[1,0]
	v_pk_mul_f32 v[166:167], v[2:3], v[152:153] op_sel_hi:[1,0]
	v_pk_mul_f32 v[170:171], v[4:5], v[152:153] op_sel_hi:[1,0]
	v_pk_fma_f32 v[120:121], v[164:165], v[120:121], v[28:29]
	v_pk_fma_f32 v[118:119], v[162:163], v[118:119], v[26:27]
	v_pk_mul_f32 v[172:173], v[30:31], v[152:153] op_sel_hi:[1,0]
	v_pk_mul_f32 v[174:175], v[32:33], v[152:153] op_sel_hi:[1,0]
	v_pk_mul_f32 v[176:177], v[14:15], v[152:153] op_sel_hi:[1,0]
	v_pk_mul_f32 v[152:153], v[16:17], v[152:153] op_sel_hi:[1,0]
	v_pk_fma_f32 v[124:125], v[170:171], v[124:125], v[24:25]
	v_pk_fma_f32 v[122:123], v[166:167], v[122:123], v[22:23]
	v_max_f32_e32 v119, 0, v119
	v_max_f32_e32 v118, 0, v118
	v_max_f32_e32 v121, 0, v121
	v_max_f32_e32 v120, 0, v120
	v_pk_fma_f32 v[128:129], v[174:175], v[128:129], v[20:21]
	v_pk_fma_f32 v[126:127], v[172:173], v[126:127], v[18:19]
	v_pk_fma_f32 v[150:151], v[152:153], v[150:151], v[12:13]
	v_pk_fma_f32 v[148:149], v[176:177], v[148:149], v[10:11]
	v_max_f32_e32 v123, 0, v123
	v_max_f32_e32 v122, 0, v122
	v_max_f32_e32 v125, 0, v125
	v_max_f32_e32 v124, 0, v124
	v_pk_mul_f32 v[120:121], v[120:121], v[120:121]
	v_pk_mul_f32 v[118:119], v[118:119], v[118:119]
	v_max_f32_e32 v127, 0, v127
	v_max_f32_e32 v126, 0, v126
	v_max_f32_e32 v129, 0, v129
	v_max_f32_e32 v128, 0, v128
	v_max_f32_e32 v149, 0, v149
	v_max_f32_e32 v148, 0, v148
	v_max_f32_e32 v151, 0, v151
	v_max_f32_e32 v150, 0, v150
	v_pk_mul_f32 v[124:125], v[124:125], v[124:125]
	v_pk_mul_f32 v[122:123], v[122:123], v[122:123]
	v_cvt_pk_bf16_f32 v118, v118, v119
	v_cvt_pk_bf16_f32 v119, v120, v121
	v_pk_mul_f32 v[128:129], v[128:129], v[128:129]
	v_cvt_pk_bf16_f32 v120, v122, v123
	v_cvt_pk_bf16_f32 v121, v124, v125
	v_pk_mul_f32 v[126:127], v[126:127], v[126:127]
	v_pk_mul_f32 v[150:151], v[150:151], v[150:151]
	v_pk_mul_f32 v[148:149], v[148:149], v[148:149]
	global_store_dwordx4 v[158:159], v[118:121], off sc1
	s_nop 1
	v_cvt_pk_bf16_f32 v118, v126, v127
	v_cvt_pk_bf16_f32 v119, v128, v129
	v_cvt_pk_bf16_f32 v120, v148, v149
	v_cvt_pk_bf16_f32 v121, v150, v151
	global_store_dwordx4 v[160:161], v[118:121], off sc1
	global_load_dword v118, v[156:157], off
	s_nop 0
	v_lshlrev_b32_e32 v119, 7, v154
	v_and_b32_e32 v138, 0x7f80, v119
	v_lshl_add_u64 v[120:121], s[30:31], 0, v[138:139]
	v_lshl_add_u64 v[122:123], s[34:35], 0, v[138:139]
	v_lshl_add_u64 v[120:121], v[120:121], 0, v[90:91]
	v_lshl_add_u64 v[122:123], v[122:123], 0, v[90:91]
	s_waitcnt vmcnt(0)
	v_pk_mul_f32 v[124:125], v[6:7], v[118:119] op_sel_hi:[1,0]
	v_pk_mul_f32 v[126:127], v[8:9], v[118:119] op_sel_hi:[1,0]
	v_pk_mul_f32 v[128:129], v[2:3], v[118:119] op_sel_hi:[1,0]
	v_pk_mul_f32 v[148:149], v[4:5], v[118:119] op_sel_hi:[1,0]
	v_pk_fma_f32 v[104:105], v[126:127], v[104:105], v[28:29]
	v_pk_fma_f32 v[102:103], v[124:125], v[102:103], v[26:27]
	v_pk_mul_f32 v[150:151], v[30:31], v[118:119] op_sel_hi:[1,0]
	v_pk_mul_f32 v[152:153], v[32:33], v[118:119] op_sel_hi:[1,0]
	v_pk_mul_f32 v[154:155], v[14:15], v[118:119] op_sel_hi:[1,0]
	v_pk_mul_f32 v[118:119], v[16:17], v[118:119] op_sel_hi:[1,0]
	v_pk_fma_f32 v[108:109], v[148:149], v[108:109], v[24:25]
	v_pk_fma_f32 v[106:107], v[128:129], v[106:107], v[22:23]
	v_max_f32_e32 v103, 0, v103
	v_max_f32_e32 v102, 0, v102
	v_max_f32_e32 v105, 0, v105
	v_max_f32_e32 v104, 0, v104
	v_pk_fma_f32 v[112:113], v[152:153], v[112:113], v[20:21]
	v_pk_fma_f32 v[110:111], v[150:151], v[110:111], v[18:19]
	v_pk_fma_f32 v[116:117], v[118:119], v[116:117], v[12:13]
	v_pk_fma_f32 v[114:115], v[154:155], v[114:115], v[10:11]
	v_max_f32_e32 v107, 0, v107
	v_max_f32_e32 v106, 0, v106
	v_max_f32_e32 v109, 0, v109
	v_max_f32_e32 v108, 0, v108
	v_pk_mul_f32 v[104:105], v[104:105], v[104:105]
	v_pk_mul_f32 v[102:103], v[102:103], v[102:103]
	v_max_f32_e32 v111, 0, v111
	v_max_f32_e32 v110, 0, v110
	v_max_f32_e32 v113, 0, v113
	v_max_f32_e32 v112, 0, v112
	v_max_f32_e32 v115, 0, v115
	v_max_f32_e32 v114, 0, v114
	v_max_f32_e32 v117, 0, v117
	v_max_f32_e32 v116, 0, v116
	v_pk_mul_f32 v[108:109], v[108:109], v[108:109]
	v_pk_mul_f32 v[106:107], v[106:107], v[106:107]
	v_cvt_pk_bf16_f32 v102, v102, v103
	v_cvt_pk_bf16_f32 v103, v104, v105
	v_pk_mul_f32 v[112:113], v[112:113], v[112:113]
	v_cvt_pk_bf16_f32 v104, v106, v107
	v_cvt_pk_bf16_f32 v105, v108, v109
	v_pk_mul_f32 v[110:111], v[110:111], v[110:111]
	v_pk_mul_f32 v[116:117], v[116:117], v[116:117]
	v_pk_mul_f32 v[114:115], v[114:115], v[114:115]
	global_store_dwordx4 v[120:121], v[102:105], off sc1
	s_nop 1
	v_cvt_pk_bf16_f32 v102, v110, v111
	v_cvt_pk_bf16_f32 v103, v112, v113
	v_cvt_pk_bf16_f32 v104, v114, v115
	v_cvt_pk_bf16_f32 v105, v116, v117
	global_store_dwordx4 v[122:123], v[102:105], off sc1
	global_load_dword v106, v[100:101], off offset:512
	s_nop 0
	v_add_u32_e32 v103, 0x80, v168
	v_ashrrev_i32_e32 v102, 8, v103
	v_lshlrev_b32_e32 v107, 7, v103
	v_ashrrev_i32_e32 v103, 31, v102
	v_lshlrev_b64 v[104:105], 7, v[102:103]
	v_lshl_add_u64 v[102:103], v[104:105], 0, s[26:27]
	v_lshl_add_u64 v[104:105], v[104:105], 0, s[28:29]
	v_lshlrev_b64 v[102:103], 15, v[102:103]
	v_lshlrev_b64 v[104:105], 15, v[104:105]
	v_lshl_add_u64 v[102:103], s[12:13], 0, v[102:103]
	v_lshl_add_u64 v[104:105], s[12:13], 0, v[104:105]
	v_and_b32_e32 v138, 0x6780, v107
	v_lshl_add_u64 v[108:109], v[102:103], 0, v[138:139]
	v_lshl_add_u64 v[110:111], v[104:105], 0, v[138:139]
	v_lshl_add_u64 v[108:109], v[108:109], 0, v[90:91]
	v_lshl_add_u64 v[110:111], v[110:111], 0, v[90:91]
	s_waitcnt vmcnt(0)
	v_pk_mul_f32 v[112:113], v[6:7], v[106:107] op_sel_hi:[1,0]
	v_pk_mul_f32 v[114:115], v[8:9], v[106:107] op_sel_hi:[1,0]
	v_pk_mul_f32 v[116:117], v[2:3], v[106:107] op_sel_hi:[1,0]
	v_pk_mul_f32 v[118:119], v[4:5], v[106:107] op_sel_hi:[1,0]
	v_pk_fma_f32 v[84:85], v[114:115], v[84:85], v[28:29]
	v_pk_fma_f32 v[82:83], v[112:113], v[82:83], v[26:27]
	v_pk_mul_f32 v[120:121], v[30:31], v[106:107] op_sel_hi:[1,0]
	v_pk_mul_f32 v[122:123], v[32:33], v[106:107] op_sel_hi:[1,0]
	v_pk_mul_f32 v[124:125], v[14:15], v[106:107] op_sel_hi:[1,0]
	v_pk_mul_f32 v[106:107], v[16:17], v[106:107] op_sel_hi:[1,0]
	v_pk_fma_f32 v[88:89], v[118:119], v[88:89], v[24:25]
	v_pk_fma_f32 v[86:87], v[116:117], v[86:87], v[22:23]
	v_max_f32_e32 v83, 0, v83
	v_max_f32_e32 v82, 0, v82
	v_max_f32_e32 v85, 0, v85
	v_max_f32_e32 v84, 0, v84
	v_pk_fma_f32 v[94:95], v[122:123], v[94:95], v[20:21]
	v_pk_fma_f32 v[92:93], v[120:121], v[92:93], v[18:19]
	v_pk_fma_f32 v[98:99], v[106:107], v[98:99], v[12:13]
	v_pk_fma_f32 v[96:97], v[124:125], v[96:97], v[10:11]
	v_max_f32_e32 v87, 0, v87
	v_max_f32_e32 v86, 0, v86
	v_max_f32_e32 v89, 0, v89
	v_max_f32_e32 v88, 0, v88
	v_pk_mul_f32 v[84:85], v[84:85], v[84:85]
	v_pk_mul_f32 v[82:83], v[82:83], v[82:83]
	v_max_f32_e32 v93, 0, v93
	v_max_f32_e32 v92, 0, v92
	v_max_f32_e32 v95, 0, v95
	v_max_f32_e32 v94, 0, v94
	v_max_f32_e32 v97, 0, v97
	v_max_f32_e32 v96, 0, v96
	v_max_f32_e32 v99, 0, v99
	v_max_f32_e32 v98, 0, v98
	v_pk_mul_f32 v[88:89], v[88:89], v[88:89]
	v_pk_mul_f32 v[86:87], v[86:87], v[86:87]
	v_cvt_pk_bf16_f32 v82, v82, v83
	v_cvt_pk_bf16_f32 v83, v84, v85
	v_pk_mul_f32 v[94:95], v[94:95], v[94:95]
	v_cvt_pk_bf16_f32 v84, v86, v87
	v_cvt_pk_bf16_f32 v85, v88, v89
	v_pk_mul_f32 v[92:93], v[92:93], v[92:93]
	v_pk_mul_f32 v[98:99], v[98:99], v[98:99]
	v_pk_mul_f32 v[96:97], v[96:97], v[96:97]
	global_store_dwordx4 v[108:109], v[82:85], off sc1
	s_nop 1
	v_cvt_pk_bf16_f32 v82, v92, v93
	v_cvt_pk_bf16_f32 v83, v94, v95
	v_cvt_pk_bf16_f32 v84, v96, v97
	v_cvt_pk_bf16_f32 v85, v98, v99
	global_store_dwordx4 v[110:111], v[82:85], off sc1
	global_load_dword v82, v[100:101], off offset:576
	s_nop 0
	v_add_u32_e32 v83, 0x4800, v169
	v_and_b32_e32 v138, 0x6f80, v83
	v_lshl_add_u64 v[84:85], v[102:103], 0, v[138:139]
	v_lshl_add_u64 v[86:87], v[104:105], 0, v[138:139]
	v_lshl_add_u64 v[84:85], v[84:85], 0, v[90:91]
	v_lshl_add_u64 v[86:87], v[86:87], 0, v[90:91]
	s_waitcnt vmcnt(0)
	v_pk_mul_f32 v[88:89], v[6:7], v[82:83] op_sel_hi:[1,0]
	v_pk_mul_f32 v[92:93], v[8:9], v[82:83] op_sel_hi:[1,0]
	v_pk_mul_f32 v[94:95], v[2:3], v[82:83] op_sel_hi:[1,0]
	v_pk_mul_f32 v[96:97], v[4:5], v[82:83] op_sel_hi:[1,0]
	v_pk_fma_f32 v[68:69], v[92:93], v[68:69], v[28:29]
	v_pk_fma_f32 v[66:67], v[88:89], v[66:67], v[26:27]
	v_pk_mul_f32 v[98:99], v[30:31], v[82:83] op_sel_hi:[1,0]
	v_pk_mul_f32 v[106:107], v[32:33], v[82:83] op_sel_hi:[1,0]
	v_pk_mul_f32 v[108:109], v[14:15], v[82:83] op_sel_hi:[1,0]
	v_pk_mul_f32 v[82:83], v[16:17], v[82:83] op_sel_hi:[1,0]
	v_pk_fma_f32 v[72:73], v[96:97], v[72:73], v[24:25]
	v_pk_fma_f32 v[70:71], v[94:95], v[70:71], v[22:23]
	v_max_f32_e32 v67, 0, v67
	v_max_f32_e32 v66, 0, v66
	v_max_f32_e32 v69, 0, v69
	v_max_f32_e32 v68, 0, v68
	v_pk_fma_f32 v[76:77], v[106:107], v[76:77], v[20:21]
	v_pk_fma_f32 v[74:75], v[98:99], v[74:75], v[18:19]
	v_pk_fma_f32 v[80:81], v[82:83], v[80:81], v[12:13]
	v_pk_fma_f32 v[78:79], v[108:109], v[78:79], v[10:11]
	v_max_f32_e32 v71, 0, v71
	v_max_f32_e32 v70, 0, v70
	v_max_f32_e32 v73, 0, v73
	v_max_f32_e32 v72, 0, v72
	v_pk_mul_f32 v[68:69], v[68:69], v[68:69]
	v_pk_mul_f32 v[66:67], v[66:67], v[66:67]
	v_max_f32_e32 v75, 0, v75
	v_max_f32_e32 v74, 0, v74
	v_max_f32_e32 v77, 0, v77
	v_max_f32_e32 v76, 0, v76
	v_max_f32_e32 v79, 0, v79
	v_max_f32_e32 v78, 0, v78
	v_max_f32_e32 v81, 0, v81
	v_max_f32_e32 v80, 0, v80
	v_pk_mul_f32 v[72:73], v[72:73], v[72:73]
	v_pk_mul_f32 v[70:71], v[70:71], v[70:71]
	v_cvt_pk_bf16_f32 v66, v66, v67
	v_cvt_pk_bf16_f32 v67, v68, v69
	v_pk_mul_f32 v[76:77], v[76:77], v[76:77]
	v_cvt_pk_bf16_f32 v68, v70, v71
	v_cvt_pk_bf16_f32 v69, v72, v73
	v_pk_mul_f32 v[74:75], v[74:75], v[74:75]
	v_pk_mul_f32 v[80:81], v[80:81], v[80:81]
	v_pk_mul_f32 v[78:79], v[78:79], v[78:79]
	global_store_dwordx4 v[84:85], v[66:69], off sc1
	s_nop 1
	v_cvt_pk_bf16_f32 v66, v74, v75
	v_cvt_pk_bf16_f32 v67, v76, v77
	v_cvt_pk_bf16_f32 v68, v78, v79
	v_cvt_pk_bf16_f32 v69, v80, v81
	global_store_dwordx4 v[86:87], v[66:69], off sc1
	global_load_dword v66, v[100:101], off offset:640
	s_nop 0
	v_add_u32_e32 v67, 0x5000, v169
	v_and_b32_e32 v138, 0x7780, v67
	v_lshl_add_u64 v[68:69], v[102:103], 0, v[138:139]
	v_lshl_add_u64 v[70:71], v[104:105], 0, v[138:139]
	v_lshl_add_u64 v[68:69], v[68:69], 0, v[90:91]
	v_lshl_add_u64 v[70:71], v[70:71], 0, v[90:91]
	s_waitcnt vmcnt(0)
	v_pk_mul_f32 v[72:73], v[6:7], v[66:67] op_sel_hi:[1,0]
	v_pk_mul_f32 v[74:75], v[8:9], v[66:67] op_sel_hi:[1,0]
	v_pk_mul_f32 v[76:77], v[2:3], v[66:67] op_sel_hi:[1,0]
	v_pk_mul_f32 v[78:79], v[4:5], v[66:67] op_sel_hi:[1,0]
	v_pk_fma_f32 v[52:53], v[74:75], v[52:53], v[28:29]
	v_pk_fma_f32 v[50:51], v[72:73], v[50:51], v[26:27]
	v_pk_mul_f32 v[80:81], v[30:31], v[66:67] op_sel_hi:[1,0]
	v_pk_mul_f32 v[82:83], v[32:33], v[66:67] op_sel_hi:[1,0]
	v_pk_mul_f32 v[84:85], v[14:15], v[66:67] op_sel_hi:[1,0]
	v_pk_mul_f32 v[66:67], v[16:17], v[66:67] op_sel_hi:[1,0]
	v_pk_fma_f32 v[56:57], v[78:79], v[56:57], v[24:25]
	v_pk_fma_f32 v[54:55], v[76:77], v[54:55], v[22:23]
	v_max_f32_e32 v51, 0, v51
	v_max_f32_e32 v50, 0, v50
	v_max_f32_e32 v53, 0, v53
	v_max_f32_e32 v52, 0, v52
	v_pk_fma_f32 v[60:61], v[82:83], v[60:61], v[20:21]
	v_pk_fma_f32 v[58:59], v[80:81], v[58:59], v[18:19]
	v_pk_fma_f32 v[64:65], v[66:67], v[64:65], v[12:13]
	v_pk_fma_f32 v[62:63], v[84:85], v[62:63], v[10:11]
	v_max_f32_e32 v55, 0, v55
	v_max_f32_e32 v54, 0, v54
	v_max_f32_e32 v57, 0, v57
	v_max_f32_e32 v56, 0, v56
	v_pk_mul_f32 v[52:53], v[52:53], v[52:53]
	v_pk_mul_f32 v[50:51], v[50:51], v[50:51]
	v_max_f32_e32 v59, 0, v59
	v_max_f32_e32 v58, 0, v58
	v_max_f32_e32 v61, 0, v61
	v_max_f32_e32 v60, 0, v60
	v_max_f32_e32 v63, 0, v63
	v_max_f32_e32 v62, 0, v62
	v_max_f32_e32 v65, 0, v65
	v_max_f32_e32 v64, 0, v64
	v_pk_mul_f32 v[56:57], v[56:57], v[56:57]
	v_pk_mul_f32 v[54:55], v[54:55], v[54:55]
	v_cvt_pk_bf16_f32 v50, v50, v51
	v_cvt_pk_bf16_f32 v51, v52, v53
	v_pk_mul_f32 v[60:61], v[60:61], v[60:61]
	v_cvt_pk_bf16_f32 v52, v54, v55
	v_cvt_pk_bf16_f32 v53, v56, v57
	v_pk_mul_f32 v[58:59], v[58:59], v[58:59]
	v_pk_mul_f32 v[64:65], v[64:65], v[64:65]
	v_pk_mul_f32 v[62:63], v[62:63], v[62:63]
	global_store_dwordx4 v[68:69], v[50:53], off sc1
	s_nop 1
	v_cvt_pk_bf16_f32 v50, v58, v59
	v_cvt_pk_bf16_f32 v51, v60, v61
	v_cvt_pk_bf16_f32 v52, v62, v63
	v_cvt_pk_bf16_f32 v53, v64, v65
	global_store_dwordx4 v[70:71], v[50:53], off sc1
	global_load_dword v50, v[100:101], off offset:704
	s_nop 0
	v_add_u32_e32 v51, 0x5800, v169
	v_and_b32_e32 v138, 0x7f80, v51
	v_lshl_add_u64 v[52:53], v[102:103], 0, v[138:139]
	v_lshl_add_u64 v[54:55], v[104:105], 0, v[138:139]
	v_lshl_add_u64 v[52:53], v[52:53], 0, v[90:91]
	v_lshl_add_u64 v[54:55], v[54:55], 0, v[90:91]
	s_waitcnt vmcnt(0)
	v_pk_mul_f32 v[2:3], v[2:3], v[50:51] op_sel_hi:[1,0]
	v_pk_mul_f32 v[4:5], v[4:5], v[50:51] op_sel_hi:[1,0]
	v_pk_mul_f32 v[6:7], v[6:7], v[50:51] op_sel_hi:[1,0]
	v_pk_mul_f32 v[8:9], v[8:9], v[50:51] op_sel_hi:[1,0]
	v_pk_mul_f32 v[30:31], v[30:31], v[50:51] op_sel_hi:[1,0]
	v_pk_fma_f32 v[4:5], v[4:5], v[40:41], v[24:25]
	v_pk_fma_f32 v[2:3], v[2:3], v[38:39], v[22:23]
	v_pk_mul_f32 v[32:33], v[32:33], v[50:51] op_sel_hi:[1,0]
	v_pk_mul_f32 v[14:15], v[14:15], v[50:51] op_sel_hi:[1,0]
	v_pk_mul_f32 v[16:17], v[16:17], v[50:51] op_sel_hi:[1,0]
	v_pk_fma_f32 v[8:9], v[8:9], v[36:37], v[28:29]
	v_pk_fma_f32 v[6:7], v[6:7], v[34:35], v[26:27]
	v_pk_fma_f32 v[18:19], v[30:31], v[42:43], v[18:19]
	v_max_f32_e32 v3, 0, v3
	v_max_f32_e32 v2, 0, v2
	v_max_f32_e32 v5, 0, v5
	v_max_f32_e32 v4, 0, v4
	v_pk_fma_f32 v[20:21], v[32:33], v[44:45], v[20:21]
	v_pk_fma_f32 v[12:13], v[16:17], v[48:49], v[12:13]
	v_pk_fma_f32 v[10:11], v[14:15], v[46:47], v[10:11]
	v_max_f32_e32 v7, 0, v7
	v_max_f32_e32 v6, 0, v6
	v_max_f32_e32 v9, 0, v9
	v_max_f32_e32 v8, 0, v8
	v_max_f32_e32 v15, 0, v19
	v_max_f32_e32 v14, 0, v18
	v_pk_mul_f32 v[18:19], v[4:5], v[4:5]
	v_pk_mul_f32 v[4:5], v[2:3], v[2:3]
	v_max_f32_e32 v17, 0, v21
	v_max_f32_e32 v16, 0, v20
	v_max_f32_e32 v11, 0, v11
	v_max_f32_e32 v10, 0, v10
	v_max_f32_e32 v13, 0, v13
	v_max_f32_e32 v12, 0, v12
	v_pk_mul_f32 v[8:9], v[8:9], v[8:9]
	v_pk_mul_f32 v[6:7], v[6:7], v[6:7]
	v_pk_mul_f32 v[16:17], v[16:17], v[16:17]
	v_cvt_pk_bf16_f32 v2, v6, v7
	v_cvt_pk_bf16_f32 v3, v8, v9
	v_cvt_pk_bf16_f32 v4, v4, v5
	v_cvt_pk_bf16_f32 v5, v18, v19
	v_pk_mul_f32 v[14:15], v[14:15], v[14:15]
	v_pk_mul_f32 v[12:13], v[12:13], v[12:13]
	v_pk_mul_f32 v[10:11], v[10:11], v[10:11]
	global_store_dwordx4 v[52:53], v[2:5], off sc1
	s_nop 1
	v_cvt_pk_bf16_f32 v2, v14, v15
	v_cvt_pk_bf16_f32 v3, v16, v17
	v_cvt_pk_bf16_f32 v4, v10, v11
	v_cvt_pk_bf16_f32 v5, v12, v13
	global_store_dwordx4 v[54:55], v[2:5], off sc1
	s_cbranch_vccnz .LBB0_3785
	s_andn2_b64 vcc, exec, s[10:11]
	s_cbranch_vccnz .LBB0_3784
	s_barrier
	s_branch .LBB0_3784

.LBB0_3942:
	s_waitcnt vmcnt(7)
	v_mov_b32_e32 v92, v63
	s_waitcnt vmcnt(6)
	v_mov_b32_e32 v93, v59
	v_mov_b32_e32 v90, v62
	v_mov_b32_e32 v91, v58
	v_pk_mul_f32 v[92:93], v[92:93], v[92:93]
	v_mov_b32_e32 v94, v65
	v_mov_b32_e32 v95, v61
	v_pk_fma_f32 v[90:91], v[90:91], v[90:91], v[92:93]
	v_mov_b32_e32 v92, v64
	v_mov_b32_e32 v93, v60
	v_pk_mul_f32 v[94:95], v[94:95], v[94:95]
	s_waitcnt vmcnt(3)
	v_mul_f32_e32 v89, v46, v46
	v_pk_fma_f32 v[92:93], v[92:93], v[92:93], v[94:95]
	v_pk_mul_f32 v[94:95], v[54:55], v[54:55]
	v_pk_add_f32 v[90:91], v[90:91], v[92:93]
	v_pk_mul_f32 v[92:93], v[56:57], v[56:57]
	v_pk_add_f32 v[90:91], v[90:91], v[90:91] op_sel:[0,1] op_sel_hi:[1,0]
	v_pk_mov_b32 v[96:97], v[94:95], v[92:93] op_sel:[1,0]
	v_mov_b32_e32 v95, v93
	v_pk_add_f32 v[92:93], v[96:97], v[94:95]
	v_mul_f32_e32 v94, v47, v47
	v_pk_add_f32 v[92:93], v[92:93], v[92:93] op_sel:[0,1] op_sel_hi:[1,0]
	v_mov_b32_e32 v91, v89
	v_mov_b32_e32 v93, v94
	v_pk_add_f32 v[94:95], v[90:91], v[92:93]
	v_mul_f32_e32 v90, v51, v51
	v_pk_fma_f32 v[96:97], v[50:51], v[50:51], v[90:91] op_sel_hi:[1,1,0]
	global_load_dwordx4 v[90:93], v[68:69], off
	v_mul_f32_e32 v98, v48, v48
	v_mov_b32_e32 v97, v98
	v_mul_f32_e32 v98, v53, v53
	v_mul_f32_e32 v100, v49, v49
	v_pk_fma_f32 v[98:99], v[52:53], v[52:53], v[98:99] op_sel_hi:[1,1,0]
	s_waitcnt vmcnt(1)
	v_mul_f32_e32 v89, v34, v34
	v_mov_b32_e32 v99, v100
	v_pk_add_f32 v[96:97], v[96:97], v[98:99]
	v_pk_mul_f32 v[98:99], v[42:43], v[42:43]
	v_pk_add_f32 v[94:95], v[94:95], v[96:97]
	v_pk_mul_f32 v[96:97], v[44:45], v[44:45]
	v_pk_add_f32 v[94:95], v[94:95], v[94:95] op_sel:[0,1] op_sel_hi:[1,0]
	v_pk_mov_b32 v[100:101], v[98:99], v[96:97] op_sel:[1,0]
	v_mov_b32_e32 v99, v97
	v_pk_add_f32 v[96:97], v[100:101], v[98:99]
	v_mul_f32_e32 v98, v35, v35
	v_pk_add_f32 v[96:97], v[96:97], v[96:97] op_sel:[0,1] op_sel_hi:[1,0]
	v_mov_b32_e32 v95, v89
	v_mov_b32_e32 v97, v98
	v_pk_add_f32 v[94:95], v[94:95], v[96:97]
	v_mul_f32_e32 v96, v39, v39
	v_mul_f32_e32 v99, v36, v36
	v_pk_fma_f32 v[96:97], v[38:39], v[38:39], v[96:97] op_sel_hi:[1,1,0]
	v_mul_f32_e32 v98, v41, v41
	v_mul_f32_e32 v100, v37, v37
	v_mov_b32_e32 v97, v99
	v_pk_fma_f32 v[98:99], v[40:41], v[40:41], v[98:99] op_sel_hi:[1,1,0]
	s_add_u32 s6, s72, s6
	v_mov_b32_e32 v99, v100
	v_pk_add_f32 v[96:97], v[96:97], v[98:99]
	s_addc_u32 s7, s73, s7
	v_pk_add_f32 v[94:95], v[94:95], v[96:97]
	s_nop 0
	v_add_f32_e32 v89, v94, v95
	ds_bpermute_b32 v94, v67, v89
	s_waitcnt lgkmcnt(0)
	v_add_f32_e32 v89, v89, v94
	ds_bpermute_b32 v94, v80, v89
	s_waitcnt lgkmcnt(0)
	v_add_f32_e32 v89, v89, v94
	ds_bpermute_b32 v94, v81, v89
	s_waitcnt lgkmcnt(0)
	v_add_f32_e32 v89, v89, v94
	ds_bpermute_b32 v94, v82, v89
	s_waitcnt lgkmcnt(0)
	v_add_f32_e32 v89, v89, v94
	ds_bpermute_b32 v94, v83, v89
	s_waitcnt lgkmcnt(0)
	v_add_f32_e32 v89, v89, v94
	ds_bpermute_b32 v94, v84, v89
	s_waitcnt lgkmcnt(0)
	v_add_f32_e32 v89, v89, v94
	v_fmamk_f32 v89, v89, 0x3a000000, v1
	v_mul_f32_e32 v94, 0x4b800000, v89
	v_cmp_gt_f32_e32 vcc, s9, v89
	s_nop 1
	v_cndmask_b32_e32 v89, v89, v94, vcc
	v_rsq_f32_e32 v89, v89
	s_nop 0
	v_mul_f32_e32 v94, 0x45800000, v89
	v_cndmask_b32_e32 v94, v89, v94, vcc
	v_pk_mul_f32 v[62:63], v[62:63], v[94:95] op_sel_hi:[1,0]
	v_pk_mul_f32 v[64:65], v[64:65], v[94:95] op_sel_hi:[1,0]
	s_waitcnt vmcnt(0)
	v_pk_mul_f32 v[90:91], v[90:91], v[62:63]
	v_pk_mul_f32 v[92:93], v[92:93], v[64:65]
	v_lshlrev_b32_e32 v62, 2, v66
	global_store_dwordx4 v62, v[90:93], s[6:7] sc1
	global_load_dwordx4 v[90:93], v[68:69], off offset:1024
	v_pk_mul_f32 v[60:61], v[60:61], v[94:95] op_sel_hi:[1,0]
	v_pk_mul_f32 v[58:59], v[58:59], v[94:95] op_sel_hi:[1,0]
	v_pk_mul_f32 v[56:57], v[56:57], v[94:95] op_sel_hi:[1,0]
	v_pk_mul_f32 v[54:55], v[54:55], v[94:95] op_sel_hi:[1,0]
	v_pk_mul_f32 v[52:53], v[52:53], v[94:95] op_sel_hi:[1,0]
	v_pk_mul_f32 v[50:51], v[50:51], v[94:95] op_sel_hi:[1,0]
	v_pk_mul_f32 v[48:49], v[48:49], v[94:95] op_sel_hi:[1,0]
	v_pk_mul_f32 v[46:47], v[46:47], v[94:95] op_sel_hi:[1,0]
	v_pk_mul_f32 v[44:45], v[44:45], v[94:95] op_sel_hi:[1,0]
	v_pk_mul_f32 v[42:43], v[42:43], v[94:95] op_sel_hi:[1,0]
	v_pk_mul_f32 v[40:41], v[40:41], v[94:95] op_sel_hi:[1,0]
	v_pk_mul_f32 v[38:39], v[38:39], v[94:95] op_sel_hi:[1,0]
	v_pk_mul_f32 v[36:37], v[36:37], v[94:95] op_sel_hi:[1,0]
	v_pk_mul_f32 v[34:35], v[34:35], v[94:95] op_sel_hi:[1,0]
	s_andn2_b64 vcc, exec, s[4:5]
	s_waitcnt vmcnt(0)
	v_pk_mul_f32 v[58:59], v[90:91], v[58:59]
	v_pk_mul_f32 v[60:61], v[92:93], v[60:61]
	global_store_dwordx4 v62, v[58:61], s[6:7] offset:1024 sc1
	global_load_dwordx4 v[58:61], v[68:69], off offset:2048
	s_waitcnt vmcnt(0)
	v_pk_mul_f32 v[54:55], v[58:59], v[54:55]
	v_pk_mul_f32 v[56:57], v[60:61], v[56:57]
	global_store_dwordx4 v62, v[54:57], s[6:7] offset:2048 sc1
	global_load_dwordx4 v[54:57], v[68:69], off offset:3072
	s_waitcnt vmcnt(0)
	v_pk_mul_f32 v[50:51], v[54:55], v[50:51]
	v_pk_mul_f32 v[52:53], v[56:57], v[52:53]
	global_store_dwordx4 v62, v[50:53], s[6:7] offset:3072 sc1
	global_load_dwordx4 v[50:53], v[70:71], off
	s_waitcnt vmcnt(0)
	v_pk_mul_f32 v[46:47], v[50:51], v[46:47]
	v_pk_mul_f32 v[48:49], v[52:53], v[48:49]
	global_store_dwordx4 v85, v[46:49], s[6:7] sc1
	global_load_dwordx4 v[46:49], v[72:73], off
	s_waitcnt vmcnt(0)
	v_pk_mul_f32 v[42:43], v[46:47], v[42:43]
	v_pk_mul_f32 v[44:45], v[48:49], v[44:45]
	global_store_dwordx4 v86, v[42:45], s[6:7] sc1
	global_load_dwordx4 v[42:45], v[74:75], off
	s_waitcnt vmcnt(0)
	v_pk_mul_f32 v[38:39], v[38:39], v[42:43]
	v_pk_mul_f32 v[40:41], v[40:41], v[44:45]
	global_store_dwordx4 v87, v[38:41], s[6:7] sc1
	global_load_dwordx4 v[38:41], v[76:77], off
	s_waitcnt vmcnt(0)
	v_pk_mul_f32 v[34:35], v[34:35], v[38:39]
	v_pk_mul_f32 v[36:37], v[36:37], v[40:41]
	global_store_dwordx4 v88, v[34:37], s[6:7] sc1
	s_cbranch_vccnz .LBB0_3939
	s_nop 0
	v_mov_b32_e32 v36, v11
	v_mov_b32_e32 v37, v15
	v_mov_b32_e32 v34, v10
	v_mov_b32_e32 v35, v14
	v_pk_mul_f32 v[36:37], v[36:37], v[36:37]
	v_mov_b32_e32 v38, v13
	v_mov_b32_e32 v39, v17
	v_pk_fma_f32 v[34:35], v[34:35], v[34:35], v[36:37]
	v_mov_b32_e32 v36, v12
	v_mov_b32_e32 v37, v16
	v_pk_mul_f32 v[38:39], v[38:39], v[38:39]
	s_ashr_i32 s3, s2, 31
	v_pk_fma_f32 v[36:37], v[36:37], v[36:37], v[38:39]
	s_lshl_b64 s[4:5], s[2:3], 13
	v_pk_add_f32 v[34:35], v[34:35], v[36:37]
	v_pk_mul_f32 v[36:37], v[6:7], v[6:7]
	v_pk_add_f32 v[38:39], v[34:35], v[34:35] op_sel_hi:[0,1]
	v_pk_mul_f32 v[34:35], v[8:9], v[8:9]
	v_mul_f32_e32 v38, v2, v2
	v_pk_mov_b32 v[40:41], v[36:37], v[34:35] op_sel:[1,0]
	v_mov_b32_e32 v37, v35
	v_pk_add_f32 v[40:41], v[40:41], v[36:37]
	global_load_dwordx4 v[34:37], v[68:69], off
	v_pk_fma_f32 v[42:43], v[2:3], v[2:3], v[38:39] op_sel_hi:[1,1,0]
	v_mul_f32_e32 v38, v4, v4
	v_pk_add_f32 v[40:41], v[40:41], v[40:41] op_sel_hi:[0,1]
	v_pk_fma_f32 v[44:45], v[4:5], v[4:5], v[38:39] op_sel_hi:[1,1,0]
	v_mul_f32_e32 v42, v30, v30
	v_mul_f32_e32 v44, v31, v31
	v_mul_f32_e32 v40, v32, v32
	v_mul_f32_e32 v38, v33, v33
	v_pk_add_f32 v[42:43], v[42:43], v[44:45]
	v_pk_add_f32 v[38:39], v[40:41], v[38:39]
	v_pk_mul_f32 v[40:41], v[28:29], v[28:29]
	v_pk_add_f32 v[38:39], v[42:43], v[38:39]
	v_pk_mul_f32 v[42:43], v[26:27], v[26:27]
	v_pk_add_f32 v[38:39], v[38:39], v[38:39] op_sel_hi:[0,1]
	v_pk_mov_b32 v[44:45], v[42:43], v[40:41] op_sel:[1,0]
	v_mov_b32_e32 v43, v41
	v_mul_f32_e32 v38, v22, v22
	v_pk_add_f32 v[40:41], v[44:45], v[42:43]
	v_pk_fma_f32 v[42:43], v[22:23], v[22:23], v[38:39] op_sel_hi:[1,1,0]
	v_mul_f32_e32 v38, v24, v24
	v_pk_add_f32 v[40:41], v[40:41], v[40:41] op_sel_hi:[0,1]
	v_pk_fma_f32 v[44:45], v[24:25], v[24:25], v[38:39] op_sel_hi:[1,1,0]
	v_mul_f32_e32 v42, v18, v18
	v_mul_f32_e32 v44, v19, v19
	v_mul_f32_e32 v40, v20, v20
	v_mul_f32_e32 v38, v21, v21
	v_pk_add_f32 v[42:43], v[42:43], v[44:45]
	v_pk_add_f32 v[38:39], v[40:41], v[38:39]
	s_add_u32 s4, s72, s4
	v_pk_add_f32 v[38:39], v[42:43], v[38:39]
	s_addc_u32 s5, s73, s5
	v_add_f32_e32 v38, v38, v39
	ds_bpermute_b32 v39, v67, v38
	s_waitcnt lgkmcnt(0)
	v_add_f32_e32 v38, v38, v39
	ds_bpermute_b32 v39, v80, v38
	s_waitcnt lgkmcnt(0)
	v_add_f32_e32 v38, v38, v39
	ds_bpermute_b32 v39, v81, v38
	s_waitcnt lgkmcnt(0)
	v_add_f32_e32 v38, v38, v39
	ds_bpermute_b32 v39, v82, v38
	s_waitcnt lgkmcnt(0)
	v_add_f32_e32 v38, v38, v39
	ds_bpermute_b32 v39, v83, v38
	s_waitcnt lgkmcnt(0)
	v_add_f32_e32 v38, v38, v39
	ds_bpermute_b32 v39, v84, v38
	s_waitcnt lgkmcnt(0)
	v_add_f32_e32 v38, v38, v39
	v_fmamk_f32 v38, v38, 0x3a000000, v1
	v_mul_f32_e32 v39, 0x4b800000, v38
	v_cmp_gt_f32_e32 vcc, s9, v38
	s_nop 1
	v_cndmask_b32_e32 v38, v38, v39, vcc
	v_rsq_f32_e32 v38, v38
	s_nop 0
	v_mul_f32_e32 v39, 0x45800000, v38
	v_cndmask_b32_e32 v38, v38, v39, vcc
	v_pk_mul_f32 v[40:41], v[14:15], v[38:39] op_sel_hi:[1,0]
	v_pk_mul_f32 v[42:43], v[16:17], v[38:39] op_sel_hi:[1,0]
	s_waitcnt vmcnt(0)
	v_pk_mul_f32 v[34:35], v[34:35], v[40:41]
	v_pk_mul_f32 v[36:37], v[36:37], v[42:43]
	global_store_dwordx4 v62, v[34:37], s[4:5] sc1
	global_load_dwordx4 v[34:37], v[68:69], off offset:1024
	v_pk_mul_f32 v[40:41], v[12:13], v[38:39] op_sel_hi:[1,0]
	v_pk_mul_f32 v[42:43], v[10:11], v[38:39] op_sel_hi:[1,0]
	s_waitcnt vmcnt(0)
	v_pk_mul_f32 v[36:37], v[36:37], v[40:41]
	v_pk_mul_f32 v[34:35], v[34:35], v[42:43]
	global_store_dwordx4 v62, v[34:37], s[4:5] offset:1024 sc1
	global_load_dwordx4 v[34:37], v[68:69], off offset:2048
	v_pk_mul_f32 v[40:41], v[8:9], v[38:39] op_sel_hi:[1,0]
	v_pk_mul_f32 v[42:43], v[6:7], v[38:39] op_sel_hi:[1,0]
	s_waitcnt vmcnt(0)
	v_pk_mul_f32 v[36:37], v[36:37], v[40:41]
	v_pk_mul_f32 v[34:35], v[34:35], v[42:43]
	global_store_dwordx4 v62, v[34:37], s[4:5] offset:2048 sc1
	global_load_dwordx4 v[34:37], v[68:69], off offset:3072
	v_pk_mul_f32 v[40:41], v[4:5], v[38:39] op_sel_hi:[1,0]
	v_pk_mul_f32 v[42:43], v[2:3], v[38:39] op_sel_hi:[1,0]
	s_waitcnt vmcnt(0)
	v_pk_mul_f32 v[36:37], v[36:37], v[40:41]
	v_pk_mul_f32 v[34:35], v[34:35], v[42:43]
	global_store_dwordx4 v62, v[34:37], s[4:5] offset:3072 sc1
	global_load_dwordx4 v[34:37], v[70:71], off
	v_pk_mul_f32 v[40:41], v[32:33], v[38:39] op_sel_hi:[1,0]
	v_pk_mul_f32 v[42:43], v[30:31], v[38:39] op_sel_hi:[1,0]
	s_waitcnt vmcnt(0)
	v_pk_mul_f32 v[36:37], v[36:37], v[40:41]
	v_pk_mul_f32 v[34:35], v[34:35], v[42:43]
	global_store_dwordx4 v85, v[34:37], s[4:5] sc1
	global_load_dwordx4 v[34:37], v[72:73], off
	v_pk_mul_f32 v[40:41], v[28:29], v[38:39] op_sel_hi:[1,0]
	v_pk_mul_f32 v[42:43], v[26:27], v[38:39] op_sel_hi:[1,0]
	s_waitcnt vmcnt(0)
	v_pk_mul_f32 v[36:37], v[36:37], v[40:41]
	v_pk_mul_f32 v[34:35], v[34:35], v[42:43]
	global_store_dwordx4 v86, v[34:37], s[4:5] sc1
	global_load_dwordx4 v[34:37], v[74:75], off
	v_pk_mul_f32 v[40:41], v[24:25], v[38:39] op_sel_hi:[1,0]
	v_pk_mul_f32 v[42:43], v[22:23], v[38:39] op_sel_hi:[1,0]
	s_waitcnt vmcnt(0)
	v_pk_mul_f32 v[36:37], v[40:41], v[36:37]
	v_pk_mul_f32 v[34:35], v[42:43], v[34:35]
	global_store_dwordx4 v87, v[34:37], s[4:5] sc1
	global_load_dwordx4 v[34:37], v[76:77], off
	v_pk_mul_f32 v[40:41], v[20:21], v[38:39] op_sel_hi:[1,0]
	v_pk_mul_f32 v[38:39], v[18:19], v[38:39] op_sel_hi:[1,0]
	s_waitcnt vmcnt(0)
	v_pk_mul_f32 v[36:37], v[40:41], v[36:37]
	v_pk_mul_f32 v[34:35], v[38:39], v[34:35]
	global_store_dwordx4 v88, v[34:37], s[4:5] sc1
	s_branch .LBB0_3939
